# MoBA: DMA issues interleaved with QK MFMAs; GEMM: first K iteration peeled with C=0 (no accumulator zeroing), last two LDS-DMA pieces of SP2 load segments issued inside the MFMA segment (vmcnt 8->6)
# speedup vs baseline: 1.0253x; 1.0029x over previous
; #define PG8_STAGE(bufoff, gbase, voff) do { _Pragma("unroll") for (int _i = 0; _i < 2; ++_i) \
;         __builtin_amdgcn_global_load_lds((const unsigned*)((const char*)(gbase) + (voff)[_i]), (PG8_LAS unsigned*)(lds + (bufoff) + ldsw + _i * 8192), 16, 0, 0); } while (0)
; #define PG8_LDA(dst, b, h) do { _Pragma("unroll") for (int m = 0; m < 4; ++m) _Pragma("unroll") for (int k = 0; k < 2; ++k) dst[m][k] = *(const PG8_LAS bf16x8*)(lds + PG8_SA(b, h) + aoff + m * 2048 + k * 1024); } while (0)
; #define PG8_LDB(dst, b, h) do { _Pragma("unroll") for (int n = 0; n < 2; ++n) _Pragma("unroll") for (int k = 0; k < 2; ++k) dst[n][k] = *(const PG8_LAS bf16x8*)(lds + PG8_SB(b, h) + boff + n * 2048 + k * 1024); } while (0)
; #define PG8_WAIT_V(n) asm volatile("s_waitcnt vmcnt(" #n ")" ::: "memory")
; #define PG8_WAIT_L(n) asm volatile("s_waitcnt lgkmcnt(" #n ")" ::: "memory")
; #define PG8_BAR __builtin_amdgcn_s_barrier()
; #define PG8_SCHED __builtin_amdgcn_sched_barrier(0)
; template <class Epi, class Sched, bool ALIGN_EPI = false, bool SP2 = false>
; __device__ __forceinline__ void gemm_phase(PG8_LAS unsigned char* lds, const Gemm g, const Sched& S, const Epi& E) {
;     ...
;         const char* nA = has_next ? (const char*)g.A + (size_t)nxt.pm * tstep : cA; const char* nB = has_next ? (const char*)g.Bt + (size_t)nxt.pn * tstep : cB;
;         for (int t = 0; t < nt; t += 2) {
;             const bool last = (t == nt - 2);
;             const char* a1 = cA + (size_t)(t + 1) * kstep;
;             const char* a2 = last ? nA : cA + (size_t)(t + 2) * kstep; const char* b2 = last ? nB : cB + (size_t)(t + 2) * kstep;
;             const char* a3 = a2 + kstep; const char* b3 = b2 + kstep;
;             if (last && has_next) S.a_ready(nxt);
;             if constexpr (SP2) {
;             PG8_LDB(B0, 0, 0); PG8_LDB(B1, 0, 1); PG8_SCHED; PG8_LDA(At, 0, 0); PG8_STAGE(PG8_SA(1, 1), a1 + hstep, voffA);
;             PG8_WAIT_V(8); PG8_WAIT_L(0); PG8_BAR; PG8_MMA(0, 0, At, B0); PG8_MMA(0, 1, At, B1); PG8_BAR; PG8_SCHED;
;             PG8_LDA(At, 0, 1); PG8_STAGE(PG8_SB(0, 0), b2, voffB); PG8_STAGE(PG8_SB(0, 1), b2 + hstep, voffB); PG8_STAGE(PG8_SA(0, 0), a2, voffA);
;             PG8_WAIT_V(8); PG8_WAIT_L(0); PG8_BAR; PG8_MMA(1, 0, At, B0); PG8_MMA(1, 1, At, B1); PG8_BAR; PG8_SCHED;
.LBB0_190:
	s_ashr_i32 s27, s26, 31
	s_lshl_b64 s[14:15], s[26:27], 19
	s_add_u32 s28, s22, s14
	s_addc_u32 s29, s23, s15
	s_and_b64 s[14:15], s[0:1], exec
	s_cselect_b32 s27, s29, s49
	s_cselect_b32 s67, s28, s48
	s_ashr_i32 s25, s24, 31
	s_lshl_b64 s[14:15], s[24:25], 19
	s_add_u32 s40, s94, s14
	s_addc_u32 s41, s96, s15
	s_and_b64 s[14:15], s[0:1], exec
	s_cselect_b32 s25, s41, s51
	s_cselect_b32 s86, s40, s50
	s_add_u32 s48, s48, 0x40080
	s_addc_u32 s49, s49, 0
	s_add_u32 s87, s50, 0x100
	s_addc_u32 s88, s51, 0
	s_mov_b32 s89, -2
	ds_read_b128 v[144:147], v155
	ds_read_b128 v[148:151], v155 offset:1024
	ds_read_b128 v[160:163], v155 offset:2048
	ds_read_b128 v[168:171], v155 offset:3072
	ds_read_b128 v[172:175], v156
	ds_read_b128 v[176:179], v156 offset:1024
	ds_read_b128 v[182:185], v156 offset:2048
	ds_read_b128 v[186:189], v156 offset:3072
	s_add_u32 s3, s48, 0xfffc0080
	s_addc_u32 s14, s49, -1
	s_cmp_eq_u32 s89, 12
	s_cselect_b32 s55, s27, s14
	s_cselect_b32 s54, s67, s3
	s_cselect_b32 s51, s25, s88
	s_cselect_b32 s50, s86, s87
	v_lshl_add_u64 v[164:165], s[48:49], 0, v[136:137]
	s_add_i32 m0, s45, 0xc000
	ds_read_b128 v[190:193], v157
	ds_read_b128 v[194:197], v157 offset:1024
	ds_read_b128 v[198:201], v157 offset:2048
	ds_read_b128 v[208:211], v157 offset:3072
	ds_read_b128 v[212:215], v157 offset:4096
	ds_read_b128 v[216:219], v157 offset:5120
	ds_read_b128 v[220:223], v157 offset:6144
	ds_read_b128 v[224:227], v157 offset:7168
	global_load_lds_dwordx4 v[164:165], off
	v_lshl_add_u64 v[164:165], s[48:49], 0, v[138:139]
	s_add_i32 m0, s45, 0xe000
	s_nop 0
	global_load_lds_dwordx4 v[164:165], off
	s_waitcnt vmcnt(8)
	s_waitcnt lgkmcnt(0)
	s_barrier
	s_setprio 1
	s_waitcnt lgkmcnt(0)
	v_mfma_f32_16x16x32_bf16 v[124:127], v[144:147], v[190:193], 0
	v_mfma_f32_16x16x32_bf16 v[120:123], v[160:163], v[190:193], 0
	v_mfma_f32_16x16x32_bf16 v[108:111], v[144:147], v[198:201], 0
	v_mfma_f32_16x16x32_bf16 v[104:107], v[160:163], v[198:201], 0
	v_mfma_f32_16x16x32_bf16 v[92:95], v[144:147], v[212:215], 0
	v_mfma_f32_16x16x32_bf16 v[88:91], v[160:163], v[212:215], 0
	v_mfma_f32_16x16x32_bf16 v[76:79], v[144:147], v[220:223], 0
	v_mfma_f32_16x16x32_bf16 v[72:75], v[160:163], v[220:223], 0
	v_mfma_f32_16x16x32_bf16 v[124:127], v[148:151], v[194:197], v[124:127]
	v_mfma_f32_16x16x32_bf16 v[120:123], v[168:171], v[194:197], v[120:123]
	v_mfma_f32_16x16x32_bf16 v[108:111], v[148:151], v[208:211], v[108:111]
	v_mfma_f32_16x16x32_bf16 v[104:107], v[168:171], v[208:211], v[104:107]
	v_mfma_f32_16x16x32_bf16 v[92:95], v[148:151], v[216:219], v[92:95]
	v_mfma_f32_16x16x32_bf16 v[88:91], v[168:171], v[216:219], v[88:91]
	v_mfma_f32_16x16x32_bf16 v[76:79], v[148:151], v[224:227], v[76:79]
	v_mfma_f32_16x16x32_bf16 v[72:75], v[168:171], v[224:227], v[72:75]
	s_setprio 0
	s_setprio 1
	v_mfma_f32_16x16x32_bf16 v[116:119], v[172:175], v[190:193], 0
	v_mfma_f32_16x16x32_bf16 v[112:115], v[182:185], v[190:193], 0
	v_mfma_f32_16x16x32_bf16 v[100:103], v[172:175], v[198:201], 0
	v_mfma_f32_16x16x32_bf16 v[96:99], v[182:185], v[198:201], 0
	v_mfma_f32_16x16x32_bf16 v[84:87], v[172:175], v[212:215], 0
	v_mfma_f32_16x16x32_bf16 v[80:83], v[182:185], v[212:215], 0
	v_mfma_f32_16x16x32_bf16 v[68:71], v[172:175], v[220:223], 0
	v_mfma_f32_16x16x32_bf16 v[64:67], v[182:185], v[220:223], 0
	v_mfma_f32_16x16x32_bf16 v[116:119], v[176:179], v[194:197], v[116:119]
	v_mfma_f32_16x16x32_bf16 v[112:115], v[186:189], v[194:197], v[112:115]
	v_mfma_f32_16x16x32_bf16 v[100:103], v[176:179], v[208:211], v[100:103]
	v_mfma_f32_16x16x32_bf16 v[96:99], v[186:189], v[208:211], v[96:99]
	v_mfma_f32_16x16x32_bf16 v[84:87], v[176:179], v[216:219], v[84:87]
	v_mfma_f32_16x16x32_bf16 v[80:83], v[186:189], v[216:219], v[80:83]
	v_mfma_f32_16x16x32_bf16 v[68:71], v[176:179], v[224:227], v[68:71]
	v_mfma_f32_16x16x32_bf16 v[64:67], v[186:189], v[224:227], v[64:67]
	s_setprio 0
	s_barrier
	s_add_i32 s3, s63, s43
	v_lshl_add_u64 v[164:165], s[50:51], 0, v[132:133]
	s_mov_b32 m0, s3
	ds_read_b128 v[190:193], v157 offset:16384
	ds_read_b128 v[194:197], v157 offset:17408
	ds_read_b128 v[198:201], v157 offset:18432
	ds_read_b128 v[208:211], v157 offset:19456
	ds_read_b128 v[212:215], v157 offset:20480
	ds_read_b128 v[216:219], v157 offset:21504
	ds_read_b128 v[220:223], v157 offset:22528
	ds_read_b128 v[224:227], v157 offset:23552
	global_load_lds_dwordx4 v[164:165], off
	s_add_i32 m0, s3, 0x2000
	s_add_u32 s14, s50, 0x40000
	v_lshl_add_u64 v[202:203], s[50:51], 0, v[128:129]
	s_addc_u32 s15, s51, 0
	s_add_i32 s3, s64, s43
	global_load_lds_dwordx4 v[202:203], off
	v_lshl_add_u64 v[228:229], s[14:15], 0, v[132:133]
	s_mov_b32 m0, s3
	v_lshl_add_u64 v[230:231], s[54:55], 0, v[130:131]
	global_load_lds_dwordx4 v[228:229], off
	v_lshl_add_u64 v[228:229], s[14:15], 0, v[128:129]
	s_add_i32 m0, s3, 0x2000
	s_nop 0
	global_load_lds_dwordx4 v[228:229], off
	s_waitcnt vmcnt(6)
	s_waitcnt lgkmcnt(0)
	s_barrier
; #define PG8_STAGE(bufoff, gbase, voff) do { _Pragma("unroll") for (int _i = 0; _i < 2; ++_i) \
;         __builtin_amdgcn_global_load_lds((const unsigned*)((const char*)(gbase) + (voff)[_i]), (PG8_LAS unsigned*)(lds + (bufoff) + ldsw + _i * 8192), 16, 0, 0); } while (0)
; #define PG8_LDA(dst, b, h) do { _Pragma("unroll") for (int m = 0; m < 4; ++m) _Pragma("unroll") for (int k = 0; k < 2; ++k) dst[m][k] = *(const PG8_LAS bf16x8*)(lds + PG8_SA(b, h) + aoff + m * 2048 + k * 1024); } while (0)
; #define PG8_LDB(dst, b, h) do { _Pragma("unroll") for (int n = 0; n < 2; ++n) _Pragma("unroll") for (int k = 0; k < 2; ++k) dst[n][k] = *(const PG8_LAS bf16x8*)(lds + PG8_SB(b, h) + boff + n * 2048 + k * 1024); } while (0)
; #define PG8_MMA(ai, bj, At, Bt) do { __builtin_amdgcn_s_setprio(1); _Pragma("unroll") for (int m = 0; m < 4; ++m) _Pragma("unroll") for (int n = 0; n < 2; ++n) _Pragma("unroll") for (int k = 0; k < 2; ++k) \
;         acc[ai][bj][m][n] = __builtin_amdgcn_mfma_f32_16x16x32_bf16(Bt[n][k], At[m][k], acc[ai][bj][m][n], 0, 0, 0); __builtin_amdgcn_s_setprio(0); } while (0)
; #define PG8_WAIT_V(n) asm volatile("s_waitcnt vmcnt(" #n ")" ::: "memory")
; #define PG8_WAIT_L(n) asm volatile("s_waitcnt lgkmcnt(" #n ")" ::: "memory")
; #define PG8_BAR __builtin_amdgcn_s_barrier()
; #define PG8_SCHED __builtin_amdgcn_sched_barrier(0)
; template <class Epi, class Sched, bool ALIGN_EPI = false, bool SP2 = false>
; __device__ __forceinline__ void gemm_phase(PG8_LAS unsigned char* lds, const Gemm g, const Sched& S, const Epi& E) {
;     ...
;             PG8_WAIT_V(8); PG8_WAIT_L(0); PG8_BAR; PG8_MMA(1, 0, At, B0); PG8_MMA(1, 1, At, B1); PG8_BAR; PG8_SCHED;
;             PG8_LDB(B0, 1, 0); PG8_LDB(B1, 1, 1); PG8_SCHED; PG8_LDA(At, 1, 0); PG8_STAGE(PG8_SA(0, 1), a2 + hstep, voffA);
;             PG8_WAIT_V(8); PG8_WAIT_L(0); PG8_BAR; PG8_MMA(0, 0, At, B0); PG8_MMA(0, 1, At, B1); PG8_BAR; PG8_SCHED;
	s_setprio 1
	s_waitcnt lgkmcnt(0)
	v_mfma_f32_16x16x32_bf16 v[60:63], v[144:147], v[190:193], 0
	v_mfma_f32_16x16x32_bf16 v[56:59], v[160:163], v[190:193], 0
	v_mfma_f32_16x16x32_bf16 v[44:47], v[144:147], v[198:201], 0
	v_mfma_f32_16x16x32_bf16 v[40:43], v[160:163], v[198:201], 0
	v_mfma_f32_16x16x32_bf16 v[28:31], v[144:147], v[212:215], 0
	v_mfma_f32_16x16x32_bf16 v[24:27], v[160:163], v[212:215], 0
	v_lshl_add_u64 v[228:229], s[54:55], 0, v[134:135]
	s_mov_b32 m0, s45
	s_nop 0
	global_load_lds_dwordx4 v[228:229], off
	v_mfma_f32_16x16x32_bf16 v[12:15], v[144:147], v[220:223], 0
	v_mfma_f32_16x16x32_bf16 v[8:11], v[160:163], v[220:223], 0
	v_mfma_f32_16x16x32_bf16 v[60:63], v[148:151], v[194:197], v[60:63]
	v_mfma_f32_16x16x32_bf16 v[56:59], v[168:171], v[194:197], v[56:59]
	v_mfma_f32_16x16x32_bf16 v[44:47], v[148:151], v[208:211], v[44:47]
	v_mfma_f32_16x16x32_bf16 v[40:43], v[168:171], v[208:211], v[40:43]
	v_mfma_f32_16x16x32_bf16 v[28:31], v[148:151], v[216:219], v[28:31]
	v_mfma_f32_16x16x32_bf16 v[24:27], v[168:171], v[216:219], v[24:27]
	v_mfma_f32_16x16x32_bf16 v[12:15], v[148:151], v[224:227], v[12:15]
	v_mfma_f32_16x16x32_bf16 v[8:11], v[168:171], v[224:227], v[8:11]
	s_setprio 0
	s_setprio 1
	v_mfma_f32_16x16x32_bf16 v[52:55], v[172:175], v[190:193], 0
	v_mfma_f32_16x16x32_bf16 v[48:51], v[182:185], v[190:193], 0
	s_mov_b32 m0, s57
	s_nop 0
	global_load_lds_dwordx4 v[230:231], off
	v_mfma_f32_16x16x32_bf16 v[36:39], v[172:175], v[198:201], 0
	v_mfma_f32_16x16x32_bf16 v[32:35], v[182:185], v[198:201], 0
	v_mfma_f32_16x16x32_bf16 v[20:23], v[172:175], v[212:215], 0
	v_mfma_f32_16x16x32_bf16 v[16:19], v[182:185], v[212:215], 0
	v_mfma_f32_16x16x32_bf16 v[4:7], v[172:175], v[220:223], 0
	v_mfma_f32_16x16x32_bf16 v[0:3], v[182:185], v[220:223], 0
	v_mfma_f32_16x16x32_bf16 v[52:55], v[176:179], v[194:197], v[52:55]
	v_mfma_f32_16x16x32_bf16 v[48:51], v[186:189], v[194:197], v[48:51]
	v_mfma_f32_16x16x32_bf16 v[36:39], v[176:179], v[208:211], v[36:39]
	v_mfma_f32_16x16x32_bf16 v[32:35], v[186:189], v[208:211], v[32:35]
	v_mfma_f32_16x16x32_bf16 v[20:23], v[176:179], v[216:219], v[20:23]
	v_mfma_f32_16x16x32_bf16 v[16:19], v[186:189], v[216:219], v[16:19]
	v_mfma_f32_16x16x32_bf16 v[4:7], v[176:179], v[224:227], v[4:7]
	v_mfma_f32_16x16x32_bf16 v[0:3], v[186:189], v[224:227], v[0:3]
	s_setprio 0
	s_barrier
	s_add_i32 s3, 0, 0x18000
	v_add_u32_e32 v159, s3, v153
	s_add_i32 s33, 0, 0x1c000
	ds_read_b128 v[144:147], v159
	ds_read_b128 v[148:151], v159 offset:1024
	ds_read_b128 v[160:163], v159 offset:2048
	ds_read_b128 v[168:171], v159 offset:3072
	v_add_u32_e32 v159, s33, v153
	ds_read_b128 v[172:175], v159
	ds_read_b128 v[176:179], v159 offset:1024
	ds_read_b128 v[182:185], v159 offset:2048
	ds_read_b128 v[186:189], v159 offset:3072
	s_add_u32 s14, s54, 0x40000
	s_addc_u32 s15, s55, 0
	s_mov_b32 m0, s58
	v_lshl_add_u64 v[232:233], s[14:15], 0, v[134:135]
	ds_read_b128 v[190:193], v157 offset:32768
	ds_read_b128 v[194:197], v157 offset:33792
	ds_read_b128 v[198:201], v157 offset:34816
	ds_read_b128 v[208:211], v157 offset:35840
	ds_read_b128 v[212:215], v157 offset:36864
	ds_read_b128 v[216:219], v157 offset:37888
	ds_read_b128 v[220:223], v157 offset:38912
	ds_read_b128 v[224:227], v157 offset:39936
	global_load_lds_dwordx4 v[232:233], off
	v_lshl_add_u64 v[232:233], s[14:15], 0, v[130:131]
	s_mov_b32 m0, s59
	s_nop 0
	global_load_lds_dwordx4 v[232:233], off
	s_waitcnt vmcnt(8)
	s_waitcnt lgkmcnt(0)
	s_barrier
	s_setprio 1
	s_waitcnt lgkmcnt(0)
	v_mfma_f32_16x16x32_bf16 v[124:127], v[144:147], v[190:193], v[124:127]
	v_mfma_f32_16x16x32_bf16 v[120:123], v[160:163], v[190:193], v[120:123]
	v_mfma_f32_16x16x32_bf16 v[108:111], v[144:147], v[198:201], v[108:111]
	v_mfma_f32_16x16x32_bf16 v[104:107], v[160:163], v[198:201], v[104:107]
	v_mfma_f32_16x16x32_bf16 v[92:95], v[144:147], v[212:215], v[92:95]
	v_mfma_f32_16x16x32_bf16 v[88:91], v[160:163], v[212:215], v[88:91]
	v_mfma_f32_16x16x32_bf16 v[76:79], v[144:147], v[220:223], v[76:79]
	v_mfma_f32_16x16x32_bf16 v[72:75], v[160:163], v[220:223], v[72:75]
	v_mfma_f32_16x16x32_bf16 v[124:127], v[148:151], v[194:197], v[124:127]
	v_mfma_f32_16x16x32_bf16 v[120:123], v[168:171], v[194:197], v[120:123]
	v_mfma_f32_16x16x32_bf16 v[108:111], v[148:151], v[208:211], v[108:111]
	v_mfma_f32_16x16x32_bf16 v[104:107], v[168:171], v[208:211], v[104:107]
	v_mfma_f32_16x16x32_bf16 v[92:95], v[148:151], v[216:219], v[92:95]
	v_mfma_f32_16x16x32_bf16 v[88:91], v[168:171], v[216:219], v[88:91]
	v_mfma_f32_16x16x32_bf16 v[76:79], v[148:151], v[224:227], v[76:79]
	v_mfma_f32_16x16x32_bf16 v[72:75], v[168:171], v[224:227], v[72:75]
	s_setprio 0
	s_setprio 1
	v_mfma_f32_16x16x32_bf16 v[116:119], v[172:175], v[190:193], v[116:119]
	v_mfma_f32_16x16x32_bf16 v[112:115], v[182:185], v[190:193], v[112:115]
	v_mfma_f32_16x16x32_bf16 v[100:103], v[172:175], v[198:201], v[100:103]
	v_mfma_f32_16x16x32_bf16 v[96:99], v[182:185], v[198:201], v[96:99]
	v_mfma_f32_16x16x32_bf16 v[84:87], v[172:175], v[212:215], v[84:87]
	v_mfma_f32_16x16x32_bf16 v[80:83], v[182:185], v[212:215], v[80:83]
	v_mfma_f32_16x16x32_bf16 v[68:71], v[172:175], v[220:223], v[68:71]
	v_mfma_f32_16x16x32_bf16 v[64:67], v[182:185], v[220:223], v[64:67]
	v_mfma_f32_16x16x32_bf16 v[116:119], v[176:179], v[194:197], v[116:119]
	v_mfma_f32_16x16x32_bf16 v[112:115], v[186:189], v[194:197], v[112:115]
	v_mfma_f32_16x16x32_bf16 v[100:103], v[176:179], v[208:211], v[100:103]
	v_mfma_f32_16x16x32_bf16 v[96:99], v[186:189], v[208:211], v[96:99]
	v_mfma_f32_16x16x32_bf16 v[84:87], v[176:179], v[216:219], v[84:87]
	v_mfma_f32_16x16x32_bf16 v[80:83], v[186:189], v[216:219], v[80:83]
	v_mfma_f32_16x16x32_bf16 v[68:71], v[176:179], v[224:227], v[68:71]
	v_mfma_f32_16x16x32_bf16 v[64:67], v[186:189], v[224:227], v[64:67]
	s_setprio 0
	s_barrier
; #define PG8_STAGE(bufoff, gbase, voff) do { _Pragma("unroll") for (int _i = 0; _i < 2; ++_i) \
;         __builtin_amdgcn_global_load_lds((const unsigned*)((const char*)(gbase) + (voff)[_i]), (PG8_LAS unsigned*)(lds + (bufoff) + ldsw + _i * 8192), 16, 0, 0); } while (0)
; #define PG8_LDA(dst, b, h) do { _Pragma("unroll") for (int m = 0; m < 4; ++m) _Pragma("unroll") for (int k = 0; k < 2; ++k) dst[m][k] = *(const PG8_LAS bf16x8*)(lds + PG8_SA(b, h) + aoff + m * 2048 + k * 1024); } while (0)
; #define PG8_LDB(dst, b, h) do { _Pragma("unroll") for (int n = 0; n < 2; ++n) _Pragma("unroll") for (int k = 0; k < 2; ++k) dst[n][k] = *(const PG8_LAS bf16x8*)(lds + PG8_SB(b, h) + boff + n * 2048 + k * 1024); } while (0)
; #define PG8_MMA(ai, bj, At, Bt) do { __builtin_amdgcn_s_setprio(1); _Pragma("unroll") for (int m = 0; m < 4; ++m) _Pragma("unroll") for (int n = 0; n < 2; ++n) _Pragma("unroll") for (int k = 0; k < 2; ++k) \
;         acc[ai][bj][m][n] = __builtin_amdgcn_mfma_f32_16x16x32_bf16(Bt[n][k], At[m][k], acc[ai][bj][m][n], 0, 0, 0); __builtin_amdgcn_s_setprio(0); } while (0)
; #define PG8_WAIT_V(n) asm volatile("s_waitcnt vmcnt(" #n ")" ::: "memory")
; #define PG8_BAR __builtin_amdgcn_s_barrier()
; template <class Epi, class Sched, bool ALIGN_EPI = false, bool SP2 = false>
; __device__ __forceinline__ void gemm_phase(PG8_LAS unsigned char* lds, const Gemm g, const Sched& S, const Epi& E) {
;     ...
;         for (int t = 0; t < nt; t += 2) {
;             const bool last = (t == nt - 2);
;             const char* a1 = cA + (size_t)(t + 1) * kstep;
;             const char* a2 = last ? nA : cA + (size_t)(t + 2) * kstep; const char* b2 = last ? nB : cB + (size_t)(t + 2) * kstep;
;             const char* a3 = a2 + kstep; const char* b3 = b2 + kstep;
;             if (last && has_next) S.a_ready(nxt);
;             if constexpr (SP2) {
;             PG8_LDB(B0, 0, 0); PG8_LDB(B1, 0, 1); PG8_SCHED; PG8_LDA(At, 0, 0); PG8_STAGE(PG8_SA(1, 1), a1 + hstep, voffA);
;             PG8_WAIT_V(8); PG8_WAIT_L(0); PG8_BAR; PG8_MMA(0, 0, At, B0); PG8_MMA(0, 1, At, B1); PG8_BAR; PG8_SCHED;
;     ...
;             PG8_LDA(At, 1, 1); PG8_STAGE(PG8_SB(1, 0), b3, voffB); PG8_STAGE(PG8_SB(1, 1), b3 + hstep, voffB); PG8_STAGE(PG8_SA(1, 0), a3, voffA);
;             PG8_WAIT_V(8); PG8_WAIT_L(0); PG8_BAR; PG8_MMA(1, 0, At, B0); PG8_MMA(1, 1, At, B1); PG8_BAR; PG8_SCHED;
	s_add_i32 s3, s3, s43
	v_lshl_add_u64 v[164:165], v[164:165], 0, s[10:11]
	s_mov_b32 m0, s3
	ds_read_b128 v[190:193], v157 offset:49152
	ds_read_b128 v[194:197], v157 offset:50176
	ds_read_b128 v[198:201], v157 offset:51200
	ds_read_b128 v[208:211], v157 offset:52224
	ds_read_b128 v[212:215], v157 offset:53248
	ds_read_b128 v[216:219], v157 offset:54272
	ds_read_b128 v[220:223], v157 offset:55296
	ds_read_b128 v[224:227], v157 offset:56320
	global_load_lds_dwordx4 v[164:165], off
	s_add_i32 m0, s3, 0x2000
	s_add_u32 s14, s50, 0x40080
	v_lshl_add_u64 v[164:165], v[202:203], 0, s[10:11]
	s_addc_u32 s15, s51, 0
	s_add_i32 s3, s33, s43
	global_load_lds_dwordx4 v[164:165], off
	v_lshl_add_u64 v[164:165], s[14:15], 0, v[132:133]
	s_mov_b32 m0, s3
	s_nop 0
	global_load_lds_dwordx4 v[164:165], off
	v_lshl_add_u64 v[164:165], s[14:15], 0, v[128:129]
	s_add_i32 m0, s3, 0x2000
	s_nop 0
	global_load_lds_dwordx4 v[164:165], off
	s_waitcnt vmcnt(6)
	s_waitcnt lgkmcnt(0)
	s_barrier
	s_setprio 1
	s_waitcnt lgkmcnt(0)
	v_mfma_f32_16x16x32_bf16 v[60:63], v[144:147], v[190:193], v[60:63]
	v_mfma_f32_16x16x32_bf16 v[56:59], v[160:163], v[190:193], v[56:59]
	v_mfma_f32_16x16x32_bf16 v[44:47], v[144:147], v[198:201], v[44:47]
	v_mfma_f32_16x16x32_bf16 v[40:43], v[160:163], v[198:201], v[40:43]
	v_mfma_f32_16x16x32_bf16 v[28:31], v[144:147], v[212:215], v[28:31]
	v_mfma_f32_16x16x32_bf16 v[24:27], v[160:163], v[212:215], v[24:27]
	v_lshl_add_u64 v[164:165], v[228:229], 0, s[10:11]
	s_mov_b32 m0, s61
	s_nop 0
	global_load_lds_dwordx4 v[164:165], off
	v_mfma_f32_16x16x32_bf16 v[12:15], v[144:147], v[220:223], v[12:15]
	v_mfma_f32_16x16x32_bf16 v[8:11], v[160:163], v[220:223], v[8:11]
	v_mfma_f32_16x16x32_bf16 v[60:63], v[148:151], v[194:197], v[60:63]
	v_mfma_f32_16x16x32_bf16 v[56:59], v[168:171], v[194:197], v[56:59]
	v_mfma_f32_16x16x32_bf16 v[44:47], v[148:151], v[208:211], v[44:47]
	v_mfma_f32_16x16x32_bf16 v[40:43], v[168:171], v[208:211], v[40:43]
	v_mfma_f32_16x16x32_bf16 v[28:31], v[148:151], v[216:219], v[28:31]
	v_mfma_f32_16x16x32_bf16 v[24:27], v[168:171], v[216:219], v[24:27]
	v_mfma_f32_16x16x32_bf16 v[12:15], v[148:151], v[224:227], v[12:15]
	v_mfma_f32_16x16x32_bf16 v[8:11], v[168:171], v[224:227], v[8:11]
	s_setprio 0
	s_setprio 1
	v_mfma_f32_16x16x32_bf16 v[52:55], v[172:175], v[190:193], v[52:55]
	v_mfma_f32_16x16x32_bf16 v[48:51], v[182:185], v[190:193], v[48:51]
	v_lshl_add_u64 v[164:165], v[230:231], 0, s[10:11]
	s_mov_b32 m0, s62
	s_nop 0
	global_load_lds_dwordx4 v[164:165], off
	v_mfma_f32_16x16x32_bf16 v[36:39], v[172:175], v[198:201], v[36:39]
	v_mfma_f32_16x16x32_bf16 v[32:35], v[182:185], v[198:201], v[32:35]
	v_mfma_f32_16x16x32_bf16 v[20:23], v[172:175], v[212:215], v[20:23]
	v_mfma_f32_16x16x32_bf16 v[16:19], v[182:185], v[212:215], v[16:19]
	v_mfma_f32_16x16x32_bf16 v[4:7], v[172:175], v[220:223], v[4:7]
	v_mfma_f32_16x16x32_bf16 v[0:3], v[182:185], v[220:223], v[0:3]
	v_mfma_f32_16x16x32_bf16 v[52:55], v[176:179], v[194:197], v[52:55]
	v_mfma_f32_16x16x32_bf16 v[48:51], v[186:189], v[194:197], v[48:51]
	v_mfma_f32_16x16x32_bf16 v[36:39], v[176:179], v[208:211], v[36:39]
	v_mfma_f32_16x16x32_bf16 v[32:35], v[186:189], v[208:211], v[32:35]
	v_mfma_f32_16x16x32_bf16 v[20:23], v[176:179], v[216:219], v[20:23]
	v_mfma_f32_16x16x32_bf16 v[16:19], v[186:189], v[216:219], v[16:19]
	v_mfma_f32_16x16x32_bf16 v[4:7], v[176:179], v[224:227], v[4:7]
	v_mfma_f32_16x16x32_bf16 v[0:3], v[186:189], v[224:227], v[0:3]
	s_setprio 0
	s_barrier
	s_add_i32 s89, s89, 2
	s_add_u32 s48, s48, 0x100
	s_addc_u32 s49, s49, 0
	s_add_u32 s87, s87, 0x100
	s_addc_u32 s88, s88, 0
.LBB0_191:
	ds_read_b128 v[144:147], v155
	ds_read_b128 v[148:151], v155 offset:1024
	ds_read_b128 v[160:163], v155 offset:2048
	ds_read_b128 v[168:171], v155 offset:3072
	ds_read_b128 v[172:175], v156
	ds_read_b128 v[176:179], v156 offset:1024
	ds_read_b128 v[182:185], v156 offset:2048
	ds_read_b128 v[186:189], v156 offset:3072
	s_add_u32 s3, s48, 0xfffc0080
	s_addc_u32 s14, s49, -1
	s_cmp_eq_u32 s89, 12
	s_cselect_b32 s55, s27, s14
	s_cselect_b32 s54, s67, s3
	s_cselect_b32 s51, s25, s88
	s_cselect_b32 s50, s86, s87
	v_lshl_add_u64 v[164:165], s[48:49], 0, v[136:137]
	s_add_i32 m0, s45, 0xc000
	ds_read_b128 v[190:193], v157
	ds_read_b128 v[194:197], v157 offset:1024
	ds_read_b128 v[198:201], v157 offset:2048
	ds_read_b128 v[208:211], v157 offset:3072
	ds_read_b128 v[212:215], v157 offset:4096
	ds_read_b128 v[216:219], v157 offset:5120
	ds_read_b128 v[220:223], v157 offset:6144
	ds_read_b128 v[224:227], v157 offset:7168
	global_load_lds_dwordx4 v[164:165], off
	v_lshl_add_u64 v[164:165], s[48:49], 0, v[138:139]
	s_add_i32 m0, s45, 0xe000
	s_nop 0
	global_load_lds_dwordx4 v[164:165], off
	s_waitcnt vmcnt(8)
	s_waitcnt lgkmcnt(0)
	s_barrier
; #define PG8_STAGE(bufoff, gbase, voff) do { _Pragma("unroll") for (int _i = 0; _i < 2; ++_i) \
;         __builtin_amdgcn_global_load_lds((const unsigned*)((const char*)(gbase) + (voff)[_i]), (PG8_LAS unsigned*)(lds + (bufoff) + ldsw + _i * 8192), 16, 0, 0); } while (0)
; #define PG8_LDA(dst, b, h) do { _Pragma("unroll") for (int m = 0; m < 4; ++m) _Pragma("unroll") for (int k = 0; k < 2; ++k) dst[m][k] = *(const PG8_LAS bf16x8*)(lds + PG8_SA(b, h) + aoff + m * 2048 + k * 1024); } while (0)
; #define PG8_LDB(dst, b, h) do { _Pragma("unroll") for (int n = 0; n < 2; ++n) _Pragma("unroll") for (int k = 0; k < 2; ++k) dst[n][k] = *(const PG8_LAS bf16x8*)(lds + PG8_SB(b, h) + boff + n * 2048 + k * 1024); } while (0)
; #define PG8_MMA(ai, bj, At, Bt) do { __builtin_amdgcn_s_setprio(1); _Pragma("unroll") for (int m = 0; m < 4; ++m) _Pragma("unroll") for (int n = 0; n < 2; ++n) _Pragma("unroll") for (int k = 0; k < 2; ++k) \
;         acc[ai][bj][m][n] = __builtin_amdgcn_mfma_f32_16x16x32_bf16(Bt[n][k], At[m][k], acc[ai][bj][m][n], 0, 0, 0); __builtin_amdgcn_s_setprio(0); } while (0)
; #define PG8_WAIT_V(n) asm volatile("s_waitcnt vmcnt(" #n ")" ::: "memory")
; #define PG8_WAIT_L(n) asm volatile("s_waitcnt lgkmcnt(" #n ")" ::: "memory")
; #define PG8_BAR __builtin_amdgcn_s_barrier()
; #define PG8_SCHED __builtin_amdgcn_sched_barrier(0)
; template <class Epi, class Sched, bool ALIGN_EPI = false, bool SP2 = false>
; __device__ __forceinline__ void gemm_phase(PG8_LAS unsigned char* lds, const Gemm g, const Sched& S, const Epi& E) {
;     ...
;             PG8_LDB(B0, 0, 0); PG8_LDB(B1, 0, 1); PG8_SCHED; PG8_LDA(At, 0, 0); PG8_STAGE(PG8_SA(1, 1), a1 + hstep, voffA);
;             PG8_WAIT_V(8); PG8_WAIT_L(0); PG8_BAR; PG8_MMA(0, 0, At, B0); PG8_MMA(0, 1, At, B1); PG8_BAR; PG8_SCHED;
;             PG8_LDA(At, 0, 1); PG8_STAGE(PG8_SB(0, 0), b2, voffB); PG8_STAGE(PG8_SB(0, 1), b2 + hstep, voffB); PG8_STAGE(PG8_SA(0, 0), a2, voffA);
;             PG8_WAIT_V(8); PG8_WAIT_L(0); PG8_BAR; PG8_MMA(1, 0, At, B0); PG8_MMA(1, 1, At, B1); PG8_BAR; PG8_SCHED;
	s_setprio 1
	s_waitcnt lgkmcnt(0)
	v_mfma_f32_16x16x32_bf16 v[124:127], v[144:147], v[190:193], v[124:127]
	v_mfma_f32_16x16x32_bf16 v[120:123], v[160:163], v[190:193], v[120:123]
	v_mfma_f32_16x16x32_bf16 v[108:111], v[144:147], v[198:201], v[108:111]
	v_mfma_f32_16x16x32_bf16 v[104:107], v[160:163], v[198:201], v[104:107]
	v_mfma_f32_16x16x32_bf16 v[92:95], v[144:147], v[212:215], v[92:95]
	v_mfma_f32_16x16x32_bf16 v[88:91], v[160:163], v[212:215], v[88:91]
	v_mfma_f32_16x16x32_bf16 v[76:79], v[144:147], v[220:223], v[76:79]
	v_mfma_f32_16x16x32_bf16 v[72:75], v[160:163], v[220:223], v[72:75]
	v_mfma_f32_16x16x32_bf16 v[124:127], v[148:151], v[194:197], v[124:127]
	v_mfma_f32_16x16x32_bf16 v[120:123], v[168:171], v[194:197], v[120:123]
	v_mfma_f32_16x16x32_bf16 v[108:111], v[148:151], v[208:211], v[108:111]
	v_mfma_f32_16x16x32_bf16 v[104:107], v[168:171], v[208:211], v[104:107]
	v_mfma_f32_16x16x32_bf16 v[92:95], v[148:151], v[216:219], v[92:95]
	v_mfma_f32_16x16x32_bf16 v[88:91], v[168:171], v[216:219], v[88:91]
	v_mfma_f32_16x16x32_bf16 v[76:79], v[148:151], v[224:227], v[76:79]
	v_mfma_f32_16x16x32_bf16 v[72:75], v[168:171], v[224:227], v[72:75]
	s_setprio 0
	s_setprio 1
	v_mfma_f32_16x16x32_bf16 v[116:119], v[172:175], v[190:193], v[116:119]
	v_mfma_f32_16x16x32_bf16 v[112:115], v[182:185], v[190:193], v[112:115]
	v_mfma_f32_16x16x32_bf16 v[100:103], v[172:175], v[198:201], v[100:103]
	v_mfma_f32_16x16x32_bf16 v[96:99], v[182:185], v[198:201], v[96:99]
	v_mfma_f32_16x16x32_bf16 v[84:87], v[172:175], v[212:215], v[84:87]
	v_mfma_f32_16x16x32_bf16 v[80:83], v[182:185], v[212:215], v[80:83]
	v_mfma_f32_16x16x32_bf16 v[68:71], v[172:175], v[220:223], v[68:71]
	v_mfma_f32_16x16x32_bf16 v[64:67], v[182:185], v[220:223], v[64:67]
	v_mfma_f32_16x16x32_bf16 v[116:119], v[176:179], v[194:197], v[116:119]
	v_mfma_f32_16x16x32_bf16 v[112:115], v[186:189], v[194:197], v[112:115]
	v_mfma_f32_16x16x32_bf16 v[100:103], v[176:179], v[208:211], v[100:103]
	v_mfma_f32_16x16x32_bf16 v[96:99], v[186:189], v[208:211], v[96:99]
	v_mfma_f32_16x16x32_bf16 v[84:87], v[176:179], v[216:219], v[84:87]
	v_mfma_f32_16x16x32_bf16 v[80:83], v[186:189], v[216:219], v[80:83]
	v_mfma_f32_16x16x32_bf16 v[68:71], v[176:179], v[224:227], v[68:71]
	v_mfma_f32_16x16x32_bf16 v[64:67], v[186:189], v[224:227], v[64:67]
	s_setprio 0
	s_barrier
	s_add_i32 s3, s63, s43
	v_lshl_add_u64 v[164:165], s[50:51], 0, v[132:133]
	s_mov_b32 m0, s3
	ds_read_b128 v[190:193], v157 offset:16384
	ds_read_b128 v[194:197], v157 offset:17408
	ds_read_b128 v[198:201], v157 offset:18432
	ds_read_b128 v[208:211], v157 offset:19456
	ds_read_b128 v[212:215], v157 offset:20480
	ds_read_b128 v[216:219], v157 offset:21504
	ds_read_b128 v[220:223], v157 offset:22528
	ds_read_b128 v[224:227], v157 offset:23552
	global_load_lds_dwordx4 v[164:165], off
	s_add_i32 m0, s3, 0x2000
	s_add_u32 s14, s50, 0x40000
	v_lshl_add_u64 v[202:203], s[50:51], 0, v[128:129]
	s_addc_u32 s15, s51, 0
	s_add_i32 s3, s64, s43
	global_load_lds_dwordx4 v[202:203], off
	v_lshl_add_u64 v[228:229], s[14:15], 0, v[132:133]
	s_mov_b32 m0, s3
	v_lshl_add_u64 v[230:231], s[54:55], 0, v[130:131]
	global_load_lds_dwordx4 v[228:229], off
	v_lshl_add_u64 v[228:229], s[14:15], 0, v[128:129]
	s_add_i32 m0, s3, 0x2000
	s_nop 0
	global_load_lds_dwordx4 v[228:229], off
	s_waitcnt vmcnt(6)
	s_waitcnt lgkmcnt(0)
	s_barrier
	s_setprio 1
	s_waitcnt lgkmcnt(0)
	v_mfma_f32_16x16x32_bf16 v[60:63], v[144:147], v[190:193], v[60:63]
	v_mfma_f32_16x16x32_bf16 v[56:59], v[160:163], v[190:193], v[56:59]
	v_mfma_f32_16x16x32_bf16 v[44:47], v[144:147], v[198:201], v[44:47]
	v_mfma_f32_16x16x32_bf16 v[40:43], v[160:163], v[198:201], v[40:43]
	v_mfma_f32_16x16x32_bf16 v[28:31], v[144:147], v[212:215], v[28:31]
	v_mfma_f32_16x16x32_bf16 v[24:27], v[160:163], v[212:215], v[24:27]
	v_lshl_add_u64 v[228:229], s[54:55], 0, v[134:135]
	s_mov_b32 m0, s45
	s_nop 0
	global_load_lds_dwordx4 v[228:229], off
	v_mfma_f32_16x16x32_bf16 v[12:15], v[144:147], v[220:223], v[12:15]
	v_mfma_f32_16x16x32_bf16 v[8:11], v[160:163], v[220:223], v[8:11]
	v_mfma_f32_16x16x32_bf16 v[60:63], v[148:151], v[194:197], v[60:63]
	v_mfma_f32_16x16x32_bf16 v[56:59], v[168:171], v[194:197], v[56:59]
	v_mfma_f32_16x16x32_bf16 v[44:47], v[148:151], v[208:211], v[44:47]
	v_mfma_f32_16x16x32_bf16 v[40:43], v[168:171], v[208:211], v[40:43]
	v_mfma_f32_16x16x32_bf16 v[28:31], v[148:151], v[216:219], v[28:31]
	v_mfma_f32_16x16x32_bf16 v[24:27], v[168:171], v[216:219], v[24:27]
	v_mfma_f32_16x16x32_bf16 v[12:15], v[148:151], v[224:227], v[12:15]
	v_mfma_f32_16x16x32_bf16 v[8:11], v[168:171], v[224:227], v[8:11]
	s_setprio 0
	s_setprio 1
	v_mfma_f32_16x16x32_bf16 v[52:55], v[172:175], v[190:193], v[52:55]
	v_mfma_f32_16x16x32_bf16 v[48:51], v[182:185], v[190:193], v[48:51]
	s_mov_b32 m0, s57
	s_nop 0
	global_load_lds_dwordx4 v[230:231], off
	v_mfma_f32_16x16x32_bf16 v[36:39], v[172:175], v[198:201], v[36:39]
	v_mfma_f32_16x16x32_bf16 v[32:35], v[182:185], v[198:201], v[32:35]
	v_mfma_f32_16x16x32_bf16 v[20:23], v[172:175], v[212:215], v[20:23]
	v_mfma_f32_16x16x32_bf16 v[16:19], v[182:185], v[212:215], v[16:19]
	v_mfma_f32_16x16x32_bf16 v[4:7], v[172:175], v[220:223], v[4:7]
	v_mfma_f32_16x16x32_bf16 v[0:3], v[182:185], v[220:223], v[0:3]
	v_mfma_f32_16x16x32_bf16 v[52:55], v[176:179], v[194:197], v[52:55]
	v_mfma_f32_16x16x32_bf16 v[48:51], v[186:189], v[194:197], v[48:51]
	v_mfma_f32_16x16x32_bf16 v[36:39], v[176:179], v[208:211], v[36:39]
	v_mfma_f32_16x16x32_bf16 v[32:35], v[186:189], v[208:211], v[32:35]
	v_mfma_f32_16x16x32_bf16 v[20:23], v[176:179], v[216:219], v[20:23]
	v_mfma_f32_16x16x32_bf16 v[16:19], v[186:189], v[216:219], v[16:19]
	v_mfma_f32_16x16x32_bf16 v[4:7], v[176:179], v[224:227], v[4:7]
	v_mfma_f32_16x16x32_bf16 v[0:3], v[186:189], v[224:227], v[0:3]
	s_setprio 0
	s_barrier
; #define PG8_STAGE(bufoff, gbase, voff) do { _Pragma("unroll") for (int _i = 0; _i < 2; ++_i) \
;         __builtin_amdgcn_global_load_lds((const unsigned*)((const char*)(gbase) + (voff)[_i]), (PG8_LAS unsigned*)(lds + (bufoff) + ldsw + _i * 8192), 16, 0, 0); } while (0)
; #define PG8_LDA(dst, b, h) do { _Pragma("unroll") for (int m = 0; m < 4; ++m) _Pragma("unroll") for (int k = 0; k < 2; ++k) dst[m][k] = *(const PG8_LAS bf16x8*)(lds + PG8_SA(b, h) + aoff + m * 2048 + k * 1024); } while (0)
; #define PG8_LDB(dst, b, h) do { _Pragma("unroll") for (int n = 0; n < 2; ++n) _Pragma("unroll") for (int k = 0; k < 2; ++k) dst[n][k] = *(const PG8_LAS bf16x8*)(lds + PG8_SB(b, h) + boff + n * 2048 + k * 1024); } while (0)
; #define PG8_MMA(ai, bj, At, Bt) do { __builtin_amdgcn_s_setprio(1); _Pragma("unroll") for (int m = 0; m < 4; ++m) _Pragma("unroll") for (int n = 0; n < 2; ++n) _Pragma("unroll") for (int k = 0; k < 2; ++k) \
;         acc[ai][bj][m][n] = __builtin_amdgcn_mfma_f32_16x16x32_bf16(Bt[n][k], At[m][k], acc[ai][bj][m][n], 0, 0, 0); __builtin_amdgcn_s_setprio(0); } while (0)
; #define PG8_WAIT_V(n) asm volatile("s_waitcnt vmcnt(" #n ")" ::: "memory")
; #define PG8_WAIT_L(n) asm volatile("s_waitcnt lgkmcnt(" #n ")" ::: "memory")
; #define PG8_BAR __builtin_amdgcn_s_barrier()
; #define PG8_SCHED __builtin_amdgcn_sched_barrier(0)
; template <class Epi, class Sched, bool ALIGN_EPI = false, bool SP2 = false>
; __device__ __forceinline__ void gemm_phase(PG8_LAS unsigned char* lds, const Gemm g, const Sched& S, const Epi& E) {
;     ...
;             PG8_LDB(B0, 1, 0); PG8_LDB(B1, 1, 1); PG8_SCHED; PG8_LDA(At, 1, 0); PG8_STAGE(PG8_SA(0, 1), a2 + hstep, voffA);
;             PG8_WAIT_V(8); PG8_WAIT_L(0); PG8_BAR; PG8_MMA(0, 0, At, B0); PG8_MMA(0, 1, At, B1); PG8_BAR; PG8_SCHED;
	s_add_i32 s3, 0, 0x18000
	v_add_u32_e32 v159, s3, v153
	s_add_i32 s33, 0, 0x1c000
	ds_read_b128 v[144:147], v159
	ds_read_b128 v[148:151], v159 offset:1024
	ds_read_b128 v[160:163], v159 offset:2048
	ds_read_b128 v[168:171], v159 offset:3072
	v_add_u32_e32 v159, s33, v153
	ds_read_b128 v[172:175], v159
	ds_read_b128 v[176:179], v159 offset:1024
	ds_read_b128 v[182:185], v159 offset:2048
	ds_read_b128 v[186:189], v159 offset:3072
	s_add_u32 s14, s54, 0x40000
	s_addc_u32 s15, s55, 0
	s_mov_b32 m0, s58
	v_lshl_add_u64 v[232:233], s[14:15], 0, v[134:135]
	ds_read_b128 v[190:193], v157 offset:32768
	ds_read_b128 v[194:197], v157 offset:33792
	ds_read_b128 v[198:201], v157 offset:34816
	ds_read_b128 v[208:211], v157 offset:35840
	ds_read_b128 v[212:215], v157 offset:36864
	ds_read_b128 v[216:219], v157 offset:37888
	ds_read_b128 v[220:223], v157 offset:38912
	ds_read_b128 v[224:227], v157 offset:39936
	global_load_lds_dwordx4 v[232:233], off
	v_lshl_add_u64 v[232:233], s[14:15], 0, v[130:131]
	s_mov_b32 m0, s59
	s_nop 0
	global_load_lds_dwordx4 v[232:233], off
	s_waitcnt vmcnt(8)
	s_waitcnt lgkmcnt(0)
	s_barrier
	s_setprio 1
	s_waitcnt lgkmcnt(0)
	v_mfma_f32_16x16x32_bf16 v[124:127], v[144:147], v[190:193], v[124:127]
	v_mfma_f32_16x16x32_bf16 v[120:123], v[160:163], v[190:193], v[120:123]
	v_mfma_f32_16x16x32_bf16 v[108:111], v[144:147], v[198:201], v[108:111]
	v_mfma_f32_16x16x32_bf16 v[104:107], v[160:163], v[198:201], v[104:107]
	v_mfma_f32_16x16x32_bf16 v[92:95], v[144:147], v[212:215], v[92:95]
	v_mfma_f32_16x16x32_bf16 v[88:91], v[160:163], v[212:215], v[88:91]
	v_mfma_f32_16x16x32_bf16 v[76:79], v[144:147], v[220:223], v[76:79]
	v_mfma_f32_16x16x32_bf16 v[72:75], v[160:163], v[220:223], v[72:75]
	v_mfma_f32_16x16x32_bf16 v[124:127], v[148:151], v[194:197], v[124:127]
	v_mfma_f32_16x16x32_bf16 v[120:123], v[168:171], v[194:197], v[120:123]
	v_mfma_f32_16x16x32_bf16 v[108:111], v[148:151], v[208:211], v[108:111]
	v_mfma_f32_16x16x32_bf16 v[104:107], v[168:171], v[208:211], v[104:107]
	v_mfma_f32_16x16x32_bf16 v[92:95], v[148:151], v[216:219], v[92:95]
	v_mfma_f32_16x16x32_bf16 v[88:91], v[168:171], v[216:219], v[88:91]
	v_mfma_f32_16x16x32_bf16 v[76:79], v[148:151], v[224:227], v[76:79]
	v_mfma_f32_16x16x32_bf16 v[72:75], v[168:171], v[224:227], v[72:75]
	s_setprio 0
	s_setprio 1
	v_mfma_f32_16x16x32_bf16 v[116:119], v[172:175], v[190:193], v[116:119]
	v_mfma_f32_16x16x32_bf16 v[112:115], v[182:185], v[190:193], v[112:115]
	v_mfma_f32_16x16x32_bf16 v[100:103], v[172:175], v[198:201], v[100:103]
	v_mfma_f32_16x16x32_bf16 v[96:99], v[182:185], v[198:201], v[96:99]
	v_mfma_f32_16x16x32_bf16 v[84:87], v[172:175], v[212:215], v[84:87]
	v_mfma_f32_16x16x32_bf16 v[80:83], v[182:185], v[212:215], v[80:83]
	v_mfma_f32_16x16x32_bf16 v[68:71], v[172:175], v[220:223], v[68:71]
	v_mfma_f32_16x16x32_bf16 v[64:67], v[182:185], v[220:223], v[64:67]
	v_mfma_f32_16x16x32_bf16 v[116:119], v[176:179], v[194:197], v[116:119]
	v_mfma_f32_16x16x32_bf16 v[112:115], v[186:189], v[194:197], v[112:115]
	v_mfma_f32_16x16x32_bf16 v[100:103], v[176:179], v[208:211], v[100:103]
	v_mfma_f32_16x16x32_bf16 v[96:99], v[186:189], v[208:211], v[96:99]
	v_mfma_f32_16x16x32_bf16 v[84:87], v[176:179], v[216:219], v[84:87]
	v_mfma_f32_16x16x32_bf16 v[80:83], v[186:189], v[216:219], v[80:83]
	v_mfma_f32_16x16x32_bf16 v[68:71], v[176:179], v[224:227], v[68:71]
	v_mfma_f32_16x16x32_bf16 v[64:67], v[186:189], v[224:227], v[64:67]
	s_setprio 0
	s_barrier
; #define PG8_STAGE(bufoff, gbase, voff) do { _Pragma("unroll") for (int _i = 0; _i < 2; ++_i) \
;         __builtin_amdgcn_global_load_lds((const unsigned*)((const char*)(gbase) + (voff)[_i]), (PG8_LAS unsigned*)(lds + (bufoff) + ldsw + _i * 8192), 16, 0, 0); } while (0)
; #define PG8_LDA(dst, b, h) do { _Pragma("unroll") for (int m = 0; m < 4; ++m) _Pragma("unroll") for (int k = 0; k < 2; ++k) dst[m][k] = *(const PG8_LAS bf16x8*)(lds + PG8_SA(b, h) + aoff + m * 2048 + k * 1024); } while (0)
; #define PG8_WAIT_V(n) asm volatile("s_waitcnt vmcnt(" #n ")" ::: "memory")
; template <class Epi, class Sched, bool ALIGN_EPI = false, bool SP2 = false>
; __device__ __forceinline__ void gemm_phase(PG8_LAS unsigned char* lds, const Gemm g, const Sched& S, const Epi& E) {
;     ...
;             PG8_LDA(At, 1, 1); PG8_STAGE(PG8_SB(1, 0), b3, voffB); PG8_STAGE(PG8_SB(1, 1), b3 + hstep, voffB); PG8_STAGE(PG8_SA(1, 0), a3, voffA);
;             PG8_WAIT_V(8); PG8_WAIT_L(0); PG8_BAR; PG8_MMA(1, 0, At, B0); PG8_MMA(1, 1, At, B1); PG8_BAR; PG8_SCHED;
;             } else {
;             PG8_LDB(B0, 0, 0); PG8_SCHED; PG8_LDA(At, 0, 0); PG8_STAGE(PG8_SA(1, 1), a1 + hstep, voffA);
;             PG8_WAIT_L(8); PG8_BAR; PG8_WAIT_L(0); PG8_MMA(0, 0, At, B0); PG8_BAR; PG8_SCHED;
;             PG8_LDB(B1, 0, 1); PG8_STAGE(PG8_SB(0, 0), b2, voffB);
;             PG8_BAR; PG8_WAIT_L(0); PG8_MMA(0, 1, At, B1); PG8_BAR;
;             PG8_LDA(At, 0, 1); PG8_STAGE(PG8_SA(0, 0), a2, voffA);
;             PG8_BAR; PG8_WAIT_L(0); PG8_MMA(1, 0, At, B0); PG8_BAR; PG8_SCHED;
;             PG8_STAGE(PG8_SB(0, 1), b2 + hstep, voffB);
;             PG8_WAIT_V(6); PG8_BAR; PG8_MMA(1, 1, At, B1); PG8_BAR;
;             PG8_LDB(B0, 1, 0); PG8_SCHED; PG8_LDA(At, 1, 0); PG8_STAGE(PG8_SA(0, 1), a2 + hstep, voffA);
;             PG8_WAIT_L(8); PG8_BAR; PG8_WAIT_L(0); PG8_MMA(0, 0, At, B0); PG8_BAR; PG8_SCHED;
;             PG8_LDB(B1, 1, 1); PG8_STAGE(PG8_SB(1, 0), b3, voffB);
;             PG8_BAR; PG8_WAIT_L(0); PG8_MMA(0, 1, At, B1); PG8_BAR;
;             PG8_LDA(At, 1, 1); PG8_STAGE(PG8_SA(1, 0), a3, voffA);
;             PG8_BAR; PG8_WAIT_L(0); PG8_MMA(1, 0, At, B0); PG8_BAR; PG8_SCHED;
;             PG8_STAGE(PG8_SB(1, 1), b3 + hstep, voffB);
;             PG8_WAIT_V(6); PG8_BAR; PG8_MMA(1, 1, At, B1); PG8_BAR;
;             }
;         }
;         if constexpr (ALIGN_EPI) { if (wr == 0) PG8_BAR; }
	s_add_i32 s3, s3, s43
	v_lshl_add_u64 v[164:165], v[164:165], 0, s[10:11]
	s_mov_b32 m0, s3
	ds_read_b128 v[190:193], v157 offset:49152
	ds_read_b128 v[194:197], v157 offset:50176
	ds_read_b128 v[198:201], v157 offset:51200
	ds_read_b128 v[208:211], v157 offset:52224
	ds_read_b128 v[212:215], v157 offset:53248
	ds_read_b128 v[216:219], v157 offset:54272
	ds_read_b128 v[220:223], v157 offset:55296
	ds_read_b128 v[224:227], v157 offset:56320
	global_load_lds_dwordx4 v[164:165], off
	s_add_i32 m0, s3, 0x2000
	s_add_u32 s14, s50, 0x40080
	v_lshl_add_u64 v[164:165], v[202:203], 0, s[10:11]
	s_addc_u32 s15, s51, 0
	s_add_i32 s3, s33, s43
	global_load_lds_dwordx4 v[164:165], off
	v_lshl_add_u64 v[164:165], s[14:15], 0, v[132:133]
	s_mov_b32 m0, s3
	s_nop 0
	global_load_lds_dwordx4 v[164:165], off
	v_lshl_add_u64 v[164:165], s[14:15], 0, v[128:129]
	s_add_i32 m0, s3, 0x2000
	s_nop 0
	global_load_lds_dwordx4 v[164:165], off
	s_waitcnt vmcnt(6)
	s_waitcnt lgkmcnt(0)
	s_barrier
	s_setprio 1
	s_waitcnt lgkmcnt(0)
	v_mfma_f32_16x16x32_bf16 v[60:63], v[144:147], v[190:193], v[60:63]
	v_mfma_f32_16x16x32_bf16 v[56:59], v[160:163], v[190:193], v[56:59]
	v_mfma_f32_16x16x32_bf16 v[44:47], v[144:147], v[198:201], v[44:47]
	v_mfma_f32_16x16x32_bf16 v[40:43], v[160:163], v[198:201], v[40:43]
	v_mfma_f32_16x16x32_bf16 v[28:31], v[144:147], v[212:215], v[28:31]
	v_mfma_f32_16x16x32_bf16 v[24:27], v[160:163], v[212:215], v[24:27]
	v_lshl_add_u64 v[164:165], v[228:229], 0, s[10:11]
	s_mov_b32 m0, s61
	s_nop 0
	global_load_lds_dwordx4 v[164:165], off
	v_mfma_f32_16x16x32_bf16 v[12:15], v[144:147], v[220:223], v[12:15]
	v_mfma_f32_16x16x32_bf16 v[8:11], v[160:163], v[220:223], v[8:11]
	v_mfma_f32_16x16x32_bf16 v[60:63], v[148:151], v[194:197], v[60:63]
	v_mfma_f32_16x16x32_bf16 v[56:59], v[168:171], v[194:197], v[56:59]
	v_mfma_f32_16x16x32_bf16 v[44:47], v[148:151], v[208:211], v[44:47]
	v_mfma_f32_16x16x32_bf16 v[40:43], v[168:171], v[208:211], v[40:43]
	v_mfma_f32_16x16x32_bf16 v[28:31], v[148:151], v[216:219], v[28:31]
	v_mfma_f32_16x16x32_bf16 v[24:27], v[168:171], v[216:219], v[24:27]
	v_mfma_f32_16x16x32_bf16 v[12:15], v[148:151], v[224:227], v[12:15]
	v_mfma_f32_16x16x32_bf16 v[8:11], v[168:171], v[224:227], v[8:11]
	s_setprio 0
	s_setprio 1
	v_mfma_f32_16x16x32_bf16 v[52:55], v[172:175], v[190:193], v[52:55]
	v_mfma_f32_16x16x32_bf16 v[48:51], v[182:185], v[190:193], v[48:51]
	v_lshl_add_u64 v[164:165], v[230:231], 0, s[10:11]
	s_mov_b32 m0, s62
	s_nop 0
	global_load_lds_dwordx4 v[164:165], off
	v_mfma_f32_16x16x32_bf16 v[36:39], v[172:175], v[198:201], v[36:39]
	v_mfma_f32_16x16x32_bf16 v[32:35], v[182:185], v[198:201], v[32:35]
	v_mfma_f32_16x16x32_bf16 v[20:23], v[172:175], v[212:215], v[20:23]
	v_mfma_f32_16x16x32_bf16 v[16:19], v[182:185], v[212:215], v[16:19]
	v_mfma_f32_16x16x32_bf16 v[4:7], v[172:175], v[220:223], v[4:7]
	v_mfma_f32_16x16x32_bf16 v[0:3], v[182:185], v[220:223], v[0:3]
	v_mfma_f32_16x16x32_bf16 v[52:55], v[176:179], v[194:197], v[52:55]
	v_mfma_f32_16x16x32_bf16 v[48:51], v[186:189], v[194:197], v[48:51]
	v_mfma_f32_16x16x32_bf16 v[36:39], v[176:179], v[208:211], v[36:39]
	v_mfma_f32_16x16x32_bf16 v[32:35], v[186:189], v[208:211], v[32:35]
	v_mfma_f32_16x16x32_bf16 v[20:23], v[176:179], v[216:219], v[20:23]
	v_mfma_f32_16x16x32_bf16 v[16:19], v[186:189], v[216:219], v[16:19]
	v_mfma_f32_16x16x32_bf16 v[4:7], v[176:179], v[224:227], v[4:7]
	v_mfma_f32_16x16x32_bf16 v[0:3], v[186:189], v[224:227], v[0:3]
	s_setprio 0
	s_barrier
	s_add_i32 s89, s89, 2
	s_add_u32 s48, s48, 0x100
	s_addc_u32 s49, s49, 0
	s_add_u32 s87, s87, 0x100
	s_addc_u32 s88, s88, 0
	s_cmp_gt_u32 s89, 13
	s_cbranch_scc0 .LBB0_191
	v_lshl_add_u32 v144, s44, 8, v152
	v_ashrrev_i32_e32 v145, 31, v144
	v_lshl_add_u64 v[150:151], v[144:145], 3, s[6:7]
	global_load_dwordx2 v[182:183], v[150:151], off
	global_load_dwordx2 v[184:185], v[150:151], off offset:128
	global_load_dwordx2 v[186:187], v[150:151], off offset:256
	global_load_dwordx2 v[188:189], v[150:151], off offset:384
	global_load_dwordx2 v[190:191], v[150:151], off offset:1024
	global_load_dwordx2 v[192:193], v[150:151], off offset:1152
	global_load_dwordx2 v[194:195], v[150:151], off offset:1280
	global_load_dwordx2 v[196:197], v[150:151], off offset:1408
	s_and_b64 vcc, exec, s[16:17]
	s_cbranch_vccz .LBB0_194
	s_barrier

; #define PG8_STAGE(bufoff, gbase, voff) do { _Pragma("unroll") for (int _i = 0; _i < 2; ++_i) \
;         __builtin_amdgcn_global_load_lds((const unsigned*)((const char*)(gbase) + (voff)[_i]), (PG8_LAS unsigned*)(lds + (bufoff) + ldsw + _i * 8192), 16, 0, 0); } while (0)
; #define PG8_LDA(dst, b, h) do { _Pragma("unroll") for (int m = 0; m < 4; ++m) _Pragma("unroll") for (int k = 0; k < 2; ++k) dst[m][k] = *(const PG8_LAS bf16x8*)(lds + PG8_SA(b, h) + aoff + m * 2048 + k * 1024); } while (0)
; #define PG8_LDB(dst, b, h) do { _Pragma("unroll") for (int n = 0; n < 2; ++n) _Pragma("unroll") for (int k = 0; k < 2; ++k) dst[n][k] = *(const PG8_LAS bf16x8*)(lds + PG8_SB(b, h) + boff + n * 2048 + k * 1024); } while (0)
; #define PG8_WAIT_V(n) asm volatile("s_waitcnt vmcnt(" #n ")" ::: "memory")
; #define PG8_WAIT_L(n) asm volatile("s_waitcnt lgkmcnt(" #n ")" ::: "memory")
; #define PG8_BAR __builtin_amdgcn_s_barrier()
; #define PG8_SCHED __builtin_amdgcn_sched_barrier(0)
; template <class Epi, class Sched, bool ALIGN_EPI = false, bool SP2 = false>
; __device__ __forceinline__ void gemm_phase(PG8_LAS unsigned char* lds, const Gemm g, const Sched& S, const Epi& E) {
;     ...
;         const char* nA = has_next ? (const char*)g.A + (size_t)nxt.pm * tstep : cA; const char* nB = has_next ? (const char*)g.Bt + (size_t)nxt.pn * tstep : cB;
;         for (int t = 0; t < nt; t += 2) {
;             const bool last = (t == nt - 2);
;             const char* a1 = cA + (size_t)(t + 1) * kstep;
;             const char* a2 = last ? nA : cA + (size_t)(t + 2) * kstep; const char* b2 = last ? nB : cB + (size_t)(t + 2) * kstep;
;             const char* a3 = a2 + kstep; const char* b3 = b2 + kstep;
;             if (last && has_next) S.a_ready(nxt);
;             if constexpr (SP2) {
;             PG8_LDB(B0, 0, 0); PG8_LDB(B1, 0, 1); PG8_SCHED; PG8_LDA(At, 0, 0); PG8_STAGE(PG8_SA(1, 1), a1 + hstep, voffA);
;             PG8_WAIT_V(8); PG8_WAIT_L(0); PG8_BAR; PG8_MMA(0, 0, At, B0); PG8_MMA(0, 1, At, B1); PG8_BAR; PG8_SCHED;
;             PG8_LDA(At, 0, 1); PG8_STAGE(PG8_SB(0, 0), b2, voffB); PG8_STAGE(PG8_SB(0, 1), b2 + hstep, voffB); PG8_STAGE(PG8_SA(0, 0), a2, voffA);
;             PG8_WAIT_V(8); PG8_WAIT_L(0); PG8_BAR; PG8_MMA(1, 0, At, B0); PG8_MMA(1, 1, At, B1); PG8_BAR; PG8_SCHED;
.LBB0_268:
	s_add_u32 s91, s50, 0x100
	s_addc_u32 s92, s51, 0
	s_mov_b32 s93, -2
	s_waitcnt lgkmcnt(0)
	ds_read_b128 v[128:131], v165
	ds_read_b128 v[132:135], v165 offset:1024
	ds_read_b128 v[152:155], v165 offset:2048
	ds_read_b128 v[156:159], v165 offset:3072
	ds_read_b128 v[172:175], v168
	ds_read_b128 v[176:179], v168 offset:1024
	ds_read_b128 v[182:185], v168 offset:2048
	ds_read_b128 v[186:189], v168 offset:3072
	s_add_u32 s50, s10, 0x100
	s_addc_u32 s51, s11, 0
	s_cmp_eq_u32 s93, 40
	s_cselect_b32 s57, s1, s51
	s_cselect_b32 s56, s0, s50
	s_cselect_b32 s55, s49, s92
	s_cselect_b32 s54, s48, s91
	v_lshl_add_u64 v[160:161], s[10:11], 0, v[144:145]
	s_add_i32 m0, s58, 0xc000
	ds_read_b128 v[190:193], v169
	ds_read_b128 v[194:197], v169 offset:1024
	ds_read_b128 v[198:201], v169 offset:2048
	ds_read_b128 v[208:211], v169 offset:3072
	ds_read_b128 v[212:215], v169 offset:4096
	ds_read_b128 v[216:219], v169 offset:5120
	ds_read_b128 v[220:223], v169 offset:6144
	ds_read_b128 v[224:227], v169 offset:7168
	global_load_lds_dwordx4 v[160:161], off
	v_lshl_add_u64 v[160:161], s[10:11], 0, v[146:147]
	s_add_i32 m0, s58, 0xe000
	s_nop 0
	global_load_lds_dwordx4 v[160:161], off
	s_waitcnt vmcnt(8)
	s_waitcnt lgkmcnt(0)
	s_barrier
	s_setprio 1
	s_waitcnt lgkmcnt(0)
	v_mfma_f32_16x16x32_bf16 v[124:127], v[128:131], v[190:193], 0
	v_mfma_f32_16x16x32_bf16 v[120:123], v[152:155], v[190:193], 0
	v_mfma_f32_16x16x32_bf16 v[108:111], v[128:131], v[198:201], 0
	v_mfma_f32_16x16x32_bf16 v[104:107], v[152:155], v[198:201], 0
	v_mfma_f32_16x16x32_bf16 v[92:95], v[128:131], v[212:215], 0
	v_mfma_f32_16x16x32_bf16 v[88:91], v[152:155], v[212:215], 0
	v_mfma_f32_16x16x32_bf16 v[76:79], v[128:131], v[220:223], 0
	v_mfma_f32_16x16x32_bf16 v[72:75], v[152:155], v[220:223], 0
	v_mfma_f32_16x16x32_bf16 v[124:127], v[132:135], v[194:197], v[124:127]
	v_mfma_f32_16x16x32_bf16 v[120:123], v[156:159], v[194:197], v[120:123]
	v_mfma_f32_16x16x32_bf16 v[108:111], v[132:135], v[208:211], v[108:111]
	v_mfma_f32_16x16x32_bf16 v[104:107], v[156:159], v[208:211], v[104:107]
	v_mfma_f32_16x16x32_bf16 v[92:95], v[132:135], v[216:219], v[92:95]
	v_mfma_f32_16x16x32_bf16 v[88:91], v[156:159], v[216:219], v[88:91]
	v_mfma_f32_16x16x32_bf16 v[76:79], v[132:135], v[224:227], v[76:79]
	v_mfma_f32_16x16x32_bf16 v[72:75], v[156:159], v[224:227], v[72:75]
	s_setprio 0
	s_setprio 1
	v_mfma_f32_16x16x32_bf16 v[116:119], v[172:175], v[190:193], 0
	v_mfma_f32_16x16x32_bf16 v[112:115], v[182:185], v[190:193], 0
	v_mfma_f32_16x16x32_bf16 v[100:103], v[172:175], v[198:201], 0
	v_mfma_f32_16x16x32_bf16 v[96:99], v[182:185], v[198:201], 0
	v_mfma_f32_16x16x32_bf16 v[84:87], v[172:175], v[212:215], 0
	v_mfma_f32_16x16x32_bf16 v[80:83], v[182:185], v[212:215], 0
	v_mfma_f32_16x16x32_bf16 v[68:71], v[172:175], v[220:223], 0
	v_mfma_f32_16x16x32_bf16 v[64:67], v[182:185], v[220:223], 0
	v_mfma_f32_16x16x32_bf16 v[116:119], v[176:179], v[194:197], v[116:119]
	v_mfma_f32_16x16x32_bf16 v[112:115], v[186:189], v[194:197], v[112:115]
	v_mfma_f32_16x16x32_bf16 v[100:103], v[176:179], v[208:211], v[100:103]
	v_mfma_f32_16x16x32_bf16 v[96:99], v[186:189], v[208:211], v[96:99]
	v_mfma_f32_16x16x32_bf16 v[84:87], v[176:179], v[216:219], v[84:87]
	v_mfma_f32_16x16x32_bf16 v[80:83], v[186:189], v[216:219], v[80:83]
	v_mfma_f32_16x16x32_bf16 v[68:71], v[176:179], v[224:227], v[68:71]
	v_mfma_f32_16x16x32_bf16 v[64:67], v[186:189], v[224:227], v[64:67]
	s_setprio 0
	s_barrier
	s_add_i32 s3, s65, s43
	v_lshl_add_u64 v[160:161], s[54:55], 0, v[138:139]
	s_mov_b32 m0, s3
	ds_read_b128 v[190:193], v169 offset:16384
	ds_read_b128 v[194:197], v169 offset:17408
	ds_read_b128 v[198:201], v169 offset:18432
	ds_read_b128 v[208:211], v169 offset:19456
	ds_read_b128 v[212:215], v169 offset:20480
	ds_read_b128 v[216:219], v169 offset:21504
	ds_read_b128 v[220:223], v169 offset:22528
	ds_read_b128 v[224:227], v169 offset:23552
	global_load_lds_dwordx4 v[160:161], off
	s_add_i32 m0, s3, 0x2000
	s_add_u32 s10, s54, 0xb0000
	v_lshl_add_u64 v[202:203], s[54:55], 0, v[142:143]
	s_addc_u32 s11, s55, 0
	s_add_i32 s3, s66, s43
	global_load_lds_dwordx4 v[202:203], off
	v_lshl_add_u64 v[228:229], s[10:11], 0, v[138:139]
	s_mov_b32 m0, s3
	v_lshl_add_u64 v[230:231], s[56:57], 0, v[140:141]
	global_load_lds_dwordx4 v[228:229], off
	v_lshl_add_u64 v[228:229], s[10:11], 0, v[142:143]
	s_add_i32 m0, s3, 0x2000
	s_nop 0
	global_load_lds_dwordx4 v[228:229], off
	s_waitcnt vmcnt(6)
	s_waitcnt lgkmcnt(0)
	s_barrier
; #define PG8_STAGE(bufoff, gbase, voff) do { _Pragma("unroll") for (int _i = 0; _i < 2; ++_i) \
;         __builtin_amdgcn_global_load_lds((const unsigned*)((const char*)(gbase) + (voff)[_i]), (PG8_LAS unsigned*)(lds + (bufoff) + ldsw + _i * 8192), 16, 0, 0); } while (0)
; #define PG8_LDA(dst, b, h) do { _Pragma("unroll") for (int m = 0; m < 4; ++m) _Pragma("unroll") for (int k = 0; k < 2; ++k) dst[m][k] = *(const PG8_LAS bf16x8*)(lds + PG8_SA(b, h) + aoff + m * 2048 + k * 1024); } while (0)
; #define PG8_LDB(dst, b, h) do { _Pragma("unroll") for (int n = 0; n < 2; ++n) _Pragma("unroll") for (int k = 0; k < 2; ++k) dst[n][k] = *(const PG8_LAS bf16x8*)(lds + PG8_SB(b, h) + boff + n * 2048 + k * 1024); } while (0)
; #define PG8_MMA(ai, bj, At, Bt) do { __builtin_amdgcn_s_setprio(1); _Pragma("unroll") for (int m = 0; m < 4; ++m) _Pragma("unroll") for (int n = 0; n < 2; ++n) _Pragma("unroll") for (int k = 0; k < 2; ++k) \
;         acc[ai][bj][m][n] = __builtin_amdgcn_mfma_f32_16x16x32_bf16(Bt[n][k], At[m][k], acc[ai][bj][m][n], 0, 0, 0); __builtin_amdgcn_s_setprio(0); } while (0)
; #define PG8_WAIT_V(n) asm volatile("s_waitcnt vmcnt(" #n ")" ::: "memory")
; #define PG8_WAIT_L(n) asm volatile("s_waitcnt lgkmcnt(" #n ")" ::: "memory")
; #define PG8_BAR __builtin_amdgcn_s_barrier()
; #define PG8_SCHED __builtin_amdgcn_sched_barrier(0)
; template <class Epi, class Sched, bool ALIGN_EPI = false, bool SP2 = false>
; __device__ __forceinline__ void gemm_phase(PG8_LAS unsigned char* lds, const Gemm g, const Sched& S, const Epi& E) {
;     ...
;             PG8_WAIT_V(8); PG8_WAIT_L(0); PG8_BAR; PG8_MMA(1, 0, At, B0); PG8_MMA(1, 1, At, B1); PG8_BAR; PG8_SCHED;
;             PG8_LDB(B0, 1, 0); PG8_LDB(B1, 1, 1); PG8_SCHED; PG8_LDA(At, 1, 0); PG8_STAGE(PG8_SA(0, 1), a2 + hstep, voffA);
;             PG8_WAIT_V(8); PG8_WAIT_L(0); PG8_BAR; PG8_MMA(0, 0, At, B0); PG8_MMA(0, 1, At, B1); PG8_BAR; PG8_SCHED;
	s_setprio 1
	s_waitcnt lgkmcnt(0)
	v_mfma_f32_16x16x32_bf16 v[60:63], v[128:131], v[190:193], 0
	v_mfma_f32_16x16x32_bf16 v[56:59], v[152:155], v[190:193], 0
	v_mfma_f32_16x16x32_bf16 v[44:47], v[128:131], v[198:201], 0
	v_mfma_f32_16x16x32_bf16 v[40:43], v[152:155], v[198:201], 0
	v_mfma_f32_16x16x32_bf16 v[28:31], v[128:131], v[212:215], 0
	v_mfma_f32_16x16x32_bf16 v[24:27], v[152:155], v[212:215], 0
	v_lshl_add_u64 v[228:229], s[56:57], 0, v[136:137]
	s_mov_b32 m0, s58
	s_nop 0
	global_load_lds_dwordx4 v[228:229], off
	v_mfma_f32_16x16x32_bf16 v[12:15], v[128:131], v[220:223], 0
	v_mfma_f32_16x16x32_bf16 v[8:11], v[152:155], v[220:223], 0
	v_mfma_f32_16x16x32_bf16 v[60:63], v[132:135], v[194:197], v[60:63]
	v_mfma_f32_16x16x32_bf16 v[56:59], v[156:159], v[194:197], v[56:59]
	v_mfma_f32_16x16x32_bf16 v[44:47], v[132:135], v[208:211], v[44:47]
	v_mfma_f32_16x16x32_bf16 v[40:43], v[156:159], v[208:211], v[40:43]
	v_mfma_f32_16x16x32_bf16 v[28:31], v[132:135], v[216:219], v[28:31]
	v_mfma_f32_16x16x32_bf16 v[24:27], v[156:159], v[216:219], v[24:27]
	v_mfma_f32_16x16x32_bf16 v[12:15], v[132:135], v[224:227], v[12:15]
	v_mfma_f32_16x16x32_bf16 v[8:11], v[156:159], v[224:227], v[8:11]
	s_setprio 0
	s_setprio 1
	v_mfma_f32_16x16x32_bf16 v[52:55], v[172:175], v[190:193], 0
	v_mfma_f32_16x16x32_bf16 v[48:51], v[182:185], v[190:193], 0
	s_mov_b32 m0, s59
	s_nop 0
	global_load_lds_dwordx4 v[230:231], off
	v_mfma_f32_16x16x32_bf16 v[36:39], v[172:175], v[198:201], 0
	v_mfma_f32_16x16x32_bf16 v[32:35], v[182:185], v[198:201], 0
	v_mfma_f32_16x16x32_bf16 v[20:23], v[172:175], v[212:215], 0
	v_mfma_f32_16x16x32_bf16 v[16:19], v[182:185], v[212:215], 0
	v_mfma_f32_16x16x32_bf16 v[4:7], v[172:175], v[220:223], 0
	v_mfma_f32_16x16x32_bf16 v[0:3], v[182:185], v[220:223], 0
	v_mfma_f32_16x16x32_bf16 v[52:55], v[176:179], v[194:197], v[52:55]
	v_mfma_f32_16x16x32_bf16 v[48:51], v[186:189], v[194:197], v[48:51]
	v_mfma_f32_16x16x32_bf16 v[36:39], v[176:179], v[208:211], v[36:39]
	v_mfma_f32_16x16x32_bf16 v[32:35], v[186:189], v[208:211], v[32:35]
	v_mfma_f32_16x16x32_bf16 v[20:23], v[176:179], v[216:219], v[20:23]
	v_mfma_f32_16x16x32_bf16 v[16:19], v[186:189], v[216:219], v[16:19]
	v_mfma_f32_16x16x32_bf16 v[4:7], v[176:179], v[224:227], v[4:7]
	v_mfma_f32_16x16x32_bf16 v[0:3], v[186:189], v[224:227], v[0:3]
	s_setprio 0
	s_barrier
	s_add_i32 s3, 0, 0x18000
	s_add_i32 s14, 0, 0x1c000
	v_add_u32_e32 v156, s3, v163
	v_add_u32_e32 v171, s14, v163
	ds_read_b128 v[128:131], v156
	ds_read_b128 v[132:135], v156 offset:1024
	ds_read_b128 v[152:155], v156 offset:2048
	ds_read_b128 v[156:159], v156 offset:3072
	ds_read_b128 v[172:175], v171
	ds_read_b128 v[176:179], v171 offset:1024
	ds_read_b128 v[182:185], v171 offset:2048
	ds_read_b128 v[186:189], v171 offset:3072
	s_add_u32 s10, s56, 0xb0000
	s_addc_u32 s11, s57, 0
	s_mov_b32 m0, s60
	v_lshl_add_u64 v[232:233], s[10:11], 0, v[136:137]
	ds_read_b128 v[190:193], v169 offset:32768
	ds_read_b128 v[194:197], v169 offset:33792
	ds_read_b128 v[198:201], v169 offset:34816
	ds_read_b128 v[208:211], v169 offset:35840
	ds_read_b128 v[212:215], v169 offset:36864
	ds_read_b128 v[216:219], v169 offset:37888
	ds_read_b128 v[220:223], v169 offset:38912
	ds_read_b128 v[224:227], v169 offset:39936
	global_load_lds_dwordx4 v[232:233], off
	v_lshl_add_u64 v[232:233], s[10:11], 0, v[140:141]
	s_mov_b32 m0, s61
	s_nop 0
	global_load_lds_dwordx4 v[232:233], off
	s_waitcnt vmcnt(8)
	s_waitcnt lgkmcnt(0)
	s_barrier
	s_setprio 1
	s_waitcnt lgkmcnt(0)
	v_mfma_f32_16x16x32_bf16 v[124:127], v[128:131], v[190:193], v[124:127]
	v_mfma_f32_16x16x32_bf16 v[120:123], v[152:155], v[190:193], v[120:123]
	v_mfma_f32_16x16x32_bf16 v[108:111], v[128:131], v[198:201], v[108:111]
	v_mfma_f32_16x16x32_bf16 v[104:107], v[152:155], v[198:201], v[104:107]
	v_mfma_f32_16x16x32_bf16 v[92:95], v[128:131], v[212:215], v[92:95]
	v_mfma_f32_16x16x32_bf16 v[88:91], v[152:155], v[212:215], v[88:91]
	v_mfma_f32_16x16x32_bf16 v[76:79], v[128:131], v[220:223], v[76:79]
	v_mfma_f32_16x16x32_bf16 v[72:75], v[152:155], v[220:223], v[72:75]
	v_mfma_f32_16x16x32_bf16 v[124:127], v[132:135], v[194:197], v[124:127]
	v_mfma_f32_16x16x32_bf16 v[120:123], v[156:159], v[194:197], v[120:123]
	v_mfma_f32_16x16x32_bf16 v[108:111], v[132:135], v[208:211], v[108:111]
	v_mfma_f32_16x16x32_bf16 v[104:107], v[156:159], v[208:211], v[104:107]
	v_mfma_f32_16x16x32_bf16 v[92:95], v[132:135], v[216:219], v[92:95]
	v_mfma_f32_16x16x32_bf16 v[88:91], v[156:159], v[216:219], v[88:91]
	v_mfma_f32_16x16x32_bf16 v[76:79], v[132:135], v[224:227], v[76:79]
	v_mfma_f32_16x16x32_bf16 v[72:75], v[156:159], v[224:227], v[72:75]
	s_setprio 0
	s_setprio 1
	v_mfma_f32_16x16x32_bf16 v[116:119], v[172:175], v[190:193], v[116:119]
	v_mfma_f32_16x16x32_bf16 v[112:115], v[182:185], v[190:193], v[112:115]
	v_mfma_f32_16x16x32_bf16 v[100:103], v[172:175], v[198:201], v[100:103]
	v_mfma_f32_16x16x32_bf16 v[96:99], v[182:185], v[198:201], v[96:99]
	v_mfma_f32_16x16x32_bf16 v[84:87], v[172:175], v[212:215], v[84:87]
	v_mfma_f32_16x16x32_bf16 v[80:83], v[182:185], v[212:215], v[80:83]
	v_mfma_f32_16x16x32_bf16 v[68:71], v[172:175], v[220:223], v[68:71]
	v_mfma_f32_16x16x32_bf16 v[64:67], v[182:185], v[220:223], v[64:67]
	v_mfma_f32_16x16x32_bf16 v[116:119], v[176:179], v[194:197], v[116:119]
	v_mfma_f32_16x16x32_bf16 v[112:115], v[186:189], v[194:197], v[112:115]
	v_mfma_f32_16x16x32_bf16 v[100:103], v[176:179], v[208:211], v[100:103]
	v_mfma_f32_16x16x32_bf16 v[96:99], v[186:189], v[208:211], v[96:99]
	v_mfma_f32_16x16x32_bf16 v[84:87], v[176:179], v[216:219], v[84:87]
	v_mfma_f32_16x16x32_bf16 v[80:83], v[186:189], v[216:219], v[80:83]
	v_mfma_f32_16x16x32_bf16 v[68:71], v[176:179], v[224:227], v[68:71]
	v_mfma_f32_16x16x32_bf16 v[64:67], v[186:189], v[224:227], v[64:67]
	s_setprio 0
	s_barrier
; #define PG8_STAGE(bufoff, gbase, voff) do { _Pragma("unroll") for (int _i = 0; _i < 2; ++_i) \
;         __builtin_amdgcn_global_load_lds((const unsigned*)((const char*)(gbase) + (voff)[_i]), (PG8_LAS unsigned*)(lds + (bufoff) + ldsw + _i * 8192), 16, 0, 0); } while (0)
; #define PG8_LDA(dst, b, h) do { _Pragma("unroll") for (int m = 0; m < 4; ++m) _Pragma("unroll") for (int k = 0; k < 2; ++k) dst[m][k] = *(const PG8_LAS bf16x8*)(lds + PG8_SA(b, h) + aoff + m * 2048 + k * 1024); } while (0)
; #define PG8_LDB(dst, b, h) do { _Pragma("unroll") for (int n = 0; n < 2; ++n) _Pragma("unroll") for (int k = 0; k < 2; ++k) dst[n][k] = *(const PG8_LAS bf16x8*)(lds + PG8_SB(b, h) + boff + n * 2048 + k * 1024); } while (0)
; #define PG8_MMA(ai, bj, At, Bt) do { __builtin_amdgcn_s_setprio(1); _Pragma("unroll") for (int m = 0; m < 4; ++m) _Pragma("unroll") for (int n = 0; n < 2; ++n) _Pragma("unroll") for (int k = 0; k < 2; ++k) \
;         acc[ai][bj][m][n] = __builtin_amdgcn_mfma_f32_16x16x32_bf16(Bt[n][k], At[m][k], acc[ai][bj][m][n], 0, 0, 0); __builtin_amdgcn_s_setprio(0); } while (0)
; #define PG8_WAIT_V(n) asm volatile("s_waitcnt vmcnt(" #n ")" ::: "memory")
; #define PG8_BAR __builtin_amdgcn_s_barrier()
; template <class Epi, class Sched, bool ALIGN_EPI = false, bool SP2 = false>
; __device__ __forceinline__ void gemm_phase(PG8_LAS unsigned char* lds, const Gemm g, const Sched& S, const Epi& E) {
;     ...
;         for (int t = 0; t < nt; t += 2) {
;             const bool last = (t == nt - 2);
;             const char* a1 = cA + (size_t)(t + 1) * kstep;
;             const char* a2 = last ? nA : cA + (size_t)(t + 2) * kstep; const char* b2 = last ? nB : cB + (size_t)(t + 2) * kstep;
;             const char* a3 = a2 + kstep; const char* b3 = b2 + kstep;
;             if (last && has_next) S.a_ready(nxt);
;             if constexpr (SP2) {
;             PG8_LDB(B0, 0, 0); PG8_LDB(B1, 0, 1); PG8_SCHED; PG8_LDA(At, 0, 0); PG8_STAGE(PG8_SA(1, 1), a1 + hstep, voffA);
;             PG8_WAIT_V(8); PG8_WAIT_L(0); PG8_BAR; PG8_MMA(0, 0, At, B0); PG8_MMA(0, 1, At, B1); PG8_BAR; PG8_SCHED;
;     ...
;             PG8_LDA(At, 1, 1); PG8_STAGE(PG8_SB(1, 0), b3, voffB); PG8_STAGE(PG8_SB(1, 1), b3 + hstep, voffB); PG8_STAGE(PG8_SA(1, 0), a3, voffA);
;             PG8_WAIT_V(8); PG8_WAIT_L(0); PG8_BAR; PG8_MMA(1, 0, At, B0); PG8_MMA(1, 1, At, B1); PG8_BAR; PG8_SCHED;
	s_add_i32 s3, s3, s43
	v_lshl_add_u64 v[160:161], v[160:161], 0, s[40:41]
	s_mov_b32 m0, s3
	ds_read_b128 v[190:193], v169 offset:49152
	ds_read_b128 v[194:197], v169 offset:50176
	ds_read_b128 v[198:201], v169 offset:51200
	ds_read_b128 v[208:211], v169 offset:52224
	ds_read_b128 v[212:215], v169 offset:53248
	ds_read_b128 v[216:219], v169 offset:54272
	ds_read_b128 v[220:223], v169 offset:55296
	ds_read_b128 v[224:227], v169 offset:56320
	global_load_lds_dwordx4 v[160:161], off
	s_add_i32 m0, s3, 0x2000
	s_add_u32 s10, s54, 0xb0080
	v_lshl_add_u64 v[160:161], v[202:203], 0, s[40:41]
	s_addc_u32 s11, s55, 0
	s_add_i32 s3, s14, s43
	global_load_lds_dwordx4 v[160:161], off
	v_lshl_add_u64 v[160:161], s[10:11], 0, v[138:139]
	s_mov_b32 m0, s3
	s_nop 0
	global_load_lds_dwordx4 v[160:161], off
	v_lshl_add_u64 v[160:161], s[10:11], 0, v[142:143]
	s_add_i32 m0, s3, 0x2000
	s_nop 0
	global_load_lds_dwordx4 v[160:161], off
	s_waitcnt vmcnt(6)
	s_waitcnt lgkmcnt(0)
	s_barrier
	s_setprio 1
	s_waitcnt lgkmcnt(0)
	v_mfma_f32_16x16x32_bf16 v[60:63], v[128:131], v[190:193], v[60:63]
	v_mfma_f32_16x16x32_bf16 v[56:59], v[152:155], v[190:193], v[56:59]
	v_mfma_f32_16x16x32_bf16 v[44:47], v[128:131], v[198:201], v[44:47]
	v_mfma_f32_16x16x32_bf16 v[40:43], v[152:155], v[198:201], v[40:43]
	v_mfma_f32_16x16x32_bf16 v[28:31], v[128:131], v[212:215], v[28:31]
	v_mfma_f32_16x16x32_bf16 v[24:27], v[152:155], v[212:215], v[24:27]
	v_lshl_add_u64 v[160:161], v[228:229], 0, s[40:41]
	s_mov_b32 m0, s63
	s_nop 0
	global_load_lds_dwordx4 v[160:161], off
	v_mfma_f32_16x16x32_bf16 v[12:15], v[128:131], v[220:223], v[12:15]
	v_mfma_f32_16x16x32_bf16 v[8:11], v[152:155], v[220:223], v[8:11]
	v_mfma_f32_16x16x32_bf16 v[60:63], v[132:135], v[194:197], v[60:63]
	v_mfma_f32_16x16x32_bf16 v[56:59], v[156:159], v[194:197], v[56:59]
	v_mfma_f32_16x16x32_bf16 v[44:47], v[132:135], v[208:211], v[44:47]
	v_mfma_f32_16x16x32_bf16 v[40:43], v[156:159], v[208:211], v[40:43]
	v_mfma_f32_16x16x32_bf16 v[28:31], v[132:135], v[216:219], v[28:31]
	v_mfma_f32_16x16x32_bf16 v[24:27], v[156:159], v[216:219], v[24:27]
	v_mfma_f32_16x16x32_bf16 v[12:15], v[132:135], v[224:227], v[12:15]
	v_mfma_f32_16x16x32_bf16 v[8:11], v[156:159], v[224:227], v[8:11]
	s_setprio 0
	s_setprio 1
	v_mfma_f32_16x16x32_bf16 v[52:55], v[172:175], v[190:193], v[52:55]
	v_mfma_f32_16x16x32_bf16 v[48:51], v[182:185], v[190:193], v[48:51]
	v_lshl_add_u64 v[160:161], v[230:231], 0, s[40:41]
	s_mov_b32 m0, s64
	s_nop 0
	global_load_lds_dwordx4 v[160:161], off
	v_mfma_f32_16x16x32_bf16 v[36:39], v[172:175], v[198:201], v[36:39]
	v_mfma_f32_16x16x32_bf16 v[32:35], v[182:185], v[198:201], v[32:35]
	v_mfma_f32_16x16x32_bf16 v[20:23], v[172:175], v[212:215], v[20:23]
	v_mfma_f32_16x16x32_bf16 v[16:19], v[182:185], v[212:215], v[16:19]
	v_mfma_f32_16x16x32_bf16 v[4:7], v[172:175], v[220:223], v[4:7]
	v_mfma_f32_16x16x32_bf16 v[0:3], v[182:185], v[220:223], v[0:3]
	v_mfma_f32_16x16x32_bf16 v[52:55], v[176:179], v[194:197], v[52:55]
	v_mfma_f32_16x16x32_bf16 v[48:51], v[186:189], v[194:197], v[48:51]
	v_mfma_f32_16x16x32_bf16 v[36:39], v[176:179], v[208:211], v[36:39]
	v_mfma_f32_16x16x32_bf16 v[32:35], v[186:189], v[208:211], v[32:35]
	v_mfma_f32_16x16x32_bf16 v[20:23], v[176:179], v[216:219], v[20:23]
	v_mfma_f32_16x16x32_bf16 v[16:19], v[186:189], v[216:219], v[16:19]
	v_mfma_f32_16x16x32_bf16 v[4:7], v[176:179], v[224:227], v[4:7]
	v_mfma_f32_16x16x32_bf16 v[0:3], v[186:189], v[224:227], v[0:3]
	s_setprio 0
	s_barrier
	s_add_i32 s93, s93, 2
	s_add_u32 s91, s91, 0x100
	s_addc_u32 s92, s92, 0
	s_mov_b64 s[10:11], s[50:51]
.LBB0_269:
	ds_read_b128 v[128:131], v165
	ds_read_b128 v[132:135], v165 offset:1024
	ds_read_b128 v[152:155], v165 offset:2048
	ds_read_b128 v[156:159], v165 offset:3072
	ds_read_b128 v[172:175], v168
	ds_read_b128 v[176:179], v168 offset:1024
	ds_read_b128 v[182:185], v168 offset:2048
	ds_read_b128 v[186:189], v168 offset:3072
	s_add_u32 s50, s10, 0x100
	s_addc_u32 s51, s11, 0
	s_cmp_eq_u32 s93, 40
	s_cselect_b32 s57, s1, s51
	s_cselect_b32 s56, s0, s50
	s_cselect_b32 s55, s49, s92
	s_cselect_b32 s54, s48, s91
	v_lshl_add_u64 v[160:161], s[10:11], 0, v[144:145]
	s_add_i32 m0, s58, 0xc000
	ds_read_b128 v[190:193], v169
	ds_read_b128 v[194:197], v169 offset:1024
	ds_read_b128 v[198:201], v169 offset:2048
	ds_read_b128 v[208:211], v169 offset:3072
	ds_read_b128 v[212:215], v169 offset:4096
	ds_read_b128 v[216:219], v169 offset:5120
	ds_read_b128 v[220:223], v169 offset:6144
	ds_read_b128 v[224:227], v169 offset:7168
	global_load_lds_dwordx4 v[160:161], off
	v_lshl_add_u64 v[160:161], s[10:11], 0, v[146:147]
	s_add_i32 m0, s58, 0xe000
	s_nop 0
	global_load_lds_dwordx4 v[160:161], off
	s_waitcnt vmcnt(8)
	s_waitcnt lgkmcnt(0)
	s_barrier
; #define PG8_STAGE(bufoff, gbase, voff) do { _Pragma("unroll") for (int _i = 0; _i < 2; ++_i) \
;         __builtin_amdgcn_global_load_lds((const unsigned*)((const char*)(gbase) + (voff)[_i]), (PG8_LAS unsigned*)(lds + (bufoff) + ldsw + _i * 8192), 16, 0, 0); } while (0)
; #define PG8_LDA(dst, b, h) do { _Pragma("unroll") for (int m = 0; m < 4; ++m) _Pragma("unroll") for (int k = 0; k < 2; ++k) dst[m][k] = *(const PG8_LAS bf16x8*)(lds + PG8_SA(b, h) + aoff + m * 2048 + k * 1024); } while (0)
; #define PG8_LDB(dst, b, h) do { _Pragma("unroll") for (int n = 0; n < 2; ++n) _Pragma("unroll") for (int k = 0; k < 2; ++k) dst[n][k] = *(const PG8_LAS bf16x8*)(lds + PG8_SB(b, h) + boff + n * 2048 + k * 1024); } while (0)
; #define PG8_MMA(ai, bj, At, Bt) do { __builtin_amdgcn_s_setprio(1); _Pragma("unroll") for (int m = 0; m < 4; ++m) _Pragma("unroll") for (int n = 0; n < 2; ++n) _Pragma("unroll") for (int k = 0; k < 2; ++k) \
;         acc[ai][bj][m][n] = __builtin_amdgcn_mfma_f32_16x16x32_bf16(Bt[n][k], At[m][k], acc[ai][bj][m][n], 0, 0, 0); __builtin_amdgcn_s_setprio(0); } while (0)
; #define PG8_WAIT_V(n) asm volatile("s_waitcnt vmcnt(" #n ")" ::: "memory")
; #define PG8_WAIT_L(n) asm volatile("s_waitcnt lgkmcnt(" #n ")" ::: "memory")
; #define PG8_BAR __builtin_amdgcn_s_barrier()
; #define PG8_SCHED __builtin_amdgcn_sched_barrier(0)
; template <class Epi, class Sched, bool ALIGN_EPI = false, bool SP2 = false>
; __device__ __forceinline__ void gemm_phase(PG8_LAS unsigned char* lds, const Gemm g, const Sched& S, const Epi& E) {
;     ...
;             PG8_LDB(B0, 0, 0); PG8_LDB(B1, 0, 1); PG8_SCHED; PG8_LDA(At, 0, 0); PG8_STAGE(PG8_SA(1, 1), a1 + hstep, voffA);
;             PG8_WAIT_V(8); PG8_WAIT_L(0); PG8_BAR; PG8_MMA(0, 0, At, B0); PG8_MMA(0, 1, At, B1); PG8_BAR; PG8_SCHED;
;             PG8_LDA(At, 0, 1); PG8_STAGE(PG8_SB(0, 0), b2, voffB); PG8_STAGE(PG8_SB(0, 1), b2 + hstep, voffB); PG8_STAGE(PG8_SA(0, 0), a2, voffA);
;             PG8_WAIT_V(8); PG8_WAIT_L(0); PG8_BAR; PG8_MMA(1, 0, At, B0); PG8_MMA(1, 1, At, B1); PG8_BAR; PG8_SCHED;
	s_setprio 1
	s_waitcnt lgkmcnt(0)
	v_mfma_f32_16x16x32_bf16 v[124:127], v[128:131], v[190:193], v[124:127]
	v_mfma_f32_16x16x32_bf16 v[120:123], v[152:155], v[190:193], v[120:123]
	v_mfma_f32_16x16x32_bf16 v[108:111], v[128:131], v[198:201], v[108:111]
	v_mfma_f32_16x16x32_bf16 v[104:107], v[152:155], v[198:201], v[104:107]
	v_mfma_f32_16x16x32_bf16 v[92:95], v[128:131], v[212:215], v[92:95]
	v_mfma_f32_16x16x32_bf16 v[88:91], v[152:155], v[212:215], v[88:91]
	v_mfma_f32_16x16x32_bf16 v[76:79], v[128:131], v[220:223], v[76:79]
	v_mfma_f32_16x16x32_bf16 v[72:75], v[152:155], v[220:223], v[72:75]
	v_mfma_f32_16x16x32_bf16 v[124:127], v[132:135], v[194:197], v[124:127]
	v_mfma_f32_16x16x32_bf16 v[120:123], v[156:159], v[194:197], v[120:123]
	v_mfma_f32_16x16x32_bf16 v[108:111], v[132:135], v[208:211], v[108:111]
	v_mfma_f32_16x16x32_bf16 v[104:107], v[156:159], v[208:211], v[104:107]
	v_mfma_f32_16x16x32_bf16 v[92:95], v[132:135], v[216:219], v[92:95]
	v_mfma_f32_16x16x32_bf16 v[88:91], v[156:159], v[216:219], v[88:91]
	v_mfma_f32_16x16x32_bf16 v[76:79], v[132:135], v[224:227], v[76:79]
	v_mfma_f32_16x16x32_bf16 v[72:75], v[156:159], v[224:227], v[72:75]
	s_setprio 0
	s_setprio 1
	v_mfma_f32_16x16x32_bf16 v[116:119], v[172:175], v[190:193], v[116:119]
	v_mfma_f32_16x16x32_bf16 v[112:115], v[182:185], v[190:193], v[112:115]
	v_mfma_f32_16x16x32_bf16 v[100:103], v[172:175], v[198:201], v[100:103]
	v_mfma_f32_16x16x32_bf16 v[96:99], v[182:185], v[198:201], v[96:99]
	v_mfma_f32_16x16x32_bf16 v[84:87], v[172:175], v[212:215], v[84:87]
	v_mfma_f32_16x16x32_bf16 v[80:83], v[182:185], v[212:215], v[80:83]
	v_mfma_f32_16x16x32_bf16 v[68:71], v[172:175], v[220:223], v[68:71]
	v_mfma_f32_16x16x32_bf16 v[64:67], v[182:185], v[220:223], v[64:67]
	v_mfma_f32_16x16x32_bf16 v[116:119], v[176:179], v[194:197], v[116:119]
	v_mfma_f32_16x16x32_bf16 v[112:115], v[186:189], v[194:197], v[112:115]
	v_mfma_f32_16x16x32_bf16 v[100:103], v[176:179], v[208:211], v[100:103]
	v_mfma_f32_16x16x32_bf16 v[96:99], v[186:189], v[208:211], v[96:99]
	v_mfma_f32_16x16x32_bf16 v[84:87], v[176:179], v[216:219], v[84:87]
	v_mfma_f32_16x16x32_bf16 v[80:83], v[186:189], v[216:219], v[80:83]
	v_mfma_f32_16x16x32_bf16 v[68:71], v[176:179], v[224:227], v[68:71]
	v_mfma_f32_16x16x32_bf16 v[64:67], v[186:189], v[224:227], v[64:67]
	s_setprio 0
	s_barrier
	s_add_i32 s3, s65, s43
	v_lshl_add_u64 v[160:161], s[54:55], 0, v[138:139]
	s_mov_b32 m0, s3
	ds_read_b128 v[190:193], v169 offset:16384
	ds_read_b128 v[194:197], v169 offset:17408
	ds_read_b128 v[198:201], v169 offset:18432
	ds_read_b128 v[208:211], v169 offset:19456
	ds_read_b128 v[212:215], v169 offset:20480
	ds_read_b128 v[216:219], v169 offset:21504
	ds_read_b128 v[220:223], v169 offset:22528
	ds_read_b128 v[224:227], v169 offset:23552
	global_load_lds_dwordx4 v[160:161], off
	s_add_i32 m0, s3, 0x2000
	s_add_u32 s10, s54, 0xb0000
	v_lshl_add_u64 v[202:203], s[54:55], 0, v[142:143]
	s_addc_u32 s11, s55, 0
	s_add_i32 s3, s66, s43
	global_load_lds_dwordx4 v[202:203], off
	v_lshl_add_u64 v[228:229], s[10:11], 0, v[138:139]
	s_mov_b32 m0, s3
	v_lshl_add_u64 v[230:231], s[56:57], 0, v[140:141]
	global_load_lds_dwordx4 v[228:229], off
	v_lshl_add_u64 v[228:229], s[10:11], 0, v[142:143]
	s_add_i32 m0, s3, 0x2000
	s_nop 0
	global_load_lds_dwordx4 v[228:229], off
	s_waitcnt vmcnt(6)
	s_waitcnt lgkmcnt(0)
	s_barrier
	s_setprio 1
	s_waitcnt lgkmcnt(0)
	v_mfma_f32_16x16x32_bf16 v[60:63], v[128:131], v[190:193], v[60:63]
	v_mfma_f32_16x16x32_bf16 v[56:59], v[152:155], v[190:193], v[56:59]
	v_mfma_f32_16x16x32_bf16 v[44:47], v[128:131], v[198:201], v[44:47]
	v_mfma_f32_16x16x32_bf16 v[40:43], v[152:155], v[198:201], v[40:43]
	v_mfma_f32_16x16x32_bf16 v[28:31], v[128:131], v[212:215], v[28:31]
	v_mfma_f32_16x16x32_bf16 v[24:27], v[152:155], v[212:215], v[24:27]
	v_lshl_add_u64 v[228:229], s[56:57], 0, v[136:137]
	s_mov_b32 m0, s58
	s_nop 0
	global_load_lds_dwordx4 v[228:229], off
	v_mfma_f32_16x16x32_bf16 v[12:15], v[128:131], v[220:223], v[12:15]
	v_mfma_f32_16x16x32_bf16 v[8:11], v[152:155], v[220:223], v[8:11]
	v_mfma_f32_16x16x32_bf16 v[60:63], v[132:135], v[194:197], v[60:63]
	v_mfma_f32_16x16x32_bf16 v[56:59], v[156:159], v[194:197], v[56:59]
	v_mfma_f32_16x16x32_bf16 v[44:47], v[132:135], v[208:211], v[44:47]
	v_mfma_f32_16x16x32_bf16 v[40:43], v[156:159], v[208:211], v[40:43]
	v_mfma_f32_16x16x32_bf16 v[28:31], v[132:135], v[216:219], v[28:31]
	v_mfma_f32_16x16x32_bf16 v[24:27], v[156:159], v[216:219], v[24:27]
	v_mfma_f32_16x16x32_bf16 v[12:15], v[132:135], v[224:227], v[12:15]
	v_mfma_f32_16x16x32_bf16 v[8:11], v[156:159], v[224:227], v[8:11]
	s_setprio 0
	s_setprio 1
	v_mfma_f32_16x16x32_bf16 v[52:55], v[172:175], v[190:193], v[52:55]
	v_mfma_f32_16x16x32_bf16 v[48:51], v[182:185], v[190:193], v[48:51]
	s_mov_b32 m0, s59
	s_nop 0
	global_load_lds_dwordx4 v[230:231], off
	v_mfma_f32_16x16x32_bf16 v[36:39], v[172:175], v[198:201], v[36:39]
	v_mfma_f32_16x16x32_bf16 v[32:35], v[182:185], v[198:201], v[32:35]
	v_mfma_f32_16x16x32_bf16 v[20:23], v[172:175], v[212:215], v[20:23]
	v_mfma_f32_16x16x32_bf16 v[16:19], v[182:185], v[212:215], v[16:19]
	v_mfma_f32_16x16x32_bf16 v[4:7], v[172:175], v[220:223], v[4:7]
	v_mfma_f32_16x16x32_bf16 v[0:3], v[182:185], v[220:223], v[0:3]
	v_mfma_f32_16x16x32_bf16 v[52:55], v[176:179], v[194:197], v[52:55]
	v_mfma_f32_16x16x32_bf16 v[48:51], v[186:189], v[194:197], v[48:51]
	v_mfma_f32_16x16x32_bf16 v[36:39], v[176:179], v[208:211], v[36:39]
	v_mfma_f32_16x16x32_bf16 v[32:35], v[186:189], v[208:211], v[32:35]
	v_mfma_f32_16x16x32_bf16 v[20:23], v[176:179], v[216:219], v[20:23]
	v_mfma_f32_16x16x32_bf16 v[16:19], v[186:189], v[216:219], v[16:19]
	v_mfma_f32_16x16x32_bf16 v[4:7], v[176:179], v[224:227], v[4:7]
	v_mfma_f32_16x16x32_bf16 v[0:3], v[186:189], v[224:227], v[0:3]
	s_setprio 0
	s_barrier
; #define PG8_STAGE(bufoff, gbase, voff) do { _Pragma("unroll") for (int _i = 0; _i < 2; ++_i) \
;         __builtin_amdgcn_global_load_lds((const unsigned*)((const char*)(gbase) + (voff)[_i]), (PG8_LAS unsigned*)(lds + (bufoff) + ldsw + _i * 8192), 16, 0, 0); } while (0)
; #define PG8_LDA(dst, b, h) do { _Pragma("unroll") for (int m = 0; m < 4; ++m) _Pragma("unroll") for (int k = 0; k < 2; ++k) dst[m][k] = *(const PG8_LAS bf16x8*)(lds + PG8_SA(b, h) + aoff + m * 2048 + k * 1024); } while (0)
; #define PG8_LDB(dst, b, h) do { _Pragma("unroll") for (int n = 0; n < 2; ++n) _Pragma("unroll") for (int k = 0; k < 2; ++k) dst[n][k] = *(const PG8_LAS bf16x8*)(lds + PG8_SB(b, h) + boff + n * 2048 + k * 1024); } while (0)
; #define PG8_MMA(ai, bj, At, Bt) do { __builtin_amdgcn_s_setprio(1); _Pragma("unroll") for (int m = 0; m < 4; ++m) _Pragma("unroll") for (int n = 0; n < 2; ++n) _Pragma("unroll") for (int k = 0; k < 2; ++k) \
;         acc[ai][bj][m][n] = __builtin_amdgcn_mfma_f32_16x16x32_bf16(Bt[n][k], At[m][k], acc[ai][bj][m][n], 0, 0, 0); __builtin_amdgcn_s_setprio(0); } while (0)
; #define PG8_WAIT_V(n) asm volatile("s_waitcnt vmcnt(" #n ")" ::: "memory")
; #define PG8_WAIT_L(n) asm volatile("s_waitcnt lgkmcnt(" #n ")" ::: "memory")
; #define PG8_BAR __builtin_amdgcn_s_barrier()
; #define PG8_SCHED __builtin_amdgcn_sched_barrier(0)
; template <class Epi, class Sched, bool ALIGN_EPI = false, bool SP2 = false>
; __device__ __forceinline__ void gemm_phase(PG8_LAS unsigned char* lds, const Gemm g, const Sched& S, const Epi& E) {
;     ...
;             PG8_LDB(B0, 1, 0); PG8_LDB(B1, 1, 1); PG8_SCHED; PG8_LDA(At, 1, 0); PG8_STAGE(PG8_SA(0, 1), a2 + hstep, voffA);
;             PG8_WAIT_V(8); PG8_WAIT_L(0); PG8_BAR; PG8_MMA(0, 0, At, B0); PG8_MMA(0, 1, At, B1); PG8_BAR; PG8_SCHED;
	s_add_i32 s3, 0, 0x18000
	s_add_i32 s14, 0, 0x1c000
	v_add_u32_e32 v156, s3, v163
	v_add_u32_e32 v171, s14, v163
	ds_read_b128 v[128:131], v156
	ds_read_b128 v[132:135], v156 offset:1024
	ds_read_b128 v[152:155], v156 offset:2048
	ds_read_b128 v[156:159], v156 offset:3072
	ds_read_b128 v[172:175], v171
	ds_read_b128 v[176:179], v171 offset:1024
	ds_read_b128 v[182:185], v171 offset:2048
	ds_read_b128 v[186:189], v171 offset:3072
	s_add_u32 s10, s56, 0xb0000
	s_addc_u32 s11, s57, 0
	s_mov_b32 m0, s60
	v_lshl_add_u64 v[232:233], s[10:11], 0, v[136:137]
	ds_read_b128 v[190:193], v169 offset:32768
	ds_read_b128 v[194:197], v169 offset:33792
	ds_read_b128 v[198:201], v169 offset:34816
	ds_read_b128 v[208:211], v169 offset:35840
	ds_read_b128 v[212:215], v169 offset:36864
	ds_read_b128 v[216:219], v169 offset:37888
	ds_read_b128 v[220:223], v169 offset:38912
	ds_read_b128 v[224:227], v169 offset:39936
	global_load_lds_dwordx4 v[232:233], off
	v_lshl_add_u64 v[232:233], s[10:11], 0, v[140:141]
	s_mov_b32 m0, s61
	s_nop 0
	global_load_lds_dwordx4 v[232:233], off
	s_waitcnt vmcnt(8)
	s_waitcnt lgkmcnt(0)
	s_barrier
	s_setprio 1
	s_waitcnt lgkmcnt(0)
	v_mfma_f32_16x16x32_bf16 v[124:127], v[128:131], v[190:193], v[124:127]
	v_mfma_f32_16x16x32_bf16 v[120:123], v[152:155], v[190:193], v[120:123]
	v_mfma_f32_16x16x32_bf16 v[108:111], v[128:131], v[198:201], v[108:111]
	v_mfma_f32_16x16x32_bf16 v[104:107], v[152:155], v[198:201], v[104:107]
	v_mfma_f32_16x16x32_bf16 v[92:95], v[128:131], v[212:215], v[92:95]
	v_mfma_f32_16x16x32_bf16 v[88:91], v[152:155], v[212:215], v[88:91]
	v_mfma_f32_16x16x32_bf16 v[76:79], v[128:131], v[220:223], v[76:79]
	v_mfma_f32_16x16x32_bf16 v[72:75], v[152:155], v[220:223], v[72:75]
	v_mfma_f32_16x16x32_bf16 v[124:127], v[132:135], v[194:197], v[124:127]
	v_mfma_f32_16x16x32_bf16 v[120:123], v[156:159], v[194:197], v[120:123]
	v_mfma_f32_16x16x32_bf16 v[108:111], v[132:135], v[208:211], v[108:111]
	v_mfma_f32_16x16x32_bf16 v[104:107], v[156:159], v[208:211], v[104:107]
	v_mfma_f32_16x16x32_bf16 v[92:95], v[132:135], v[216:219], v[92:95]
	v_mfma_f32_16x16x32_bf16 v[88:91], v[156:159], v[216:219], v[88:91]
	v_mfma_f32_16x16x32_bf16 v[76:79], v[132:135], v[224:227], v[76:79]
	v_mfma_f32_16x16x32_bf16 v[72:75], v[156:159], v[224:227], v[72:75]
	s_setprio 0
	s_setprio 1
	v_mfma_f32_16x16x32_bf16 v[116:119], v[172:175], v[190:193], v[116:119]
	v_mfma_f32_16x16x32_bf16 v[112:115], v[182:185], v[190:193], v[112:115]
	v_mfma_f32_16x16x32_bf16 v[100:103], v[172:175], v[198:201], v[100:103]
	v_mfma_f32_16x16x32_bf16 v[96:99], v[182:185], v[198:201], v[96:99]
	v_mfma_f32_16x16x32_bf16 v[84:87], v[172:175], v[212:215], v[84:87]
	v_mfma_f32_16x16x32_bf16 v[80:83], v[182:185], v[212:215], v[80:83]
	v_mfma_f32_16x16x32_bf16 v[68:71], v[172:175], v[220:223], v[68:71]
	v_mfma_f32_16x16x32_bf16 v[64:67], v[182:185], v[220:223], v[64:67]
	v_mfma_f32_16x16x32_bf16 v[116:119], v[176:179], v[194:197], v[116:119]
	v_mfma_f32_16x16x32_bf16 v[112:115], v[186:189], v[194:197], v[112:115]
	v_mfma_f32_16x16x32_bf16 v[100:103], v[176:179], v[208:211], v[100:103]
	v_mfma_f32_16x16x32_bf16 v[96:99], v[186:189], v[208:211], v[96:99]
	v_mfma_f32_16x16x32_bf16 v[84:87], v[176:179], v[216:219], v[84:87]
	v_mfma_f32_16x16x32_bf16 v[80:83], v[186:189], v[216:219], v[80:83]
	v_mfma_f32_16x16x32_bf16 v[68:71], v[176:179], v[224:227], v[68:71]
	v_mfma_f32_16x16x32_bf16 v[64:67], v[186:189], v[224:227], v[64:67]
	s_setprio 0
	s_barrier
; #define PG8_STAGE(bufoff, gbase, voff) do { _Pragma("unroll") for (int _i = 0; _i < 2; ++_i) \
;         __builtin_amdgcn_global_load_lds((const unsigned*)((const char*)(gbase) + (voff)[_i]), (PG8_LAS unsigned*)(lds + (bufoff) + ldsw + _i * 8192), 16, 0, 0); } while (0)
; #define PG8_LDA(dst, b, h) do { _Pragma("unroll") for (int m = 0; m < 4; ++m) _Pragma("unroll") for (int k = 0; k < 2; ++k) dst[m][k] = *(const PG8_LAS bf16x8*)(lds + PG8_SA(b, h) + aoff + m * 2048 + k * 1024); } while (0)
; #define PG8_WAIT_V(n) asm volatile("s_waitcnt vmcnt(" #n ")" ::: "memory")
; template <class Epi, class Sched, bool ALIGN_EPI = false, bool SP2 = false>
; __device__ __forceinline__ void gemm_phase(PG8_LAS unsigned char* lds, const Gemm g, const Sched& S, const Epi& E) {
;     ...
;             PG8_LDA(At, 1, 1); PG8_STAGE(PG8_SB(1, 0), b3, voffB); PG8_STAGE(PG8_SB(1, 1), b3 + hstep, voffB); PG8_STAGE(PG8_SA(1, 0), a3, voffA);
;             PG8_WAIT_V(8); PG8_WAIT_L(0); PG8_BAR; PG8_MMA(1, 0, At, B0); PG8_MMA(1, 1, At, B1); PG8_BAR; PG8_SCHED;
;             } else {
;             PG8_LDB(B0, 0, 0); PG8_SCHED; PG8_LDA(At, 0, 0); PG8_STAGE(PG8_SA(1, 1), a1 + hstep, voffA);
;             PG8_WAIT_L(8); PG8_BAR; PG8_WAIT_L(0); PG8_MMA(0, 0, At, B0); PG8_BAR; PG8_SCHED;
;             PG8_LDB(B1, 0, 1); PG8_STAGE(PG8_SB(0, 0), b2, voffB);
;             PG8_BAR; PG8_WAIT_L(0); PG8_MMA(0, 1, At, B1); PG8_BAR;
;             PG8_LDA(At, 0, 1); PG8_STAGE(PG8_SA(0, 0), a2, voffA);
;             PG8_BAR; PG8_WAIT_L(0); PG8_MMA(1, 0, At, B0); PG8_BAR; PG8_SCHED;
;             PG8_STAGE(PG8_SB(0, 1), b2 + hstep, voffB);
;             PG8_WAIT_V(6); PG8_BAR; PG8_MMA(1, 1, At, B1); PG8_BAR;
;             PG8_LDB(B0, 1, 0); PG8_SCHED; PG8_LDA(At, 1, 0); PG8_STAGE(PG8_SA(0, 1), a2 + hstep, voffA);
;             PG8_WAIT_L(8); PG8_BAR; PG8_WAIT_L(0); PG8_MMA(0, 0, At, B0); PG8_BAR; PG8_SCHED;
;             PG8_LDB(B1, 1, 1); PG8_STAGE(PG8_SB(1, 0), b3, voffB);
;             PG8_BAR; PG8_WAIT_L(0); PG8_MMA(0, 1, At, B1); PG8_BAR;
;             PG8_LDA(At, 1, 1); PG8_STAGE(PG8_SA(1, 0), a3, voffA);
;             PG8_BAR; PG8_WAIT_L(0); PG8_MMA(1, 0, At, B0); PG8_BAR; PG8_SCHED;
;             PG8_STAGE(PG8_SB(1, 1), b3 + hstep, voffB);
;             PG8_WAIT_V(6); PG8_BAR; PG8_MMA(1, 1, At, B1); PG8_BAR;
;             }
;         }
;         if constexpr (ALIGN_EPI) { if (wr == 0) PG8_BAR; }
	s_add_i32 s3, s3, s43
	v_lshl_add_u64 v[160:161], v[160:161], 0, s[40:41]
	s_mov_b32 m0, s3
	ds_read_b128 v[190:193], v169 offset:49152
	ds_read_b128 v[194:197], v169 offset:50176
	ds_read_b128 v[198:201], v169 offset:51200
	ds_read_b128 v[208:211], v169 offset:52224
	ds_read_b128 v[212:215], v169 offset:53248
	ds_read_b128 v[216:219], v169 offset:54272
	ds_read_b128 v[220:223], v169 offset:55296
	ds_read_b128 v[224:227], v169 offset:56320
	global_load_lds_dwordx4 v[160:161], off
	s_add_i32 m0, s3, 0x2000
	s_add_u32 s10, s54, 0xb0080
	v_lshl_add_u64 v[160:161], v[202:203], 0, s[40:41]
	s_addc_u32 s11, s55, 0
	s_add_i32 s3, s14, s43
	global_load_lds_dwordx4 v[160:161], off
	v_lshl_add_u64 v[160:161], s[10:11], 0, v[138:139]
	s_mov_b32 m0, s3
	s_nop 0
	global_load_lds_dwordx4 v[160:161], off
	v_lshl_add_u64 v[160:161], s[10:11], 0, v[142:143]
	s_add_i32 m0, s3, 0x2000
	s_nop 0
	global_load_lds_dwordx4 v[160:161], off
	s_waitcnt vmcnt(6)
	s_waitcnt lgkmcnt(0)
	s_barrier
	s_setprio 1
	s_waitcnt lgkmcnt(0)
	v_mfma_f32_16x16x32_bf16 v[60:63], v[128:131], v[190:193], v[60:63]
	v_mfma_f32_16x16x32_bf16 v[56:59], v[152:155], v[190:193], v[56:59]
	v_mfma_f32_16x16x32_bf16 v[44:47], v[128:131], v[198:201], v[44:47]
	v_mfma_f32_16x16x32_bf16 v[40:43], v[152:155], v[198:201], v[40:43]
	v_mfma_f32_16x16x32_bf16 v[28:31], v[128:131], v[212:215], v[28:31]
	v_mfma_f32_16x16x32_bf16 v[24:27], v[152:155], v[212:215], v[24:27]
	v_lshl_add_u64 v[160:161], v[228:229], 0, s[40:41]
	s_mov_b32 m0, s63
	s_nop 0
	global_load_lds_dwordx4 v[160:161], off
	v_mfma_f32_16x16x32_bf16 v[12:15], v[128:131], v[220:223], v[12:15]
	v_mfma_f32_16x16x32_bf16 v[8:11], v[152:155], v[220:223], v[8:11]
	v_mfma_f32_16x16x32_bf16 v[60:63], v[132:135], v[194:197], v[60:63]
	v_mfma_f32_16x16x32_bf16 v[56:59], v[156:159], v[194:197], v[56:59]
	v_mfma_f32_16x16x32_bf16 v[44:47], v[132:135], v[208:211], v[44:47]
	v_mfma_f32_16x16x32_bf16 v[40:43], v[156:159], v[208:211], v[40:43]
	v_mfma_f32_16x16x32_bf16 v[28:31], v[132:135], v[216:219], v[28:31]
	v_mfma_f32_16x16x32_bf16 v[24:27], v[156:159], v[216:219], v[24:27]
	v_mfma_f32_16x16x32_bf16 v[12:15], v[132:135], v[224:227], v[12:15]
	v_mfma_f32_16x16x32_bf16 v[8:11], v[156:159], v[224:227], v[8:11]
	s_setprio 0
	s_setprio 1
	v_mfma_f32_16x16x32_bf16 v[52:55], v[172:175], v[190:193], v[52:55]
	v_mfma_f32_16x16x32_bf16 v[48:51], v[182:185], v[190:193], v[48:51]
	v_lshl_add_u64 v[160:161], v[230:231], 0, s[40:41]
	s_mov_b32 m0, s64
	s_nop 0
	global_load_lds_dwordx4 v[160:161], off
	v_mfma_f32_16x16x32_bf16 v[36:39], v[172:175], v[198:201], v[36:39]
	v_mfma_f32_16x16x32_bf16 v[32:35], v[182:185], v[198:201], v[32:35]
	v_mfma_f32_16x16x32_bf16 v[20:23], v[172:175], v[212:215], v[20:23]
	v_mfma_f32_16x16x32_bf16 v[16:19], v[182:185], v[212:215], v[16:19]
	v_mfma_f32_16x16x32_bf16 v[4:7], v[172:175], v[220:223], v[4:7]
	v_mfma_f32_16x16x32_bf16 v[0:3], v[182:185], v[220:223], v[0:3]
	v_mfma_f32_16x16x32_bf16 v[52:55], v[176:179], v[194:197], v[52:55]
	v_mfma_f32_16x16x32_bf16 v[48:51], v[186:189], v[194:197], v[48:51]
	v_mfma_f32_16x16x32_bf16 v[36:39], v[176:179], v[208:211], v[36:39]
	v_mfma_f32_16x16x32_bf16 v[32:35], v[186:189], v[208:211], v[32:35]
	v_mfma_f32_16x16x32_bf16 v[20:23], v[176:179], v[216:219], v[20:23]
	v_mfma_f32_16x16x32_bf16 v[16:19], v[186:189], v[216:219], v[16:19]
	v_mfma_f32_16x16x32_bf16 v[4:7], v[176:179], v[224:227], v[4:7]
	v_mfma_f32_16x16x32_bf16 v[0:3], v[186:189], v[224:227], v[0:3]
	s_setprio 0
	s_barrier
	s_add_i32 s93, s93, 2
	s_add_u32 s91, s91, 0x100
	s_addc_u32 s92, s92, 0
	s_cmp_gt_u32 s93, 41
	s_mov_b64 s[10:11], s[50:51]
	s_cbranch_scc0 .LBB0_269
	s_and_b64 vcc, exec, s[44:45]
	s_cbranch_vccz .LBB0_272
	s_barrier

; #define PG8_STAGE(bufoff, gbase, voff) do { _Pragma("unroll") for (int _i = 0; _i < 2; ++_i) \
;         __builtin_amdgcn_global_load_lds((const unsigned*)((const char*)(gbase) + (voff)[_i]), (PG8_LAS unsigned*)(lds + (bufoff) + ldsw + _i * 8192), 16, 0, 0); } while (0)
; #define PG8_LDA(dst, b, h) do { _Pragma("unroll") for (int m = 0; m < 4; ++m) _Pragma("unroll") for (int k = 0; k < 2; ++k) dst[m][k] = *(const PG8_LAS bf16x8*)(lds + PG8_SA(b, h) + aoff + m * 2048 + k * 1024); } while (0)
; #define PG8_LDB(dst, b, h) do { _Pragma("unroll") for (int n = 0; n < 2; ++n) _Pragma("unroll") for (int k = 0; k < 2; ++k) dst[n][k] = *(const PG8_LAS bf16x8*)(lds + PG8_SB(b, h) + boff + n * 2048 + k * 1024); } while (0)
; #define PG8_WAIT_V(n) asm volatile("s_waitcnt vmcnt(" #n ")" ::: "memory")
; #define PG8_WAIT_L(n) asm volatile("s_waitcnt lgkmcnt(" #n ")" ::: "memory")
; #define PG8_BAR __builtin_amdgcn_s_barrier()
; #define PG8_SCHED __builtin_amdgcn_sched_barrier(0)
; template <class Epi, class Sched, bool ALIGN_EPI = false, bool SP2 = false>
; __device__ __forceinline__ void gemm_phase(PG8_LAS unsigned char* lds, const Gemm g, const Sched& S, const Epi& E) {
;     ...
;         const char* nA = has_next ? (const char*)g.A + (size_t)nxt.pm * tstep : cA; const char* nB = has_next ? (const char*)g.Bt + (size_t)nxt.pn * tstep : cB;
;         for (int t = 0; t < nt; t += 2) {
;             const bool last = (t == nt - 2);
;             const char* a1 = cA + (size_t)(t + 1) * kstep;
;             const char* a2 = last ? nA : cA + (size_t)(t + 2) * kstep; const char* b2 = last ? nB : cB + (size_t)(t + 2) * kstep;
;             const char* a3 = a2 + kstep; const char* b3 = b2 + kstep;
;             if (last && has_next) S.a_ready(nxt);
;             if constexpr (SP2) {
;             PG8_LDB(B0, 0, 0); PG8_LDB(B1, 0, 1); PG8_SCHED; PG8_LDA(At, 0, 0); PG8_STAGE(PG8_SA(1, 1), a1 + hstep, voffA);
;             PG8_WAIT_V(8); PG8_WAIT_L(0); PG8_BAR; PG8_MMA(0, 0, At, B0); PG8_MMA(0, 1, At, B1); PG8_BAR; PG8_SCHED;
;             PG8_LDA(At, 0, 1); PG8_STAGE(PG8_SB(0, 0), b2, voffB); PG8_STAGE(PG8_SB(0, 1), b2 + hstep, voffB); PG8_STAGE(PG8_SA(0, 0), a2, voffA);
;             PG8_WAIT_V(8); PG8_WAIT_L(0); PG8_BAR; PG8_MMA(1, 0, At, B0); PG8_MMA(1, 1, At, B1); PG8_BAR; PG8_SCHED;
.LBB0_416:
	s_ashr_i32 s45, s44, 31
	s_lshl_b64 s[14:15], s[44:45], 19
	s_add_u32 s48, s22, s14
	s_addc_u32 s49, s23, s15
	s_and_b64 s[14:15], s[6:7], exec
	s_cselect_b32 s45, s49, s55
	s_cselect_b32 s89, s48, s54
	s_ashr_i32 s41, s40, 31
	s_lshl_b64 s[14:15], s[40:41], 19
	s_add_u32 s50, s84, s14
	s_addc_u32 s51, s85, s15
	s_and_b64 s[14:15], s[6:7], exec
	s_cselect_b32 s41, s51, s57
	s_cselect_b32 s90, s50, s56
	s_add_u32 s54, s54, 0x40080
	s_addc_u32 s55, s55, 0
	s_add_u32 s91, s56, 0x100
	s_addc_u32 s92, s57, 0
	s_mov_b32 s93, -2
	ds_read_b128 v[154:157], v169
	ds_read_b128 v[158:161], v169 offset:1024
	ds_read_b128 v[162:165], v169 offset:2048
	ds_read_b128 v[174:177], v169 offset:3072
	ds_read_b128 v[182:185], v170
	ds_read_b128 v[186:189], v170 offset:1024
	ds_read_b128 v[190:193], v170 offset:2048
	ds_read_b128 v[194:197], v170 offset:3072
	s_add_u32 s3, s54, 0xfffc0080
	s_addc_u32 s14, s55, -1
	s_cmp_eq_u32 s93, 12
	s_cselect_b32 s59, s45, s14
	s_cselect_b32 s58, s89, s3
	s_cselect_b32 s57, s41, s92
	s_cselect_b32 s56, s90, s91
	v_lshl_add_u64 v[178:179], s[54:55], 0, v[146:147]
	s_add_i32 m0, s60, 0xc000
	ds_read_b128 v[198:201], v171
	ds_read_b128 v[208:211], v171 offset:1024
	ds_read_b128 v[212:215], v171 offset:2048
	ds_read_b128 v[216:219], v171 offset:3072
	ds_read_b128 v[220:223], v171 offset:4096
	ds_read_b128 v[224:227], v171 offset:5120
	ds_read_b128 v[228:231], v171 offset:6144
	ds_read_b128 v[232:235], v171 offset:7168
	global_load_lds_dwordx4 v[178:179], off
	v_lshl_add_u64 v[178:179], s[54:55], 0, v[148:149]
	s_add_i32 m0, s60, 0xe000
	s_nop 0
	global_load_lds_dwordx4 v[178:179], off
	s_waitcnt vmcnt(8)
	s_waitcnt lgkmcnt(0)
	s_barrier
	s_setprio 1
	s_waitcnt lgkmcnt(0)
	v_mfma_f32_16x16x32_bf16 v[124:127], v[154:157], v[198:201], 0
	v_mfma_f32_16x16x32_bf16 v[120:123], v[162:165], v[198:201], 0
	v_mfma_f32_16x16x32_bf16 v[116:119], v[154:157], v[212:215], 0
	v_mfma_f32_16x16x32_bf16 v[112:115], v[162:165], v[212:215], 0
	v_mfma_f32_16x16x32_bf16 v[108:111], v[154:157], v[220:223], 0
	v_mfma_f32_16x16x32_bf16 v[104:107], v[162:165], v[220:223], 0
	v_mfma_f32_16x16x32_bf16 v[100:103], v[154:157], v[228:231], 0
	v_mfma_f32_16x16x32_bf16 v[96:99], v[162:165], v[228:231], 0
	v_mfma_f32_16x16x32_bf16 v[124:127], v[158:161], v[208:211], v[124:127]
	v_mfma_f32_16x16x32_bf16 v[120:123], v[174:177], v[208:211], v[120:123]
	v_mfma_f32_16x16x32_bf16 v[116:119], v[158:161], v[216:219], v[116:119]
	v_mfma_f32_16x16x32_bf16 v[112:115], v[174:177], v[216:219], v[112:115]
	v_mfma_f32_16x16x32_bf16 v[108:111], v[158:161], v[224:227], v[108:111]
	v_mfma_f32_16x16x32_bf16 v[104:107], v[174:177], v[224:227], v[104:107]
	v_mfma_f32_16x16x32_bf16 v[100:103], v[158:161], v[232:235], v[100:103]
	v_mfma_f32_16x16x32_bf16 v[96:99], v[174:177], v[232:235], v[96:99]
	s_setprio 0
	s_setprio 1
	v_mfma_f32_16x16x32_bf16 v[68:71], v[182:185], v[198:201], 0
	v_mfma_f32_16x16x32_bf16 v[64:67], v[190:193], v[198:201], 0
	v_mfma_f32_16x16x32_bf16 v[52:55], v[182:185], v[212:215], 0
	v_mfma_f32_16x16x32_bf16 v[48:51], v[190:193], v[212:215], 0
	v_mfma_f32_16x16x32_bf16 v[44:47], v[182:185], v[220:223], 0
	v_mfma_f32_16x16x32_bf16 v[40:43], v[190:193], v[220:223], 0
	v_mfma_f32_16x16x32_bf16 v[36:39], v[182:185], v[228:231], 0
	v_mfma_f32_16x16x32_bf16 v[32:35], v[190:193], v[228:231], 0
	v_mfma_f32_16x16x32_bf16 v[68:71], v[186:189], v[208:211], v[68:71]
	v_mfma_f32_16x16x32_bf16 v[64:67], v[194:197], v[208:211], v[64:67]
	v_mfma_f32_16x16x32_bf16 v[52:55], v[186:189], v[216:219], v[52:55]
	v_mfma_f32_16x16x32_bf16 v[48:51], v[194:197], v[216:219], v[48:51]
	v_mfma_f32_16x16x32_bf16 v[44:47], v[186:189], v[224:227], v[44:47]
	v_mfma_f32_16x16x32_bf16 v[40:43], v[194:197], v[224:227], v[40:43]
	v_mfma_f32_16x16x32_bf16 v[36:39], v[186:189], v[232:235], v[36:39]
	v_mfma_f32_16x16x32_bf16 v[32:35], v[194:197], v[232:235], v[32:35]
	s_setprio 0
	s_barrier
	s_add_i32 s3, s86, s34
	v_lshl_add_u64 v[178:179], s[56:57], 0, v[132:133]
	s_mov_b32 m0, s3
	ds_read_b128 v[198:201], v171 offset:16384
	ds_read_b128 v[208:211], v171 offset:17408
	ds_read_b128 v[212:215], v171 offset:18432
	ds_read_b128 v[216:219], v171 offset:19456
	ds_read_b128 v[220:223], v171 offset:20480
	ds_read_b128 v[224:227], v171 offset:21504
	ds_read_b128 v[228:231], v171 offset:22528
	ds_read_b128 v[232:235], v171 offset:23552
	global_load_lds_dwordx4 v[178:179], off
	s_add_i32 m0, s3, 0x2000
	s_add_u32 s14, s56, 0x40000
	v_lshl_add_u64 v[202:203], s[56:57], 0, v[128:129]
	s_addc_u32 s15, s57, 0
	s_add_i32 s3, s87, s34
	global_load_lds_dwordx4 v[202:203], off
	v_lshl_add_u64 v[236:237], s[14:15], 0, v[132:133]
	s_mov_b32 m0, s3
	v_lshl_add_u64 v[238:239], s[58:59], 0, v[130:131]
	global_load_lds_dwordx4 v[236:237], off
	v_lshl_add_u64 v[236:237], s[14:15], 0, v[128:129]
	s_add_i32 m0, s3, 0x2000
	s_nop 0
	global_load_lds_dwordx4 v[236:237], off
	s_waitcnt vmcnt(6)
	s_waitcnt lgkmcnt(0)
	s_barrier
; #define PG8_STAGE(bufoff, gbase, voff) do { _Pragma("unroll") for (int _i = 0; _i < 2; ++_i) \
;         __builtin_amdgcn_global_load_lds((const unsigned*)((const char*)(gbase) + (voff)[_i]), (PG8_LAS unsigned*)(lds + (bufoff) + ldsw + _i * 8192), 16, 0, 0); } while (0)
; #define PG8_LDA(dst, b, h) do { _Pragma("unroll") for (int m = 0; m < 4; ++m) _Pragma("unroll") for (int k = 0; k < 2; ++k) dst[m][k] = *(const PG8_LAS bf16x8*)(lds + PG8_SA(b, h) + aoff + m * 2048 + k * 1024); } while (0)
; #define PG8_LDB(dst, b, h) do { _Pragma("unroll") for (int n = 0; n < 2; ++n) _Pragma("unroll") for (int k = 0; k < 2; ++k) dst[n][k] = *(const PG8_LAS bf16x8*)(lds + PG8_SB(b, h) + boff + n * 2048 + k * 1024); } while (0)
; #define PG8_MMA(ai, bj, At, Bt) do { __builtin_amdgcn_s_setprio(1); _Pragma("unroll") for (int m = 0; m < 4; ++m) _Pragma("unroll") for (int n = 0; n < 2; ++n) _Pragma("unroll") for (int k = 0; k < 2; ++k) \
;         acc[ai][bj][m][n] = __builtin_amdgcn_mfma_f32_16x16x32_bf16(Bt[n][k], At[m][k], acc[ai][bj][m][n], 0, 0, 0); __builtin_amdgcn_s_setprio(0); } while (0)
; #define PG8_WAIT_V(n) asm volatile("s_waitcnt vmcnt(" #n ")" ::: "memory")
; #define PG8_WAIT_L(n) asm volatile("s_waitcnt lgkmcnt(" #n ")" ::: "memory")
; #define PG8_BAR __builtin_amdgcn_s_barrier()
; #define PG8_SCHED __builtin_amdgcn_sched_barrier(0)
; template <class Epi, class Sched, bool ALIGN_EPI = false, bool SP2 = false>
; __device__ __forceinline__ void gemm_phase(PG8_LAS unsigned char* lds, const Gemm g, const Sched& S, const Epi& E) {
;     ...
;             PG8_WAIT_V(8); PG8_WAIT_L(0); PG8_BAR; PG8_MMA(1, 0, At, B0); PG8_MMA(1, 1, At, B1); PG8_BAR; PG8_SCHED;
;             PG8_LDB(B0, 1, 0); PG8_LDB(B1, 1, 1); PG8_SCHED; PG8_LDA(At, 1, 0); PG8_STAGE(PG8_SA(0, 1), a2 + hstep, voffA);
;             PG8_WAIT_V(8); PG8_WAIT_L(0); PG8_BAR; PG8_MMA(0, 0, At, B0); PG8_MMA(0, 1, At, B1); PG8_BAR; PG8_SCHED;
	s_setprio 1
	s_waitcnt lgkmcnt(0)
	v_mfma_f32_16x16x32_bf16 v[92:95], v[154:157], v[198:201], 0
	v_mfma_f32_16x16x32_bf16 v[88:91], v[162:165], v[198:201], 0
	v_mfma_f32_16x16x32_bf16 v[84:87], v[154:157], v[212:215], 0
	v_mfma_f32_16x16x32_bf16 v[80:83], v[162:165], v[212:215], 0
	v_mfma_f32_16x16x32_bf16 v[76:79], v[154:157], v[220:223], 0
	v_mfma_f32_16x16x32_bf16 v[72:75], v[162:165], v[220:223], 0
	v_lshl_add_u64 v[236:237], s[58:59], 0, v[134:135]
	s_mov_b32 m0, s60
	s_nop 0
	global_load_lds_dwordx4 v[236:237], off
	v_mfma_f32_16x16x32_bf16 v[60:63], v[154:157], v[228:231], 0
	v_mfma_f32_16x16x32_bf16 v[56:59], v[162:165], v[228:231], 0
	v_mfma_f32_16x16x32_bf16 v[92:95], v[158:161], v[208:211], v[92:95]
	v_mfma_f32_16x16x32_bf16 v[88:91], v[174:177], v[208:211], v[88:91]
	v_mfma_f32_16x16x32_bf16 v[84:87], v[158:161], v[216:219], v[84:87]
	v_mfma_f32_16x16x32_bf16 v[80:83], v[174:177], v[216:219], v[80:83]
	v_mfma_f32_16x16x32_bf16 v[76:79], v[158:161], v[224:227], v[76:79]
	v_mfma_f32_16x16x32_bf16 v[72:75], v[174:177], v[224:227], v[72:75]
	v_mfma_f32_16x16x32_bf16 v[60:63], v[158:161], v[232:235], v[60:63]
	v_mfma_f32_16x16x32_bf16 v[56:59], v[174:177], v[232:235], v[56:59]
	s_setprio 0
	s_setprio 1
	v_mfma_f32_16x16x32_bf16 v[28:31], v[182:185], v[198:201], 0
	v_mfma_f32_16x16x32_bf16 v[24:27], v[190:193], v[198:201], 0
	s_mov_b32 m0, s61
	s_nop 0
	global_load_lds_dwordx4 v[238:239], off
	v_mfma_f32_16x16x32_bf16 v[20:23], v[182:185], v[212:215], 0
	v_mfma_f32_16x16x32_bf16 v[16:19], v[190:193], v[212:215], 0
	v_mfma_f32_16x16x32_bf16 v[12:15], v[182:185], v[220:223], 0
	v_mfma_f32_16x16x32_bf16 v[8:11], v[190:193], v[220:223], 0
	v_mfma_f32_16x16x32_bf16 v[4:7], v[182:185], v[228:231], 0
	v_mfma_f32_16x16x32_bf16 v[0:3], v[190:193], v[228:231], 0
	v_mfma_f32_16x16x32_bf16 v[28:31], v[186:189], v[208:211], v[28:31]
	v_mfma_f32_16x16x32_bf16 v[24:27], v[194:197], v[208:211], v[24:27]
	v_mfma_f32_16x16x32_bf16 v[20:23], v[186:189], v[216:219], v[20:23]
	v_mfma_f32_16x16x32_bf16 v[16:19], v[194:197], v[216:219], v[16:19]
	v_mfma_f32_16x16x32_bf16 v[12:15], v[186:189], v[224:227], v[12:15]
	v_mfma_f32_16x16x32_bf16 v[8:11], v[194:197], v[224:227], v[8:11]
	v_mfma_f32_16x16x32_bf16 v[4:7], v[186:189], v[232:235], v[4:7]
	v_mfma_f32_16x16x32_bf16 v[0:3], v[194:197], v[232:235], v[0:3]
	s_setprio 0
	s_barrier
	s_add_i32 s3, 0, 0x18000
	v_add_u32_e32 v136, s3, v143
	s_add_i32 s33, 0, 0x1c000
	ds_read_b128 v[154:157], v136
	ds_read_b128 v[158:161], v136 offset:1024
	ds_read_b128 v[162:165], v136 offset:2048
	ds_read_b128 v[174:177], v136 offset:3072
	v_add_u32_e32 v136, s33, v143
	ds_read_b128 v[182:185], v136
	ds_read_b128 v[186:189], v136 offset:1024
	ds_read_b128 v[190:193], v136 offset:2048
	ds_read_b128 v[194:197], v136 offset:3072
	s_add_u32 s14, s58, 0x40000
	s_addc_u32 s15, s59, 0
	s_mov_b32 m0, s62
	v_lshl_add_u64 v[240:241], s[14:15], 0, v[134:135]
	ds_read_b128 v[198:201], v171 offset:32768
	ds_read_b128 v[208:211], v171 offset:33792
	ds_read_b128 v[212:215], v171 offset:34816
	ds_read_b128 v[216:219], v171 offset:35840
	ds_read_b128 v[220:223], v171 offset:36864
	ds_read_b128 v[224:227], v171 offset:37888
	ds_read_b128 v[228:231], v171 offset:38912
	ds_read_b128 v[232:235], v171 offset:39936
	global_load_lds_dwordx4 v[240:241], off
	v_lshl_add_u64 v[240:241], s[14:15], 0, v[130:131]
	s_mov_b32 m0, s63
	s_nop 0
	global_load_lds_dwordx4 v[240:241], off
	s_waitcnt vmcnt(8)
	s_waitcnt lgkmcnt(0)
	s_barrier
	s_setprio 1
	s_waitcnt lgkmcnt(0)
	v_mfma_f32_16x16x32_bf16 v[124:127], v[154:157], v[198:201], v[124:127]
	v_mfma_f32_16x16x32_bf16 v[120:123], v[162:165], v[198:201], v[120:123]
	v_mfma_f32_16x16x32_bf16 v[116:119], v[154:157], v[212:215], v[116:119]
	v_mfma_f32_16x16x32_bf16 v[112:115], v[162:165], v[212:215], v[112:115]
	v_mfma_f32_16x16x32_bf16 v[108:111], v[154:157], v[220:223], v[108:111]
	v_mfma_f32_16x16x32_bf16 v[104:107], v[162:165], v[220:223], v[104:107]
	v_mfma_f32_16x16x32_bf16 v[100:103], v[154:157], v[228:231], v[100:103]
	v_mfma_f32_16x16x32_bf16 v[96:99], v[162:165], v[228:231], v[96:99]
	v_mfma_f32_16x16x32_bf16 v[124:127], v[158:161], v[208:211], v[124:127]
	v_mfma_f32_16x16x32_bf16 v[120:123], v[174:177], v[208:211], v[120:123]
	v_mfma_f32_16x16x32_bf16 v[116:119], v[158:161], v[216:219], v[116:119]
	v_mfma_f32_16x16x32_bf16 v[112:115], v[174:177], v[216:219], v[112:115]
	v_mfma_f32_16x16x32_bf16 v[108:111], v[158:161], v[224:227], v[108:111]
	v_mfma_f32_16x16x32_bf16 v[104:107], v[174:177], v[224:227], v[104:107]
	v_mfma_f32_16x16x32_bf16 v[100:103], v[158:161], v[232:235], v[100:103]
	v_mfma_f32_16x16x32_bf16 v[96:99], v[174:177], v[232:235], v[96:99]
	s_setprio 0
	s_setprio 1
	v_mfma_f32_16x16x32_bf16 v[68:71], v[182:185], v[198:201], v[68:71]
	v_mfma_f32_16x16x32_bf16 v[64:67], v[190:193], v[198:201], v[64:67]
	v_mfma_f32_16x16x32_bf16 v[52:55], v[182:185], v[212:215], v[52:55]
	v_mfma_f32_16x16x32_bf16 v[48:51], v[190:193], v[212:215], v[48:51]
	v_mfma_f32_16x16x32_bf16 v[44:47], v[182:185], v[220:223], v[44:47]
	v_mfma_f32_16x16x32_bf16 v[40:43], v[190:193], v[220:223], v[40:43]
	v_mfma_f32_16x16x32_bf16 v[36:39], v[182:185], v[228:231], v[36:39]
	v_mfma_f32_16x16x32_bf16 v[32:35], v[190:193], v[228:231], v[32:35]
	v_mfma_f32_16x16x32_bf16 v[68:71], v[186:189], v[208:211], v[68:71]
	v_mfma_f32_16x16x32_bf16 v[64:67], v[194:197], v[208:211], v[64:67]
	v_mfma_f32_16x16x32_bf16 v[52:55], v[186:189], v[216:219], v[52:55]
	v_mfma_f32_16x16x32_bf16 v[48:51], v[194:197], v[216:219], v[48:51]
	v_mfma_f32_16x16x32_bf16 v[44:47], v[186:189], v[224:227], v[44:47]
	v_mfma_f32_16x16x32_bf16 v[40:43], v[194:197], v[224:227], v[40:43]
	v_mfma_f32_16x16x32_bf16 v[36:39], v[186:189], v[232:235], v[36:39]
	v_mfma_f32_16x16x32_bf16 v[32:35], v[194:197], v[232:235], v[32:35]
	s_setprio 0
	s_barrier
; #define PG8_STAGE(bufoff, gbase, voff) do { _Pragma("unroll") for (int _i = 0; _i < 2; ++_i) \
;         __builtin_amdgcn_global_load_lds((const unsigned*)((const char*)(gbase) + (voff)[_i]), (PG8_LAS unsigned*)(lds + (bufoff) + ldsw + _i * 8192), 16, 0, 0); } while (0)
; #define PG8_LDA(dst, b, h) do { _Pragma("unroll") for (int m = 0; m < 4; ++m) _Pragma("unroll") for (int k = 0; k < 2; ++k) dst[m][k] = *(const PG8_LAS bf16x8*)(lds + PG8_SA(b, h) + aoff + m * 2048 + k * 1024); } while (0)
; #define PG8_LDB(dst, b, h) do { _Pragma("unroll") for (int n = 0; n < 2; ++n) _Pragma("unroll") for (int k = 0; k < 2; ++k) dst[n][k] = *(const PG8_LAS bf16x8*)(lds + PG8_SB(b, h) + boff + n * 2048 + k * 1024); } while (0)
; #define PG8_MMA(ai, bj, At, Bt) do { __builtin_amdgcn_s_setprio(1); _Pragma("unroll") for (int m = 0; m < 4; ++m) _Pragma("unroll") for (int n = 0; n < 2; ++n) _Pragma("unroll") for (int k = 0; k < 2; ++k) \
;         acc[ai][bj][m][n] = __builtin_amdgcn_mfma_f32_16x16x32_bf16(Bt[n][k], At[m][k], acc[ai][bj][m][n], 0, 0, 0); __builtin_amdgcn_s_setprio(0); } while (0)
; #define PG8_WAIT_V(n) asm volatile("s_waitcnt vmcnt(" #n ")" ::: "memory")
; #define PG8_BAR __builtin_amdgcn_s_barrier()
; template <class Epi, class Sched, bool ALIGN_EPI = false, bool SP2 = false>
; __device__ __forceinline__ void gemm_phase(PG8_LAS unsigned char* lds, const Gemm g, const Sched& S, const Epi& E) {
;     ...
;         for (int t = 0; t < nt; t += 2) {
;             const bool last = (t == nt - 2);
;             const char* a1 = cA + (size_t)(t + 1) * kstep;
;             const char* a2 = last ? nA : cA + (size_t)(t + 2) * kstep; const char* b2 = last ? nB : cB + (size_t)(t + 2) * kstep;
;             const char* a3 = a2 + kstep; const char* b3 = b2 + kstep;
;             if (last && has_next) S.a_ready(nxt);
;             if constexpr (SP2) {
;             PG8_LDB(B0, 0, 0); PG8_LDB(B1, 0, 1); PG8_SCHED; PG8_LDA(At, 0, 0); PG8_STAGE(PG8_SA(1, 1), a1 + hstep, voffA);
;             PG8_WAIT_V(8); PG8_WAIT_L(0); PG8_BAR; PG8_MMA(0, 0, At, B0); PG8_MMA(0, 1, At, B1); PG8_BAR; PG8_SCHED;
;     ...
;             PG8_LDA(At, 1, 1); PG8_STAGE(PG8_SB(1, 0), b3, voffB); PG8_STAGE(PG8_SB(1, 1), b3 + hstep, voffB); PG8_STAGE(PG8_SA(1, 0), a3, voffA);
;             PG8_WAIT_V(8); PG8_WAIT_L(0); PG8_BAR; PG8_MMA(1, 0, At, B0); PG8_MMA(1, 1, At, B1); PG8_BAR; PG8_SCHED;
	s_add_i32 s3, s3, s34
	v_lshl_add_u64 v[178:179], v[178:179], 0, s[8:9]
	s_mov_b32 m0, s3
	ds_read_b128 v[198:201], v171 offset:49152
	ds_read_b128 v[208:211], v171 offset:50176
	ds_read_b128 v[212:215], v171 offset:51200
	ds_read_b128 v[216:219], v171 offset:52224
	ds_read_b128 v[220:223], v171 offset:53248
	ds_read_b128 v[224:227], v171 offset:54272
	ds_read_b128 v[228:231], v171 offset:55296
	ds_read_b128 v[232:235], v171 offset:56320
	global_load_lds_dwordx4 v[178:179], off
	s_add_i32 m0, s3, 0x2000
	s_add_u32 s14, s56, 0x40080
	v_lshl_add_u64 v[178:179], v[202:203], 0, s[8:9]
	s_addc_u32 s15, s57, 0
	s_add_i32 s3, s33, s34
	global_load_lds_dwordx4 v[178:179], off
	v_lshl_add_u64 v[178:179], s[14:15], 0, v[132:133]
	s_mov_b32 m0, s3
	s_nop 0
	global_load_lds_dwordx4 v[178:179], off
	v_lshl_add_u64 v[178:179], s[14:15], 0, v[128:129]
	s_add_i32 m0, s3, 0x2000
	s_nop 0
	global_load_lds_dwordx4 v[178:179], off
	s_waitcnt vmcnt(6)
	s_waitcnt lgkmcnt(0)
	s_barrier
	s_setprio 1
	s_waitcnt lgkmcnt(0)
	v_mfma_f32_16x16x32_bf16 v[92:95], v[154:157], v[198:201], v[92:95]
	v_mfma_f32_16x16x32_bf16 v[88:91], v[162:165], v[198:201], v[88:91]
	v_mfma_f32_16x16x32_bf16 v[84:87], v[154:157], v[212:215], v[84:87]
	v_mfma_f32_16x16x32_bf16 v[80:83], v[162:165], v[212:215], v[80:83]
	v_mfma_f32_16x16x32_bf16 v[76:79], v[154:157], v[220:223], v[76:79]
	v_mfma_f32_16x16x32_bf16 v[72:75], v[162:165], v[220:223], v[72:75]
	v_lshl_add_u64 v[178:179], v[236:237], 0, s[8:9]
	s_mov_b32 m0, s66
	s_nop 0
	global_load_lds_dwordx4 v[178:179], off
	v_mfma_f32_16x16x32_bf16 v[60:63], v[154:157], v[228:231], v[60:63]
	v_mfma_f32_16x16x32_bf16 v[56:59], v[162:165], v[228:231], v[56:59]
	v_mfma_f32_16x16x32_bf16 v[92:95], v[158:161], v[208:211], v[92:95]
	v_mfma_f32_16x16x32_bf16 v[88:91], v[174:177], v[208:211], v[88:91]
	v_mfma_f32_16x16x32_bf16 v[84:87], v[158:161], v[216:219], v[84:87]
	v_mfma_f32_16x16x32_bf16 v[80:83], v[174:177], v[216:219], v[80:83]
	v_mfma_f32_16x16x32_bf16 v[76:79], v[158:161], v[224:227], v[76:79]
	v_mfma_f32_16x16x32_bf16 v[72:75], v[174:177], v[224:227], v[72:75]
	v_mfma_f32_16x16x32_bf16 v[60:63], v[158:161], v[232:235], v[60:63]
	v_mfma_f32_16x16x32_bf16 v[56:59], v[174:177], v[232:235], v[56:59]
	s_setprio 0
	s_setprio 1
	v_mfma_f32_16x16x32_bf16 v[28:31], v[182:185], v[198:201], v[28:31]
	v_mfma_f32_16x16x32_bf16 v[24:27], v[190:193], v[198:201], v[24:27]
	v_lshl_add_u64 v[178:179], v[238:239], 0, s[8:9]
	s_mov_b32 m0, s67
	s_nop 0
	global_load_lds_dwordx4 v[178:179], off
	v_mfma_f32_16x16x32_bf16 v[20:23], v[182:185], v[212:215], v[20:23]
	v_mfma_f32_16x16x32_bf16 v[16:19], v[190:193], v[212:215], v[16:19]
	v_mfma_f32_16x16x32_bf16 v[12:15], v[182:185], v[220:223], v[12:15]
	v_mfma_f32_16x16x32_bf16 v[8:11], v[190:193], v[220:223], v[8:11]
	v_mfma_f32_16x16x32_bf16 v[4:7], v[182:185], v[228:231], v[4:7]
	v_mfma_f32_16x16x32_bf16 v[0:3], v[190:193], v[228:231], v[0:3]
	v_mfma_f32_16x16x32_bf16 v[28:31], v[186:189], v[208:211], v[28:31]
	v_mfma_f32_16x16x32_bf16 v[24:27], v[194:197], v[208:211], v[24:27]
	v_mfma_f32_16x16x32_bf16 v[20:23], v[186:189], v[216:219], v[20:23]
	v_mfma_f32_16x16x32_bf16 v[16:19], v[194:197], v[216:219], v[16:19]
	v_mfma_f32_16x16x32_bf16 v[12:15], v[186:189], v[224:227], v[12:15]
	v_mfma_f32_16x16x32_bf16 v[8:11], v[194:197], v[224:227], v[8:11]
	v_mfma_f32_16x16x32_bf16 v[4:7], v[186:189], v[232:235], v[4:7]
	v_mfma_f32_16x16x32_bf16 v[0:3], v[194:197], v[232:235], v[0:3]
	s_setprio 0
	s_barrier
	s_add_i32 s93, s93, 2
	s_add_u32 s54, s54, 0x100
	s_addc_u32 s55, s55, 0
	s_add_u32 s91, s91, 0x100
	s_addc_u32 s92, s92, 0
.LBB0_417:
	ds_read_b128 v[154:157], v169
	ds_read_b128 v[158:161], v169 offset:1024
	ds_read_b128 v[162:165], v169 offset:2048
	ds_read_b128 v[174:177], v169 offset:3072
	ds_read_b128 v[182:185], v170
	ds_read_b128 v[186:189], v170 offset:1024
	ds_read_b128 v[190:193], v170 offset:2048
	ds_read_b128 v[194:197], v170 offset:3072
	s_add_u32 s3, s54, 0xfffc0080
	s_addc_u32 s14, s55, -1
	s_cmp_eq_u32 s93, 12
	s_cselect_b32 s59, s45, s14
	s_cselect_b32 s58, s89, s3
	s_cselect_b32 s57, s41, s92
	s_cselect_b32 s56, s90, s91
	v_lshl_add_u64 v[178:179], s[54:55], 0, v[146:147]
	s_add_i32 m0, s60, 0xc000
	ds_read_b128 v[198:201], v171
	ds_read_b128 v[208:211], v171 offset:1024
	ds_read_b128 v[212:215], v171 offset:2048
	ds_read_b128 v[216:219], v171 offset:3072
	ds_read_b128 v[220:223], v171 offset:4096
	ds_read_b128 v[224:227], v171 offset:5120
	ds_read_b128 v[228:231], v171 offset:6144
	ds_read_b128 v[232:235], v171 offset:7168
	global_load_lds_dwordx4 v[178:179], off
	v_lshl_add_u64 v[178:179], s[54:55], 0, v[148:149]
	s_add_i32 m0, s60, 0xe000
	s_nop 0
	global_load_lds_dwordx4 v[178:179], off
	s_waitcnt vmcnt(8)
	s_waitcnt lgkmcnt(0)
	s_barrier
; #define PG8_STAGE(bufoff, gbase, voff) do { _Pragma("unroll") for (int _i = 0; _i < 2; ++_i) \
;         __builtin_amdgcn_global_load_lds((const unsigned*)((const char*)(gbase) + (voff)[_i]), (PG8_LAS unsigned*)(lds + (bufoff) + ldsw + _i * 8192), 16, 0, 0); } while (0)
; #define PG8_LDA(dst, b, h) do { _Pragma("unroll") for (int m = 0; m < 4; ++m) _Pragma("unroll") for (int k = 0; k < 2; ++k) dst[m][k] = *(const PG8_LAS bf16x8*)(lds + PG8_SA(b, h) + aoff + m * 2048 + k * 1024); } while (0)
; #define PG8_LDB(dst, b, h) do { _Pragma("unroll") for (int n = 0; n < 2; ++n) _Pragma("unroll") for (int k = 0; k < 2; ++k) dst[n][k] = *(const PG8_LAS bf16x8*)(lds + PG8_SB(b, h) + boff + n * 2048 + k * 1024); } while (0)
; #define PG8_MMA(ai, bj, At, Bt) do { __builtin_amdgcn_s_setprio(1); _Pragma("unroll") for (int m = 0; m < 4; ++m) _Pragma("unroll") for (int n = 0; n < 2; ++n) _Pragma("unroll") for (int k = 0; k < 2; ++k) \
;         acc[ai][bj][m][n] = __builtin_amdgcn_mfma_f32_16x16x32_bf16(Bt[n][k], At[m][k], acc[ai][bj][m][n], 0, 0, 0); __builtin_amdgcn_s_setprio(0); } while (0)
; #define PG8_WAIT_V(n) asm volatile("s_waitcnt vmcnt(" #n ")" ::: "memory")
; #define PG8_WAIT_L(n) asm volatile("s_waitcnt lgkmcnt(" #n ")" ::: "memory")
; #define PG8_BAR __builtin_amdgcn_s_barrier()
; #define PG8_SCHED __builtin_amdgcn_sched_barrier(0)
; template <class Epi, class Sched, bool ALIGN_EPI = false, bool SP2 = false>
; __device__ __forceinline__ void gemm_phase(PG8_LAS unsigned char* lds, const Gemm g, const Sched& S, const Epi& E) {
;     ...
;             PG8_LDB(B0, 0, 0); PG8_LDB(B1, 0, 1); PG8_SCHED; PG8_LDA(At, 0, 0); PG8_STAGE(PG8_SA(1, 1), a1 + hstep, voffA);
;             PG8_WAIT_V(8); PG8_WAIT_L(0); PG8_BAR; PG8_MMA(0, 0, At, B0); PG8_MMA(0, 1, At, B1); PG8_BAR; PG8_SCHED;
;             PG8_LDA(At, 0, 1); PG8_STAGE(PG8_SB(0, 0), b2, voffB); PG8_STAGE(PG8_SB(0, 1), b2 + hstep, voffB); PG8_STAGE(PG8_SA(0, 0), a2, voffA);
;             PG8_WAIT_V(8); PG8_WAIT_L(0); PG8_BAR; PG8_MMA(1, 0, At, B0); PG8_MMA(1, 1, At, B1); PG8_BAR; PG8_SCHED;
	s_setprio 1
	s_waitcnt lgkmcnt(0)
	v_mfma_f32_16x16x32_bf16 v[124:127], v[154:157], v[198:201], v[124:127]
	v_mfma_f32_16x16x32_bf16 v[120:123], v[162:165], v[198:201], v[120:123]
	v_mfma_f32_16x16x32_bf16 v[116:119], v[154:157], v[212:215], v[116:119]
	v_mfma_f32_16x16x32_bf16 v[112:115], v[162:165], v[212:215], v[112:115]
	v_mfma_f32_16x16x32_bf16 v[108:111], v[154:157], v[220:223], v[108:111]
	v_mfma_f32_16x16x32_bf16 v[104:107], v[162:165], v[220:223], v[104:107]
	v_mfma_f32_16x16x32_bf16 v[100:103], v[154:157], v[228:231], v[100:103]
	v_mfma_f32_16x16x32_bf16 v[96:99], v[162:165], v[228:231], v[96:99]
	v_mfma_f32_16x16x32_bf16 v[124:127], v[158:161], v[208:211], v[124:127]
	v_mfma_f32_16x16x32_bf16 v[120:123], v[174:177], v[208:211], v[120:123]
	v_mfma_f32_16x16x32_bf16 v[116:119], v[158:161], v[216:219], v[116:119]
	v_mfma_f32_16x16x32_bf16 v[112:115], v[174:177], v[216:219], v[112:115]
	v_mfma_f32_16x16x32_bf16 v[108:111], v[158:161], v[224:227], v[108:111]
	v_mfma_f32_16x16x32_bf16 v[104:107], v[174:177], v[224:227], v[104:107]
	v_mfma_f32_16x16x32_bf16 v[100:103], v[158:161], v[232:235], v[100:103]
	v_mfma_f32_16x16x32_bf16 v[96:99], v[174:177], v[232:235], v[96:99]
	s_setprio 0
	s_setprio 1
	v_mfma_f32_16x16x32_bf16 v[68:71], v[182:185], v[198:201], v[68:71]
	v_mfma_f32_16x16x32_bf16 v[64:67], v[190:193], v[198:201], v[64:67]
	v_mfma_f32_16x16x32_bf16 v[52:55], v[182:185], v[212:215], v[52:55]
	v_mfma_f32_16x16x32_bf16 v[48:51], v[190:193], v[212:215], v[48:51]
	v_mfma_f32_16x16x32_bf16 v[44:47], v[182:185], v[220:223], v[44:47]
	v_mfma_f32_16x16x32_bf16 v[40:43], v[190:193], v[220:223], v[40:43]
	v_mfma_f32_16x16x32_bf16 v[36:39], v[182:185], v[228:231], v[36:39]
	v_mfma_f32_16x16x32_bf16 v[32:35], v[190:193], v[228:231], v[32:35]
	v_mfma_f32_16x16x32_bf16 v[68:71], v[186:189], v[208:211], v[68:71]
	v_mfma_f32_16x16x32_bf16 v[64:67], v[194:197], v[208:211], v[64:67]
	v_mfma_f32_16x16x32_bf16 v[52:55], v[186:189], v[216:219], v[52:55]
	v_mfma_f32_16x16x32_bf16 v[48:51], v[194:197], v[216:219], v[48:51]
	v_mfma_f32_16x16x32_bf16 v[44:47], v[186:189], v[224:227], v[44:47]
	v_mfma_f32_16x16x32_bf16 v[40:43], v[194:197], v[224:227], v[40:43]
	v_mfma_f32_16x16x32_bf16 v[36:39], v[186:189], v[232:235], v[36:39]
	v_mfma_f32_16x16x32_bf16 v[32:35], v[194:197], v[232:235], v[32:35]
	s_setprio 0
	s_barrier
	s_add_i32 s3, s86, s34
	v_lshl_add_u64 v[178:179], s[56:57], 0, v[132:133]
	s_mov_b32 m0, s3
	ds_read_b128 v[198:201], v171 offset:16384
	ds_read_b128 v[208:211], v171 offset:17408
	ds_read_b128 v[212:215], v171 offset:18432
	ds_read_b128 v[216:219], v171 offset:19456
	ds_read_b128 v[220:223], v171 offset:20480
	ds_read_b128 v[224:227], v171 offset:21504
	ds_read_b128 v[228:231], v171 offset:22528
	ds_read_b128 v[232:235], v171 offset:23552
	global_load_lds_dwordx4 v[178:179], off
	s_add_i32 m0, s3, 0x2000
	s_add_u32 s14, s56, 0x40000
	v_lshl_add_u64 v[202:203], s[56:57], 0, v[128:129]
	s_addc_u32 s15, s57, 0
	s_add_i32 s3, s87, s34
	global_load_lds_dwordx4 v[202:203], off
	v_lshl_add_u64 v[236:237], s[14:15], 0, v[132:133]
	s_mov_b32 m0, s3
	v_lshl_add_u64 v[238:239], s[58:59], 0, v[130:131]
	global_load_lds_dwordx4 v[236:237], off
	v_lshl_add_u64 v[236:237], s[14:15], 0, v[128:129]
	s_add_i32 m0, s3, 0x2000
	s_nop 0
	global_load_lds_dwordx4 v[236:237], off
	s_waitcnt vmcnt(6)
	s_waitcnt lgkmcnt(0)
	s_barrier
	s_setprio 1
	s_waitcnt lgkmcnt(0)
	v_mfma_f32_16x16x32_bf16 v[92:95], v[154:157], v[198:201], v[92:95]
	v_mfma_f32_16x16x32_bf16 v[88:91], v[162:165], v[198:201], v[88:91]
	v_mfma_f32_16x16x32_bf16 v[84:87], v[154:157], v[212:215], v[84:87]
	v_mfma_f32_16x16x32_bf16 v[80:83], v[162:165], v[212:215], v[80:83]
	v_mfma_f32_16x16x32_bf16 v[76:79], v[154:157], v[220:223], v[76:79]
	v_mfma_f32_16x16x32_bf16 v[72:75], v[162:165], v[220:223], v[72:75]
	v_lshl_add_u64 v[236:237], s[58:59], 0, v[134:135]
	s_mov_b32 m0, s60
	s_nop 0
	global_load_lds_dwordx4 v[236:237], off
	v_mfma_f32_16x16x32_bf16 v[60:63], v[154:157], v[228:231], v[60:63]
	v_mfma_f32_16x16x32_bf16 v[56:59], v[162:165], v[228:231], v[56:59]
	v_mfma_f32_16x16x32_bf16 v[92:95], v[158:161], v[208:211], v[92:95]
	v_mfma_f32_16x16x32_bf16 v[88:91], v[174:177], v[208:211], v[88:91]
	v_mfma_f32_16x16x32_bf16 v[84:87], v[158:161], v[216:219], v[84:87]
	v_mfma_f32_16x16x32_bf16 v[80:83], v[174:177], v[216:219], v[80:83]
	v_mfma_f32_16x16x32_bf16 v[76:79], v[158:161], v[224:227], v[76:79]
	v_mfma_f32_16x16x32_bf16 v[72:75], v[174:177], v[224:227], v[72:75]
	v_mfma_f32_16x16x32_bf16 v[60:63], v[158:161], v[232:235], v[60:63]
	v_mfma_f32_16x16x32_bf16 v[56:59], v[174:177], v[232:235], v[56:59]
	s_setprio 0
	s_setprio 1
	v_mfma_f32_16x16x32_bf16 v[28:31], v[182:185], v[198:201], v[28:31]
	v_mfma_f32_16x16x32_bf16 v[24:27], v[190:193], v[198:201], v[24:27]
	s_mov_b32 m0, s61
	s_nop 0
	global_load_lds_dwordx4 v[238:239], off
	v_mfma_f32_16x16x32_bf16 v[20:23], v[182:185], v[212:215], v[20:23]
	v_mfma_f32_16x16x32_bf16 v[16:19], v[190:193], v[212:215], v[16:19]
	v_mfma_f32_16x16x32_bf16 v[12:15], v[182:185], v[220:223], v[12:15]
	v_mfma_f32_16x16x32_bf16 v[8:11], v[190:193], v[220:223], v[8:11]
	v_mfma_f32_16x16x32_bf16 v[4:7], v[182:185], v[228:231], v[4:7]
	v_mfma_f32_16x16x32_bf16 v[0:3], v[190:193], v[228:231], v[0:3]
	v_mfma_f32_16x16x32_bf16 v[28:31], v[186:189], v[208:211], v[28:31]
	v_mfma_f32_16x16x32_bf16 v[24:27], v[194:197], v[208:211], v[24:27]
	v_mfma_f32_16x16x32_bf16 v[20:23], v[186:189], v[216:219], v[20:23]
	v_mfma_f32_16x16x32_bf16 v[16:19], v[194:197], v[216:219], v[16:19]
	v_mfma_f32_16x16x32_bf16 v[12:15], v[186:189], v[224:227], v[12:15]
	v_mfma_f32_16x16x32_bf16 v[8:11], v[194:197], v[224:227], v[8:11]
	v_mfma_f32_16x16x32_bf16 v[4:7], v[186:189], v[232:235], v[4:7]
	v_mfma_f32_16x16x32_bf16 v[0:3], v[194:197], v[232:235], v[0:3]
	s_setprio 0
	s_barrier
; #define PG8_STAGE(bufoff, gbase, voff) do { _Pragma("unroll") for (int _i = 0; _i < 2; ++_i) \
;         __builtin_amdgcn_global_load_lds((const unsigned*)((const char*)(gbase) + (voff)[_i]), (PG8_LAS unsigned*)(lds + (bufoff) + ldsw + _i * 8192), 16, 0, 0); } while (0)
; #define PG8_LDA(dst, b, h) do { _Pragma("unroll") for (int m = 0; m < 4; ++m) _Pragma("unroll") for (int k = 0; k < 2; ++k) dst[m][k] = *(const PG8_LAS bf16x8*)(lds + PG8_SA(b, h) + aoff + m * 2048 + k * 1024); } while (0)
; #define PG8_LDB(dst, b, h) do { _Pragma("unroll") for (int n = 0; n < 2; ++n) _Pragma("unroll") for (int k = 0; k < 2; ++k) dst[n][k] = *(const PG8_LAS bf16x8*)(lds + PG8_SB(b, h) + boff + n * 2048 + k * 1024); } while (0)
; #define PG8_MMA(ai, bj, At, Bt) do { __builtin_amdgcn_s_setprio(1); _Pragma("unroll") for (int m = 0; m < 4; ++m) _Pragma("unroll") for (int n = 0; n < 2; ++n) _Pragma("unroll") for (int k = 0; k < 2; ++k) \
;         acc[ai][bj][m][n] = __builtin_amdgcn_mfma_f32_16x16x32_bf16(Bt[n][k], At[m][k], acc[ai][bj][m][n], 0, 0, 0); __builtin_amdgcn_s_setprio(0); } while (0)
; #define PG8_WAIT_V(n) asm volatile("s_waitcnt vmcnt(" #n ")" ::: "memory")
; #define PG8_WAIT_L(n) asm volatile("s_waitcnt lgkmcnt(" #n ")" ::: "memory")
; #define PG8_BAR __builtin_amdgcn_s_barrier()
; #define PG8_SCHED __builtin_amdgcn_sched_barrier(0)
; template <class Epi, class Sched, bool ALIGN_EPI = false, bool SP2 = false>
; __device__ __forceinline__ void gemm_phase(PG8_LAS unsigned char* lds, const Gemm g, const Sched& S, const Epi& E) {
;     ...
;             PG8_LDB(B0, 1, 0); PG8_LDB(B1, 1, 1); PG8_SCHED; PG8_LDA(At, 1, 0); PG8_STAGE(PG8_SA(0, 1), a2 + hstep, voffA);
;             PG8_WAIT_V(8); PG8_WAIT_L(0); PG8_BAR; PG8_MMA(0, 0, At, B0); PG8_MMA(0, 1, At, B1); PG8_BAR; PG8_SCHED;
	s_add_i32 s3, 0, 0x18000
	v_add_u32_e32 v136, s3, v143
	s_add_i32 s33, 0, 0x1c000
	ds_read_b128 v[154:157], v136
	ds_read_b128 v[158:161], v136 offset:1024
	ds_read_b128 v[162:165], v136 offset:2048
	ds_read_b128 v[174:177], v136 offset:3072
	v_add_u32_e32 v136, s33, v143
	ds_read_b128 v[182:185], v136
	ds_read_b128 v[186:189], v136 offset:1024
	ds_read_b128 v[190:193], v136 offset:2048
	ds_read_b128 v[194:197], v136 offset:3072
	s_add_u32 s14, s58, 0x40000
	s_addc_u32 s15, s59, 0
	s_mov_b32 m0, s62
	v_lshl_add_u64 v[240:241], s[14:15], 0, v[134:135]
	ds_read_b128 v[198:201], v171 offset:32768
	ds_read_b128 v[208:211], v171 offset:33792
	ds_read_b128 v[212:215], v171 offset:34816
	ds_read_b128 v[216:219], v171 offset:35840
	ds_read_b128 v[220:223], v171 offset:36864
	ds_read_b128 v[224:227], v171 offset:37888
	ds_read_b128 v[228:231], v171 offset:38912
	ds_read_b128 v[232:235], v171 offset:39936
	global_load_lds_dwordx4 v[240:241], off
	v_lshl_add_u64 v[240:241], s[14:15], 0, v[130:131]
	s_mov_b32 m0, s63
	s_nop 0
	global_load_lds_dwordx4 v[240:241], off
	s_waitcnt vmcnt(8)
	s_waitcnt lgkmcnt(0)
	s_barrier
	s_setprio 1
	s_waitcnt lgkmcnt(0)
	v_mfma_f32_16x16x32_bf16 v[124:127], v[154:157], v[198:201], v[124:127]
	v_mfma_f32_16x16x32_bf16 v[120:123], v[162:165], v[198:201], v[120:123]
	v_mfma_f32_16x16x32_bf16 v[116:119], v[154:157], v[212:215], v[116:119]
	v_mfma_f32_16x16x32_bf16 v[112:115], v[162:165], v[212:215], v[112:115]
	v_mfma_f32_16x16x32_bf16 v[108:111], v[154:157], v[220:223], v[108:111]
	v_mfma_f32_16x16x32_bf16 v[104:107], v[162:165], v[220:223], v[104:107]
	v_mfma_f32_16x16x32_bf16 v[100:103], v[154:157], v[228:231], v[100:103]
	v_mfma_f32_16x16x32_bf16 v[96:99], v[162:165], v[228:231], v[96:99]
	v_mfma_f32_16x16x32_bf16 v[124:127], v[158:161], v[208:211], v[124:127]
	v_mfma_f32_16x16x32_bf16 v[120:123], v[174:177], v[208:211], v[120:123]
	v_mfma_f32_16x16x32_bf16 v[116:119], v[158:161], v[216:219], v[116:119]
	v_mfma_f32_16x16x32_bf16 v[112:115], v[174:177], v[216:219], v[112:115]
	v_mfma_f32_16x16x32_bf16 v[108:111], v[158:161], v[224:227], v[108:111]
	v_mfma_f32_16x16x32_bf16 v[104:107], v[174:177], v[224:227], v[104:107]
	v_mfma_f32_16x16x32_bf16 v[100:103], v[158:161], v[232:235], v[100:103]
	v_mfma_f32_16x16x32_bf16 v[96:99], v[174:177], v[232:235], v[96:99]
	s_setprio 0
	s_setprio 1
	v_mfma_f32_16x16x32_bf16 v[68:71], v[182:185], v[198:201], v[68:71]
	v_mfma_f32_16x16x32_bf16 v[64:67], v[190:193], v[198:201], v[64:67]
	v_mfma_f32_16x16x32_bf16 v[52:55], v[182:185], v[212:215], v[52:55]
	v_mfma_f32_16x16x32_bf16 v[48:51], v[190:193], v[212:215], v[48:51]
	v_mfma_f32_16x16x32_bf16 v[44:47], v[182:185], v[220:223], v[44:47]
	v_mfma_f32_16x16x32_bf16 v[40:43], v[190:193], v[220:223], v[40:43]
	v_mfma_f32_16x16x32_bf16 v[36:39], v[182:185], v[228:231], v[36:39]
	v_mfma_f32_16x16x32_bf16 v[32:35], v[190:193], v[228:231], v[32:35]
	v_mfma_f32_16x16x32_bf16 v[68:71], v[186:189], v[208:211], v[68:71]
	v_mfma_f32_16x16x32_bf16 v[64:67], v[194:197], v[208:211], v[64:67]
	v_mfma_f32_16x16x32_bf16 v[52:55], v[186:189], v[216:219], v[52:55]
	v_mfma_f32_16x16x32_bf16 v[48:51], v[194:197], v[216:219], v[48:51]
	v_mfma_f32_16x16x32_bf16 v[44:47], v[186:189], v[224:227], v[44:47]
	v_mfma_f32_16x16x32_bf16 v[40:43], v[194:197], v[224:227], v[40:43]
	v_mfma_f32_16x16x32_bf16 v[36:39], v[186:189], v[232:235], v[36:39]
	v_mfma_f32_16x16x32_bf16 v[32:35], v[194:197], v[232:235], v[32:35]
	s_setprio 0
	s_barrier
; #define PG8_STAGE(bufoff, gbase, voff) do { _Pragma("unroll") for (int _i = 0; _i < 2; ++_i) \
;         __builtin_amdgcn_global_load_lds((const unsigned*)((const char*)(gbase) + (voff)[_i]), (PG8_LAS unsigned*)(lds + (bufoff) + ldsw + _i * 8192), 16, 0, 0); } while (0)
; #define PG8_LDA(dst, b, h) do { _Pragma("unroll") for (int m = 0; m < 4; ++m) _Pragma("unroll") for (int k = 0; k < 2; ++k) dst[m][k] = *(const PG8_LAS bf16x8*)(lds + PG8_SA(b, h) + aoff + m * 2048 + k * 1024); } while (0)
; #define PG8_WAIT_V(n) asm volatile("s_waitcnt vmcnt(" #n ")" ::: "memory")
; template <class Epi, class Sched, bool ALIGN_EPI = false, bool SP2 = false>
; __device__ __forceinline__ void gemm_phase(PG8_LAS unsigned char* lds, const Gemm g, const Sched& S, const Epi& E) {
;     ...
;             PG8_LDA(At, 1, 1); PG8_STAGE(PG8_SB(1, 0), b3, voffB); PG8_STAGE(PG8_SB(1, 1), b3 + hstep, voffB); PG8_STAGE(PG8_SA(1, 0), a3, voffA);
;             PG8_WAIT_V(8); PG8_WAIT_L(0); PG8_BAR; PG8_MMA(1, 0, At, B0); PG8_MMA(1, 1, At, B1); PG8_BAR; PG8_SCHED;
;             } else {
;             PG8_LDB(B0, 0, 0); PG8_SCHED; PG8_LDA(At, 0, 0); PG8_STAGE(PG8_SA(1, 1), a1 + hstep, voffA);
;             PG8_WAIT_L(8); PG8_BAR; PG8_WAIT_L(0); PG8_MMA(0, 0, At, B0); PG8_BAR; PG8_SCHED;
;             PG8_LDB(B1, 0, 1); PG8_STAGE(PG8_SB(0, 0), b2, voffB);
;             PG8_BAR; PG8_WAIT_L(0); PG8_MMA(0, 1, At, B1); PG8_BAR;
;             PG8_LDA(At, 0, 1); PG8_STAGE(PG8_SA(0, 0), a2, voffA);
;             PG8_BAR; PG8_WAIT_L(0); PG8_MMA(1, 0, At, B0); PG8_BAR; PG8_SCHED;
;             PG8_STAGE(PG8_SB(0, 1), b2 + hstep, voffB);
;             PG8_WAIT_V(6); PG8_BAR; PG8_MMA(1, 1, At, B1); PG8_BAR;
;             PG8_LDB(B0, 1, 0); PG8_SCHED; PG8_LDA(At, 1, 0); PG8_STAGE(PG8_SA(0, 1), a2 + hstep, voffA);
;             PG8_WAIT_L(8); PG8_BAR; PG8_WAIT_L(0); PG8_MMA(0, 0, At, B0); PG8_BAR; PG8_SCHED;
;             PG8_LDB(B1, 1, 1); PG8_STAGE(PG8_SB(1, 0), b3, voffB);
;             PG8_BAR; PG8_WAIT_L(0); PG8_MMA(0, 1, At, B1); PG8_BAR;
;             PG8_LDA(At, 1, 1); PG8_STAGE(PG8_SA(1, 0), a3, voffA);
;             PG8_BAR; PG8_WAIT_L(0); PG8_MMA(1, 0, At, B0); PG8_BAR; PG8_SCHED;
;             PG8_STAGE(PG8_SB(1, 1), b3 + hstep, voffB);
;             PG8_WAIT_V(6); PG8_BAR; PG8_MMA(1, 1, At, B1); PG8_BAR;
;             }
;         }
;         if constexpr (ALIGN_EPI) { if (wr == 0) PG8_BAR; }
	s_add_i32 s3, s3, s34
	v_lshl_add_u64 v[178:179], v[178:179], 0, s[8:9]
	s_mov_b32 m0, s3
	ds_read_b128 v[198:201], v171 offset:49152
	ds_read_b128 v[208:211], v171 offset:50176
	ds_read_b128 v[212:215], v171 offset:51200
	ds_read_b128 v[216:219], v171 offset:52224
	ds_read_b128 v[220:223], v171 offset:53248
	ds_read_b128 v[224:227], v171 offset:54272
	ds_read_b128 v[228:231], v171 offset:55296
	ds_read_b128 v[232:235], v171 offset:56320
	global_load_lds_dwordx4 v[178:179], off
	s_add_i32 m0, s3, 0x2000
	s_add_u32 s14, s56, 0x40080
	v_lshl_add_u64 v[178:179], v[202:203], 0, s[8:9]
	s_addc_u32 s15, s57, 0
	s_add_i32 s3, s33, s34
	global_load_lds_dwordx4 v[178:179], off
	v_lshl_add_u64 v[178:179], s[14:15], 0, v[132:133]
	s_mov_b32 m0, s3
	s_nop 0
	global_load_lds_dwordx4 v[178:179], off
	v_lshl_add_u64 v[178:179], s[14:15], 0, v[128:129]
	s_add_i32 m0, s3, 0x2000
	s_nop 0
	global_load_lds_dwordx4 v[178:179], off
	s_waitcnt vmcnt(6)
	s_waitcnt lgkmcnt(0)
	s_barrier
	s_setprio 1
	s_waitcnt lgkmcnt(0)
	v_mfma_f32_16x16x32_bf16 v[92:95], v[154:157], v[198:201], v[92:95]
	v_mfma_f32_16x16x32_bf16 v[88:91], v[162:165], v[198:201], v[88:91]
	v_mfma_f32_16x16x32_bf16 v[84:87], v[154:157], v[212:215], v[84:87]
	v_mfma_f32_16x16x32_bf16 v[80:83], v[162:165], v[212:215], v[80:83]
	v_mfma_f32_16x16x32_bf16 v[76:79], v[154:157], v[220:223], v[76:79]
	v_mfma_f32_16x16x32_bf16 v[72:75], v[162:165], v[220:223], v[72:75]
	v_lshl_add_u64 v[178:179], v[236:237], 0, s[8:9]
	s_mov_b32 m0, s66
	s_nop 0
	global_load_lds_dwordx4 v[178:179], off
	v_mfma_f32_16x16x32_bf16 v[60:63], v[154:157], v[228:231], v[60:63]
	v_mfma_f32_16x16x32_bf16 v[56:59], v[162:165], v[228:231], v[56:59]
	v_mfma_f32_16x16x32_bf16 v[92:95], v[158:161], v[208:211], v[92:95]
	v_mfma_f32_16x16x32_bf16 v[88:91], v[174:177], v[208:211], v[88:91]
	v_mfma_f32_16x16x32_bf16 v[84:87], v[158:161], v[216:219], v[84:87]
	v_mfma_f32_16x16x32_bf16 v[80:83], v[174:177], v[216:219], v[80:83]
	v_mfma_f32_16x16x32_bf16 v[76:79], v[158:161], v[224:227], v[76:79]
	v_mfma_f32_16x16x32_bf16 v[72:75], v[174:177], v[224:227], v[72:75]
	v_mfma_f32_16x16x32_bf16 v[60:63], v[158:161], v[232:235], v[60:63]
	v_mfma_f32_16x16x32_bf16 v[56:59], v[174:177], v[232:235], v[56:59]
	s_setprio 0
	s_setprio 1
	v_mfma_f32_16x16x32_bf16 v[28:31], v[182:185], v[198:201], v[28:31]
	v_mfma_f32_16x16x32_bf16 v[24:27], v[190:193], v[198:201], v[24:27]
	v_lshl_add_u64 v[178:179], v[238:239], 0, s[8:9]
	s_mov_b32 m0, s67
	s_nop 0
	global_load_lds_dwordx4 v[178:179], off
	v_mfma_f32_16x16x32_bf16 v[20:23], v[182:185], v[212:215], v[20:23]
	v_mfma_f32_16x16x32_bf16 v[16:19], v[190:193], v[212:215], v[16:19]
	v_mfma_f32_16x16x32_bf16 v[12:15], v[182:185], v[220:223], v[12:15]
	v_mfma_f32_16x16x32_bf16 v[8:11], v[190:193], v[220:223], v[8:11]
	v_mfma_f32_16x16x32_bf16 v[4:7], v[182:185], v[228:231], v[4:7]
	v_mfma_f32_16x16x32_bf16 v[0:3], v[190:193], v[228:231], v[0:3]
	v_mfma_f32_16x16x32_bf16 v[28:31], v[186:189], v[208:211], v[28:31]
	v_mfma_f32_16x16x32_bf16 v[24:27], v[194:197], v[208:211], v[24:27]
	v_mfma_f32_16x16x32_bf16 v[20:23], v[186:189], v[216:219], v[20:23]
	v_mfma_f32_16x16x32_bf16 v[16:19], v[194:197], v[216:219], v[16:19]
	v_mfma_f32_16x16x32_bf16 v[12:15], v[186:189], v[224:227], v[12:15]
	v_mfma_f32_16x16x32_bf16 v[8:11], v[194:197], v[224:227], v[8:11]
	v_mfma_f32_16x16x32_bf16 v[4:7], v[186:189], v[232:235], v[4:7]
	v_mfma_f32_16x16x32_bf16 v[0:3], v[194:197], v[232:235], v[0:3]
	s_setprio 0
	s_barrier
	s_add_i32 s93, s93, 2
	s_add_u32 s54, s54, 0x100
	s_addc_u32 s55, s55, 0
	s_add_u32 s91, s91, 0x100
	s_addc_u32 s92, s92, 0
	s_cmp_gt_u32 s93, 13
	s_cbranch_scc0 .LBB0_417
	s_and_b64 vcc, exec, s[10:11]
	s_cbranch_vccz .LBB0_420
	s_barrier

; #define PG8_STAGE(bufoff, gbase, voff) do { _Pragma("unroll") for (int _i = 0; _i < 2; ++_i) \
;         __builtin_amdgcn_global_load_lds((const unsigned*)((const char*)(gbase) + (voff)[_i]), (PG8_LAS unsigned*)(lds + (bufoff) + ldsw + _i * 8192), 16, 0, 0); } while (0)
; #define PG8_LDA(dst, b, h) do { _Pragma("unroll") for (int m = 0; m < 4; ++m) _Pragma("unroll") for (int k = 0; k < 2; ++k) dst[m][k] = *(const PG8_LAS bf16x8*)(lds + PG8_SA(b, h) + aoff + m * 2048 + k * 1024); } while (0)
; #define PG8_LDB(dst, b, h) do { _Pragma("unroll") for (int n = 0; n < 2; ++n) _Pragma("unroll") for (int k = 0; k < 2; ++k) dst[n][k] = *(const PG8_LAS bf16x8*)(lds + PG8_SB(b, h) + boff + n * 2048 + k * 1024); } while (0)
; #define PG8_WAIT_V(n) asm volatile("s_waitcnt vmcnt(" #n ")" ::: "memory")
; #define PG8_WAIT_L(n) asm volatile("s_waitcnt lgkmcnt(" #n ")" ::: "memory")
; #define PG8_BAR __builtin_amdgcn_s_barrier()
; #define PG8_SCHED __builtin_amdgcn_sched_barrier(0)
; template <class Epi, class Sched, bool ALIGN_EPI = false, bool SP2 = false>
; __device__ __forceinline__ void gemm_phase(PG8_LAS unsigned char* lds, const Gemm g, const Sched& S, const Epi& E) {
;     ...
;         const char* nA = has_next ? (const char*)g.A + (size_t)nxt.pm * tstep : cA; const char* nB = has_next ? (const char*)g.Bt + (size_t)nxt.pn * tstep : cB;
;         for (int t = 0; t < nt; t += 2) {
;             const bool last = (t == nt - 2);
;             const char* a1 = cA + (size_t)(t + 1) * kstep;
;             const char* a2 = last ? nA : cA + (size_t)(t + 2) * kstep; const char* b2 = last ? nB : cB + (size_t)(t + 2) * kstep;
;             const char* a3 = a2 + kstep; const char* b3 = b2 + kstep;
;             if (last && has_next) S.a_ready(nxt);
;             if constexpr (SP2) {
;             PG8_LDB(B0, 0, 0); PG8_LDB(B1, 0, 1); PG8_SCHED; PG8_LDA(At, 0, 0); PG8_STAGE(PG8_SA(1, 1), a1 + hstep, voffA);
;             PG8_WAIT_V(8); PG8_WAIT_L(0); PG8_BAR; PG8_MMA(0, 0, At, B0); PG8_MMA(0, 1, At, B1); PG8_BAR; PG8_SCHED;
;             PG8_LDA(At, 0, 1); PG8_STAGE(PG8_SB(0, 0), b2, voffB); PG8_STAGE(PG8_SB(0, 1), b2 + hstep, voffB); PG8_STAGE(PG8_SA(0, 0), a2, voffA);
;             PG8_WAIT_V(8); PG8_WAIT_L(0); PG8_BAR; PG8_MMA(1, 0, At, B0); PG8_MMA(1, 1, At, B1); PG8_BAR; PG8_SCHED;
.LBB0_458:
	s_ashr_i32 s49, s48, 31
	s_lshl_b64 s[14:15], s[48:49], 19
	s_add_u32 s50, s34, s14
	s_addc_u32 s51, s43, s15
	s_and_b64 s[14:15], s[40:41], exec
	s_cselect_b32 s49, s51, s59
	s_cselect_b32 s55, s50, s58
	s_ashr_i32 s45, s44, 31
	s_lshl_b64 s[14:15], s[44:45], 19
	v_readlane_b32 s3, v250, 13
	s_add_u32 s52, s3, s14
	v_readlane_b32 s3, v250, 14
	s_addc_u32 s53, s3, s15
	s_and_b64 s[14:15], s[40:41], exec
	s_cselect_b32 s45, s53, s61
	s_cselect_b32 s57, s52, s60
	s_add_u32 s58, s58, 0x40080
	s_addc_u32 s59, s59, 0
	s_add_u32 s96, s60, 0x100
	s_addc_u32 s97, s61, 0
	s_mov_b32 vcc_lo, -2
	ds_read_b128 v[170:173], v165
	ds_read_b128 v[174:177], v165 offset:1024
	ds_read_b128 v[182:185], v165 offset:2048
	ds_read_b128 v[186:189], v165 offset:3072
	ds_read_b128 v[190:193], v168
	ds_read_b128 v[194:197], v168 offset:1024
	ds_read_b128 v[198:201], v168 offset:2048
	ds_read_b128 v[208:211], v168 offset:3072
	s_add_u32 s3, s58, 0xfffc0080
	s_addc_u32 s14, s59, -1
	s_cmp_eq_u32 vcc_lo, 12
	s_cselect_b32 s63, s49, s14
	s_cselect_b32 s62, s55, s3
	s_cselect_b32 s61, s45, s97
	s_cselect_b32 s60, s57, s96
	v_lshl_add_u64 v[178:179], s[58:59], 0, v[160:161]
	s_add_i32 m0, s85, 0xc000
	ds_read_b128 v[212:215], v164
	ds_read_b128 v[216:219], v164 offset:1024
	ds_read_b128 v[220:223], v164 offset:2048
	ds_read_b128 v[224:227], v164 offset:3072
	ds_read_b128 v[228:231], v164 offset:4096
	ds_read_b128 v[232:235], v164 offset:5120
	ds_read_b128 v[236:239], v164 offset:6144
	ds_read_b128 v[240:243], v164 offset:7168
	global_load_lds_dwordx4 v[178:179], off
	v_lshl_add_u64 v[178:179], s[58:59], 0, v[162:163]
	s_add_i32 m0, s85, 0xe000
	s_nop 0
	global_load_lds_dwordx4 v[178:179], off
	s_waitcnt vmcnt(8)
	s_waitcnt lgkmcnt(0)
	s_barrier
	s_setprio 1
	s_waitcnt lgkmcnt(0)
	v_mfma_f32_16x16x32_bf16 v[124:127], v[170:173], v[212:215], 0
	v_mfma_f32_16x16x32_bf16 v[120:123], v[182:185], v[212:215], 0
	v_mfma_f32_16x16x32_bf16 v[116:119], v[170:173], v[220:223], 0
	v_mfma_f32_16x16x32_bf16 v[112:115], v[182:185], v[220:223], 0
	v_mfma_f32_16x16x32_bf16 v[108:111], v[170:173], v[228:231], 0
	v_mfma_f32_16x16x32_bf16 v[104:107], v[182:185], v[228:231], 0
	v_mfma_f32_16x16x32_bf16 v[100:103], v[170:173], v[236:239], 0
	v_mfma_f32_16x16x32_bf16 v[96:99], v[182:185], v[236:239], 0
	v_mfma_f32_16x16x32_bf16 v[124:127], v[174:177], v[216:219], v[124:127]
	v_mfma_f32_16x16x32_bf16 v[120:123], v[186:189], v[216:219], v[120:123]
	v_mfma_f32_16x16x32_bf16 v[116:119], v[174:177], v[224:227], v[116:119]
	v_mfma_f32_16x16x32_bf16 v[112:115], v[186:189], v[224:227], v[112:115]
	v_mfma_f32_16x16x32_bf16 v[108:111], v[174:177], v[232:235], v[108:111]
	v_mfma_f32_16x16x32_bf16 v[104:107], v[186:189], v[232:235], v[104:107]
	v_mfma_f32_16x16x32_bf16 v[100:103], v[174:177], v[240:243], v[100:103]
	v_mfma_f32_16x16x32_bf16 v[96:99], v[186:189], v[240:243], v[96:99]
	s_setprio 0
	s_setprio 1
	v_mfma_f32_16x16x32_bf16 v[60:63], v[190:193], v[212:215], 0
	v_mfma_f32_16x16x32_bf16 v[56:59], v[198:201], v[212:215], 0
	v_mfma_f32_16x16x32_bf16 v[52:55], v[190:193], v[220:223], 0
	v_mfma_f32_16x16x32_bf16 v[48:51], v[198:201], v[220:223], 0
	v_mfma_f32_16x16x32_bf16 v[44:47], v[190:193], v[228:231], 0
	v_mfma_f32_16x16x32_bf16 v[40:43], v[198:201], v[228:231], 0
	v_mfma_f32_16x16x32_bf16 v[36:39], v[190:193], v[236:239], 0
	v_mfma_f32_16x16x32_bf16 v[32:35], v[198:201], v[236:239], 0
	v_mfma_f32_16x16x32_bf16 v[60:63], v[194:197], v[216:219], v[60:63]
	v_mfma_f32_16x16x32_bf16 v[56:59], v[208:211], v[216:219], v[56:59]
	v_mfma_f32_16x16x32_bf16 v[52:55], v[194:197], v[224:227], v[52:55]
	v_mfma_f32_16x16x32_bf16 v[48:51], v[208:211], v[224:227], v[48:51]
	v_mfma_f32_16x16x32_bf16 v[44:47], v[194:197], v[232:235], v[44:47]
	v_mfma_f32_16x16x32_bf16 v[40:43], v[208:211], v[232:235], v[40:43]
	v_mfma_f32_16x16x32_bf16 v[36:39], v[194:197], v[240:243], v[36:39]
	v_mfma_f32_16x16x32_bf16 v[32:35], v[208:211], v[240:243], v[32:35]
	s_setprio 0
	s_barrier
	s_add_i32 s3, s94, s84
	v_lshl_add_u64 v[178:179], s[60:61], 0, v[130:131]
	s_mov_b32 m0, s3
	ds_read_b128 v[212:215], v164 offset:16384
	ds_read_b128 v[216:219], v164 offset:17408
	ds_read_b128 v[220:223], v164 offset:18432
	ds_read_b128 v[224:227], v164 offset:19456
	ds_read_b128 v[228:231], v164 offset:20480
	ds_read_b128 v[232:235], v164 offset:21504
	ds_read_b128 v[236:239], v164 offset:22528
	ds_read_b128 v[240:243], v164 offset:23552
	global_load_lds_dwordx4 v[178:179], off
	s_add_i32 m0, s3, 0x2000
	s_add_u32 s14, s60, 0x40000
	v_lshl_add_u64 v[202:203], s[60:61], 0, v[134:135]
	s_addc_u32 s15, s61, 0
	s_add_i32 s3, s95, s84
	global_load_lds_dwordx4 v[202:203], off
	v_lshl_add_u64 v[244:245], s[14:15], 0, v[130:131]
	s_mov_b32 m0, s3
	v_lshl_add_u64 v[246:247], s[62:63], 0, v[132:133]
	global_load_lds_dwordx4 v[244:245], off
	v_lshl_add_u64 v[244:245], s[14:15], 0, v[134:135]
	s_add_i32 m0, s3, 0x2000
	s_nop 0
	global_load_lds_dwordx4 v[244:245], off
	s_waitcnt vmcnt(6)
	s_waitcnt lgkmcnt(0)
	s_barrier
; #define PG8_STAGE(bufoff, gbase, voff) do { _Pragma("unroll") for (int _i = 0; _i < 2; ++_i) \
;         __builtin_amdgcn_global_load_lds((const unsigned*)((const char*)(gbase) + (voff)[_i]), (PG8_LAS unsigned*)(lds + (bufoff) + ldsw + _i * 8192), 16, 0, 0); } while (0)
; #define PG8_LDA(dst, b, h) do { _Pragma("unroll") for (int m = 0; m < 4; ++m) _Pragma("unroll") for (int k = 0; k < 2; ++k) dst[m][k] = *(const PG8_LAS bf16x8*)(lds + PG8_SA(b, h) + aoff + m * 2048 + k * 1024); } while (0)
; #define PG8_LDB(dst, b, h) do { _Pragma("unroll") for (int n = 0; n < 2; ++n) _Pragma("unroll") for (int k = 0; k < 2; ++k) dst[n][k] = *(const PG8_LAS bf16x8*)(lds + PG8_SB(b, h) + boff + n * 2048 + k * 1024); } while (0)
; #define PG8_MMA(ai, bj, At, Bt) do { __builtin_amdgcn_s_setprio(1); _Pragma("unroll") for (int m = 0; m < 4; ++m) _Pragma("unroll") for (int n = 0; n < 2; ++n) _Pragma("unroll") for (int k = 0; k < 2; ++k) \
;         acc[ai][bj][m][n] = __builtin_amdgcn_mfma_f32_16x16x32_bf16(Bt[n][k], At[m][k], acc[ai][bj][m][n], 0, 0, 0); __builtin_amdgcn_s_setprio(0); } while (0)
; #define PG8_WAIT_V(n) asm volatile("s_waitcnt vmcnt(" #n ")" ::: "memory")
; #define PG8_WAIT_L(n) asm volatile("s_waitcnt lgkmcnt(" #n ")" ::: "memory")
; #define PG8_BAR __builtin_amdgcn_s_barrier()
; #define PG8_SCHED __builtin_amdgcn_sched_barrier(0)
; template <class Epi, class Sched, bool ALIGN_EPI = false, bool SP2 = false>
; __device__ __forceinline__ void gemm_phase(PG8_LAS unsigned char* lds, const Gemm g, const Sched& S, const Epi& E) {
;     ...
;             PG8_WAIT_V(8); PG8_WAIT_L(0); PG8_BAR; PG8_MMA(1, 0, At, B0); PG8_MMA(1, 1, At, B1); PG8_BAR; PG8_SCHED;
;             PG8_LDB(B0, 1, 0); PG8_LDB(B1, 1, 1); PG8_SCHED; PG8_LDA(At, 1, 0); PG8_STAGE(PG8_SA(0, 1), a2 + hstep, voffA);
;             PG8_WAIT_V(8); PG8_WAIT_L(0); PG8_BAR; PG8_MMA(0, 0, At, B0); PG8_MMA(0, 1, At, B1); PG8_BAR; PG8_SCHED;
	s_setprio 1
	s_waitcnt lgkmcnt(0)
	v_mfma_f32_16x16x32_bf16 v[92:95], v[170:173], v[212:215], 0
	v_mfma_f32_16x16x32_bf16 v[88:91], v[182:185], v[212:215], 0
	v_mfma_f32_16x16x32_bf16 v[84:87], v[170:173], v[220:223], 0
	v_mfma_f32_16x16x32_bf16 v[80:83], v[182:185], v[220:223], 0
	v_mfma_f32_16x16x32_bf16 v[76:79], v[170:173], v[228:231], 0
	v_mfma_f32_16x16x32_bf16 v[72:75], v[182:185], v[228:231], 0
	v_lshl_add_u64 v[244:245], s[62:63], 0, v[128:129]
	s_mov_b32 m0, s85
	s_nop 0
	global_load_lds_dwordx4 v[244:245], off
	v_mfma_f32_16x16x32_bf16 v[68:71], v[170:173], v[236:239], 0
	v_mfma_f32_16x16x32_bf16 v[64:67], v[182:185], v[236:239], 0
	v_mfma_f32_16x16x32_bf16 v[92:95], v[174:177], v[216:219], v[92:95]
	v_mfma_f32_16x16x32_bf16 v[88:91], v[186:189], v[216:219], v[88:91]
	v_mfma_f32_16x16x32_bf16 v[84:87], v[174:177], v[224:227], v[84:87]
	v_mfma_f32_16x16x32_bf16 v[80:83], v[186:189], v[224:227], v[80:83]
	v_mfma_f32_16x16x32_bf16 v[76:79], v[174:177], v[232:235], v[76:79]
	v_mfma_f32_16x16x32_bf16 v[72:75], v[186:189], v[232:235], v[72:75]
	v_mfma_f32_16x16x32_bf16 v[68:71], v[174:177], v[240:243], v[68:71]
	v_mfma_f32_16x16x32_bf16 v[64:67], v[186:189], v[240:243], v[64:67]
	s_setprio 0
	s_setprio 1
	v_mfma_f32_16x16x32_bf16 v[28:31], v[190:193], v[212:215], 0
	v_mfma_f32_16x16x32_bf16 v[24:27], v[198:201], v[212:215], 0
	s_mov_b32 m0, s86
	s_nop 0
	global_load_lds_dwordx4 v[246:247], off
	v_mfma_f32_16x16x32_bf16 v[20:23], v[190:193], v[220:223], 0
	v_mfma_f32_16x16x32_bf16 v[16:19], v[198:201], v[220:223], 0
	v_mfma_f32_16x16x32_bf16 v[12:15], v[190:193], v[228:231], 0
	v_mfma_f32_16x16x32_bf16 v[8:11], v[198:201], v[228:231], 0
	v_mfma_f32_16x16x32_bf16 v[4:7], v[190:193], v[236:239], 0
	v_mfma_f32_16x16x32_bf16 v[0:3], v[198:201], v[236:239], 0
	v_mfma_f32_16x16x32_bf16 v[28:31], v[194:197], v[216:219], v[28:31]
	v_mfma_f32_16x16x32_bf16 v[24:27], v[208:211], v[216:219], v[24:27]
	v_mfma_f32_16x16x32_bf16 v[20:23], v[194:197], v[224:227], v[20:23]
	v_mfma_f32_16x16x32_bf16 v[16:19], v[208:211], v[224:227], v[16:19]
	v_mfma_f32_16x16x32_bf16 v[12:15], v[194:197], v[232:235], v[12:15]
	v_mfma_f32_16x16x32_bf16 v[8:11], v[208:211], v[232:235], v[8:11]
	v_mfma_f32_16x16x32_bf16 v[4:7], v[194:197], v[240:243], v[4:7]
	v_mfma_f32_16x16x32_bf16 v[0:3], v[208:211], v[240:243], v[0:3]
	s_setprio 0
	s_barrier
	s_add_i32 s3, 0, 0x18000
	v_add_u32_e32 v136, s3, v141
	s_add_i32 s33, 0, 0x1c000
	ds_read_b128 v[170:173], v136
	ds_read_b128 v[174:177], v136 offset:1024
	ds_read_b128 v[182:185], v136 offset:2048
	ds_read_b128 v[186:189], v136 offset:3072
	v_add_u32_e32 v136, s33, v141
	ds_read_b128 v[190:193], v136
	ds_read_b128 v[194:197], v136 offset:1024
	ds_read_b128 v[198:201], v136 offset:2048
	ds_read_b128 v[208:211], v136 offset:3072
	s_add_u32 s14, s62, 0x40000
	s_addc_u32 s15, s63, 0
	s_mov_b32 m0, s87
	v_lshl_add_u64 v[248:249], s[14:15], 0, v[128:129]
	ds_read_b128 v[212:215], v164 offset:32768
	ds_read_b128 v[216:219], v164 offset:33792
	ds_read_b128 v[220:223], v164 offset:34816
	ds_read_b128 v[224:227], v164 offset:35840
	ds_read_b128 v[228:231], v164 offset:36864
	ds_read_b128 v[232:235], v164 offset:37888
	ds_read_b128 v[236:239], v164 offset:38912
	ds_read_b128 v[240:243], v164 offset:39936
	global_load_lds_dwordx4 v[248:249], off
	v_lshl_add_u64 v[248:249], s[14:15], 0, v[132:133]
	s_mov_b32 m0, s88
	s_nop 0
	global_load_lds_dwordx4 v[248:249], off
	s_waitcnt vmcnt(8)
	s_waitcnt lgkmcnt(0)
	s_barrier
	s_setprio 1
	s_waitcnt lgkmcnt(0)
	v_mfma_f32_16x16x32_bf16 v[124:127], v[170:173], v[212:215], v[124:127]
	v_mfma_f32_16x16x32_bf16 v[120:123], v[182:185], v[212:215], v[120:123]
	v_mfma_f32_16x16x32_bf16 v[116:119], v[170:173], v[220:223], v[116:119]
	v_mfma_f32_16x16x32_bf16 v[112:115], v[182:185], v[220:223], v[112:115]
	v_mfma_f32_16x16x32_bf16 v[108:111], v[170:173], v[228:231], v[108:111]
	v_mfma_f32_16x16x32_bf16 v[104:107], v[182:185], v[228:231], v[104:107]
	v_mfma_f32_16x16x32_bf16 v[100:103], v[170:173], v[236:239], v[100:103]
	v_mfma_f32_16x16x32_bf16 v[96:99], v[182:185], v[236:239], v[96:99]
	v_mfma_f32_16x16x32_bf16 v[124:127], v[174:177], v[216:219], v[124:127]
	v_mfma_f32_16x16x32_bf16 v[120:123], v[186:189], v[216:219], v[120:123]
	v_mfma_f32_16x16x32_bf16 v[116:119], v[174:177], v[224:227], v[116:119]
	v_mfma_f32_16x16x32_bf16 v[112:115], v[186:189], v[224:227], v[112:115]
	v_mfma_f32_16x16x32_bf16 v[108:111], v[174:177], v[232:235], v[108:111]
	v_mfma_f32_16x16x32_bf16 v[104:107], v[186:189], v[232:235], v[104:107]
	v_mfma_f32_16x16x32_bf16 v[100:103], v[174:177], v[240:243], v[100:103]
	v_mfma_f32_16x16x32_bf16 v[96:99], v[186:189], v[240:243], v[96:99]
	s_setprio 0
	s_setprio 1
	v_mfma_f32_16x16x32_bf16 v[60:63], v[190:193], v[212:215], v[60:63]
	v_mfma_f32_16x16x32_bf16 v[56:59], v[198:201], v[212:215], v[56:59]
	v_mfma_f32_16x16x32_bf16 v[52:55], v[190:193], v[220:223], v[52:55]
	v_mfma_f32_16x16x32_bf16 v[48:51], v[198:201], v[220:223], v[48:51]
	v_mfma_f32_16x16x32_bf16 v[44:47], v[190:193], v[228:231], v[44:47]
	v_mfma_f32_16x16x32_bf16 v[40:43], v[198:201], v[228:231], v[40:43]
	v_mfma_f32_16x16x32_bf16 v[36:39], v[190:193], v[236:239], v[36:39]
	v_mfma_f32_16x16x32_bf16 v[32:35], v[198:201], v[236:239], v[32:35]
	v_mfma_f32_16x16x32_bf16 v[60:63], v[194:197], v[216:219], v[60:63]
	v_mfma_f32_16x16x32_bf16 v[56:59], v[208:211], v[216:219], v[56:59]
	v_mfma_f32_16x16x32_bf16 v[52:55], v[194:197], v[224:227], v[52:55]
	v_mfma_f32_16x16x32_bf16 v[48:51], v[208:211], v[224:227], v[48:51]
	v_mfma_f32_16x16x32_bf16 v[44:47], v[194:197], v[232:235], v[44:47]
	v_mfma_f32_16x16x32_bf16 v[40:43], v[208:211], v[232:235], v[40:43]
	v_mfma_f32_16x16x32_bf16 v[36:39], v[194:197], v[240:243], v[36:39]
	v_mfma_f32_16x16x32_bf16 v[32:35], v[208:211], v[240:243], v[32:35]
	s_setprio 0
	s_barrier
; #define PG8_STAGE(bufoff, gbase, voff) do { _Pragma("unroll") for (int _i = 0; _i < 2; ++_i) \
;         __builtin_amdgcn_global_load_lds((const unsigned*)((const char*)(gbase) + (voff)[_i]), (PG8_LAS unsigned*)(lds + (bufoff) + ldsw + _i * 8192), 16, 0, 0); } while (0)
; #define PG8_LDA(dst, b, h) do { _Pragma("unroll") for (int m = 0; m < 4; ++m) _Pragma("unroll") for (int k = 0; k < 2; ++k) dst[m][k] = *(const PG8_LAS bf16x8*)(lds + PG8_SA(b, h) + aoff + m * 2048 + k * 1024); } while (0)
; #define PG8_LDB(dst, b, h) do { _Pragma("unroll") for (int n = 0; n < 2; ++n) _Pragma("unroll") for (int k = 0; k < 2; ++k) dst[n][k] = *(const PG8_LAS bf16x8*)(lds + PG8_SB(b, h) + boff + n * 2048 + k * 1024); } while (0)
; #define PG8_MMA(ai, bj, At, Bt) do { __builtin_amdgcn_s_setprio(1); _Pragma("unroll") for (int m = 0; m < 4; ++m) _Pragma("unroll") for (int n = 0; n < 2; ++n) _Pragma("unroll") for (int k = 0; k < 2; ++k) \
;         acc[ai][bj][m][n] = __builtin_amdgcn_mfma_f32_16x16x32_bf16(Bt[n][k], At[m][k], acc[ai][bj][m][n], 0, 0, 0); __builtin_amdgcn_s_setprio(0); } while (0)
; #define PG8_WAIT_V(n) asm volatile("s_waitcnt vmcnt(" #n ")" ::: "memory")
; #define PG8_BAR __builtin_amdgcn_s_barrier()
; template <class Epi, class Sched, bool ALIGN_EPI = false, bool SP2 = false>
; __device__ __forceinline__ void gemm_phase(PG8_LAS unsigned char* lds, const Gemm g, const Sched& S, const Epi& E) {
;     ...
;         for (int t = 0; t < nt; t += 2) {
;             const bool last = (t == nt - 2);
;             const char* a1 = cA + (size_t)(t + 1) * kstep;
;             const char* a2 = last ? nA : cA + (size_t)(t + 2) * kstep; const char* b2 = last ? nB : cB + (size_t)(t + 2) * kstep;
;             const char* a3 = a2 + kstep; const char* b3 = b2 + kstep;
;             if (last && has_next) S.a_ready(nxt);
;             if constexpr (SP2) {
;             PG8_LDB(B0, 0, 0); PG8_LDB(B1, 0, 1); PG8_SCHED; PG8_LDA(At, 0, 0); PG8_STAGE(PG8_SA(1, 1), a1 + hstep, voffA);
;             PG8_WAIT_V(8); PG8_WAIT_L(0); PG8_BAR; PG8_MMA(0, 0, At, B0); PG8_MMA(0, 1, At, B1); PG8_BAR; PG8_SCHED;
;     ...
;             PG8_LDA(At, 1, 1); PG8_STAGE(PG8_SB(1, 0), b3, voffB); PG8_STAGE(PG8_SB(1, 1), b3 + hstep, voffB); PG8_STAGE(PG8_SA(1, 0), a3, voffA);
;             PG8_WAIT_V(8); PG8_WAIT_L(0); PG8_BAR; PG8_MMA(1, 0, At, B0); PG8_MMA(1, 1, At, B1); PG8_BAR; PG8_SCHED;
	s_add_i32 s3, s3, s84
	v_lshl_add_u64 v[178:179], v[178:179], 0, s[8:9]
	s_mov_b32 m0, s3
	ds_read_b128 v[212:215], v164 offset:49152
	ds_read_b128 v[216:219], v164 offset:50176
	ds_read_b128 v[220:223], v164 offset:51200
	ds_read_b128 v[224:227], v164 offset:52224
	ds_read_b128 v[228:231], v164 offset:53248
	ds_read_b128 v[232:235], v164 offset:54272
	ds_read_b128 v[236:239], v164 offset:55296
	ds_read_b128 v[240:243], v164 offset:56320
	global_load_lds_dwordx4 v[178:179], off
	s_add_i32 m0, s3, 0x2000
	s_add_u32 s14, s60, 0x40080
	v_lshl_add_u64 v[178:179], v[202:203], 0, s[8:9]
	s_addc_u32 s15, s61, 0
	s_add_i32 s3, s33, s84
	global_load_lds_dwordx4 v[178:179], off
	v_lshl_add_u64 v[178:179], s[14:15], 0, v[130:131]
	s_mov_b32 m0, s3
	s_nop 0
	global_load_lds_dwordx4 v[178:179], off
	v_lshl_add_u64 v[178:179], s[14:15], 0, v[134:135]
	s_add_i32 m0, s3, 0x2000
	s_nop 0
	global_load_lds_dwordx4 v[178:179], off
	s_waitcnt vmcnt(6)
	s_waitcnt lgkmcnt(0)
	s_barrier
	s_setprio 1
	s_waitcnt lgkmcnt(0)
	v_mfma_f32_16x16x32_bf16 v[92:95], v[170:173], v[212:215], v[92:95]
	v_mfma_f32_16x16x32_bf16 v[88:91], v[182:185], v[212:215], v[88:91]
	v_mfma_f32_16x16x32_bf16 v[84:87], v[170:173], v[220:223], v[84:87]
	v_mfma_f32_16x16x32_bf16 v[80:83], v[182:185], v[220:223], v[80:83]
	v_mfma_f32_16x16x32_bf16 v[76:79], v[170:173], v[228:231], v[76:79]
	v_mfma_f32_16x16x32_bf16 v[72:75], v[182:185], v[228:231], v[72:75]
	v_lshl_add_u64 v[178:179], v[244:245], 0, s[8:9]
	s_mov_b32 m0, s90
	s_nop 0
	global_load_lds_dwordx4 v[178:179], off
	v_mfma_f32_16x16x32_bf16 v[68:71], v[170:173], v[236:239], v[68:71]
	v_mfma_f32_16x16x32_bf16 v[64:67], v[182:185], v[236:239], v[64:67]
	v_mfma_f32_16x16x32_bf16 v[92:95], v[174:177], v[216:219], v[92:95]
	v_mfma_f32_16x16x32_bf16 v[88:91], v[186:189], v[216:219], v[88:91]
	v_mfma_f32_16x16x32_bf16 v[84:87], v[174:177], v[224:227], v[84:87]
	v_mfma_f32_16x16x32_bf16 v[80:83], v[186:189], v[224:227], v[80:83]
	v_mfma_f32_16x16x32_bf16 v[76:79], v[174:177], v[232:235], v[76:79]
	v_mfma_f32_16x16x32_bf16 v[72:75], v[186:189], v[232:235], v[72:75]
	v_mfma_f32_16x16x32_bf16 v[68:71], v[174:177], v[240:243], v[68:71]
	v_mfma_f32_16x16x32_bf16 v[64:67], v[186:189], v[240:243], v[64:67]
	s_setprio 0
	s_setprio 1
	v_mfma_f32_16x16x32_bf16 v[28:31], v[190:193], v[212:215], v[28:31]
	v_mfma_f32_16x16x32_bf16 v[24:27], v[198:201], v[212:215], v[24:27]
	v_lshl_add_u64 v[178:179], v[246:247], 0, s[8:9]
	s_mov_b32 m0, s91
	s_nop 0
	global_load_lds_dwordx4 v[178:179], off
	v_mfma_f32_16x16x32_bf16 v[20:23], v[190:193], v[220:223], v[20:23]
	v_mfma_f32_16x16x32_bf16 v[16:19], v[198:201], v[220:223], v[16:19]
	v_mfma_f32_16x16x32_bf16 v[12:15], v[190:193], v[228:231], v[12:15]
	v_mfma_f32_16x16x32_bf16 v[8:11], v[198:201], v[228:231], v[8:11]
	v_mfma_f32_16x16x32_bf16 v[4:7], v[190:193], v[236:239], v[4:7]
	v_mfma_f32_16x16x32_bf16 v[0:3], v[198:201], v[236:239], v[0:3]
	v_mfma_f32_16x16x32_bf16 v[28:31], v[194:197], v[216:219], v[28:31]
	v_mfma_f32_16x16x32_bf16 v[24:27], v[208:211], v[216:219], v[24:27]
	v_mfma_f32_16x16x32_bf16 v[20:23], v[194:197], v[224:227], v[20:23]
	v_mfma_f32_16x16x32_bf16 v[16:19], v[208:211], v[224:227], v[16:19]
	v_mfma_f32_16x16x32_bf16 v[12:15], v[194:197], v[232:235], v[12:15]
	v_mfma_f32_16x16x32_bf16 v[8:11], v[208:211], v[232:235], v[8:11]
	v_mfma_f32_16x16x32_bf16 v[4:7], v[194:197], v[240:243], v[4:7]
	v_mfma_f32_16x16x32_bf16 v[0:3], v[208:211], v[240:243], v[0:3]
	s_setprio 0
	s_barrier
	s_add_i32 vcc_lo, vcc_lo, 2
	s_add_u32 s58, s58, 0x100
	s_addc_u32 s59, s59, 0
	s_add_u32 s96, s96, 0x100
	s_addc_u32 s97, s97, 0
.LBB0_459:
	ds_read_b128 v[170:173], v165
	ds_read_b128 v[174:177], v165 offset:1024
	ds_read_b128 v[182:185], v165 offset:2048
	ds_read_b128 v[186:189], v165 offset:3072
	ds_read_b128 v[190:193], v168
	ds_read_b128 v[194:197], v168 offset:1024
	ds_read_b128 v[198:201], v168 offset:2048
	ds_read_b128 v[208:211], v168 offset:3072
	s_add_u32 s3, s58, 0xfffc0080
	s_addc_u32 s14, s59, -1
	s_cmp_eq_u32 vcc_lo, 12
	s_cselect_b32 s63, s49, s14
	s_cselect_b32 s62, s55, s3
	s_cselect_b32 s61, s45, s97
	s_cselect_b32 s60, s57, s96
	v_lshl_add_u64 v[178:179], s[58:59], 0, v[160:161]
	s_add_i32 m0, s85, 0xc000
	ds_read_b128 v[212:215], v164
	ds_read_b128 v[216:219], v164 offset:1024
	ds_read_b128 v[220:223], v164 offset:2048
	ds_read_b128 v[224:227], v164 offset:3072
	ds_read_b128 v[228:231], v164 offset:4096
	ds_read_b128 v[232:235], v164 offset:5120
	ds_read_b128 v[236:239], v164 offset:6144
	ds_read_b128 v[240:243], v164 offset:7168
	global_load_lds_dwordx4 v[178:179], off
	v_lshl_add_u64 v[178:179], s[58:59], 0, v[162:163]
	s_add_i32 m0, s85, 0xe000
	s_nop 0
	global_load_lds_dwordx4 v[178:179], off
	s_waitcnt vmcnt(8)
	s_waitcnt lgkmcnt(0)
	s_barrier
; #define PG8_STAGE(bufoff, gbase, voff) do { _Pragma("unroll") for (int _i = 0; _i < 2; ++_i) \
;         __builtin_amdgcn_global_load_lds((const unsigned*)((const char*)(gbase) + (voff)[_i]), (PG8_LAS unsigned*)(lds + (bufoff) + ldsw + _i * 8192), 16, 0, 0); } while (0)
; #define PG8_LDA(dst, b, h) do { _Pragma("unroll") for (int m = 0; m < 4; ++m) _Pragma("unroll") for (int k = 0; k < 2; ++k) dst[m][k] = *(const PG8_LAS bf16x8*)(lds + PG8_SA(b, h) + aoff + m * 2048 + k * 1024); } while (0)
; #define PG8_LDB(dst, b, h) do { _Pragma("unroll") for (int n = 0; n < 2; ++n) _Pragma("unroll") for (int k = 0; k < 2; ++k) dst[n][k] = *(const PG8_LAS bf16x8*)(lds + PG8_SB(b, h) + boff + n * 2048 + k * 1024); } while (0)
; #define PG8_MMA(ai, bj, At, Bt) do { __builtin_amdgcn_s_setprio(1); _Pragma("unroll") for (int m = 0; m < 4; ++m) _Pragma("unroll") for (int n = 0; n < 2; ++n) _Pragma("unroll") for (int k = 0; k < 2; ++k) \
;         acc[ai][bj][m][n] = __builtin_amdgcn_mfma_f32_16x16x32_bf16(Bt[n][k], At[m][k], acc[ai][bj][m][n], 0, 0, 0); __builtin_amdgcn_s_setprio(0); } while (0)
; #define PG8_WAIT_V(n) asm volatile("s_waitcnt vmcnt(" #n ")" ::: "memory")
; #define PG8_WAIT_L(n) asm volatile("s_waitcnt lgkmcnt(" #n ")" ::: "memory")
; #define PG8_BAR __builtin_amdgcn_s_barrier()
; #define PG8_SCHED __builtin_amdgcn_sched_barrier(0)
; template <class Epi, class Sched, bool ALIGN_EPI = false, bool SP2 = false>
; __device__ __forceinline__ void gemm_phase(PG8_LAS unsigned char* lds, const Gemm g, const Sched& S, const Epi& E) {
;     ...
;             PG8_LDB(B0, 0, 0); PG8_LDB(B1, 0, 1); PG8_SCHED; PG8_LDA(At, 0, 0); PG8_STAGE(PG8_SA(1, 1), a1 + hstep, voffA);
;             PG8_WAIT_V(8); PG8_WAIT_L(0); PG8_BAR; PG8_MMA(0, 0, At, B0); PG8_MMA(0, 1, At, B1); PG8_BAR; PG8_SCHED;
;             PG8_LDA(At, 0, 1); PG8_STAGE(PG8_SB(0, 0), b2, voffB); PG8_STAGE(PG8_SB(0, 1), b2 + hstep, voffB); PG8_STAGE(PG8_SA(0, 0), a2, voffA);
;             PG8_WAIT_V(8); PG8_WAIT_L(0); PG8_BAR; PG8_MMA(1, 0, At, B0); PG8_MMA(1, 1, At, B1); PG8_BAR; PG8_SCHED;
	s_setprio 1
	s_waitcnt lgkmcnt(0)
	v_mfma_f32_16x16x32_bf16 v[124:127], v[170:173], v[212:215], v[124:127]
	v_mfma_f32_16x16x32_bf16 v[120:123], v[182:185], v[212:215], v[120:123]
	v_mfma_f32_16x16x32_bf16 v[116:119], v[170:173], v[220:223], v[116:119]
	v_mfma_f32_16x16x32_bf16 v[112:115], v[182:185], v[220:223], v[112:115]
	v_mfma_f32_16x16x32_bf16 v[108:111], v[170:173], v[228:231], v[108:111]
	v_mfma_f32_16x16x32_bf16 v[104:107], v[182:185], v[228:231], v[104:107]
	v_mfma_f32_16x16x32_bf16 v[100:103], v[170:173], v[236:239], v[100:103]
	v_mfma_f32_16x16x32_bf16 v[96:99], v[182:185], v[236:239], v[96:99]
	v_mfma_f32_16x16x32_bf16 v[124:127], v[174:177], v[216:219], v[124:127]
	v_mfma_f32_16x16x32_bf16 v[120:123], v[186:189], v[216:219], v[120:123]
	v_mfma_f32_16x16x32_bf16 v[116:119], v[174:177], v[224:227], v[116:119]
	v_mfma_f32_16x16x32_bf16 v[112:115], v[186:189], v[224:227], v[112:115]
	v_mfma_f32_16x16x32_bf16 v[108:111], v[174:177], v[232:235], v[108:111]
	v_mfma_f32_16x16x32_bf16 v[104:107], v[186:189], v[232:235], v[104:107]
	v_mfma_f32_16x16x32_bf16 v[100:103], v[174:177], v[240:243], v[100:103]
	v_mfma_f32_16x16x32_bf16 v[96:99], v[186:189], v[240:243], v[96:99]
	s_setprio 0
	s_setprio 1
	v_mfma_f32_16x16x32_bf16 v[60:63], v[190:193], v[212:215], v[60:63]
	v_mfma_f32_16x16x32_bf16 v[56:59], v[198:201], v[212:215], v[56:59]
	v_mfma_f32_16x16x32_bf16 v[52:55], v[190:193], v[220:223], v[52:55]
	v_mfma_f32_16x16x32_bf16 v[48:51], v[198:201], v[220:223], v[48:51]
	v_mfma_f32_16x16x32_bf16 v[44:47], v[190:193], v[228:231], v[44:47]
	v_mfma_f32_16x16x32_bf16 v[40:43], v[198:201], v[228:231], v[40:43]
	v_mfma_f32_16x16x32_bf16 v[36:39], v[190:193], v[236:239], v[36:39]
	v_mfma_f32_16x16x32_bf16 v[32:35], v[198:201], v[236:239], v[32:35]
	v_mfma_f32_16x16x32_bf16 v[60:63], v[194:197], v[216:219], v[60:63]
	v_mfma_f32_16x16x32_bf16 v[56:59], v[208:211], v[216:219], v[56:59]
	v_mfma_f32_16x16x32_bf16 v[52:55], v[194:197], v[224:227], v[52:55]
	v_mfma_f32_16x16x32_bf16 v[48:51], v[208:211], v[224:227], v[48:51]
	v_mfma_f32_16x16x32_bf16 v[44:47], v[194:197], v[232:235], v[44:47]
	v_mfma_f32_16x16x32_bf16 v[40:43], v[208:211], v[232:235], v[40:43]
	v_mfma_f32_16x16x32_bf16 v[36:39], v[194:197], v[240:243], v[36:39]
	v_mfma_f32_16x16x32_bf16 v[32:35], v[208:211], v[240:243], v[32:35]
	s_setprio 0
	s_barrier
	s_add_i32 s3, s94, s84
	v_lshl_add_u64 v[178:179], s[60:61], 0, v[130:131]
	s_mov_b32 m0, s3
	ds_read_b128 v[212:215], v164 offset:16384
	ds_read_b128 v[216:219], v164 offset:17408
	ds_read_b128 v[220:223], v164 offset:18432
	ds_read_b128 v[224:227], v164 offset:19456
	ds_read_b128 v[228:231], v164 offset:20480
	ds_read_b128 v[232:235], v164 offset:21504
	ds_read_b128 v[236:239], v164 offset:22528
	ds_read_b128 v[240:243], v164 offset:23552
	global_load_lds_dwordx4 v[178:179], off
	s_add_i32 m0, s3, 0x2000
	s_add_u32 s14, s60, 0x40000
	v_lshl_add_u64 v[202:203], s[60:61], 0, v[134:135]
	s_addc_u32 s15, s61, 0
	s_add_i32 s3, s95, s84
	global_load_lds_dwordx4 v[202:203], off
	v_lshl_add_u64 v[244:245], s[14:15], 0, v[130:131]
	s_mov_b32 m0, s3
	v_lshl_add_u64 v[246:247], s[62:63], 0, v[132:133]
	global_load_lds_dwordx4 v[244:245], off
	v_lshl_add_u64 v[244:245], s[14:15], 0, v[134:135]
	s_add_i32 m0, s3, 0x2000
	s_nop 0
	global_load_lds_dwordx4 v[244:245], off
	s_waitcnt vmcnt(6)
	s_waitcnt lgkmcnt(0)
	s_barrier
	s_setprio 1
	s_waitcnt lgkmcnt(0)
	v_mfma_f32_16x16x32_bf16 v[92:95], v[170:173], v[212:215], v[92:95]
	v_mfma_f32_16x16x32_bf16 v[88:91], v[182:185], v[212:215], v[88:91]
	v_mfma_f32_16x16x32_bf16 v[84:87], v[170:173], v[220:223], v[84:87]
	v_mfma_f32_16x16x32_bf16 v[80:83], v[182:185], v[220:223], v[80:83]
	v_mfma_f32_16x16x32_bf16 v[76:79], v[170:173], v[228:231], v[76:79]
	v_mfma_f32_16x16x32_bf16 v[72:75], v[182:185], v[228:231], v[72:75]
	v_lshl_add_u64 v[244:245], s[62:63], 0, v[128:129]
	s_mov_b32 m0, s85
	s_nop 0
	global_load_lds_dwordx4 v[244:245], off
	v_mfma_f32_16x16x32_bf16 v[68:71], v[170:173], v[236:239], v[68:71]
	v_mfma_f32_16x16x32_bf16 v[64:67], v[182:185], v[236:239], v[64:67]
	v_mfma_f32_16x16x32_bf16 v[92:95], v[174:177], v[216:219], v[92:95]
	v_mfma_f32_16x16x32_bf16 v[88:91], v[186:189], v[216:219], v[88:91]
	v_mfma_f32_16x16x32_bf16 v[84:87], v[174:177], v[224:227], v[84:87]
	v_mfma_f32_16x16x32_bf16 v[80:83], v[186:189], v[224:227], v[80:83]
	v_mfma_f32_16x16x32_bf16 v[76:79], v[174:177], v[232:235], v[76:79]
	v_mfma_f32_16x16x32_bf16 v[72:75], v[186:189], v[232:235], v[72:75]
	v_mfma_f32_16x16x32_bf16 v[68:71], v[174:177], v[240:243], v[68:71]
	v_mfma_f32_16x16x32_bf16 v[64:67], v[186:189], v[240:243], v[64:67]
	s_setprio 0
	s_setprio 1
	v_mfma_f32_16x16x32_bf16 v[28:31], v[190:193], v[212:215], v[28:31]
	v_mfma_f32_16x16x32_bf16 v[24:27], v[198:201], v[212:215], v[24:27]
	s_mov_b32 m0, s86
	s_nop 0
	global_load_lds_dwordx4 v[246:247], off
	v_mfma_f32_16x16x32_bf16 v[20:23], v[190:193], v[220:223], v[20:23]
	v_mfma_f32_16x16x32_bf16 v[16:19], v[198:201], v[220:223], v[16:19]
	v_mfma_f32_16x16x32_bf16 v[12:15], v[190:193], v[228:231], v[12:15]
	v_mfma_f32_16x16x32_bf16 v[8:11], v[198:201], v[228:231], v[8:11]
	v_mfma_f32_16x16x32_bf16 v[4:7], v[190:193], v[236:239], v[4:7]
	v_mfma_f32_16x16x32_bf16 v[0:3], v[198:201], v[236:239], v[0:3]
	v_mfma_f32_16x16x32_bf16 v[28:31], v[194:197], v[216:219], v[28:31]
	v_mfma_f32_16x16x32_bf16 v[24:27], v[208:211], v[216:219], v[24:27]
	v_mfma_f32_16x16x32_bf16 v[20:23], v[194:197], v[224:227], v[20:23]
	v_mfma_f32_16x16x32_bf16 v[16:19], v[208:211], v[224:227], v[16:19]
	v_mfma_f32_16x16x32_bf16 v[12:15], v[194:197], v[232:235], v[12:15]
	v_mfma_f32_16x16x32_bf16 v[8:11], v[208:211], v[232:235], v[8:11]
	v_mfma_f32_16x16x32_bf16 v[4:7], v[194:197], v[240:243], v[4:7]
	v_mfma_f32_16x16x32_bf16 v[0:3], v[208:211], v[240:243], v[0:3]
	s_setprio 0
	s_barrier
; #define PG8_STAGE(bufoff, gbase, voff) do { _Pragma("unroll") for (int _i = 0; _i < 2; ++_i) \
;         __builtin_amdgcn_global_load_lds((const unsigned*)((const char*)(gbase) + (voff)[_i]), (PG8_LAS unsigned*)(lds + (bufoff) + ldsw + _i * 8192), 16, 0, 0); } while (0)
; #define PG8_LDA(dst, b, h) do { _Pragma("unroll") for (int m = 0; m < 4; ++m) _Pragma("unroll") for (int k = 0; k < 2; ++k) dst[m][k] = *(const PG8_LAS bf16x8*)(lds + PG8_SA(b, h) + aoff + m * 2048 + k * 1024); } while (0)
; #define PG8_LDB(dst, b, h) do { _Pragma("unroll") for (int n = 0; n < 2; ++n) _Pragma("unroll") for (int k = 0; k < 2; ++k) dst[n][k] = *(const PG8_LAS bf16x8*)(lds + PG8_SB(b, h) + boff + n * 2048 + k * 1024); } while (0)
; #define PG8_MMA(ai, bj, At, Bt) do { __builtin_amdgcn_s_setprio(1); _Pragma("unroll") for (int m = 0; m < 4; ++m) _Pragma("unroll") for (int n = 0; n < 2; ++n) _Pragma("unroll") for (int k = 0; k < 2; ++k) \
;         acc[ai][bj][m][n] = __builtin_amdgcn_mfma_f32_16x16x32_bf16(Bt[n][k], At[m][k], acc[ai][bj][m][n], 0, 0, 0); __builtin_amdgcn_s_setprio(0); } while (0)
; #define PG8_WAIT_V(n) asm volatile("s_waitcnt vmcnt(" #n ")" ::: "memory")
; #define PG8_WAIT_L(n) asm volatile("s_waitcnt lgkmcnt(" #n ")" ::: "memory")
; #define PG8_BAR __builtin_amdgcn_s_barrier()
; #define PG8_SCHED __builtin_amdgcn_sched_barrier(0)
; template <class Epi, class Sched, bool ALIGN_EPI = false, bool SP2 = false>
; __device__ __forceinline__ void gemm_phase(PG8_LAS unsigned char* lds, const Gemm g, const Sched& S, const Epi& E) {
;     ...
;             PG8_LDB(B0, 1, 0); PG8_LDB(B1, 1, 1); PG8_SCHED; PG8_LDA(At, 1, 0); PG8_STAGE(PG8_SA(0, 1), a2 + hstep, voffA);
;             PG8_WAIT_V(8); PG8_WAIT_L(0); PG8_BAR; PG8_MMA(0, 0, At, B0); PG8_MMA(0, 1, At, B1); PG8_BAR; PG8_SCHED;
	s_add_i32 s3, 0, 0x18000
	v_add_u32_e32 v136, s3, v141
	s_add_i32 s33, 0, 0x1c000
	ds_read_b128 v[170:173], v136
	ds_read_b128 v[174:177], v136 offset:1024
	ds_read_b128 v[182:185], v136 offset:2048
	ds_read_b128 v[186:189], v136 offset:3072
	v_add_u32_e32 v136, s33, v141
	ds_read_b128 v[190:193], v136
	ds_read_b128 v[194:197], v136 offset:1024
	ds_read_b128 v[198:201], v136 offset:2048
	ds_read_b128 v[208:211], v136 offset:3072
	s_add_u32 s14, s62, 0x40000
	s_addc_u32 s15, s63, 0
	s_mov_b32 m0, s87
	v_lshl_add_u64 v[248:249], s[14:15], 0, v[128:129]
	ds_read_b128 v[212:215], v164 offset:32768
	ds_read_b128 v[216:219], v164 offset:33792
	ds_read_b128 v[220:223], v164 offset:34816
	ds_read_b128 v[224:227], v164 offset:35840
	ds_read_b128 v[228:231], v164 offset:36864
	ds_read_b128 v[232:235], v164 offset:37888
	ds_read_b128 v[236:239], v164 offset:38912
	ds_read_b128 v[240:243], v164 offset:39936
	global_load_lds_dwordx4 v[248:249], off
	v_lshl_add_u64 v[248:249], s[14:15], 0, v[132:133]
	s_mov_b32 m0, s88
	s_nop 0
	global_load_lds_dwordx4 v[248:249], off
	s_waitcnt vmcnt(8)
	s_waitcnt lgkmcnt(0)
	s_barrier
	s_setprio 1
	s_waitcnt lgkmcnt(0)
	v_mfma_f32_16x16x32_bf16 v[124:127], v[170:173], v[212:215], v[124:127]
	v_mfma_f32_16x16x32_bf16 v[120:123], v[182:185], v[212:215], v[120:123]
	v_mfma_f32_16x16x32_bf16 v[116:119], v[170:173], v[220:223], v[116:119]
	v_mfma_f32_16x16x32_bf16 v[112:115], v[182:185], v[220:223], v[112:115]
	v_mfma_f32_16x16x32_bf16 v[108:111], v[170:173], v[228:231], v[108:111]
	v_mfma_f32_16x16x32_bf16 v[104:107], v[182:185], v[228:231], v[104:107]
	v_mfma_f32_16x16x32_bf16 v[100:103], v[170:173], v[236:239], v[100:103]
	v_mfma_f32_16x16x32_bf16 v[96:99], v[182:185], v[236:239], v[96:99]
	v_mfma_f32_16x16x32_bf16 v[124:127], v[174:177], v[216:219], v[124:127]
	v_mfma_f32_16x16x32_bf16 v[120:123], v[186:189], v[216:219], v[120:123]
	v_mfma_f32_16x16x32_bf16 v[116:119], v[174:177], v[224:227], v[116:119]
	v_mfma_f32_16x16x32_bf16 v[112:115], v[186:189], v[224:227], v[112:115]
	v_mfma_f32_16x16x32_bf16 v[108:111], v[174:177], v[232:235], v[108:111]
	v_mfma_f32_16x16x32_bf16 v[104:107], v[186:189], v[232:235], v[104:107]
	v_mfma_f32_16x16x32_bf16 v[100:103], v[174:177], v[240:243], v[100:103]
	v_mfma_f32_16x16x32_bf16 v[96:99], v[186:189], v[240:243], v[96:99]
	s_setprio 0
	s_setprio 1
	v_mfma_f32_16x16x32_bf16 v[60:63], v[190:193], v[212:215], v[60:63]
	v_mfma_f32_16x16x32_bf16 v[56:59], v[198:201], v[212:215], v[56:59]
	v_mfma_f32_16x16x32_bf16 v[52:55], v[190:193], v[220:223], v[52:55]
	v_mfma_f32_16x16x32_bf16 v[48:51], v[198:201], v[220:223], v[48:51]
	v_mfma_f32_16x16x32_bf16 v[44:47], v[190:193], v[228:231], v[44:47]
	v_mfma_f32_16x16x32_bf16 v[40:43], v[198:201], v[228:231], v[40:43]
	v_mfma_f32_16x16x32_bf16 v[36:39], v[190:193], v[236:239], v[36:39]
	v_mfma_f32_16x16x32_bf16 v[32:35], v[198:201], v[236:239], v[32:35]
	v_mfma_f32_16x16x32_bf16 v[60:63], v[194:197], v[216:219], v[60:63]
	v_mfma_f32_16x16x32_bf16 v[56:59], v[208:211], v[216:219], v[56:59]
	v_mfma_f32_16x16x32_bf16 v[52:55], v[194:197], v[224:227], v[52:55]
	v_mfma_f32_16x16x32_bf16 v[48:51], v[208:211], v[224:227], v[48:51]
	v_mfma_f32_16x16x32_bf16 v[44:47], v[194:197], v[232:235], v[44:47]
	v_mfma_f32_16x16x32_bf16 v[40:43], v[208:211], v[232:235], v[40:43]
	v_mfma_f32_16x16x32_bf16 v[36:39], v[194:197], v[240:243], v[36:39]
	v_mfma_f32_16x16x32_bf16 v[32:35], v[208:211], v[240:243], v[32:35]
	s_setprio 0
	s_barrier
; #define PG8_STAGE(bufoff, gbase, voff) do { _Pragma("unroll") for (int _i = 0; _i < 2; ++_i) \
;         __builtin_amdgcn_global_load_lds((const unsigned*)((const char*)(gbase) + (voff)[_i]), (PG8_LAS unsigned*)(lds + (bufoff) + ldsw + _i * 8192), 16, 0, 0); } while (0)
; #define PG8_LDA(dst, b, h) do { _Pragma("unroll") for (int m = 0; m < 4; ++m) _Pragma("unroll") for (int k = 0; k < 2; ++k) dst[m][k] = *(const PG8_LAS bf16x8*)(lds + PG8_SA(b, h) + aoff + m * 2048 + k * 1024); } while (0)
; #define PG8_MMA(ai, bj, At, Bt) do { __builtin_amdgcn_s_setprio(1); _Pragma("unroll") for (int m = 0; m < 4; ++m) _Pragma("unroll") for (int n = 0; n < 2; ++n) _Pragma("unroll") for (int k = 0; k < 2; ++k) \
;         acc[ai][bj][m][n] = __builtin_amdgcn_mfma_f32_16x16x32_bf16(Bt[n][k], At[m][k], acc[ai][bj][m][n], 0, 0, 0); __builtin_amdgcn_s_setprio(0); } while (0)
; #define PG8_WAIT_V(n) asm volatile("s_waitcnt vmcnt(" #n ")" ::: "memory")
; #define PG8_WAIT_L(n) asm volatile("s_waitcnt lgkmcnt(" #n ")" ::: "memory")
; #define PG8_BAR __builtin_amdgcn_s_barrier()
; #define PG8_SCHED __builtin_amdgcn_sched_barrier(0)
; template <class Epi, class Sched, bool ALIGN_EPI = false, bool SP2 = false>
; __device__ __forceinline__ void gemm_phase(PG8_LAS unsigned char* lds, const Gemm g, const Sched& S, const Epi& E) {
;     ...
;         for (int t = 0; t < nt; t += 2) {
;             const bool last = (t == nt - 2);
;             const char* a1 = cA + (size_t)(t + 1) * kstep;
;             const char* a2 = last ? nA : cA + (size_t)(t + 2) * kstep; const char* b2 = last ? nB : cB + (size_t)(t + 2) * kstep;
;     ...
;             PG8_LDA(At, 1, 1); PG8_STAGE(PG8_SB(1, 0), b3, voffB); PG8_STAGE(PG8_SB(1, 1), b3 + hstep, voffB); PG8_STAGE(PG8_SA(1, 0), a3, voffA);
;             PG8_WAIT_V(8); PG8_WAIT_L(0); PG8_BAR; PG8_MMA(1, 0, At, B0); PG8_MMA(1, 1, At, B1); PG8_BAR; PG8_SCHED;
	s_add_i32 s3, s3, s84
	v_lshl_add_u64 v[178:179], v[178:179], 0, s[8:9]
	s_mov_b32 m0, s3
	ds_read_b128 v[212:215], v164 offset:49152
	ds_read_b128 v[216:219], v164 offset:50176
	ds_read_b128 v[220:223], v164 offset:51200
	ds_read_b128 v[224:227], v164 offset:52224
	ds_read_b128 v[228:231], v164 offset:53248
	ds_read_b128 v[232:235], v164 offset:54272
	ds_read_b128 v[236:239], v164 offset:55296
	ds_read_b128 v[240:243], v164 offset:56320
	global_load_lds_dwordx4 v[178:179], off
	s_add_i32 m0, s3, 0x2000
	s_add_u32 s14, s60, 0x40080
	v_lshl_add_u64 v[178:179], v[202:203], 0, s[8:9]
	s_addc_u32 s15, s61, 0
	s_add_i32 s3, s33, s84
	global_load_lds_dwordx4 v[178:179], off
	v_lshl_add_u64 v[178:179], s[14:15], 0, v[130:131]
	s_mov_b32 m0, s3
	s_nop 0
	global_load_lds_dwordx4 v[178:179], off
	v_lshl_add_u64 v[178:179], s[14:15], 0, v[134:135]
	s_add_i32 m0, s3, 0x2000
	s_nop 0
	global_load_lds_dwordx4 v[178:179], off
	s_waitcnt vmcnt(6)
	s_waitcnt lgkmcnt(0)
	s_barrier
	s_setprio 1
	s_waitcnt lgkmcnt(0)
	v_mfma_f32_16x16x32_bf16 v[92:95], v[170:173], v[212:215], v[92:95]
	v_mfma_f32_16x16x32_bf16 v[88:91], v[182:185], v[212:215], v[88:91]
	v_mfma_f32_16x16x32_bf16 v[84:87], v[170:173], v[220:223], v[84:87]
	v_mfma_f32_16x16x32_bf16 v[80:83], v[182:185], v[220:223], v[80:83]
	v_mfma_f32_16x16x32_bf16 v[76:79], v[170:173], v[228:231], v[76:79]
	v_mfma_f32_16x16x32_bf16 v[72:75], v[182:185], v[228:231], v[72:75]
	v_lshl_add_u64 v[178:179], v[244:245], 0, s[8:9]
	s_mov_b32 m0, s90
	s_nop 0
	global_load_lds_dwordx4 v[178:179], off
	v_mfma_f32_16x16x32_bf16 v[68:71], v[170:173], v[236:239], v[68:71]
	v_mfma_f32_16x16x32_bf16 v[64:67], v[182:185], v[236:239], v[64:67]
	v_mfma_f32_16x16x32_bf16 v[92:95], v[174:177], v[216:219], v[92:95]
	v_mfma_f32_16x16x32_bf16 v[88:91], v[186:189], v[216:219], v[88:91]
	v_mfma_f32_16x16x32_bf16 v[84:87], v[174:177], v[224:227], v[84:87]
	v_mfma_f32_16x16x32_bf16 v[80:83], v[186:189], v[224:227], v[80:83]
	v_mfma_f32_16x16x32_bf16 v[76:79], v[174:177], v[232:235], v[76:79]
	v_mfma_f32_16x16x32_bf16 v[72:75], v[186:189], v[232:235], v[72:75]
	v_mfma_f32_16x16x32_bf16 v[68:71], v[174:177], v[240:243], v[68:71]
	v_mfma_f32_16x16x32_bf16 v[64:67], v[186:189], v[240:243], v[64:67]
	s_setprio 0
	s_setprio 1
	v_mfma_f32_16x16x32_bf16 v[28:31], v[190:193], v[212:215], v[28:31]
	v_mfma_f32_16x16x32_bf16 v[24:27], v[198:201], v[212:215], v[24:27]
	v_lshl_add_u64 v[178:179], v[246:247], 0, s[8:9]
	s_mov_b32 m0, s91
	s_nop 0
	global_load_lds_dwordx4 v[178:179], off
	v_mfma_f32_16x16x32_bf16 v[20:23], v[190:193], v[220:223], v[20:23]
	v_mfma_f32_16x16x32_bf16 v[16:19], v[198:201], v[220:223], v[16:19]
	v_mfma_f32_16x16x32_bf16 v[12:15], v[190:193], v[228:231], v[12:15]
	v_mfma_f32_16x16x32_bf16 v[8:11], v[198:201], v[228:231], v[8:11]
	v_mfma_f32_16x16x32_bf16 v[4:7], v[190:193], v[236:239], v[4:7]
	v_mfma_f32_16x16x32_bf16 v[0:3], v[198:201], v[236:239], v[0:3]
	v_mfma_f32_16x16x32_bf16 v[28:31], v[194:197], v[216:219], v[28:31]
	v_mfma_f32_16x16x32_bf16 v[24:27], v[208:211], v[216:219], v[24:27]
	v_mfma_f32_16x16x32_bf16 v[20:23], v[194:197], v[224:227], v[20:23]
	v_mfma_f32_16x16x32_bf16 v[16:19], v[208:211], v[224:227], v[16:19]
	v_mfma_f32_16x16x32_bf16 v[12:15], v[194:197], v[232:235], v[12:15]
	v_mfma_f32_16x16x32_bf16 v[8:11], v[208:211], v[232:235], v[8:11]
	v_mfma_f32_16x16x32_bf16 v[4:7], v[194:197], v[240:243], v[4:7]
	v_mfma_f32_16x16x32_bf16 v[0:3], v[208:211], v[240:243], v[0:3]
	s_setprio 0
	s_barrier
	s_add_i32 vcc_lo, vcc_lo, 2
	s_add_u32 s58, s58, 0x100
	s_addc_u32 s59, s59, 0
	s_add_u32 s96, s96, 0x100
	s_addc_u32 s97, s97, 0
	s_cmp_gt_u32 vcc_lo, 13
	s_cbranch_scc0 .LBB0_459
	s_and_b64 vcc, exec, s[10:11]
	s_cbranch_vccz .LBB0_462
	s_barrier

; #define PG8_STAGE(bufoff, gbase, voff) do { _Pragma("unroll") for (int _i = 0; _i < 2; ++_i) \
;         __builtin_amdgcn_global_load_lds((const unsigned*)((const char*)(gbase) + (voff)[_i]), (PG8_LAS unsigned*)(lds + (bufoff) + ldsw + _i * 8192), 16, 0, 0); } while (0)
; #define PG8_LDA(dst, b, h) do { _Pragma("unroll") for (int m = 0; m < 4; ++m) _Pragma("unroll") for (int k = 0; k < 2; ++k) dst[m][k] = *(const PG8_LAS bf16x8*)(lds + PG8_SA(b, h) + aoff + m * 2048 + k * 1024); } while (0)
; #define PG8_LDB(dst, b, h) do { _Pragma("unroll") for (int n = 0; n < 2; ++n) _Pragma("unroll") for (int k = 0; k < 2; ++k) dst[n][k] = *(const PG8_LAS bf16x8*)(lds + PG8_SB(b, h) + boff + n * 2048 + k * 1024); } while (0)
; #define PG8_MMA(ai, bj, At, Bt) do { __builtin_amdgcn_s_setprio(1); _Pragma("unroll") for (int m = 0; m < 4; ++m) _Pragma("unroll") for (int n = 0; n < 2; ++n) _Pragma("unroll") for (int k = 0; k < 2; ++k) \
;         acc[ai][bj][m][n] = __builtin_amdgcn_mfma_f32_16x16x32_bf16(Bt[n][k], At[m][k], acc[ai][bj][m][n], 0, 0, 0); __builtin_amdgcn_s_setprio(0); } while (0)
; #define PG8_WAIT_V(n) asm volatile("s_waitcnt vmcnt(" #n ")" ::: "memory")
; #define PG8_WAIT_L(n) asm volatile("s_waitcnt lgkmcnt(" #n ")" ::: "memory")
; #define PG8_BAR __builtin_amdgcn_s_barrier()
; #define PG8_SCHED __builtin_amdgcn_sched_barrier(0)
; template <class Epi, class Sched, bool ALIGN_EPI = false, bool SP2 = false>
; __device__ __forceinline__ void gemm_phase(PG8_LAS unsigned char* lds, const Gemm g, const Sched& S, const Epi& E) {
;     ...
;             PG8_LDB(B0, 0, 0); PG8_LDB(B1, 0, 1); PG8_SCHED; PG8_LDA(At, 0, 0); PG8_STAGE(PG8_SA(1, 1), a1 + hstep, voffA);
;             PG8_WAIT_V(8); PG8_WAIT_L(0); PG8_BAR; PG8_MMA(0, 0, At, B0); PG8_MMA(0, 1, At, B1); PG8_BAR; PG8_SCHED;
;             PG8_LDA(At, 0, 1); PG8_STAGE(PG8_SB(0, 0), b2, voffB); PG8_STAGE(PG8_SB(0, 1), b2 + hstep, voffB); PG8_STAGE(PG8_SA(0, 0), a2, voffA);
;             PG8_WAIT_V(8); PG8_WAIT_L(0); PG8_BAR; PG8_MMA(1, 0, At, B0); PG8_MMA(1, 1, At, B1); PG8_BAR; PG8_SCHED;
.LBB0_495:
	ds_read_b128 v[170:173], v165
	ds_read_b128 v[174:177], v165 offset:1024
	ds_read_b128 v[182:185], v165 offset:2048
	ds_read_b128 v[186:189], v165 offset:3072
	ds_read_b128 v[190:193], v168
	ds_read_b128 v[194:197], v168 offset:1024
	ds_read_b128 v[198:201], v168 offset:2048
	ds_read_b128 v[208:211], v168 offset:3072
	s_add_u32 s3, s60, 0xfffc0080
	s_addc_u32 s14, s61, -1
	s_cmp_eq_u32 s97, 12
	s_cselect_b32 s65, s49, s14
	s_cselect_b32 s64, s57, s3
	s_cselect_b32 s63, s45, s96
	s_cselect_b32 s62, s94, s95
	v_lshl_add_u64 v[178:179], s[60:61], 0, v[160:161]
	s_add_i32 m0, s59, 0xc000
	ds_read_b128 v[212:215], v164
	ds_read_b128 v[216:219], v164 offset:1024
	ds_read_b128 v[220:223], v164 offset:2048
	ds_read_b128 v[224:227], v164 offset:3072
	ds_read_b128 v[228:231], v164 offset:4096
	ds_read_b128 v[232:235], v164 offset:5120
	ds_read_b128 v[236:239], v164 offset:6144
	ds_read_b128 v[240:243], v164 offset:7168
	global_load_lds_dwordx4 v[178:179], off
	v_lshl_add_u64 v[178:179], s[60:61], 0, v[162:163]
	s_add_i32 m0, s59, 0xe000
	s_nop 0
	global_load_lds_dwordx4 v[178:179], off
	s_waitcnt vmcnt(8)
	s_waitcnt lgkmcnt(0)
	s_barrier
	s_setprio 1
	s_waitcnt lgkmcnt(0)
	v_mfma_f32_16x16x32_bf16 v[124:127], v[170:173], v[212:215], v[124:127]
	v_mfma_f32_16x16x32_bf16 v[120:123], v[182:185], v[212:215], v[120:123]
	v_mfma_f32_16x16x32_bf16 v[116:119], v[170:173], v[220:223], v[116:119]
	v_mfma_f32_16x16x32_bf16 v[112:115], v[182:185], v[220:223], v[112:115]
	v_mfma_f32_16x16x32_bf16 v[108:111], v[170:173], v[228:231], v[108:111]
	v_mfma_f32_16x16x32_bf16 v[104:107], v[182:185], v[228:231], v[104:107]
	v_mfma_f32_16x16x32_bf16 v[100:103], v[170:173], v[236:239], v[100:103]
	v_mfma_f32_16x16x32_bf16 v[96:99], v[182:185], v[236:239], v[96:99]
	v_mfma_f32_16x16x32_bf16 v[124:127], v[174:177], v[216:219], v[124:127]
	v_mfma_f32_16x16x32_bf16 v[120:123], v[186:189], v[216:219], v[120:123]
	v_mfma_f32_16x16x32_bf16 v[116:119], v[174:177], v[224:227], v[116:119]
	v_mfma_f32_16x16x32_bf16 v[112:115], v[186:189], v[224:227], v[112:115]
	v_mfma_f32_16x16x32_bf16 v[108:111], v[174:177], v[232:235], v[108:111]
	v_mfma_f32_16x16x32_bf16 v[104:107], v[186:189], v[232:235], v[104:107]
	v_mfma_f32_16x16x32_bf16 v[100:103], v[174:177], v[240:243], v[100:103]
	v_mfma_f32_16x16x32_bf16 v[96:99], v[186:189], v[240:243], v[96:99]
	s_setprio 0
	s_setprio 1
	v_mfma_f32_16x16x32_bf16 v[60:63], v[190:193], v[212:215], v[60:63]
	v_mfma_f32_16x16x32_bf16 v[56:59], v[198:201], v[212:215], v[56:59]
	v_mfma_f32_16x16x32_bf16 v[52:55], v[190:193], v[220:223], v[52:55]
	v_mfma_f32_16x16x32_bf16 v[48:51], v[198:201], v[220:223], v[48:51]
	v_mfma_f32_16x16x32_bf16 v[44:47], v[190:193], v[228:231], v[44:47]
	v_mfma_f32_16x16x32_bf16 v[40:43], v[198:201], v[228:231], v[40:43]
	v_mfma_f32_16x16x32_bf16 v[36:39], v[190:193], v[236:239], v[36:39]
	v_mfma_f32_16x16x32_bf16 v[32:35], v[198:201], v[236:239], v[32:35]
	v_mfma_f32_16x16x32_bf16 v[60:63], v[194:197], v[216:219], v[60:63]
	v_mfma_f32_16x16x32_bf16 v[56:59], v[208:211], v[216:219], v[56:59]
	v_mfma_f32_16x16x32_bf16 v[52:55], v[194:197], v[224:227], v[52:55]
	v_mfma_f32_16x16x32_bf16 v[48:51], v[208:211], v[224:227], v[48:51]
	v_mfma_f32_16x16x32_bf16 v[44:47], v[194:197], v[232:235], v[44:47]
	v_mfma_f32_16x16x32_bf16 v[40:43], v[208:211], v[232:235], v[40:43]
	v_mfma_f32_16x16x32_bf16 v[36:39], v[194:197], v[240:243], v[36:39]
	v_mfma_f32_16x16x32_bf16 v[32:35], v[208:211], v[240:243], v[32:35]
	s_setprio 0
	s_barrier
	s_add_i32 s3, s92, s75
	v_lshl_add_u64 v[178:179], s[62:63], 0, v[130:131]
	s_mov_b32 m0, s3
	ds_read_b128 v[212:215], v164 offset:16384
	ds_read_b128 v[216:219], v164 offset:17408
	ds_read_b128 v[220:223], v164 offset:18432
	ds_read_b128 v[224:227], v164 offset:19456
	ds_read_b128 v[228:231], v164 offset:20480
	ds_read_b128 v[232:235], v164 offset:21504
	ds_read_b128 v[236:239], v164 offset:22528
	ds_read_b128 v[240:243], v164 offset:23552
	global_load_lds_dwordx4 v[178:179], off
	s_add_i32 m0, s3, 0x2000
	s_add_u32 s14, s62, 0x40000
	v_lshl_add_u64 v[202:203], s[62:63], 0, v[134:135]
	s_addc_u32 s15, s63, 0
	s_add_i32 s3, s93, s75
	global_load_lds_dwordx4 v[202:203], off
	v_lshl_add_u64 v[244:245], s[14:15], 0, v[130:131]
	s_mov_b32 m0, s3
	v_lshl_add_u64 v[246:247], s[64:65], 0, v[132:133]
	global_load_lds_dwordx4 v[244:245], off
	v_lshl_add_u64 v[244:245], s[14:15], 0, v[134:135]
	s_add_i32 m0, s3, 0x2000
	s_nop 0
	global_load_lds_dwordx4 v[244:245], off
	s_waitcnt vmcnt(6)
	s_waitcnt lgkmcnt(0)
	s_barrier
; #define PG8_STAGE(bufoff, gbase, voff) do { _Pragma("unroll") for (int _i = 0; _i < 2; ++_i) \
;         __builtin_amdgcn_global_load_lds((const unsigned*)((const char*)(gbase) + (voff)[_i]), (PG8_LAS unsigned*)(lds + (bufoff) + ldsw + _i * 8192), 16, 0, 0); } while (0)
; #define PG8_LDA(dst, b, h) do { _Pragma("unroll") for (int m = 0; m < 4; ++m) _Pragma("unroll") for (int k = 0; k < 2; ++k) dst[m][k] = *(const PG8_LAS bf16x8*)(lds + PG8_SA(b, h) + aoff + m * 2048 + k * 1024); } while (0)
; #define PG8_LDB(dst, b, h) do { _Pragma("unroll") for (int n = 0; n < 2; ++n) _Pragma("unroll") for (int k = 0; k < 2; ++k) dst[n][k] = *(const PG8_LAS bf16x8*)(lds + PG8_SB(b, h) + boff + n * 2048 + k * 1024); } while (0)
; #define PG8_MMA(ai, bj, At, Bt) do { __builtin_amdgcn_s_setprio(1); _Pragma("unroll") for (int m = 0; m < 4; ++m) _Pragma("unroll") for (int n = 0; n < 2; ++n) _Pragma("unroll") for (int k = 0; k < 2; ++k) \
;         acc[ai][bj][m][n] = __builtin_amdgcn_mfma_f32_16x16x32_bf16(Bt[n][k], At[m][k], acc[ai][bj][m][n], 0, 0, 0); __builtin_amdgcn_s_setprio(0); } while (0)
; #define PG8_WAIT_V(n) asm volatile("s_waitcnt vmcnt(" #n ")" ::: "memory")
; #define PG8_WAIT_L(n) asm volatile("s_waitcnt lgkmcnt(" #n ")" ::: "memory")
; #define PG8_BAR __builtin_amdgcn_s_barrier()
; #define PG8_SCHED __builtin_amdgcn_sched_barrier(0)
; template <class Epi, class Sched, bool ALIGN_EPI = false, bool SP2 = false>
; __device__ __forceinline__ void gemm_phase(PG8_LAS unsigned char* lds, const Gemm g, const Sched& S, const Epi& E) {
;     ...
;             PG8_WAIT_V(8); PG8_WAIT_L(0); PG8_BAR; PG8_MMA(1, 0, At, B0); PG8_MMA(1, 1, At, B1); PG8_BAR; PG8_SCHED;
;             PG8_LDB(B0, 1, 0); PG8_LDB(B1, 1, 1); PG8_SCHED; PG8_LDA(At, 1, 0); PG8_STAGE(PG8_SA(0, 1), a2 + hstep, voffA);
;             PG8_WAIT_V(8); PG8_WAIT_L(0); PG8_BAR; PG8_MMA(0, 0, At, B0); PG8_MMA(0, 1, At, B1); PG8_BAR; PG8_SCHED;
	s_setprio 1
	s_waitcnt lgkmcnt(0)
	v_mfma_f32_16x16x32_bf16 v[92:95], v[170:173], v[212:215], v[92:95]
	v_mfma_f32_16x16x32_bf16 v[88:91], v[182:185], v[212:215], v[88:91]
	v_mfma_f32_16x16x32_bf16 v[84:87], v[170:173], v[220:223], v[84:87]
	v_mfma_f32_16x16x32_bf16 v[80:83], v[182:185], v[220:223], v[80:83]
	v_mfma_f32_16x16x32_bf16 v[76:79], v[170:173], v[228:231], v[76:79]
	v_mfma_f32_16x16x32_bf16 v[72:75], v[182:185], v[228:231], v[72:75]
	v_lshl_add_u64 v[244:245], s[64:65], 0, v[128:129]
	s_mov_b32 m0, s59
	s_nop 0
	global_load_lds_dwordx4 v[244:245], off
	v_mfma_f32_16x16x32_bf16 v[68:71], v[170:173], v[236:239], v[68:71]
	v_mfma_f32_16x16x32_bf16 v[64:67], v[182:185], v[236:239], v[64:67]
	v_mfma_f32_16x16x32_bf16 v[92:95], v[174:177], v[216:219], v[92:95]
	v_mfma_f32_16x16x32_bf16 v[88:91], v[186:189], v[216:219], v[88:91]
	v_mfma_f32_16x16x32_bf16 v[84:87], v[174:177], v[224:227], v[84:87]
	v_mfma_f32_16x16x32_bf16 v[80:83], v[186:189], v[224:227], v[80:83]
	v_mfma_f32_16x16x32_bf16 v[76:79], v[174:177], v[232:235], v[76:79]
	v_mfma_f32_16x16x32_bf16 v[72:75], v[186:189], v[232:235], v[72:75]
	v_mfma_f32_16x16x32_bf16 v[68:71], v[174:177], v[240:243], v[68:71]
	v_mfma_f32_16x16x32_bf16 v[64:67], v[186:189], v[240:243], v[64:67]
	s_setprio 0
	s_setprio 1
	v_mfma_f32_16x16x32_bf16 v[28:31], v[190:193], v[212:215], v[28:31]
	v_mfma_f32_16x16x32_bf16 v[24:27], v[198:201], v[212:215], v[24:27]
	s_mov_b32 m0, s84
	s_nop 0
	global_load_lds_dwordx4 v[246:247], off
	v_mfma_f32_16x16x32_bf16 v[20:23], v[190:193], v[220:223], v[20:23]
	v_mfma_f32_16x16x32_bf16 v[16:19], v[198:201], v[220:223], v[16:19]
	v_mfma_f32_16x16x32_bf16 v[12:15], v[190:193], v[228:231], v[12:15]
	v_mfma_f32_16x16x32_bf16 v[8:11], v[198:201], v[228:231], v[8:11]
	v_mfma_f32_16x16x32_bf16 v[4:7], v[190:193], v[236:239], v[4:7]
	v_mfma_f32_16x16x32_bf16 v[0:3], v[198:201], v[236:239], v[0:3]
	v_mfma_f32_16x16x32_bf16 v[28:31], v[194:197], v[216:219], v[28:31]
	v_mfma_f32_16x16x32_bf16 v[24:27], v[208:211], v[216:219], v[24:27]
	v_mfma_f32_16x16x32_bf16 v[20:23], v[194:197], v[224:227], v[20:23]
	v_mfma_f32_16x16x32_bf16 v[16:19], v[208:211], v[224:227], v[16:19]
	v_mfma_f32_16x16x32_bf16 v[12:15], v[194:197], v[232:235], v[12:15]
	v_mfma_f32_16x16x32_bf16 v[8:11], v[208:211], v[232:235], v[8:11]
	v_mfma_f32_16x16x32_bf16 v[4:7], v[194:197], v[240:243], v[4:7]
	v_mfma_f32_16x16x32_bf16 v[0:3], v[208:211], v[240:243], v[0:3]
	s_setprio 0
	s_barrier
	s_add_i32 s3, 0, 0x18000
	v_add_u32_e32 v136, s3, v141
	s_add_i32 s33, 0, 0x1c000
	ds_read_b128 v[170:173], v136
	ds_read_b128 v[174:177], v136 offset:1024
	ds_read_b128 v[182:185], v136 offset:2048
	ds_read_b128 v[186:189], v136 offset:3072
	v_add_u32_e32 v136, s33, v141
	ds_read_b128 v[190:193], v136
	ds_read_b128 v[194:197], v136 offset:1024
	ds_read_b128 v[198:201], v136 offset:2048
	ds_read_b128 v[208:211], v136 offset:3072
	s_add_u32 s14, s64, 0x40000
	s_addc_u32 s15, s65, 0
	s_mov_b32 m0, s85
	v_lshl_add_u64 v[248:249], s[14:15], 0, v[128:129]
	ds_read_b128 v[212:215], v164 offset:32768
	ds_read_b128 v[216:219], v164 offset:33792
	ds_read_b128 v[220:223], v164 offset:34816
	ds_read_b128 v[224:227], v164 offset:35840
	ds_read_b128 v[228:231], v164 offset:36864
	ds_read_b128 v[232:235], v164 offset:37888
	ds_read_b128 v[236:239], v164 offset:38912
	ds_read_b128 v[240:243], v164 offset:39936
	global_load_lds_dwordx4 v[248:249], off
	v_lshl_add_u64 v[248:249], s[14:15], 0, v[132:133]
	s_mov_b32 m0, s86
	s_nop 0
	global_load_lds_dwordx4 v[248:249], off
	s_waitcnt vmcnt(8)
	s_waitcnt lgkmcnt(0)
	s_barrier
	s_setprio 1
	s_waitcnt lgkmcnt(0)
	v_mfma_f32_16x16x32_bf16 v[124:127], v[170:173], v[212:215], v[124:127]
	v_mfma_f32_16x16x32_bf16 v[120:123], v[182:185], v[212:215], v[120:123]
	v_mfma_f32_16x16x32_bf16 v[116:119], v[170:173], v[220:223], v[116:119]
	v_mfma_f32_16x16x32_bf16 v[112:115], v[182:185], v[220:223], v[112:115]
	v_mfma_f32_16x16x32_bf16 v[108:111], v[170:173], v[228:231], v[108:111]
	v_mfma_f32_16x16x32_bf16 v[104:107], v[182:185], v[228:231], v[104:107]
	v_mfma_f32_16x16x32_bf16 v[100:103], v[170:173], v[236:239], v[100:103]
	v_mfma_f32_16x16x32_bf16 v[96:99], v[182:185], v[236:239], v[96:99]
	v_mfma_f32_16x16x32_bf16 v[124:127], v[174:177], v[216:219], v[124:127]
	v_mfma_f32_16x16x32_bf16 v[120:123], v[186:189], v[216:219], v[120:123]
	v_mfma_f32_16x16x32_bf16 v[116:119], v[174:177], v[224:227], v[116:119]
	v_mfma_f32_16x16x32_bf16 v[112:115], v[186:189], v[224:227], v[112:115]
	v_mfma_f32_16x16x32_bf16 v[108:111], v[174:177], v[232:235], v[108:111]
	v_mfma_f32_16x16x32_bf16 v[104:107], v[186:189], v[232:235], v[104:107]
	v_mfma_f32_16x16x32_bf16 v[100:103], v[174:177], v[240:243], v[100:103]
	v_mfma_f32_16x16x32_bf16 v[96:99], v[186:189], v[240:243], v[96:99]
	s_setprio 0
	s_setprio 1
	v_mfma_f32_16x16x32_bf16 v[60:63], v[190:193], v[212:215], v[60:63]
	v_mfma_f32_16x16x32_bf16 v[56:59], v[198:201], v[212:215], v[56:59]
	v_mfma_f32_16x16x32_bf16 v[52:55], v[190:193], v[220:223], v[52:55]
	v_mfma_f32_16x16x32_bf16 v[48:51], v[198:201], v[220:223], v[48:51]
	v_mfma_f32_16x16x32_bf16 v[44:47], v[190:193], v[228:231], v[44:47]
	v_mfma_f32_16x16x32_bf16 v[40:43], v[198:201], v[228:231], v[40:43]
	v_mfma_f32_16x16x32_bf16 v[36:39], v[190:193], v[236:239], v[36:39]
	v_mfma_f32_16x16x32_bf16 v[32:35], v[198:201], v[236:239], v[32:35]
	v_mfma_f32_16x16x32_bf16 v[60:63], v[194:197], v[216:219], v[60:63]
	v_mfma_f32_16x16x32_bf16 v[56:59], v[208:211], v[216:219], v[56:59]
	v_mfma_f32_16x16x32_bf16 v[52:55], v[194:197], v[224:227], v[52:55]
	v_mfma_f32_16x16x32_bf16 v[48:51], v[208:211], v[224:227], v[48:51]
	v_mfma_f32_16x16x32_bf16 v[44:47], v[194:197], v[232:235], v[44:47]
	v_mfma_f32_16x16x32_bf16 v[40:43], v[208:211], v[232:235], v[40:43]
	v_mfma_f32_16x16x32_bf16 v[36:39], v[194:197], v[240:243], v[36:39]
	v_mfma_f32_16x16x32_bf16 v[32:35], v[208:211], v[240:243], v[32:35]
	s_setprio 0
	s_barrier
; #define PG8_STAGE(bufoff, gbase, voff) do { _Pragma("unroll") for (int _i = 0; _i < 2; ++_i) \
;         __builtin_amdgcn_global_load_lds((const unsigned*)((const char*)(gbase) + (voff)[_i]), (PG8_LAS unsigned*)(lds + (bufoff) + ldsw + _i * 8192), 16, 0, 0); } while (0)
; #define PG8_LDA(dst, b, h) do { _Pragma("unroll") for (int m = 0; m < 4; ++m) _Pragma("unroll") for (int k = 0; k < 2; ++k) dst[m][k] = *(const PG8_LAS bf16x8*)(lds + PG8_SA(b, h) + aoff + m * 2048 + k * 1024); } while (0)
; #define PG8_MMA(ai, bj, At, Bt) do { __builtin_amdgcn_s_setprio(1); _Pragma("unroll") for (int m = 0; m < 4; ++m) _Pragma("unroll") for (int n = 0; n < 2; ++n) _Pragma("unroll") for (int k = 0; k < 2; ++k) \
;         acc[ai][bj][m][n] = __builtin_amdgcn_mfma_f32_16x16x32_bf16(Bt[n][k], At[m][k], acc[ai][bj][m][n], 0, 0, 0); __builtin_amdgcn_s_setprio(0); } while (0)
; #define PG8_WAIT_V(n) asm volatile("s_waitcnt vmcnt(" #n ")" ::: "memory")
; #define PG8_WAIT_L(n) asm volatile("s_waitcnt lgkmcnt(" #n ")" ::: "memory")
; #define PG8_BAR __builtin_amdgcn_s_barrier()
; #define PG8_SCHED __builtin_amdgcn_sched_barrier(0)
; template <class Epi, class Sched, bool ALIGN_EPI = false, bool SP2 = false>
; __device__ __forceinline__ void gemm_phase(PG8_LAS unsigned char* lds, const Gemm g, const Sched& S, const Epi& E) {
;     ...
;         for (int t = 0; t < nt; t += 2) {
;             const bool last = (t == nt - 2);
;             const char* a1 = cA + (size_t)(t + 1) * kstep;
;             const char* a2 = last ? nA : cA + (size_t)(t + 2) * kstep; const char* b2 = last ? nB : cB + (size_t)(t + 2) * kstep;
;     ...
;             PG8_LDA(At, 1, 1); PG8_STAGE(PG8_SB(1, 0), b3, voffB); PG8_STAGE(PG8_SB(1, 1), b3 + hstep, voffB); PG8_STAGE(PG8_SA(1, 0), a3, voffA);
;             PG8_WAIT_V(8); PG8_WAIT_L(0); PG8_BAR; PG8_MMA(1, 0, At, B0); PG8_MMA(1, 1, At, B1); PG8_BAR; PG8_SCHED;
	s_add_i32 s3, s3, s75
	v_lshl_add_u64 v[178:179], v[178:179], 0, s[10:11]
	s_mov_b32 m0, s3
	ds_read_b128 v[212:215], v164 offset:49152
	ds_read_b128 v[216:219], v164 offset:50176
	ds_read_b128 v[220:223], v164 offset:51200
	ds_read_b128 v[224:227], v164 offset:52224
	ds_read_b128 v[228:231], v164 offset:53248
	ds_read_b128 v[232:235], v164 offset:54272
	ds_read_b128 v[236:239], v164 offset:55296
	ds_read_b128 v[240:243], v164 offset:56320
	global_load_lds_dwordx4 v[178:179], off
	s_add_i32 m0, s3, 0x2000
	s_add_u32 s14, s62, 0x40080
	v_lshl_add_u64 v[178:179], v[202:203], 0, s[10:11]
	s_addc_u32 s15, s63, 0
	s_add_i32 s3, s33, s75
	global_load_lds_dwordx4 v[178:179], off
	v_lshl_add_u64 v[178:179], s[14:15], 0, v[130:131]
	s_mov_b32 m0, s3
	s_nop 0
	global_load_lds_dwordx4 v[178:179], off
	v_lshl_add_u64 v[178:179], s[14:15], 0, v[134:135]
	s_add_i32 m0, s3, 0x2000
	s_nop 0
	global_load_lds_dwordx4 v[178:179], off
	s_waitcnt vmcnt(6)
	s_waitcnt lgkmcnt(0)
	s_barrier
	s_setprio 1
	s_waitcnt lgkmcnt(0)
	v_mfma_f32_16x16x32_bf16 v[92:95], v[170:173], v[212:215], v[92:95]
	v_mfma_f32_16x16x32_bf16 v[88:91], v[182:185], v[212:215], v[88:91]
	v_mfma_f32_16x16x32_bf16 v[84:87], v[170:173], v[220:223], v[84:87]
	v_mfma_f32_16x16x32_bf16 v[80:83], v[182:185], v[220:223], v[80:83]
	v_mfma_f32_16x16x32_bf16 v[76:79], v[170:173], v[228:231], v[76:79]
	v_mfma_f32_16x16x32_bf16 v[72:75], v[182:185], v[228:231], v[72:75]
	v_lshl_add_u64 v[178:179], v[244:245], 0, s[10:11]
	s_mov_b32 m0, s88
	s_nop 0
	global_load_lds_dwordx4 v[178:179], off
	v_mfma_f32_16x16x32_bf16 v[68:71], v[170:173], v[236:239], v[68:71]
	v_mfma_f32_16x16x32_bf16 v[64:67], v[182:185], v[236:239], v[64:67]
	v_mfma_f32_16x16x32_bf16 v[92:95], v[174:177], v[216:219], v[92:95]
	v_mfma_f32_16x16x32_bf16 v[88:91], v[186:189], v[216:219], v[88:91]
	v_mfma_f32_16x16x32_bf16 v[84:87], v[174:177], v[224:227], v[84:87]
	v_mfma_f32_16x16x32_bf16 v[80:83], v[186:189], v[224:227], v[80:83]
	v_mfma_f32_16x16x32_bf16 v[76:79], v[174:177], v[232:235], v[76:79]
	v_mfma_f32_16x16x32_bf16 v[72:75], v[186:189], v[232:235], v[72:75]
	v_mfma_f32_16x16x32_bf16 v[68:71], v[174:177], v[240:243], v[68:71]
	v_mfma_f32_16x16x32_bf16 v[64:67], v[186:189], v[240:243], v[64:67]
	s_setprio 0
	s_setprio 1
	v_mfma_f32_16x16x32_bf16 v[28:31], v[190:193], v[212:215], v[28:31]
	v_mfma_f32_16x16x32_bf16 v[24:27], v[198:201], v[212:215], v[24:27]
	v_lshl_add_u64 v[178:179], v[246:247], 0, s[10:11]
	s_mov_b32 m0, s89
	s_nop 0
	global_load_lds_dwordx4 v[178:179], off
	v_mfma_f32_16x16x32_bf16 v[20:23], v[190:193], v[220:223], v[20:23]
	v_mfma_f32_16x16x32_bf16 v[16:19], v[198:201], v[220:223], v[16:19]
	v_mfma_f32_16x16x32_bf16 v[12:15], v[190:193], v[228:231], v[12:15]
	v_mfma_f32_16x16x32_bf16 v[8:11], v[198:201], v[228:231], v[8:11]
	v_mfma_f32_16x16x32_bf16 v[4:7], v[190:193], v[236:239], v[4:7]
	v_mfma_f32_16x16x32_bf16 v[0:3], v[198:201], v[236:239], v[0:3]
	v_mfma_f32_16x16x32_bf16 v[28:31], v[194:197], v[216:219], v[28:31]
	v_mfma_f32_16x16x32_bf16 v[24:27], v[208:211], v[216:219], v[24:27]
	v_mfma_f32_16x16x32_bf16 v[20:23], v[194:197], v[224:227], v[20:23]
	v_mfma_f32_16x16x32_bf16 v[16:19], v[208:211], v[224:227], v[16:19]
	v_mfma_f32_16x16x32_bf16 v[12:15], v[194:197], v[232:235], v[12:15]
	v_mfma_f32_16x16x32_bf16 v[8:11], v[208:211], v[232:235], v[8:11]
	v_mfma_f32_16x16x32_bf16 v[4:7], v[194:197], v[240:243], v[4:7]
	v_mfma_f32_16x16x32_bf16 v[0:3], v[208:211], v[240:243], v[0:3]
	s_setprio 0
	s_barrier
	s_add_i32 s97, s97, 2
	s_add_u32 s60, s60, 0x100
	s_addc_u32 s61, s61, 0
	s_add_u32 s95, s95, 0x100
	s_addc_u32 s96, s96, 0
	s_cmp_lt_u32 s97, 14
	s_cbranch_scc1 .LBB0_495
	s_andn2_b64 vcc, exec, s[40:41]
	s_cbranch_vccnz .LBB0_498
	s_barrier

; #define PG8_STAGE(bufoff, gbase, voff) do { _Pragma("unroll") for (int _i = 0; _i < 2; ++_i) \
;         __builtin_amdgcn_global_load_lds((const unsigned*)((const char*)(gbase) + (voff)[_i]), (PG8_LAS unsigned*)(lds + (bufoff) + ldsw + _i * 8192), 16, 0, 0); } while (0)
; #define PG8_LDA(dst, b, h) do { _Pragma("unroll") for (int m = 0; m < 4; ++m) _Pragma("unroll") for (int k = 0; k < 2; ++k) dst[m][k] = *(const PG8_LAS bf16x8*)(lds + PG8_SA(b, h) + aoff + m * 2048 + k * 1024); } while (0)
; #define PG8_LDB(dst, b, h) do { _Pragma("unroll") for (int n = 0; n < 2; ++n) _Pragma("unroll") for (int k = 0; k < 2; ++k) dst[n][k] = *(const PG8_LAS bf16x8*)(lds + PG8_SB(b, h) + boff + n * 2048 + k * 1024); } while (0)
; #define PG8_MMA(ai, bj, At, Bt) do { __builtin_amdgcn_s_setprio(1); _Pragma("unroll") for (int m = 0; m < 4; ++m) _Pragma("unroll") for (int n = 0; n < 2; ++n) _Pragma("unroll") for (int k = 0; k < 2; ++k) \
;         acc[ai][bj][m][n] = __builtin_amdgcn_mfma_f32_16x16x32_bf16(Bt[n][k], At[m][k], acc[ai][bj][m][n], 0, 0, 0); __builtin_amdgcn_s_setprio(0); } while (0)
; #define PG8_WAIT_V(n) asm volatile("s_waitcnt vmcnt(" #n ")" ::: "memory")
; #define PG8_WAIT_L(n) asm volatile("s_waitcnt lgkmcnt(" #n ")" ::: "memory")
; #define PG8_BAR __builtin_amdgcn_s_barrier()
; #define PG8_SCHED __builtin_amdgcn_sched_barrier(0)
; template <class Epi, class Sched, bool ALIGN_EPI = false, bool SP2 = false>
; __device__ __forceinline__ void gemm_phase(PG8_LAS unsigned char* lds, const Gemm g, const Sched& S, const Epi& E) {
;     ...
;             PG8_LDB(B0, 0, 0); PG8_LDB(B1, 0, 1); PG8_SCHED; PG8_LDA(At, 0, 0); PG8_STAGE(PG8_SA(1, 1), a1 + hstep, voffA);
;             PG8_WAIT_V(8); PG8_WAIT_L(0); PG8_BAR; PG8_MMA(0, 0, At, B0); PG8_MMA(0, 1, At, B1); PG8_BAR; PG8_SCHED;
;             PG8_LDA(At, 0, 1); PG8_STAGE(PG8_SB(0, 0), b2, voffB); PG8_STAGE(PG8_SB(0, 1), b2 + hstep, voffB); PG8_STAGE(PG8_SA(0, 0), a2, voffA);
;             PG8_WAIT_V(8); PG8_WAIT_L(0); PG8_BAR; PG8_MMA(1, 0, At, B0); PG8_MMA(1, 1, At, B1); PG8_BAR; PG8_SCHED;
;     ...
; #pragma unroll
;         for (int a = 0; a < 2; ++a)
; #pragma unroll
;             for (int b = 0; b < 2; ++b)
; #pragma unroll
;                 for (int m = 0; m < 4; ++m)
; #pragma unroll
;                     for (int n = 0; n < 2; ++n) acc[a][b][m][n] = (f32x4){0.f, 0.f, 0.f, 0.f};
;         cur = nxt; cA = nA; cB = nB; ++ui;
.LBB0_649:
	s_ashr_i32 s51, s50, 31
	s_lshl_b64 s[14:15], s[50:51], 19
	s_add_u32 s52, s40, s14
	s_addc_u32 s53, s41, s15
	s_and_b64 s[14:15], s[8:9], exec
	s_cselect_b32 s51, s53, s61
	s_cselect_b32 s57, s52, s60
	s_ashr_i32 s49, s48, 31
	s_lshl_b64 s[14:15], s[48:49], 19
	s_add_u32 s54, s82, s14
	s_addc_u32 s55, s83, s15
	s_and_b64 s[14:15], s[8:9], exec
	s_cselect_b32 s49, s55, s63
	s_cselect_b32 s89, s54, s62
	s_add_u32 s60, s60, 0x40080
	s_addc_u32 s61, s61, 0
	s_add_u32 s90, s62, 0x100
	s_addc_u32 s91, s63, 0
	s_mov_b32 s92, -2
	s_waitcnt lgkmcnt(0)
	s_waitcnt vmcnt(0)
	ds_read_b128 v[148:151], v155
	ds_read_b128 v[160:163], v155 offset:1024
	ds_read_b128 v[164:167], v155 offset:2048
	ds_read_b128 v[168:171], v155 offset:3072
	ds_read_b128 v[172:175], v156
	ds_read_b128 v[176:179], v156 offset:1024
	ds_read_b128 v[182:185], v156 offset:2048
	ds_read_b128 v[186:189], v156 offset:3072
	s_add_u32 s3, s60, 0xfffc0080
	s_addc_u32 s14, s61, -1
	s_cmp_eq_u32 s92, 12
	s_cselect_b32 s65, s51, s14
	s_cselect_b32 s64, s57, s3
	s_cselect_b32 s63, s49, s91
	s_cselect_b32 s62, s89, s90
	v_lshl_add_u64 v[202:203], s[60:61], 0, v[140:141]
	s_add_i32 m0, s43, 0xc000
	ds_read_b128 v[190:193], v157
	ds_read_b128 v[194:197], v157 offset:1024
	ds_read_b128 v[198:201], v157 offset:2048
	ds_read_b128 v[208:211], v157 offset:3072
	ds_read_b128 v[212:215], v157 offset:4096
	ds_read_b128 v[216:219], v157 offset:5120
	ds_read_b128 v[220:223], v157 offset:6144
	ds_read_b128 v[224:227], v157 offset:7168
	global_load_lds_dwordx4 v[202:203], off
	v_lshl_add_u64 v[202:203], s[60:61], 0, v[142:143]
	s_add_i32 m0, s43, 0xe000
	s_nop 0
	global_load_lds_dwordx4 v[202:203], off
	s_waitcnt vmcnt(8)
	s_waitcnt lgkmcnt(0)
	s_barrier
	s_setprio 1
	s_waitcnt lgkmcnt(0)
	v_mfma_f32_16x16x32_bf16 v[124:127], v[148:151], v[190:193], 0
	v_mfma_f32_16x16x32_bf16 v[120:123], v[164:167], v[190:193], 0
	v_mfma_f32_16x16x32_bf16 v[108:111], v[148:151], v[198:201], 0
	v_mfma_f32_16x16x32_bf16 v[104:107], v[164:167], v[198:201], 0
	v_mfma_f32_16x16x32_bf16 v[92:95], v[148:151], v[212:215], 0
	v_mfma_f32_16x16x32_bf16 v[88:91], v[164:167], v[212:215], 0
	v_mfma_f32_16x16x32_bf16 v[76:79], v[148:151], v[220:223], 0
	v_mfma_f32_16x16x32_bf16 v[72:75], v[164:167], v[220:223], 0
	v_mfma_f32_16x16x32_bf16 v[124:127], v[160:163], v[194:197], v[124:127]
	v_mfma_f32_16x16x32_bf16 v[120:123], v[168:171], v[194:197], v[120:123]
	v_mfma_f32_16x16x32_bf16 v[108:111], v[160:163], v[208:211], v[108:111]
	v_mfma_f32_16x16x32_bf16 v[104:107], v[168:171], v[208:211], v[104:107]
	v_mfma_f32_16x16x32_bf16 v[92:95], v[160:163], v[216:219], v[92:95]
	v_mfma_f32_16x16x32_bf16 v[88:91], v[168:171], v[216:219], v[88:91]
	v_mfma_f32_16x16x32_bf16 v[76:79], v[160:163], v[224:227], v[76:79]
	v_mfma_f32_16x16x32_bf16 v[72:75], v[168:171], v[224:227], v[72:75]
	s_setprio 0
	s_setprio 1
	v_mfma_f32_16x16x32_bf16 v[116:119], v[172:175], v[190:193], 0
	v_mfma_f32_16x16x32_bf16 v[112:115], v[182:185], v[190:193], 0
	v_mfma_f32_16x16x32_bf16 v[100:103], v[172:175], v[198:201], 0
	v_mfma_f32_16x16x32_bf16 v[96:99], v[182:185], v[198:201], 0
	v_mfma_f32_16x16x32_bf16 v[84:87], v[172:175], v[212:215], 0
	v_mfma_f32_16x16x32_bf16 v[80:83], v[182:185], v[212:215], 0
	v_mfma_f32_16x16x32_bf16 v[68:71], v[172:175], v[220:223], 0
	v_mfma_f32_16x16x32_bf16 v[64:67], v[182:185], v[220:223], 0
	v_mfma_f32_16x16x32_bf16 v[116:119], v[176:179], v[194:197], v[116:119]
	v_mfma_f32_16x16x32_bf16 v[112:115], v[186:189], v[194:197], v[112:115]
	v_mfma_f32_16x16x32_bf16 v[100:103], v[176:179], v[208:211], v[100:103]
	v_mfma_f32_16x16x32_bf16 v[96:99], v[186:189], v[208:211], v[96:99]
	v_mfma_f32_16x16x32_bf16 v[84:87], v[176:179], v[216:219], v[84:87]
	v_mfma_f32_16x16x32_bf16 v[80:83], v[186:189], v[216:219], v[80:83]
	v_mfma_f32_16x16x32_bf16 v[68:71], v[176:179], v[224:227], v[68:71]
	v_mfma_f32_16x16x32_bf16 v[64:67], v[186:189], v[224:227], v[64:67]
	s_setprio 0
	s_barrier
	s_add_i32 s3, s85, s34
	v_lshl_add_u64 v[202:203], s[62:63], 0, v[134:135]
	s_mov_b32 m0, s3
	ds_read_b128 v[190:193], v157 offset:16384
	ds_read_b128 v[194:197], v157 offset:17408
	ds_read_b128 v[198:201], v157 offset:18432
	ds_read_b128 v[208:211], v157 offset:19456
	ds_read_b128 v[212:215], v157 offset:20480
	ds_read_b128 v[216:219], v157 offset:21504
	ds_read_b128 v[220:223], v157 offset:22528
	ds_read_b128 v[224:227], v157 offset:23552
	global_load_lds_dwordx4 v[202:203], off
	s_add_i32 m0, s3, 0x2000
	s_add_u32 s14, s62, 0x40000
	v_lshl_add_u64 v[228:229], s[62:63], 0, v[138:139]
	s_addc_u32 s15, s63, 0
	s_add_i32 s3, s86, s34
	global_load_lds_dwordx4 v[228:229], off
	v_lshl_add_u64 v[230:231], s[14:15], 0, v[134:135]
	s_mov_b32 m0, s3
	v_lshl_add_u64 v[232:233], s[64:65], 0, v[136:137]
	global_load_lds_dwordx4 v[230:231], off
	v_lshl_add_u64 v[230:231], s[14:15], 0, v[138:139]
	s_add_i32 m0, s3, 0x2000
	s_nop 0
	global_load_lds_dwordx4 v[230:231], off
	s_waitcnt vmcnt(6)
	s_waitcnt lgkmcnt(0)
	s_barrier
; #define PG8_STAGE(bufoff, gbase, voff) do { _Pragma("unroll") for (int _i = 0; _i < 2; ++_i) \
;         __builtin_amdgcn_global_load_lds((const unsigned*)((const char*)(gbase) + (voff)[_i]), (PG8_LAS unsigned*)(lds + (bufoff) + ldsw + _i * 8192), 16, 0, 0); } while (0)
; #define PG8_LDA(dst, b, h) do { _Pragma("unroll") for (int m = 0; m < 4; ++m) _Pragma("unroll") for (int k = 0; k < 2; ++k) dst[m][k] = *(const PG8_LAS bf16x8*)(lds + PG8_SA(b, h) + aoff + m * 2048 + k * 1024); } while (0)
; #define PG8_LDB(dst, b, h) do { _Pragma("unroll") for (int n = 0; n < 2; ++n) _Pragma("unroll") for (int k = 0; k < 2; ++k) dst[n][k] = *(const PG8_LAS bf16x8*)(lds + PG8_SB(b, h) + boff + n * 2048 + k * 1024); } while (0)
; #define PG8_MMA(ai, bj, At, Bt) do { __builtin_amdgcn_s_setprio(1); _Pragma("unroll") for (int m = 0; m < 4; ++m) _Pragma("unroll") for (int n = 0; n < 2; ++n) _Pragma("unroll") for (int k = 0; k < 2; ++k) \
;         acc[ai][bj][m][n] = __builtin_amdgcn_mfma_f32_16x16x32_bf16(Bt[n][k], At[m][k], acc[ai][bj][m][n], 0, 0, 0); __builtin_amdgcn_s_setprio(0); } while (0)
; #define PG8_WAIT_V(n) asm volatile("s_waitcnt vmcnt(" #n ")" ::: "memory")
; #define PG8_WAIT_L(n) asm volatile("s_waitcnt lgkmcnt(" #n ")" ::: "memory")
; #define PG8_BAR __builtin_amdgcn_s_barrier()
; #define PG8_SCHED __builtin_amdgcn_sched_barrier(0)
; template <class Epi, class Sched, bool ALIGN_EPI = false, bool SP2 = false>
; __device__ __forceinline__ void gemm_phase(PG8_LAS unsigned char* lds, const Gemm g, const Sched& S, const Epi& E) {
;     ...
;             PG8_WAIT_V(8); PG8_WAIT_L(0); PG8_BAR; PG8_MMA(1, 0, At, B0); PG8_MMA(1, 1, At, B1); PG8_BAR; PG8_SCHED;
;             PG8_LDB(B0, 1, 0); PG8_LDB(B1, 1, 1); PG8_SCHED; PG8_LDA(At, 1, 0); PG8_STAGE(PG8_SA(0, 1), a2 + hstep, voffA);
;             PG8_WAIT_V(8); PG8_WAIT_L(0); PG8_BAR; PG8_MMA(0, 0, At, B0); PG8_MMA(0, 1, At, B1); PG8_BAR; PG8_SCHED;
	s_setprio 1
	s_waitcnt lgkmcnt(0)
	v_mfma_f32_16x16x32_bf16 v[60:63], v[148:151], v[190:193], 0
	v_mfma_f32_16x16x32_bf16 v[56:59], v[164:167], v[190:193], 0
	v_mfma_f32_16x16x32_bf16 v[44:47], v[148:151], v[198:201], 0
	v_mfma_f32_16x16x32_bf16 v[40:43], v[164:167], v[198:201], 0
	v_mfma_f32_16x16x32_bf16 v[28:31], v[148:151], v[212:215], 0
	v_mfma_f32_16x16x32_bf16 v[24:27], v[164:167], v[212:215], 0
	v_lshl_add_u64 v[230:231], s[64:65], 0, v[132:133]
	s_mov_b32 m0, s43
	s_nop 0
	global_load_lds_dwordx4 v[230:231], off
	v_mfma_f32_16x16x32_bf16 v[12:15], v[148:151], v[220:223], 0
	v_mfma_f32_16x16x32_bf16 v[8:11], v[164:167], v[220:223], 0
	v_mfma_f32_16x16x32_bf16 v[60:63], v[160:163], v[194:197], v[60:63]
	v_mfma_f32_16x16x32_bf16 v[56:59], v[168:171], v[194:197], v[56:59]
	v_mfma_f32_16x16x32_bf16 v[44:47], v[160:163], v[208:211], v[44:47]
	v_mfma_f32_16x16x32_bf16 v[40:43], v[168:171], v[208:211], v[40:43]
	v_mfma_f32_16x16x32_bf16 v[28:31], v[160:163], v[216:219], v[28:31]
	v_mfma_f32_16x16x32_bf16 v[24:27], v[168:171], v[216:219], v[24:27]
	v_mfma_f32_16x16x32_bf16 v[12:15], v[160:163], v[224:227], v[12:15]
	v_mfma_f32_16x16x32_bf16 v[8:11], v[168:171], v[224:227], v[8:11]
	s_setprio 0
	s_setprio 1
	v_mfma_f32_16x16x32_bf16 v[52:55], v[172:175], v[190:193], 0
	v_mfma_f32_16x16x32_bf16 v[48:51], v[182:185], v[190:193], 0
	s_mov_b32 m0, s59
	s_nop 0
	global_load_lds_dwordx4 v[232:233], off
	v_mfma_f32_16x16x32_bf16 v[36:39], v[172:175], v[198:201], 0
	v_mfma_f32_16x16x32_bf16 v[32:35], v[182:185], v[198:201], 0
	v_mfma_f32_16x16x32_bf16 v[20:23], v[172:175], v[212:215], 0
	v_mfma_f32_16x16x32_bf16 v[16:19], v[182:185], v[212:215], 0
	v_mfma_f32_16x16x32_bf16 v[4:7], v[172:175], v[220:223], 0
	v_mfma_f32_16x16x32_bf16 v[0:3], v[182:185], v[220:223], 0
	v_mfma_f32_16x16x32_bf16 v[52:55], v[176:179], v[194:197], v[52:55]
	v_mfma_f32_16x16x32_bf16 v[48:51], v[186:189], v[194:197], v[48:51]
	v_mfma_f32_16x16x32_bf16 v[36:39], v[176:179], v[208:211], v[36:39]
	v_mfma_f32_16x16x32_bf16 v[32:35], v[186:189], v[208:211], v[32:35]
	v_mfma_f32_16x16x32_bf16 v[20:23], v[176:179], v[216:219], v[20:23]
	v_mfma_f32_16x16x32_bf16 v[16:19], v[186:189], v[216:219], v[16:19]
	v_mfma_f32_16x16x32_bf16 v[4:7], v[176:179], v[224:227], v[4:7]
	v_mfma_f32_16x16x32_bf16 v[0:3], v[186:189], v[224:227], v[0:3]
	s_setprio 0
	s_barrier
	s_add_i32 s3, 0, 0x18000
	v_add_u32_e32 v159, s3, v131
	s_add_i32 s33, 0, 0x1c000
	ds_read_b128 v[148:151], v159
	ds_read_b128 v[160:163], v159 offset:1024
	ds_read_b128 v[164:167], v159 offset:2048
	ds_read_b128 v[168:171], v159 offset:3072
	v_add_u32_e32 v159, s33, v131
	ds_read_b128 v[172:175], v159
	ds_read_b128 v[176:179], v159 offset:1024
	ds_read_b128 v[182:185], v159 offset:2048
	ds_read_b128 v[186:189], v159 offset:3072
	s_add_u32 s14, s64, 0x40000
	s_addc_u32 s15, s65, 0
	s_mov_b32 m0, s66
	v_lshl_add_u64 v[234:235], s[14:15], 0, v[132:133]
	ds_read_b128 v[190:193], v157 offset:32768
	ds_read_b128 v[194:197], v157 offset:33792
	ds_read_b128 v[198:201], v157 offset:34816
	ds_read_b128 v[208:211], v157 offset:35840
	ds_read_b128 v[212:215], v157 offset:36864
	ds_read_b128 v[216:219], v157 offset:37888
	ds_read_b128 v[220:223], v157 offset:38912
	ds_read_b128 v[224:227], v157 offset:39936
	global_load_lds_dwordx4 v[234:235], off
	v_lshl_add_u64 v[234:235], s[14:15], 0, v[136:137]
	s_mov_b32 m0, s67
	s_nop 0
	global_load_lds_dwordx4 v[234:235], off
	s_waitcnt vmcnt(8)
	s_waitcnt lgkmcnt(0)
	s_barrier
	s_setprio 1
	s_waitcnt lgkmcnt(0)
	v_mfma_f32_16x16x32_bf16 v[124:127], v[148:151], v[190:193], v[124:127]
	v_mfma_f32_16x16x32_bf16 v[120:123], v[164:167], v[190:193], v[120:123]
	v_mfma_f32_16x16x32_bf16 v[108:111], v[148:151], v[198:201], v[108:111]
	v_mfma_f32_16x16x32_bf16 v[104:107], v[164:167], v[198:201], v[104:107]
	v_mfma_f32_16x16x32_bf16 v[92:95], v[148:151], v[212:215], v[92:95]
	v_mfma_f32_16x16x32_bf16 v[88:91], v[164:167], v[212:215], v[88:91]
	v_mfma_f32_16x16x32_bf16 v[76:79], v[148:151], v[220:223], v[76:79]
	v_mfma_f32_16x16x32_bf16 v[72:75], v[164:167], v[220:223], v[72:75]
	v_mfma_f32_16x16x32_bf16 v[124:127], v[160:163], v[194:197], v[124:127]
	v_mfma_f32_16x16x32_bf16 v[120:123], v[168:171], v[194:197], v[120:123]
	v_mfma_f32_16x16x32_bf16 v[108:111], v[160:163], v[208:211], v[108:111]
	v_mfma_f32_16x16x32_bf16 v[104:107], v[168:171], v[208:211], v[104:107]
	v_mfma_f32_16x16x32_bf16 v[92:95], v[160:163], v[216:219], v[92:95]
	v_mfma_f32_16x16x32_bf16 v[88:91], v[168:171], v[216:219], v[88:91]
	v_mfma_f32_16x16x32_bf16 v[76:79], v[160:163], v[224:227], v[76:79]
	v_mfma_f32_16x16x32_bf16 v[72:75], v[168:171], v[224:227], v[72:75]
	s_setprio 0
	s_setprio 1
	v_mfma_f32_16x16x32_bf16 v[116:119], v[172:175], v[190:193], v[116:119]
	v_mfma_f32_16x16x32_bf16 v[112:115], v[182:185], v[190:193], v[112:115]
	v_mfma_f32_16x16x32_bf16 v[100:103], v[172:175], v[198:201], v[100:103]
	v_mfma_f32_16x16x32_bf16 v[96:99], v[182:185], v[198:201], v[96:99]
	v_mfma_f32_16x16x32_bf16 v[84:87], v[172:175], v[212:215], v[84:87]
	v_mfma_f32_16x16x32_bf16 v[80:83], v[182:185], v[212:215], v[80:83]
	v_mfma_f32_16x16x32_bf16 v[68:71], v[172:175], v[220:223], v[68:71]
	v_mfma_f32_16x16x32_bf16 v[64:67], v[182:185], v[220:223], v[64:67]
	v_mfma_f32_16x16x32_bf16 v[116:119], v[176:179], v[194:197], v[116:119]
	v_mfma_f32_16x16x32_bf16 v[112:115], v[186:189], v[194:197], v[112:115]
	v_mfma_f32_16x16x32_bf16 v[100:103], v[176:179], v[208:211], v[100:103]
	v_mfma_f32_16x16x32_bf16 v[96:99], v[186:189], v[208:211], v[96:99]
	v_mfma_f32_16x16x32_bf16 v[84:87], v[176:179], v[216:219], v[84:87]
	v_mfma_f32_16x16x32_bf16 v[80:83], v[186:189], v[216:219], v[80:83]
	v_mfma_f32_16x16x32_bf16 v[68:71], v[176:179], v[224:227], v[68:71]
	v_mfma_f32_16x16x32_bf16 v[64:67], v[186:189], v[224:227], v[64:67]
	s_setprio 0
	s_barrier
; #define PG8_STAGE(bufoff, gbase, voff) do { _Pragma("unroll") for (int _i = 0; _i < 2; ++_i) \
;         __builtin_amdgcn_global_load_lds((const unsigned*)((const char*)(gbase) + (voff)[_i]), (PG8_LAS unsigned*)(lds + (bufoff) + ldsw + _i * 8192), 16, 0, 0); } while (0)
; #define PG8_LDA(dst, b, h) do { _Pragma("unroll") for (int m = 0; m < 4; ++m) _Pragma("unroll") for (int k = 0; k < 2; ++k) dst[m][k] = *(const PG8_LAS bf16x8*)(lds + PG8_SA(b, h) + aoff + m * 2048 + k * 1024); } while (0)
; #define PG8_LDB(dst, b, h) do { _Pragma("unroll") for (int n = 0; n < 2; ++n) _Pragma("unroll") for (int k = 0; k < 2; ++k) dst[n][k] = *(const PG8_LAS bf16x8*)(lds + PG8_SB(b, h) + boff + n * 2048 + k * 1024); } while (0)
; #define PG8_MMA(ai, bj, At, Bt) do { __builtin_amdgcn_s_setprio(1); _Pragma("unroll") for (int m = 0; m < 4; ++m) _Pragma("unroll") for (int n = 0; n < 2; ++n) _Pragma("unroll") for (int k = 0; k < 2; ++k) \
;         acc[ai][bj][m][n] = __builtin_amdgcn_mfma_f32_16x16x32_bf16(Bt[n][k], At[m][k], acc[ai][bj][m][n], 0, 0, 0); __builtin_amdgcn_s_setprio(0); } while (0)
; #define PG8_WAIT_V(n) asm volatile("s_waitcnt vmcnt(" #n ")" ::: "memory")
; #define PG8_WAIT_L(n) asm volatile("s_waitcnt lgkmcnt(" #n ")" ::: "memory")
; #define PG8_BAR __builtin_amdgcn_s_barrier()
; #define PG8_SCHED __builtin_amdgcn_sched_barrier(0)
; template <class Epi, class Sched, bool ALIGN_EPI = false, bool SP2 = false>
; __device__ __forceinline__ void gemm_phase(PG8_LAS unsigned char* lds, const Gemm g, const Sched& S, const Epi& E) {
;     ...
;             PG8_LDB(B0, 0, 0); PG8_LDB(B1, 0, 1); PG8_SCHED; PG8_LDA(At, 0, 0); PG8_STAGE(PG8_SA(1, 1), a1 + hstep, voffA);
;             PG8_WAIT_V(8); PG8_WAIT_L(0); PG8_BAR; PG8_MMA(0, 0, At, B0); PG8_MMA(0, 1, At, B1); PG8_BAR; PG8_SCHED;
;     ...
;             PG8_LDA(At, 1, 1); PG8_STAGE(PG8_SB(1, 0), b3, voffB); PG8_STAGE(PG8_SB(1, 1), b3 + hstep, voffB); PG8_STAGE(PG8_SA(1, 0), a3, voffA);
;             PG8_WAIT_V(8); PG8_WAIT_L(0); PG8_BAR; PG8_MMA(1, 0, At, B0); PG8_MMA(1, 1, At, B1); PG8_BAR; PG8_SCHED;
	s_add_i32 s3, s3, s34
	v_lshl_add_u64 v[202:203], v[202:203], 0, s[38:39]
	s_mov_b32 m0, s3
	ds_read_b128 v[190:193], v157 offset:49152
	ds_read_b128 v[194:197], v157 offset:50176
	ds_read_b128 v[198:201], v157 offset:51200
	ds_read_b128 v[208:211], v157 offset:52224
	ds_read_b128 v[212:215], v157 offset:53248
	ds_read_b128 v[216:219], v157 offset:54272
	ds_read_b128 v[220:223], v157 offset:55296
	ds_read_b128 v[224:227], v157 offset:56320
	global_load_lds_dwordx4 v[202:203], off
	s_add_i32 m0, s3, 0x2000
	s_add_u32 s14, s62, 0x40080
	v_lshl_add_u64 v[202:203], v[228:229], 0, s[38:39]
	s_addc_u32 s15, s63, 0
	s_add_i32 s3, s33, s34
	global_load_lds_dwordx4 v[202:203], off
	v_lshl_add_u64 v[202:203], s[14:15], 0, v[134:135]
	s_mov_b32 m0, s3
	s_nop 0
	global_load_lds_dwordx4 v[202:203], off
	v_lshl_add_u64 v[202:203], s[14:15], 0, v[138:139]
	s_add_i32 m0, s3, 0x2000
	s_nop 0
	global_load_lds_dwordx4 v[202:203], off
	s_waitcnt vmcnt(6)
	s_waitcnt lgkmcnt(0)
	s_barrier
	s_setprio 1
	s_waitcnt lgkmcnt(0)
	v_mfma_f32_16x16x32_bf16 v[60:63], v[148:151], v[190:193], v[60:63]
	v_mfma_f32_16x16x32_bf16 v[56:59], v[164:167], v[190:193], v[56:59]
	v_mfma_f32_16x16x32_bf16 v[44:47], v[148:151], v[198:201], v[44:47]
	v_mfma_f32_16x16x32_bf16 v[40:43], v[164:167], v[198:201], v[40:43]
	v_mfma_f32_16x16x32_bf16 v[28:31], v[148:151], v[212:215], v[28:31]
	v_mfma_f32_16x16x32_bf16 v[24:27], v[164:167], v[212:215], v[24:27]
	v_lshl_add_u64 v[202:203], v[230:231], 0, s[38:39]
	s_mov_b32 m0, s75
	s_nop 0
	global_load_lds_dwordx4 v[202:203], off
	v_mfma_f32_16x16x32_bf16 v[12:15], v[148:151], v[220:223], v[12:15]
	v_mfma_f32_16x16x32_bf16 v[8:11], v[164:167], v[220:223], v[8:11]
	v_mfma_f32_16x16x32_bf16 v[60:63], v[160:163], v[194:197], v[60:63]
	v_mfma_f32_16x16x32_bf16 v[56:59], v[168:171], v[194:197], v[56:59]
	v_mfma_f32_16x16x32_bf16 v[44:47], v[160:163], v[208:211], v[44:47]
	v_mfma_f32_16x16x32_bf16 v[40:43], v[168:171], v[208:211], v[40:43]
	v_mfma_f32_16x16x32_bf16 v[28:31], v[160:163], v[216:219], v[28:31]
	v_mfma_f32_16x16x32_bf16 v[24:27], v[168:171], v[216:219], v[24:27]
	v_mfma_f32_16x16x32_bf16 v[12:15], v[160:163], v[224:227], v[12:15]
	v_mfma_f32_16x16x32_bf16 v[8:11], v[168:171], v[224:227], v[8:11]
	s_setprio 0
	s_setprio 1
	v_mfma_f32_16x16x32_bf16 v[52:55], v[172:175], v[190:193], v[52:55]
	v_mfma_f32_16x16x32_bf16 v[48:51], v[182:185], v[190:193], v[48:51]
	v_lshl_add_u64 v[202:203], v[232:233], 0, s[38:39]
	s_mov_b32 m0, s84
	s_nop 0
	global_load_lds_dwordx4 v[202:203], off
	v_mfma_f32_16x16x32_bf16 v[36:39], v[172:175], v[198:201], v[36:39]
	v_mfma_f32_16x16x32_bf16 v[32:35], v[182:185], v[198:201], v[32:35]
	v_mfma_f32_16x16x32_bf16 v[20:23], v[172:175], v[212:215], v[20:23]
	v_mfma_f32_16x16x32_bf16 v[16:19], v[182:185], v[212:215], v[16:19]
	v_mfma_f32_16x16x32_bf16 v[4:7], v[172:175], v[220:223], v[4:7]
	v_mfma_f32_16x16x32_bf16 v[0:3], v[182:185], v[220:223], v[0:3]
	v_mfma_f32_16x16x32_bf16 v[52:55], v[176:179], v[194:197], v[52:55]
	v_mfma_f32_16x16x32_bf16 v[48:51], v[186:189], v[194:197], v[48:51]
	v_mfma_f32_16x16x32_bf16 v[36:39], v[176:179], v[208:211], v[36:39]
	v_mfma_f32_16x16x32_bf16 v[32:35], v[186:189], v[208:211], v[32:35]
	v_mfma_f32_16x16x32_bf16 v[20:23], v[176:179], v[216:219], v[20:23]
	v_mfma_f32_16x16x32_bf16 v[16:19], v[186:189], v[216:219], v[16:19]
	v_mfma_f32_16x16x32_bf16 v[4:7], v[176:179], v[224:227], v[4:7]
	v_mfma_f32_16x16x32_bf16 v[0:3], v[186:189], v[224:227], v[0:3]
	s_setprio 0
	s_barrier
	s_add_i32 s92, s92, 2
	s_add_u32 s60, s60, 0x100
	s_addc_u32 s61, s61, 0
	s_add_u32 s90, s90, 0x100
	s_addc_u32 s91, s91, 0
.LBB0_650:
	ds_read_b128 v[148:151], v155
	ds_read_b128 v[160:163], v155 offset:1024
	ds_read_b128 v[164:167], v155 offset:2048
	ds_read_b128 v[168:171], v155 offset:3072
	ds_read_b128 v[172:175], v156
	ds_read_b128 v[176:179], v156 offset:1024
	ds_read_b128 v[182:185], v156 offset:2048
	ds_read_b128 v[186:189], v156 offset:3072
	s_add_u32 s3, s60, 0xfffc0080
	s_addc_u32 s14, s61, -1
	s_cmp_eq_u32 s92, 12
	s_cselect_b32 s65, s51, s14
	s_cselect_b32 s64, s57, s3
	s_cselect_b32 s63, s49, s91
	s_cselect_b32 s62, s89, s90
	v_lshl_add_u64 v[202:203], s[60:61], 0, v[140:141]
	s_add_i32 m0, s43, 0xc000
	ds_read_b128 v[190:193], v157
	ds_read_b128 v[194:197], v157 offset:1024
	ds_read_b128 v[198:201], v157 offset:2048
	ds_read_b128 v[208:211], v157 offset:3072
	ds_read_b128 v[212:215], v157 offset:4096
	ds_read_b128 v[216:219], v157 offset:5120
	ds_read_b128 v[220:223], v157 offset:6144
	ds_read_b128 v[224:227], v157 offset:7168
	global_load_lds_dwordx4 v[202:203], off
	v_lshl_add_u64 v[202:203], s[60:61], 0, v[142:143]
	s_add_i32 m0, s43, 0xe000
	s_nop 0
	global_load_lds_dwordx4 v[202:203], off
	s_waitcnt vmcnt(8)
	s_waitcnt lgkmcnt(0)
	s_barrier
; #define PG8_STAGE(bufoff, gbase, voff) do { _Pragma("unroll") for (int _i = 0; _i < 2; ++_i) \
;         __builtin_amdgcn_global_load_lds((const unsigned*)((const char*)(gbase) + (voff)[_i]), (PG8_LAS unsigned*)(lds + (bufoff) + ldsw + _i * 8192), 16, 0, 0); } while (0)
; #define PG8_LDA(dst, b, h) do { _Pragma("unroll") for (int m = 0; m < 4; ++m) _Pragma("unroll") for (int k = 0; k < 2; ++k) dst[m][k] = *(const PG8_LAS bf16x8*)(lds + PG8_SA(b, h) + aoff + m * 2048 + k * 1024); } while (0)
; #define PG8_MMA(ai, bj, At, Bt) do { __builtin_amdgcn_s_setprio(1); _Pragma("unroll") for (int m = 0; m < 4; ++m) _Pragma("unroll") for (int n = 0; n < 2; ++n) _Pragma("unroll") for (int k = 0; k < 2; ++k) \
;         acc[ai][bj][m][n] = __builtin_amdgcn_mfma_f32_16x16x32_bf16(Bt[n][k], At[m][k], acc[ai][bj][m][n], 0, 0, 0); __builtin_amdgcn_s_setprio(0); } while (0)
; #define PG8_WAIT_V(n) asm volatile("s_waitcnt vmcnt(" #n ")" ::: "memory")
; #define PG8_WAIT_L(n) asm volatile("s_waitcnt lgkmcnt(" #n ")" ::: "memory")
; #define PG8_BAR __builtin_amdgcn_s_barrier()
; #define PG8_SCHED __builtin_amdgcn_sched_barrier(0)
; template <class Epi, class Sched, bool ALIGN_EPI = false, bool SP2 = false>
; __device__ __forceinline__ void gemm_phase(PG8_LAS unsigned char* lds, const Gemm g, const Sched& S, const Epi& E) {
;     ...
;             PG8_WAIT_V(8); PG8_WAIT_L(0); PG8_BAR; PG8_MMA(0, 0, At, B0); PG8_MMA(0, 1, At, B1); PG8_BAR; PG8_SCHED;
;             PG8_LDA(At, 0, 1); PG8_STAGE(PG8_SB(0, 0), b2, voffB); PG8_STAGE(PG8_SB(0, 1), b2 + hstep, voffB); PG8_STAGE(PG8_SA(0, 0), a2, voffA);
;             PG8_WAIT_V(8); PG8_WAIT_L(0); PG8_BAR; PG8_MMA(1, 0, At, B0); PG8_MMA(1, 1, At, B1); PG8_BAR; PG8_SCHED;
	s_setprio 1
	s_waitcnt lgkmcnt(0)
	v_mfma_f32_16x16x32_bf16 v[124:127], v[148:151], v[190:193], v[124:127]
	v_mfma_f32_16x16x32_bf16 v[120:123], v[164:167], v[190:193], v[120:123]
	v_mfma_f32_16x16x32_bf16 v[108:111], v[148:151], v[198:201], v[108:111]
	v_mfma_f32_16x16x32_bf16 v[104:107], v[164:167], v[198:201], v[104:107]
	v_mfma_f32_16x16x32_bf16 v[92:95], v[148:151], v[212:215], v[92:95]
	v_mfma_f32_16x16x32_bf16 v[88:91], v[164:167], v[212:215], v[88:91]
	v_mfma_f32_16x16x32_bf16 v[76:79], v[148:151], v[220:223], v[76:79]
	v_mfma_f32_16x16x32_bf16 v[72:75], v[164:167], v[220:223], v[72:75]
	v_mfma_f32_16x16x32_bf16 v[124:127], v[160:163], v[194:197], v[124:127]
	v_mfma_f32_16x16x32_bf16 v[120:123], v[168:171], v[194:197], v[120:123]
	v_mfma_f32_16x16x32_bf16 v[108:111], v[160:163], v[208:211], v[108:111]
	v_mfma_f32_16x16x32_bf16 v[104:107], v[168:171], v[208:211], v[104:107]
	v_mfma_f32_16x16x32_bf16 v[92:95], v[160:163], v[216:219], v[92:95]
	v_mfma_f32_16x16x32_bf16 v[88:91], v[168:171], v[216:219], v[88:91]
	v_mfma_f32_16x16x32_bf16 v[76:79], v[160:163], v[224:227], v[76:79]
	v_mfma_f32_16x16x32_bf16 v[72:75], v[168:171], v[224:227], v[72:75]
	s_setprio 0
	s_setprio 1
	v_mfma_f32_16x16x32_bf16 v[116:119], v[172:175], v[190:193], v[116:119]
	v_mfma_f32_16x16x32_bf16 v[112:115], v[182:185], v[190:193], v[112:115]
	v_mfma_f32_16x16x32_bf16 v[100:103], v[172:175], v[198:201], v[100:103]
	v_mfma_f32_16x16x32_bf16 v[96:99], v[182:185], v[198:201], v[96:99]
	v_mfma_f32_16x16x32_bf16 v[84:87], v[172:175], v[212:215], v[84:87]
	v_mfma_f32_16x16x32_bf16 v[80:83], v[182:185], v[212:215], v[80:83]
	v_mfma_f32_16x16x32_bf16 v[68:71], v[172:175], v[220:223], v[68:71]
	v_mfma_f32_16x16x32_bf16 v[64:67], v[182:185], v[220:223], v[64:67]
	v_mfma_f32_16x16x32_bf16 v[116:119], v[176:179], v[194:197], v[116:119]
	v_mfma_f32_16x16x32_bf16 v[112:115], v[186:189], v[194:197], v[112:115]
	v_mfma_f32_16x16x32_bf16 v[100:103], v[176:179], v[208:211], v[100:103]
	v_mfma_f32_16x16x32_bf16 v[96:99], v[186:189], v[208:211], v[96:99]
	v_mfma_f32_16x16x32_bf16 v[84:87], v[176:179], v[216:219], v[84:87]
	v_mfma_f32_16x16x32_bf16 v[80:83], v[186:189], v[216:219], v[80:83]
	v_mfma_f32_16x16x32_bf16 v[68:71], v[176:179], v[224:227], v[68:71]
	v_mfma_f32_16x16x32_bf16 v[64:67], v[186:189], v[224:227], v[64:67]
	s_setprio 0
	s_barrier
	s_add_i32 s3, s85, s34
	v_lshl_add_u64 v[202:203], s[62:63], 0, v[134:135]
	s_mov_b32 m0, s3
	ds_read_b128 v[190:193], v157 offset:16384
	ds_read_b128 v[194:197], v157 offset:17408
	ds_read_b128 v[198:201], v157 offset:18432
	ds_read_b128 v[208:211], v157 offset:19456
	ds_read_b128 v[212:215], v157 offset:20480
	ds_read_b128 v[216:219], v157 offset:21504
	ds_read_b128 v[220:223], v157 offset:22528
	ds_read_b128 v[224:227], v157 offset:23552
	global_load_lds_dwordx4 v[202:203], off
	s_add_i32 m0, s3, 0x2000
	s_add_u32 s14, s62, 0x40000
	v_lshl_add_u64 v[228:229], s[62:63], 0, v[138:139]
	s_addc_u32 s15, s63, 0
	s_add_i32 s3, s86, s34
	global_load_lds_dwordx4 v[228:229], off
	v_lshl_add_u64 v[230:231], s[14:15], 0, v[134:135]
	s_mov_b32 m0, s3
	v_lshl_add_u64 v[232:233], s[64:65], 0, v[136:137]
	global_load_lds_dwordx4 v[230:231], off
	v_lshl_add_u64 v[230:231], s[14:15], 0, v[138:139]
	s_add_i32 m0, s3, 0x2000
	s_nop 0
	global_load_lds_dwordx4 v[230:231], off
	s_waitcnt vmcnt(6)
	s_waitcnt lgkmcnt(0)
	s_barrier
	s_setprio 1
	s_waitcnt lgkmcnt(0)
	v_mfma_f32_16x16x32_bf16 v[60:63], v[148:151], v[190:193], v[60:63]
	v_mfma_f32_16x16x32_bf16 v[56:59], v[164:167], v[190:193], v[56:59]
	v_mfma_f32_16x16x32_bf16 v[44:47], v[148:151], v[198:201], v[44:47]
	v_mfma_f32_16x16x32_bf16 v[40:43], v[164:167], v[198:201], v[40:43]
	v_mfma_f32_16x16x32_bf16 v[28:31], v[148:151], v[212:215], v[28:31]
	v_mfma_f32_16x16x32_bf16 v[24:27], v[164:167], v[212:215], v[24:27]
	v_lshl_add_u64 v[230:231], s[64:65], 0, v[132:133]
	s_mov_b32 m0, s43
	s_nop 0
	global_load_lds_dwordx4 v[230:231], off
	v_mfma_f32_16x16x32_bf16 v[12:15], v[148:151], v[220:223], v[12:15]
	v_mfma_f32_16x16x32_bf16 v[8:11], v[164:167], v[220:223], v[8:11]
	v_mfma_f32_16x16x32_bf16 v[60:63], v[160:163], v[194:197], v[60:63]
	v_mfma_f32_16x16x32_bf16 v[56:59], v[168:171], v[194:197], v[56:59]
	v_mfma_f32_16x16x32_bf16 v[44:47], v[160:163], v[208:211], v[44:47]
	v_mfma_f32_16x16x32_bf16 v[40:43], v[168:171], v[208:211], v[40:43]
	v_mfma_f32_16x16x32_bf16 v[28:31], v[160:163], v[216:219], v[28:31]
	v_mfma_f32_16x16x32_bf16 v[24:27], v[168:171], v[216:219], v[24:27]
	v_mfma_f32_16x16x32_bf16 v[12:15], v[160:163], v[224:227], v[12:15]
	v_mfma_f32_16x16x32_bf16 v[8:11], v[168:171], v[224:227], v[8:11]
	s_setprio 0
	s_setprio 1
	v_mfma_f32_16x16x32_bf16 v[52:55], v[172:175], v[190:193], v[52:55]
	v_mfma_f32_16x16x32_bf16 v[48:51], v[182:185], v[190:193], v[48:51]
	s_mov_b32 m0, s59
	s_nop 0
	global_load_lds_dwordx4 v[232:233], off
	v_mfma_f32_16x16x32_bf16 v[36:39], v[172:175], v[198:201], v[36:39]
	v_mfma_f32_16x16x32_bf16 v[32:35], v[182:185], v[198:201], v[32:35]
	v_mfma_f32_16x16x32_bf16 v[20:23], v[172:175], v[212:215], v[20:23]
	v_mfma_f32_16x16x32_bf16 v[16:19], v[182:185], v[212:215], v[16:19]
	v_mfma_f32_16x16x32_bf16 v[4:7], v[172:175], v[220:223], v[4:7]
	v_mfma_f32_16x16x32_bf16 v[0:3], v[182:185], v[220:223], v[0:3]
	v_mfma_f32_16x16x32_bf16 v[52:55], v[176:179], v[194:197], v[52:55]
	v_mfma_f32_16x16x32_bf16 v[48:51], v[186:189], v[194:197], v[48:51]
	v_mfma_f32_16x16x32_bf16 v[36:39], v[176:179], v[208:211], v[36:39]
	v_mfma_f32_16x16x32_bf16 v[32:35], v[186:189], v[208:211], v[32:35]
	v_mfma_f32_16x16x32_bf16 v[20:23], v[176:179], v[216:219], v[20:23]
	v_mfma_f32_16x16x32_bf16 v[16:19], v[186:189], v[216:219], v[16:19]
	v_mfma_f32_16x16x32_bf16 v[4:7], v[176:179], v[224:227], v[4:7]
	v_mfma_f32_16x16x32_bf16 v[0:3], v[186:189], v[224:227], v[0:3]
	s_setprio 0
	s_barrier
; #define PG8_STAGE(bufoff, gbase, voff) do { _Pragma("unroll") for (int _i = 0; _i < 2; ++_i) \
;         __builtin_amdgcn_global_load_lds((const unsigned*)((const char*)(gbase) + (voff)[_i]), (PG8_LAS unsigned*)(lds + (bufoff) + ldsw + _i * 8192), 16, 0, 0); } while (0)
; #define PG8_LDA(dst, b, h) do { _Pragma("unroll") for (int m = 0; m < 4; ++m) _Pragma("unroll") for (int k = 0; k < 2; ++k) dst[m][k] = *(const PG8_LAS bf16x8*)(lds + PG8_SA(b, h) + aoff + m * 2048 + k * 1024); } while (0)
; #define PG8_LDB(dst, b, h) do { _Pragma("unroll") for (int n = 0; n < 2; ++n) _Pragma("unroll") for (int k = 0; k < 2; ++k) dst[n][k] = *(const PG8_LAS bf16x8*)(lds + PG8_SB(b, h) + boff + n * 2048 + k * 1024); } while (0)
; #define PG8_MMA(ai, bj, At, Bt) do { __builtin_amdgcn_s_setprio(1); _Pragma("unroll") for (int m = 0; m < 4; ++m) _Pragma("unroll") for (int n = 0; n < 2; ++n) _Pragma("unroll") for (int k = 0; k < 2; ++k) \
;         acc[ai][bj][m][n] = __builtin_amdgcn_mfma_f32_16x16x32_bf16(Bt[n][k], At[m][k], acc[ai][bj][m][n], 0, 0, 0); __builtin_amdgcn_s_setprio(0); } while (0)
; #define PG8_WAIT_V(n) asm volatile("s_waitcnt vmcnt(" #n ")" ::: "memory")
; #define PG8_WAIT_L(n) asm volatile("s_waitcnt lgkmcnt(" #n ")" ::: "memory")
; #define PG8_BAR __builtin_amdgcn_s_barrier()
; #define PG8_SCHED __builtin_amdgcn_sched_barrier(0)
; template <class Epi, class Sched, bool ALIGN_EPI = false, bool SP2 = false>
; __device__ __forceinline__ void gemm_phase(PG8_LAS unsigned char* lds, const Gemm g, const Sched& S, const Epi& E) {
;     ...
;             PG8_LDB(B0, 1, 0); PG8_LDB(B1, 1, 1); PG8_SCHED; PG8_LDA(At, 1, 0); PG8_STAGE(PG8_SA(0, 1), a2 + hstep, voffA);
;             PG8_WAIT_V(8); PG8_WAIT_L(0); PG8_BAR; PG8_MMA(0, 0, At, B0); PG8_MMA(0, 1, At, B1); PG8_BAR; PG8_SCHED;
	s_add_i32 s3, 0, 0x18000
	v_add_u32_e32 v159, s3, v131
	s_add_i32 s33, 0, 0x1c000
	ds_read_b128 v[148:151], v159
	ds_read_b128 v[160:163], v159 offset:1024
	ds_read_b128 v[164:167], v159 offset:2048
	ds_read_b128 v[168:171], v159 offset:3072
	v_add_u32_e32 v159, s33, v131
	ds_read_b128 v[172:175], v159
	ds_read_b128 v[176:179], v159 offset:1024
	ds_read_b128 v[182:185], v159 offset:2048
	ds_read_b128 v[186:189], v159 offset:3072
	s_add_u32 s14, s64, 0x40000
	s_addc_u32 s15, s65, 0
	s_mov_b32 m0, s66
	v_lshl_add_u64 v[234:235], s[14:15], 0, v[132:133]
	ds_read_b128 v[190:193], v157 offset:32768
	ds_read_b128 v[194:197], v157 offset:33792
	ds_read_b128 v[198:201], v157 offset:34816
	ds_read_b128 v[208:211], v157 offset:35840
	ds_read_b128 v[212:215], v157 offset:36864
	ds_read_b128 v[216:219], v157 offset:37888
	ds_read_b128 v[220:223], v157 offset:38912
	ds_read_b128 v[224:227], v157 offset:39936
	global_load_lds_dwordx4 v[234:235], off
	v_lshl_add_u64 v[234:235], s[14:15], 0, v[136:137]
	s_mov_b32 m0, s67
	s_nop 0
	global_load_lds_dwordx4 v[234:235], off
	s_waitcnt vmcnt(8)
	s_waitcnt lgkmcnt(0)
	s_barrier
	s_setprio 1
	s_waitcnt lgkmcnt(0)
	v_mfma_f32_16x16x32_bf16 v[124:127], v[148:151], v[190:193], v[124:127]
	v_mfma_f32_16x16x32_bf16 v[120:123], v[164:167], v[190:193], v[120:123]
	v_mfma_f32_16x16x32_bf16 v[108:111], v[148:151], v[198:201], v[108:111]
	v_mfma_f32_16x16x32_bf16 v[104:107], v[164:167], v[198:201], v[104:107]
	v_mfma_f32_16x16x32_bf16 v[92:95], v[148:151], v[212:215], v[92:95]
	v_mfma_f32_16x16x32_bf16 v[88:91], v[164:167], v[212:215], v[88:91]
	v_mfma_f32_16x16x32_bf16 v[76:79], v[148:151], v[220:223], v[76:79]
	v_mfma_f32_16x16x32_bf16 v[72:75], v[164:167], v[220:223], v[72:75]
	v_mfma_f32_16x16x32_bf16 v[124:127], v[160:163], v[194:197], v[124:127]
	v_mfma_f32_16x16x32_bf16 v[120:123], v[168:171], v[194:197], v[120:123]
	v_mfma_f32_16x16x32_bf16 v[108:111], v[160:163], v[208:211], v[108:111]
	v_mfma_f32_16x16x32_bf16 v[104:107], v[168:171], v[208:211], v[104:107]
	v_mfma_f32_16x16x32_bf16 v[92:95], v[160:163], v[216:219], v[92:95]
	v_mfma_f32_16x16x32_bf16 v[88:91], v[168:171], v[216:219], v[88:91]
	v_mfma_f32_16x16x32_bf16 v[76:79], v[160:163], v[224:227], v[76:79]
	v_mfma_f32_16x16x32_bf16 v[72:75], v[168:171], v[224:227], v[72:75]
	s_setprio 0
	s_setprio 1
	v_mfma_f32_16x16x32_bf16 v[116:119], v[172:175], v[190:193], v[116:119]
	v_mfma_f32_16x16x32_bf16 v[112:115], v[182:185], v[190:193], v[112:115]
	v_mfma_f32_16x16x32_bf16 v[100:103], v[172:175], v[198:201], v[100:103]
	v_mfma_f32_16x16x32_bf16 v[96:99], v[182:185], v[198:201], v[96:99]
	v_mfma_f32_16x16x32_bf16 v[84:87], v[172:175], v[212:215], v[84:87]
	v_mfma_f32_16x16x32_bf16 v[80:83], v[182:185], v[212:215], v[80:83]
	v_mfma_f32_16x16x32_bf16 v[68:71], v[172:175], v[220:223], v[68:71]
	v_mfma_f32_16x16x32_bf16 v[64:67], v[182:185], v[220:223], v[64:67]
	v_mfma_f32_16x16x32_bf16 v[116:119], v[176:179], v[194:197], v[116:119]
	v_mfma_f32_16x16x32_bf16 v[112:115], v[186:189], v[194:197], v[112:115]
	v_mfma_f32_16x16x32_bf16 v[100:103], v[176:179], v[208:211], v[100:103]
	v_mfma_f32_16x16x32_bf16 v[96:99], v[186:189], v[208:211], v[96:99]
	v_mfma_f32_16x16x32_bf16 v[84:87], v[176:179], v[216:219], v[84:87]
	v_mfma_f32_16x16x32_bf16 v[80:83], v[186:189], v[216:219], v[80:83]
	v_mfma_f32_16x16x32_bf16 v[68:71], v[176:179], v[224:227], v[68:71]
	v_mfma_f32_16x16x32_bf16 v[64:67], v[186:189], v[224:227], v[64:67]
	s_setprio 0
	s_barrier
; #define PG8_STAGE(bufoff, gbase, voff) do { _Pragma("unroll") for (int _i = 0; _i < 2; ++_i) \
;         __builtin_amdgcn_global_load_lds((const unsigned*)((const char*)(gbase) + (voff)[_i]), (PG8_LAS unsigned*)(lds + (bufoff) + ldsw + _i * 8192), 16, 0, 0); } while (0)
; #define PG8_LDA(dst, b, h) do { _Pragma("unroll") for (int m = 0; m < 4; ++m) _Pragma("unroll") for (int k = 0; k < 2; ++k) dst[m][k] = *(const PG8_LAS bf16x8*)(lds + PG8_SA(b, h) + aoff + m * 2048 + k * 1024); } while (0)
; #define PG8_MMA(ai, bj, At, Bt) do { __builtin_amdgcn_s_setprio(1); _Pragma("unroll") for (int m = 0; m < 4; ++m) _Pragma("unroll") for (int n = 0; n < 2; ++n) _Pragma("unroll") for (int k = 0; k < 2; ++k) \
;         acc[ai][bj][m][n] = __builtin_amdgcn_mfma_f32_16x16x32_bf16(Bt[n][k], At[m][k], acc[ai][bj][m][n], 0, 0, 0); __builtin_amdgcn_s_setprio(0); } while (0)
; #define PG8_WAIT_V(n) asm volatile("s_waitcnt vmcnt(" #n ")" ::: "memory")
; #define PG8_WAIT_L(n) asm volatile("s_waitcnt lgkmcnt(" #n ")" ::: "memory")
; #define PG8_BAR __builtin_amdgcn_s_barrier()
; #define PG8_SCHED __builtin_amdgcn_sched_barrier(0)
; template <class Epi, class Sched, bool ALIGN_EPI = false, bool SP2 = false>
; __device__ __forceinline__ void gemm_phase(PG8_LAS unsigned char* lds, const Gemm g, const Sched& S, const Epi& E) {
;     ...
;         for (int t = 0; t < nt; t += 2) {
;             const bool last = (t == nt - 2);
;             const char* a1 = cA + (size_t)(t + 1) * kstep;
;             const char* a2 = last ? nA : cA + (size_t)(t + 2) * kstep; const char* b2 = last ? nB : cB + (size_t)(t + 2) * kstep;
;     ...
;             PG8_LDA(At, 1, 1); PG8_STAGE(PG8_SB(1, 0), b3, voffB); PG8_STAGE(PG8_SB(1, 1), b3 + hstep, voffB); PG8_STAGE(PG8_SA(1, 0), a3, voffA);
;             PG8_WAIT_V(8); PG8_WAIT_L(0); PG8_BAR; PG8_MMA(1, 0, At, B0); PG8_MMA(1, 1, At, B1); PG8_BAR; PG8_SCHED;
	s_add_i32 s3, s3, s34
	v_lshl_add_u64 v[202:203], v[202:203], 0, s[38:39]
	s_mov_b32 m0, s3
	ds_read_b128 v[190:193], v157 offset:49152
	ds_read_b128 v[194:197], v157 offset:50176
	ds_read_b128 v[198:201], v157 offset:51200
	ds_read_b128 v[208:211], v157 offset:52224
	ds_read_b128 v[212:215], v157 offset:53248
	ds_read_b128 v[216:219], v157 offset:54272
	ds_read_b128 v[220:223], v157 offset:55296
	ds_read_b128 v[224:227], v157 offset:56320
	global_load_lds_dwordx4 v[202:203], off
	s_add_i32 m0, s3, 0x2000
	s_add_u32 s14, s62, 0x40080
	v_lshl_add_u64 v[202:203], v[228:229], 0, s[38:39]
	s_addc_u32 s15, s63, 0
	s_add_i32 s3, s33, s34
	global_load_lds_dwordx4 v[202:203], off
	v_lshl_add_u64 v[202:203], s[14:15], 0, v[134:135]
	s_mov_b32 m0, s3
	s_nop 0
	global_load_lds_dwordx4 v[202:203], off
	v_lshl_add_u64 v[202:203], s[14:15], 0, v[138:139]
	s_add_i32 m0, s3, 0x2000
	s_nop 0
	global_load_lds_dwordx4 v[202:203], off
	s_waitcnt vmcnt(6)
	s_waitcnt lgkmcnt(0)
	s_barrier
	s_setprio 1
	s_waitcnt lgkmcnt(0)
	v_mfma_f32_16x16x32_bf16 v[60:63], v[148:151], v[190:193], v[60:63]
	v_mfma_f32_16x16x32_bf16 v[56:59], v[164:167], v[190:193], v[56:59]
	v_mfma_f32_16x16x32_bf16 v[44:47], v[148:151], v[198:201], v[44:47]
	v_mfma_f32_16x16x32_bf16 v[40:43], v[164:167], v[198:201], v[40:43]
	v_mfma_f32_16x16x32_bf16 v[28:31], v[148:151], v[212:215], v[28:31]
	v_mfma_f32_16x16x32_bf16 v[24:27], v[164:167], v[212:215], v[24:27]
	v_lshl_add_u64 v[202:203], v[230:231], 0, s[38:39]
	s_mov_b32 m0, s75
	s_nop 0
	global_load_lds_dwordx4 v[202:203], off
	v_mfma_f32_16x16x32_bf16 v[12:15], v[148:151], v[220:223], v[12:15]
	v_mfma_f32_16x16x32_bf16 v[8:11], v[164:167], v[220:223], v[8:11]
	v_mfma_f32_16x16x32_bf16 v[60:63], v[160:163], v[194:197], v[60:63]
	v_mfma_f32_16x16x32_bf16 v[56:59], v[168:171], v[194:197], v[56:59]
	v_mfma_f32_16x16x32_bf16 v[44:47], v[160:163], v[208:211], v[44:47]
	v_mfma_f32_16x16x32_bf16 v[40:43], v[168:171], v[208:211], v[40:43]
	v_mfma_f32_16x16x32_bf16 v[28:31], v[160:163], v[216:219], v[28:31]
	v_mfma_f32_16x16x32_bf16 v[24:27], v[168:171], v[216:219], v[24:27]
	v_mfma_f32_16x16x32_bf16 v[12:15], v[160:163], v[224:227], v[12:15]
	v_mfma_f32_16x16x32_bf16 v[8:11], v[168:171], v[224:227], v[8:11]
	s_setprio 0
	s_setprio 1
	v_mfma_f32_16x16x32_bf16 v[52:55], v[172:175], v[190:193], v[52:55]
	v_mfma_f32_16x16x32_bf16 v[48:51], v[182:185], v[190:193], v[48:51]
	v_lshl_add_u64 v[202:203], v[232:233], 0, s[38:39]
	s_mov_b32 m0, s84
	s_nop 0
	global_load_lds_dwordx4 v[202:203], off
	v_mfma_f32_16x16x32_bf16 v[36:39], v[172:175], v[198:201], v[36:39]
	v_mfma_f32_16x16x32_bf16 v[32:35], v[182:185], v[198:201], v[32:35]
	v_mfma_f32_16x16x32_bf16 v[20:23], v[172:175], v[212:215], v[20:23]
	v_mfma_f32_16x16x32_bf16 v[16:19], v[182:185], v[212:215], v[16:19]
	v_mfma_f32_16x16x32_bf16 v[4:7], v[172:175], v[220:223], v[4:7]
	v_mfma_f32_16x16x32_bf16 v[0:3], v[182:185], v[220:223], v[0:3]
	v_mfma_f32_16x16x32_bf16 v[52:55], v[176:179], v[194:197], v[52:55]
	v_mfma_f32_16x16x32_bf16 v[48:51], v[186:189], v[194:197], v[48:51]
	v_mfma_f32_16x16x32_bf16 v[36:39], v[176:179], v[208:211], v[36:39]
	v_mfma_f32_16x16x32_bf16 v[32:35], v[186:189], v[208:211], v[32:35]
	v_mfma_f32_16x16x32_bf16 v[20:23], v[176:179], v[216:219], v[20:23]
	v_mfma_f32_16x16x32_bf16 v[16:19], v[186:189], v[216:219], v[16:19]
	v_mfma_f32_16x16x32_bf16 v[4:7], v[176:179], v[224:227], v[4:7]
	v_mfma_f32_16x16x32_bf16 v[0:3], v[186:189], v[224:227], v[0:3]
	s_setprio 0
	s_barrier
	s_add_i32 s92, s92, 2
	s_add_u32 s60, s60, 0x100
	s_addc_u32 s61, s61, 0
	s_add_u32 s90, s90, 0x100
	s_addc_u32 s91, s91, 0
	s_cmp_gt_u32 s92, 13
	s_cbranch_scc0 .LBB0_650
	s_and_b64 vcc, exec, s[44:45]
	s_cbranch_vccz .LBB0_653
	s_barrier

; #define PG8_STAGE(bufoff, gbase, voff) do { _Pragma("unroll") for (int _i = 0; _i < 2; ++_i) \
;         __builtin_amdgcn_global_load_lds((const unsigned*)((const char*)(gbase) + (voff)[_i]), (PG8_LAS unsigned*)(lds + (bufoff) + ldsw + _i * 8192), 16, 0, 0); } while (0)
; #define PG8_LDA(dst, b, h) do { _Pragma("unroll") for (int m = 0; m < 4; ++m) _Pragma("unroll") for (int k = 0; k < 2; ++k) dst[m][k] = *(const PG8_LAS bf16x8*)(lds + PG8_SA(b, h) + aoff + m * 2048 + k * 1024); } while (0)
; #define PG8_LDB(dst, b, h) do { _Pragma("unroll") for (int n = 0; n < 2; ++n) _Pragma("unroll") for (int k = 0; k < 2; ++k) dst[n][k] = *(const PG8_LAS bf16x8*)(lds + PG8_SB(b, h) + boff + n * 2048 + k * 1024); } while (0)
; #define PG8_MMA(ai, bj, At, Bt) do { __builtin_amdgcn_s_setprio(1); _Pragma("unroll") for (int m = 0; m < 4; ++m) _Pragma("unroll") for (int n = 0; n < 2; ++n) _Pragma("unroll") for (int k = 0; k < 2; ++k) \
;         acc[ai][bj][m][n] = __builtin_amdgcn_mfma_f32_16x16x32_bf16(Bt[n][k], At[m][k], acc[ai][bj][m][n], 0, 0, 0); __builtin_amdgcn_s_setprio(0); } while (0)
; #define PG8_WAIT_V(n) asm volatile("s_waitcnt vmcnt(" #n ")" ::: "memory")
; #define PG8_WAIT_L(n) asm volatile("s_waitcnt lgkmcnt(" #n ")" ::: "memory")
; #define PG8_BAR __builtin_amdgcn_s_barrier()
; #define PG8_SCHED __builtin_amdgcn_sched_barrier(0)
; template <class Epi, class Sched, bool ALIGN_EPI = false, bool SP2 = false>
; __device__ __forceinline__ void gemm_phase(PG8_LAS unsigned char* lds, const Gemm g, const Sched& S, const Epi& E) {
;     ...
;             PG8_LDB(B0, 0, 0); PG8_LDB(B1, 0, 1); PG8_SCHED; PG8_LDA(At, 0, 0); PG8_STAGE(PG8_SA(1, 1), a1 + hstep, voffA);
;             PG8_WAIT_V(8); PG8_WAIT_L(0); PG8_BAR; PG8_MMA(0, 0, At, B0); PG8_MMA(0, 1, At, B1); PG8_BAR; PG8_SCHED;
;             PG8_LDA(At, 0, 1); PG8_STAGE(PG8_SB(0, 0), b2, voffB); PG8_STAGE(PG8_SB(0, 1), b2 + hstep, voffB); PG8_STAGE(PG8_SA(0, 0), a2, voffA);
;             PG8_WAIT_V(8); PG8_WAIT_L(0); PG8_BAR; PG8_MMA(1, 0, At, B0); PG8_MMA(1, 1, At, B1); PG8_BAR; PG8_SCHED;
;     ...
; #pragma unroll
;         for (int a = 0; a < 2; ++a)
; #pragma unroll
;             for (int b = 0; b < 2; ++b)
; #pragma unroll
;                 for (int m = 0; m < 4; ++m)
; #pragma unroll
;                     for (int n = 0; n < 2; ++n) acc[a][b][m][n] = (f32x4){0.f, 0.f, 0.f, 0.f};
;         cur = nxt; cA = nA; cB = nB; ++ui;
.LBB0_737:
	s_ashr_i32 s51, s50, 31
	s_lshl_b64 s[14:15], s[50:51], 19
	s_add_u32 s52, s22, s14
	s_addc_u32 s53, s23, s15
	s_and_b64 s[14:15], s[8:9], exec
	s_cselect_b32 s51, s53, s57
	s_cselect_b32 s82, s52, s56
	s_ashr_i32 s49, s48, 31
	s_lshl_b64 s[14:15], s[48:49], 19
	v_readlane_b32 s3, v250, 15
	s_add_u32 s54, s3, s14
	v_readlane_b32 s3, v250, 16
	s_addc_u32 s55, s3, s15
	s_and_b64 s[14:15], s[8:9], exec
	s_cselect_b32 s49, s55, s59
	s_cselect_b32 s83, s54, s58
	s_add_u32 s56, s56, 0x40080
	s_addc_u32 s57, s57, 0
	s_add_u32 s84, s58, 0x100
	s_addc_u32 s85, s59, 0
	s_mov_b32 s86, -2
	s_waitcnt vmcnt(0)
	ds_read_b128 v[148:151], v155
	ds_read_b128 v[160:163], v155 offset:1024
	ds_read_b128 v[164:167], v155 offset:2048
	ds_read_b128 v[168:171], v155 offset:3072
	ds_read_b128 v[172:175], v156
	ds_read_b128 v[176:179], v156 offset:1024
	ds_read_b128 v[182:185], v156 offset:2048
	ds_read_b128 v[186:189], v156 offset:3072
	s_add_u32 s3, s56, 0xfffc0080
	s_addc_u32 s14, s57, -1
	s_cmp_eq_u32 s86, 12
	s_cselect_b32 s61, s51, s14
	s_cselect_b32 s60, s82, s3
	s_cselect_b32 s59, s49, s85
	s_cselect_b32 s58, s83, s84
	v_lshl_add_u64 v[202:203], s[56:57], 0, v[140:141]
	s_add_i32 m0, s43, 0xc000
	ds_read_b128 v[190:193], v157
	ds_read_b128 v[194:197], v157 offset:1024
	ds_read_b128 v[198:201], v157 offset:2048
	ds_read_b128 v[208:211], v157 offset:3072
	ds_read_b128 v[212:215], v157 offset:4096
	ds_read_b128 v[216:219], v157 offset:5120
	ds_read_b128 v[220:223], v157 offset:6144
	ds_read_b128 v[224:227], v157 offset:7168
	global_load_lds_dwordx4 v[202:203], off
	v_lshl_add_u64 v[202:203], s[56:57], 0, v[142:143]
	s_add_i32 m0, s43, 0xe000
	s_nop 0
	global_load_lds_dwordx4 v[202:203], off
	s_waitcnt vmcnt(8)
	s_waitcnt lgkmcnt(0)
	s_barrier
	s_setprio 1
	s_waitcnt lgkmcnt(0)
	v_mfma_f32_16x16x32_bf16 v[124:127], v[148:151], v[190:193], 0
	v_mfma_f32_16x16x32_bf16 v[120:123], v[164:167], v[190:193], 0
	v_mfma_f32_16x16x32_bf16 v[108:111], v[148:151], v[198:201], 0
	v_mfma_f32_16x16x32_bf16 v[104:107], v[164:167], v[198:201], 0
	v_mfma_f32_16x16x32_bf16 v[92:95], v[148:151], v[212:215], 0
	v_mfma_f32_16x16x32_bf16 v[88:91], v[164:167], v[212:215], 0
	v_mfma_f32_16x16x32_bf16 v[76:79], v[148:151], v[220:223], 0
	v_mfma_f32_16x16x32_bf16 v[72:75], v[164:167], v[220:223], 0
	v_mfma_f32_16x16x32_bf16 v[124:127], v[160:163], v[194:197], v[124:127]
	v_mfma_f32_16x16x32_bf16 v[120:123], v[168:171], v[194:197], v[120:123]
	v_mfma_f32_16x16x32_bf16 v[108:111], v[160:163], v[208:211], v[108:111]
	v_mfma_f32_16x16x32_bf16 v[104:107], v[168:171], v[208:211], v[104:107]
	v_mfma_f32_16x16x32_bf16 v[92:95], v[160:163], v[216:219], v[92:95]
	v_mfma_f32_16x16x32_bf16 v[88:91], v[168:171], v[216:219], v[88:91]
	v_mfma_f32_16x16x32_bf16 v[76:79], v[160:163], v[224:227], v[76:79]
	v_mfma_f32_16x16x32_bf16 v[72:75], v[168:171], v[224:227], v[72:75]
	s_setprio 0
	s_setprio 1
	v_mfma_f32_16x16x32_bf16 v[116:119], v[172:175], v[190:193], 0
	v_mfma_f32_16x16x32_bf16 v[112:115], v[182:185], v[190:193], 0
	v_mfma_f32_16x16x32_bf16 v[100:103], v[172:175], v[198:201], 0
	v_mfma_f32_16x16x32_bf16 v[96:99], v[182:185], v[198:201], 0
	v_mfma_f32_16x16x32_bf16 v[84:87], v[172:175], v[212:215], 0
	v_mfma_f32_16x16x32_bf16 v[80:83], v[182:185], v[212:215], 0
	v_mfma_f32_16x16x32_bf16 v[68:71], v[172:175], v[220:223], 0
	v_mfma_f32_16x16x32_bf16 v[64:67], v[182:185], v[220:223], 0
	v_mfma_f32_16x16x32_bf16 v[116:119], v[176:179], v[194:197], v[116:119]
	v_mfma_f32_16x16x32_bf16 v[112:115], v[186:189], v[194:197], v[112:115]
	v_mfma_f32_16x16x32_bf16 v[100:103], v[176:179], v[208:211], v[100:103]
	v_mfma_f32_16x16x32_bf16 v[96:99], v[186:189], v[208:211], v[96:99]
	v_mfma_f32_16x16x32_bf16 v[84:87], v[176:179], v[216:219], v[84:87]
	v_mfma_f32_16x16x32_bf16 v[80:83], v[186:189], v[216:219], v[80:83]
	v_mfma_f32_16x16x32_bf16 v[68:71], v[176:179], v[224:227], v[68:71]
	v_mfma_f32_16x16x32_bf16 v[64:67], v[186:189], v[224:227], v[64:67]
	s_setprio 0
	s_barrier
	s_add_i32 s3, s74, s34
	v_lshl_add_u64 v[202:203], s[58:59], 0, v[136:137]
	s_mov_b32 m0, s3
	ds_read_b128 v[190:193], v157 offset:16384
	ds_read_b128 v[194:197], v157 offset:17408
	ds_read_b128 v[198:201], v157 offset:18432
	ds_read_b128 v[208:211], v157 offset:19456
	ds_read_b128 v[212:215], v157 offset:20480
	ds_read_b128 v[216:219], v157 offset:21504
	ds_read_b128 v[220:223], v157 offset:22528
	ds_read_b128 v[224:227], v157 offset:23552
	global_load_lds_dwordx4 v[202:203], off
	s_add_i32 m0, s3, 0x2000
	s_add_u32 s14, s58, 0x40000
	v_lshl_add_u64 v[228:229], s[58:59], 0, v[132:133]
	s_addc_u32 s15, s59, 0
	s_add_i32 s3, s75, s34
	global_load_lds_dwordx4 v[228:229], off
	v_lshl_add_u64 v[230:231], s[14:15], 0, v[136:137]
	s_mov_b32 m0, s3
	v_lshl_add_u64 v[232:233], s[60:61], 0, v[134:135]
	global_load_lds_dwordx4 v[230:231], off
	v_lshl_add_u64 v[230:231], s[14:15], 0, v[132:133]
	s_add_i32 m0, s3, 0x2000
	s_nop 0
	global_load_lds_dwordx4 v[230:231], off
	s_waitcnt vmcnt(6)
	s_waitcnt lgkmcnt(0)
	s_barrier
; #define PG8_STAGE(bufoff, gbase, voff) do { _Pragma("unroll") for (int _i = 0; _i < 2; ++_i) \
;         __builtin_amdgcn_global_load_lds((const unsigned*)((const char*)(gbase) + (voff)[_i]), (PG8_LAS unsigned*)(lds + (bufoff) + ldsw + _i * 8192), 16, 0, 0); } while (0)
; #define PG8_LDA(dst, b, h) do { _Pragma("unroll") for (int m = 0; m < 4; ++m) _Pragma("unroll") for (int k = 0; k < 2; ++k) dst[m][k] = *(const PG8_LAS bf16x8*)(lds + PG8_SA(b, h) + aoff + m * 2048 + k * 1024); } while (0)
; #define PG8_LDB(dst, b, h) do { _Pragma("unroll") for (int n = 0; n < 2; ++n) _Pragma("unroll") for (int k = 0; k < 2; ++k) dst[n][k] = *(const PG8_LAS bf16x8*)(lds + PG8_SB(b, h) + boff + n * 2048 + k * 1024); } while (0)
; #define PG8_MMA(ai, bj, At, Bt) do { __builtin_amdgcn_s_setprio(1); _Pragma("unroll") for (int m = 0; m < 4; ++m) _Pragma("unroll") for (int n = 0; n < 2; ++n) _Pragma("unroll") for (int k = 0; k < 2; ++k) \
;         acc[ai][bj][m][n] = __builtin_amdgcn_mfma_f32_16x16x32_bf16(Bt[n][k], At[m][k], acc[ai][bj][m][n], 0, 0, 0); __builtin_amdgcn_s_setprio(0); } while (0)
; #define PG8_WAIT_V(n) asm volatile("s_waitcnt vmcnt(" #n ")" ::: "memory")
; #define PG8_WAIT_L(n) asm volatile("s_waitcnt lgkmcnt(" #n ")" ::: "memory")
; #define PG8_BAR __builtin_amdgcn_s_barrier()
; #define PG8_SCHED __builtin_amdgcn_sched_barrier(0)
; template <class Epi, class Sched, bool ALIGN_EPI = false, bool SP2 = false>
; __device__ __forceinline__ void gemm_phase(PG8_LAS unsigned char* lds, const Gemm g, const Sched& S, const Epi& E) {
;     ...
;             PG8_WAIT_V(8); PG8_WAIT_L(0); PG8_BAR; PG8_MMA(1, 0, At, B0); PG8_MMA(1, 1, At, B1); PG8_BAR; PG8_SCHED;
;             PG8_LDB(B0, 1, 0); PG8_LDB(B1, 1, 1); PG8_SCHED; PG8_LDA(At, 1, 0); PG8_STAGE(PG8_SA(0, 1), a2 + hstep, voffA);
;             PG8_WAIT_V(8); PG8_WAIT_L(0); PG8_BAR; PG8_MMA(0, 0, At, B0); PG8_MMA(0, 1, At, B1); PG8_BAR; PG8_SCHED;
	s_setprio 1
	s_waitcnt lgkmcnt(0)
	v_mfma_f32_16x16x32_bf16 v[60:63], v[148:151], v[190:193], 0
	v_mfma_f32_16x16x32_bf16 v[56:59], v[164:167], v[190:193], 0
	v_mfma_f32_16x16x32_bf16 v[44:47], v[148:151], v[198:201], 0
	v_mfma_f32_16x16x32_bf16 v[40:43], v[164:167], v[198:201], 0
	v_mfma_f32_16x16x32_bf16 v[28:31], v[148:151], v[212:215], 0
	v_mfma_f32_16x16x32_bf16 v[24:27], v[164:167], v[212:215], 0
	v_lshl_add_u64 v[230:231], s[60:61], 0, v[138:139]
	s_mov_b32 m0, s43
	s_nop 0
	global_load_lds_dwordx4 v[230:231], off
	v_mfma_f32_16x16x32_bf16 v[12:15], v[148:151], v[220:223], 0
	v_mfma_f32_16x16x32_bf16 v[8:11], v[164:167], v[220:223], 0
	v_mfma_f32_16x16x32_bf16 v[60:63], v[160:163], v[194:197], v[60:63]
	v_mfma_f32_16x16x32_bf16 v[56:59], v[168:171], v[194:197], v[56:59]
	v_mfma_f32_16x16x32_bf16 v[44:47], v[160:163], v[208:211], v[44:47]
	v_mfma_f32_16x16x32_bf16 v[40:43], v[168:171], v[208:211], v[40:43]
	v_mfma_f32_16x16x32_bf16 v[28:31], v[160:163], v[216:219], v[28:31]
	v_mfma_f32_16x16x32_bf16 v[24:27], v[168:171], v[216:219], v[24:27]
	v_mfma_f32_16x16x32_bf16 v[12:15], v[160:163], v[224:227], v[12:15]
	v_mfma_f32_16x16x32_bf16 v[8:11], v[168:171], v[224:227], v[8:11]
	s_setprio 0
	s_setprio 1
	v_mfma_f32_16x16x32_bf16 v[52:55], v[172:175], v[190:193], 0
	v_mfma_f32_16x16x32_bf16 v[48:51], v[182:185], v[190:193], 0
	s_mov_b32 m0, s62
	s_nop 0
	global_load_lds_dwordx4 v[232:233], off
	v_mfma_f32_16x16x32_bf16 v[36:39], v[172:175], v[198:201], 0
	v_mfma_f32_16x16x32_bf16 v[32:35], v[182:185], v[198:201], 0
	v_mfma_f32_16x16x32_bf16 v[20:23], v[172:175], v[212:215], 0
	v_mfma_f32_16x16x32_bf16 v[16:19], v[182:185], v[212:215], 0
	v_mfma_f32_16x16x32_bf16 v[4:7], v[172:175], v[220:223], 0
	v_mfma_f32_16x16x32_bf16 v[0:3], v[182:185], v[220:223], 0
	v_mfma_f32_16x16x32_bf16 v[52:55], v[176:179], v[194:197], v[52:55]
	v_mfma_f32_16x16x32_bf16 v[48:51], v[186:189], v[194:197], v[48:51]
	v_mfma_f32_16x16x32_bf16 v[36:39], v[176:179], v[208:211], v[36:39]
	v_mfma_f32_16x16x32_bf16 v[32:35], v[186:189], v[208:211], v[32:35]
	v_mfma_f32_16x16x32_bf16 v[20:23], v[176:179], v[216:219], v[20:23]
	v_mfma_f32_16x16x32_bf16 v[16:19], v[186:189], v[216:219], v[16:19]
	v_mfma_f32_16x16x32_bf16 v[4:7], v[176:179], v[224:227], v[4:7]
	v_mfma_f32_16x16x32_bf16 v[0:3], v[186:189], v[224:227], v[0:3]
	s_setprio 0
	s_barrier
	s_add_i32 s3, 0, 0x18000
	v_add_u32_e32 v159, s3, v131
	s_add_i32 s33, 0, 0x1c000
	ds_read_b128 v[148:151], v159
	ds_read_b128 v[160:163], v159 offset:1024
	ds_read_b128 v[164:167], v159 offset:2048
	ds_read_b128 v[168:171], v159 offset:3072
	v_add_u32_e32 v159, s33, v131
	ds_read_b128 v[172:175], v159
	ds_read_b128 v[176:179], v159 offset:1024
	ds_read_b128 v[182:185], v159 offset:2048
	ds_read_b128 v[186:189], v159 offset:3072
	s_add_u32 s14, s60, 0x40000
	s_addc_u32 s15, s61, 0
	s_mov_b32 m0, s63
	v_lshl_add_u64 v[234:235], s[14:15], 0, v[138:139]
	ds_read_b128 v[190:193], v157 offset:32768
	ds_read_b128 v[194:197], v157 offset:33792
	ds_read_b128 v[198:201], v157 offset:34816
	ds_read_b128 v[208:211], v157 offset:35840
	ds_read_b128 v[212:215], v157 offset:36864
	ds_read_b128 v[216:219], v157 offset:37888
	ds_read_b128 v[220:223], v157 offset:38912
	ds_read_b128 v[224:227], v157 offset:39936
	global_load_lds_dwordx4 v[234:235], off
	v_lshl_add_u64 v[234:235], s[14:15], 0, v[134:135]
	s_mov_b32 m0, s64
	s_nop 0
	global_load_lds_dwordx4 v[234:235], off
	s_waitcnt vmcnt(8)
	s_waitcnt lgkmcnt(0)
	s_barrier
	s_setprio 1
	s_waitcnt lgkmcnt(0)
	v_mfma_f32_16x16x32_bf16 v[124:127], v[148:151], v[190:193], v[124:127]
	v_mfma_f32_16x16x32_bf16 v[120:123], v[164:167], v[190:193], v[120:123]
	v_mfma_f32_16x16x32_bf16 v[108:111], v[148:151], v[198:201], v[108:111]
	v_mfma_f32_16x16x32_bf16 v[104:107], v[164:167], v[198:201], v[104:107]
	v_mfma_f32_16x16x32_bf16 v[92:95], v[148:151], v[212:215], v[92:95]
	v_mfma_f32_16x16x32_bf16 v[88:91], v[164:167], v[212:215], v[88:91]
	v_mfma_f32_16x16x32_bf16 v[76:79], v[148:151], v[220:223], v[76:79]
	v_mfma_f32_16x16x32_bf16 v[72:75], v[164:167], v[220:223], v[72:75]
	v_mfma_f32_16x16x32_bf16 v[124:127], v[160:163], v[194:197], v[124:127]
	v_mfma_f32_16x16x32_bf16 v[120:123], v[168:171], v[194:197], v[120:123]
	v_mfma_f32_16x16x32_bf16 v[108:111], v[160:163], v[208:211], v[108:111]
	v_mfma_f32_16x16x32_bf16 v[104:107], v[168:171], v[208:211], v[104:107]
	v_mfma_f32_16x16x32_bf16 v[92:95], v[160:163], v[216:219], v[92:95]
	v_mfma_f32_16x16x32_bf16 v[88:91], v[168:171], v[216:219], v[88:91]
	v_mfma_f32_16x16x32_bf16 v[76:79], v[160:163], v[224:227], v[76:79]
	v_mfma_f32_16x16x32_bf16 v[72:75], v[168:171], v[224:227], v[72:75]
	s_setprio 0
	s_setprio 1
	v_mfma_f32_16x16x32_bf16 v[116:119], v[172:175], v[190:193], v[116:119]
	v_mfma_f32_16x16x32_bf16 v[112:115], v[182:185], v[190:193], v[112:115]
	v_mfma_f32_16x16x32_bf16 v[100:103], v[172:175], v[198:201], v[100:103]
	v_mfma_f32_16x16x32_bf16 v[96:99], v[182:185], v[198:201], v[96:99]
	v_mfma_f32_16x16x32_bf16 v[84:87], v[172:175], v[212:215], v[84:87]
	v_mfma_f32_16x16x32_bf16 v[80:83], v[182:185], v[212:215], v[80:83]
	v_mfma_f32_16x16x32_bf16 v[68:71], v[172:175], v[220:223], v[68:71]
	v_mfma_f32_16x16x32_bf16 v[64:67], v[182:185], v[220:223], v[64:67]
	v_mfma_f32_16x16x32_bf16 v[116:119], v[176:179], v[194:197], v[116:119]
	v_mfma_f32_16x16x32_bf16 v[112:115], v[186:189], v[194:197], v[112:115]
	v_mfma_f32_16x16x32_bf16 v[100:103], v[176:179], v[208:211], v[100:103]
	v_mfma_f32_16x16x32_bf16 v[96:99], v[186:189], v[208:211], v[96:99]
	v_mfma_f32_16x16x32_bf16 v[84:87], v[176:179], v[216:219], v[84:87]
	v_mfma_f32_16x16x32_bf16 v[80:83], v[186:189], v[216:219], v[80:83]
	v_mfma_f32_16x16x32_bf16 v[68:71], v[176:179], v[224:227], v[68:71]
	v_mfma_f32_16x16x32_bf16 v[64:67], v[186:189], v[224:227], v[64:67]
	s_setprio 0
	s_barrier
; #define PG8_STAGE(bufoff, gbase, voff) do { _Pragma("unroll") for (int _i = 0; _i < 2; ++_i) \
;         __builtin_amdgcn_global_load_lds((const unsigned*)((const char*)(gbase) + (voff)[_i]), (PG8_LAS unsigned*)(lds + (bufoff) + ldsw + _i * 8192), 16, 0, 0); } while (0)
; #define PG8_LDA(dst, b, h) do { _Pragma("unroll") for (int m = 0; m < 4; ++m) _Pragma("unroll") for (int k = 0; k < 2; ++k) dst[m][k] = *(const PG8_LAS bf16x8*)(lds + PG8_SA(b, h) + aoff + m * 2048 + k * 1024); } while (0)
; #define PG8_LDB(dst, b, h) do { _Pragma("unroll") for (int n = 0; n < 2; ++n) _Pragma("unroll") for (int k = 0; k < 2; ++k) dst[n][k] = *(const PG8_LAS bf16x8*)(lds + PG8_SB(b, h) + boff + n * 2048 + k * 1024); } while (0)
; #define PG8_MMA(ai, bj, At, Bt) do { __builtin_amdgcn_s_setprio(1); _Pragma("unroll") for (int m = 0; m < 4; ++m) _Pragma("unroll") for (int n = 0; n < 2; ++n) _Pragma("unroll") for (int k = 0; k < 2; ++k) \
;         acc[ai][bj][m][n] = __builtin_amdgcn_mfma_f32_16x16x32_bf16(Bt[n][k], At[m][k], acc[ai][bj][m][n], 0, 0, 0); __builtin_amdgcn_s_setprio(0); } while (0)
; #define PG8_WAIT_V(n) asm volatile("s_waitcnt vmcnt(" #n ")" ::: "memory")
; #define PG8_WAIT_L(n) asm volatile("s_waitcnt lgkmcnt(" #n ")" ::: "memory")
; #define PG8_BAR __builtin_amdgcn_s_barrier()
; #define PG8_SCHED __builtin_amdgcn_sched_barrier(0)
; template <class Epi, class Sched, bool ALIGN_EPI = false, bool SP2 = false>
; __device__ __forceinline__ void gemm_phase(PG8_LAS unsigned char* lds, const Gemm g, const Sched& S, const Epi& E) {
;     ...
;             PG8_LDB(B0, 0, 0); PG8_LDB(B1, 0, 1); PG8_SCHED; PG8_LDA(At, 0, 0); PG8_STAGE(PG8_SA(1, 1), a1 + hstep, voffA);
;             PG8_WAIT_V(8); PG8_WAIT_L(0); PG8_BAR; PG8_MMA(0, 0, At, B0); PG8_MMA(0, 1, At, B1); PG8_BAR; PG8_SCHED;
;     ...
;             PG8_LDA(At, 1, 1); PG8_STAGE(PG8_SB(1, 0), b3, voffB); PG8_STAGE(PG8_SB(1, 1), b3 + hstep, voffB); PG8_STAGE(PG8_SA(1, 0), a3, voffA);
;             PG8_WAIT_V(8); PG8_WAIT_L(0); PG8_BAR; PG8_MMA(1, 0, At, B0); PG8_MMA(1, 1, At, B1); PG8_BAR; PG8_SCHED;
	s_add_i32 s3, s3, s34
	v_lshl_add_u64 v[202:203], v[202:203], 0, s[38:39]
	s_mov_b32 m0, s3
	ds_read_b128 v[190:193], v157 offset:49152
	ds_read_b128 v[194:197], v157 offset:50176
	ds_read_b128 v[198:201], v157 offset:51200
	ds_read_b128 v[208:211], v157 offset:52224
	ds_read_b128 v[212:215], v157 offset:53248
	ds_read_b128 v[216:219], v157 offset:54272
	ds_read_b128 v[220:223], v157 offset:55296
	ds_read_b128 v[224:227], v157 offset:56320
	global_load_lds_dwordx4 v[202:203], off
	s_add_i32 m0, s3, 0x2000
	s_add_u32 s14, s58, 0x40080
	v_lshl_add_u64 v[202:203], v[228:229], 0, s[38:39]
	s_addc_u32 s15, s59, 0
	s_add_i32 s3, s33, s34
	global_load_lds_dwordx4 v[202:203], off
	v_lshl_add_u64 v[202:203], s[14:15], 0, v[136:137]
	s_mov_b32 m0, s3
	s_nop 0
	global_load_lds_dwordx4 v[202:203], off
	v_lshl_add_u64 v[202:203], s[14:15], 0, v[132:133]
	s_add_i32 m0, s3, 0x2000
	s_nop 0
	global_load_lds_dwordx4 v[202:203], off
	s_waitcnt vmcnt(6)
	s_waitcnt lgkmcnt(0)
	s_barrier
	s_setprio 1
	s_waitcnt lgkmcnt(0)
	v_mfma_f32_16x16x32_bf16 v[60:63], v[148:151], v[190:193], v[60:63]
	v_mfma_f32_16x16x32_bf16 v[56:59], v[164:167], v[190:193], v[56:59]
	v_mfma_f32_16x16x32_bf16 v[44:47], v[148:151], v[198:201], v[44:47]
	v_mfma_f32_16x16x32_bf16 v[40:43], v[164:167], v[198:201], v[40:43]
	v_mfma_f32_16x16x32_bf16 v[28:31], v[148:151], v[212:215], v[28:31]
	v_mfma_f32_16x16x32_bf16 v[24:27], v[164:167], v[212:215], v[24:27]
	v_lshl_add_u64 v[202:203], v[230:231], 0, s[38:39]
	s_mov_b32 m0, s66
	s_nop 0
	global_load_lds_dwordx4 v[202:203], off
	v_mfma_f32_16x16x32_bf16 v[12:15], v[148:151], v[220:223], v[12:15]
	v_mfma_f32_16x16x32_bf16 v[8:11], v[164:167], v[220:223], v[8:11]
	v_mfma_f32_16x16x32_bf16 v[60:63], v[160:163], v[194:197], v[60:63]
	v_mfma_f32_16x16x32_bf16 v[56:59], v[168:171], v[194:197], v[56:59]
	v_mfma_f32_16x16x32_bf16 v[44:47], v[160:163], v[208:211], v[44:47]
	v_mfma_f32_16x16x32_bf16 v[40:43], v[168:171], v[208:211], v[40:43]
	v_mfma_f32_16x16x32_bf16 v[28:31], v[160:163], v[216:219], v[28:31]
	v_mfma_f32_16x16x32_bf16 v[24:27], v[168:171], v[216:219], v[24:27]
	v_mfma_f32_16x16x32_bf16 v[12:15], v[160:163], v[224:227], v[12:15]
	v_mfma_f32_16x16x32_bf16 v[8:11], v[168:171], v[224:227], v[8:11]
	s_setprio 0
	s_setprio 1
	v_mfma_f32_16x16x32_bf16 v[52:55], v[172:175], v[190:193], v[52:55]
	v_mfma_f32_16x16x32_bf16 v[48:51], v[182:185], v[190:193], v[48:51]
	v_lshl_add_u64 v[202:203], v[232:233], 0, s[38:39]
	s_mov_b32 m0, s67
	s_nop 0
	global_load_lds_dwordx4 v[202:203], off
	v_mfma_f32_16x16x32_bf16 v[36:39], v[172:175], v[198:201], v[36:39]
	v_mfma_f32_16x16x32_bf16 v[32:35], v[182:185], v[198:201], v[32:35]
	v_mfma_f32_16x16x32_bf16 v[20:23], v[172:175], v[212:215], v[20:23]
	v_mfma_f32_16x16x32_bf16 v[16:19], v[182:185], v[212:215], v[16:19]
	v_mfma_f32_16x16x32_bf16 v[4:7], v[172:175], v[220:223], v[4:7]
	v_mfma_f32_16x16x32_bf16 v[0:3], v[182:185], v[220:223], v[0:3]
	v_mfma_f32_16x16x32_bf16 v[52:55], v[176:179], v[194:197], v[52:55]
	v_mfma_f32_16x16x32_bf16 v[48:51], v[186:189], v[194:197], v[48:51]
	v_mfma_f32_16x16x32_bf16 v[36:39], v[176:179], v[208:211], v[36:39]
	v_mfma_f32_16x16x32_bf16 v[32:35], v[186:189], v[208:211], v[32:35]
	v_mfma_f32_16x16x32_bf16 v[20:23], v[176:179], v[216:219], v[20:23]
	v_mfma_f32_16x16x32_bf16 v[16:19], v[186:189], v[216:219], v[16:19]
	v_mfma_f32_16x16x32_bf16 v[4:7], v[176:179], v[224:227], v[4:7]
	v_mfma_f32_16x16x32_bf16 v[0:3], v[186:189], v[224:227], v[0:3]
	s_setprio 0
	s_barrier
	s_add_i32 s86, s86, 2
	s_add_u32 s56, s56, 0x100
	s_addc_u32 s57, s57, 0
	s_add_u32 s84, s84, 0x100
	s_addc_u32 s85, s85, 0
.LBB0_738:
	ds_read_b128 v[148:151], v155
	ds_read_b128 v[160:163], v155 offset:1024
	ds_read_b128 v[164:167], v155 offset:2048
	ds_read_b128 v[168:171], v155 offset:3072
	ds_read_b128 v[172:175], v156
	ds_read_b128 v[176:179], v156 offset:1024
	ds_read_b128 v[182:185], v156 offset:2048
	ds_read_b128 v[186:189], v156 offset:3072
	s_add_u32 s3, s56, 0xfffc0080
	s_addc_u32 s14, s57, -1
	s_cmp_eq_u32 s86, 12
	s_cselect_b32 s61, s51, s14
	s_cselect_b32 s60, s82, s3
	s_cselect_b32 s59, s49, s85
	s_cselect_b32 s58, s83, s84
	v_lshl_add_u64 v[202:203], s[56:57], 0, v[140:141]
	s_add_i32 m0, s43, 0xc000
	ds_read_b128 v[190:193], v157
	ds_read_b128 v[194:197], v157 offset:1024
	ds_read_b128 v[198:201], v157 offset:2048
	ds_read_b128 v[208:211], v157 offset:3072
	ds_read_b128 v[212:215], v157 offset:4096
	ds_read_b128 v[216:219], v157 offset:5120
	ds_read_b128 v[220:223], v157 offset:6144
	ds_read_b128 v[224:227], v157 offset:7168
	global_load_lds_dwordx4 v[202:203], off
	v_lshl_add_u64 v[202:203], s[56:57], 0, v[142:143]
	s_add_i32 m0, s43, 0xe000
	s_nop 0
	global_load_lds_dwordx4 v[202:203], off
	s_waitcnt vmcnt(8)
	s_waitcnt lgkmcnt(0)
	s_barrier
; #define PG8_STAGE(bufoff, gbase, voff) do { _Pragma("unroll") for (int _i = 0; _i < 2; ++_i) \
;         __builtin_amdgcn_global_load_lds((const unsigned*)((const char*)(gbase) + (voff)[_i]), (PG8_LAS unsigned*)(lds + (bufoff) + ldsw + _i * 8192), 16, 0, 0); } while (0)
; #define PG8_LDA(dst, b, h) do { _Pragma("unroll") for (int m = 0; m < 4; ++m) _Pragma("unroll") for (int k = 0; k < 2; ++k) dst[m][k] = *(const PG8_LAS bf16x8*)(lds + PG8_SA(b, h) + aoff + m * 2048 + k * 1024); } while (0)
; #define PG8_MMA(ai, bj, At, Bt) do { __builtin_amdgcn_s_setprio(1); _Pragma("unroll") for (int m = 0; m < 4; ++m) _Pragma("unroll") for (int n = 0; n < 2; ++n) _Pragma("unroll") for (int k = 0; k < 2; ++k) \
;         acc[ai][bj][m][n] = __builtin_amdgcn_mfma_f32_16x16x32_bf16(Bt[n][k], At[m][k], acc[ai][bj][m][n], 0, 0, 0); __builtin_amdgcn_s_setprio(0); } while (0)
; #define PG8_WAIT_V(n) asm volatile("s_waitcnt vmcnt(" #n ")" ::: "memory")
; #define PG8_WAIT_L(n) asm volatile("s_waitcnt lgkmcnt(" #n ")" ::: "memory")
; #define PG8_BAR __builtin_amdgcn_s_barrier()
; #define PG8_SCHED __builtin_amdgcn_sched_barrier(0)
; template <class Epi, class Sched, bool ALIGN_EPI = false, bool SP2 = false>
; __device__ __forceinline__ void gemm_phase(PG8_LAS unsigned char* lds, const Gemm g, const Sched& S, const Epi& E) {
;     ...
;             PG8_WAIT_V(8); PG8_WAIT_L(0); PG8_BAR; PG8_MMA(0, 0, At, B0); PG8_MMA(0, 1, At, B1); PG8_BAR; PG8_SCHED;
;             PG8_LDA(At, 0, 1); PG8_STAGE(PG8_SB(0, 0), b2, voffB); PG8_STAGE(PG8_SB(0, 1), b2 + hstep, voffB); PG8_STAGE(PG8_SA(0, 0), a2, voffA);
;             PG8_WAIT_V(8); PG8_WAIT_L(0); PG8_BAR; PG8_MMA(1, 0, At, B0); PG8_MMA(1, 1, At, B1); PG8_BAR; PG8_SCHED;
	s_setprio 1
	s_waitcnt lgkmcnt(0)
	v_mfma_f32_16x16x32_bf16 v[124:127], v[148:151], v[190:193], v[124:127]
	v_mfma_f32_16x16x32_bf16 v[120:123], v[164:167], v[190:193], v[120:123]
	v_mfma_f32_16x16x32_bf16 v[108:111], v[148:151], v[198:201], v[108:111]
	v_mfma_f32_16x16x32_bf16 v[104:107], v[164:167], v[198:201], v[104:107]
	v_mfma_f32_16x16x32_bf16 v[92:95], v[148:151], v[212:215], v[92:95]
	v_mfma_f32_16x16x32_bf16 v[88:91], v[164:167], v[212:215], v[88:91]
	v_mfma_f32_16x16x32_bf16 v[76:79], v[148:151], v[220:223], v[76:79]
	v_mfma_f32_16x16x32_bf16 v[72:75], v[164:167], v[220:223], v[72:75]
	v_mfma_f32_16x16x32_bf16 v[124:127], v[160:163], v[194:197], v[124:127]
	v_mfma_f32_16x16x32_bf16 v[120:123], v[168:171], v[194:197], v[120:123]
	v_mfma_f32_16x16x32_bf16 v[108:111], v[160:163], v[208:211], v[108:111]
	v_mfma_f32_16x16x32_bf16 v[104:107], v[168:171], v[208:211], v[104:107]
	v_mfma_f32_16x16x32_bf16 v[92:95], v[160:163], v[216:219], v[92:95]
	v_mfma_f32_16x16x32_bf16 v[88:91], v[168:171], v[216:219], v[88:91]
	v_mfma_f32_16x16x32_bf16 v[76:79], v[160:163], v[224:227], v[76:79]
	v_mfma_f32_16x16x32_bf16 v[72:75], v[168:171], v[224:227], v[72:75]
	s_setprio 0
	s_setprio 1
	v_mfma_f32_16x16x32_bf16 v[116:119], v[172:175], v[190:193], v[116:119]
	v_mfma_f32_16x16x32_bf16 v[112:115], v[182:185], v[190:193], v[112:115]
	v_mfma_f32_16x16x32_bf16 v[100:103], v[172:175], v[198:201], v[100:103]
	v_mfma_f32_16x16x32_bf16 v[96:99], v[182:185], v[198:201], v[96:99]
	v_mfma_f32_16x16x32_bf16 v[84:87], v[172:175], v[212:215], v[84:87]
	v_mfma_f32_16x16x32_bf16 v[80:83], v[182:185], v[212:215], v[80:83]
	v_mfma_f32_16x16x32_bf16 v[68:71], v[172:175], v[220:223], v[68:71]
	v_mfma_f32_16x16x32_bf16 v[64:67], v[182:185], v[220:223], v[64:67]
	v_mfma_f32_16x16x32_bf16 v[116:119], v[176:179], v[194:197], v[116:119]
	v_mfma_f32_16x16x32_bf16 v[112:115], v[186:189], v[194:197], v[112:115]
	v_mfma_f32_16x16x32_bf16 v[100:103], v[176:179], v[208:211], v[100:103]
	v_mfma_f32_16x16x32_bf16 v[96:99], v[186:189], v[208:211], v[96:99]
	v_mfma_f32_16x16x32_bf16 v[84:87], v[176:179], v[216:219], v[84:87]
	v_mfma_f32_16x16x32_bf16 v[80:83], v[186:189], v[216:219], v[80:83]
	v_mfma_f32_16x16x32_bf16 v[68:71], v[176:179], v[224:227], v[68:71]
	v_mfma_f32_16x16x32_bf16 v[64:67], v[186:189], v[224:227], v[64:67]
	s_setprio 0
	s_barrier
	s_add_i32 s3, s74, s34
	v_lshl_add_u64 v[202:203], s[58:59], 0, v[136:137]
	s_mov_b32 m0, s3
	ds_read_b128 v[190:193], v157 offset:16384
	ds_read_b128 v[194:197], v157 offset:17408
	ds_read_b128 v[198:201], v157 offset:18432
	ds_read_b128 v[208:211], v157 offset:19456
	ds_read_b128 v[212:215], v157 offset:20480
	ds_read_b128 v[216:219], v157 offset:21504
	ds_read_b128 v[220:223], v157 offset:22528
	ds_read_b128 v[224:227], v157 offset:23552
	global_load_lds_dwordx4 v[202:203], off
	s_add_i32 m0, s3, 0x2000
	s_add_u32 s14, s58, 0x40000
	v_lshl_add_u64 v[228:229], s[58:59], 0, v[132:133]
	s_addc_u32 s15, s59, 0
	s_add_i32 s3, s75, s34
	global_load_lds_dwordx4 v[228:229], off
	v_lshl_add_u64 v[230:231], s[14:15], 0, v[136:137]
	s_mov_b32 m0, s3
	v_lshl_add_u64 v[232:233], s[60:61], 0, v[134:135]
	global_load_lds_dwordx4 v[230:231], off
	v_lshl_add_u64 v[230:231], s[14:15], 0, v[132:133]
	s_add_i32 m0, s3, 0x2000
	s_nop 0
	global_load_lds_dwordx4 v[230:231], off
	s_waitcnt vmcnt(6)
	s_waitcnt lgkmcnt(0)
	s_barrier
	s_setprio 1
	s_waitcnt lgkmcnt(0)
	v_mfma_f32_16x16x32_bf16 v[60:63], v[148:151], v[190:193], v[60:63]
	v_mfma_f32_16x16x32_bf16 v[56:59], v[164:167], v[190:193], v[56:59]
	v_mfma_f32_16x16x32_bf16 v[44:47], v[148:151], v[198:201], v[44:47]
	v_mfma_f32_16x16x32_bf16 v[40:43], v[164:167], v[198:201], v[40:43]
	v_mfma_f32_16x16x32_bf16 v[28:31], v[148:151], v[212:215], v[28:31]
	v_mfma_f32_16x16x32_bf16 v[24:27], v[164:167], v[212:215], v[24:27]
	v_lshl_add_u64 v[230:231], s[60:61], 0, v[138:139]
	s_mov_b32 m0, s43
	s_nop 0
	global_load_lds_dwordx4 v[230:231], off
	v_mfma_f32_16x16x32_bf16 v[12:15], v[148:151], v[220:223], v[12:15]
	v_mfma_f32_16x16x32_bf16 v[8:11], v[164:167], v[220:223], v[8:11]
	v_mfma_f32_16x16x32_bf16 v[60:63], v[160:163], v[194:197], v[60:63]
	v_mfma_f32_16x16x32_bf16 v[56:59], v[168:171], v[194:197], v[56:59]
	v_mfma_f32_16x16x32_bf16 v[44:47], v[160:163], v[208:211], v[44:47]
	v_mfma_f32_16x16x32_bf16 v[40:43], v[168:171], v[208:211], v[40:43]
	v_mfma_f32_16x16x32_bf16 v[28:31], v[160:163], v[216:219], v[28:31]
	v_mfma_f32_16x16x32_bf16 v[24:27], v[168:171], v[216:219], v[24:27]
	v_mfma_f32_16x16x32_bf16 v[12:15], v[160:163], v[224:227], v[12:15]
	v_mfma_f32_16x16x32_bf16 v[8:11], v[168:171], v[224:227], v[8:11]
	s_setprio 0
	s_setprio 1
	v_mfma_f32_16x16x32_bf16 v[52:55], v[172:175], v[190:193], v[52:55]
	v_mfma_f32_16x16x32_bf16 v[48:51], v[182:185], v[190:193], v[48:51]
	s_mov_b32 m0, s62
	s_nop 0
	global_load_lds_dwordx4 v[232:233], off
	v_mfma_f32_16x16x32_bf16 v[36:39], v[172:175], v[198:201], v[36:39]
	v_mfma_f32_16x16x32_bf16 v[32:35], v[182:185], v[198:201], v[32:35]
	v_mfma_f32_16x16x32_bf16 v[20:23], v[172:175], v[212:215], v[20:23]
	v_mfma_f32_16x16x32_bf16 v[16:19], v[182:185], v[212:215], v[16:19]
	v_mfma_f32_16x16x32_bf16 v[4:7], v[172:175], v[220:223], v[4:7]
	v_mfma_f32_16x16x32_bf16 v[0:3], v[182:185], v[220:223], v[0:3]
	v_mfma_f32_16x16x32_bf16 v[52:55], v[176:179], v[194:197], v[52:55]
	v_mfma_f32_16x16x32_bf16 v[48:51], v[186:189], v[194:197], v[48:51]
	v_mfma_f32_16x16x32_bf16 v[36:39], v[176:179], v[208:211], v[36:39]
	v_mfma_f32_16x16x32_bf16 v[32:35], v[186:189], v[208:211], v[32:35]
	v_mfma_f32_16x16x32_bf16 v[20:23], v[176:179], v[216:219], v[20:23]
	v_mfma_f32_16x16x32_bf16 v[16:19], v[186:189], v[216:219], v[16:19]
	v_mfma_f32_16x16x32_bf16 v[4:7], v[176:179], v[224:227], v[4:7]
	v_mfma_f32_16x16x32_bf16 v[0:3], v[186:189], v[224:227], v[0:3]
	s_setprio 0
	s_barrier
; #define PG8_STAGE(bufoff, gbase, voff) do { _Pragma("unroll") for (int _i = 0; _i < 2; ++_i) \
;         __builtin_amdgcn_global_load_lds((const unsigned*)((const char*)(gbase) + (voff)[_i]), (PG8_LAS unsigned*)(lds + (bufoff) + ldsw + _i * 8192), 16, 0, 0); } while (0)
; #define PG8_LDA(dst, b, h) do { _Pragma("unroll") for (int m = 0; m < 4; ++m) _Pragma("unroll") for (int k = 0; k < 2; ++k) dst[m][k] = *(const PG8_LAS bf16x8*)(lds + PG8_SA(b, h) + aoff + m * 2048 + k * 1024); } while (0)
; #define PG8_LDB(dst, b, h) do { _Pragma("unroll") for (int n = 0; n < 2; ++n) _Pragma("unroll") for (int k = 0; k < 2; ++k) dst[n][k] = *(const PG8_LAS bf16x8*)(lds + PG8_SB(b, h) + boff + n * 2048 + k * 1024); } while (0)
; #define PG8_MMA(ai, bj, At, Bt) do { __builtin_amdgcn_s_setprio(1); _Pragma("unroll") for (int m = 0; m < 4; ++m) _Pragma("unroll") for (int n = 0; n < 2; ++n) _Pragma("unroll") for (int k = 0; k < 2; ++k) \
;         acc[ai][bj][m][n] = __builtin_amdgcn_mfma_f32_16x16x32_bf16(Bt[n][k], At[m][k], acc[ai][bj][m][n], 0, 0, 0); __builtin_amdgcn_s_setprio(0); } while (0)
; #define PG8_WAIT_V(n) asm volatile("s_waitcnt vmcnt(" #n ")" ::: "memory")
; #define PG8_WAIT_L(n) asm volatile("s_waitcnt lgkmcnt(" #n ")" ::: "memory")
; #define PG8_BAR __builtin_amdgcn_s_barrier()
; #define PG8_SCHED __builtin_amdgcn_sched_barrier(0)
; template <class Epi, class Sched, bool ALIGN_EPI = false, bool SP2 = false>
; __device__ __forceinline__ void gemm_phase(PG8_LAS unsigned char* lds, const Gemm g, const Sched& S, const Epi& E) {
;     ...
;             PG8_LDB(B0, 1, 0); PG8_LDB(B1, 1, 1); PG8_SCHED; PG8_LDA(At, 1, 0); PG8_STAGE(PG8_SA(0, 1), a2 + hstep, voffA);
;             PG8_WAIT_V(8); PG8_WAIT_L(0); PG8_BAR; PG8_MMA(0, 0, At, B0); PG8_MMA(0, 1, At, B1); PG8_BAR; PG8_SCHED;
	s_add_i32 s3, 0, 0x18000
	v_add_u32_e32 v159, s3, v131
	s_add_i32 s33, 0, 0x1c000
	ds_read_b128 v[148:151], v159
	ds_read_b128 v[160:163], v159 offset:1024
	ds_read_b128 v[164:167], v159 offset:2048
	ds_read_b128 v[168:171], v159 offset:3072
	v_add_u32_e32 v159, s33, v131
	ds_read_b128 v[172:175], v159
	ds_read_b128 v[176:179], v159 offset:1024
	ds_read_b128 v[182:185], v159 offset:2048
	ds_read_b128 v[186:189], v159 offset:3072
	s_add_u32 s14, s60, 0x40000
	s_addc_u32 s15, s61, 0
	s_mov_b32 m0, s63
	v_lshl_add_u64 v[234:235], s[14:15], 0, v[138:139]
	ds_read_b128 v[190:193], v157 offset:32768
	ds_read_b128 v[194:197], v157 offset:33792
	ds_read_b128 v[198:201], v157 offset:34816
	ds_read_b128 v[208:211], v157 offset:35840
	ds_read_b128 v[212:215], v157 offset:36864
	ds_read_b128 v[216:219], v157 offset:37888
	ds_read_b128 v[220:223], v157 offset:38912
	ds_read_b128 v[224:227], v157 offset:39936
	global_load_lds_dwordx4 v[234:235], off
	v_lshl_add_u64 v[234:235], s[14:15], 0, v[134:135]
	s_mov_b32 m0, s64
	s_nop 0
	global_load_lds_dwordx4 v[234:235], off
	s_waitcnt vmcnt(8)
	s_waitcnt lgkmcnt(0)
	s_barrier
	s_setprio 1
	s_waitcnt lgkmcnt(0)
	v_mfma_f32_16x16x32_bf16 v[124:127], v[148:151], v[190:193], v[124:127]
	v_mfma_f32_16x16x32_bf16 v[120:123], v[164:167], v[190:193], v[120:123]
	v_mfma_f32_16x16x32_bf16 v[108:111], v[148:151], v[198:201], v[108:111]
	v_mfma_f32_16x16x32_bf16 v[104:107], v[164:167], v[198:201], v[104:107]
	v_mfma_f32_16x16x32_bf16 v[92:95], v[148:151], v[212:215], v[92:95]
	v_mfma_f32_16x16x32_bf16 v[88:91], v[164:167], v[212:215], v[88:91]
	v_mfma_f32_16x16x32_bf16 v[76:79], v[148:151], v[220:223], v[76:79]
	v_mfma_f32_16x16x32_bf16 v[72:75], v[164:167], v[220:223], v[72:75]
	v_mfma_f32_16x16x32_bf16 v[124:127], v[160:163], v[194:197], v[124:127]
	v_mfma_f32_16x16x32_bf16 v[120:123], v[168:171], v[194:197], v[120:123]
	v_mfma_f32_16x16x32_bf16 v[108:111], v[160:163], v[208:211], v[108:111]
	v_mfma_f32_16x16x32_bf16 v[104:107], v[168:171], v[208:211], v[104:107]
	v_mfma_f32_16x16x32_bf16 v[92:95], v[160:163], v[216:219], v[92:95]
	v_mfma_f32_16x16x32_bf16 v[88:91], v[168:171], v[216:219], v[88:91]
	v_mfma_f32_16x16x32_bf16 v[76:79], v[160:163], v[224:227], v[76:79]
	v_mfma_f32_16x16x32_bf16 v[72:75], v[168:171], v[224:227], v[72:75]
	s_setprio 0
	s_setprio 1
	v_mfma_f32_16x16x32_bf16 v[116:119], v[172:175], v[190:193], v[116:119]
	v_mfma_f32_16x16x32_bf16 v[112:115], v[182:185], v[190:193], v[112:115]
	v_mfma_f32_16x16x32_bf16 v[100:103], v[172:175], v[198:201], v[100:103]
	v_mfma_f32_16x16x32_bf16 v[96:99], v[182:185], v[198:201], v[96:99]
	v_mfma_f32_16x16x32_bf16 v[84:87], v[172:175], v[212:215], v[84:87]
	v_mfma_f32_16x16x32_bf16 v[80:83], v[182:185], v[212:215], v[80:83]
	v_mfma_f32_16x16x32_bf16 v[68:71], v[172:175], v[220:223], v[68:71]
	v_mfma_f32_16x16x32_bf16 v[64:67], v[182:185], v[220:223], v[64:67]
	v_mfma_f32_16x16x32_bf16 v[116:119], v[176:179], v[194:197], v[116:119]
	v_mfma_f32_16x16x32_bf16 v[112:115], v[186:189], v[194:197], v[112:115]
	v_mfma_f32_16x16x32_bf16 v[100:103], v[176:179], v[208:211], v[100:103]
	v_mfma_f32_16x16x32_bf16 v[96:99], v[186:189], v[208:211], v[96:99]
	v_mfma_f32_16x16x32_bf16 v[84:87], v[176:179], v[216:219], v[84:87]
	v_mfma_f32_16x16x32_bf16 v[80:83], v[186:189], v[216:219], v[80:83]
	v_mfma_f32_16x16x32_bf16 v[68:71], v[176:179], v[224:227], v[68:71]
	v_mfma_f32_16x16x32_bf16 v[64:67], v[186:189], v[224:227], v[64:67]
	s_setprio 0
	s_barrier
; #define PG8_STAGE(bufoff, gbase, voff) do { _Pragma("unroll") for (int _i = 0; _i < 2; ++_i) \
;         __builtin_amdgcn_global_load_lds((const unsigned*)((const char*)(gbase) + (voff)[_i]), (PG8_LAS unsigned*)(lds + (bufoff) + ldsw + _i * 8192), 16, 0, 0); } while (0)
; #define PG8_LDA(dst, b, h) do { _Pragma("unroll") for (int m = 0; m < 4; ++m) _Pragma("unroll") for (int k = 0; k < 2; ++k) dst[m][k] = *(const PG8_LAS bf16x8*)(lds + PG8_SA(b, h) + aoff + m * 2048 + k * 1024); } while (0)
; #define PG8_MMA(ai, bj, At, Bt) do { __builtin_amdgcn_s_setprio(1); _Pragma("unroll") for (int m = 0; m < 4; ++m) _Pragma("unroll") for (int n = 0; n < 2; ++n) _Pragma("unroll") for (int k = 0; k < 2; ++k) \
;         acc[ai][bj][m][n] = __builtin_amdgcn_mfma_f32_16x16x32_bf16(Bt[n][k], At[m][k], acc[ai][bj][m][n], 0, 0, 0); __builtin_amdgcn_s_setprio(0); } while (0)
; #define PG8_WAIT_V(n) asm volatile("s_waitcnt vmcnt(" #n ")" ::: "memory")
; #define PG8_WAIT_L(n) asm volatile("s_waitcnt lgkmcnt(" #n ")" ::: "memory")
; #define PG8_BAR __builtin_amdgcn_s_barrier()
; #define PG8_SCHED __builtin_amdgcn_sched_barrier(0)
; template <class Epi, class Sched, bool ALIGN_EPI = false, bool SP2 = false>
; __device__ __forceinline__ void gemm_phase(PG8_LAS unsigned char* lds, const Gemm g, const Sched& S, const Epi& E) {
;     ...
;         for (int t = 0; t < nt; t += 2) {
;             const bool last = (t == nt - 2);
;             const char* a1 = cA + (size_t)(t + 1) * kstep;
;             const char* a2 = last ? nA : cA + (size_t)(t + 2) * kstep; const char* b2 = last ? nB : cB + (size_t)(t + 2) * kstep;
;     ...
;             PG8_LDA(At, 1, 1); PG8_STAGE(PG8_SB(1, 0), b3, voffB); PG8_STAGE(PG8_SB(1, 1), b3 + hstep, voffB); PG8_STAGE(PG8_SA(1, 0), a3, voffA);
;             PG8_WAIT_V(8); PG8_WAIT_L(0); PG8_BAR; PG8_MMA(1, 0, At, B0); PG8_MMA(1, 1, At, B1); PG8_BAR; PG8_SCHED;
	s_add_i32 s3, s3, s34
	v_lshl_add_u64 v[202:203], v[202:203], 0, s[38:39]
	s_mov_b32 m0, s3
	ds_read_b128 v[190:193], v157 offset:49152
	ds_read_b128 v[194:197], v157 offset:50176
	ds_read_b128 v[198:201], v157 offset:51200
	ds_read_b128 v[208:211], v157 offset:52224
	ds_read_b128 v[212:215], v157 offset:53248
	ds_read_b128 v[216:219], v157 offset:54272
	ds_read_b128 v[220:223], v157 offset:55296
	ds_read_b128 v[224:227], v157 offset:56320
	global_load_lds_dwordx4 v[202:203], off
	s_add_i32 m0, s3, 0x2000
	s_add_u32 s14, s58, 0x40080
	v_lshl_add_u64 v[202:203], v[228:229], 0, s[38:39]
	s_addc_u32 s15, s59, 0
	s_add_i32 s3, s33, s34
	global_load_lds_dwordx4 v[202:203], off
	v_lshl_add_u64 v[202:203], s[14:15], 0, v[136:137]
	s_mov_b32 m0, s3
	s_nop 0
	global_load_lds_dwordx4 v[202:203], off
	v_lshl_add_u64 v[202:203], s[14:15], 0, v[132:133]
	s_add_i32 m0, s3, 0x2000
	s_nop 0
	global_load_lds_dwordx4 v[202:203], off
	s_waitcnt vmcnt(6)
	s_waitcnt lgkmcnt(0)
	s_barrier
	s_setprio 1
	s_waitcnt lgkmcnt(0)
	v_mfma_f32_16x16x32_bf16 v[60:63], v[148:151], v[190:193], v[60:63]
	v_mfma_f32_16x16x32_bf16 v[56:59], v[164:167], v[190:193], v[56:59]
	v_mfma_f32_16x16x32_bf16 v[44:47], v[148:151], v[198:201], v[44:47]
	v_mfma_f32_16x16x32_bf16 v[40:43], v[164:167], v[198:201], v[40:43]
	v_mfma_f32_16x16x32_bf16 v[28:31], v[148:151], v[212:215], v[28:31]
	v_mfma_f32_16x16x32_bf16 v[24:27], v[164:167], v[212:215], v[24:27]
	v_lshl_add_u64 v[202:203], v[230:231], 0, s[38:39]
	s_mov_b32 m0, s66
	s_nop 0
	global_load_lds_dwordx4 v[202:203], off
	v_mfma_f32_16x16x32_bf16 v[12:15], v[148:151], v[220:223], v[12:15]
	v_mfma_f32_16x16x32_bf16 v[8:11], v[164:167], v[220:223], v[8:11]
	v_mfma_f32_16x16x32_bf16 v[60:63], v[160:163], v[194:197], v[60:63]
	v_mfma_f32_16x16x32_bf16 v[56:59], v[168:171], v[194:197], v[56:59]
	v_mfma_f32_16x16x32_bf16 v[44:47], v[160:163], v[208:211], v[44:47]
	v_mfma_f32_16x16x32_bf16 v[40:43], v[168:171], v[208:211], v[40:43]
	v_mfma_f32_16x16x32_bf16 v[28:31], v[160:163], v[216:219], v[28:31]
	v_mfma_f32_16x16x32_bf16 v[24:27], v[168:171], v[216:219], v[24:27]
	v_mfma_f32_16x16x32_bf16 v[12:15], v[160:163], v[224:227], v[12:15]
	v_mfma_f32_16x16x32_bf16 v[8:11], v[168:171], v[224:227], v[8:11]
	s_setprio 0
	s_setprio 1
	v_mfma_f32_16x16x32_bf16 v[52:55], v[172:175], v[190:193], v[52:55]
	v_mfma_f32_16x16x32_bf16 v[48:51], v[182:185], v[190:193], v[48:51]
	v_lshl_add_u64 v[202:203], v[232:233], 0, s[38:39]
	s_mov_b32 m0, s67
	s_nop 0
	global_load_lds_dwordx4 v[202:203], off
	v_mfma_f32_16x16x32_bf16 v[36:39], v[172:175], v[198:201], v[36:39]
	v_mfma_f32_16x16x32_bf16 v[32:35], v[182:185], v[198:201], v[32:35]
	v_mfma_f32_16x16x32_bf16 v[20:23], v[172:175], v[212:215], v[20:23]
	v_mfma_f32_16x16x32_bf16 v[16:19], v[182:185], v[212:215], v[16:19]
	v_mfma_f32_16x16x32_bf16 v[4:7], v[172:175], v[220:223], v[4:7]
	v_mfma_f32_16x16x32_bf16 v[0:3], v[182:185], v[220:223], v[0:3]
	v_mfma_f32_16x16x32_bf16 v[52:55], v[176:179], v[194:197], v[52:55]
	v_mfma_f32_16x16x32_bf16 v[48:51], v[186:189], v[194:197], v[48:51]
	v_mfma_f32_16x16x32_bf16 v[36:39], v[176:179], v[208:211], v[36:39]
	v_mfma_f32_16x16x32_bf16 v[32:35], v[186:189], v[208:211], v[32:35]
	v_mfma_f32_16x16x32_bf16 v[20:23], v[176:179], v[216:219], v[20:23]
	v_mfma_f32_16x16x32_bf16 v[16:19], v[186:189], v[216:219], v[16:19]
	v_mfma_f32_16x16x32_bf16 v[4:7], v[176:179], v[224:227], v[4:7]
	v_mfma_f32_16x16x32_bf16 v[0:3], v[186:189], v[224:227], v[0:3]
	s_setprio 0
	s_barrier
	s_add_i32 s86, s86, 2
	s_add_u32 s56, s56, 0x100
	s_addc_u32 s57, s57, 0
	s_add_u32 s84, s84, 0x100
	s_addc_u32 s85, s85, 0
	s_cmp_gt_u32 s86, 13
	s_cbranch_scc0 .LBB0_738
	s_and_b64 vcc, exec, s[44:45]
	s_cbranch_vccz .LBB0_741
	s_barrier

; #define PG8_STAGE(bufoff, gbase, voff) do { _Pragma("unroll") for (int _i = 0; _i < 2; ++_i) \
;         __builtin_amdgcn_global_load_lds((const unsigned*)((const char*)(gbase) + (voff)[_i]), (PG8_LAS unsigned*)(lds + (bufoff) + ldsw + _i * 8192), 16, 0, 0); } while (0)
; #define PG8_LDA(dst, b, h) do { _Pragma("unroll") for (int m = 0; m < 4; ++m) _Pragma("unroll") for (int k = 0; k < 2; ++k) dst[m][k] = *(const PG8_LAS bf16x8*)(lds + PG8_SA(b, h) + aoff + m * 2048 + k * 1024); } while (0)
; #define PG8_LDB(dst, b, h) do { _Pragma("unroll") for (int n = 0; n < 2; ++n) _Pragma("unroll") for (int k = 0; k < 2; ++k) dst[n][k] = *(const PG8_LAS bf16x8*)(lds + PG8_SB(b, h) + boff + n * 2048 + k * 1024); } while (0)
; #define PG8_MMA(ai, bj, At, Bt) do { __builtin_amdgcn_s_setprio(1); _Pragma("unroll") for (int m = 0; m < 4; ++m) _Pragma("unroll") for (int n = 0; n < 2; ++n) _Pragma("unroll") for (int k = 0; k < 2; ++k) \
;         acc[ai][bj][m][n] = __builtin_amdgcn_mfma_f32_16x16x32_bf16(Bt[n][k], At[m][k], acc[ai][bj][m][n], 0, 0, 0); __builtin_amdgcn_s_setprio(0); } while (0)
; #define PG8_BAR __builtin_amdgcn_s_barrier()
; template <class Epi, class Sched, bool ALIGN_EPI = false, bool SP2 = false>
; __device__ __forceinline__ void gemm_phase(PG8_LAS unsigned char* lds, const Gemm g, const Sched& S, const Epi& E) {
;     ...
;             PG8_LDB(B0, 0, 0); PG8_LDB(B1, 0, 1); PG8_SCHED; PG8_LDA(At, 0, 0); PG8_STAGE(PG8_SA(1, 1), a1 + hstep, voffA);
;             PG8_WAIT_V(8); PG8_WAIT_L(0); PG8_BAR; PG8_MMA(0, 0, At, B0); PG8_MMA(0, 1, At, B1); PG8_BAR; PG8_SCHED;
;             PG8_LDA(At, 0, 1); PG8_STAGE(PG8_SB(0, 0), b2, voffB); PG8_STAGE(PG8_SB(0, 1), b2 + hstep, voffB); PG8_STAGE(PG8_SA(0, 0), a2, voffA);
;             PG8_WAIT_V(8); PG8_WAIT_L(0); PG8_BAR; PG8_MMA(1, 0, At, B0); PG8_MMA(1, 1, At, B1); PG8_BAR; PG8_SCHED;
; template <int l> __device__ __forceinline__ void layer_body(const Args& args, LAS unsigned char* lds, const XcdBarrier& bar) {
;     ...
;         GSYNC();
;         for (int rep = 0; rep < NREP(8); ++rep) { const bool fin = rep == NREP(8) - 1; pg8::Gemm g{XO, W + WO_XO + (size_t)l * D * XAW, T, D, XAW}; pg8::StaticOrder S; S.init(T, D, G, bx);
;           pg8::EpiResid E{nullptr, XB, fin ? ssl + 3 * TS16 : SS + 9 * TS16, fin ? 1.0f : 0.0f};
;           pg8::gemm_phase<pg8::EpiResid, pg8::StaticOrder, true, true>(lds, g, S, E); }
.LBB0_872:
	s_ashr_i32 s49, s48, 31
	s_lshl_b64 s[50:51], s[48:49], 18
	s_add_u32 s50, s92, s50
	s_addc_u32 s51, s93, s51
	s_and_b64 s[52:53], s[10:11], exec
	s_cselect_b32 s49, s51, s59
	s_cselect_b32 s55, s50, s58
	s_ashr_i32 s45, s44, 31
	s_lshl_b64 s[52:53], s[44:45], 18
	s_add_u32 s52, s76, s52
	s_addc_u32 s53, s77, s53
	s_and_b64 s[62:63], s[10:11], exec
	s_cselect_b32 s45, s53, s61
	s_cselect_b32 s84, s52, s60
	s_add_u32 s58, s58, 0x20080
	s_addc_u32 s59, s59, 0
	s_add_u32 s85, s60, 0x100
	s_addc_u32 s86, s61, 0
	s_mov_b32 s87, -2
	s_waitcnt lgkmcnt(0)
	ds_read_b128 v[144:147], v151
	ds_read_b128 v[156:159], v151 offset:1024
	ds_read_b128 v[160:163], v151 offset:2048
	ds_read_b128 v[164:167], v151 offset:3072
	ds_read_b128 v[168:171], v152
	ds_read_b128 v[172:175], v152 offset:1024
	ds_read_b128 v[176:179], v152 offset:2048
	ds_read_b128 v[182:185], v152 offset:3072
	s_add_u32 s3, s58, 0xfffe0080
	s_addc_u32 s33, s59, -1
	s_cmp_eq_u32 s87, 4
	s_cselect_b32 s63, s49, s33
	s_cselect_b32 s62, s55, s3
	s_cselect_b32 s61, s45, s86
	s_cselect_b32 s60, s84, s85
	v_lshl_add_u64 v[202:203], s[58:59], 0, v[136:137]
	s_add_i32 m0, s15, 0xc000
	ds_read_b128 v[186:189], v153
	ds_read_b128 v[190:193], v153 offset:1024
	ds_read_b128 v[194:197], v153 offset:2048
	ds_read_b128 v[198:201], v153 offset:3072
	ds_read_b128 v[208:211], v153 offset:4096
	ds_read_b128 v[212:215], v153 offset:5120
	ds_read_b128 v[216:219], v153 offset:6144
	ds_read_b128 v[220:223], v153 offset:7168
	global_load_lds_dwordx4 v[202:203], off
	v_lshl_add_u64 v[202:203], s[58:59], 0, v[138:139]
	s_add_i32 m0, s15, 0xe000
	s_nop 0
	global_load_lds_dwordx4 v[202:203], off
	s_waitcnt vmcnt(8)
	s_waitcnt lgkmcnt(0)
	s_barrier
	s_setprio 1
	s_waitcnt lgkmcnt(0)
	v_mfma_f32_16x16x32_bf16 v[124:127], v[144:147], v[186:189], 0
	v_mfma_f32_16x16x32_bf16 v[120:123], v[160:163], v[186:189], 0
	v_mfma_f32_16x16x32_bf16 v[108:111], v[144:147], v[194:197], 0
	v_mfma_f32_16x16x32_bf16 v[104:107], v[160:163], v[194:197], 0
	v_mfma_f32_16x16x32_bf16 v[92:95], v[144:147], v[208:211], 0
	v_mfma_f32_16x16x32_bf16 v[88:91], v[160:163], v[208:211], 0
	v_mfma_f32_16x16x32_bf16 v[76:79], v[144:147], v[216:219], 0
	v_mfma_f32_16x16x32_bf16 v[72:75], v[160:163], v[216:219], 0
	v_mfma_f32_16x16x32_bf16 v[124:127], v[156:159], v[190:193], v[124:127]
	v_mfma_f32_16x16x32_bf16 v[120:123], v[164:167], v[190:193], v[120:123]
	v_mfma_f32_16x16x32_bf16 v[108:111], v[156:159], v[198:201], v[108:111]
	v_mfma_f32_16x16x32_bf16 v[104:107], v[164:167], v[198:201], v[104:107]
	v_mfma_f32_16x16x32_bf16 v[92:95], v[156:159], v[212:215], v[92:95]
	v_mfma_f32_16x16x32_bf16 v[88:91], v[164:167], v[212:215], v[88:91]
	v_mfma_f32_16x16x32_bf16 v[76:79], v[156:159], v[220:223], v[76:79]
	v_mfma_f32_16x16x32_bf16 v[72:75], v[164:167], v[220:223], v[72:75]
	s_setprio 0
	s_setprio 1
	v_mfma_f32_16x16x32_bf16 v[116:119], v[168:171], v[186:189], 0
	v_mfma_f32_16x16x32_bf16 v[112:115], v[176:179], v[186:189], 0
	v_mfma_f32_16x16x32_bf16 v[100:103], v[168:171], v[194:197], 0
	v_mfma_f32_16x16x32_bf16 v[96:99], v[176:179], v[194:197], 0
	v_mfma_f32_16x16x32_bf16 v[84:87], v[168:171], v[208:211], 0
	v_mfma_f32_16x16x32_bf16 v[80:83], v[176:179], v[208:211], 0
	v_mfma_f32_16x16x32_bf16 v[68:71], v[168:171], v[216:219], 0
	v_mfma_f32_16x16x32_bf16 v[64:67], v[176:179], v[216:219], 0
	v_mfma_f32_16x16x32_bf16 v[116:119], v[172:175], v[190:193], v[116:119]
	v_mfma_f32_16x16x32_bf16 v[112:115], v[182:185], v[190:193], v[112:115]
	v_mfma_f32_16x16x32_bf16 v[100:103], v[172:175], v[198:201], v[100:103]
	v_mfma_f32_16x16x32_bf16 v[96:99], v[182:185], v[198:201], v[96:99]
	v_mfma_f32_16x16x32_bf16 v[84:87], v[172:175], v[212:215], v[84:87]
	v_mfma_f32_16x16x32_bf16 v[80:83], v[182:185], v[212:215], v[80:83]
	v_mfma_f32_16x16x32_bf16 v[68:71], v[172:175], v[220:223], v[68:71]
	v_mfma_f32_16x16x32_bf16 v[64:67], v[182:185], v[220:223], v[64:67]
	s_setprio 0
	s_barrier
	s_add_i32 s3, s74, s14
	v_lshl_add_u64 v[202:203], s[60:61], 0, v[130:131]
	s_mov_b32 m0, s3
	ds_read_b128 v[186:189], v153 offset:16384
	ds_read_b128 v[190:193], v153 offset:17408
	ds_read_b128 v[194:197], v153 offset:18432
	ds_read_b128 v[198:201], v153 offset:19456
	ds_read_b128 v[208:211], v153 offset:20480
	ds_read_b128 v[212:215], v153 offset:21504
	ds_read_b128 v[216:219], v153 offset:22528
	ds_read_b128 v[220:223], v153 offset:23552
	global_load_lds_dwordx4 v[202:203], off
	s_add_i32 m0, s3, 0x2000
	s_add_u32 s78, s60, 0x20000
	v_lshl_add_u64 v[224:225], s[60:61], 0, v[134:135]
	s_addc_u32 s79, s61, 0
	s_add_i32 s3, s75, s14
	global_load_lds_dwordx4 v[224:225], off
	v_lshl_add_u64 v[226:227], s[78:79], 0, v[130:131]
	s_mov_b32 m0, s3
	v_lshl_add_u64 v[228:229], s[62:63], 0, v[132:133]
	global_load_lds_dwordx4 v[226:227], off
	v_lshl_add_u64 v[226:227], s[78:79], 0, v[134:135]
	s_add_i32 m0, s3, 0x2000
	s_nop 0
	global_load_lds_dwordx4 v[226:227], off
	s_waitcnt vmcnt(6)
	s_waitcnt lgkmcnt(0)
	s_barrier
; #define PG8_STAGE(bufoff, gbase, voff) do { _Pragma("unroll") for (int _i = 0; _i < 2; ++_i) \
;         __builtin_amdgcn_global_load_lds((const unsigned*)((const char*)(gbase) + (voff)[_i]), (PG8_LAS unsigned*)(lds + (bufoff) + ldsw + _i * 8192), 16, 0, 0); } while (0)
; #define PG8_LDA(dst, b, h) do { _Pragma("unroll") for (int m = 0; m < 4; ++m) _Pragma("unroll") for (int k = 0; k < 2; ++k) dst[m][k] = *(const PG8_LAS bf16x8*)(lds + PG8_SA(b, h) + aoff + m * 2048 + k * 1024); } while (0)
; #define PG8_LDB(dst, b, h) do { _Pragma("unroll") for (int n = 0; n < 2; ++n) _Pragma("unroll") for (int k = 0; k < 2; ++k) dst[n][k] = *(const PG8_LAS bf16x8*)(lds + PG8_SB(b, h) + boff + n * 2048 + k * 1024); } while (0)
; #define PG8_MMA(ai, bj, At, Bt) do { __builtin_amdgcn_s_setprio(1); _Pragma("unroll") for (int m = 0; m < 4; ++m) _Pragma("unroll") for (int n = 0; n < 2; ++n) _Pragma("unroll") for (int k = 0; k < 2; ++k) \
;         acc[ai][bj][m][n] = __builtin_amdgcn_mfma_f32_16x16x32_bf16(Bt[n][k], At[m][k], acc[ai][bj][m][n], 0, 0, 0); __builtin_amdgcn_s_setprio(0); } while (0)
; #define PG8_WAIT_V(n) asm volatile("s_waitcnt vmcnt(" #n ")" ::: "memory")
; #define PG8_WAIT_L(n) asm volatile("s_waitcnt lgkmcnt(" #n ")" ::: "memory")
; #define PG8_BAR __builtin_amdgcn_s_barrier()
; #define PG8_SCHED __builtin_amdgcn_sched_barrier(0)
; template <class Epi, class Sched, bool ALIGN_EPI = false, bool SP2 = false>
; __device__ __forceinline__ void gemm_phase(PG8_LAS unsigned char* lds, const Gemm g, const Sched& S, const Epi& E) {
;     ...
;             PG8_WAIT_V(8); PG8_WAIT_L(0); PG8_BAR; PG8_MMA(1, 0, At, B0); PG8_MMA(1, 1, At, B1); PG8_BAR; PG8_SCHED;
;             PG8_LDB(B0, 1, 0); PG8_LDB(B1, 1, 1); PG8_SCHED; PG8_LDA(At, 1, 0); PG8_STAGE(PG8_SA(0, 1), a2 + hstep, voffA);
;             PG8_WAIT_V(8); PG8_WAIT_L(0); PG8_BAR; PG8_MMA(0, 0, At, B0); PG8_MMA(0, 1, At, B1); PG8_BAR; PG8_SCHED;
	s_setprio 1
	s_waitcnt lgkmcnt(0)
	v_mfma_f32_16x16x32_bf16 v[60:63], v[144:147], v[186:189], 0
	v_mfma_f32_16x16x32_bf16 v[56:59], v[160:163], v[186:189], 0
	v_mfma_f32_16x16x32_bf16 v[44:47], v[144:147], v[194:197], 0
	v_mfma_f32_16x16x32_bf16 v[40:43], v[160:163], v[194:197], 0
	v_mfma_f32_16x16x32_bf16 v[28:31], v[144:147], v[208:211], 0
	v_mfma_f32_16x16x32_bf16 v[24:27], v[160:163], v[208:211], 0
	v_lshl_add_u64 v[226:227], s[62:63], 0, v[128:129]
	s_mov_b32 m0, s15
	s_nop 0
	global_load_lds_dwordx4 v[226:227], off
	v_mfma_f32_16x16x32_bf16 v[12:15], v[144:147], v[216:219], 0
	v_mfma_f32_16x16x32_bf16 v[8:11], v[160:163], v[216:219], 0
	v_mfma_f32_16x16x32_bf16 v[60:63], v[156:159], v[190:193], v[60:63]
	v_mfma_f32_16x16x32_bf16 v[56:59], v[164:167], v[190:193], v[56:59]
	v_mfma_f32_16x16x32_bf16 v[44:47], v[156:159], v[198:201], v[44:47]
	v_mfma_f32_16x16x32_bf16 v[40:43], v[164:167], v[198:201], v[40:43]
	v_mfma_f32_16x16x32_bf16 v[28:31], v[156:159], v[212:215], v[28:31]
	v_mfma_f32_16x16x32_bf16 v[24:27], v[164:167], v[212:215], v[24:27]
	v_mfma_f32_16x16x32_bf16 v[12:15], v[156:159], v[220:223], v[12:15]
	v_mfma_f32_16x16x32_bf16 v[8:11], v[164:167], v[220:223], v[8:11]
	s_setprio 0
	s_setprio 1
	v_mfma_f32_16x16x32_bf16 v[52:55], v[168:171], v[186:189], 0
	v_mfma_f32_16x16x32_bf16 v[48:51], v[176:179], v[186:189], 0
	s_mov_b32 m0, s34
	s_nop 0
	global_load_lds_dwordx4 v[228:229], off
	v_mfma_f32_16x16x32_bf16 v[36:39], v[168:171], v[194:197], 0
	v_mfma_f32_16x16x32_bf16 v[32:35], v[176:179], v[194:197], 0
	v_mfma_f32_16x16x32_bf16 v[20:23], v[168:171], v[208:211], 0
	v_mfma_f32_16x16x32_bf16 v[16:19], v[176:179], v[208:211], 0
	v_mfma_f32_16x16x32_bf16 v[4:7], v[168:171], v[216:219], 0
	v_mfma_f32_16x16x32_bf16 v[0:3], v[176:179], v[216:219], 0
	v_mfma_f32_16x16x32_bf16 v[52:55], v[172:175], v[190:193], v[52:55]
	v_mfma_f32_16x16x32_bf16 v[48:51], v[182:185], v[190:193], v[48:51]
	v_mfma_f32_16x16x32_bf16 v[36:39], v[172:175], v[198:201], v[36:39]
	v_mfma_f32_16x16x32_bf16 v[32:35], v[182:185], v[198:201], v[32:35]
	v_mfma_f32_16x16x32_bf16 v[20:23], v[172:175], v[212:215], v[20:23]
	v_mfma_f32_16x16x32_bf16 v[16:19], v[182:185], v[212:215], v[16:19]
	v_mfma_f32_16x16x32_bf16 v[4:7], v[172:175], v[220:223], v[4:7]
	v_mfma_f32_16x16x32_bf16 v[0:3], v[182:185], v[220:223], v[0:3]
	s_setprio 0
	s_barrier
	s_add_i32 s3, 0, 0x18000
	v_add_u32_e32 v155, s3, v149
	s_add_i32 s33, 0, 0x1c000
	ds_read_b128 v[144:147], v155
	ds_read_b128 v[156:159], v155 offset:1024
	ds_read_b128 v[160:163], v155 offset:2048
	ds_read_b128 v[164:167], v155 offset:3072
	v_add_u32_e32 v155, s33, v149
	ds_read_b128 v[168:171], v155
	ds_read_b128 v[172:175], v155 offset:1024
	ds_read_b128 v[176:179], v155 offset:2048
	ds_read_b128 v[182:185], v155 offset:3072
	s_add_u32 s62, s62, 0x20000
	s_addc_u32 s63, s63, 0
	s_mov_b32 m0, s57
	v_lshl_add_u64 v[230:231], s[62:63], 0, v[128:129]
	ds_read_b128 v[186:189], v153 offset:32768
	ds_read_b128 v[190:193], v153 offset:33792
	ds_read_b128 v[194:197], v153 offset:34816
	ds_read_b128 v[198:201], v153 offset:35840
	ds_read_b128 v[208:211], v153 offset:36864
	ds_read_b128 v[212:215], v153 offset:37888
	ds_read_b128 v[216:219], v153 offset:38912
	ds_read_b128 v[220:223], v153 offset:39936
	global_load_lds_dwordx4 v[230:231], off
	v_lshl_add_u64 v[230:231], s[62:63], 0, v[132:133]
	s_mov_b32 m0, s64
	s_nop 0
	global_load_lds_dwordx4 v[230:231], off
	s_waitcnt vmcnt(8)
	s_waitcnt lgkmcnt(0)
	s_barrier
	s_setprio 1
	s_waitcnt lgkmcnt(0)
	v_mfma_f32_16x16x32_bf16 v[124:127], v[144:147], v[186:189], v[124:127]
	v_mfma_f32_16x16x32_bf16 v[120:123], v[160:163], v[186:189], v[120:123]
	v_mfma_f32_16x16x32_bf16 v[108:111], v[144:147], v[194:197], v[108:111]
	v_mfma_f32_16x16x32_bf16 v[104:107], v[160:163], v[194:197], v[104:107]
	v_mfma_f32_16x16x32_bf16 v[92:95], v[144:147], v[208:211], v[92:95]
	v_mfma_f32_16x16x32_bf16 v[88:91], v[160:163], v[208:211], v[88:91]
	v_mfma_f32_16x16x32_bf16 v[76:79], v[144:147], v[216:219], v[76:79]
	v_mfma_f32_16x16x32_bf16 v[72:75], v[160:163], v[216:219], v[72:75]
	v_mfma_f32_16x16x32_bf16 v[124:127], v[156:159], v[190:193], v[124:127]
	v_mfma_f32_16x16x32_bf16 v[120:123], v[164:167], v[190:193], v[120:123]
	v_mfma_f32_16x16x32_bf16 v[108:111], v[156:159], v[198:201], v[108:111]
	v_mfma_f32_16x16x32_bf16 v[104:107], v[164:167], v[198:201], v[104:107]
	v_mfma_f32_16x16x32_bf16 v[92:95], v[156:159], v[212:215], v[92:95]
	v_mfma_f32_16x16x32_bf16 v[88:91], v[164:167], v[212:215], v[88:91]
	v_mfma_f32_16x16x32_bf16 v[76:79], v[156:159], v[220:223], v[76:79]
	v_mfma_f32_16x16x32_bf16 v[72:75], v[164:167], v[220:223], v[72:75]
	s_setprio 0
	s_setprio 1
	v_mfma_f32_16x16x32_bf16 v[116:119], v[168:171], v[186:189], v[116:119]
	v_mfma_f32_16x16x32_bf16 v[112:115], v[176:179], v[186:189], v[112:115]
	v_mfma_f32_16x16x32_bf16 v[100:103], v[168:171], v[194:197], v[100:103]
	v_mfma_f32_16x16x32_bf16 v[96:99], v[176:179], v[194:197], v[96:99]
	v_mfma_f32_16x16x32_bf16 v[84:87], v[168:171], v[208:211], v[84:87]
	v_mfma_f32_16x16x32_bf16 v[80:83], v[176:179], v[208:211], v[80:83]
	v_mfma_f32_16x16x32_bf16 v[68:71], v[168:171], v[216:219], v[68:71]
	v_mfma_f32_16x16x32_bf16 v[64:67], v[176:179], v[216:219], v[64:67]
	v_mfma_f32_16x16x32_bf16 v[116:119], v[172:175], v[190:193], v[116:119]
	v_mfma_f32_16x16x32_bf16 v[112:115], v[182:185], v[190:193], v[112:115]
	v_mfma_f32_16x16x32_bf16 v[100:103], v[172:175], v[198:201], v[100:103]
	v_mfma_f32_16x16x32_bf16 v[96:99], v[182:185], v[198:201], v[96:99]
	v_mfma_f32_16x16x32_bf16 v[84:87], v[172:175], v[212:215], v[84:87]
	v_mfma_f32_16x16x32_bf16 v[80:83], v[182:185], v[212:215], v[80:83]
	v_mfma_f32_16x16x32_bf16 v[68:71], v[172:175], v[220:223], v[68:71]
	v_mfma_f32_16x16x32_bf16 v[64:67], v[182:185], v[220:223], v[64:67]
	s_setprio 0
	s_barrier
; #define PG8_STAGE(bufoff, gbase, voff) do { _Pragma("unroll") for (int _i = 0; _i < 2; ++_i) \
;         __builtin_amdgcn_global_load_lds((const unsigned*)((const char*)(gbase) + (voff)[_i]), (PG8_LAS unsigned*)(lds + (bufoff) + ldsw + _i * 8192), 16, 0, 0); } while (0)
; #define PG8_LDA(dst, b, h) do { _Pragma("unroll") for (int m = 0; m < 4; ++m) _Pragma("unroll") for (int k = 0; k < 2; ++k) dst[m][k] = *(const PG8_LAS bf16x8*)(lds + PG8_SA(b, h) + aoff + m * 2048 + k * 1024); } while (0)
; #define PG8_LDB(dst, b, h) do { _Pragma("unroll") for (int n = 0; n < 2; ++n) _Pragma("unroll") for (int k = 0; k < 2; ++k) dst[n][k] = *(const PG8_LAS bf16x8*)(lds + PG8_SB(b, h) + boff + n * 2048 + k * 1024); } while (0)
; #define PG8_MMA(ai, bj, At, Bt) do { __builtin_amdgcn_s_setprio(1); _Pragma("unroll") for (int m = 0; m < 4; ++m) _Pragma("unroll") for (int n = 0; n < 2; ++n) _Pragma("unroll") for (int k = 0; k < 2; ++k) \
;         acc[ai][bj][m][n] = __builtin_amdgcn_mfma_f32_16x16x32_bf16(Bt[n][k], At[m][k], acc[ai][bj][m][n], 0, 0, 0); __builtin_amdgcn_s_setprio(0); } while (0)
; #define PG8_WAIT_V(n) asm volatile("s_waitcnt vmcnt(" #n ")" ::: "memory")
; #define PG8_WAIT_L(n) asm volatile("s_waitcnt lgkmcnt(" #n ")" ::: "memory")
; #define PG8_BAR __builtin_amdgcn_s_barrier()
; #define PG8_SCHED __builtin_amdgcn_sched_barrier(0)
; template <class Epi, class Sched, bool ALIGN_EPI = false, bool SP2 = false>
; __device__ __forceinline__ void gemm_phase(PG8_LAS unsigned char* lds, const Gemm g, const Sched& S, const Epi& E) {
;     ...
;             PG8_LDB(B0, 0, 0); PG8_LDB(B1, 0, 1); PG8_SCHED; PG8_LDA(At, 0, 0); PG8_STAGE(PG8_SA(1, 1), a1 + hstep, voffA);
;             PG8_WAIT_V(8); PG8_WAIT_L(0); PG8_BAR; PG8_MMA(0, 0, At, B0); PG8_MMA(0, 1, At, B1); PG8_BAR; PG8_SCHED;
;     ...
;             PG8_LDA(At, 1, 1); PG8_STAGE(PG8_SB(1, 0), b3, voffB); PG8_STAGE(PG8_SB(1, 1), b3 + hstep, voffB); PG8_STAGE(PG8_SA(1, 0), a3, voffA);
;             PG8_WAIT_V(8); PG8_WAIT_L(0); PG8_BAR; PG8_MMA(1, 0, At, B0); PG8_MMA(1, 1, At, B1); PG8_BAR; PG8_SCHED;
	s_add_i32 s3, s3, s14
	v_lshl_add_u64 v[202:203], v[202:203], 0, s[38:39]
	s_mov_b32 m0, s3
	ds_read_b128 v[186:189], v153 offset:49152
	ds_read_b128 v[190:193], v153 offset:50176
	ds_read_b128 v[194:197], v153 offset:51200
	ds_read_b128 v[198:201], v153 offset:52224
	ds_read_b128 v[208:211], v153 offset:53248
	ds_read_b128 v[212:215], v153 offset:54272
	ds_read_b128 v[216:219], v153 offset:55296
	ds_read_b128 v[220:223], v153 offset:56320
	global_load_lds_dwordx4 v[202:203], off
	s_add_i32 m0, s3, 0x2000
	s_add_u32 s60, s60, 0x20080
	v_lshl_add_u64 v[202:203], v[224:225], 0, s[38:39]
	s_addc_u32 s61, s61, 0
	s_add_i32 s3, s33, s14
	global_load_lds_dwordx4 v[202:203], off
	v_lshl_add_u64 v[202:203], s[60:61], 0, v[130:131]
	s_mov_b32 m0, s3
	s_nop 0
	global_load_lds_dwordx4 v[202:203], off
	v_lshl_add_u64 v[202:203], s[60:61], 0, v[134:135]
	s_add_i32 m0, s3, 0x2000
	s_nop 0
	global_load_lds_dwordx4 v[202:203], off
	s_waitcnt vmcnt(6)
	s_waitcnt lgkmcnt(0)
	s_barrier
	s_setprio 1
	s_waitcnt lgkmcnt(0)
	v_mfma_f32_16x16x32_bf16 v[60:63], v[144:147], v[186:189], v[60:63]
	v_mfma_f32_16x16x32_bf16 v[56:59], v[160:163], v[186:189], v[56:59]
	v_mfma_f32_16x16x32_bf16 v[44:47], v[144:147], v[194:197], v[44:47]
	v_mfma_f32_16x16x32_bf16 v[40:43], v[160:163], v[194:197], v[40:43]
	v_mfma_f32_16x16x32_bf16 v[28:31], v[144:147], v[208:211], v[28:31]
	v_mfma_f32_16x16x32_bf16 v[24:27], v[160:163], v[208:211], v[24:27]
	v_lshl_add_u64 v[202:203], v[226:227], 0, s[38:39]
	s_mov_b32 m0, s66
	s_nop 0
	global_load_lds_dwordx4 v[202:203], off
	v_mfma_f32_16x16x32_bf16 v[12:15], v[144:147], v[216:219], v[12:15]
	v_mfma_f32_16x16x32_bf16 v[8:11], v[160:163], v[216:219], v[8:11]
	v_mfma_f32_16x16x32_bf16 v[60:63], v[156:159], v[190:193], v[60:63]
	v_mfma_f32_16x16x32_bf16 v[56:59], v[164:167], v[190:193], v[56:59]
	v_mfma_f32_16x16x32_bf16 v[44:47], v[156:159], v[198:201], v[44:47]
	v_mfma_f32_16x16x32_bf16 v[40:43], v[164:167], v[198:201], v[40:43]
	v_mfma_f32_16x16x32_bf16 v[28:31], v[156:159], v[212:215], v[28:31]
	v_mfma_f32_16x16x32_bf16 v[24:27], v[164:167], v[212:215], v[24:27]
	v_mfma_f32_16x16x32_bf16 v[12:15], v[156:159], v[220:223], v[12:15]
	v_mfma_f32_16x16x32_bf16 v[8:11], v[164:167], v[220:223], v[8:11]
	s_setprio 0
	s_setprio 1
	v_mfma_f32_16x16x32_bf16 v[52:55], v[168:171], v[186:189], v[52:55]
	v_mfma_f32_16x16x32_bf16 v[48:51], v[176:179], v[186:189], v[48:51]
	v_lshl_add_u64 v[202:203], v[228:229], 0, s[38:39]
	s_mov_b32 m0, s67
	s_nop 0
	global_load_lds_dwordx4 v[202:203], off
	v_mfma_f32_16x16x32_bf16 v[36:39], v[168:171], v[194:197], v[36:39]
	v_mfma_f32_16x16x32_bf16 v[32:35], v[176:179], v[194:197], v[32:35]
	v_mfma_f32_16x16x32_bf16 v[20:23], v[168:171], v[208:211], v[20:23]
	v_mfma_f32_16x16x32_bf16 v[16:19], v[176:179], v[208:211], v[16:19]
	v_mfma_f32_16x16x32_bf16 v[4:7], v[168:171], v[216:219], v[4:7]
	v_mfma_f32_16x16x32_bf16 v[0:3], v[176:179], v[216:219], v[0:3]
	v_mfma_f32_16x16x32_bf16 v[52:55], v[172:175], v[190:193], v[52:55]
	v_mfma_f32_16x16x32_bf16 v[48:51], v[182:185], v[190:193], v[48:51]
	v_mfma_f32_16x16x32_bf16 v[36:39], v[172:175], v[198:201], v[36:39]
	v_mfma_f32_16x16x32_bf16 v[32:35], v[182:185], v[198:201], v[32:35]
	v_mfma_f32_16x16x32_bf16 v[20:23], v[172:175], v[212:215], v[20:23]
	v_mfma_f32_16x16x32_bf16 v[16:19], v[182:185], v[212:215], v[16:19]
	v_mfma_f32_16x16x32_bf16 v[4:7], v[172:175], v[220:223], v[4:7]
	v_mfma_f32_16x16x32_bf16 v[0:3], v[182:185], v[220:223], v[0:3]
	s_setprio 0
	s_barrier
	s_add_i32 s87, s87, 2
	s_add_u32 s58, s58, 0x100
	s_addc_u32 s59, s59, 0
	s_add_u32 s85, s85, 0x100
	s_addc_u32 s86, s86, 0
.LBB0_873:
	ds_read_b128 v[144:147], v151
	ds_read_b128 v[156:159], v151 offset:1024
	ds_read_b128 v[160:163], v151 offset:2048
	ds_read_b128 v[164:167], v151 offset:3072
	ds_read_b128 v[168:171], v152
	ds_read_b128 v[172:175], v152 offset:1024
	ds_read_b128 v[176:179], v152 offset:2048
	ds_read_b128 v[182:185], v152 offset:3072
	s_add_u32 s3, s58, 0xfffe0080
	s_addc_u32 s33, s59, -1
	s_cmp_eq_u32 s87, 4
	s_cselect_b32 s63, s49, s33
	s_cselect_b32 s62, s55, s3
	s_cselect_b32 s61, s45, s86
	s_cselect_b32 s60, s84, s85
	v_lshl_add_u64 v[202:203], s[58:59], 0, v[136:137]
	s_add_i32 m0, s15, 0xc000
	ds_read_b128 v[186:189], v153
	ds_read_b128 v[190:193], v153 offset:1024
	ds_read_b128 v[194:197], v153 offset:2048
	ds_read_b128 v[198:201], v153 offset:3072
	ds_read_b128 v[208:211], v153 offset:4096
	ds_read_b128 v[212:215], v153 offset:5120
	ds_read_b128 v[216:219], v153 offset:6144
	ds_read_b128 v[220:223], v153 offset:7168
	global_load_lds_dwordx4 v[202:203], off
	v_lshl_add_u64 v[202:203], s[58:59], 0, v[138:139]
	s_add_i32 m0, s15, 0xe000
	s_nop 0
	global_load_lds_dwordx4 v[202:203], off
	s_waitcnt vmcnt(8)
	s_waitcnt lgkmcnt(0)
	s_barrier
; #define PG8_STAGE(bufoff, gbase, voff) do { _Pragma("unroll") for (int _i = 0; _i < 2; ++_i) \
;         __builtin_amdgcn_global_load_lds((const unsigned*)((const char*)(gbase) + (voff)[_i]), (PG8_LAS unsigned*)(lds + (bufoff) + ldsw + _i * 8192), 16, 0, 0); } while (0)
; #define PG8_LDA(dst, b, h) do { _Pragma("unroll") for (int m = 0; m < 4; ++m) _Pragma("unroll") for (int k = 0; k < 2; ++k) dst[m][k] = *(const PG8_LAS bf16x8*)(lds + PG8_SA(b, h) + aoff + m * 2048 + k * 1024); } while (0)
; #define PG8_MMA(ai, bj, At, Bt) do { __builtin_amdgcn_s_setprio(1); _Pragma("unroll") for (int m = 0; m < 4; ++m) _Pragma("unroll") for (int n = 0; n < 2; ++n) _Pragma("unroll") for (int k = 0; k < 2; ++k) \
;         acc[ai][bj][m][n] = __builtin_amdgcn_mfma_f32_16x16x32_bf16(Bt[n][k], At[m][k], acc[ai][bj][m][n], 0, 0, 0); __builtin_amdgcn_s_setprio(0); } while (0)
; #define PG8_WAIT_V(n) asm volatile("s_waitcnt vmcnt(" #n ")" ::: "memory")
; #define PG8_WAIT_L(n) asm volatile("s_waitcnt lgkmcnt(" #n ")" ::: "memory")
; #define PG8_BAR __builtin_amdgcn_s_barrier()
; #define PG8_SCHED __builtin_amdgcn_sched_barrier(0)
; template <class Epi, class Sched, bool ALIGN_EPI = false, bool SP2 = false>
; __device__ __forceinline__ void gemm_phase(PG8_LAS unsigned char* lds, const Gemm g, const Sched& S, const Epi& E) {
;     ...
;             PG8_WAIT_V(8); PG8_WAIT_L(0); PG8_BAR; PG8_MMA(0, 0, At, B0); PG8_MMA(0, 1, At, B1); PG8_BAR; PG8_SCHED;
;             PG8_LDA(At, 0, 1); PG8_STAGE(PG8_SB(0, 0), b2, voffB); PG8_STAGE(PG8_SB(0, 1), b2 + hstep, voffB); PG8_STAGE(PG8_SA(0, 0), a2, voffA);
;             PG8_WAIT_V(8); PG8_WAIT_L(0); PG8_BAR; PG8_MMA(1, 0, At, B0); PG8_MMA(1, 1, At, B1); PG8_BAR; PG8_SCHED;
	s_setprio 1
	s_waitcnt lgkmcnt(0)
	v_mfma_f32_16x16x32_bf16 v[124:127], v[144:147], v[186:189], v[124:127]
	v_mfma_f32_16x16x32_bf16 v[120:123], v[160:163], v[186:189], v[120:123]
	v_mfma_f32_16x16x32_bf16 v[108:111], v[144:147], v[194:197], v[108:111]
	v_mfma_f32_16x16x32_bf16 v[104:107], v[160:163], v[194:197], v[104:107]
	v_mfma_f32_16x16x32_bf16 v[92:95], v[144:147], v[208:211], v[92:95]
	v_mfma_f32_16x16x32_bf16 v[88:91], v[160:163], v[208:211], v[88:91]
	v_mfma_f32_16x16x32_bf16 v[76:79], v[144:147], v[216:219], v[76:79]
	v_mfma_f32_16x16x32_bf16 v[72:75], v[160:163], v[216:219], v[72:75]
	v_mfma_f32_16x16x32_bf16 v[124:127], v[156:159], v[190:193], v[124:127]
	v_mfma_f32_16x16x32_bf16 v[120:123], v[164:167], v[190:193], v[120:123]
	v_mfma_f32_16x16x32_bf16 v[108:111], v[156:159], v[198:201], v[108:111]
	v_mfma_f32_16x16x32_bf16 v[104:107], v[164:167], v[198:201], v[104:107]
	v_mfma_f32_16x16x32_bf16 v[92:95], v[156:159], v[212:215], v[92:95]
	v_mfma_f32_16x16x32_bf16 v[88:91], v[164:167], v[212:215], v[88:91]
	v_mfma_f32_16x16x32_bf16 v[76:79], v[156:159], v[220:223], v[76:79]
	v_mfma_f32_16x16x32_bf16 v[72:75], v[164:167], v[220:223], v[72:75]
	s_setprio 0
	s_setprio 1
	v_mfma_f32_16x16x32_bf16 v[116:119], v[168:171], v[186:189], v[116:119]
	v_mfma_f32_16x16x32_bf16 v[112:115], v[176:179], v[186:189], v[112:115]
	v_mfma_f32_16x16x32_bf16 v[100:103], v[168:171], v[194:197], v[100:103]
	v_mfma_f32_16x16x32_bf16 v[96:99], v[176:179], v[194:197], v[96:99]
	v_mfma_f32_16x16x32_bf16 v[84:87], v[168:171], v[208:211], v[84:87]
	v_mfma_f32_16x16x32_bf16 v[80:83], v[176:179], v[208:211], v[80:83]
	v_mfma_f32_16x16x32_bf16 v[68:71], v[168:171], v[216:219], v[68:71]
	v_mfma_f32_16x16x32_bf16 v[64:67], v[176:179], v[216:219], v[64:67]
	v_mfma_f32_16x16x32_bf16 v[116:119], v[172:175], v[190:193], v[116:119]
	v_mfma_f32_16x16x32_bf16 v[112:115], v[182:185], v[190:193], v[112:115]
	v_mfma_f32_16x16x32_bf16 v[100:103], v[172:175], v[198:201], v[100:103]
	v_mfma_f32_16x16x32_bf16 v[96:99], v[182:185], v[198:201], v[96:99]
	v_mfma_f32_16x16x32_bf16 v[84:87], v[172:175], v[212:215], v[84:87]
	v_mfma_f32_16x16x32_bf16 v[80:83], v[182:185], v[212:215], v[80:83]
	v_mfma_f32_16x16x32_bf16 v[68:71], v[172:175], v[220:223], v[68:71]
	v_mfma_f32_16x16x32_bf16 v[64:67], v[182:185], v[220:223], v[64:67]
	s_setprio 0
	s_barrier
	s_add_i32 s3, s74, s14
	v_lshl_add_u64 v[202:203], s[60:61], 0, v[130:131]
	s_mov_b32 m0, s3
	ds_read_b128 v[186:189], v153 offset:16384
	ds_read_b128 v[190:193], v153 offset:17408
	ds_read_b128 v[194:197], v153 offset:18432
	ds_read_b128 v[198:201], v153 offset:19456
	ds_read_b128 v[208:211], v153 offset:20480
	ds_read_b128 v[212:215], v153 offset:21504
	ds_read_b128 v[216:219], v153 offset:22528
	ds_read_b128 v[220:223], v153 offset:23552
	global_load_lds_dwordx4 v[202:203], off
	s_add_i32 m0, s3, 0x2000
	s_add_u32 s78, s60, 0x20000
	v_lshl_add_u64 v[224:225], s[60:61], 0, v[134:135]
	s_addc_u32 s79, s61, 0
	s_add_i32 s3, s75, s14
	global_load_lds_dwordx4 v[224:225], off
	v_lshl_add_u64 v[226:227], s[78:79], 0, v[130:131]
	s_mov_b32 m0, s3
	v_lshl_add_u64 v[228:229], s[62:63], 0, v[132:133]
	global_load_lds_dwordx4 v[226:227], off
	v_lshl_add_u64 v[226:227], s[78:79], 0, v[134:135]
	s_add_i32 m0, s3, 0x2000
	s_nop 0
	global_load_lds_dwordx4 v[226:227], off
	s_waitcnt vmcnt(6)
	s_waitcnt lgkmcnt(0)
	s_barrier
	s_setprio 1
	s_waitcnt lgkmcnt(0)
	v_mfma_f32_16x16x32_bf16 v[60:63], v[144:147], v[186:189], v[60:63]
	v_mfma_f32_16x16x32_bf16 v[56:59], v[160:163], v[186:189], v[56:59]
	v_mfma_f32_16x16x32_bf16 v[44:47], v[144:147], v[194:197], v[44:47]
	v_mfma_f32_16x16x32_bf16 v[40:43], v[160:163], v[194:197], v[40:43]
	v_mfma_f32_16x16x32_bf16 v[28:31], v[144:147], v[208:211], v[28:31]
	v_mfma_f32_16x16x32_bf16 v[24:27], v[160:163], v[208:211], v[24:27]
	v_lshl_add_u64 v[226:227], s[62:63], 0, v[128:129]
	s_mov_b32 m0, s15
	s_nop 0
	global_load_lds_dwordx4 v[226:227], off
	v_mfma_f32_16x16x32_bf16 v[12:15], v[144:147], v[216:219], v[12:15]
	v_mfma_f32_16x16x32_bf16 v[8:11], v[160:163], v[216:219], v[8:11]
	v_mfma_f32_16x16x32_bf16 v[60:63], v[156:159], v[190:193], v[60:63]
	v_mfma_f32_16x16x32_bf16 v[56:59], v[164:167], v[190:193], v[56:59]
	v_mfma_f32_16x16x32_bf16 v[44:47], v[156:159], v[198:201], v[44:47]
	v_mfma_f32_16x16x32_bf16 v[40:43], v[164:167], v[198:201], v[40:43]
	v_mfma_f32_16x16x32_bf16 v[28:31], v[156:159], v[212:215], v[28:31]
	v_mfma_f32_16x16x32_bf16 v[24:27], v[164:167], v[212:215], v[24:27]
	v_mfma_f32_16x16x32_bf16 v[12:15], v[156:159], v[220:223], v[12:15]
	v_mfma_f32_16x16x32_bf16 v[8:11], v[164:167], v[220:223], v[8:11]
	s_setprio 0
	s_setprio 1
	v_mfma_f32_16x16x32_bf16 v[52:55], v[168:171], v[186:189], v[52:55]
	v_mfma_f32_16x16x32_bf16 v[48:51], v[176:179], v[186:189], v[48:51]
	s_mov_b32 m0, s34
	s_nop 0
	global_load_lds_dwordx4 v[228:229], off
	v_mfma_f32_16x16x32_bf16 v[36:39], v[168:171], v[194:197], v[36:39]
	v_mfma_f32_16x16x32_bf16 v[32:35], v[176:179], v[194:197], v[32:35]
	v_mfma_f32_16x16x32_bf16 v[20:23], v[168:171], v[208:211], v[20:23]
	v_mfma_f32_16x16x32_bf16 v[16:19], v[176:179], v[208:211], v[16:19]
	v_mfma_f32_16x16x32_bf16 v[4:7], v[168:171], v[216:219], v[4:7]
	v_mfma_f32_16x16x32_bf16 v[0:3], v[176:179], v[216:219], v[0:3]
	v_mfma_f32_16x16x32_bf16 v[52:55], v[172:175], v[190:193], v[52:55]
	v_mfma_f32_16x16x32_bf16 v[48:51], v[182:185], v[190:193], v[48:51]
	v_mfma_f32_16x16x32_bf16 v[36:39], v[172:175], v[198:201], v[36:39]
	v_mfma_f32_16x16x32_bf16 v[32:35], v[182:185], v[198:201], v[32:35]
	v_mfma_f32_16x16x32_bf16 v[20:23], v[172:175], v[212:215], v[20:23]
	v_mfma_f32_16x16x32_bf16 v[16:19], v[182:185], v[212:215], v[16:19]
	v_mfma_f32_16x16x32_bf16 v[4:7], v[172:175], v[220:223], v[4:7]
	v_mfma_f32_16x16x32_bf16 v[0:3], v[182:185], v[220:223], v[0:3]
	s_setprio 0
	s_barrier
; #define PG8_STAGE(bufoff, gbase, voff) do { _Pragma("unroll") for (int _i = 0; _i < 2; ++_i) \
;         __builtin_amdgcn_global_load_lds((const unsigned*)((const char*)(gbase) + (voff)[_i]), (PG8_LAS unsigned*)(lds + (bufoff) + ldsw + _i * 8192), 16, 0, 0); } while (0)
; #define PG8_LDA(dst, b, h) do { _Pragma("unroll") for (int m = 0; m < 4; ++m) _Pragma("unroll") for (int k = 0; k < 2; ++k) dst[m][k] = *(const PG8_LAS bf16x8*)(lds + PG8_SA(b, h) + aoff + m * 2048 + k * 1024); } while (0)
; #define PG8_LDB(dst, b, h) do { _Pragma("unroll") for (int n = 0; n < 2; ++n) _Pragma("unroll") for (int k = 0; k < 2; ++k) dst[n][k] = *(const PG8_LAS bf16x8*)(lds + PG8_SB(b, h) + boff + n * 2048 + k * 1024); } while (0)
; #define PG8_MMA(ai, bj, At, Bt) do { __builtin_amdgcn_s_setprio(1); _Pragma("unroll") for (int m = 0; m < 4; ++m) _Pragma("unroll") for (int n = 0; n < 2; ++n) _Pragma("unroll") for (int k = 0; k < 2; ++k) \
;         acc[ai][bj][m][n] = __builtin_amdgcn_mfma_f32_16x16x32_bf16(Bt[n][k], At[m][k], acc[ai][bj][m][n], 0, 0, 0); __builtin_amdgcn_s_setprio(0); } while (0)
; #define PG8_WAIT_V(n) asm volatile("s_waitcnt vmcnt(" #n ")" ::: "memory")
; #define PG8_WAIT_L(n) asm volatile("s_waitcnt lgkmcnt(" #n ")" ::: "memory")
; #define PG8_BAR __builtin_amdgcn_s_barrier()
; #define PG8_SCHED __builtin_amdgcn_sched_barrier(0)
; template <class Epi, class Sched, bool ALIGN_EPI = false, bool SP2 = false>
; __device__ __forceinline__ void gemm_phase(PG8_LAS unsigned char* lds, const Gemm g, const Sched& S, const Epi& E) {
;     ...
;             PG8_LDB(B0, 1, 0); PG8_LDB(B1, 1, 1); PG8_SCHED; PG8_LDA(At, 1, 0); PG8_STAGE(PG8_SA(0, 1), a2 + hstep, voffA);
;             PG8_WAIT_V(8); PG8_WAIT_L(0); PG8_BAR; PG8_MMA(0, 0, At, B0); PG8_MMA(0, 1, At, B1); PG8_BAR; PG8_SCHED;
	s_add_i32 s3, 0, 0x18000
	v_add_u32_e32 v155, s3, v149
	s_add_i32 s33, 0, 0x1c000
	ds_read_b128 v[144:147], v155
	ds_read_b128 v[156:159], v155 offset:1024
	ds_read_b128 v[160:163], v155 offset:2048
	ds_read_b128 v[164:167], v155 offset:3072
	v_add_u32_e32 v155, s33, v149
	ds_read_b128 v[168:171], v155
	ds_read_b128 v[172:175], v155 offset:1024
	ds_read_b128 v[176:179], v155 offset:2048
	ds_read_b128 v[182:185], v155 offset:3072
	s_add_u32 s62, s62, 0x20000
	s_addc_u32 s63, s63, 0
	s_mov_b32 m0, s57
	v_lshl_add_u64 v[230:231], s[62:63], 0, v[128:129]
	ds_read_b128 v[186:189], v153 offset:32768
	ds_read_b128 v[190:193], v153 offset:33792
	ds_read_b128 v[194:197], v153 offset:34816
	ds_read_b128 v[198:201], v153 offset:35840
	ds_read_b128 v[208:211], v153 offset:36864
	ds_read_b128 v[212:215], v153 offset:37888
	ds_read_b128 v[216:219], v153 offset:38912
	ds_read_b128 v[220:223], v153 offset:39936
	global_load_lds_dwordx4 v[230:231], off
	v_lshl_add_u64 v[230:231], s[62:63], 0, v[132:133]
	s_mov_b32 m0, s64
	s_nop 0
	global_load_lds_dwordx4 v[230:231], off
	s_waitcnt vmcnt(8)
	s_waitcnt lgkmcnt(0)
	s_barrier
	s_setprio 1
	s_waitcnt lgkmcnt(0)
	v_mfma_f32_16x16x32_bf16 v[124:127], v[144:147], v[186:189], v[124:127]
	v_mfma_f32_16x16x32_bf16 v[120:123], v[160:163], v[186:189], v[120:123]
	v_mfma_f32_16x16x32_bf16 v[108:111], v[144:147], v[194:197], v[108:111]
	v_mfma_f32_16x16x32_bf16 v[104:107], v[160:163], v[194:197], v[104:107]
	v_mfma_f32_16x16x32_bf16 v[92:95], v[144:147], v[208:211], v[92:95]
	v_mfma_f32_16x16x32_bf16 v[88:91], v[160:163], v[208:211], v[88:91]
	v_mfma_f32_16x16x32_bf16 v[76:79], v[144:147], v[216:219], v[76:79]
	v_mfma_f32_16x16x32_bf16 v[72:75], v[160:163], v[216:219], v[72:75]
	v_mfma_f32_16x16x32_bf16 v[124:127], v[156:159], v[190:193], v[124:127]
	v_mfma_f32_16x16x32_bf16 v[120:123], v[164:167], v[190:193], v[120:123]
	v_mfma_f32_16x16x32_bf16 v[108:111], v[156:159], v[198:201], v[108:111]
	v_mfma_f32_16x16x32_bf16 v[104:107], v[164:167], v[198:201], v[104:107]
	v_mfma_f32_16x16x32_bf16 v[92:95], v[156:159], v[212:215], v[92:95]
	v_mfma_f32_16x16x32_bf16 v[88:91], v[164:167], v[212:215], v[88:91]
	v_mfma_f32_16x16x32_bf16 v[76:79], v[156:159], v[220:223], v[76:79]
	v_mfma_f32_16x16x32_bf16 v[72:75], v[164:167], v[220:223], v[72:75]
	s_setprio 0
	s_setprio 1
	v_mfma_f32_16x16x32_bf16 v[116:119], v[168:171], v[186:189], v[116:119]
	v_mfma_f32_16x16x32_bf16 v[112:115], v[176:179], v[186:189], v[112:115]
	v_mfma_f32_16x16x32_bf16 v[100:103], v[168:171], v[194:197], v[100:103]
	v_mfma_f32_16x16x32_bf16 v[96:99], v[176:179], v[194:197], v[96:99]
	v_mfma_f32_16x16x32_bf16 v[84:87], v[168:171], v[208:211], v[84:87]
	v_mfma_f32_16x16x32_bf16 v[80:83], v[176:179], v[208:211], v[80:83]
	v_mfma_f32_16x16x32_bf16 v[68:71], v[168:171], v[216:219], v[68:71]
	v_mfma_f32_16x16x32_bf16 v[64:67], v[176:179], v[216:219], v[64:67]
	v_mfma_f32_16x16x32_bf16 v[116:119], v[172:175], v[190:193], v[116:119]
	v_mfma_f32_16x16x32_bf16 v[112:115], v[182:185], v[190:193], v[112:115]
	v_mfma_f32_16x16x32_bf16 v[100:103], v[172:175], v[198:201], v[100:103]
	v_mfma_f32_16x16x32_bf16 v[96:99], v[182:185], v[198:201], v[96:99]
	v_mfma_f32_16x16x32_bf16 v[84:87], v[172:175], v[212:215], v[84:87]
	v_mfma_f32_16x16x32_bf16 v[80:83], v[182:185], v[212:215], v[80:83]
	v_mfma_f32_16x16x32_bf16 v[68:71], v[172:175], v[220:223], v[68:71]
	v_mfma_f32_16x16x32_bf16 v[64:67], v[182:185], v[220:223], v[64:67]
	s_setprio 0
	s_barrier
; #define PG8_STAGE(bufoff, gbase, voff) do { _Pragma("unroll") for (int _i = 0; _i < 2; ++_i) \
;         __builtin_amdgcn_global_load_lds((const unsigned*)((const char*)(gbase) + (voff)[_i]), (PG8_LAS unsigned*)(lds + (bufoff) + ldsw + _i * 8192), 16, 0, 0); } while (0)
; #define PG8_LDA(dst, b, h) do { _Pragma("unroll") for (int m = 0; m < 4; ++m) _Pragma("unroll") for (int k = 0; k < 2; ++k) dst[m][k] = *(const PG8_LAS bf16x8*)(lds + PG8_SA(b, h) + aoff + m * 2048 + k * 1024); } while (0)
; #define PG8_MMA(ai, bj, At, Bt) do { __builtin_amdgcn_s_setprio(1); _Pragma("unroll") for (int m = 0; m < 4; ++m) _Pragma("unroll") for (int n = 0; n < 2; ++n) _Pragma("unroll") for (int k = 0; k < 2; ++k) \
;         acc[ai][bj][m][n] = __builtin_amdgcn_mfma_f32_16x16x32_bf16(Bt[n][k], At[m][k], acc[ai][bj][m][n], 0, 0, 0); __builtin_amdgcn_s_setprio(0); } while (0)
; #define PG8_WAIT_V(n) asm volatile("s_waitcnt vmcnt(" #n ")" ::: "memory")
; #define PG8_WAIT_L(n) asm volatile("s_waitcnt lgkmcnt(" #n ")" ::: "memory")
; #define PG8_BAR __builtin_amdgcn_s_barrier()
; #define PG8_SCHED __builtin_amdgcn_sched_barrier(0)
; template <class Epi, class Sched, bool ALIGN_EPI = false, bool SP2 = false>
; __device__ __forceinline__ void gemm_phase(PG8_LAS unsigned char* lds, const Gemm g, const Sched& S, const Epi& E) {
;     ...
;         for (int t = 0; t < nt; t += 2) {
;             const bool last = (t == nt - 2);
;             const char* a1 = cA + (size_t)(t + 1) * kstep;
;             const char* a2 = last ? nA : cA + (size_t)(t + 2) * kstep; const char* b2 = last ? nB : cB + (size_t)(t + 2) * kstep;
;     ...
;             PG8_LDA(At, 1, 1); PG8_STAGE(PG8_SB(1, 0), b3, voffB); PG8_STAGE(PG8_SB(1, 1), b3 + hstep, voffB); PG8_STAGE(PG8_SA(1, 0), a3, voffA);
;             PG8_WAIT_V(8); PG8_WAIT_L(0); PG8_BAR; PG8_MMA(1, 0, At, B0); PG8_MMA(1, 1, At, B1); PG8_BAR; PG8_SCHED;
	s_add_i32 s3, s3, s14
	v_lshl_add_u64 v[202:203], v[202:203], 0, s[38:39]
	s_mov_b32 m0, s3
	ds_read_b128 v[186:189], v153 offset:49152
	ds_read_b128 v[190:193], v153 offset:50176
	ds_read_b128 v[194:197], v153 offset:51200
	ds_read_b128 v[198:201], v153 offset:52224
	ds_read_b128 v[208:211], v153 offset:53248
	ds_read_b128 v[212:215], v153 offset:54272
	ds_read_b128 v[216:219], v153 offset:55296
	ds_read_b128 v[220:223], v153 offset:56320
	global_load_lds_dwordx4 v[202:203], off
	s_add_i32 m0, s3, 0x2000
	s_add_u32 s60, s60, 0x20080
	v_lshl_add_u64 v[202:203], v[224:225], 0, s[38:39]
	s_addc_u32 s61, s61, 0
	s_add_i32 s3, s33, s14
	global_load_lds_dwordx4 v[202:203], off
	v_lshl_add_u64 v[202:203], s[60:61], 0, v[130:131]
	s_mov_b32 m0, s3
	s_nop 0
	global_load_lds_dwordx4 v[202:203], off
	v_lshl_add_u64 v[202:203], s[60:61], 0, v[134:135]
	s_add_i32 m0, s3, 0x2000
	s_nop 0
	global_load_lds_dwordx4 v[202:203], off
	s_waitcnt vmcnt(6)
	s_waitcnt lgkmcnt(0)
	s_barrier
	s_setprio 1
	s_waitcnt lgkmcnt(0)
	v_mfma_f32_16x16x32_bf16 v[60:63], v[144:147], v[186:189], v[60:63]
	v_mfma_f32_16x16x32_bf16 v[56:59], v[160:163], v[186:189], v[56:59]
	v_mfma_f32_16x16x32_bf16 v[44:47], v[144:147], v[194:197], v[44:47]
	v_mfma_f32_16x16x32_bf16 v[40:43], v[160:163], v[194:197], v[40:43]
	v_mfma_f32_16x16x32_bf16 v[28:31], v[144:147], v[208:211], v[28:31]
	v_mfma_f32_16x16x32_bf16 v[24:27], v[160:163], v[208:211], v[24:27]
	v_lshl_add_u64 v[202:203], v[226:227], 0, s[38:39]
	s_mov_b32 m0, s66
	s_nop 0
	global_load_lds_dwordx4 v[202:203], off
	v_mfma_f32_16x16x32_bf16 v[12:15], v[144:147], v[216:219], v[12:15]
	v_mfma_f32_16x16x32_bf16 v[8:11], v[160:163], v[216:219], v[8:11]
	v_mfma_f32_16x16x32_bf16 v[60:63], v[156:159], v[190:193], v[60:63]
	v_mfma_f32_16x16x32_bf16 v[56:59], v[164:167], v[190:193], v[56:59]
	v_mfma_f32_16x16x32_bf16 v[44:47], v[156:159], v[198:201], v[44:47]
	v_mfma_f32_16x16x32_bf16 v[40:43], v[164:167], v[198:201], v[40:43]
	v_mfma_f32_16x16x32_bf16 v[28:31], v[156:159], v[212:215], v[28:31]
	v_mfma_f32_16x16x32_bf16 v[24:27], v[164:167], v[212:215], v[24:27]
	v_mfma_f32_16x16x32_bf16 v[12:15], v[156:159], v[220:223], v[12:15]
	v_mfma_f32_16x16x32_bf16 v[8:11], v[164:167], v[220:223], v[8:11]
	s_setprio 0
	s_setprio 1
	v_mfma_f32_16x16x32_bf16 v[52:55], v[168:171], v[186:189], v[52:55]
	v_mfma_f32_16x16x32_bf16 v[48:51], v[176:179], v[186:189], v[48:51]
	v_lshl_add_u64 v[202:203], v[228:229], 0, s[38:39]
	s_mov_b32 m0, s67
	s_nop 0
	global_load_lds_dwordx4 v[202:203], off
	v_mfma_f32_16x16x32_bf16 v[36:39], v[168:171], v[194:197], v[36:39]
	v_mfma_f32_16x16x32_bf16 v[32:35], v[176:179], v[194:197], v[32:35]
	v_mfma_f32_16x16x32_bf16 v[20:23], v[168:171], v[208:211], v[20:23]
	v_mfma_f32_16x16x32_bf16 v[16:19], v[176:179], v[208:211], v[16:19]
	v_mfma_f32_16x16x32_bf16 v[4:7], v[168:171], v[216:219], v[4:7]
	v_mfma_f32_16x16x32_bf16 v[0:3], v[176:179], v[216:219], v[0:3]
	v_mfma_f32_16x16x32_bf16 v[52:55], v[172:175], v[190:193], v[52:55]
	v_mfma_f32_16x16x32_bf16 v[48:51], v[182:185], v[190:193], v[48:51]
	v_mfma_f32_16x16x32_bf16 v[36:39], v[172:175], v[198:201], v[36:39]
	v_mfma_f32_16x16x32_bf16 v[32:35], v[182:185], v[198:201], v[32:35]
	v_mfma_f32_16x16x32_bf16 v[20:23], v[172:175], v[212:215], v[20:23]
	v_mfma_f32_16x16x32_bf16 v[16:19], v[182:185], v[212:215], v[16:19]
	v_mfma_f32_16x16x32_bf16 v[4:7], v[172:175], v[220:223], v[4:7]
	v_mfma_f32_16x16x32_bf16 v[0:3], v[182:185], v[220:223], v[0:3]
	s_setprio 0
	s_barrier
	s_add_i32 s87, s87, 2
	s_add_u32 s58, s58, 0x100
	s_addc_u32 s59, s59, 0
	s_add_u32 s85, s85, 0x100
	s_addc_u32 s86, s86, 0
	s_cmp_gt_u32 s87, 5
	s_cbranch_scc0 .LBB0_873
	s_and_b64 vcc, exec, s[42:43]
	s_cbranch_vccz .LBB0_876
	s_barrier

; #define PG8_STAGE(bufoff, gbase, voff) do { _Pragma("unroll") for (int _i = 0; _i < 2; ++_i) \
;         __builtin_amdgcn_global_load_lds((const unsigned*)((const char*)(gbase) + (voff)[_i]), (PG8_LAS unsigned*)(lds + (bufoff) + ldsw + _i * 8192), 16, 0, 0); } while (0)
; #define PG8_LDA(dst, b, h) do { _Pragma("unroll") for (int m = 0; m < 4; ++m) _Pragma("unroll") for (int k = 0; k < 2; ++k) dst[m][k] = *(const PG8_LAS bf16x8*)(lds + PG8_SA(b, h) + aoff + m * 2048 + k * 1024); } while (0)
; #define PG8_LDB(dst, b, h) do { _Pragma("unroll") for (int n = 0; n < 2; ++n) _Pragma("unroll") for (int k = 0; k < 2; ++k) dst[n][k] = *(const PG8_LAS bf16x8*)(lds + PG8_SB(b, h) + boff + n * 2048 + k * 1024); } while (0)
; #define PG8_MMA(ai, bj, At, Bt) do { __builtin_amdgcn_s_setprio(1); _Pragma("unroll") for (int m = 0; m < 4; ++m) _Pragma("unroll") for (int n = 0; n < 2; ++n) _Pragma("unroll") for (int k = 0; k < 2; ++k) \
;         acc[ai][bj][m][n] = __builtin_amdgcn_mfma_f32_16x16x32_bf16(Bt[n][k], At[m][k], acc[ai][bj][m][n], 0, 0, 0); __builtin_amdgcn_s_setprio(0); } while (0)
; #define PG8_WAIT_V(n) asm volatile("s_waitcnt vmcnt(" #n ")" ::: "memory")
; #define PG8_WAIT_L(n) asm volatile("s_waitcnt lgkmcnt(" #n ")" ::: "memory")
; #define PG8_BAR __builtin_amdgcn_s_barrier()
; #define PG8_SCHED __builtin_amdgcn_sched_barrier(0)
; template <class Epi, class Sched, bool ALIGN_EPI = false, bool SP2 = false>
; __device__ __forceinline__ void gemm_phase(PG8_LAS unsigned char* lds, const Gemm g, const Sched& S, const Epi& E) {
;     ...
;             PG8_LDB(B0, 0, 0); PG8_LDB(B1, 0, 1); PG8_SCHED; PG8_LDA(At, 0, 0); PG8_STAGE(PG8_SA(1, 1), a1 + hstep, voffA);
;             PG8_WAIT_V(8); PG8_WAIT_L(0); PG8_BAR; PG8_MMA(0, 0, At, B0); PG8_MMA(0, 1, At, B1); PG8_BAR; PG8_SCHED;
;             PG8_LDA(At, 0, 1); PG8_STAGE(PG8_SB(0, 0), b2, voffB); PG8_STAGE(PG8_SB(0, 1), b2 + hstep, voffB); PG8_STAGE(PG8_SA(0, 0), a2, voffA);
;             PG8_WAIT_V(8); PG8_WAIT_L(0); PG8_BAR; PG8_MMA(1, 0, At, B0); PG8_MMA(1, 1, At, B1); PG8_BAR; PG8_SCHED;
;     ...
; #pragma unroll
;         for (int a = 0; a < 2; ++a)
; #pragma unroll
;             for (int b = 0; b < 2; ++b)
; #pragma unroll
;                 for (int m = 0; m < 4; ++m)
; #pragma unroll
;                     for (int n = 0; n < 2; ++n) acc[a][b][m][n] = (f32x4){0.f, 0.f, 0.f, 0.f};
;         cur = nxt; cA = nA; cB = nB; ++ui;
.LBB0_956:
	s_ashr_i32 s45, s44, 31
	s_lshl_b64 s[48:49], s[44:45], 19
	s_add_u32 s48, s22, s48
	s_addc_u32 s49, s23, s49
	s_and_b64 s[50:51], s[10:11], exec
	s_cselect_b32 s45, s49, s55
	s_cselect_b32 s75, s48, s54
	s_ashr_i32 s43, s42, 31
	s_lshl_b64 s[50:51], s[42:43], 19
	v_readlane_b32 s3, v250, 18
	s_add_u32 s50, s3, s50
	v_readlane_b32 s3, v250, 19
	s_addc_u32 s51, s3, s51
	s_and_b64 s[58:59], s[10:11], exec
	s_cselect_b32 s43, s51, s57
	s_cselect_b32 s76, s50, s56
	s_add_u32 s54, s54, 0x40080
	s_addc_u32 s55, s55, 0
	s_add_u32 s77, s56, 0x100
	s_addc_u32 s82, s57, 0
	s_mov_b32 s83, -2
	ds_read_b128 v[144:147], v155
	ds_read_b128 v[148:151], v155 offset:1024
	ds_read_b128 v[160:163], v155 offset:2048
	ds_read_b128 v[164:167], v155 offset:3072
	ds_read_b128 v[168:171], v156
	ds_read_b128 v[172:175], v156 offset:1024
	ds_read_b128 v[176:179], v156 offset:2048
	ds_read_b128 v[182:185], v156 offset:3072
	s_add_u32 s3, s54, 0xfffc0080
	s_addc_u32 s33, s55, -1
	s_cmp_eq_u32 s83, 12
	s_cselect_b32 s59, s45, s33
	s_cselect_b32 s58, s75, s3
	s_cselect_b32 s57, s43, s82
	s_cselect_b32 s56, s76, s77
	v_lshl_add_u64 v[202:203], s[54:55], 0, v[136:137]
	s_add_i32 m0, s34, 0xc000
	ds_read_b128 v[186:189], v157
	ds_read_b128 v[190:193], v157 offset:1024
	ds_read_b128 v[194:197], v157 offset:2048
	ds_read_b128 v[198:201], v157 offset:3072
	ds_read_b128 v[208:211], v157 offset:4096
	ds_read_b128 v[212:215], v157 offset:5120
	ds_read_b128 v[216:219], v157 offset:6144
	ds_read_b128 v[220:223], v157 offset:7168
	global_load_lds_dwordx4 v[202:203], off
	v_lshl_add_u64 v[202:203], s[54:55], 0, v[138:139]
	s_add_i32 m0, s34, 0xe000
	s_nop 0
	global_load_lds_dwordx4 v[202:203], off
	s_waitcnt vmcnt(8)
	s_waitcnt lgkmcnt(0)
	s_barrier
	s_setprio 1
	s_waitcnt lgkmcnt(0)
	v_mfma_f32_16x16x32_bf16 v[124:127], v[144:147], v[186:189], 0
	v_mfma_f32_16x16x32_bf16 v[120:123], v[160:163], v[186:189], 0
	v_mfma_f32_16x16x32_bf16 v[108:111], v[144:147], v[194:197], 0
	v_mfma_f32_16x16x32_bf16 v[104:107], v[160:163], v[194:197], 0
	v_mfma_f32_16x16x32_bf16 v[92:95], v[144:147], v[208:211], 0
	v_mfma_f32_16x16x32_bf16 v[88:91], v[160:163], v[208:211], 0
	v_mfma_f32_16x16x32_bf16 v[76:79], v[144:147], v[216:219], 0
	v_mfma_f32_16x16x32_bf16 v[72:75], v[160:163], v[216:219], 0
	v_mfma_f32_16x16x32_bf16 v[124:127], v[148:151], v[190:193], v[124:127]
	v_mfma_f32_16x16x32_bf16 v[120:123], v[164:167], v[190:193], v[120:123]
	v_mfma_f32_16x16x32_bf16 v[108:111], v[148:151], v[198:201], v[108:111]
	v_mfma_f32_16x16x32_bf16 v[104:107], v[164:167], v[198:201], v[104:107]
	v_mfma_f32_16x16x32_bf16 v[92:95], v[148:151], v[212:215], v[92:95]
	v_mfma_f32_16x16x32_bf16 v[88:91], v[164:167], v[212:215], v[88:91]
	v_mfma_f32_16x16x32_bf16 v[76:79], v[148:151], v[220:223], v[76:79]
	v_mfma_f32_16x16x32_bf16 v[72:75], v[164:167], v[220:223], v[72:75]
	s_setprio 0
	s_setprio 1
	v_mfma_f32_16x16x32_bf16 v[116:119], v[168:171], v[186:189], 0
	v_mfma_f32_16x16x32_bf16 v[112:115], v[176:179], v[186:189], 0
	v_mfma_f32_16x16x32_bf16 v[100:103], v[168:171], v[194:197], 0
	v_mfma_f32_16x16x32_bf16 v[96:99], v[176:179], v[194:197], 0
	v_mfma_f32_16x16x32_bf16 v[84:87], v[168:171], v[208:211], 0
	v_mfma_f32_16x16x32_bf16 v[80:83], v[176:179], v[208:211], 0
	v_mfma_f32_16x16x32_bf16 v[68:71], v[168:171], v[216:219], 0
	v_mfma_f32_16x16x32_bf16 v[64:67], v[176:179], v[216:219], 0
	v_mfma_f32_16x16x32_bf16 v[116:119], v[172:175], v[190:193], v[116:119]
	v_mfma_f32_16x16x32_bf16 v[112:115], v[182:185], v[190:193], v[112:115]
	v_mfma_f32_16x16x32_bf16 v[100:103], v[172:175], v[198:201], v[100:103]
	v_mfma_f32_16x16x32_bf16 v[96:99], v[182:185], v[198:201], v[96:99]
	v_mfma_f32_16x16x32_bf16 v[84:87], v[172:175], v[212:215], v[84:87]
	v_mfma_f32_16x16x32_bf16 v[80:83], v[182:185], v[212:215], v[80:83]
	v_mfma_f32_16x16x32_bf16 v[68:71], v[172:175], v[220:223], v[68:71]
	v_mfma_f32_16x16x32_bf16 v[64:67], v[182:185], v[220:223], v[64:67]
	s_setprio 0
	s_barrier
	s_add_i32 s3, s65, s14
	v_lshl_add_u64 v[202:203], s[56:57], 0, v[132:133]
	s_mov_b32 m0, s3
	ds_read_b128 v[186:189], v157 offset:16384
	ds_read_b128 v[190:193], v157 offset:17408
	ds_read_b128 v[194:197], v157 offset:18432
	ds_read_b128 v[198:201], v157 offset:19456
	ds_read_b128 v[208:211], v157 offset:20480
	ds_read_b128 v[212:215], v157 offset:21504
	ds_read_b128 v[216:219], v157 offset:22528
	ds_read_b128 v[220:223], v157 offset:23552
	global_load_lds_dwordx4 v[202:203], off
	s_add_i32 m0, s3, 0x2000
	s_add_u32 s78, s56, 0x40000
	v_lshl_add_u64 v[224:225], s[56:57], 0, v[128:129]
	s_addc_u32 s79, s57, 0
	s_add_i32 s3, s66, s14
	global_load_lds_dwordx4 v[224:225], off
	v_lshl_add_u64 v[226:227], s[78:79], 0, v[132:133]
	s_mov_b32 m0, s3
	v_lshl_add_u64 v[228:229], s[58:59], 0, v[130:131]
	global_load_lds_dwordx4 v[226:227], off
	v_lshl_add_u64 v[226:227], s[78:79], 0, v[128:129]
	s_add_i32 m0, s3, 0x2000
	s_nop 0
	global_load_lds_dwordx4 v[226:227], off
	s_waitcnt vmcnt(6)
	s_waitcnt lgkmcnt(0)
	s_barrier
; #define PG8_STAGE(bufoff, gbase, voff) do { _Pragma("unroll") for (int _i = 0; _i < 2; ++_i) \
;         __builtin_amdgcn_global_load_lds((const unsigned*)((const char*)(gbase) + (voff)[_i]), (PG8_LAS unsigned*)(lds + (bufoff) + ldsw + _i * 8192), 16, 0, 0); } while (0)
; #define PG8_LDA(dst, b, h) do { _Pragma("unroll") for (int m = 0; m < 4; ++m) _Pragma("unroll") for (int k = 0; k < 2; ++k) dst[m][k] = *(const PG8_LAS bf16x8*)(lds + PG8_SA(b, h) + aoff + m * 2048 + k * 1024); } while (0)
; #define PG8_LDB(dst, b, h) do { _Pragma("unroll") for (int n = 0; n < 2; ++n) _Pragma("unroll") for (int k = 0; k < 2; ++k) dst[n][k] = *(const PG8_LAS bf16x8*)(lds + PG8_SB(b, h) + boff + n * 2048 + k * 1024); } while (0)
; #define PG8_MMA(ai, bj, At, Bt) do { __builtin_amdgcn_s_setprio(1); _Pragma("unroll") for (int m = 0; m < 4; ++m) _Pragma("unroll") for (int n = 0; n < 2; ++n) _Pragma("unroll") for (int k = 0; k < 2; ++k) \
;         acc[ai][bj][m][n] = __builtin_amdgcn_mfma_f32_16x16x32_bf16(Bt[n][k], At[m][k], acc[ai][bj][m][n], 0, 0, 0); __builtin_amdgcn_s_setprio(0); } while (0)
; #define PG8_WAIT_V(n) asm volatile("s_waitcnt vmcnt(" #n ")" ::: "memory")
; #define PG8_WAIT_L(n) asm volatile("s_waitcnt lgkmcnt(" #n ")" ::: "memory")
; #define PG8_BAR __builtin_amdgcn_s_barrier()
; #define PG8_SCHED __builtin_amdgcn_sched_barrier(0)
; template <class Epi, class Sched, bool ALIGN_EPI = false, bool SP2 = false>
; __device__ __forceinline__ void gemm_phase(PG8_LAS unsigned char* lds, const Gemm g, const Sched& S, const Epi& E) {
;     ...
;             PG8_WAIT_V(8); PG8_WAIT_L(0); PG8_BAR; PG8_MMA(1, 0, At, B0); PG8_MMA(1, 1, At, B1); PG8_BAR; PG8_SCHED;
;             PG8_LDB(B0, 1, 0); PG8_LDB(B1, 1, 1); PG8_SCHED; PG8_LDA(At, 1, 0); PG8_STAGE(PG8_SA(0, 1), a2 + hstep, voffA);
;             PG8_WAIT_V(8); PG8_WAIT_L(0); PG8_BAR; PG8_MMA(0, 0, At, B0); PG8_MMA(0, 1, At, B1); PG8_BAR; PG8_SCHED;
	s_setprio 1
	s_waitcnt lgkmcnt(0)
	v_mfma_f32_16x16x32_bf16 v[60:63], v[144:147], v[186:189], 0
	v_mfma_f32_16x16x32_bf16 v[56:59], v[160:163], v[186:189], 0
	v_mfma_f32_16x16x32_bf16 v[44:47], v[144:147], v[194:197], 0
	v_mfma_f32_16x16x32_bf16 v[40:43], v[160:163], v[194:197], 0
	v_mfma_f32_16x16x32_bf16 v[28:31], v[144:147], v[208:211], 0
	v_mfma_f32_16x16x32_bf16 v[24:27], v[160:163], v[208:211], 0
	v_lshl_add_u64 v[226:227], s[58:59], 0, v[134:135]
	s_mov_b32 m0, s34
	s_nop 0
	global_load_lds_dwordx4 v[226:227], off
	v_mfma_f32_16x16x32_bf16 v[12:15], v[144:147], v[216:219], 0
	v_mfma_f32_16x16x32_bf16 v[8:11], v[160:163], v[216:219], 0
	v_mfma_f32_16x16x32_bf16 v[60:63], v[148:151], v[190:193], v[60:63]
	v_mfma_f32_16x16x32_bf16 v[56:59], v[164:167], v[190:193], v[56:59]
	v_mfma_f32_16x16x32_bf16 v[44:47], v[148:151], v[198:201], v[44:47]
	v_mfma_f32_16x16x32_bf16 v[40:43], v[164:167], v[198:201], v[40:43]
	v_mfma_f32_16x16x32_bf16 v[28:31], v[148:151], v[212:215], v[28:31]
	v_mfma_f32_16x16x32_bf16 v[24:27], v[164:167], v[212:215], v[24:27]
	v_mfma_f32_16x16x32_bf16 v[12:15], v[148:151], v[220:223], v[12:15]
	v_mfma_f32_16x16x32_bf16 v[8:11], v[164:167], v[220:223], v[8:11]
	s_setprio 0
	s_setprio 1
	v_mfma_f32_16x16x32_bf16 v[52:55], v[168:171], v[186:189], 0
	v_mfma_f32_16x16x32_bf16 v[48:51], v[176:179], v[186:189], 0
	s_mov_b32 m0, s53
	s_nop 0
	global_load_lds_dwordx4 v[228:229], off
	v_mfma_f32_16x16x32_bf16 v[36:39], v[168:171], v[194:197], 0
	v_mfma_f32_16x16x32_bf16 v[32:35], v[176:179], v[194:197], 0
	v_mfma_f32_16x16x32_bf16 v[20:23], v[168:171], v[208:211], 0
	v_mfma_f32_16x16x32_bf16 v[16:19], v[176:179], v[208:211], 0
	v_mfma_f32_16x16x32_bf16 v[4:7], v[168:171], v[216:219], 0
	v_mfma_f32_16x16x32_bf16 v[0:3], v[176:179], v[216:219], 0
	v_mfma_f32_16x16x32_bf16 v[52:55], v[172:175], v[190:193], v[52:55]
	v_mfma_f32_16x16x32_bf16 v[48:51], v[182:185], v[190:193], v[48:51]
	v_mfma_f32_16x16x32_bf16 v[36:39], v[172:175], v[198:201], v[36:39]
	v_mfma_f32_16x16x32_bf16 v[32:35], v[182:185], v[198:201], v[32:35]
	v_mfma_f32_16x16x32_bf16 v[20:23], v[172:175], v[212:215], v[20:23]
	v_mfma_f32_16x16x32_bf16 v[16:19], v[182:185], v[212:215], v[16:19]
	v_mfma_f32_16x16x32_bf16 v[4:7], v[172:175], v[220:223], v[4:7]
	v_mfma_f32_16x16x32_bf16 v[0:3], v[182:185], v[220:223], v[0:3]
	s_setprio 0
	s_barrier
	s_add_i32 s3, 0, 0x18000
	v_add_u32_e32 v159, s3, v153
	s_add_i32 s33, 0, 0x1c000
	ds_read_b128 v[144:147], v159
	ds_read_b128 v[148:151], v159 offset:1024
	ds_read_b128 v[160:163], v159 offset:2048
	ds_read_b128 v[164:167], v159 offset:3072
	v_add_u32_e32 v159, s33, v153
	ds_read_b128 v[168:171], v159
	ds_read_b128 v[172:175], v159 offset:1024
	ds_read_b128 v[176:179], v159 offset:2048
	ds_read_b128 v[182:185], v159 offset:3072
	s_add_u32 s58, s58, 0x40000
	s_addc_u32 s59, s59, 0
	s_mov_b32 m0, s60
	v_lshl_add_u64 v[230:231], s[58:59], 0, v[134:135]
	ds_read_b128 v[186:189], v157 offset:32768
	ds_read_b128 v[190:193], v157 offset:33792
	ds_read_b128 v[194:197], v157 offset:34816
	ds_read_b128 v[198:201], v157 offset:35840
	ds_read_b128 v[208:211], v157 offset:36864
	ds_read_b128 v[212:215], v157 offset:37888
	ds_read_b128 v[216:219], v157 offset:38912
	ds_read_b128 v[220:223], v157 offset:39936
	global_load_lds_dwordx4 v[230:231], off
	v_lshl_add_u64 v[230:231], s[58:59], 0, v[130:131]
	s_mov_b32 m0, s61
	s_nop 0
	global_load_lds_dwordx4 v[230:231], off
	s_waitcnt vmcnt(8)
	s_waitcnt lgkmcnt(0)
	s_barrier
	s_setprio 1
	s_waitcnt lgkmcnt(0)
	v_mfma_f32_16x16x32_bf16 v[124:127], v[144:147], v[186:189], v[124:127]
	v_mfma_f32_16x16x32_bf16 v[120:123], v[160:163], v[186:189], v[120:123]
	v_mfma_f32_16x16x32_bf16 v[108:111], v[144:147], v[194:197], v[108:111]
	v_mfma_f32_16x16x32_bf16 v[104:107], v[160:163], v[194:197], v[104:107]
	v_mfma_f32_16x16x32_bf16 v[92:95], v[144:147], v[208:211], v[92:95]
	v_mfma_f32_16x16x32_bf16 v[88:91], v[160:163], v[208:211], v[88:91]
	v_mfma_f32_16x16x32_bf16 v[76:79], v[144:147], v[216:219], v[76:79]
	v_mfma_f32_16x16x32_bf16 v[72:75], v[160:163], v[216:219], v[72:75]
	v_mfma_f32_16x16x32_bf16 v[124:127], v[148:151], v[190:193], v[124:127]
	v_mfma_f32_16x16x32_bf16 v[120:123], v[164:167], v[190:193], v[120:123]
	v_mfma_f32_16x16x32_bf16 v[108:111], v[148:151], v[198:201], v[108:111]
	v_mfma_f32_16x16x32_bf16 v[104:107], v[164:167], v[198:201], v[104:107]
	v_mfma_f32_16x16x32_bf16 v[92:95], v[148:151], v[212:215], v[92:95]
	v_mfma_f32_16x16x32_bf16 v[88:91], v[164:167], v[212:215], v[88:91]
	v_mfma_f32_16x16x32_bf16 v[76:79], v[148:151], v[220:223], v[76:79]
	v_mfma_f32_16x16x32_bf16 v[72:75], v[164:167], v[220:223], v[72:75]
	s_setprio 0
	s_setprio 1
	v_mfma_f32_16x16x32_bf16 v[116:119], v[168:171], v[186:189], v[116:119]
	v_mfma_f32_16x16x32_bf16 v[112:115], v[176:179], v[186:189], v[112:115]
	v_mfma_f32_16x16x32_bf16 v[100:103], v[168:171], v[194:197], v[100:103]
	v_mfma_f32_16x16x32_bf16 v[96:99], v[176:179], v[194:197], v[96:99]
	v_mfma_f32_16x16x32_bf16 v[84:87], v[168:171], v[208:211], v[84:87]
	v_mfma_f32_16x16x32_bf16 v[80:83], v[176:179], v[208:211], v[80:83]
	v_mfma_f32_16x16x32_bf16 v[68:71], v[168:171], v[216:219], v[68:71]
	v_mfma_f32_16x16x32_bf16 v[64:67], v[176:179], v[216:219], v[64:67]
	v_mfma_f32_16x16x32_bf16 v[116:119], v[172:175], v[190:193], v[116:119]
	v_mfma_f32_16x16x32_bf16 v[112:115], v[182:185], v[190:193], v[112:115]
	v_mfma_f32_16x16x32_bf16 v[100:103], v[172:175], v[198:201], v[100:103]
	v_mfma_f32_16x16x32_bf16 v[96:99], v[182:185], v[198:201], v[96:99]
	v_mfma_f32_16x16x32_bf16 v[84:87], v[172:175], v[212:215], v[84:87]
	v_mfma_f32_16x16x32_bf16 v[80:83], v[182:185], v[212:215], v[80:83]
	v_mfma_f32_16x16x32_bf16 v[68:71], v[172:175], v[220:223], v[68:71]
	v_mfma_f32_16x16x32_bf16 v[64:67], v[182:185], v[220:223], v[64:67]
	s_setprio 0
	s_barrier
; #define PG8_STAGE(bufoff, gbase, voff) do { _Pragma("unroll") for (int _i = 0; _i < 2; ++_i) \
;         __builtin_amdgcn_global_load_lds((const unsigned*)((const char*)(gbase) + (voff)[_i]), (PG8_LAS unsigned*)(lds + (bufoff) + ldsw + _i * 8192), 16, 0, 0); } while (0)
; #define PG8_LDA(dst, b, h) do { _Pragma("unroll") for (int m = 0; m < 4; ++m) _Pragma("unroll") for (int k = 0; k < 2; ++k) dst[m][k] = *(const PG8_LAS bf16x8*)(lds + PG8_SA(b, h) + aoff + m * 2048 + k * 1024); } while (0)
; #define PG8_LDB(dst, b, h) do { _Pragma("unroll") for (int n = 0; n < 2; ++n) _Pragma("unroll") for (int k = 0; k < 2; ++k) dst[n][k] = *(const PG8_LAS bf16x8*)(lds + PG8_SB(b, h) + boff + n * 2048 + k * 1024); } while (0)
; #define PG8_MMA(ai, bj, At, Bt) do { __builtin_amdgcn_s_setprio(1); _Pragma("unroll") for (int m = 0; m < 4; ++m) _Pragma("unroll") for (int n = 0; n < 2; ++n) _Pragma("unroll") for (int k = 0; k < 2; ++k) \
;         acc[ai][bj][m][n] = __builtin_amdgcn_mfma_f32_16x16x32_bf16(Bt[n][k], At[m][k], acc[ai][bj][m][n], 0, 0, 0); __builtin_amdgcn_s_setprio(0); } while (0)
; #define PG8_WAIT_V(n) asm volatile("s_waitcnt vmcnt(" #n ")" ::: "memory")
; template <class Epi, class Sched, bool ALIGN_EPI = false, bool SP2 = false>
; __device__ __forceinline__ void gemm_phase(PG8_LAS unsigned char* lds, const Gemm g, const Sched& S, const Epi& E) {
;     ...
;             PG8_LDB(B0, 0, 0); PG8_LDB(B1, 0, 1); PG8_SCHED; PG8_LDA(At, 0, 0); PG8_STAGE(PG8_SA(1, 1), a1 + hstep, voffA);
;             PG8_WAIT_V(8); PG8_WAIT_L(0); PG8_BAR; PG8_MMA(0, 0, At, B0); PG8_MMA(0, 1, At, B1); PG8_BAR; PG8_SCHED;
;             PG8_LDA(At, 0, 1); PG8_STAGE(PG8_SB(0, 0), b2, voffB); PG8_STAGE(PG8_SB(0, 1), b2 + hstep, voffB); PG8_STAGE(PG8_SA(0, 0), a2, voffA);
;             PG8_WAIT_V(8); PG8_WAIT_L(0); PG8_BAR; PG8_MMA(1, 0, At, B0); PG8_MMA(1, 1, At, B1); PG8_BAR; PG8_SCHED;
;             PG8_LDB(B0, 1, 0); PG8_LDB(B1, 1, 1); PG8_SCHED; PG8_LDA(At, 1, 0); PG8_STAGE(PG8_SA(0, 1), a2 + hstep, voffA);
;             PG8_WAIT_V(8); PG8_WAIT_L(0); PG8_BAR; PG8_MMA(0, 0, At, B0); PG8_MMA(0, 1, At, B1); PG8_BAR; PG8_SCHED;
;             PG8_LDA(At, 1, 1); PG8_STAGE(PG8_SB(1, 0), b3, voffB); PG8_STAGE(PG8_SB(1, 1), b3 + hstep, voffB); PG8_STAGE(PG8_SA(1, 0), a3, voffA);
;             PG8_WAIT_V(8); PG8_WAIT_L(0); PG8_BAR; PG8_MMA(1, 0, At, B0); PG8_MMA(1, 1, At, B1); PG8_BAR; PG8_SCHED;
	s_add_i32 s3, s3, s14
	v_lshl_add_u64 v[202:203], v[202:203], 0, s[36:37]
	s_mov_b32 m0, s3
	ds_read_b128 v[186:189], v157 offset:49152
	ds_read_b128 v[190:193], v157 offset:50176
	ds_read_b128 v[194:197], v157 offset:51200
	ds_read_b128 v[198:201], v157 offset:52224
	ds_read_b128 v[208:211], v157 offset:53248
	ds_read_b128 v[212:215], v157 offset:54272
	ds_read_b128 v[216:219], v157 offset:55296
	ds_read_b128 v[220:223], v157 offset:56320
	global_load_lds_dwordx4 v[202:203], off
	s_add_i32 m0, s3, 0x2000
	s_add_u32 s56, s56, 0x40080
	v_lshl_add_u64 v[202:203], v[224:225], 0, s[36:37]
	s_addc_u32 s57, s57, 0
	s_add_i32 s3, s33, s14
	global_load_lds_dwordx4 v[202:203], off
	v_lshl_add_u64 v[202:203], s[56:57], 0, v[132:133]
	s_mov_b32 m0, s3
	s_nop 0
	global_load_lds_dwordx4 v[202:203], off
	v_lshl_add_u64 v[202:203], s[56:57], 0, v[128:129]
	s_add_i32 m0, s3, 0x2000
	s_nop 0
	global_load_lds_dwordx4 v[202:203], off
	s_waitcnt vmcnt(6)
	s_waitcnt lgkmcnt(0)
	s_barrier
	s_setprio 1
	s_waitcnt lgkmcnt(0)
	v_mfma_f32_16x16x32_bf16 v[60:63], v[144:147], v[186:189], v[60:63]
	v_mfma_f32_16x16x32_bf16 v[56:59], v[160:163], v[186:189], v[56:59]
	v_mfma_f32_16x16x32_bf16 v[44:47], v[144:147], v[194:197], v[44:47]
	v_mfma_f32_16x16x32_bf16 v[40:43], v[160:163], v[194:197], v[40:43]
	v_mfma_f32_16x16x32_bf16 v[28:31], v[144:147], v[208:211], v[28:31]
	v_mfma_f32_16x16x32_bf16 v[24:27], v[160:163], v[208:211], v[24:27]
	v_lshl_add_u64 v[202:203], v[226:227], 0, s[36:37]
	s_mov_b32 m0, s63
	s_nop 0
	global_load_lds_dwordx4 v[202:203], off
	v_mfma_f32_16x16x32_bf16 v[12:15], v[144:147], v[216:219], v[12:15]
	v_mfma_f32_16x16x32_bf16 v[8:11], v[160:163], v[216:219], v[8:11]
	v_mfma_f32_16x16x32_bf16 v[60:63], v[148:151], v[190:193], v[60:63]
	v_mfma_f32_16x16x32_bf16 v[56:59], v[164:167], v[190:193], v[56:59]
	v_mfma_f32_16x16x32_bf16 v[44:47], v[148:151], v[198:201], v[44:47]
	v_mfma_f32_16x16x32_bf16 v[40:43], v[164:167], v[198:201], v[40:43]
	v_mfma_f32_16x16x32_bf16 v[28:31], v[148:151], v[212:215], v[28:31]
	v_mfma_f32_16x16x32_bf16 v[24:27], v[164:167], v[212:215], v[24:27]
	v_mfma_f32_16x16x32_bf16 v[12:15], v[148:151], v[220:223], v[12:15]
	v_mfma_f32_16x16x32_bf16 v[8:11], v[164:167], v[220:223], v[8:11]
	s_setprio 0
	s_setprio 1
	v_mfma_f32_16x16x32_bf16 v[52:55], v[168:171], v[186:189], v[52:55]
	v_mfma_f32_16x16x32_bf16 v[48:51], v[176:179], v[186:189], v[48:51]
	v_lshl_add_u64 v[202:203], v[228:229], 0, s[36:37]
	s_mov_b32 m0, s64
	s_nop 0
	global_load_lds_dwordx4 v[202:203], off
	v_mfma_f32_16x16x32_bf16 v[36:39], v[168:171], v[194:197], v[36:39]
	v_mfma_f32_16x16x32_bf16 v[32:35], v[176:179], v[194:197], v[32:35]
	v_mfma_f32_16x16x32_bf16 v[20:23], v[168:171], v[208:211], v[20:23]
	v_mfma_f32_16x16x32_bf16 v[16:19], v[176:179], v[208:211], v[16:19]
	v_mfma_f32_16x16x32_bf16 v[4:7], v[168:171], v[216:219], v[4:7]
	v_mfma_f32_16x16x32_bf16 v[0:3], v[176:179], v[216:219], v[0:3]
	v_mfma_f32_16x16x32_bf16 v[52:55], v[172:175], v[190:193], v[52:55]
	v_mfma_f32_16x16x32_bf16 v[48:51], v[182:185], v[190:193], v[48:51]
	v_mfma_f32_16x16x32_bf16 v[36:39], v[172:175], v[198:201], v[36:39]
	v_mfma_f32_16x16x32_bf16 v[32:35], v[182:185], v[198:201], v[32:35]
	v_mfma_f32_16x16x32_bf16 v[20:23], v[172:175], v[212:215], v[20:23]
	v_mfma_f32_16x16x32_bf16 v[16:19], v[182:185], v[212:215], v[16:19]
	v_mfma_f32_16x16x32_bf16 v[4:7], v[172:175], v[220:223], v[4:7]
	v_mfma_f32_16x16x32_bf16 v[0:3], v[182:185], v[220:223], v[0:3]
	s_setprio 0
	s_barrier
	s_add_i32 s83, s83, 2
	s_add_u32 s54, s54, 0x100
	s_addc_u32 s55, s55, 0
	s_add_u32 s77, s77, 0x100
	s_addc_u32 s82, s82, 0
.LBB0_957:
	ds_read_b128 v[144:147], v155
	ds_read_b128 v[148:151], v155 offset:1024
	ds_read_b128 v[160:163], v155 offset:2048
	ds_read_b128 v[164:167], v155 offset:3072
	ds_read_b128 v[168:171], v156
	ds_read_b128 v[172:175], v156 offset:1024
	ds_read_b128 v[176:179], v156 offset:2048
	ds_read_b128 v[182:185], v156 offset:3072
	s_add_u32 s3, s54, 0xfffc0080
	s_addc_u32 s33, s55, -1
	s_cmp_eq_u32 s83, 12
	s_cselect_b32 s59, s45, s33
	s_cselect_b32 s58, s75, s3
	s_cselect_b32 s57, s43, s82
	s_cselect_b32 s56, s76, s77
	v_lshl_add_u64 v[202:203], s[54:55], 0, v[136:137]
	s_add_i32 m0, s34, 0xc000
	ds_read_b128 v[186:189], v157
	ds_read_b128 v[190:193], v157 offset:1024
	ds_read_b128 v[194:197], v157 offset:2048
	ds_read_b128 v[198:201], v157 offset:3072
	ds_read_b128 v[208:211], v157 offset:4096
	ds_read_b128 v[212:215], v157 offset:5120
	ds_read_b128 v[216:219], v157 offset:6144
	ds_read_b128 v[220:223], v157 offset:7168
	global_load_lds_dwordx4 v[202:203], off
	v_lshl_add_u64 v[202:203], s[54:55], 0, v[138:139]
	s_add_i32 m0, s34, 0xe000
	s_nop 0
	global_load_lds_dwordx4 v[202:203], off
	s_waitcnt vmcnt(8)
	s_waitcnt lgkmcnt(0)
	s_barrier
; #define PG8_STAGE(bufoff, gbase, voff) do { _Pragma("unroll") for (int _i = 0; _i < 2; ++_i) \
;         __builtin_amdgcn_global_load_lds((const unsigned*)((const char*)(gbase) + (voff)[_i]), (PG8_LAS unsigned*)(lds + (bufoff) + ldsw + _i * 8192), 16, 0, 0); } while (0)
; #define PG8_LDA(dst, b, h) do { _Pragma("unroll") for (int m = 0; m < 4; ++m) _Pragma("unroll") for (int k = 0; k < 2; ++k) dst[m][k] = *(const PG8_LAS bf16x8*)(lds + PG8_SA(b, h) + aoff + m * 2048 + k * 1024); } while (0)
; #define PG8_MMA(ai, bj, At, Bt) do { __builtin_amdgcn_s_setprio(1); _Pragma("unroll") for (int m = 0; m < 4; ++m) _Pragma("unroll") for (int n = 0; n < 2; ++n) _Pragma("unroll") for (int k = 0; k < 2; ++k) \
;         acc[ai][bj][m][n] = __builtin_amdgcn_mfma_f32_16x16x32_bf16(Bt[n][k], At[m][k], acc[ai][bj][m][n], 0, 0, 0); __builtin_amdgcn_s_setprio(0); } while (0)
; #define PG8_WAIT_V(n) asm volatile("s_waitcnt vmcnt(" #n ")" ::: "memory")
; #define PG8_WAIT_L(n) asm volatile("s_waitcnt lgkmcnt(" #n ")" ::: "memory")
; #define PG8_BAR __builtin_amdgcn_s_barrier()
; #define PG8_SCHED __builtin_amdgcn_sched_barrier(0)
; template <class Epi, class Sched, bool ALIGN_EPI = false, bool SP2 = false>
; __device__ __forceinline__ void gemm_phase(PG8_LAS unsigned char* lds, const Gemm g, const Sched& S, const Epi& E) {
;     ...
;             PG8_WAIT_V(8); PG8_WAIT_L(0); PG8_BAR; PG8_MMA(0, 0, At, B0); PG8_MMA(0, 1, At, B1); PG8_BAR; PG8_SCHED;
;             PG8_LDA(At, 0, 1); PG8_STAGE(PG8_SB(0, 0), b2, voffB); PG8_STAGE(PG8_SB(0, 1), b2 + hstep, voffB); PG8_STAGE(PG8_SA(0, 0), a2, voffA);
;             PG8_WAIT_V(8); PG8_WAIT_L(0); PG8_BAR; PG8_MMA(1, 0, At, B0); PG8_MMA(1, 1, At, B1); PG8_BAR; PG8_SCHED;
	s_setprio 1
	s_waitcnt lgkmcnt(0)
	v_mfma_f32_16x16x32_bf16 v[124:127], v[144:147], v[186:189], v[124:127]
	v_mfma_f32_16x16x32_bf16 v[120:123], v[160:163], v[186:189], v[120:123]
	v_mfma_f32_16x16x32_bf16 v[108:111], v[144:147], v[194:197], v[108:111]
	v_mfma_f32_16x16x32_bf16 v[104:107], v[160:163], v[194:197], v[104:107]
	v_mfma_f32_16x16x32_bf16 v[92:95], v[144:147], v[208:211], v[92:95]
	v_mfma_f32_16x16x32_bf16 v[88:91], v[160:163], v[208:211], v[88:91]
	v_mfma_f32_16x16x32_bf16 v[76:79], v[144:147], v[216:219], v[76:79]
	v_mfma_f32_16x16x32_bf16 v[72:75], v[160:163], v[216:219], v[72:75]
	v_mfma_f32_16x16x32_bf16 v[124:127], v[148:151], v[190:193], v[124:127]
	v_mfma_f32_16x16x32_bf16 v[120:123], v[164:167], v[190:193], v[120:123]
	v_mfma_f32_16x16x32_bf16 v[108:111], v[148:151], v[198:201], v[108:111]
	v_mfma_f32_16x16x32_bf16 v[104:107], v[164:167], v[198:201], v[104:107]
	v_mfma_f32_16x16x32_bf16 v[92:95], v[148:151], v[212:215], v[92:95]
	v_mfma_f32_16x16x32_bf16 v[88:91], v[164:167], v[212:215], v[88:91]
	v_mfma_f32_16x16x32_bf16 v[76:79], v[148:151], v[220:223], v[76:79]
	v_mfma_f32_16x16x32_bf16 v[72:75], v[164:167], v[220:223], v[72:75]
	s_setprio 0
	s_setprio 1
	v_mfma_f32_16x16x32_bf16 v[116:119], v[168:171], v[186:189], v[116:119]
	v_mfma_f32_16x16x32_bf16 v[112:115], v[176:179], v[186:189], v[112:115]
	v_mfma_f32_16x16x32_bf16 v[100:103], v[168:171], v[194:197], v[100:103]
	v_mfma_f32_16x16x32_bf16 v[96:99], v[176:179], v[194:197], v[96:99]
	v_mfma_f32_16x16x32_bf16 v[84:87], v[168:171], v[208:211], v[84:87]
	v_mfma_f32_16x16x32_bf16 v[80:83], v[176:179], v[208:211], v[80:83]
	v_mfma_f32_16x16x32_bf16 v[68:71], v[168:171], v[216:219], v[68:71]
	v_mfma_f32_16x16x32_bf16 v[64:67], v[176:179], v[216:219], v[64:67]
	v_mfma_f32_16x16x32_bf16 v[116:119], v[172:175], v[190:193], v[116:119]
	v_mfma_f32_16x16x32_bf16 v[112:115], v[182:185], v[190:193], v[112:115]
	v_mfma_f32_16x16x32_bf16 v[100:103], v[172:175], v[198:201], v[100:103]
	v_mfma_f32_16x16x32_bf16 v[96:99], v[182:185], v[198:201], v[96:99]
	v_mfma_f32_16x16x32_bf16 v[84:87], v[172:175], v[212:215], v[84:87]
	v_mfma_f32_16x16x32_bf16 v[80:83], v[182:185], v[212:215], v[80:83]
	v_mfma_f32_16x16x32_bf16 v[68:71], v[172:175], v[220:223], v[68:71]
	v_mfma_f32_16x16x32_bf16 v[64:67], v[182:185], v[220:223], v[64:67]
	s_setprio 0
	s_barrier
	s_add_i32 s3, s65, s14
	v_lshl_add_u64 v[202:203], s[56:57], 0, v[132:133]
	s_mov_b32 m0, s3
	ds_read_b128 v[186:189], v157 offset:16384
	ds_read_b128 v[190:193], v157 offset:17408
	ds_read_b128 v[194:197], v157 offset:18432
	ds_read_b128 v[198:201], v157 offset:19456
	ds_read_b128 v[208:211], v157 offset:20480
	ds_read_b128 v[212:215], v157 offset:21504
	ds_read_b128 v[216:219], v157 offset:22528
	ds_read_b128 v[220:223], v157 offset:23552
	global_load_lds_dwordx4 v[202:203], off
	s_add_i32 m0, s3, 0x2000
	s_add_u32 s78, s56, 0x40000
	v_lshl_add_u64 v[224:225], s[56:57], 0, v[128:129]
	s_addc_u32 s79, s57, 0
	s_add_i32 s3, s66, s14
	global_load_lds_dwordx4 v[224:225], off
	v_lshl_add_u64 v[226:227], s[78:79], 0, v[132:133]
	s_mov_b32 m0, s3
	v_lshl_add_u64 v[228:229], s[58:59], 0, v[130:131]
	global_load_lds_dwordx4 v[226:227], off
	v_lshl_add_u64 v[226:227], s[78:79], 0, v[128:129]
	s_add_i32 m0, s3, 0x2000
	s_nop 0
	global_load_lds_dwordx4 v[226:227], off
	s_waitcnt vmcnt(6)
	s_waitcnt lgkmcnt(0)
	s_barrier
	s_setprio 1
	s_waitcnt lgkmcnt(0)
	v_mfma_f32_16x16x32_bf16 v[60:63], v[144:147], v[186:189], v[60:63]
	v_mfma_f32_16x16x32_bf16 v[56:59], v[160:163], v[186:189], v[56:59]
	v_mfma_f32_16x16x32_bf16 v[44:47], v[144:147], v[194:197], v[44:47]
	v_mfma_f32_16x16x32_bf16 v[40:43], v[160:163], v[194:197], v[40:43]
	v_mfma_f32_16x16x32_bf16 v[28:31], v[144:147], v[208:211], v[28:31]
	v_mfma_f32_16x16x32_bf16 v[24:27], v[160:163], v[208:211], v[24:27]
	v_lshl_add_u64 v[226:227], s[58:59], 0, v[134:135]
	s_mov_b32 m0, s34
	s_nop 0
	global_load_lds_dwordx4 v[226:227], off
	v_mfma_f32_16x16x32_bf16 v[12:15], v[144:147], v[216:219], v[12:15]
	v_mfma_f32_16x16x32_bf16 v[8:11], v[160:163], v[216:219], v[8:11]
	v_mfma_f32_16x16x32_bf16 v[60:63], v[148:151], v[190:193], v[60:63]
	v_mfma_f32_16x16x32_bf16 v[56:59], v[164:167], v[190:193], v[56:59]
	v_mfma_f32_16x16x32_bf16 v[44:47], v[148:151], v[198:201], v[44:47]
	v_mfma_f32_16x16x32_bf16 v[40:43], v[164:167], v[198:201], v[40:43]
	v_mfma_f32_16x16x32_bf16 v[28:31], v[148:151], v[212:215], v[28:31]
	v_mfma_f32_16x16x32_bf16 v[24:27], v[164:167], v[212:215], v[24:27]
	v_mfma_f32_16x16x32_bf16 v[12:15], v[148:151], v[220:223], v[12:15]
	v_mfma_f32_16x16x32_bf16 v[8:11], v[164:167], v[220:223], v[8:11]
	s_setprio 0
	s_setprio 1
	v_mfma_f32_16x16x32_bf16 v[52:55], v[168:171], v[186:189], v[52:55]
	v_mfma_f32_16x16x32_bf16 v[48:51], v[176:179], v[186:189], v[48:51]
	s_mov_b32 m0, s53
	s_nop 0
	global_load_lds_dwordx4 v[228:229], off
	v_mfma_f32_16x16x32_bf16 v[36:39], v[168:171], v[194:197], v[36:39]
	v_mfma_f32_16x16x32_bf16 v[32:35], v[176:179], v[194:197], v[32:35]
	v_mfma_f32_16x16x32_bf16 v[20:23], v[168:171], v[208:211], v[20:23]
	v_mfma_f32_16x16x32_bf16 v[16:19], v[176:179], v[208:211], v[16:19]
	v_mfma_f32_16x16x32_bf16 v[4:7], v[168:171], v[216:219], v[4:7]
	v_mfma_f32_16x16x32_bf16 v[0:3], v[176:179], v[216:219], v[0:3]
	v_mfma_f32_16x16x32_bf16 v[52:55], v[172:175], v[190:193], v[52:55]
	v_mfma_f32_16x16x32_bf16 v[48:51], v[182:185], v[190:193], v[48:51]
	v_mfma_f32_16x16x32_bf16 v[36:39], v[172:175], v[198:201], v[36:39]
	v_mfma_f32_16x16x32_bf16 v[32:35], v[182:185], v[198:201], v[32:35]
	v_mfma_f32_16x16x32_bf16 v[20:23], v[172:175], v[212:215], v[20:23]
	v_mfma_f32_16x16x32_bf16 v[16:19], v[182:185], v[212:215], v[16:19]
	v_mfma_f32_16x16x32_bf16 v[4:7], v[172:175], v[220:223], v[4:7]
	v_mfma_f32_16x16x32_bf16 v[0:3], v[182:185], v[220:223], v[0:3]
	s_setprio 0
	s_barrier
; #define PG8_STAGE(bufoff, gbase, voff) do { _Pragma("unroll") for (int _i = 0; _i < 2; ++_i) \
;         __builtin_amdgcn_global_load_lds((const unsigned*)((const char*)(gbase) + (voff)[_i]), (PG8_LAS unsigned*)(lds + (bufoff) + ldsw + _i * 8192), 16, 0, 0); } while (0)
; #define PG8_LDA(dst, b, h) do { _Pragma("unroll") for (int m = 0; m < 4; ++m) _Pragma("unroll") for (int k = 0; k < 2; ++k) dst[m][k] = *(const PG8_LAS bf16x8*)(lds + PG8_SA(b, h) + aoff + m * 2048 + k * 1024); } while (0)
; #define PG8_LDB(dst, b, h) do { _Pragma("unroll") for (int n = 0; n < 2; ++n) _Pragma("unroll") for (int k = 0; k < 2; ++k) dst[n][k] = *(const PG8_LAS bf16x8*)(lds + PG8_SB(b, h) + boff + n * 2048 + k * 1024); } while (0)
; #define PG8_MMA(ai, bj, At, Bt) do { __builtin_amdgcn_s_setprio(1); _Pragma("unroll") for (int m = 0; m < 4; ++m) _Pragma("unroll") for (int n = 0; n < 2; ++n) _Pragma("unroll") for (int k = 0; k < 2; ++k) \
;         acc[ai][bj][m][n] = __builtin_amdgcn_mfma_f32_16x16x32_bf16(Bt[n][k], At[m][k], acc[ai][bj][m][n], 0, 0, 0); __builtin_amdgcn_s_setprio(0); } while (0)
; #define PG8_WAIT_V(n) asm volatile("s_waitcnt vmcnt(" #n ")" ::: "memory")
; #define PG8_WAIT_L(n) asm volatile("s_waitcnt lgkmcnt(" #n ")" ::: "memory")
; #define PG8_BAR __builtin_amdgcn_s_barrier()
; #define PG8_SCHED __builtin_amdgcn_sched_barrier(0)
; template <class Epi, class Sched, bool ALIGN_EPI = false, bool SP2 = false>
; __device__ __forceinline__ void gemm_phase(PG8_LAS unsigned char* lds, const Gemm g, const Sched& S, const Epi& E) {
;     ...
;             PG8_LDB(B0, 1, 0); PG8_LDB(B1, 1, 1); PG8_SCHED; PG8_LDA(At, 1, 0); PG8_STAGE(PG8_SA(0, 1), a2 + hstep, voffA);
;             PG8_WAIT_V(8); PG8_WAIT_L(0); PG8_BAR; PG8_MMA(0, 0, At, B0); PG8_MMA(0, 1, At, B1); PG8_BAR; PG8_SCHED;
	s_add_i32 s3, 0, 0x18000
	v_add_u32_e32 v159, s3, v153
	s_add_i32 s33, 0, 0x1c000
	ds_read_b128 v[144:147], v159
	ds_read_b128 v[148:151], v159 offset:1024
	ds_read_b128 v[160:163], v159 offset:2048
	ds_read_b128 v[164:167], v159 offset:3072
	v_add_u32_e32 v159, s33, v153
	ds_read_b128 v[168:171], v159
	ds_read_b128 v[172:175], v159 offset:1024
	ds_read_b128 v[176:179], v159 offset:2048
	ds_read_b128 v[182:185], v159 offset:3072
	s_add_u32 s58, s58, 0x40000
	s_addc_u32 s59, s59, 0
	s_mov_b32 m0, s60
	v_lshl_add_u64 v[230:231], s[58:59], 0, v[134:135]
	ds_read_b128 v[186:189], v157 offset:32768
	ds_read_b128 v[190:193], v157 offset:33792
	ds_read_b128 v[194:197], v157 offset:34816
	ds_read_b128 v[198:201], v157 offset:35840
	ds_read_b128 v[208:211], v157 offset:36864
	ds_read_b128 v[212:215], v157 offset:37888
	ds_read_b128 v[216:219], v157 offset:38912
	ds_read_b128 v[220:223], v157 offset:39936
	global_load_lds_dwordx4 v[230:231], off
	v_lshl_add_u64 v[230:231], s[58:59], 0, v[130:131]
	s_mov_b32 m0, s61
	s_nop 0
	global_load_lds_dwordx4 v[230:231], off
	s_waitcnt vmcnt(8)
	s_waitcnt lgkmcnt(0)
	s_barrier
	s_setprio 1
	s_waitcnt lgkmcnt(0)
	v_mfma_f32_16x16x32_bf16 v[124:127], v[144:147], v[186:189], v[124:127]
	v_mfma_f32_16x16x32_bf16 v[120:123], v[160:163], v[186:189], v[120:123]
	v_mfma_f32_16x16x32_bf16 v[108:111], v[144:147], v[194:197], v[108:111]
	v_mfma_f32_16x16x32_bf16 v[104:107], v[160:163], v[194:197], v[104:107]
	v_mfma_f32_16x16x32_bf16 v[92:95], v[144:147], v[208:211], v[92:95]
	v_mfma_f32_16x16x32_bf16 v[88:91], v[160:163], v[208:211], v[88:91]
	v_mfma_f32_16x16x32_bf16 v[76:79], v[144:147], v[216:219], v[76:79]
	v_mfma_f32_16x16x32_bf16 v[72:75], v[160:163], v[216:219], v[72:75]
	v_mfma_f32_16x16x32_bf16 v[124:127], v[148:151], v[190:193], v[124:127]
	v_mfma_f32_16x16x32_bf16 v[120:123], v[164:167], v[190:193], v[120:123]
	v_mfma_f32_16x16x32_bf16 v[108:111], v[148:151], v[198:201], v[108:111]
	v_mfma_f32_16x16x32_bf16 v[104:107], v[164:167], v[198:201], v[104:107]
	v_mfma_f32_16x16x32_bf16 v[92:95], v[148:151], v[212:215], v[92:95]
	v_mfma_f32_16x16x32_bf16 v[88:91], v[164:167], v[212:215], v[88:91]
	v_mfma_f32_16x16x32_bf16 v[76:79], v[148:151], v[220:223], v[76:79]
	v_mfma_f32_16x16x32_bf16 v[72:75], v[164:167], v[220:223], v[72:75]
	s_setprio 0
	s_setprio 1
	v_mfma_f32_16x16x32_bf16 v[116:119], v[168:171], v[186:189], v[116:119]
	v_mfma_f32_16x16x32_bf16 v[112:115], v[176:179], v[186:189], v[112:115]
	v_mfma_f32_16x16x32_bf16 v[100:103], v[168:171], v[194:197], v[100:103]
	v_mfma_f32_16x16x32_bf16 v[96:99], v[176:179], v[194:197], v[96:99]
	v_mfma_f32_16x16x32_bf16 v[84:87], v[168:171], v[208:211], v[84:87]
	v_mfma_f32_16x16x32_bf16 v[80:83], v[176:179], v[208:211], v[80:83]
	v_mfma_f32_16x16x32_bf16 v[68:71], v[168:171], v[216:219], v[68:71]
	v_mfma_f32_16x16x32_bf16 v[64:67], v[176:179], v[216:219], v[64:67]
	v_mfma_f32_16x16x32_bf16 v[116:119], v[172:175], v[190:193], v[116:119]
	v_mfma_f32_16x16x32_bf16 v[112:115], v[182:185], v[190:193], v[112:115]
	v_mfma_f32_16x16x32_bf16 v[100:103], v[172:175], v[198:201], v[100:103]
	v_mfma_f32_16x16x32_bf16 v[96:99], v[182:185], v[198:201], v[96:99]
	v_mfma_f32_16x16x32_bf16 v[84:87], v[172:175], v[212:215], v[84:87]
	v_mfma_f32_16x16x32_bf16 v[80:83], v[182:185], v[212:215], v[80:83]
	v_mfma_f32_16x16x32_bf16 v[68:71], v[172:175], v[220:223], v[68:71]
	v_mfma_f32_16x16x32_bf16 v[64:67], v[182:185], v[220:223], v[64:67]
	s_setprio 0
	s_barrier
; #define PG8_STAGE(bufoff, gbase, voff) do { _Pragma("unroll") for (int _i = 0; _i < 2; ++_i) \
;         __builtin_amdgcn_global_load_lds((const unsigned*)((const char*)(gbase) + (voff)[_i]), (PG8_LAS unsigned*)(lds + (bufoff) + ldsw + _i * 8192), 16, 0, 0); } while (0)
; #define PG8_LDA(dst, b, h) do { _Pragma("unroll") for (int m = 0; m < 4; ++m) _Pragma("unroll") for (int k = 0; k < 2; ++k) dst[m][k] = *(const PG8_LAS bf16x8*)(lds + PG8_SA(b, h) + aoff + m * 2048 + k * 1024); } while (0)
; #define PG8_MMA(ai, bj, At, Bt) do { __builtin_amdgcn_s_setprio(1); _Pragma("unroll") for (int m = 0; m < 4; ++m) _Pragma("unroll") for (int n = 0; n < 2; ++n) _Pragma("unroll") for (int k = 0; k < 2; ++k) \
;         acc[ai][bj][m][n] = __builtin_amdgcn_mfma_f32_16x16x32_bf16(Bt[n][k], At[m][k], acc[ai][bj][m][n], 0, 0, 0); __builtin_amdgcn_s_setprio(0); } while (0)
; #define PG8_WAIT_V(n) asm volatile("s_waitcnt vmcnt(" #n ")" ::: "memory")
; #define PG8_WAIT_L(n) asm volatile("s_waitcnt lgkmcnt(" #n ")" ::: "memory")
; #define PG8_BAR __builtin_amdgcn_s_barrier()
; #define PG8_SCHED __builtin_amdgcn_sched_barrier(0)
; __device__ __forceinline__ float row_rs(const float* ssp, int row) { const unsigned long long v = ((const unsigned long long*)ssp)[row];
;     return __builtin_amdgcn_rsqf((float)v * (1.0f / 4294967296.0f) * (1.0f / 1024.0f) + RMS_EPS); }
; template <class Epi, class Sched, bool ALIGN_EPI = false, bool SP2 = false>
; __device__ __forceinline__ void gemm_phase(PG8_LAS unsigned char* lds, const Gemm g, const Sched& S, const Epi& E) {
;     ...
;             PG8_LDA(At, 1, 1); PG8_STAGE(PG8_SB(1, 0), b3, voffB); PG8_STAGE(PG8_SB(1, 1), b3 + hstep, voffB); PG8_STAGE(PG8_SA(1, 0), a3, voffA);
;             PG8_WAIT_V(8); PG8_WAIT_L(0); PG8_BAR; PG8_MMA(1, 0, At, B0); PG8_MMA(1, 1, At, B1); PG8_BAR; PG8_SCHED;
	s_add_i32 s3, s3, s14
	v_lshl_add_u64 v[202:203], v[202:203], 0, s[36:37]
	s_mov_b32 m0, s3
	ds_read_b128 v[186:189], v157 offset:49152
	ds_read_b128 v[190:193], v157 offset:50176
	ds_read_b128 v[194:197], v157 offset:51200
	ds_read_b128 v[198:201], v157 offset:52224
	ds_read_b128 v[208:211], v157 offset:53248
	ds_read_b128 v[212:215], v157 offset:54272
	ds_read_b128 v[216:219], v157 offset:55296
	ds_read_b128 v[220:223], v157 offset:56320
	global_load_lds_dwordx4 v[202:203], off
	s_add_i32 m0, s3, 0x2000
	s_add_u32 s56, s56, 0x40080
	v_lshl_add_u64 v[202:203], v[224:225], 0, s[36:37]
	s_addc_u32 s57, s57, 0
	s_add_i32 s3, s33, s14
	global_load_lds_dwordx4 v[202:203], off
	v_lshl_add_u64 v[202:203], s[56:57], 0, v[132:133]
	s_mov_b32 m0, s3
	s_nop 0
	global_load_lds_dwordx4 v[202:203], off
	v_lshl_add_u64 v[202:203], s[56:57], 0, v[128:129]
	s_add_i32 m0, s3, 0x2000
	s_nop 0
	global_load_lds_dwordx4 v[202:203], off
	s_waitcnt vmcnt(6)
	s_waitcnt lgkmcnt(0)
	s_barrier
	s_setprio 1
	s_waitcnt lgkmcnt(0)
	v_mfma_f32_16x16x32_bf16 v[60:63], v[144:147], v[186:189], v[60:63]
	v_mfma_f32_16x16x32_bf16 v[56:59], v[160:163], v[186:189], v[56:59]
	v_mfma_f32_16x16x32_bf16 v[44:47], v[144:147], v[194:197], v[44:47]
	v_mfma_f32_16x16x32_bf16 v[40:43], v[160:163], v[194:197], v[40:43]
	v_mfma_f32_16x16x32_bf16 v[28:31], v[144:147], v[208:211], v[28:31]
	v_mfma_f32_16x16x32_bf16 v[24:27], v[160:163], v[208:211], v[24:27]
	v_lshl_add_u64 v[202:203], v[226:227], 0, s[36:37]
	s_mov_b32 m0, s63
	s_nop 0
	global_load_lds_dwordx4 v[202:203], off
	v_mfma_f32_16x16x32_bf16 v[12:15], v[144:147], v[216:219], v[12:15]
	v_mfma_f32_16x16x32_bf16 v[8:11], v[160:163], v[216:219], v[8:11]
	v_mfma_f32_16x16x32_bf16 v[60:63], v[148:151], v[190:193], v[60:63]
	v_mfma_f32_16x16x32_bf16 v[56:59], v[164:167], v[190:193], v[56:59]
	v_mfma_f32_16x16x32_bf16 v[44:47], v[148:151], v[198:201], v[44:47]
	v_mfma_f32_16x16x32_bf16 v[40:43], v[164:167], v[198:201], v[40:43]
	v_mfma_f32_16x16x32_bf16 v[28:31], v[148:151], v[212:215], v[28:31]
	v_mfma_f32_16x16x32_bf16 v[24:27], v[164:167], v[212:215], v[24:27]
	v_mfma_f32_16x16x32_bf16 v[12:15], v[148:151], v[220:223], v[12:15]
	v_mfma_f32_16x16x32_bf16 v[8:11], v[164:167], v[220:223], v[8:11]
	s_setprio 0
	s_setprio 1
	v_mfma_f32_16x16x32_bf16 v[52:55], v[168:171], v[186:189], v[52:55]
	v_mfma_f32_16x16x32_bf16 v[48:51], v[176:179], v[186:189], v[48:51]
	v_lshl_add_u64 v[202:203], v[228:229], 0, s[36:37]
	s_mov_b32 m0, s64
	s_nop 0
	global_load_lds_dwordx4 v[202:203], off
	v_mfma_f32_16x16x32_bf16 v[36:39], v[168:171], v[194:197], v[36:39]
	v_mfma_f32_16x16x32_bf16 v[32:35], v[176:179], v[194:197], v[32:35]
	v_mfma_f32_16x16x32_bf16 v[20:23], v[168:171], v[208:211], v[20:23]
	v_mfma_f32_16x16x32_bf16 v[16:19], v[176:179], v[208:211], v[16:19]
	v_mfma_f32_16x16x32_bf16 v[4:7], v[168:171], v[216:219], v[4:7]
	v_mfma_f32_16x16x32_bf16 v[0:3], v[176:179], v[216:219], v[0:3]
	v_mfma_f32_16x16x32_bf16 v[52:55], v[172:175], v[190:193], v[52:55]
	v_mfma_f32_16x16x32_bf16 v[48:51], v[182:185], v[190:193], v[48:51]
	v_mfma_f32_16x16x32_bf16 v[36:39], v[172:175], v[198:201], v[36:39]
	v_mfma_f32_16x16x32_bf16 v[32:35], v[182:185], v[198:201], v[32:35]
	v_mfma_f32_16x16x32_bf16 v[20:23], v[172:175], v[212:215], v[20:23]
	v_mfma_f32_16x16x32_bf16 v[16:19], v[182:185], v[212:215], v[16:19]
	v_mfma_f32_16x16x32_bf16 v[4:7], v[172:175], v[220:223], v[4:7]
	v_mfma_f32_16x16x32_bf16 v[0:3], v[182:185], v[220:223], v[0:3]
	s_setprio 0
	s_barrier
	s_add_i32 s83, s83, 2
	s_add_u32 s54, s54, 0x100
	s_addc_u32 s55, s55, 0
	s_add_u32 s77, s77, 0x100
	s_addc_u32 s82, s82, 0
	s_cmp_gt_u32 s83, 13
	s_cbranch_scc0 .LBB0_957
	v_lshl_add_u32 v144, s52, 8, v152
	v_ashrrev_i32_e32 v145, 31, v144
	v_lshl_add_u64 v[150:151], v[144:145], 3, s[0:1]
	global_load_dwordx2 v[182:183], v[150:151], off
	global_load_dwordx2 v[184:185], v[150:151], off offset:128
	global_load_dwordx2 v[186:187], v[150:151], off offset:256
	global_load_dwordx2 v[188:189], v[150:151], off offset:384
	global_load_dwordx2 v[190:191], v[150:151], off offset:1024
	global_load_dwordx2 v[192:193], v[150:151], off offset:1152
	global_load_dwordx2 v[194:195], v[150:151], off offset:1280
	global_load_dwordx2 v[196:197], v[150:151], off offset:1408
	s_and_b64 vcc, exec, s[38:39]
	s_cbranch_vccz .LBB0_960
	s_barrier

; #define PG8_STAGE(bufoff, gbase, voff) do { _Pragma("unroll") for (int _i = 0; _i < 2; ++_i) \
;         __builtin_amdgcn_global_load_lds((const unsigned*)((const char*)(gbase) + (voff)[_i]), (PG8_LAS unsigned*)(lds + (bufoff) + ldsw + _i * 8192), 16, 0, 0); } while (0)
; #define PG8_LDA(dst, b, h) do { _Pragma("unroll") for (int m = 0; m < 4; ++m) _Pragma("unroll") for (int k = 0; k < 2; ++k) dst[m][k] = *(const PG8_LAS bf16x8*)(lds + PG8_SA(b, h) + aoff + m * 2048 + k * 1024); } while (0)
; #define PG8_LDB(dst, b, h) do { _Pragma("unroll") for (int n = 0; n < 2; ++n) _Pragma("unroll") for (int k = 0; k < 2; ++k) dst[n][k] = *(const PG8_LAS bf16x8*)(lds + PG8_SB(b, h) + boff + n * 2048 + k * 1024); } while (0)
; #define PG8_MMA(ai, bj, At, Bt) do { __builtin_amdgcn_s_setprio(1); _Pragma("unroll") for (int m = 0; m < 4; ++m) _Pragma("unroll") for (int n = 0; n < 2; ++n) _Pragma("unroll") for (int k = 0; k < 2; ++k) \
;         acc[ai][bj][m][n] = __builtin_amdgcn_mfma_f32_16x16x32_bf16(Bt[n][k], At[m][k], acc[ai][bj][m][n], 0, 0, 0); __builtin_amdgcn_s_setprio(0); } while (0)
; #define PG8_WAIT_V(n) asm volatile("s_waitcnt vmcnt(" #n ")" ::: "memory")
; #define PG8_WAIT_L(n) asm volatile("s_waitcnt lgkmcnt(" #n ")" ::: "memory")
; #define PG8_BAR __builtin_amdgcn_s_barrier()
; #define PG8_SCHED __builtin_amdgcn_sched_barrier(0)
; template <class Epi, class Sched, bool ALIGN_EPI = false, bool SP2 = false>
; __device__ __forceinline__ void gemm_phase(PG8_LAS unsigned char* lds, const Gemm g, const Sched& S, const Epi& E) {
;     ...
;             PG8_LDB(B0, 0, 0); PG8_LDB(B1, 0, 1); PG8_SCHED; PG8_LDA(At, 0, 0); PG8_STAGE(PG8_SA(1, 1), a1 + hstep, voffA);
;             PG8_WAIT_V(8); PG8_WAIT_L(0); PG8_BAR; PG8_MMA(0, 0, At, B0); PG8_MMA(0, 1, At, B1); PG8_BAR; PG8_SCHED;
;             PG8_LDA(At, 0, 1); PG8_STAGE(PG8_SB(0, 0), b2, voffB); PG8_STAGE(PG8_SB(0, 1), b2 + hstep, voffB); PG8_STAGE(PG8_SA(0, 0), a2, voffA);
;             PG8_WAIT_V(8); PG8_WAIT_L(0); PG8_BAR; PG8_MMA(1, 0, At, B0); PG8_MMA(1, 1, At, B1); PG8_BAR; PG8_SCHED;
.LBB0_1034:
	s_add_u32 s75, s52, 0x100
	s_addc_u32 s76, s53, 0
	s_mov_b32 s77, -2
	s_waitcnt lgkmcnt(0)
	ds_read_b128 v[144:147], v151
	ds_read_b128 v[156:159], v151 offset:1024
	ds_read_b128 v[160:163], v151 offset:2048
	ds_read_b128 v[164:167], v151 offset:3072
	ds_read_b128 v[168:171], v152
	ds_read_b128 v[172:175], v152 offset:1024
	ds_read_b128 v[176:179], v152 offset:2048
	ds_read_b128 v[182:185], v152 offset:3072
	s_add_u32 s52, s50, 0x100
	s_addc_u32 s53, s51, 0
	s_cmp_eq_u32 s77, 40
	s_cselect_b32 s57, s1, s53
	s_cselect_b32 s56, s0, s52
	s_cselect_b32 s55, s49, s76
	s_cselect_b32 s54, s48, s75
	v_lshl_add_u64 v[202:203], s[50:51], 0, v[136:137]
	s_add_i32 m0, s14, 0xc000
	ds_read_b128 v[186:189], v153
	ds_read_b128 v[190:193], v153 offset:1024
	ds_read_b128 v[194:197], v153 offset:2048
	ds_read_b128 v[198:201], v153 offset:3072
	ds_read_b128 v[208:211], v153 offset:4096
	ds_read_b128 v[212:215], v153 offset:5120
	ds_read_b128 v[216:219], v153 offset:6144
	ds_read_b128 v[220:223], v153 offset:7168
	global_load_lds_dwordx4 v[202:203], off
	v_lshl_add_u64 v[202:203], s[50:51], 0, v[138:139]
	s_add_i32 m0, s14, 0xe000
	s_nop 0
	global_load_lds_dwordx4 v[202:203], off
	s_waitcnt vmcnt(8)
	s_waitcnt lgkmcnt(0)
	s_barrier
	s_setprio 1
	s_waitcnt lgkmcnt(0)
	v_mfma_f32_16x16x32_bf16 v[124:127], v[144:147], v[186:189], 0
	v_mfma_f32_16x16x32_bf16 v[120:123], v[160:163], v[186:189], 0
	v_mfma_f32_16x16x32_bf16 v[108:111], v[144:147], v[194:197], 0
	v_mfma_f32_16x16x32_bf16 v[104:107], v[160:163], v[194:197], 0
	v_mfma_f32_16x16x32_bf16 v[92:95], v[144:147], v[208:211], 0
	v_mfma_f32_16x16x32_bf16 v[88:91], v[160:163], v[208:211], 0
	v_mfma_f32_16x16x32_bf16 v[76:79], v[144:147], v[216:219], 0
	v_mfma_f32_16x16x32_bf16 v[72:75], v[160:163], v[216:219], 0
	v_mfma_f32_16x16x32_bf16 v[124:127], v[156:159], v[190:193], v[124:127]
	v_mfma_f32_16x16x32_bf16 v[120:123], v[164:167], v[190:193], v[120:123]
	v_mfma_f32_16x16x32_bf16 v[108:111], v[156:159], v[198:201], v[108:111]
	v_mfma_f32_16x16x32_bf16 v[104:107], v[164:167], v[198:201], v[104:107]
	v_mfma_f32_16x16x32_bf16 v[92:95], v[156:159], v[212:215], v[92:95]
	v_mfma_f32_16x16x32_bf16 v[88:91], v[164:167], v[212:215], v[88:91]
	v_mfma_f32_16x16x32_bf16 v[76:79], v[156:159], v[220:223], v[76:79]
	v_mfma_f32_16x16x32_bf16 v[72:75], v[164:167], v[220:223], v[72:75]
	s_setprio 0
	s_setprio 1
	v_mfma_f32_16x16x32_bf16 v[116:119], v[168:171], v[186:189], 0
	v_mfma_f32_16x16x32_bf16 v[112:115], v[176:179], v[186:189], 0
	v_mfma_f32_16x16x32_bf16 v[100:103], v[168:171], v[194:197], 0
	v_mfma_f32_16x16x32_bf16 v[96:99], v[176:179], v[194:197], 0
	v_mfma_f32_16x16x32_bf16 v[84:87], v[168:171], v[208:211], 0
	v_mfma_f32_16x16x32_bf16 v[80:83], v[176:179], v[208:211], 0
	v_mfma_f32_16x16x32_bf16 v[68:71], v[168:171], v[216:219], 0
	v_mfma_f32_16x16x32_bf16 v[64:67], v[176:179], v[216:219], 0
	v_mfma_f32_16x16x32_bf16 v[116:119], v[172:175], v[190:193], v[116:119]
	v_mfma_f32_16x16x32_bf16 v[112:115], v[182:185], v[190:193], v[112:115]
	v_mfma_f32_16x16x32_bf16 v[100:103], v[172:175], v[198:201], v[100:103]
	v_mfma_f32_16x16x32_bf16 v[96:99], v[182:185], v[198:201], v[96:99]
	v_mfma_f32_16x16x32_bf16 v[84:87], v[172:175], v[212:215], v[84:87]
	v_mfma_f32_16x16x32_bf16 v[80:83], v[182:185], v[212:215], v[80:83]
	v_mfma_f32_16x16x32_bf16 v[68:71], v[172:175], v[220:223], v[68:71]
	v_mfma_f32_16x16x32_bf16 v[64:67], v[182:185], v[220:223], v[64:67]
	s_setprio 0
	s_barrier
	s_add_i32 s50, s61, s3
	v_lshl_add_u64 v[202:203], s[54:55], 0, v[130:131]
	s_mov_b32 m0, s50
	ds_read_b128 v[186:189], v153 offset:16384
	ds_read_b128 v[190:193], v153 offset:17408
	ds_read_b128 v[194:197], v153 offset:18432
	ds_read_b128 v[198:201], v153 offset:19456
	ds_read_b128 v[208:211], v153 offset:20480
	ds_read_b128 v[212:215], v153 offset:21504
	ds_read_b128 v[216:219], v153 offset:22528
	ds_read_b128 v[220:223], v153 offset:23552
	global_load_lds_dwordx4 v[202:203], off
	s_add_i32 m0, s50, 0x2000
	s_add_u32 s50, s54, 0xb0000
	v_lshl_add_u64 v[224:225], s[54:55], 0, v[134:135]
	s_addc_u32 s51, s55, 0
	s_add_i32 s78, s62, s3
	global_load_lds_dwordx4 v[224:225], off
	v_lshl_add_u64 v[226:227], s[50:51], 0, v[130:131]
	s_mov_b32 m0, s78
	v_lshl_add_u64 v[228:229], s[56:57], 0, v[132:133]
	global_load_lds_dwordx4 v[226:227], off
	v_lshl_add_u64 v[226:227], s[50:51], 0, v[134:135]
	s_add_i32 m0, s78, 0x2000
	s_nop 0
	global_load_lds_dwordx4 v[226:227], off
	s_waitcnt vmcnt(6)
	s_waitcnt lgkmcnt(0)
	s_barrier
; #define PG8_STAGE(bufoff, gbase, voff) do { _Pragma("unroll") for (int _i = 0; _i < 2; ++_i) \
;         __builtin_amdgcn_global_load_lds((const unsigned*)((const char*)(gbase) + (voff)[_i]), (PG8_LAS unsigned*)(lds + (bufoff) + ldsw + _i * 8192), 16, 0, 0); } while (0)
; #define PG8_LDA(dst, b, h) do { _Pragma("unroll") for (int m = 0; m < 4; ++m) _Pragma("unroll") for (int k = 0; k < 2; ++k) dst[m][k] = *(const PG8_LAS bf16x8*)(lds + PG8_SA(b, h) + aoff + m * 2048 + k * 1024); } while (0)
; #define PG8_LDB(dst, b, h) do { _Pragma("unroll") for (int n = 0; n < 2; ++n) _Pragma("unroll") for (int k = 0; k < 2; ++k) dst[n][k] = *(const PG8_LAS bf16x8*)(lds + PG8_SB(b, h) + boff + n * 2048 + k * 1024); } while (0)
; #define PG8_MMA(ai, bj, At, Bt) do { __builtin_amdgcn_s_setprio(1); _Pragma("unroll") for (int m = 0; m < 4; ++m) _Pragma("unroll") for (int n = 0; n < 2; ++n) _Pragma("unroll") for (int k = 0; k < 2; ++k) \
;         acc[ai][bj][m][n] = __builtin_amdgcn_mfma_f32_16x16x32_bf16(Bt[n][k], At[m][k], acc[ai][bj][m][n], 0, 0, 0); __builtin_amdgcn_s_setprio(0); } while (0)
; #define PG8_WAIT_V(n) asm volatile("s_waitcnt vmcnt(" #n ")" ::: "memory")
; #define PG8_WAIT_L(n) asm volatile("s_waitcnt lgkmcnt(" #n ")" ::: "memory")
; #define PG8_BAR __builtin_amdgcn_s_barrier()
; #define PG8_SCHED __builtin_amdgcn_sched_barrier(0)
; template <class Epi, class Sched, bool ALIGN_EPI = false, bool SP2 = false>
; __device__ __forceinline__ void gemm_phase(PG8_LAS unsigned char* lds, const Gemm g, const Sched& S, const Epi& E) {
;     ...
;             PG8_WAIT_V(8); PG8_WAIT_L(0); PG8_BAR; PG8_MMA(1, 0, At, B0); PG8_MMA(1, 1, At, B1); PG8_BAR; PG8_SCHED;
;             PG8_LDB(B0, 1, 0); PG8_LDB(B1, 1, 1); PG8_SCHED; PG8_LDA(At, 1, 0); PG8_STAGE(PG8_SA(0, 1), a2 + hstep, voffA);
;             PG8_WAIT_V(8); PG8_WAIT_L(0); PG8_BAR; PG8_MMA(0, 0, At, B0); PG8_MMA(0, 1, At, B1); PG8_BAR; PG8_SCHED;
	s_setprio 1
	s_waitcnt lgkmcnt(0)
	v_mfma_f32_16x16x32_bf16 v[60:63], v[144:147], v[186:189], 0
	v_mfma_f32_16x16x32_bf16 v[56:59], v[160:163], v[186:189], 0
	v_mfma_f32_16x16x32_bf16 v[44:47], v[144:147], v[194:197], 0
	v_mfma_f32_16x16x32_bf16 v[40:43], v[160:163], v[194:197], 0
	v_mfma_f32_16x16x32_bf16 v[28:31], v[144:147], v[208:211], 0
	v_mfma_f32_16x16x32_bf16 v[24:27], v[160:163], v[208:211], 0
	v_lshl_add_u64 v[226:227], s[56:57], 0, v[128:129]
	s_mov_b32 m0, s14
	s_nop 0
	global_load_lds_dwordx4 v[226:227], off
	v_mfma_f32_16x16x32_bf16 v[12:15], v[144:147], v[216:219], 0
	v_mfma_f32_16x16x32_bf16 v[8:11], v[160:163], v[216:219], 0
	v_mfma_f32_16x16x32_bf16 v[60:63], v[156:159], v[190:193], v[60:63]
	v_mfma_f32_16x16x32_bf16 v[56:59], v[164:167], v[190:193], v[56:59]
	v_mfma_f32_16x16x32_bf16 v[44:47], v[156:159], v[198:201], v[44:47]
	v_mfma_f32_16x16x32_bf16 v[40:43], v[164:167], v[198:201], v[40:43]
	v_mfma_f32_16x16x32_bf16 v[28:31], v[156:159], v[212:215], v[28:31]
	v_mfma_f32_16x16x32_bf16 v[24:27], v[164:167], v[212:215], v[24:27]
	v_mfma_f32_16x16x32_bf16 v[12:15], v[156:159], v[220:223], v[12:15]
	v_mfma_f32_16x16x32_bf16 v[8:11], v[164:167], v[220:223], v[8:11]
	s_setprio 0
	s_setprio 1
	v_mfma_f32_16x16x32_bf16 v[52:55], v[168:171], v[186:189], 0
	v_mfma_f32_16x16x32_bf16 v[48:51], v[176:179], v[186:189], 0
	s_mov_b32 m0, s15
	s_nop 0
	global_load_lds_dwordx4 v[228:229], off
	v_mfma_f32_16x16x32_bf16 v[36:39], v[168:171], v[194:197], 0
	v_mfma_f32_16x16x32_bf16 v[32:35], v[176:179], v[194:197], 0
	v_mfma_f32_16x16x32_bf16 v[20:23], v[168:171], v[208:211], 0
	v_mfma_f32_16x16x32_bf16 v[16:19], v[176:179], v[208:211], 0
	v_mfma_f32_16x16x32_bf16 v[4:7], v[168:171], v[216:219], 0
	v_mfma_f32_16x16x32_bf16 v[0:3], v[176:179], v[216:219], 0
	v_mfma_f32_16x16x32_bf16 v[52:55], v[172:175], v[190:193], v[52:55]
	v_mfma_f32_16x16x32_bf16 v[48:51], v[182:185], v[190:193], v[48:51]
	v_mfma_f32_16x16x32_bf16 v[36:39], v[172:175], v[198:201], v[36:39]
	v_mfma_f32_16x16x32_bf16 v[32:35], v[182:185], v[198:201], v[32:35]
	v_mfma_f32_16x16x32_bf16 v[20:23], v[172:175], v[212:215], v[20:23]
	v_mfma_f32_16x16x32_bf16 v[16:19], v[182:185], v[212:215], v[16:19]
	v_mfma_f32_16x16x32_bf16 v[4:7], v[172:175], v[220:223], v[4:7]
	v_mfma_f32_16x16x32_bf16 v[0:3], v[182:185], v[220:223], v[0:3]
	s_setprio 0
	s_barrier
	s_add_i32 s78, 0, 0x18000
	v_add_u32_e32 v155, s78, v149
	s_add_i32 s79, 0, 0x1c000
	ds_read_b128 v[144:147], v155
	ds_read_b128 v[156:159], v155 offset:1024
	ds_read_b128 v[160:163], v155 offset:2048
	ds_read_b128 v[164:167], v155 offset:3072
	v_add_u32_e32 v155, s79, v149
	ds_read_b128 v[168:171], v155
	ds_read_b128 v[172:175], v155 offset:1024
	ds_read_b128 v[176:179], v155 offset:2048
	ds_read_b128 v[182:185], v155 offset:3072
	s_add_u32 s50, s56, 0xb0000
	s_addc_u32 s51, s57, 0
	s_mov_b32 m0, s33
	v_lshl_add_u64 v[230:231], s[50:51], 0, v[128:129]
	ds_read_b128 v[186:189], v153 offset:32768
	ds_read_b128 v[190:193], v153 offset:33792
	ds_read_b128 v[194:197], v153 offset:34816
	ds_read_b128 v[198:201], v153 offset:35840
	ds_read_b128 v[208:211], v153 offset:36864
	ds_read_b128 v[212:215], v153 offset:37888
	ds_read_b128 v[216:219], v153 offset:38912
	ds_read_b128 v[220:223], v153 offset:39936
	global_load_lds_dwordx4 v[230:231], off
	v_lshl_add_u64 v[230:231], s[50:51], 0, v[132:133]
	s_mov_b32 m0, s34
	s_nop 0
	global_load_lds_dwordx4 v[230:231], off
	s_waitcnt vmcnt(8)
	s_waitcnt lgkmcnt(0)
	s_barrier
	s_setprio 1
	s_waitcnt lgkmcnt(0)
	v_mfma_f32_16x16x32_bf16 v[124:127], v[144:147], v[186:189], v[124:127]
	v_mfma_f32_16x16x32_bf16 v[120:123], v[160:163], v[186:189], v[120:123]
	v_mfma_f32_16x16x32_bf16 v[108:111], v[144:147], v[194:197], v[108:111]
	v_mfma_f32_16x16x32_bf16 v[104:107], v[160:163], v[194:197], v[104:107]
	v_mfma_f32_16x16x32_bf16 v[92:95], v[144:147], v[208:211], v[92:95]
	v_mfma_f32_16x16x32_bf16 v[88:91], v[160:163], v[208:211], v[88:91]
	v_mfma_f32_16x16x32_bf16 v[76:79], v[144:147], v[216:219], v[76:79]
	v_mfma_f32_16x16x32_bf16 v[72:75], v[160:163], v[216:219], v[72:75]
	v_mfma_f32_16x16x32_bf16 v[124:127], v[156:159], v[190:193], v[124:127]
	v_mfma_f32_16x16x32_bf16 v[120:123], v[164:167], v[190:193], v[120:123]
	v_mfma_f32_16x16x32_bf16 v[108:111], v[156:159], v[198:201], v[108:111]
	v_mfma_f32_16x16x32_bf16 v[104:107], v[164:167], v[198:201], v[104:107]
	v_mfma_f32_16x16x32_bf16 v[92:95], v[156:159], v[212:215], v[92:95]
	v_mfma_f32_16x16x32_bf16 v[88:91], v[164:167], v[212:215], v[88:91]
	v_mfma_f32_16x16x32_bf16 v[76:79], v[156:159], v[220:223], v[76:79]
	v_mfma_f32_16x16x32_bf16 v[72:75], v[164:167], v[220:223], v[72:75]
	s_setprio 0
	s_setprio 1
	v_mfma_f32_16x16x32_bf16 v[116:119], v[168:171], v[186:189], v[116:119]
	v_mfma_f32_16x16x32_bf16 v[112:115], v[176:179], v[186:189], v[112:115]
	v_mfma_f32_16x16x32_bf16 v[100:103], v[168:171], v[194:197], v[100:103]
	v_mfma_f32_16x16x32_bf16 v[96:99], v[176:179], v[194:197], v[96:99]
	v_mfma_f32_16x16x32_bf16 v[84:87], v[168:171], v[208:211], v[84:87]
	v_mfma_f32_16x16x32_bf16 v[80:83], v[176:179], v[208:211], v[80:83]
	v_mfma_f32_16x16x32_bf16 v[68:71], v[168:171], v[216:219], v[68:71]
	v_mfma_f32_16x16x32_bf16 v[64:67], v[176:179], v[216:219], v[64:67]
	v_mfma_f32_16x16x32_bf16 v[116:119], v[172:175], v[190:193], v[116:119]
	v_mfma_f32_16x16x32_bf16 v[112:115], v[182:185], v[190:193], v[112:115]
	v_mfma_f32_16x16x32_bf16 v[100:103], v[172:175], v[198:201], v[100:103]
	v_mfma_f32_16x16x32_bf16 v[96:99], v[182:185], v[198:201], v[96:99]
	v_mfma_f32_16x16x32_bf16 v[84:87], v[172:175], v[212:215], v[84:87]
	v_mfma_f32_16x16x32_bf16 v[80:83], v[182:185], v[212:215], v[80:83]
	v_mfma_f32_16x16x32_bf16 v[68:71], v[172:175], v[220:223], v[68:71]
	v_mfma_f32_16x16x32_bf16 v[64:67], v[182:185], v[220:223], v[64:67]
	s_setprio 0
	s_barrier
; #define PG8_STAGE(bufoff, gbase, voff) do { _Pragma("unroll") for (int _i = 0; _i < 2; ++_i) \
;         __builtin_amdgcn_global_load_lds((const unsigned*)((const char*)(gbase) + (voff)[_i]), (PG8_LAS unsigned*)(lds + (bufoff) + ldsw + _i * 8192), 16, 0, 0); } while (0)
; #define PG8_LDA(dst, b, h) do { _Pragma("unroll") for (int m = 0; m < 4; ++m) _Pragma("unroll") for (int k = 0; k < 2; ++k) dst[m][k] = *(const PG8_LAS bf16x8*)(lds + PG8_SA(b, h) + aoff + m * 2048 + k * 1024); } while (0)
; #define PG8_LDB(dst, b, h) do { _Pragma("unroll") for (int n = 0; n < 2; ++n) _Pragma("unroll") for (int k = 0; k < 2; ++k) dst[n][k] = *(const PG8_LAS bf16x8*)(lds + PG8_SB(b, h) + boff + n * 2048 + k * 1024); } while (0)
; #define PG8_MMA(ai, bj, At, Bt) do { __builtin_amdgcn_s_setprio(1); _Pragma("unroll") for (int m = 0; m < 4; ++m) _Pragma("unroll") for (int n = 0; n < 2; ++n) _Pragma("unroll") for (int k = 0; k < 2; ++k) \
;         acc[ai][bj][m][n] = __builtin_amdgcn_mfma_f32_16x16x32_bf16(Bt[n][k], At[m][k], acc[ai][bj][m][n], 0, 0, 0); __builtin_amdgcn_s_setprio(0); } while (0)
; #define PG8_WAIT_V(n) asm volatile("s_waitcnt vmcnt(" #n ")" ::: "memory")
; template <class Epi, class Sched, bool ALIGN_EPI = false, bool SP2 = false>
; __device__ __forceinline__ void gemm_phase(PG8_LAS unsigned char* lds, const Gemm g, const Sched& S, const Epi& E) {
;     ...
;             PG8_LDB(B0, 0, 0); PG8_LDB(B1, 0, 1); PG8_SCHED; PG8_LDA(At, 0, 0); PG8_STAGE(PG8_SA(1, 1), a1 + hstep, voffA);
;             PG8_WAIT_V(8); PG8_WAIT_L(0); PG8_BAR; PG8_MMA(0, 0, At, B0); PG8_MMA(0, 1, At, B1); PG8_BAR; PG8_SCHED;
;             PG8_LDA(At, 0, 1); PG8_STAGE(PG8_SB(0, 0), b2, voffB); PG8_STAGE(PG8_SB(0, 1), b2 + hstep, voffB); PG8_STAGE(PG8_SA(0, 0), a2, voffA);
;             PG8_WAIT_V(8); PG8_WAIT_L(0); PG8_BAR; PG8_MMA(1, 0, At, B0); PG8_MMA(1, 1, At, B1); PG8_BAR; PG8_SCHED;
;             PG8_LDB(B0, 1, 0); PG8_LDB(B1, 1, 1); PG8_SCHED; PG8_LDA(At, 1, 0); PG8_STAGE(PG8_SA(0, 1), a2 + hstep, voffA);
;             PG8_WAIT_V(8); PG8_WAIT_L(0); PG8_BAR; PG8_MMA(0, 0, At, B0); PG8_MMA(0, 1, At, B1); PG8_BAR; PG8_SCHED;
;             PG8_LDA(At, 1, 1); PG8_STAGE(PG8_SB(1, 0), b3, voffB); PG8_STAGE(PG8_SB(1, 1), b3 + hstep, voffB); PG8_STAGE(PG8_SA(1, 0), a3, voffA);
;             PG8_WAIT_V(8); PG8_WAIT_L(0); PG8_BAR; PG8_MMA(1, 0, At, B0); PG8_MMA(1, 1, At, B1); PG8_BAR; PG8_SCHED;
	s_add_i32 s50, s78, s3
	v_lshl_add_u64 v[202:203], v[202:203], 0, s[42:43]
	s_mov_b32 m0, s50
	ds_read_b128 v[186:189], v153 offset:49152
	ds_read_b128 v[190:193], v153 offset:50176
	ds_read_b128 v[194:197], v153 offset:51200
	ds_read_b128 v[198:201], v153 offset:52224
	ds_read_b128 v[208:211], v153 offset:53248
	ds_read_b128 v[212:215], v153 offset:54272
	ds_read_b128 v[216:219], v153 offset:55296
	ds_read_b128 v[220:223], v153 offset:56320
	global_load_lds_dwordx4 v[202:203], off
	s_add_i32 m0, s50, 0x2000
	s_add_u32 s50, s54, 0xb0080
	v_lshl_add_u64 v[202:203], v[224:225], 0, s[42:43]
	s_addc_u32 s51, s55, 0
	s_add_i32 s54, s79, s3
	global_load_lds_dwordx4 v[202:203], off
	v_lshl_add_u64 v[202:203], s[50:51], 0, v[130:131]
	s_mov_b32 m0, s54
	s_nop 0
	global_load_lds_dwordx4 v[202:203], off
	v_lshl_add_u64 v[202:203], s[50:51], 0, v[134:135]
	s_add_i32 m0, s54, 0x2000
	s_nop 0
	global_load_lds_dwordx4 v[202:203], off
	s_waitcnt vmcnt(6)
	s_waitcnt lgkmcnt(0)
	s_barrier
	s_setprio 1
	s_waitcnt lgkmcnt(0)
	v_mfma_f32_16x16x32_bf16 v[60:63], v[144:147], v[186:189], v[60:63]
	v_mfma_f32_16x16x32_bf16 v[56:59], v[160:163], v[186:189], v[56:59]
	v_mfma_f32_16x16x32_bf16 v[44:47], v[144:147], v[194:197], v[44:47]
	v_mfma_f32_16x16x32_bf16 v[40:43], v[160:163], v[194:197], v[40:43]
	v_mfma_f32_16x16x32_bf16 v[28:31], v[144:147], v[208:211], v[28:31]
	v_mfma_f32_16x16x32_bf16 v[24:27], v[160:163], v[208:211], v[24:27]
	v_lshl_add_u64 v[202:203], v[226:227], 0, s[42:43]
	s_mov_b32 m0, s59
	s_nop 0
	global_load_lds_dwordx4 v[202:203], off
	v_mfma_f32_16x16x32_bf16 v[12:15], v[144:147], v[216:219], v[12:15]
	v_mfma_f32_16x16x32_bf16 v[8:11], v[160:163], v[216:219], v[8:11]
	v_mfma_f32_16x16x32_bf16 v[60:63], v[156:159], v[190:193], v[60:63]
	v_mfma_f32_16x16x32_bf16 v[56:59], v[164:167], v[190:193], v[56:59]
	v_mfma_f32_16x16x32_bf16 v[44:47], v[156:159], v[198:201], v[44:47]
	v_mfma_f32_16x16x32_bf16 v[40:43], v[164:167], v[198:201], v[40:43]
	v_mfma_f32_16x16x32_bf16 v[28:31], v[156:159], v[212:215], v[28:31]
	v_mfma_f32_16x16x32_bf16 v[24:27], v[164:167], v[212:215], v[24:27]
	v_mfma_f32_16x16x32_bf16 v[12:15], v[156:159], v[220:223], v[12:15]
	v_mfma_f32_16x16x32_bf16 v[8:11], v[164:167], v[220:223], v[8:11]
	s_setprio 0
	s_setprio 1
	v_mfma_f32_16x16x32_bf16 v[52:55], v[168:171], v[186:189], v[52:55]
	v_mfma_f32_16x16x32_bf16 v[48:51], v[176:179], v[186:189], v[48:51]
	v_lshl_add_u64 v[202:203], v[228:229], 0, s[42:43]
	s_mov_b32 m0, s60
	s_nop 0
	global_load_lds_dwordx4 v[202:203], off
	v_mfma_f32_16x16x32_bf16 v[36:39], v[168:171], v[194:197], v[36:39]
	v_mfma_f32_16x16x32_bf16 v[32:35], v[176:179], v[194:197], v[32:35]
	v_mfma_f32_16x16x32_bf16 v[20:23], v[168:171], v[208:211], v[20:23]
	v_mfma_f32_16x16x32_bf16 v[16:19], v[176:179], v[208:211], v[16:19]
	v_mfma_f32_16x16x32_bf16 v[4:7], v[168:171], v[216:219], v[4:7]
	v_mfma_f32_16x16x32_bf16 v[0:3], v[176:179], v[216:219], v[0:3]
	v_mfma_f32_16x16x32_bf16 v[52:55], v[172:175], v[190:193], v[52:55]
	v_mfma_f32_16x16x32_bf16 v[48:51], v[182:185], v[190:193], v[48:51]
	v_mfma_f32_16x16x32_bf16 v[36:39], v[172:175], v[198:201], v[36:39]
	v_mfma_f32_16x16x32_bf16 v[32:35], v[182:185], v[198:201], v[32:35]
	v_mfma_f32_16x16x32_bf16 v[20:23], v[172:175], v[212:215], v[20:23]
	v_mfma_f32_16x16x32_bf16 v[16:19], v[182:185], v[212:215], v[16:19]
	v_mfma_f32_16x16x32_bf16 v[4:7], v[172:175], v[220:223], v[4:7]
	v_mfma_f32_16x16x32_bf16 v[0:3], v[182:185], v[220:223], v[0:3]
	s_setprio 0
	s_barrier
	s_add_i32 s77, s77, 2
	s_add_u32 s75, s75, 0x100
	s_addc_u32 s76, s76, 0
	s_mov_b64 s[50:51], s[52:53]
.LBB0_1035:
	ds_read_b128 v[144:147], v151
	ds_read_b128 v[156:159], v151 offset:1024
	ds_read_b128 v[160:163], v151 offset:2048
	ds_read_b128 v[164:167], v151 offset:3072
	ds_read_b128 v[168:171], v152
	ds_read_b128 v[172:175], v152 offset:1024
	ds_read_b128 v[176:179], v152 offset:2048
	ds_read_b128 v[182:185], v152 offset:3072
	s_add_u32 s52, s50, 0x100
	s_addc_u32 s53, s51, 0
	s_cmp_eq_u32 s77, 40
	s_cselect_b32 s57, s1, s53
	s_cselect_b32 s56, s0, s52
	s_cselect_b32 s55, s49, s76
	s_cselect_b32 s54, s48, s75
	v_lshl_add_u64 v[202:203], s[50:51], 0, v[136:137]
	s_add_i32 m0, s14, 0xc000
	ds_read_b128 v[186:189], v153
	ds_read_b128 v[190:193], v153 offset:1024
	ds_read_b128 v[194:197], v153 offset:2048
	ds_read_b128 v[198:201], v153 offset:3072
	ds_read_b128 v[208:211], v153 offset:4096
	ds_read_b128 v[212:215], v153 offset:5120
	ds_read_b128 v[216:219], v153 offset:6144
	ds_read_b128 v[220:223], v153 offset:7168
	global_load_lds_dwordx4 v[202:203], off
	v_lshl_add_u64 v[202:203], s[50:51], 0, v[138:139]
	s_add_i32 m0, s14, 0xe000
	s_nop 0
	global_load_lds_dwordx4 v[202:203], off
	s_waitcnt vmcnt(8)
	s_waitcnt lgkmcnt(0)
	s_barrier
; #define PG8_STAGE(bufoff, gbase, voff) do { _Pragma("unroll") for (int _i = 0; _i < 2; ++_i) \
;         __builtin_amdgcn_global_load_lds((const unsigned*)((const char*)(gbase) + (voff)[_i]), (PG8_LAS unsigned*)(lds + (bufoff) + ldsw + _i * 8192), 16, 0, 0); } while (0)
; #define PG8_LDA(dst, b, h) do { _Pragma("unroll") for (int m = 0; m < 4; ++m) _Pragma("unroll") for (int k = 0; k < 2; ++k) dst[m][k] = *(const PG8_LAS bf16x8*)(lds + PG8_SA(b, h) + aoff + m * 2048 + k * 1024); } while (0)
; #define PG8_MMA(ai, bj, At, Bt) do { __builtin_amdgcn_s_setprio(1); _Pragma("unroll") for (int m = 0; m < 4; ++m) _Pragma("unroll") for (int n = 0; n < 2; ++n) _Pragma("unroll") for (int k = 0; k < 2; ++k) \
;         acc[ai][bj][m][n] = __builtin_amdgcn_mfma_f32_16x16x32_bf16(Bt[n][k], At[m][k], acc[ai][bj][m][n], 0, 0, 0); __builtin_amdgcn_s_setprio(0); } while (0)
; #define PG8_WAIT_V(n) asm volatile("s_waitcnt vmcnt(" #n ")" ::: "memory")
; #define PG8_WAIT_L(n) asm volatile("s_waitcnt lgkmcnt(" #n ")" ::: "memory")
; #define PG8_BAR __builtin_amdgcn_s_barrier()
; #define PG8_SCHED __builtin_amdgcn_sched_barrier(0)
; template <class Epi, class Sched, bool ALIGN_EPI = false, bool SP2 = false>
; __device__ __forceinline__ void gemm_phase(PG8_LAS unsigned char* lds, const Gemm g, const Sched& S, const Epi& E) {
;     ...
;             PG8_WAIT_V(8); PG8_WAIT_L(0); PG8_BAR; PG8_MMA(0, 0, At, B0); PG8_MMA(0, 1, At, B1); PG8_BAR; PG8_SCHED;
;             PG8_LDA(At, 0, 1); PG8_STAGE(PG8_SB(0, 0), b2, voffB); PG8_STAGE(PG8_SB(0, 1), b2 + hstep, voffB); PG8_STAGE(PG8_SA(0, 0), a2, voffA);
;             PG8_WAIT_V(8); PG8_WAIT_L(0); PG8_BAR; PG8_MMA(1, 0, At, B0); PG8_MMA(1, 1, At, B1); PG8_BAR; PG8_SCHED;
	s_setprio 1
	s_waitcnt lgkmcnt(0)
	v_mfma_f32_16x16x32_bf16 v[124:127], v[144:147], v[186:189], v[124:127]
	v_mfma_f32_16x16x32_bf16 v[120:123], v[160:163], v[186:189], v[120:123]
	v_mfma_f32_16x16x32_bf16 v[108:111], v[144:147], v[194:197], v[108:111]
	v_mfma_f32_16x16x32_bf16 v[104:107], v[160:163], v[194:197], v[104:107]
	v_mfma_f32_16x16x32_bf16 v[92:95], v[144:147], v[208:211], v[92:95]
	v_mfma_f32_16x16x32_bf16 v[88:91], v[160:163], v[208:211], v[88:91]
	v_mfma_f32_16x16x32_bf16 v[76:79], v[144:147], v[216:219], v[76:79]
	v_mfma_f32_16x16x32_bf16 v[72:75], v[160:163], v[216:219], v[72:75]
	v_mfma_f32_16x16x32_bf16 v[124:127], v[156:159], v[190:193], v[124:127]
	v_mfma_f32_16x16x32_bf16 v[120:123], v[164:167], v[190:193], v[120:123]
	v_mfma_f32_16x16x32_bf16 v[108:111], v[156:159], v[198:201], v[108:111]
	v_mfma_f32_16x16x32_bf16 v[104:107], v[164:167], v[198:201], v[104:107]
	v_mfma_f32_16x16x32_bf16 v[92:95], v[156:159], v[212:215], v[92:95]
	v_mfma_f32_16x16x32_bf16 v[88:91], v[164:167], v[212:215], v[88:91]
	v_mfma_f32_16x16x32_bf16 v[76:79], v[156:159], v[220:223], v[76:79]
	v_mfma_f32_16x16x32_bf16 v[72:75], v[164:167], v[220:223], v[72:75]
	s_setprio 0
	s_setprio 1
	v_mfma_f32_16x16x32_bf16 v[116:119], v[168:171], v[186:189], v[116:119]
	v_mfma_f32_16x16x32_bf16 v[112:115], v[176:179], v[186:189], v[112:115]
	v_mfma_f32_16x16x32_bf16 v[100:103], v[168:171], v[194:197], v[100:103]
	v_mfma_f32_16x16x32_bf16 v[96:99], v[176:179], v[194:197], v[96:99]
	v_mfma_f32_16x16x32_bf16 v[84:87], v[168:171], v[208:211], v[84:87]
	v_mfma_f32_16x16x32_bf16 v[80:83], v[176:179], v[208:211], v[80:83]
	v_mfma_f32_16x16x32_bf16 v[68:71], v[168:171], v[216:219], v[68:71]
	v_mfma_f32_16x16x32_bf16 v[64:67], v[176:179], v[216:219], v[64:67]
	v_mfma_f32_16x16x32_bf16 v[116:119], v[172:175], v[190:193], v[116:119]
	v_mfma_f32_16x16x32_bf16 v[112:115], v[182:185], v[190:193], v[112:115]
	v_mfma_f32_16x16x32_bf16 v[100:103], v[172:175], v[198:201], v[100:103]
	v_mfma_f32_16x16x32_bf16 v[96:99], v[182:185], v[198:201], v[96:99]
	v_mfma_f32_16x16x32_bf16 v[84:87], v[172:175], v[212:215], v[84:87]
	v_mfma_f32_16x16x32_bf16 v[80:83], v[182:185], v[212:215], v[80:83]
	v_mfma_f32_16x16x32_bf16 v[68:71], v[172:175], v[220:223], v[68:71]
	v_mfma_f32_16x16x32_bf16 v[64:67], v[182:185], v[220:223], v[64:67]
	s_setprio 0
	s_barrier
	s_add_i32 s50, s61, s3
	v_lshl_add_u64 v[202:203], s[54:55], 0, v[130:131]
	s_mov_b32 m0, s50
	ds_read_b128 v[186:189], v153 offset:16384
	ds_read_b128 v[190:193], v153 offset:17408
	ds_read_b128 v[194:197], v153 offset:18432
	ds_read_b128 v[198:201], v153 offset:19456
	ds_read_b128 v[208:211], v153 offset:20480
	ds_read_b128 v[212:215], v153 offset:21504
	ds_read_b128 v[216:219], v153 offset:22528
	ds_read_b128 v[220:223], v153 offset:23552
	global_load_lds_dwordx4 v[202:203], off
	s_add_i32 m0, s50, 0x2000
	s_add_u32 s50, s54, 0xb0000
	v_lshl_add_u64 v[224:225], s[54:55], 0, v[134:135]
	s_addc_u32 s51, s55, 0
	s_add_i32 s78, s62, s3
	global_load_lds_dwordx4 v[224:225], off
	v_lshl_add_u64 v[226:227], s[50:51], 0, v[130:131]
	s_mov_b32 m0, s78
	v_lshl_add_u64 v[228:229], s[56:57], 0, v[132:133]
	global_load_lds_dwordx4 v[226:227], off
	v_lshl_add_u64 v[226:227], s[50:51], 0, v[134:135]
	s_add_i32 m0, s78, 0x2000
	s_nop 0
	global_load_lds_dwordx4 v[226:227], off
	s_waitcnt vmcnt(6)
	s_waitcnt lgkmcnt(0)
	s_barrier
	s_setprio 1
	s_waitcnt lgkmcnt(0)
	v_mfma_f32_16x16x32_bf16 v[60:63], v[144:147], v[186:189], v[60:63]
	v_mfma_f32_16x16x32_bf16 v[56:59], v[160:163], v[186:189], v[56:59]
	v_mfma_f32_16x16x32_bf16 v[44:47], v[144:147], v[194:197], v[44:47]
	v_mfma_f32_16x16x32_bf16 v[40:43], v[160:163], v[194:197], v[40:43]
	v_mfma_f32_16x16x32_bf16 v[28:31], v[144:147], v[208:211], v[28:31]
	v_mfma_f32_16x16x32_bf16 v[24:27], v[160:163], v[208:211], v[24:27]
	v_lshl_add_u64 v[226:227], s[56:57], 0, v[128:129]
	s_mov_b32 m0, s14
	s_nop 0
	global_load_lds_dwordx4 v[226:227], off
	v_mfma_f32_16x16x32_bf16 v[12:15], v[144:147], v[216:219], v[12:15]
	v_mfma_f32_16x16x32_bf16 v[8:11], v[160:163], v[216:219], v[8:11]
	v_mfma_f32_16x16x32_bf16 v[60:63], v[156:159], v[190:193], v[60:63]
	v_mfma_f32_16x16x32_bf16 v[56:59], v[164:167], v[190:193], v[56:59]
	v_mfma_f32_16x16x32_bf16 v[44:47], v[156:159], v[198:201], v[44:47]
	v_mfma_f32_16x16x32_bf16 v[40:43], v[164:167], v[198:201], v[40:43]
	v_mfma_f32_16x16x32_bf16 v[28:31], v[156:159], v[212:215], v[28:31]
	v_mfma_f32_16x16x32_bf16 v[24:27], v[164:167], v[212:215], v[24:27]
	v_mfma_f32_16x16x32_bf16 v[12:15], v[156:159], v[220:223], v[12:15]
	v_mfma_f32_16x16x32_bf16 v[8:11], v[164:167], v[220:223], v[8:11]
	s_setprio 0
	s_setprio 1
	v_mfma_f32_16x16x32_bf16 v[52:55], v[168:171], v[186:189], v[52:55]
	v_mfma_f32_16x16x32_bf16 v[48:51], v[176:179], v[186:189], v[48:51]
	s_mov_b32 m0, s15
	s_nop 0
	global_load_lds_dwordx4 v[228:229], off
	v_mfma_f32_16x16x32_bf16 v[36:39], v[168:171], v[194:197], v[36:39]
	v_mfma_f32_16x16x32_bf16 v[32:35], v[176:179], v[194:197], v[32:35]
	v_mfma_f32_16x16x32_bf16 v[20:23], v[168:171], v[208:211], v[20:23]
	v_mfma_f32_16x16x32_bf16 v[16:19], v[176:179], v[208:211], v[16:19]
	v_mfma_f32_16x16x32_bf16 v[4:7], v[168:171], v[216:219], v[4:7]
	v_mfma_f32_16x16x32_bf16 v[0:3], v[176:179], v[216:219], v[0:3]
	v_mfma_f32_16x16x32_bf16 v[52:55], v[172:175], v[190:193], v[52:55]
	v_mfma_f32_16x16x32_bf16 v[48:51], v[182:185], v[190:193], v[48:51]
	v_mfma_f32_16x16x32_bf16 v[36:39], v[172:175], v[198:201], v[36:39]
	v_mfma_f32_16x16x32_bf16 v[32:35], v[182:185], v[198:201], v[32:35]
	v_mfma_f32_16x16x32_bf16 v[20:23], v[172:175], v[212:215], v[20:23]
	v_mfma_f32_16x16x32_bf16 v[16:19], v[182:185], v[212:215], v[16:19]
	v_mfma_f32_16x16x32_bf16 v[4:7], v[172:175], v[220:223], v[4:7]
	v_mfma_f32_16x16x32_bf16 v[0:3], v[182:185], v[220:223], v[0:3]
	s_setprio 0
	s_barrier
; #define PG8_STAGE(bufoff, gbase, voff) do { _Pragma("unroll") for (int _i = 0; _i < 2; ++_i) \
;         __builtin_amdgcn_global_load_lds((const unsigned*)((const char*)(gbase) + (voff)[_i]), (PG8_LAS unsigned*)(lds + (bufoff) + ldsw + _i * 8192), 16, 0, 0); } while (0)
; #define PG8_LDA(dst, b, h) do { _Pragma("unroll") for (int m = 0; m < 4; ++m) _Pragma("unroll") for (int k = 0; k < 2; ++k) dst[m][k] = *(const PG8_LAS bf16x8*)(lds + PG8_SA(b, h) + aoff + m * 2048 + k * 1024); } while (0)
; #define PG8_LDB(dst, b, h) do { _Pragma("unroll") for (int n = 0; n < 2; ++n) _Pragma("unroll") for (int k = 0; k < 2; ++k) dst[n][k] = *(const PG8_LAS bf16x8*)(lds + PG8_SB(b, h) + boff + n * 2048 + k * 1024); } while (0)
; #define PG8_MMA(ai, bj, At, Bt) do { __builtin_amdgcn_s_setprio(1); _Pragma("unroll") for (int m = 0; m < 4; ++m) _Pragma("unroll") for (int n = 0; n < 2; ++n) _Pragma("unroll") for (int k = 0; k < 2; ++k) \
;         acc[ai][bj][m][n] = __builtin_amdgcn_mfma_f32_16x16x32_bf16(Bt[n][k], At[m][k], acc[ai][bj][m][n], 0, 0, 0); __builtin_amdgcn_s_setprio(0); } while (0)
; #define PG8_WAIT_V(n) asm volatile("s_waitcnt vmcnt(" #n ")" ::: "memory")
; #define PG8_WAIT_L(n) asm volatile("s_waitcnt lgkmcnt(" #n ")" ::: "memory")
; #define PG8_BAR __builtin_amdgcn_s_barrier()
; #define PG8_SCHED __builtin_amdgcn_sched_barrier(0)
; template <class Epi, class Sched, bool ALIGN_EPI = false, bool SP2 = false>
; __device__ __forceinline__ void gemm_phase(PG8_LAS unsigned char* lds, const Gemm g, const Sched& S, const Epi& E) {
;     ...
;             PG8_LDB(B0, 1, 0); PG8_LDB(B1, 1, 1); PG8_SCHED; PG8_LDA(At, 1, 0); PG8_STAGE(PG8_SA(0, 1), a2 + hstep, voffA);
;             PG8_WAIT_V(8); PG8_WAIT_L(0); PG8_BAR; PG8_MMA(0, 0, At, B0); PG8_MMA(0, 1, At, B1); PG8_BAR; PG8_SCHED;
	s_add_i32 s78, 0, 0x18000
	v_add_u32_e32 v155, s78, v149
	s_add_i32 s79, 0, 0x1c000
	ds_read_b128 v[144:147], v155
	ds_read_b128 v[156:159], v155 offset:1024
	ds_read_b128 v[160:163], v155 offset:2048
	ds_read_b128 v[164:167], v155 offset:3072
	v_add_u32_e32 v155, s79, v149
	ds_read_b128 v[168:171], v155
	ds_read_b128 v[172:175], v155 offset:1024
	ds_read_b128 v[176:179], v155 offset:2048
	ds_read_b128 v[182:185], v155 offset:3072
	s_add_u32 s50, s56, 0xb0000
	s_addc_u32 s51, s57, 0
	s_mov_b32 m0, s33
	v_lshl_add_u64 v[230:231], s[50:51], 0, v[128:129]
	ds_read_b128 v[186:189], v153 offset:32768
	ds_read_b128 v[190:193], v153 offset:33792
	ds_read_b128 v[194:197], v153 offset:34816
	ds_read_b128 v[198:201], v153 offset:35840
	ds_read_b128 v[208:211], v153 offset:36864
	ds_read_b128 v[212:215], v153 offset:37888
	ds_read_b128 v[216:219], v153 offset:38912
	ds_read_b128 v[220:223], v153 offset:39936
	global_load_lds_dwordx4 v[230:231], off
	v_lshl_add_u64 v[230:231], s[50:51], 0, v[132:133]
	s_mov_b32 m0, s34
	s_nop 0
	global_load_lds_dwordx4 v[230:231], off
	s_waitcnt vmcnt(8)
	s_waitcnt lgkmcnt(0)
	s_barrier
	s_setprio 1
	s_waitcnt lgkmcnt(0)
	v_mfma_f32_16x16x32_bf16 v[124:127], v[144:147], v[186:189], v[124:127]
	v_mfma_f32_16x16x32_bf16 v[120:123], v[160:163], v[186:189], v[120:123]
	v_mfma_f32_16x16x32_bf16 v[108:111], v[144:147], v[194:197], v[108:111]
	v_mfma_f32_16x16x32_bf16 v[104:107], v[160:163], v[194:197], v[104:107]
	v_mfma_f32_16x16x32_bf16 v[92:95], v[144:147], v[208:211], v[92:95]
	v_mfma_f32_16x16x32_bf16 v[88:91], v[160:163], v[208:211], v[88:91]
	v_mfma_f32_16x16x32_bf16 v[76:79], v[144:147], v[216:219], v[76:79]
	v_mfma_f32_16x16x32_bf16 v[72:75], v[160:163], v[216:219], v[72:75]
	v_mfma_f32_16x16x32_bf16 v[124:127], v[156:159], v[190:193], v[124:127]
	v_mfma_f32_16x16x32_bf16 v[120:123], v[164:167], v[190:193], v[120:123]
	v_mfma_f32_16x16x32_bf16 v[108:111], v[156:159], v[198:201], v[108:111]
	v_mfma_f32_16x16x32_bf16 v[104:107], v[164:167], v[198:201], v[104:107]
	v_mfma_f32_16x16x32_bf16 v[92:95], v[156:159], v[212:215], v[92:95]
	v_mfma_f32_16x16x32_bf16 v[88:91], v[164:167], v[212:215], v[88:91]
	v_mfma_f32_16x16x32_bf16 v[76:79], v[156:159], v[220:223], v[76:79]
	v_mfma_f32_16x16x32_bf16 v[72:75], v[164:167], v[220:223], v[72:75]
	s_setprio 0
	s_setprio 1
	v_mfma_f32_16x16x32_bf16 v[116:119], v[168:171], v[186:189], v[116:119]
	v_mfma_f32_16x16x32_bf16 v[112:115], v[176:179], v[186:189], v[112:115]
	v_mfma_f32_16x16x32_bf16 v[100:103], v[168:171], v[194:197], v[100:103]
	v_mfma_f32_16x16x32_bf16 v[96:99], v[176:179], v[194:197], v[96:99]
	v_mfma_f32_16x16x32_bf16 v[84:87], v[168:171], v[208:211], v[84:87]
	v_mfma_f32_16x16x32_bf16 v[80:83], v[176:179], v[208:211], v[80:83]
	v_mfma_f32_16x16x32_bf16 v[68:71], v[168:171], v[216:219], v[68:71]
	v_mfma_f32_16x16x32_bf16 v[64:67], v[176:179], v[216:219], v[64:67]
	v_mfma_f32_16x16x32_bf16 v[116:119], v[172:175], v[190:193], v[116:119]
	v_mfma_f32_16x16x32_bf16 v[112:115], v[182:185], v[190:193], v[112:115]
	v_mfma_f32_16x16x32_bf16 v[100:103], v[172:175], v[198:201], v[100:103]
	v_mfma_f32_16x16x32_bf16 v[96:99], v[182:185], v[198:201], v[96:99]
	v_mfma_f32_16x16x32_bf16 v[84:87], v[172:175], v[212:215], v[84:87]
	v_mfma_f32_16x16x32_bf16 v[80:83], v[182:185], v[212:215], v[80:83]
	v_mfma_f32_16x16x32_bf16 v[68:71], v[172:175], v[220:223], v[68:71]
	v_mfma_f32_16x16x32_bf16 v[64:67], v[182:185], v[220:223], v[64:67]
	s_setprio 0
	s_barrier
; #define PG8_STAGE(bufoff, gbase, voff) do { _Pragma("unroll") for (int _i = 0; _i < 2; ++_i) \
;         __builtin_amdgcn_global_load_lds((const unsigned*)((const char*)(gbase) + (voff)[_i]), (PG8_LAS unsigned*)(lds + (bufoff) + ldsw + _i * 8192), 16, 0, 0); } while (0)
; #define PG8_LDA(dst, b, h) do { _Pragma("unroll") for (int m = 0; m < 4; ++m) _Pragma("unroll") for (int k = 0; k < 2; ++k) dst[m][k] = *(const PG8_LAS bf16x8*)(lds + PG8_SA(b, h) + aoff + m * 2048 + k * 1024); } while (0)
; #define PG8_MMA(ai, bj, At, Bt) do { __builtin_amdgcn_s_setprio(1); _Pragma("unroll") for (int m = 0; m < 4; ++m) _Pragma("unroll") for (int n = 0; n < 2; ++n) _Pragma("unroll") for (int k = 0; k < 2; ++k) \
;         acc[ai][bj][m][n] = __builtin_amdgcn_mfma_f32_16x16x32_bf16(Bt[n][k], At[m][k], acc[ai][bj][m][n], 0, 0, 0); __builtin_amdgcn_s_setprio(0); } while (0)
; #define PG8_WAIT_V(n) asm volatile("s_waitcnt vmcnt(" #n ")" ::: "memory")
; #define PG8_WAIT_L(n) asm volatile("s_waitcnt lgkmcnt(" #n ")" ::: "memory")
; #define PG8_BAR __builtin_amdgcn_s_barrier()
; #define PG8_SCHED __builtin_amdgcn_sched_barrier(0)
; template <class Epi, class Sched, bool ALIGN_EPI = false, bool SP2 = false>
; __device__ __forceinline__ void gemm_phase(PG8_LAS unsigned char* lds, const Gemm g, const Sched& S, const Epi& E) {
;     ...
;             PG8_LDA(At, 1, 1); PG8_STAGE(PG8_SB(1, 0), b3, voffB); PG8_STAGE(PG8_SB(1, 1), b3 + hstep, voffB); PG8_STAGE(PG8_SA(1, 0), a3, voffA);
;             PG8_WAIT_V(8); PG8_WAIT_L(0); PG8_BAR; PG8_MMA(1, 0, At, B0); PG8_MMA(1, 1, At, B1); PG8_BAR; PG8_SCHED;
;     ...
;         if constexpr (ALIGN_EPI) { if (wr == 0) PG8_BAR; }
	s_add_i32 s50, s78, s3
	v_lshl_add_u64 v[202:203], v[202:203], 0, s[42:43]
	s_mov_b32 m0, s50
	ds_read_b128 v[186:189], v153 offset:49152
	ds_read_b128 v[190:193], v153 offset:50176
	ds_read_b128 v[194:197], v153 offset:51200
	ds_read_b128 v[198:201], v153 offset:52224
	ds_read_b128 v[208:211], v153 offset:53248
	ds_read_b128 v[212:215], v153 offset:54272
	ds_read_b128 v[216:219], v153 offset:55296
	ds_read_b128 v[220:223], v153 offset:56320
	global_load_lds_dwordx4 v[202:203], off
	s_add_i32 m0, s50, 0x2000
	s_add_u32 s50, s54, 0xb0080
	v_lshl_add_u64 v[202:203], v[224:225], 0, s[42:43]
	s_addc_u32 s51, s55, 0
	s_add_i32 s54, s79, s3
	global_load_lds_dwordx4 v[202:203], off
	v_lshl_add_u64 v[202:203], s[50:51], 0, v[130:131]
	s_mov_b32 m0, s54
	s_nop 0
	global_load_lds_dwordx4 v[202:203], off
	v_lshl_add_u64 v[202:203], s[50:51], 0, v[134:135]
	s_add_i32 m0, s54, 0x2000
	s_nop 0
	global_load_lds_dwordx4 v[202:203], off
	s_waitcnt vmcnt(6)
	s_waitcnt lgkmcnt(0)
	s_barrier
	s_setprio 1
	s_waitcnt lgkmcnt(0)
	v_mfma_f32_16x16x32_bf16 v[60:63], v[144:147], v[186:189], v[60:63]
	v_mfma_f32_16x16x32_bf16 v[56:59], v[160:163], v[186:189], v[56:59]
	v_mfma_f32_16x16x32_bf16 v[44:47], v[144:147], v[194:197], v[44:47]
	v_mfma_f32_16x16x32_bf16 v[40:43], v[160:163], v[194:197], v[40:43]
	v_mfma_f32_16x16x32_bf16 v[28:31], v[144:147], v[208:211], v[28:31]
	v_mfma_f32_16x16x32_bf16 v[24:27], v[160:163], v[208:211], v[24:27]
	v_lshl_add_u64 v[202:203], v[226:227], 0, s[42:43]
	s_mov_b32 m0, s59
	s_nop 0
	global_load_lds_dwordx4 v[202:203], off
	v_mfma_f32_16x16x32_bf16 v[12:15], v[144:147], v[216:219], v[12:15]
	v_mfma_f32_16x16x32_bf16 v[8:11], v[160:163], v[216:219], v[8:11]
	v_mfma_f32_16x16x32_bf16 v[60:63], v[156:159], v[190:193], v[60:63]
	v_mfma_f32_16x16x32_bf16 v[56:59], v[164:167], v[190:193], v[56:59]
	v_mfma_f32_16x16x32_bf16 v[44:47], v[156:159], v[198:201], v[44:47]
	v_mfma_f32_16x16x32_bf16 v[40:43], v[164:167], v[198:201], v[40:43]
	v_mfma_f32_16x16x32_bf16 v[28:31], v[156:159], v[212:215], v[28:31]
	v_mfma_f32_16x16x32_bf16 v[24:27], v[164:167], v[212:215], v[24:27]
	v_mfma_f32_16x16x32_bf16 v[12:15], v[156:159], v[220:223], v[12:15]
	v_mfma_f32_16x16x32_bf16 v[8:11], v[164:167], v[220:223], v[8:11]
	s_setprio 0
	s_setprio 1
	v_mfma_f32_16x16x32_bf16 v[52:55], v[168:171], v[186:189], v[52:55]
	v_mfma_f32_16x16x32_bf16 v[48:51], v[176:179], v[186:189], v[48:51]
	v_lshl_add_u64 v[202:203], v[228:229], 0, s[42:43]
	s_mov_b32 m0, s60
	s_nop 0
	global_load_lds_dwordx4 v[202:203], off
	v_mfma_f32_16x16x32_bf16 v[36:39], v[168:171], v[194:197], v[36:39]
	v_mfma_f32_16x16x32_bf16 v[32:35], v[176:179], v[194:197], v[32:35]
	v_mfma_f32_16x16x32_bf16 v[20:23], v[168:171], v[208:211], v[20:23]
	v_mfma_f32_16x16x32_bf16 v[16:19], v[176:179], v[208:211], v[16:19]
	v_mfma_f32_16x16x32_bf16 v[4:7], v[168:171], v[216:219], v[4:7]
	v_mfma_f32_16x16x32_bf16 v[0:3], v[176:179], v[216:219], v[0:3]
	v_mfma_f32_16x16x32_bf16 v[52:55], v[172:175], v[190:193], v[52:55]
	v_mfma_f32_16x16x32_bf16 v[48:51], v[182:185], v[190:193], v[48:51]
	v_mfma_f32_16x16x32_bf16 v[36:39], v[172:175], v[198:201], v[36:39]
	v_mfma_f32_16x16x32_bf16 v[32:35], v[182:185], v[198:201], v[32:35]
	v_mfma_f32_16x16x32_bf16 v[20:23], v[172:175], v[212:215], v[20:23]
	v_mfma_f32_16x16x32_bf16 v[16:19], v[182:185], v[212:215], v[16:19]
	v_mfma_f32_16x16x32_bf16 v[4:7], v[172:175], v[220:223], v[4:7]
	v_mfma_f32_16x16x32_bf16 v[0:3], v[182:185], v[220:223], v[0:3]
	s_setprio 0
	s_barrier
	s_add_i32 s77, s77, 2
	s_add_u32 s75, s75, 0x100
	s_addc_u32 s76, s76, 0
	s_cmp_gt_u32 s77, 41
	s_mov_b64 s[50:51], s[52:53]
	s_cbranch_scc0 .LBB0_1035
	s_and_b64 vcc, exec, s[44:45]
	s_cbranch_vccz .LBB0_1038
	s_barrier

; #define PG8_STAGE(bufoff, gbase, voff) do { _Pragma("unroll") for (int _i = 0; _i < 2; ++_i) \
;         __builtin_amdgcn_global_load_lds((const unsigned*)((const char*)(gbase) + (voff)[_i]), (PG8_LAS unsigned*)(lds + (bufoff) + ldsw + _i * 8192), 16, 0, 0); } while (0)
; #define PG8_LDA(dst, b, h) do { _Pragma("unroll") for (int m = 0; m < 4; ++m) _Pragma("unroll") for (int k = 0; k < 2; ++k) dst[m][k] = *(const PG8_LAS bf16x8*)(lds + PG8_SA(b, h) + aoff + m * 2048 + k * 1024); } while (0)
; #define PG8_LDB(dst, b, h) do { _Pragma("unroll") for (int n = 0; n < 2; ++n) _Pragma("unroll") for (int k = 0; k < 2; ++k) dst[n][k] = *(const PG8_LAS bf16x8*)(lds + PG8_SB(b, h) + boff + n * 2048 + k * 1024); } while (0)
; #define PG8_WAIT_V(n) asm volatile("s_waitcnt vmcnt(" #n ")" ::: "memory")
; #define PG8_WAIT_L(n) asm volatile("s_waitcnt lgkmcnt(" #n ")" ::: "memory")
; #define PG8_BAR __builtin_amdgcn_s_barrier()
; #define PG8_SCHED __builtin_amdgcn_sched_barrier(0)
; template <class Epi, class Sched, bool ALIGN_EPI = false, bool SP2 = false>
; __device__ __forceinline__ void gemm_phase(PG8_LAS unsigned char* lds, const Gemm g, const Sched& S, const Epi& E) {
;     ...
;         const bool has_next = S.next(ui + 1, nxt);
;         const char* nA = has_next ? (const char*)g.A + (size_t)nxt.pm * tstep : cA; const char* nB = has_next ? (const char*)g.Bt + (size_t)nxt.pn * tstep : cB;
;         for (int t = 0; t < nt; t += 2) {
;             const bool last = (t == nt - 2);
;             const char* a1 = cA + (size_t)(t + 1) * kstep;
;             const char* a2 = last ? nA : cA + (size_t)(t + 2) * kstep; const char* b2 = last ? nB : cB + (size_t)(t + 2) * kstep;
;             const char* a3 = a2 + kstep; const char* b3 = b2 + kstep;
;             if (last && has_next) S.a_ready(nxt);
;             if constexpr (SP2) {
;             PG8_LDB(B0, 0, 0); PG8_LDB(B1, 0, 1); PG8_SCHED; PG8_LDA(At, 0, 0); PG8_STAGE(PG8_SA(1, 1), a1 + hstep, voffA);
;             PG8_WAIT_V(8); PG8_WAIT_L(0); PG8_BAR; PG8_MMA(0, 0, At, B0); PG8_MMA(0, 1, At, B1); PG8_BAR; PG8_SCHED;
;             PG8_LDA(At, 0, 1); PG8_STAGE(PG8_SB(0, 0), b2, voffB); PG8_STAGE(PG8_SB(0, 1), b2 + hstep, voffB); PG8_STAGE(PG8_SA(0, 0), a2, voffA);
;             PG8_WAIT_V(8); PG8_WAIT_L(0); PG8_BAR; PG8_MMA(1, 0, At, B0); PG8_MMA(1, 1, At, B1); PG8_BAR; PG8_SCHED;
.LBB0_1118:
	s_ashr_i32 s45, s44, 31
	s_lshl_b64 s[48:49], s[44:45], 19
	s_add_u32 s48, s22, s48
	s_addc_u32 s49, s23, s49
	s_and_b64 s[50:51], s[10:11], exec
	s_cselect_b32 s45, s49, s55
	s_cselect_b32 s76, s48, s54
	s_ashr_i32 s43, s42, 31
	s_lshl_b64 s[50:51], s[42:43], 19
	s_add_u32 s50, s14, s50
	s_addc_u32 s51, s15, s51
	s_and_b64 s[58:59], s[10:11], exec
	s_cselect_b32 s43, s51, s57
	s_cselect_b32 s77, s50, s56
	s_add_u32 s54, s54, 0x40080
	s_addc_u32 s55, s55, 0
	s_add_u32 s82, s56, 0x100
	s_addc_u32 s83, s57, 0
	s_mov_b32 s84, -2
	ds_read_b128 v[144:147], v155
	ds_read_b128 v[148:151], v155 offset:1024
	ds_read_b128 v[160:163], v155 offset:2048
	ds_read_b128 v[164:167], v155 offset:3072
	ds_read_b128 v[168:171], v156
	ds_read_b128 v[172:175], v156 offset:1024
	ds_read_b128 v[176:179], v156 offset:2048
	ds_read_b128 v[182:185], v156 offset:3072
	s_add_u32 s56, s54, 0xfffc0080
	s_addc_u32 s57, s55, -1
	s_cmp_eq_u32 s84, 12
	s_cselect_b32 s59, s45, s57
	s_cselect_b32 s58, s76, s56
	s_cselect_b32 s57, s43, s83
	s_cselect_b32 s56, s77, s82
	v_lshl_add_u64 v[224:225], s[54:55], 0, v[136:137]
	s_add_i32 m0, s53, 0xc000
	ds_read_b128 v[186:189], v157
	ds_read_b128 v[190:193], v157 offset:1024
	ds_read_b128 v[194:197], v157 offset:2048
	ds_read_b128 v[198:201], v157 offset:3072
	ds_read_b128 v[208:211], v157 offset:4096
	ds_read_b128 v[212:215], v157 offset:5120
	ds_read_b128 v[216:219], v157 offset:6144
	ds_read_b128 v[220:223], v157 offset:7168
	global_load_lds_dwordx4 v[224:225], off
	v_lshl_add_u64 v[224:225], s[54:55], 0, v[138:139]
	s_add_i32 m0, s53, 0xe000
	s_nop 0
	global_load_lds_dwordx4 v[224:225], off
	s_waitcnt vmcnt(8)
	s_waitcnt lgkmcnt(0)
	s_barrier
	s_setprio 1
	s_waitcnt lgkmcnt(0)
	v_mfma_f32_16x16x32_bf16 v[124:127], v[144:147], v[186:189], 0
	v_mfma_f32_16x16x32_bf16 v[120:123], v[160:163], v[186:189], 0
	v_mfma_f32_16x16x32_bf16 v[108:111], v[144:147], v[194:197], 0
	v_mfma_f32_16x16x32_bf16 v[104:107], v[160:163], v[194:197], 0
	v_mfma_f32_16x16x32_bf16 v[92:95], v[144:147], v[208:211], 0
	v_mfma_f32_16x16x32_bf16 v[88:91], v[160:163], v[208:211], 0
	v_mfma_f32_16x16x32_bf16 v[76:79], v[144:147], v[216:219], 0
	v_mfma_f32_16x16x32_bf16 v[72:75], v[160:163], v[216:219], 0
	v_mfma_f32_16x16x32_bf16 v[124:127], v[148:151], v[190:193], v[124:127]
	v_mfma_f32_16x16x32_bf16 v[120:123], v[164:167], v[190:193], v[120:123]
	v_mfma_f32_16x16x32_bf16 v[108:111], v[148:151], v[198:201], v[108:111]
	v_mfma_f32_16x16x32_bf16 v[104:107], v[164:167], v[198:201], v[104:107]
	v_mfma_f32_16x16x32_bf16 v[92:95], v[148:151], v[212:215], v[92:95]
	v_mfma_f32_16x16x32_bf16 v[88:91], v[164:167], v[212:215], v[88:91]
	v_mfma_f32_16x16x32_bf16 v[76:79], v[148:151], v[220:223], v[76:79]
	v_mfma_f32_16x16x32_bf16 v[72:75], v[164:167], v[220:223], v[72:75]
	s_setprio 0
	s_setprio 1
	v_mfma_f32_16x16x32_bf16 v[116:119], v[168:171], v[186:189], 0
	v_mfma_f32_16x16x32_bf16 v[112:115], v[176:179], v[186:189], 0
	v_mfma_f32_16x16x32_bf16 v[100:103], v[168:171], v[194:197], 0
	v_mfma_f32_16x16x32_bf16 v[96:99], v[176:179], v[194:197], 0
	v_mfma_f32_16x16x32_bf16 v[84:87], v[168:171], v[208:211], 0
	v_mfma_f32_16x16x32_bf16 v[80:83], v[176:179], v[208:211], 0
	v_mfma_f32_16x16x32_bf16 v[68:71], v[168:171], v[216:219], 0
	v_mfma_f32_16x16x32_bf16 v[64:67], v[176:179], v[216:219], 0
	v_mfma_f32_16x16x32_bf16 v[116:119], v[172:175], v[190:193], v[116:119]
	v_mfma_f32_16x16x32_bf16 v[112:115], v[182:185], v[190:193], v[112:115]
	v_mfma_f32_16x16x32_bf16 v[100:103], v[172:175], v[198:201], v[100:103]
	v_mfma_f32_16x16x32_bf16 v[96:99], v[182:185], v[198:201], v[96:99]
	v_mfma_f32_16x16x32_bf16 v[84:87], v[172:175], v[212:215], v[84:87]
	v_mfma_f32_16x16x32_bf16 v[80:83], v[182:185], v[212:215], v[80:83]
	v_mfma_f32_16x16x32_bf16 v[68:71], v[172:175], v[220:223], v[68:71]
	v_mfma_f32_16x16x32_bf16 v[64:67], v[182:185], v[220:223], v[64:67]
	s_setprio 0
	s_barrier
	s_add_i32 s78, s66, s33
	v_lshl_add_u64 v[224:225], s[56:57], 0, v[132:133]
	s_mov_b32 m0, s78
	ds_read_b128 v[186:189], v157 offset:16384
	ds_read_b128 v[190:193], v157 offset:17408
	ds_read_b128 v[194:197], v157 offset:18432
	ds_read_b128 v[198:201], v157 offset:19456
	ds_read_b128 v[208:211], v157 offset:20480
	ds_read_b128 v[212:215], v157 offset:21504
	ds_read_b128 v[216:219], v157 offset:22528
	ds_read_b128 v[220:223], v157 offset:23552
	global_load_lds_dwordx4 v[224:225], off
	s_add_i32 m0, s78, 0x2000
	s_add_u32 s78, s56, 0x40000
	v_lshl_add_u64 v[226:227], s[56:57], 0, v[128:129]
	s_addc_u32 s79, s57, 0
	s_add_i32 s85, s67, s33
	global_load_lds_dwordx4 v[226:227], off
	v_lshl_add_u64 v[228:229], s[78:79], 0, v[132:133]
	s_mov_b32 m0, s85
	v_lshl_add_u64 v[230:231], s[58:59], 0, v[130:131]
	global_load_lds_dwordx4 v[228:229], off
	v_lshl_add_u64 v[228:229], s[78:79], 0, v[128:129]
	s_add_i32 m0, s85, 0x2000
	s_nop 0
	global_load_lds_dwordx4 v[228:229], off
	s_waitcnt vmcnt(6)
	s_waitcnt lgkmcnt(0)
	s_barrier
; #define PG8_STAGE(bufoff, gbase, voff) do { _Pragma("unroll") for (int _i = 0; _i < 2; ++_i) \
;         __builtin_amdgcn_global_load_lds((const unsigned*)((const char*)(gbase) + (voff)[_i]), (PG8_LAS unsigned*)(lds + (bufoff) + ldsw + _i * 8192), 16, 0, 0); } while (0)
; #define PG8_LDA(dst, b, h) do { _Pragma("unroll") for (int m = 0; m < 4; ++m) _Pragma("unroll") for (int k = 0; k < 2; ++k) dst[m][k] = *(const PG8_LAS bf16x8*)(lds + PG8_SA(b, h) + aoff + m * 2048 + k * 1024); } while (0)
; #define PG8_LDB(dst, b, h) do { _Pragma("unroll") for (int n = 0; n < 2; ++n) _Pragma("unroll") for (int k = 0; k < 2; ++k) dst[n][k] = *(const PG8_LAS bf16x8*)(lds + PG8_SB(b, h) + boff + n * 2048 + k * 1024); } while (0)
; #define PG8_MMA(ai, bj, At, Bt) do { __builtin_amdgcn_s_setprio(1); _Pragma("unroll") for (int m = 0; m < 4; ++m) _Pragma("unroll") for (int n = 0; n < 2; ++n) _Pragma("unroll") for (int k = 0; k < 2; ++k) \
;         acc[ai][bj][m][n] = __builtin_amdgcn_mfma_f32_16x16x32_bf16(Bt[n][k], At[m][k], acc[ai][bj][m][n], 0, 0, 0); __builtin_amdgcn_s_setprio(0); } while (0)
; #define PG8_WAIT_V(n) asm volatile("s_waitcnt vmcnt(" #n ")" ::: "memory")
; #define PG8_WAIT_L(n) asm volatile("s_waitcnt lgkmcnt(" #n ")" ::: "memory")
; #define PG8_BAR __builtin_amdgcn_s_barrier()
; #define PG8_SCHED __builtin_amdgcn_sched_barrier(0)
; template <class Epi, class Sched, bool ALIGN_EPI = false, bool SP2 = false>
; __device__ __forceinline__ void gemm_phase(PG8_LAS unsigned char* lds, const Gemm g, const Sched& S, const Epi& E) {
;     ...
;             PG8_WAIT_V(8); PG8_WAIT_L(0); PG8_BAR; PG8_MMA(1, 0, At, B0); PG8_MMA(1, 1, At, B1); PG8_BAR; PG8_SCHED;
;             PG8_LDB(B0, 1, 0); PG8_LDB(B1, 1, 1); PG8_SCHED; PG8_LDA(At, 1, 0); PG8_STAGE(PG8_SA(0, 1), a2 + hstep, voffA);
;             PG8_WAIT_V(8); PG8_WAIT_L(0); PG8_BAR; PG8_MMA(0, 0, At, B0); PG8_MMA(0, 1, At, B1); PG8_BAR; PG8_SCHED;
	s_setprio 1
	s_waitcnt lgkmcnt(0)
	v_mfma_f32_16x16x32_bf16 v[60:63], v[144:147], v[186:189], 0
	v_mfma_f32_16x16x32_bf16 v[56:59], v[160:163], v[186:189], 0
	v_mfma_f32_16x16x32_bf16 v[44:47], v[144:147], v[194:197], 0
	v_mfma_f32_16x16x32_bf16 v[40:43], v[160:163], v[194:197], 0
	v_mfma_f32_16x16x32_bf16 v[28:31], v[144:147], v[208:211], 0
	v_mfma_f32_16x16x32_bf16 v[24:27], v[160:163], v[208:211], 0
	v_lshl_add_u64 v[228:229], s[58:59], 0, v[134:135]
	s_mov_b32 m0, s53
	s_nop 0
	global_load_lds_dwordx4 v[228:229], off
	v_mfma_f32_16x16x32_bf16 v[12:15], v[144:147], v[216:219], 0
	v_mfma_f32_16x16x32_bf16 v[8:11], v[160:163], v[216:219], 0
	v_mfma_f32_16x16x32_bf16 v[60:63], v[148:151], v[190:193], v[60:63]
	v_mfma_f32_16x16x32_bf16 v[56:59], v[164:167], v[190:193], v[56:59]
	v_mfma_f32_16x16x32_bf16 v[44:47], v[148:151], v[198:201], v[44:47]
	v_mfma_f32_16x16x32_bf16 v[40:43], v[164:167], v[198:201], v[40:43]
	v_mfma_f32_16x16x32_bf16 v[28:31], v[148:151], v[212:215], v[28:31]
	v_mfma_f32_16x16x32_bf16 v[24:27], v[164:167], v[212:215], v[24:27]
	v_mfma_f32_16x16x32_bf16 v[12:15], v[148:151], v[220:223], v[12:15]
	v_mfma_f32_16x16x32_bf16 v[8:11], v[164:167], v[220:223], v[8:11]
	s_setprio 0
	s_setprio 1
	v_mfma_f32_16x16x32_bf16 v[52:55], v[168:171], v[186:189], 0
	v_mfma_f32_16x16x32_bf16 v[48:51], v[176:179], v[186:189], 0
	s_mov_b32 m0, s60
	s_nop 0
	global_load_lds_dwordx4 v[230:231], off
	v_mfma_f32_16x16x32_bf16 v[36:39], v[168:171], v[194:197], 0
	v_mfma_f32_16x16x32_bf16 v[32:35], v[176:179], v[194:197], 0
	v_mfma_f32_16x16x32_bf16 v[20:23], v[168:171], v[208:211], 0
	v_mfma_f32_16x16x32_bf16 v[16:19], v[176:179], v[208:211], 0
	v_mfma_f32_16x16x32_bf16 v[4:7], v[168:171], v[216:219], 0
	v_mfma_f32_16x16x32_bf16 v[0:3], v[176:179], v[216:219], 0
	v_mfma_f32_16x16x32_bf16 v[52:55], v[172:175], v[190:193], v[52:55]
	v_mfma_f32_16x16x32_bf16 v[48:51], v[182:185], v[190:193], v[48:51]
	v_mfma_f32_16x16x32_bf16 v[36:39], v[172:175], v[198:201], v[36:39]
	v_mfma_f32_16x16x32_bf16 v[32:35], v[182:185], v[198:201], v[32:35]
	v_mfma_f32_16x16x32_bf16 v[20:23], v[172:175], v[212:215], v[20:23]
	v_mfma_f32_16x16x32_bf16 v[16:19], v[182:185], v[212:215], v[16:19]
	v_mfma_f32_16x16x32_bf16 v[4:7], v[172:175], v[220:223], v[4:7]
	v_mfma_f32_16x16x32_bf16 v[0:3], v[182:185], v[220:223], v[0:3]
	s_setprio 0
	s_barrier
	s_add_i32 s78, 0, 0x18000
	v_add_u32_e32 v159, s78, v153
	s_add_i32 s79, 0, 0x1c000
	ds_read_b128 v[144:147], v159
	ds_read_b128 v[148:151], v159 offset:1024
	ds_read_b128 v[160:163], v159 offset:2048
	ds_read_b128 v[164:167], v159 offset:3072
	v_add_u32_e32 v159, s79, v153
	ds_read_b128 v[168:171], v159
	ds_read_b128 v[172:175], v159 offset:1024
	ds_read_b128 v[176:179], v159 offset:2048
	ds_read_b128 v[182:185], v159 offset:3072
	s_add_u32 s58, s58, 0x40000
	s_addc_u32 s59, s59, 0
	s_mov_b32 m0, s61
	v_lshl_add_u64 v[232:233], s[58:59], 0, v[134:135]
	ds_read_b128 v[186:189], v157 offset:32768
	ds_read_b128 v[190:193], v157 offset:33792
	ds_read_b128 v[194:197], v157 offset:34816
	ds_read_b128 v[198:201], v157 offset:35840
	ds_read_b128 v[208:211], v157 offset:36864
	ds_read_b128 v[212:215], v157 offset:37888
	ds_read_b128 v[216:219], v157 offset:38912
	ds_read_b128 v[220:223], v157 offset:39936
	global_load_lds_dwordx4 v[232:233], off
	v_lshl_add_u64 v[232:233], s[58:59], 0, v[130:131]
	s_mov_b32 m0, s62
	s_nop 0
	global_load_lds_dwordx4 v[232:233], off
	s_waitcnt vmcnt(8)
	s_waitcnt lgkmcnt(0)
	s_barrier
	s_setprio 1
	s_waitcnt lgkmcnt(0)
	v_mfma_f32_16x16x32_bf16 v[124:127], v[144:147], v[186:189], v[124:127]
	v_mfma_f32_16x16x32_bf16 v[120:123], v[160:163], v[186:189], v[120:123]
	v_mfma_f32_16x16x32_bf16 v[108:111], v[144:147], v[194:197], v[108:111]
	v_mfma_f32_16x16x32_bf16 v[104:107], v[160:163], v[194:197], v[104:107]
	v_mfma_f32_16x16x32_bf16 v[92:95], v[144:147], v[208:211], v[92:95]
	v_mfma_f32_16x16x32_bf16 v[88:91], v[160:163], v[208:211], v[88:91]
	v_mfma_f32_16x16x32_bf16 v[76:79], v[144:147], v[216:219], v[76:79]
	v_mfma_f32_16x16x32_bf16 v[72:75], v[160:163], v[216:219], v[72:75]
	v_mfma_f32_16x16x32_bf16 v[124:127], v[148:151], v[190:193], v[124:127]
	v_mfma_f32_16x16x32_bf16 v[120:123], v[164:167], v[190:193], v[120:123]
	v_mfma_f32_16x16x32_bf16 v[108:111], v[148:151], v[198:201], v[108:111]
	v_mfma_f32_16x16x32_bf16 v[104:107], v[164:167], v[198:201], v[104:107]
	v_mfma_f32_16x16x32_bf16 v[92:95], v[148:151], v[212:215], v[92:95]
	v_mfma_f32_16x16x32_bf16 v[88:91], v[164:167], v[212:215], v[88:91]
	v_mfma_f32_16x16x32_bf16 v[76:79], v[148:151], v[220:223], v[76:79]
	v_mfma_f32_16x16x32_bf16 v[72:75], v[164:167], v[220:223], v[72:75]
	s_setprio 0
	s_setprio 1
	v_mfma_f32_16x16x32_bf16 v[116:119], v[168:171], v[186:189], v[116:119]
	v_mfma_f32_16x16x32_bf16 v[112:115], v[176:179], v[186:189], v[112:115]
	v_mfma_f32_16x16x32_bf16 v[100:103], v[168:171], v[194:197], v[100:103]
	v_mfma_f32_16x16x32_bf16 v[96:99], v[176:179], v[194:197], v[96:99]
	v_mfma_f32_16x16x32_bf16 v[84:87], v[168:171], v[208:211], v[84:87]
	v_mfma_f32_16x16x32_bf16 v[80:83], v[176:179], v[208:211], v[80:83]
	v_mfma_f32_16x16x32_bf16 v[68:71], v[168:171], v[216:219], v[68:71]
	v_mfma_f32_16x16x32_bf16 v[64:67], v[176:179], v[216:219], v[64:67]
	v_mfma_f32_16x16x32_bf16 v[116:119], v[172:175], v[190:193], v[116:119]
	v_mfma_f32_16x16x32_bf16 v[112:115], v[182:185], v[190:193], v[112:115]
	v_mfma_f32_16x16x32_bf16 v[100:103], v[172:175], v[198:201], v[100:103]
	v_mfma_f32_16x16x32_bf16 v[96:99], v[182:185], v[198:201], v[96:99]
	v_mfma_f32_16x16x32_bf16 v[84:87], v[172:175], v[212:215], v[84:87]
	v_mfma_f32_16x16x32_bf16 v[80:83], v[182:185], v[212:215], v[80:83]
	v_mfma_f32_16x16x32_bf16 v[68:71], v[172:175], v[220:223], v[68:71]
	v_mfma_f32_16x16x32_bf16 v[64:67], v[182:185], v[220:223], v[64:67]
	s_setprio 0
	s_barrier
; #define PG8_STAGE(bufoff, gbase, voff) do { _Pragma("unroll") for (int _i = 0; _i < 2; ++_i) \
;         __builtin_amdgcn_global_load_lds((const unsigned*)((const char*)(gbase) + (voff)[_i]), (PG8_LAS unsigned*)(lds + (bufoff) + ldsw + _i * 8192), 16, 0, 0); } while (0)
; #define PG8_LDA(dst, b, h) do { _Pragma("unroll") for (int m = 0; m < 4; ++m) _Pragma("unroll") for (int k = 0; k < 2; ++k) dst[m][k] = *(const PG8_LAS bf16x8*)(lds + PG8_SA(b, h) + aoff + m * 2048 + k * 1024); } while (0)
; #define PG8_LDB(dst, b, h) do { _Pragma("unroll") for (int n = 0; n < 2; ++n) _Pragma("unroll") for (int k = 0; k < 2; ++k) dst[n][k] = *(const PG8_LAS bf16x8*)(lds + PG8_SB(b, h) + boff + n * 2048 + k * 1024); } while (0)
; #define PG8_MMA(ai, bj, At, Bt) do { __builtin_amdgcn_s_setprio(1); _Pragma("unroll") for (int m = 0; m < 4; ++m) _Pragma("unroll") for (int n = 0; n < 2; ++n) _Pragma("unroll") for (int k = 0; k < 2; ++k) \
;         acc[ai][bj][m][n] = __builtin_amdgcn_mfma_f32_16x16x32_bf16(Bt[n][k], At[m][k], acc[ai][bj][m][n], 0, 0, 0); __builtin_amdgcn_s_setprio(0); } while (0)
; #define PG8_WAIT_V(n) asm volatile("s_waitcnt vmcnt(" #n ")" ::: "memory")
; template <class Epi, class Sched, bool ALIGN_EPI = false, bool SP2 = false>
; __device__ __forceinline__ void gemm_phase(PG8_LAS unsigned char* lds, const Gemm g, const Sched& S, const Epi& E) {
;     ...
;             PG8_LDB(B0, 0, 0); PG8_LDB(B1, 0, 1); PG8_SCHED; PG8_LDA(At, 0, 0); PG8_STAGE(PG8_SA(1, 1), a1 + hstep, voffA);
;             PG8_WAIT_V(8); PG8_WAIT_L(0); PG8_BAR; PG8_MMA(0, 0, At, B0); PG8_MMA(0, 1, At, B1); PG8_BAR; PG8_SCHED;
;             PG8_LDA(At, 0, 1); PG8_STAGE(PG8_SB(0, 0), b2, voffB); PG8_STAGE(PG8_SB(0, 1), b2 + hstep, voffB); PG8_STAGE(PG8_SA(0, 0), a2, voffA);
;             PG8_WAIT_V(8); PG8_WAIT_L(0); PG8_BAR; PG8_MMA(1, 0, At, B0); PG8_MMA(1, 1, At, B1); PG8_BAR; PG8_SCHED;
;             PG8_LDB(B0, 1, 0); PG8_LDB(B1, 1, 1); PG8_SCHED; PG8_LDA(At, 1, 0); PG8_STAGE(PG8_SA(0, 1), a2 + hstep, voffA);
;             PG8_WAIT_V(8); PG8_WAIT_L(0); PG8_BAR; PG8_MMA(0, 0, At, B0); PG8_MMA(0, 1, At, B1); PG8_BAR; PG8_SCHED;
;             PG8_LDA(At, 1, 1); PG8_STAGE(PG8_SB(1, 0), b3, voffB); PG8_STAGE(PG8_SB(1, 1), b3 + hstep, voffB); PG8_STAGE(PG8_SA(1, 0), a3, voffA);
;             PG8_WAIT_V(8); PG8_WAIT_L(0); PG8_BAR; PG8_MMA(1, 0, At, B0); PG8_MMA(1, 1, At, B1); PG8_BAR; PG8_SCHED;
	s_add_i32 s58, s78, s33
	v_lshl_add_u64 v[224:225], v[224:225], 0, s[12:13]
	s_mov_b32 m0, s58
	ds_read_b128 v[186:189], v157 offset:49152
	ds_read_b128 v[190:193], v157 offset:50176
	ds_read_b128 v[194:197], v157 offset:51200
	ds_read_b128 v[198:201], v157 offset:52224
	ds_read_b128 v[208:211], v157 offset:53248
	ds_read_b128 v[212:215], v157 offset:54272
	ds_read_b128 v[216:219], v157 offset:55296
	ds_read_b128 v[220:223], v157 offset:56320
	global_load_lds_dwordx4 v[224:225], off
	s_add_i32 m0, s58, 0x2000
	s_add_u32 s56, s56, 0x40080
	v_lshl_add_u64 v[224:225], v[226:227], 0, s[12:13]
	s_addc_u32 s57, s57, 0
	s_add_i32 s58, s79, s33
	global_load_lds_dwordx4 v[224:225], off
	v_lshl_add_u64 v[224:225], s[56:57], 0, v[132:133]
	s_mov_b32 m0, s58
	s_nop 0
	global_load_lds_dwordx4 v[224:225], off
	v_lshl_add_u64 v[224:225], s[56:57], 0, v[128:129]
	s_add_i32 m0, s58, 0x2000
	s_nop 0
	global_load_lds_dwordx4 v[224:225], off
	s_waitcnt vmcnt(6)
	s_waitcnt lgkmcnt(0)
	s_barrier
	s_setprio 1
	s_waitcnt lgkmcnt(0)
	v_mfma_f32_16x16x32_bf16 v[60:63], v[144:147], v[186:189], v[60:63]
	v_mfma_f32_16x16x32_bf16 v[56:59], v[160:163], v[186:189], v[56:59]
	v_mfma_f32_16x16x32_bf16 v[44:47], v[144:147], v[194:197], v[44:47]
	v_mfma_f32_16x16x32_bf16 v[40:43], v[160:163], v[194:197], v[40:43]
	v_mfma_f32_16x16x32_bf16 v[28:31], v[144:147], v[208:211], v[28:31]
	v_mfma_f32_16x16x32_bf16 v[24:27], v[160:163], v[208:211], v[24:27]
	v_lshl_add_u64 v[224:225], v[228:229], 0, s[12:13]
	s_mov_b32 m0, s64
	s_nop 0
	global_load_lds_dwordx4 v[224:225], off
	v_mfma_f32_16x16x32_bf16 v[12:15], v[144:147], v[216:219], v[12:15]
	v_mfma_f32_16x16x32_bf16 v[8:11], v[160:163], v[216:219], v[8:11]
	v_mfma_f32_16x16x32_bf16 v[60:63], v[148:151], v[190:193], v[60:63]
	v_mfma_f32_16x16x32_bf16 v[56:59], v[164:167], v[190:193], v[56:59]
	v_mfma_f32_16x16x32_bf16 v[44:47], v[148:151], v[198:201], v[44:47]
	v_mfma_f32_16x16x32_bf16 v[40:43], v[164:167], v[198:201], v[40:43]
	v_mfma_f32_16x16x32_bf16 v[28:31], v[148:151], v[212:215], v[28:31]
	v_mfma_f32_16x16x32_bf16 v[24:27], v[164:167], v[212:215], v[24:27]
	v_mfma_f32_16x16x32_bf16 v[12:15], v[148:151], v[220:223], v[12:15]
	v_mfma_f32_16x16x32_bf16 v[8:11], v[164:167], v[220:223], v[8:11]
	s_setprio 0
	s_setprio 1
	v_mfma_f32_16x16x32_bf16 v[52:55], v[168:171], v[186:189], v[52:55]
	v_mfma_f32_16x16x32_bf16 v[48:51], v[176:179], v[186:189], v[48:51]
	v_lshl_add_u64 v[224:225], v[230:231], 0, s[12:13]
	s_mov_b32 m0, s65
	s_nop 0
	global_load_lds_dwordx4 v[224:225], off
	v_mfma_f32_16x16x32_bf16 v[36:39], v[168:171], v[194:197], v[36:39]
	v_mfma_f32_16x16x32_bf16 v[32:35], v[176:179], v[194:197], v[32:35]
	v_mfma_f32_16x16x32_bf16 v[20:23], v[168:171], v[208:211], v[20:23]
	v_mfma_f32_16x16x32_bf16 v[16:19], v[176:179], v[208:211], v[16:19]
	v_mfma_f32_16x16x32_bf16 v[4:7], v[168:171], v[216:219], v[4:7]
	v_mfma_f32_16x16x32_bf16 v[0:3], v[176:179], v[216:219], v[0:3]
	v_mfma_f32_16x16x32_bf16 v[52:55], v[172:175], v[190:193], v[52:55]
	v_mfma_f32_16x16x32_bf16 v[48:51], v[182:185], v[190:193], v[48:51]
	v_mfma_f32_16x16x32_bf16 v[36:39], v[172:175], v[198:201], v[36:39]
	v_mfma_f32_16x16x32_bf16 v[32:35], v[182:185], v[198:201], v[32:35]
	v_mfma_f32_16x16x32_bf16 v[20:23], v[172:175], v[212:215], v[20:23]
	v_mfma_f32_16x16x32_bf16 v[16:19], v[182:185], v[212:215], v[16:19]
	v_mfma_f32_16x16x32_bf16 v[4:7], v[172:175], v[220:223], v[4:7]
	v_mfma_f32_16x16x32_bf16 v[0:3], v[182:185], v[220:223], v[0:3]
	s_setprio 0
	s_barrier
	s_add_i32 s84, s84, 2
	s_add_u32 s54, s54, 0x100
	s_addc_u32 s55, s55, 0
	s_add_u32 s82, s82, 0x100
	s_addc_u32 s83, s83, 0
.LBB0_1119:
	ds_read_b128 v[144:147], v155
	ds_read_b128 v[148:151], v155 offset:1024
	ds_read_b128 v[160:163], v155 offset:2048
	ds_read_b128 v[164:167], v155 offset:3072
	ds_read_b128 v[168:171], v156
	ds_read_b128 v[172:175], v156 offset:1024
	ds_read_b128 v[176:179], v156 offset:2048
	ds_read_b128 v[182:185], v156 offset:3072
	s_add_u32 s56, s54, 0xfffc0080
	s_addc_u32 s57, s55, -1
	s_cmp_eq_u32 s84, 12
	s_cselect_b32 s59, s45, s57
	s_cselect_b32 s58, s76, s56
	s_cselect_b32 s57, s43, s83
	s_cselect_b32 s56, s77, s82
	v_lshl_add_u64 v[224:225], s[54:55], 0, v[136:137]
	s_add_i32 m0, s53, 0xc000
	ds_read_b128 v[186:189], v157
	ds_read_b128 v[190:193], v157 offset:1024
	ds_read_b128 v[194:197], v157 offset:2048
	ds_read_b128 v[198:201], v157 offset:3072
	ds_read_b128 v[208:211], v157 offset:4096
	ds_read_b128 v[212:215], v157 offset:5120
	ds_read_b128 v[216:219], v157 offset:6144
	ds_read_b128 v[220:223], v157 offset:7168
	global_load_lds_dwordx4 v[224:225], off
	v_lshl_add_u64 v[224:225], s[54:55], 0, v[138:139]
	s_add_i32 m0, s53, 0xe000
	s_nop 0
	global_load_lds_dwordx4 v[224:225], off
	s_waitcnt vmcnt(8)
	s_waitcnt lgkmcnt(0)
	s_barrier
; #define PG8_STAGE(bufoff, gbase, voff) do { _Pragma("unroll") for (int _i = 0; _i < 2; ++_i) \
;         __builtin_amdgcn_global_load_lds((const unsigned*)((const char*)(gbase) + (voff)[_i]), (PG8_LAS unsigned*)(lds + (bufoff) + ldsw + _i * 8192), 16, 0, 0); } while (0)
; #define PG8_LDA(dst, b, h) do { _Pragma("unroll") for (int m = 0; m < 4; ++m) _Pragma("unroll") for (int k = 0; k < 2; ++k) dst[m][k] = *(const PG8_LAS bf16x8*)(lds + PG8_SA(b, h) + aoff + m * 2048 + k * 1024); } while (0)
; #define PG8_MMA(ai, bj, At, Bt) do { __builtin_amdgcn_s_setprio(1); _Pragma("unroll") for (int m = 0; m < 4; ++m) _Pragma("unroll") for (int n = 0; n < 2; ++n) _Pragma("unroll") for (int k = 0; k < 2; ++k) \
;         acc[ai][bj][m][n] = __builtin_amdgcn_mfma_f32_16x16x32_bf16(Bt[n][k], At[m][k], acc[ai][bj][m][n], 0, 0, 0); __builtin_amdgcn_s_setprio(0); } while (0)
; #define PG8_WAIT_V(n) asm volatile("s_waitcnt vmcnt(" #n ")" ::: "memory")
; #define PG8_WAIT_L(n) asm volatile("s_waitcnt lgkmcnt(" #n ")" ::: "memory")
; #define PG8_BAR __builtin_amdgcn_s_barrier()
; #define PG8_SCHED __builtin_amdgcn_sched_barrier(0)
; template <class Epi, class Sched, bool ALIGN_EPI = false, bool SP2 = false>
; __device__ __forceinline__ void gemm_phase(PG8_LAS unsigned char* lds, const Gemm g, const Sched& S, const Epi& E) {
;     ...
;             PG8_WAIT_V(8); PG8_WAIT_L(0); PG8_BAR; PG8_MMA(0, 0, At, B0); PG8_MMA(0, 1, At, B1); PG8_BAR; PG8_SCHED;
;             PG8_LDA(At, 0, 1); PG8_STAGE(PG8_SB(0, 0), b2, voffB); PG8_STAGE(PG8_SB(0, 1), b2 + hstep, voffB); PG8_STAGE(PG8_SA(0, 0), a2, voffA);
;             PG8_WAIT_V(8); PG8_WAIT_L(0); PG8_BAR; PG8_MMA(1, 0, At, B0); PG8_MMA(1, 1, At, B1); PG8_BAR; PG8_SCHED;
	s_setprio 1
	s_waitcnt lgkmcnt(0)
	v_mfma_f32_16x16x32_bf16 v[124:127], v[144:147], v[186:189], v[124:127]
	v_mfma_f32_16x16x32_bf16 v[120:123], v[160:163], v[186:189], v[120:123]
	v_mfma_f32_16x16x32_bf16 v[108:111], v[144:147], v[194:197], v[108:111]
	v_mfma_f32_16x16x32_bf16 v[104:107], v[160:163], v[194:197], v[104:107]
	v_mfma_f32_16x16x32_bf16 v[92:95], v[144:147], v[208:211], v[92:95]
	v_mfma_f32_16x16x32_bf16 v[88:91], v[160:163], v[208:211], v[88:91]
	v_mfma_f32_16x16x32_bf16 v[76:79], v[144:147], v[216:219], v[76:79]
	v_mfma_f32_16x16x32_bf16 v[72:75], v[160:163], v[216:219], v[72:75]
	v_mfma_f32_16x16x32_bf16 v[124:127], v[148:151], v[190:193], v[124:127]
	v_mfma_f32_16x16x32_bf16 v[120:123], v[164:167], v[190:193], v[120:123]
	v_mfma_f32_16x16x32_bf16 v[108:111], v[148:151], v[198:201], v[108:111]
	v_mfma_f32_16x16x32_bf16 v[104:107], v[164:167], v[198:201], v[104:107]
	v_mfma_f32_16x16x32_bf16 v[92:95], v[148:151], v[212:215], v[92:95]
	v_mfma_f32_16x16x32_bf16 v[88:91], v[164:167], v[212:215], v[88:91]
	v_mfma_f32_16x16x32_bf16 v[76:79], v[148:151], v[220:223], v[76:79]
	v_mfma_f32_16x16x32_bf16 v[72:75], v[164:167], v[220:223], v[72:75]
	s_setprio 0
	s_setprio 1
	v_mfma_f32_16x16x32_bf16 v[116:119], v[168:171], v[186:189], v[116:119]
	v_mfma_f32_16x16x32_bf16 v[112:115], v[176:179], v[186:189], v[112:115]
	v_mfma_f32_16x16x32_bf16 v[100:103], v[168:171], v[194:197], v[100:103]
	v_mfma_f32_16x16x32_bf16 v[96:99], v[176:179], v[194:197], v[96:99]
	v_mfma_f32_16x16x32_bf16 v[84:87], v[168:171], v[208:211], v[84:87]
	v_mfma_f32_16x16x32_bf16 v[80:83], v[176:179], v[208:211], v[80:83]
	v_mfma_f32_16x16x32_bf16 v[68:71], v[168:171], v[216:219], v[68:71]
	v_mfma_f32_16x16x32_bf16 v[64:67], v[176:179], v[216:219], v[64:67]
	v_mfma_f32_16x16x32_bf16 v[116:119], v[172:175], v[190:193], v[116:119]
	v_mfma_f32_16x16x32_bf16 v[112:115], v[182:185], v[190:193], v[112:115]
	v_mfma_f32_16x16x32_bf16 v[100:103], v[172:175], v[198:201], v[100:103]
	v_mfma_f32_16x16x32_bf16 v[96:99], v[182:185], v[198:201], v[96:99]
	v_mfma_f32_16x16x32_bf16 v[84:87], v[172:175], v[212:215], v[84:87]
	v_mfma_f32_16x16x32_bf16 v[80:83], v[182:185], v[212:215], v[80:83]
	v_mfma_f32_16x16x32_bf16 v[68:71], v[172:175], v[220:223], v[68:71]
	v_mfma_f32_16x16x32_bf16 v[64:67], v[182:185], v[220:223], v[64:67]
	s_setprio 0
	s_barrier
	s_add_i32 s78, s66, s33
	v_lshl_add_u64 v[224:225], s[56:57], 0, v[132:133]
	s_mov_b32 m0, s78
	ds_read_b128 v[186:189], v157 offset:16384
	ds_read_b128 v[190:193], v157 offset:17408
	ds_read_b128 v[194:197], v157 offset:18432
	ds_read_b128 v[198:201], v157 offset:19456
	ds_read_b128 v[208:211], v157 offset:20480
	ds_read_b128 v[212:215], v157 offset:21504
	ds_read_b128 v[216:219], v157 offset:22528
	ds_read_b128 v[220:223], v157 offset:23552
	global_load_lds_dwordx4 v[224:225], off
	s_add_i32 m0, s78, 0x2000
	s_add_u32 s78, s56, 0x40000
	v_lshl_add_u64 v[226:227], s[56:57], 0, v[128:129]
	s_addc_u32 s79, s57, 0
	s_add_i32 s85, s67, s33
	global_load_lds_dwordx4 v[226:227], off
	v_lshl_add_u64 v[228:229], s[78:79], 0, v[132:133]
	s_mov_b32 m0, s85
	v_lshl_add_u64 v[230:231], s[58:59], 0, v[130:131]
	global_load_lds_dwordx4 v[228:229], off
	v_lshl_add_u64 v[228:229], s[78:79], 0, v[128:129]
	s_add_i32 m0, s85, 0x2000
	s_nop 0
	global_load_lds_dwordx4 v[228:229], off
	s_waitcnt vmcnt(6)
	s_waitcnt lgkmcnt(0)
	s_barrier
	s_setprio 1
	s_waitcnt lgkmcnt(0)
	v_mfma_f32_16x16x32_bf16 v[60:63], v[144:147], v[186:189], v[60:63]
	v_mfma_f32_16x16x32_bf16 v[56:59], v[160:163], v[186:189], v[56:59]
	v_mfma_f32_16x16x32_bf16 v[44:47], v[144:147], v[194:197], v[44:47]
	v_mfma_f32_16x16x32_bf16 v[40:43], v[160:163], v[194:197], v[40:43]
	v_mfma_f32_16x16x32_bf16 v[28:31], v[144:147], v[208:211], v[28:31]
	v_mfma_f32_16x16x32_bf16 v[24:27], v[160:163], v[208:211], v[24:27]
	v_lshl_add_u64 v[228:229], s[58:59], 0, v[134:135]
	s_mov_b32 m0, s53
	s_nop 0
	global_load_lds_dwordx4 v[228:229], off
	v_mfma_f32_16x16x32_bf16 v[12:15], v[144:147], v[216:219], v[12:15]
	v_mfma_f32_16x16x32_bf16 v[8:11], v[160:163], v[216:219], v[8:11]
	v_mfma_f32_16x16x32_bf16 v[60:63], v[148:151], v[190:193], v[60:63]
	v_mfma_f32_16x16x32_bf16 v[56:59], v[164:167], v[190:193], v[56:59]
	v_mfma_f32_16x16x32_bf16 v[44:47], v[148:151], v[198:201], v[44:47]
	v_mfma_f32_16x16x32_bf16 v[40:43], v[164:167], v[198:201], v[40:43]
	v_mfma_f32_16x16x32_bf16 v[28:31], v[148:151], v[212:215], v[28:31]
	v_mfma_f32_16x16x32_bf16 v[24:27], v[164:167], v[212:215], v[24:27]
	v_mfma_f32_16x16x32_bf16 v[12:15], v[148:151], v[220:223], v[12:15]
	v_mfma_f32_16x16x32_bf16 v[8:11], v[164:167], v[220:223], v[8:11]
	s_setprio 0
	s_setprio 1
	v_mfma_f32_16x16x32_bf16 v[52:55], v[168:171], v[186:189], v[52:55]
	v_mfma_f32_16x16x32_bf16 v[48:51], v[176:179], v[186:189], v[48:51]
	s_mov_b32 m0, s60
	s_nop 0
	global_load_lds_dwordx4 v[230:231], off
	v_mfma_f32_16x16x32_bf16 v[36:39], v[168:171], v[194:197], v[36:39]
	v_mfma_f32_16x16x32_bf16 v[32:35], v[176:179], v[194:197], v[32:35]
	v_mfma_f32_16x16x32_bf16 v[20:23], v[168:171], v[208:211], v[20:23]
	v_mfma_f32_16x16x32_bf16 v[16:19], v[176:179], v[208:211], v[16:19]
	v_mfma_f32_16x16x32_bf16 v[4:7], v[168:171], v[216:219], v[4:7]
	v_mfma_f32_16x16x32_bf16 v[0:3], v[176:179], v[216:219], v[0:3]
	v_mfma_f32_16x16x32_bf16 v[52:55], v[172:175], v[190:193], v[52:55]
	v_mfma_f32_16x16x32_bf16 v[48:51], v[182:185], v[190:193], v[48:51]
	v_mfma_f32_16x16x32_bf16 v[36:39], v[172:175], v[198:201], v[36:39]
	v_mfma_f32_16x16x32_bf16 v[32:35], v[182:185], v[198:201], v[32:35]
	v_mfma_f32_16x16x32_bf16 v[20:23], v[172:175], v[212:215], v[20:23]
	v_mfma_f32_16x16x32_bf16 v[16:19], v[182:185], v[212:215], v[16:19]
	v_mfma_f32_16x16x32_bf16 v[4:7], v[172:175], v[220:223], v[4:7]
	v_mfma_f32_16x16x32_bf16 v[0:3], v[182:185], v[220:223], v[0:3]
	s_setprio 0
	s_barrier
; #define PG8_STAGE(bufoff, gbase, voff) do { _Pragma("unroll") for (int _i = 0; _i < 2; ++_i) \
;         __builtin_amdgcn_global_load_lds((const unsigned*)((const char*)(gbase) + (voff)[_i]), (PG8_LAS unsigned*)(lds + (bufoff) + ldsw + _i * 8192), 16, 0, 0); } while (0)
; #define PG8_LDA(dst, b, h) do { _Pragma("unroll") for (int m = 0; m < 4; ++m) _Pragma("unroll") for (int k = 0; k < 2; ++k) dst[m][k] = *(const PG8_LAS bf16x8*)(lds + PG8_SA(b, h) + aoff + m * 2048 + k * 1024); } while (0)
; #define PG8_LDB(dst, b, h) do { _Pragma("unroll") for (int n = 0; n < 2; ++n) _Pragma("unroll") for (int k = 0; k < 2; ++k) dst[n][k] = *(const PG8_LAS bf16x8*)(lds + PG8_SB(b, h) + boff + n * 2048 + k * 1024); } while (0)
; #define PG8_MMA(ai, bj, At, Bt) do { __builtin_amdgcn_s_setprio(1); _Pragma("unroll") for (int m = 0; m < 4; ++m) _Pragma("unroll") for (int n = 0; n < 2; ++n) _Pragma("unroll") for (int k = 0; k < 2; ++k) \
;         acc[ai][bj][m][n] = __builtin_amdgcn_mfma_f32_16x16x32_bf16(Bt[n][k], At[m][k], acc[ai][bj][m][n], 0, 0, 0); __builtin_amdgcn_s_setprio(0); } while (0)
; #define PG8_WAIT_V(n) asm volatile("s_waitcnt vmcnt(" #n ")" ::: "memory")
; #define PG8_WAIT_L(n) asm volatile("s_waitcnt lgkmcnt(" #n ")" ::: "memory")
; #define PG8_BAR __builtin_amdgcn_s_barrier()
; #define PG8_SCHED __builtin_amdgcn_sched_barrier(0)
; template <class Epi, class Sched, bool ALIGN_EPI = false, bool SP2 = false>
; __device__ __forceinline__ void gemm_phase(PG8_LAS unsigned char* lds, const Gemm g, const Sched& S, const Epi& E) {
;     ...
;             PG8_LDB(B0, 1, 0); PG8_LDB(B1, 1, 1); PG8_SCHED; PG8_LDA(At, 1, 0); PG8_STAGE(PG8_SA(0, 1), a2 + hstep, voffA);
;             PG8_WAIT_V(8); PG8_WAIT_L(0); PG8_BAR; PG8_MMA(0, 0, At, B0); PG8_MMA(0, 1, At, B1); PG8_BAR; PG8_SCHED;
	s_add_i32 s78, 0, 0x18000
	v_add_u32_e32 v159, s78, v153
	s_add_i32 s79, 0, 0x1c000
	ds_read_b128 v[144:147], v159
	ds_read_b128 v[148:151], v159 offset:1024
	ds_read_b128 v[160:163], v159 offset:2048
	ds_read_b128 v[164:167], v159 offset:3072
	v_add_u32_e32 v159, s79, v153
	ds_read_b128 v[168:171], v159
	ds_read_b128 v[172:175], v159 offset:1024
	ds_read_b128 v[176:179], v159 offset:2048
	ds_read_b128 v[182:185], v159 offset:3072
	s_add_u32 s58, s58, 0x40000
	s_addc_u32 s59, s59, 0
	s_mov_b32 m0, s61
	v_lshl_add_u64 v[232:233], s[58:59], 0, v[134:135]
	ds_read_b128 v[186:189], v157 offset:32768
	ds_read_b128 v[190:193], v157 offset:33792
	ds_read_b128 v[194:197], v157 offset:34816
	ds_read_b128 v[198:201], v157 offset:35840
	ds_read_b128 v[208:211], v157 offset:36864
	ds_read_b128 v[212:215], v157 offset:37888
	ds_read_b128 v[216:219], v157 offset:38912
	ds_read_b128 v[220:223], v157 offset:39936
	global_load_lds_dwordx4 v[232:233], off
	v_lshl_add_u64 v[232:233], s[58:59], 0, v[130:131]
	s_mov_b32 m0, s62
	s_nop 0
	global_load_lds_dwordx4 v[232:233], off
	s_waitcnt vmcnt(8)
	s_waitcnt lgkmcnt(0)
	s_barrier
	s_setprio 1
	s_waitcnt lgkmcnt(0)
	v_mfma_f32_16x16x32_bf16 v[124:127], v[144:147], v[186:189], v[124:127]
	v_mfma_f32_16x16x32_bf16 v[120:123], v[160:163], v[186:189], v[120:123]
	v_mfma_f32_16x16x32_bf16 v[108:111], v[144:147], v[194:197], v[108:111]
	v_mfma_f32_16x16x32_bf16 v[104:107], v[160:163], v[194:197], v[104:107]
	v_mfma_f32_16x16x32_bf16 v[92:95], v[144:147], v[208:211], v[92:95]
	v_mfma_f32_16x16x32_bf16 v[88:91], v[160:163], v[208:211], v[88:91]
	v_mfma_f32_16x16x32_bf16 v[76:79], v[144:147], v[216:219], v[76:79]
	v_mfma_f32_16x16x32_bf16 v[72:75], v[160:163], v[216:219], v[72:75]
	v_mfma_f32_16x16x32_bf16 v[124:127], v[148:151], v[190:193], v[124:127]
	v_mfma_f32_16x16x32_bf16 v[120:123], v[164:167], v[190:193], v[120:123]
	v_mfma_f32_16x16x32_bf16 v[108:111], v[148:151], v[198:201], v[108:111]
	v_mfma_f32_16x16x32_bf16 v[104:107], v[164:167], v[198:201], v[104:107]
	v_mfma_f32_16x16x32_bf16 v[92:95], v[148:151], v[212:215], v[92:95]
	v_mfma_f32_16x16x32_bf16 v[88:91], v[164:167], v[212:215], v[88:91]
	v_mfma_f32_16x16x32_bf16 v[76:79], v[148:151], v[220:223], v[76:79]
	v_mfma_f32_16x16x32_bf16 v[72:75], v[164:167], v[220:223], v[72:75]
	s_setprio 0
	s_setprio 1
	v_mfma_f32_16x16x32_bf16 v[116:119], v[168:171], v[186:189], v[116:119]
	v_mfma_f32_16x16x32_bf16 v[112:115], v[176:179], v[186:189], v[112:115]
	v_mfma_f32_16x16x32_bf16 v[100:103], v[168:171], v[194:197], v[100:103]
	v_mfma_f32_16x16x32_bf16 v[96:99], v[176:179], v[194:197], v[96:99]
	v_mfma_f32_16x16x32_bf16 v[84:87], v[168:171], v[208:211], v[84:87]
	v_mfma_f32_16x16x32_bf16 v[80:83], v[176:179], v[208:211], v[80:83]
	v_mfma_f32_16x16x32_bf16 v[68:71], v[168:171], v[216:219], v[68:71]
	v_mfma_f32_16x16x32_bf16 v[64:67], v[176:179], v[216:219], v[64:67]
	v_mfma_f32_16x16x32_bf16 v[116:119], v[172:175], v[190:193], v[116:119]
	v_mfma_f32_16x16x32_bf16 v[112:115], v[182:185], v[190:193], v[112:115]
	v_mfma_f32_16x16x32_bf16 v[100:103], v[172:175], v[198:201], v[100:103]
	v_mfma_f32_16x16x32_bf16 v[96:99], v[182:185], v[198:201], v[96:99]
	v_mfma_f32_16x16x32_bf16 v[84:87], v[172:175], v[212:215], v[84:87]
	v_mfma_f32_16x16x32_bf16 v[80:83], v[182:185], v[212:215], v[80:83]
	v_mfma_f32_16x16x32_bf16 v[68:71], v[172:175], v[220:223], v[68:71]
	v_mfma_f32_16x16x32_bf16 v[64:67], v[182:185], v[220:223], v[64:67]
	s_setprio 0
	s_barrier
; #define PG8_STAGE(bufoff, gbase, voff) do { _Pragma("unroll") for (int _i = 0; _i < 2; ++_i) \
;         __builtin_amdgcn_global_load_lds((const unsigned*)((const char*)(gbase) + (voff)[_i]), (PG8_LAS unsigned*)(lds + (bufoff) + ldsw + _i * 8192), 16, 0, 0); } while (0)
; #define PG8_LDA(dst, b, h) do { _Pragma("unroll") for (int m = 0; m < 4; ++m) _Pragma("unroll") for (int k = 0; k < 2; ++k) dst[m][k] = *(const PG8_LAS bf16x8*)(lds + PG8_SA(b, h) + aoff + m * 2048 + k * 1024); } while (0)
; #define PG8_MMA(ai, bj, At, Bt) do { __builtin_amdgcn_s_setprio(1); _Pragma("unroll") for (int m = 0; m < 4; ++m) _Pragma("unroll") for (int n = 0; n < 2; ++n) _Pragma("unroll") for (int k = 0; k < 2; ++k) \
;         acc[ai][bj][m][n] = __builtin_amdgcn_mfma_f32_16x16x32_bf16(Bt[n][k], At[m][k], acc[ai][bj][m][n], 0, 0, 0); __builtin_amdgcn_s_setprio(0); } while (0)
; #define PG8_WAIT_V(n) asm volatile("s_waitcnt vmcnt(" #n ")" ::: "memory")
; #define PG8_WAIT_L(n) asm volatile("s_waitcnt lgkmcnt(" #n ")" ::: "memory")
; #define PG8_BAR __builtin_amdgcn_s_barrier()
; #define PG8_SCHED __builtin_amdgcn_sched_barrier(0)
; __device__ __forceinline__ float row_rs(const float* ssp, int row) { const unsigned long long v = ((const unsigned long long*)ssp)[row];
;     return __builtin_amdgcn_rsqf((float)v * (1.0f / 4294967296.0f) * (1.0f / 1024.0f) + RMS_EPS); }
; template <class Epi, class Sched, bool ALIGN_EPI = false, bool SP2 = false>
; __device__ __forceinline__ void gemm_phase(PG8_LAS unsigned char* lds, const Gemm g, const Sched& S, const Epi& E) {
;     ...
;             PG8_LDA(At, 1, 1); PG8_STAGE(PG8_SB(1, 0), b3, voffB); PG8_STAGE(PG8_SB(1, 1), b3 + hstep, voffB); PG8_STAGE(PG8_SA(1, 0), a3, voffA);
;             PG8_WAIT_V(8); PG8_WAIT_L(0); PG8_BAR; PG8_MMA(1, 0, At, B0); PG8_MMA(1, 1, At, B1); PG8_BAR; PG8_SCHED;
	s_add_i32 s58, s78, s33
	v_lshl_add_u64 v[224:225], v[224:225], 0, s[12:13]
	s_mov_b32 m0, s58
	ds_read_b128 v[186:189], v157 offset:49152
	ds_read_b128 v[190:193], v157 offset:50176
	ds_read_b128 v[194:197], v157 offset:51200
	ds_read_b128 v[198:201], v157 offset:52224
	ds_read_b128 v[208:211], v157 offset:53248
	ds_read_b128 v[212:215], v157 offset:54272
	ds_read_b128 v[216:219], v157 offset:55296
	ds_read_b128 v[220:223], v157 offset:56320
	global_load_lds_dwordx4 v[224:225], off
	s_add_i32 m0, s58, 0x2000
	s_add_u32 s56, s56, 0x40080
	v_lshl_add_u64 v[224:225], v[226:227], 0, s[12:13]
	s_addc_u32 s57, s57, 0
	s_add_i32 s58, s79, s33
	global_load_lds_dwordx4 v[224:225], off
	v_lshl_add_u64 v[224:225], s[56:57], 0, v[132:133]
	s_mov_b32 m0, s58
	s_nop 0
	global_load_lds_dwordx4 v[224:225], off
	v_lshl_add_u64 v[224:225], s[56:57], 0, v[128:129]
	s_add_i32 m0, s58, 0x2000
	s_nop 0
	global_load_lds_dwordx4 v[224:225], off
	s_waitcnt vmcnt(6)
	s_waitcnt lgkmcnt(0)
	s_barrier
	s_setprio 1
	s_waitcnt lgkmcnt(0)
	v_mfma_f32_16x16x32_bf16 v[60:63], v[144:147], v[186:189], v[60:63]
	v_mfma_f32_16x16x32_bf16 v[56:59], v[160:163], v[186:189], v[56:59]
	v_mfma_f32_16x16x32_bf16 v[44:47], v[144:147], v[194:197], v[44:47]
	v_mfma_f32_16x16x32_bf16 v[40:43], v[160:163], v[194:197], v[40:43]
	v_mfma_f32_16x16x32_bf16 v[28:31], v[144:147], v[208:211], v[28:31]
	v_mfma_f32_16x16x32_bf16 v[24:27], v[160:163], v[208:211], v[24:27]
	v_lshl_add_u64 v[224:225], v[228:229], 0, s[12:13]
	s_mov_b32 m0, s64
	s_nop 0
	global_load_lds_dwordx4 v[224:225], off
	v_mfma_f32_16x16x32_bf16 v[12:15], v[144:147], v[216:219], v[12:15]
	v_mfma_f32_16x16x32_bf16 v[8:11], v[160:163], v[216:219], v[8:11]
	v_mfma_f32_16x16x32_bf16 v[60:63], v[148:151], v[190:193], v[60:63]
	v_mfma_f32_16x16x32_bf16 v[56:59], v[164:167], v[190:193], v[56:59]
	v_mfma_f32_16x16x32_bf16 v[44:47], v[148:151], v[198:201], v[44:47]
	v_mfma_f32_16x16x32_bf16 v[40:43], v[164:167], v[198:201], v[40:43]
	v_mfma_f32_16x16x32_bf16 v[28:31], v[148:151], v[212:215], v[28:31]
	v_mfma_f32_16x16x32_bf16 v[24:27], v[164:167], v[212:215], v[24:27]
	v_mfma_f32_16x16x32_bf16 v[12:15], v[148:151], v[220:223], v[12:15]
	v_mfma_f32_16x16x32_bf16 v[8:11], v[164:167], v[220:223], v[8:11]
	s_setprio 0
	s_setprio 1
	v_mfma_f32_16x16x32_bf16 v[52:55], v[168:171], v[186:189], v[52:55]
	v_mfma_f32_16x16x32_bf16 v[48:51], v[176:179], v[186:189], v[48:51]
	v_lshl_add_u64 v[224:225], v[230:231], 0, s[12:13]
	s_mov_b32 m0, s65
	s_nop 0
	global_load_lds_dwordx4 v[224:225], off
	v_mfma_f32_16x16x32_bf16 v[36:39], v[168:171], v[194:197], v[36:39]
	v_mfma_f32_16x16x32_bf16 v[32:35], v[176:179], v[194:197], v[32:35]
	v_mfma_f32_16x16x32_bf16 v[20:23], v[168:171], v[208:211], v[20:23]
	v_mfma_f32_16x16x32_bf16 v[16:19], v[176:179], v[208:211], v[16:19]
	v_mfma_f32_16x16x32_bf16 v[4:7], v[168:171], v[216:219], v[4:7]
	v_mfma_f32_16x16x32_bf16 v[0:3], v[176:179], v[216:219], v[0:3]
	v_mfma_f32_16x16x32_bf16 v[52:55], v[172:175], v[190:193], v[52:55]
	v_mfma_f32_16x16x32_bf16 v[48:51], v[182:185], v[190:193], v[48:51]
	v_mfma_f32_16x16x32_bf16 v[36:39], v[172:175], v[198:201], v[36:39]
	v_mfma_f32_16x16x32_bf16 v[32:35], v[182:185], v[198:201], v[32:35]
	v_mfma_f32_16x16x32_bf16 v[20:23], v[172:175], v[212:215], v[20:23]
	v_mfma_f32_16x16x32_bf16 v[16:19], v[182:185], v[212:215], v[16:19]
	v_mfma_f32_16x16x32_bf16 v[4:7], v[172:175], v[220:223], v[4:7]
	v_mfma_f32_16x16x32_bf16 v[0:3], v[182:185], v[220:223], v[0:3]
	s_setprio 0
	s_barrier
	s_add_i32 s84, s84, 2
	s_add_u32 s54, s54, 0x100
	s_addc_u32 s55, s55, 0
	s_add_u32 s82, s82, 0x100
	s_addc_u32 s83, s83, 0
	s_cmp_gt_u32 s84, 13
	s_cbranch_scc0 .LBB0_1119
	v_lshl_add_u32 v144, s52, 8, v152
	v_ashrrev_i32_e32 v145, 31, v144
	v_lshl_add_u64 v[150:151], v[144:145], 3, s[36:37]
	global_load_dwordx2 v[182:183], v[150:151], off
	global_load_dwordx2 v[184:185], v[150:151], off offset:128
	global_load_dwordx2 v[186:187], v[150:151], off offset:256
	global_load_dwordx2 v[188:189], v[150:151], off offset:384
	global_load_dwordx2 v[190:191], v[150:151], off offset:1024
	global_load_dwordx2 v[192:193], v[150:151], off offset:1152
	global_load_dwordx2 v[194:195], v[150:151], off offset:1280
	global_load_dwordx2 v[196:197], v[150:151], off offset:1408
	s_and_b64 vcc, exec, s[38:39]
	s_cbranch_vccz .LBB0_1122
	s_barrier

; #define PG8_STAGE(bufoff, gbase, voff) do { _Pragma("unroll") for (int _i = 0; _i < 2; ++_i) \
;         __builtin_amdgcn_global_load_lds((const unsigned*)((const char*)(gbase) + (voff)[_i]), (PG8_LAS unsigned*)(lds + (bufoff) + ldsw + _i * 8192), 16, 0, 0); } while (0)
; #define PG8_LDA(dst, b, h) do { _Pragma("unroll") for (int m = 0; m < 4; ++m) _Pragma("unroll") for (int k = 0; k < 2; ++k) dst[m][k] = *(const PG8_LAS bf16x8*)(lds + PG8_SA(b, h) + aoff + m * 2048 + k * 1024); } while (0)
; #define PG8_LDB(dst, b, h) do { _Pragma("unroll") for (int n = 0; n < 2; ++n) _Pragma("unroll") for (int k = 0; k < 2; ++k) dst[n][k] = *(const PG8_LAS bf16x8*)(lds + PG8_SB(b, h) + boff + n * 2048 + k * 1024); } while (0)
; #define PG8_MMA(ai, bj, At, Bt) do { __builtin_amdgcn_s_setprio(1); _Pragma("unroll") for (int m = 0; m < 4; ++m) _Pragma("unroll") for (int n = 0; n < 2; ++n) _Pragma("unroll") for (int k = 0; k < 2; ++k) \
;         acc[ai][bj][m][n] = __builtin_amdgcn_mfma_f32_16x16x32_bf16(Bt[n][k], At[m][k], acc[ai][bj][m][n], 0, 0, 0); __builtin_amdgcn_s_setprio(0); } while (0)
; #define PG8_WAIT_V(n) asm volatile("s_waitcnt vmcnt(" #n ")" ::: "memory")
; #define PG8_WAIT_L(n) asm volatile("s_waitcnt lgkmcnt(" #n ")" ::: "memory")
; #define PG8_BAR __builtin_amdgcn_s_barrier()
; #define PG8_SCHED __builtin_amdgcn_sched_barrier(0)
; template <class Epi, class Sched, bool ALIGN_EPI = false, bool SP2 = false>
; __device__ __forceinline__ void gemm_phase(PG8_LAS unsigned char* lds, const Gemm g, const Sched& S, const Epi& E) {
;     ...
;             PG8_LDB(B0, 0, 0); PG8_LDB(B1, 0, 1); PG8_SCHED; PG8_LDA(At, 0, 0); PG8_STAGE(PG8_SA(1, 1), a1 + hstep, voffA);
;             PG8_WAIT_V(8); PG8_WAIT_L(0); PG8_BAR; PG8_MMA(0, 0, At, B0); PG8_MMA(0, 1, At, B1); PG8_BAR; PG8_SCHED;
;             PG8_LDA(At, 0, 1); PG8_STAGE(PG8_SB(0, 0), b2, voffB); PG8_STAGE(PG8_SB(0, 1), b2 + hstep, voffB); PG8_STAGE(PG8_SA(0, 0), a2, voffA);
;             PG8_WAIT_V(8); PG8_WAIT_L(0); PG8_BAR; PG8_MMA(1, 0, At, B0); PG8_MMA(1, 1, At, B1); PG8_BAR; PG8_SCHED;
.LBB0_1196:
	s_add_u32 s82, s52, 0x100
	s_addc_u32 s83, s53, 0
	s_mov_b32 s84, -2
	s_waitcnt lgkmcnt(0)
	ds_read_b128 v[144:147], v151
	ds_read_b128 v[156:159], v151 offset:1024
	ds_read_b128 v[160:163], v151 offset:2048
	ds_read_b128 v[164:167], v151 offset:3072
	ds_read_b128 v[168:171], v152
	ds_read_b128 v[172:175], v152 offset:1024
	ds_read_b128 v[176:179], v152 offset:2048
	ds_read_b128 v[182:185], v152 offset:3072
	s_add_u32 s52, s50, 0x100
	s_addc_u32 s53, s51, 0
	s_cmp_eq_u32 s84, 40
	s_cselect_b32 s57, s1, s53
	s_cselect_b32 s56, s0, s52
	s_cselect_b32 s55, s49, s83
	s_cselect_b32 s54, s48, s82
	v_lshl_add_u64 v[224:225], s[50:51], 0, v[136:137]
	s_add_i32 m0, s34, 0xc000
	ds_read_b128 v[186:189], v153
	ds_read_b128 v[190:193], v153 offset:1024
	ds_read_b128 v[194:197], v153 offset:2048
	ds_read_b128 v[198:201], v153 offset:3072
	ds_read_b128 v[208:211], v153 offset:4096
	ds_read_b128 v[212:215], v153 offset:5120
	ds_read_b128 v[216:219], v153 offset:6144
	ds_read_b128 v[220:223], v153 offset:7168
	global_load_lds_dwordx4 v[224:225], off
	v_lshl_add_u64 v[224:225], s[50:51], 0, v[138:139]
	s_add_i32 m0, s34, 0xe000
	s_nop 0
	global_load_lds_dwordx4 v[224:225], off
	s_waitcnt vmcnt(8)
	s_waitcnt lgkmcnt(0)
	s_barrier
	s_setprio 1
	s_waitcnt lgkmcnt(0)
	v_mfma_f32_16x16x32_bf16 v[124:127], v[144:147], v[186:189], 0
	v_mfma_f32_16x16x32_bf16 v[120:123], v[160:163], v[186:189], 0
	v_mfma_f32_16x16x32_bf16 v[108:111], v[144:147], v[194:197], 0
	v_mfma_f32_16x16x32_bf16 v[104:107], v[160:163], v[194:197], 0
	v_mfma_f32_16x16x32_bf16 v[92:95], v[144:147], v[208:211], 0
	v_mfma_f32_16x16x32_bf16 v[88:91], v[160:163], v[208:211], 0
	v_mfma_f32_16x16x32_bf16 v[76:79], v[144:147], v[216:219], 0
	v_mfma_f32_16x16x32_bf16 v[72:75], v[160:163], v[216:219], 0
	v_mfma_f32_16x16x32_bf16 v[124:127], v[156:159], v[190:193], v[124:127]
	v_mfma_f32_16x16x32_bf16 v[120:123], v[164:167], v[190:193], v[120:123]
	v_mfma_f32_16x16x32_bf16 v[108:111], v[156:159], v[198:201], v[108:111]
	v_mfma_f32_16x16x32_bf16 v[104:107], v[164:167], v[198:201], v[104:107]
	v_mfma_f32_16x16x32_bf16 v[92:95], v[156:159], v[212:215], v[92:95]
	v_mfma_f32_16x16x32_bf16 v[88:91], v[164:167], v[212:215], v[88:91]
	v_mfma_f32_16x16x32_bf16 v[76:79], v[156:159], v[220:223], v[76:79]
	v_mfma_f32_16x16x32_bf16 v[72:75], v[164:167], v[220:223], v[72:75]
	s_setprio 0
	s_setprio 1
	v_mfma_f32_16x16x32_bf16 v[116:119], v[168:171], v[186:189], 0
	v_mfma_f32_16x16x32_bf16 v[112:115], v[176:179], v[186:189], 0
	v_mfma_f32_16x16x32_bf16 v[100:103], v[168:171], v[194:197], 0
	v_mfma_f32_16x16x32_bf16 v[96:99], v[176:179], v[194:197], 0
	v_mfma_f32_16x16x32_bf16 v[84:87], v[168:171], v[208:211], 0
	v_mfma_f32_16x16x32_bf16 v[80:83], v[176:179], v[208:211], 0
	v_mfma_f32_16x16x32_bf16 v[68:71], v[168:171], v[216:219], 0
	v_mfma_f32_16x16x32_bf16 v[64:67], v[176:179], v[216:219], 0
	v_mfma_f32_16x16x32_bf16 v[116:119], v[172:175], v[190:193], v[116:119]
	v_mfma_f32_16x16x32_bf16 v[112:115], v[182:185], v[190:193], v[112:115]
	v_mfma_f32_16x16x32_bf16 v[100:103], v[172:175], v[198:201], v[100:103]
	v_mfma_f32_16x16x32_bf16 v[96:99], v[182:185], v[198:201], v[96:99]
	v_mfma_f32_16x16x32_bf16 v[84:87], v[172:175], v[212:215], v[84:87]
	v_mfma_f32_16x16x32_bf16 v[80:83], v[182:185], v[212:215], v[80:83]
	v_mfma_f32_16x16x32_bf16 v[68:71], v[172:175], v[220:223], v[68:71]
	v_mfma_f32_16x16x32_bf16 v[64:67], v[182:185], v[220:223], v[64:67]
	s_setprio 0
	s_barrier
	s_add_i32 s50, s64, s33
	v_lshl_add_u64 v[224:225], s[54:55], 0, v[130:131]
	s_mov_b32 m0, s50
	ds_read_b128 v[186:189], v153 offset:16384
	ds_read_b128 v[190:193], v153 offset:17408
	ds_read_b128 v[194:197], v153 offset:18432
	ds_read_b128 v[198:201], v153 offset:19456
	ds_read_b128 v[208:211], v153 offset:20480
	ds_read_b128 v[212:215], v153 offset:21504
	ds_read_b128 v[216:219], v153 offset:22528
	ds_read_b128 v[220:223], v153 offset:23552
	global_load_lds_dwordx4 v[224:225], off
	s_add_i32 m0, s50, 0x2000
	s_add_u32 s50, s54, 0xb0000
	v_lshl_add_u64 v[226:227], s[54:55], 0, v[134:135]
	s_addc_u32 s51, s55, 0
	s_add_i32 s78, s65, s33
	global_load_lds_dwordx4 v[226:227], off
	v_lshl_add_u64 v[228:229], s[50:51], 0, v[130:131]
	s_mov_b32 m0, s78
	v_lshl_add_u64 v[230:231], s[56:57], 0, v[132:133]
	global_load_lds_dwordx4 v[228:229], off
	v_lshl_add_u64 v[228:229], s[50:51], 0, v[134:135]
	s_add_i32 m0, s78, 0x2000
	s_nop 0
	global_load_lds_dwordx4 v[228:229], off
	s_waitcnt vmcnt(6)
	s_waitcnt lgkmcnt(0)
	s_barrier
; #define PG8_STAGE(bufoff, gbase, voff) do { _Pragma("unroll") for (int _i = 0; _i < 2; ++_i) \
;         __builtin_amdgcn_global_load_lds((const unsigned*)((const char*)(gbase) + (voff)[_i]), (PG8_LAS unsigned*)(lds + (bufoff) + ldsw + _i * 8192), 16, 0, 0); } while (0)
; #define PG8_LDA(dst, b, h) do { _Pragma("unroll") for (int m = 0; m < 4; ++m) _Pragma("unroll") for (int k = 0; k < 2; ++k) dst[m][k] = *(const PG8_LAS bf16x8*)(lds + PG8_SA(b, h) + aoff + m * 2048 + k * 1024); } while (0)
; #define PG8_LDB(dst, b, h) do { _Pragma("unroll") for (int n = 0; n < 2; ++n) _Pragma("unroll") for (int k = 0; k < 2; ++k) dst[n][k] = *(const PG8_LAS bf16x8*)(lds + PG8_SB(b, h) + boff + n * 2048 + k * 1024); } while (0)
; #define PG8_MMA(ai, bj, At, Bt) do { __builtin_amdgcn_s_setprio(1); _Pragma("unroll") for (int m = 0; m < 4; ++m) _Pragma("unroll") for (int n = 0; n < 2; ++n) _Pragma("unroll") for (int k = 0; k < 2; ++k) \
;         acc[ai][bj][m][n] = __builtin_amdgcn_mfma_f32_16x16x32_bf16(Bt[n][k], At[m][k], acc[ai][bj][m][n], 0, 0, 0); __builtin_amdgcn_s_setprio(0); } while (0)
; #define PG8_WAIT_V(n) asm volatile("s_waitcnt vmcnt(" #n ")" ::: "memory")
; #define PG8_WAIT_L(n) asm volatile("s_waitcnt lgkmcnt(" #n ")" ::: "memory")
; #define PG8_BAR __builtin_amdgcn_s_barrier()
; #define PG8_SCHED __builtin_amdgcn_sched_barrier(0)
; template <class Epi, class Sched, bool ALIGN_EPI = false, bool SP2 = false>
; __device__ __forceinline__ void gemm_phase(PG8_LAS unsigned char* lds, const Gemm g, const Sched& S, const Epi& E) {
;     ...
;             PG8_WAIT_V(8); PG8_WAIT_L(0); PG8_BAR; PG8_MMA(1, 0, At, B0); PG8_MMA(1, 1, At, B1); PG8_BAR; PG8_SCHED;
;             PG8_LDB(B0, 1, 0); PG8_LDB(B1, 1, 1); PG8_SCHED; PG8_LDA(At, 1, 0); PG8_STAGE(PG8_SA(0, 1), a2 + hstep, voffA);
;             PG8_WAIT_V(8); PG8_WAIT_L(0); PG8_BAR; PG8_MMA(0, 0, At, B0); PG8_MMA(0, 1, At, B1); PG8_BAR; PG8_SCHED;
	s_setprio 1
	s_waitcnt lgkmcnt(0)
	v_mfma_f32_16x16x32_bf16 v[60:63], v[144:147], v[186:189], 0
	v_mfma_f32_16x16x32_bf16 v[56:59], v[160:163], v[186:189], 0
	v_mfma_f32_16x16x32_bf16 v[44:47], v[144:147], v[194:197], 0
	v_mfma_f32_16x16x32_bf16 v[40:43], v[160:163], v[194:197], 0
	v_mfma_f32_16x16x32_bf16 v[28:31], v[144:147], v[208:211], 0
	v_mfma_f32_16x16x32_bf16 v[24:27], v[160:163], v[208:211], 0
	v_lshl_add_u64 v[228:229], s[56:57], 0, v[128:129]
	s_mov_b32 m0, s34
	s_nop 0
	global_load_lds_dwordx4 v[228:229], off
	v_mfma_f32_16x16x32_bf16 v[12:15], v[144:147], v[216:219], 0
	v_mfma_f32_16x16x32_bf16 v[8:11], v[160:163], v[216:219], 0
	v_mfma_f32_16x16x32_bf16 v[60:63], v[156:159], v[190:193], v[60:63]
	v_mfma_f32_16x16x32_bf16 v[56:59], v[164:167], v[190:193], v[56:59]
	v_mfma_f32_16x16x32_bf16 v[44:47], v[156:159], v[198:201], v[44:47]
	v_mfma_f32_16x16x32_bf16 v[40:43], v[164:167], v[198:201], v[40:43]
	v_mfma_f32_16x16x32_bf16 v[28:31], v[156:159], v[212:215], v[28:31]
	v_mfma_f32_16x16x32_bf16 v[24:27], v[164:167], v[212:215], v[24:27]
	v_mfma_f32_16x16x32_bf16 v[12:15], v[156:159], v[220:223], v[12:15]
	v_mfma_f32_16x16x32_bf16 v[8:11], v[164:167], v[220:223], v[8:11]
	s_setprio 0
	s_setprio 1
	v_mfma_f32_16x16x32_bf16 v[52:55], v[168:171], v[186:189], 0
	v_mfma_f32_16x16x32_bf16 v[48:51], v[176:179], v[186:189], 0
	s_mov_b32 m0, s58
	s_nop 0
	global_load_lds_dwordx4 v[230:231], off
	v_mfma_f32_16x16x32_bf16 v[36:39], v[168:171], v[194:197], 0
	v_mfma_f32_16x16x32_bf16 v[32:35], v[176:179], v[194:197], 0
	v_mfma_f32_16x16x32_bf16 v[20:23], v[168:171], v[208:211], 0
	v_mfma_f32_16x16x32_bf16 v[16:19], v[176:179], v[208:211], 0
	v_mfma_f32_16x16x32_bf16 v[4:7], v[168:171], v[216:219], 0
	v_mfma_f32_16x16x32_bf16 v[0:3], v[176:179], v[216:219], 0
	v_mfma_f32_16x16x32_bf16 v[52:55], v[172:175], v[190:193], v[52:55]
	v_mfma_f32_16x16x32_bf16 v[48:51], v[182:185], v[190:193], v[48:51]
	v_mfma_f32_16x16x32_bf16 v[36:39], v[172:175], v[198:201], v[36:39]
	v_mfma_f32_16x16x32_bf16 v[32:35], v[182:185], v[198:201], v[32:35]
	v_mfma_f32_16x16x32_bf16 v[20:23], v[172:175], v[212:215], v[20:23]
	v_mfma_f32_16x16x32_bf16 v[16:19], v[182:185], v[212:215], v[16:19]
	v_mfma_f32_16x16x32_bf16 v[4:7], v[172:175], v[220:223], v[4:7]
	v_mfma_f32_16x16x32_bf16 v[0:3], v[182:185], v[220:223], v[0:3]
	s_setprio 0
	s_barrier
	s_add_i32 s78, 0, 0x18000
	v_add_u32_e32 v155, s78, v149
	s_add_i32 s79, 0, 0x1c000
	ds_read_b128 v[144:147], v155
	ds_read_b128 v[156:159], v155 offset:1024
	ds_read_b128 v[160:163], v155 offset:2048
	ds_read_b128 v[164:167], v155 offset:3072
	v_add_u32_e32 v155, s79, v149
	ds_read_b128 v[168:171], v155
	ds_read_b128 v[172:175], v155 offset:1024
	ds_read_b128 v[176:179], v155 offset:2048
	ds_read_b128 v[182:185], v155 offset:3072
	s_add_u32 s50, s56, 0xb0000
	s_addc_u32 s51, s57, 0
	s_mov_b32 m0, s59
	v_lshl_add_u64 v[232:233], s[50:51], 0, v[128:129]
	ds_read_b128 v[186:189], v153 offset:32768
	ds_read_b128 v[190:193], v153 offset:33792
	ds_read_b128 v[194:197], v153 offset:34816
	ds_read_b128 v[198:201], v153 offset:35840
	ds_read_b128 v[208:211], v153 offset:36864
	ds_read_b128 v[212:215], v153 offset:37888
	ds_read_b128 v[216:219], v153 offset:38912
	ds_read_b128 v[220:223], v153 offset:39936
	global_load_lds_dwordx4 v[232:233], off
	v_lshl_add_u64 v[232:233], s[50:51], 0, v[132:133]
	s_mov_b32 m0, s60
	s_nop 0
	global_load_lds_dwordx4 v[232:233], off
	s_waitcnt vmcnt(8)
	s_waitcnt lgkmcnt(0)
	s_barrier
	s_setprio 1
	s_waitcnt lgkmcnt(0)
	v_mfma_f32_16x16x32_bf16 v[124:127], v[144:147], v[186:189], v[124:127]
	v_mfma_f32_16x16x32_bf16 v[120:123], v[160:163], v[186:189], v[120:123]
	v_mfma_f32_16x16x32_bf16 v[108:111], v[144:147], v[194:197], v[108:111]
	v_mfma_f32_16x16x32_bf16 v[104:107], v[160:163], v[194:197], v[104:107]
	v_mfma_f32_16x16x32_bf16 v[92:95], v[144:147], v[208:211], v[92:95]
	v_mfma_f32_16x16x32_bf16 v[88:91], v[160:163], v[208:211], v[88:91]
	v_mfma_f32_16x16x32_bf16 v[76:79], v[144:147], v[216:219], v[76:79]
	v_mfma_f32_16x16x32_bf16 v[72:75], v[160:163], v[216:219], v[72:75]
	v_mfma_f32_16x16x32_bf16 v[124:127], v[156:159], v[190:193], v[124:127]
	v_mfma_f32_16x16x32_bf16 v[120:123], v[164:167], v[190:193], v[120:123]
	v_mfma_f32_16x16x32_bf16 v[108:111], v[156:159], v[198:201], v[108:111]
	v_mfma_f32_16x16x32_bf16 v[104:107], v[164:167], v[198:201], v[104:107]
	v_mfma_f32_16x16x32_bf16 v[92:95], v[156:159], v[212:215], v[92:95]
	v_mfma_f32_16x16x32_bf16 v[88:91], v[164:167], v[212:215], v[88:91]
	v_mfma_f32_16x16x32_bf16 v[76:79], v[156:159], v[220:223], v[76:79]
	v_mfma_f32_16x16x32_bf16 v[72:75], v[164:167], v[220:223], v[72:75]
	s_setprio 0
	s_setprio 1
	v_mfma_f32_16x16x32_bf16 v[116:119], v[168:171], v[186:189], v[116:119]
	v_mfma_f32_16x16x32_bf16 v[112:115], v[176:179], v[186:189], v[112:115]
	v_mfma_f32_16x16x32_bf16 v[100:103], v[168:171], v[194:197], v[100:103]
	v_mfma_f32_16x16x32_bf16 v[96:99], v[176:179], v[194:197], v[96:99]
	v_mfma_f32_16x16x32_bf16 v[84:87], v[168:171], v[208:211], v[84:87]
	v_mfma_f32_16x16x32_bf16 v[80:83], v[176:179], v[208:211], v[80:83]
	v_mfma_f32_16x16x32_bf16 v[68:71], v[168:171], v[216:219], v[68:71]
	v_mfma_f32_16x16x32_bf16 v[64:67], v[176:179], v[216:219], v[64:67]
	v_mfma_f32_16x16x32_bf16 v[116:119], v[172:175], v[190:193], v[116:119]
	v_mfma_f32_16x16x32_bf16 v[112:115], v[182:185], v[190:193], v[112:115]
	v_mfma_f32_16x16x32_bf16 v[100:103], v[172:175], v[198:201], v[100:103]
	v_mfma_f32_16x16x32_bf16 v[96:99], v[182:185], v[198:201], v[96:99]
	v_mfma_f32_16x16x32_bf16 v[84:87], v[172:175], v[212:215], v[84:87]
	v_mfma_f32_16x16x32_bf16 v[80:83], v[182:185], v[212:215], v[80:83]
	v_mfma_f32_16x16x32_bf16 v[68:71], v[172:175], v[220:223], v[68:71]
	v_mfma_f32_16x16x32_bf16 v[64:67], v[182:185], v[220:223], v[64:67]
	s_setprio 0
	s_barrier
; #define PG8_STAGE(bufoff, gbase, voff) do { _Pragma("unroll") for (int _i = 0; _i < 2; ++_i) \
;         __builtin_amdgcn_global_load_lds((const unsigned*)((const char*)(gbase) + (voff)[_i]), (PG8_LAS unsigned*)(lds + (bufoff) + ldsw + _i * 8192), 16, 0, 0); } while (0)
; #define PG8_LDA(dst, b, h) do { _Pragma("unroll") for (int m = 0; m < 4; ++m) _Pragma("unroll") for (int k = 0; k < 2; ++k) dst[m][k] = *(const PG8_LAS bf16x8*)(lds + PG8_SA(b, h) + aoff + m * 2048 + k * 1024); } while (0)
; #define PG8_LDB(dst, b, h) do { _Pragma("unroll") for (int n = 0; n < 2; ++n) _Pragma("unroll") for (int k = 0; k < 2; ++k) dst[n][k] = *(const PG8_LAS bf16x8*)(lds + PG8_SB(b, h) + boff + n * 2048 + k * 1024); } while (0)
; #define PG8_MMA(ai, bj, At, Bt) do { __builtin_amdgcn_s_setprio(1); _Pragma("unroll") for (int m = 0; m < 4; ++m) _Pragma("unroll") for (int n = 0; n < 2; ++n) _Pragma("unroll") for (int k = 0; k < 2; ++k) \
;         acc[ai][bj][m][n] = __builtin_amdgcn_mfma_f32_16x16x32_bf16(Bt[n][k], At[m][k], acc[ai][bj][m][n], 0, 0, 0); __builtin_amdgcn_s_setprio(0); } while (0)
; #define PG8_WAIT_V(n) asm volatile("s_waitcnt vmcnt(" #n ")" ::: "memory")
; template <class Epi, class Sched, bool ALIGN_EPI = false, bool SP2 = false>
; __device__ __forceinline__ void gemm_phase(PG8_LAS unsigned char* lds, const Gemm g, const Sched& S, const Epi& E) {
;     ...
;             PG8_LDB(B0, 0, 0); PG8_LDB(B1, 0, 1); PG8_SCHED; PG8_LDA(At, 0, 0); PG8_STAGE(PG8_SA(1, 1), a1 + hstep, voffA);
;             PG8_WAIT_V(8); PG8_WAIT_L(0); PG8_BAR; PG8_MMA(0, 0, At, B0); PG8_MMA(0, 1, At, B1); PG8_BAR; PG8_SCHED;
;             PG8_LDA(At, 0, 1); PG8_STAGE(PG8_SB(0, 0), b2, voffB); PG8_STAGE(PG8_SB(0, 1), b2 + hstep, voffB); PG8_STAGE(PG8_SA(0, 0), a2, voffA);
;             PG8_WAIT_V(8); PG8_WAIT_L(0); PG8_BAR; PG8_MMA(1, 0, At, B0); PG8_MMA(1, 1, At, B1); PG8_BAR; PG8_SCHED;
;             PG8_LDB(B0, 1, 0); PG8_LDB(B1, 1, 1); PG8_SCHED; PG8_LDA(At, 1, 0); PG8_STAGE(PG8_SA(0, 1), a2 + hstep, voffA);
;             PG8_WAIT_V(8); PG8_WAIT_L(0); PG8_BAR; PG8_MMA(0, 0, At, B0); PG8_MMA(0, 1, At, B1); PG8_BAR; PG8_SCHED;
;             PG8_LDA(At, 1, 1); PG8_STAGE(PG8_SB(1, 0), b3, voffB); PG8_STAGE(PG8_SB(1, 1), b3 + hstep, voffB); PG8_STAGE(PG8_SA(1, 0), a3, voffA);
;             PG8_WAIT_V(8); PG8_WAIT_L(0); PG8_BAR; PG8_MMA(1, 0, At, B0); PG8_MMA(1, 1, At, B1); PG8_BAR; PG8_SCHED;
	s_add_i32 s50, s78, s33
	v_lshl_add_u64 v[224:225], v[224:225], 0, s[42:43]
	s_mov_b32 m0, s50
	ds_read_b128 v[186:189], v153 offset:49152
	ds_read_b128 v[190:193], v153 offset:50176
	ds_read_b128 v[194:197], v153 offset:51200
	ds_read_b128 v[198:201], v153 offset:52224
	ds_read_b128 v[208:211], v153 offset:53248
	ds_read_b128 v[212:215], v153 offset:54272
	ds_read_b128 v[216:219], v153 offset:55296
	ds_read_b128 v[220:223], v153 offset:56320
	global_load_lds_dwordx4 v[224:225], off
	s_add_i32 m0, s50, 0x2000
	s_add_u32 s50, s54, 0xb0080
	v_lshl_add_u64 v[224:225], v[226:227], 0, s[42:43]
	s_addc_u32 s51, s55, 0
	s_add_i32 s54, s79, s33
	global_load_lds_dwordx4 v[224:225], off
	v_lshl_add_u64 v[224:225], s[50:51], 0, v[130:131]
	s_mov_b32 m0, s54
	s_nop 0
	global_load_lds_dwordx4 v[224:225], off
	v_lshl_add_u64 v[224:225], s[50:51], 0, v[134:135]
	s_add_i32 m0, s54, 0x2000
	s_nop 0
	global_load_lds_dwordx4 v[224:225], off
	s_waitcnt vmcnt(6)
	s_waitcnt lgkmcnt(0)
	s_barrier
	s_setprio 1
	s_waitcnt lgkmcnt(0)
	v_mfma_f32_16x16x32_bf16 v[60:63], v[144:147], v[186:189], v[60:63]
	v_mfma_f32_16x16x32_bf16 v[56:59], v[160:163], v[186:189], v[56:59]
	v_mfma_f32_16x16x32_bf16 v[44:47], v[144:147], v[194:197], v[44:47]
	v_mfma_f32_16x16x32_bf16 v[40:43], v[160:163], v[194:197], v[40:43]
	v_mfma_f32_16x16x32_bf16 v[28:31], v[144:147], v[208:211], v[28:31]
	v_mfma_f32_16x16x32_bf16 v[24:27], v[160:163], v[208:211], v[24:27]
	v_lshl_add_u64 v[224:225], v[228:229], 0, s[42:43]
	s_mov_b32 m0, s62
	s_nop 0
	global_load_lds_dwordx4 v[224:225], off
	v_mfma_f32_16x16x32_bf16 v[12:15], v[144:147], v[216:219], v[12:15]
	v_mfma_f32_16x16x32_bf16 v[8:11], v[160:163], v[216:219], v[8:11]
	v_mfma_f32_16x16x32_bf16 v[60:63], v[156:159], v[190:193], v[60:63]
	v_mfma_f32_16x16x32_bf16 v[56:59], v[164:167], v[190:193], v[56:59]
	v_mfma_f32_16x16x32_bf16 v[44:47], v[156:159], v[198:201], v[44:47]
	v_mfma_f32_16x16x32_bf16 v[40:43], v[164:167], v[198:201], v[40:43]
	v_mfma_f32_16x16x32_bf16 v[28:31], v[156:159], v[212:215], v[28:31]
	v_mfma_f32_16x16x32_bf16 v[24:27], v[164:167], v[212:215], v[24:27]
	v_mfma_f32_16x16x32_bf16 v[12:15], v[156:159], v[220:223], v[12:15]
	v_mfma_f32_16x16x32_bf16 v[8:11], v[164:167], v[220:223], v[8:11]
	s_setprio 0
	s_setprio 1
	v_mfma_f32_16x16x32_bf16 v[52:55], v[168:171], v[186:189], v[52:55]
	v_mfma_f32_16x16x32_bf16 v[48:51], v[176:179], v[186:189], v[48:51]
	v_lshl_add_u64 v[224:225], v[230:231], 0, s[42:43]
	s_mov_b32 m0, s63
	s_nop 0
	global_load_lds_dwordx4 v[224:225], off
	v_mfma_f32_16x16x32_bf16 v[36:39], v[168:171], v[194:197], v[36:39]
	v_mfma_f32_16x16x32_bf16 v[32:35], v[176:179], v[194:197], v[32:35]
	v_mfma_f32_16x16x32_bf16 v[20:23], v[168:171], v[208:211], v[20:23]
	v_mfma_f32_16x16x32_bf16 v[16:19], v[176:179], v[208:211], v[16:19]
	v_mfma_f32_16x16x32_bf16 v[4:7], v[168:171], v[216:219], v[4:7]
	v_mfma_f32_16x16x32_bf16 v[0:3], v[176:179], v[216:219], v[0:3]
	v_mfma_f32_16x16x32_bf16 v[52:55], v[172:175], v[190:193], v[52:55]
	v_mfma_f32_16x16x32_bf16 v[48:51], v[182:185], v[190:193], v[48:51]
	v_mfma_f32_16x16x32_bf16 v[36:39], v[172:175], v[198:201], v[36:39]
	v_mfma_f32_16x16x32_bf16 v[32:35], v[182:185], v[198:201], v[32:35]
	v_mfma_f32_16x16x32_bf16 v[20:23], v[172:175], v[212:215], v[20:23]
	v_mfma_f32_16x16x32_bf16 v[16:19], v[182:185], v[212:215], v[16:19]
	v_mfma_f32_16x16x32_bf16 v[4:7], v[172:175], v[220:223], v[4:7]
	v_mfma_f32_16x16x32_bf16 v[0:3], v[182:185], v[220:223], v[0:3]
	s_setprio 0
	s_barrier
	s_add_i32 s84, s84, 2
	s_add_u32 s82, s82, 0x100
	s_addc_u32 s83, s83, 0
	s_mov_b64 s[50:51], s[52:53]
.LBB0_1197:
	ds_read_b128 v[144:147], v151
	ds_read_b128 v[156:159], v151 offset:1024
	ds_read_b128 v[160:163], v151 offset:2048
	ds_read_b128 v[164:167], v151 offset:3072
	ds_read_b128 v[168:171], v152
	ds_read_b128 v[172:175], v152 offset:1024
	ds_read_b128 v[176:179], v152 offset:2048
	ds_read_b128 v[182:185], v152 offset:3072
	s_add_u32 s52, s50, 0x100
	s_addc_u32 s53, s51, 0
	s_cmp_eq_u32 s84, 40
	s_cselect_b32 s57, s1, s53
	s_cselect_b32 s56, s0, s52
	s_cselect_b32 s55, s49, s83
	s_cselect_b32 s54, s48, s82
	v_lshl_add_u64 v[224:225], s[50:51], 0, v[136:137]
	s_add_i32 m0, s34, 0xc000
	ds_read_b128 v[186:189], v153
	ds_read_b128 v[190:193], v153 offset:1024
	ds_read_b128 v[194:197], v153 offset:2048
	ds_read_b128 v[198:201], v153 offset:3072
	ds_read_b128 v[208:211], v153 offset:4096
	ds_read_b128 v[212:215], v153 offset:5120
	ds_read_b128 v[216:219], v153 offset:6144
	ds_read_b128 v[220:223], v153 offset:7168
	global_load_lds_dwordx4 v[224:225], off
	v_lshl_add_u64 v[224:225], s[50:51], 0, v[138:139]
	s_add_i32 m0, s34, 0xe000
	s_nop 0
	global_load_lds_dwordx4 v[224:225], off
	s_waitcnt vmcnt(8)
	s_waitcnt lgkmcnt(0)
	s_barrier
; #define PG8_STAGE(bufoff, gbase, voff) do { _Pragma("unroll") for (int _i = 0; _i < 2; ++_i) \
;         __builtin_amdgcn_global_load_lds((const unsigned*)((const char*)(gbase) + (voff)[_i]), (PG8_LAS unsigned*)(lds + (bufoff) + ldsw + _i * 8192), 16, 0, 0); } while (0)
; #define PG8_LDA(dst, b, h) do { _Pragma("unroll") for (int m = 0; m < 4; ++m) _Pragma("unroll") for (int k = 0; k < 2; ++k) dst[m][k] = *(const PG8_LAS bf16x8*)(lds + PG8_SA(b, h) + aoff + m * 2048 + k * 1024); } while (0)
; #define PG8_MMA(ai, bj, At, Bt) do { __builtin_amdgcn_s_setprio(1); _Pragma("unroll") for (int m = 0; m < 4; ++m) _Pragma("unroll") for (int n = 0; n < 2; ++n) _Pragma("unroll") for (int k = 0; k < 2; ++k) \
;         acc[ai][bj][m][n] = __builtin_amdgcn_mfma_f32_16x16x32_bf16(Bt[n][k], At[m][k], acc[ai][bj][m][n], 0, 0, 0); __builtin_amdgcn_s_setprio(0); } while (0)
; #define PG8_WAIT_V(n) asm volatile("s_waitcnt vmcnt(" #n ")" ::: "memory")
; #define PG8_WAIT_L(n) asm volatile("s_waitcnt lgkmcnt(" #n ")" ::: "memory")
; #define PG8_BAR __builtin_amdgcn_s_barrier()
; #define PG8_SCHED __builtin_amdgcn_sched_barrier(0)
; template <class Epi, class Sched, bool ALIGN_EPI = false, bool SP2 = false>
; __device__ __forceinline__ void gemm_phase(PG8_LAS unsigned char* lds, const Gemm g, const Sched& S, const Epi& E) {
;     ...
;             PG8_WAIT_V(8); PG8_WAIT_L(0); PG8_BAR; PG8_MMA(0, 0, At, B0); PG8_MMA(0, 1, At, B1); PG8_BAR; PG8_SCHED;
;             PG8_LDA(At, 0, 1); PG8_STAGE(PG8_SB(0, 0), b2, voffB); PG8_STAGE(PG8_SB(0, 1), b2 + hstep, voffB); PG8_STAGE(PG8_SA(0, 0), a2, voffA);
;             PG8_WAIT_V(8); PG8_WAIT_L(0); PG8_BAR; PG8_MMA(1, 0, At, B0); PG8_MMA(1, 1, At, B1); PG8_BAR; PG8_SCHED;
	s_setprio 1
	s_waitcnt lgkmcnt(0)
	v_mfma_f32_16x16x32_bf16 v[124:127], v[144:147], v[186:189], v[124:127]
	v_mfma_f32_16x16x32_bf16 v[120:123], v[160:163], v[186:189], v[120:123]
	v_mfma_f32_16x16x32_bf16 v[108:111], v[144:147], v[194:197], v[108:111]
	v_mfma_f32_16x16x32_bf16 v[104:107], v[160:163], v[194:197], v[104:107]
	v_mfma_f32_16x16x32_bf16 v[92:95], v[144:147], v[208:211], v[92:95]
	v_mfma_f32_16x16x32_bf16 v[88:91], v[160:163], v[208:211], v[88:91]
	v_mfma_f32_16x16x32_bf16 v[76:79], v[144:147], v[216:219], v[76:79]
	v_mfma_f32_16x16x32_bf16 v[72:75], v[160:163], v[216:219], v[72:75]
	v_mfma_f32_16x16x32_bf16 v[124:127], v[156:159], v[190:193], v[124:127]
	v_mfma_f32_16x16x32_bf16 v[120:123], v[164:167], v[190:193], v[120:123]
	v_mfma_f32_16x16x32_bf16 v[108:111], v[156:159], v[198:201], v[108:111]
	v_mfma_f32_16x16x32_bf16 v[104:107], v[164:167], v[198:201], v[104:107]
	v_mfma_f32_16x16x32_bf16 v[92:95], v[156:159], v[212:215], v[92:95]
	v_mfma_f32_16x16x32_bf16 v[88:91], v[164:167], v[212:215], v[88:91]
	v_mfma_f32_16x16x32_bf16 v[76:79], v[156:159], v[220:223], v[76:79]
	v_mfma_f32_16x16x32_bf16 v[72:75], v[164:167], v[220:223], v[72:75]
	s_setprio 0
	s_setprio 1
	v_mfma_f32_16x16x32_bf16 v[116:119], v[168:171], v[186:189], v[116:119]
	v_mfma_f32_16x16x32_bf16 v[112:115], v[176:179], v[186:189], v[112:115]
	v_mfma_f32_16x16x32_bf16 v[100:103], v[168:171], v[194:197], v[100:103]
	v_mfma_f32_16x16x32_bf16 v[96:99], v[176:179], v[194:197], v[96:99]
	v_mfma_f32_16x16x32_bf16 v[84:87], v[168:171], v[208:211], v[84:87]
	v_mfma_f32_16x16x32_bf16 v[80:83], v[176:179], v[208:211], v[80:83]
	v_mfma_f32_16x16x32_bf16 v[68:71], v[168:171], v[216:219], v[68:71]
	v_mfma_f32_16x16x32_bf16 v[64:67], v[176:179], v[216:219], v[64:67]
	v_mfma_f32_16x16x32_bf16 v[116:119], v[172:175], v[190:193], v[116:119]
	v_mfma_f32_16x16x32_bf16 v[112:115], v[182:185], v[190:193], v[112:115]
	v_mfma_f32_16x16x32_bf16 v[100:103], v[172:175], v[198:201], v[100:103]
	v_mfma_f32_16x16x32_bf16 v[96:99], v[182:185], v[198:201], v[96:99]
	v_mfma_f32_16x16x32_bf16 v[84:87], v[172:175], v[212:215], v[84:87]
	v_mfma_f32_16x16x32_bf16 v[80:83], v[182:185], v[212:215], v[80:83]
	v_mfma_f32_16x16x32_bf16 v[68:71], v[172:175], v[220:223], v[68:71]
	v_mfma_f32_16x16x32_bf16 v[64:67], v[182:185], v[220:223], v[64:67]
	s_setprio 0
	s_barrier
	s_add_i32 s50, s64, s33
	v_lshl_add_u64 v[224:225], s[54:55], 0, v[130:131]
	s_mov_b32 m0, s50
	ds_read_b128 v[186:189], v153 offset:16384
	ds_read_b128 v[190:193], v153 offset:17408
	ds_read_b128 v[194:197], v153 offset:18432
	ds_read_b128 v[198:201], v153 offset:19456
	ds_read_b128 v[208:211], v153 offset:20480
	ds_read_b128 v[212:215], v153 offset:21504
	ds_read_b128 v[216:219], v153 offset:22528
	ds_read_b128 v[220:223], v153 offset:23552
	global_load_lds_dwordx4 v[224:225], off
	s_add_i32 m0, s50, 0x2000
	s_add_u32 s50, s54, 0xb0000
	v_lshl_add_u64 v[226:227], s[54:55], 0, v[134:135]
	s_addc_u32 s51, s55, 0
	s_add_i32 s78, s65, s33
	global_load_lds_dwordx4 v[226:227], off
	v_lshl_add_u64 v[228:229], s[50:51], 0, v[130:131]
	s_mov_b32 m0, s78
	v_lshl_add_u64 v[230:231], s[56:57], 0, v[132:133]
	global_load_lds_dwordx4 v[228:229], off
	v_lshl_add_u64 v[228:229], s[50:51], 0, v[134:135]
	s_add_i32 m0, s78, 0x2000
	s_nop 0
	global_load_lds_dwordx4 v[228:229], off
	s_waitcnt vmcnt(6)
	s_waitcnt lgkmcnt(0)
	s_barrier
	s_setprio 1
	s_waitcnt lgkmcnt(0)
	v_mfma_f32_16x16x32_bf16 v[60:63], v[144:147], v[186:189], v[60:63]
	v_mfma_f32_16x16x32_bf16 v[56:59], v[160:163], v[186:189], v[56:59]
	v_mfma_f32_16x16x32_bf16 v[44:47], v[144:147], v[194:197], v[44:47]
	v_mfma_f32_16x16x32_bf16 v[40:43], v[160:163], v[194:197], v[40:43]
	v_mfma_f32_16x16x32_bf16 v[28:31], v[144:147], v[208:211], v[28:31]
	v_mfma_f32_16x16x32_bf16 v[24:27], v[160:163], v[208:211], v[24:27]
	v_lshl_add_u64 v[228:229], s[56:57], 0, v[128:129]
	s_mov_b32 m0, s34
	s_nop 0
	global_load_lds_dwordx4 v[228:229], off
	v_mfma_f32_16x16x32_bf16 v[12:15], v[144:147], v[216:219], v[12:15]
	v_mfma_f32_16x16x32_bf16 v[8:11], v[160:163], v[216:219], v[8:11]
	v_mfma_f32_16x16x32_bf16 v[60:63], v[156:159], v[190:193], v[60:63]
	v_mfma_f32_16x16x32_bf16 v[56:59], v[164:167], v[190:193], v[56:59]
	v_mfma_f32_16x16x32_bf16 v[44:47], v[156:159], v[198:201], v[44:47]
	v_mfma_f32_16x16x32_bf16 v[40:43], v[164:167], v[198:201], v[40:43]
	v_mfma_f32_16x16x32_bf16 v[28:31], v[156:159], v[212:215], v[28:31]
	v_mfma_f32_16x16x32_bf16 v[24:27], v[164:167], v[212:215], v[24:27]
	v_mfma_f32_16x16x32_bf16 v[12:15], v[156:159], v[220:223], v[12:15]
	v_mfma_f32_16x16x32_bf16 v[8:11], v[164:167], v[220:223], v[8:11]
	s_setprio 0
	s_setprio 1
	v_mfma_f32_16x16x32_bf16 v[52:55], v[168:171], v[186:189], v[52:55]
	v_mfma_f32_16x16x32_bf16 v[48:51], v[176:179], v[186:189], v[48:51]
	s_mov_b32 m0, s58
	s_nop 0
	global_load_lds_dwordx4 v[230:231], off
	v_mfma_f32_16x16x32_bf16 v[36:39], v[168:171], v[194:197], v[36:39]
	v_mfma_f32_16x16x32_bf16 v[32:35], v[176:179], v[194:197], v[32:35]
	v_mfma_f32_16x16x32_bf16 v[20:23], v[168:171], v[208:211], v[20:23]
	v_mfma_f32_16x16x32_bf16 v[16:19], v[176:179], v[208:211], v[16:19]
	v_mfma_f32_16x16x32_bf16 v[4:7], v[168:171], v[216:219], v[4:7]
	v_mfma_f32_16x16x32_bf16 v[0:3], v[176:179], v[216:219], v[0:3]
	v_mfma_f32_16x16x32_bf16 v[52:55], v[172:175], v[190:193], v[52:55]
	v_mfma_f32_16x16x32_bf16 v[48:51], v[182:185], v[190:193], v[48:51]
	v_mfma_f32_16x16x32_bf16 v[36:39], v[172:175], v[198:201], v[36:39]
	v_mfma_f32_16x16x32_bf16 v[32:35], v[182:185], v[198:201], v[32:35]
	v_mfma_f32_16x16x32_bf16 v[20:23], v[172:175], v[212:215], v[20:23]
	v_mfma_f32_16x16x32_bf16 v[16:19], v[182:185], v[212:215], v[16:19]
	v_mfma_f32_16x16x32_bf16 v[4:7], v[172:175], v[220:223], v[4:7]
	v_mfma_f32_16x16x32_bf16 v[0:3], v[182:185], v[220:223], v[0:3]
	s_setprio 0
	s_barrier
; #define PG8_STAGE(bufoff, gbase, voff) do { _Pragma("unroll") for (int _i = 0; _i < 2; ++_i) \
;         __builtin_amdgcn_global_load_lds((const unsigned*)((const char*)(gbase) + (voff)[_i]), (PG8_LAS unsigned*)(lds + (bufoff) + ldsw + _i * 8192), 16, 0, 0); } while (0)
; #define PG8_LDA(dst, b, h) do { _Pragma("unroll") for (int m = 0; m < 4; ++m) _Pragma("unroll") for (int k = 0; k < 2; ++k) dst[m][k] = *(const PG8_LAS bf16x8*)(lds + PG8_SA(b, h) + aoff + m * 2048 + k * 1024); } while (0)
; #define PG8_LDB(dst, b, h) do { _Pragma("unroll") for (int n = 0; n < 2; ++n) _Pragma("unroll") for (int k = 0; k < 2; ++k) dst[n][k] = *(const PG8_LAS bf16x8*)(lds + PG8_SB(b, h) + boff + n * 2048 + k * 1024); } while (0)
; #define PG8_MMA(ai, bj, At, Bt) do { __builtin_amdgcn_s_setprio(1); _Pragma("unroll") for (int m = 0; m < 4; ++m) _Pragma("unroll") for (int n = 0; n < 2; ++n) _Pragma("unroll") for (int k = 0; k < 2; ++k) \
;         acc[ai][bj][m][n] = __builtin_amdgcn_mfma_f32_16x16x32_bf16(Bt[n][k], At[m][k], acc[ai][bj][m][n], 0, 0, 0); __builtin_amdgcn_s_setprio(0); } while (0)
; #define PG8_WAIT_V(n) asm volatile("s_waitcnt vmcnt(" #n ")" ::: "memory")
; #define PG8_WAIT_L(n) asm volatile("s_waitcnt lgkmcnt(" #n ")" ::: "memory")
; #define PG8_BAR __builtin_amdgcn_s_barrier()
; #define PG8_SCHED __builtin_amdgcn_sched_barrier(0)
; template <class Epi, class Sched, bool ALIGN_EPI = false, bool SP2 = false>
; __device__ __forceinline__ void gemm_phase(PG8_LAS unsigned char* lds, const Gemm g, const Sched& S, const Epi& E) {
;     ...
;             PG8_LDB(B0, 1, 0); PG8_LDB(B1, 1, 1); PG8_SCHED; PG8_LDA(At, 1, 0); PG8_STAGE(PG8_SA(0, 1), a2 + hstep, voffA);
;             PG8_WAIT_V(8); PG8_WAIT_L(0); PG8_BAR; PG8_MMA(0, 0, At, B0); PG8_MMA(0, 1, At, B1); PG8_BAR; PG8_SCHED;
	s_add_i32 s78, 0, 0x18000
	v_add_u32_e32 v155, s78, v149
	s_add_i32 s79, 0, 0x1c000
	ds_read_b128 v[144:147], v155
	ds_read_b128 v[156:159], v155 offset:1024
	ds_read_b128 v[160:163], v155 offset:2048
	ds_read_b128 v[164:167], v155 offset:3072
	v_add_u32_e32 v155, s79, v149
	ds_read_b128 v[168:171], v155
	ds_read_b128 v[172:175], v155 offset:1024
	ds_read_b128 v[176:179], v155 offset:2048
	ds_read_b128 v[182:185], v155 offset:3072
	s_add_u32 s50, s56, 0xb0000
	s_addc_u32 s51, s57, 0
	s_mov_b32 m0, s59
	v_lshl_add_u64 v[232:233], s[50:51], 0, v[128:129]
	ds_read_b128 v[186:189], v153 offset:32768
	ds_read_b128 v[190:193], v153 offset:33792
	ds_read_b128 v[194:197], v153 offset:34816
	ds_read_b128 v[198:201], v153 offset:35840
	ds_read_b128 v[208:211], v153 offset:36864
	ds_read_b128 v[212:215], v153 offset:37888
	ds_read_b128 v[216:219], v153 offset:38912
	ds_read_b128 v[220:223], v153 offset:39936
	global_load_lds_dwordx4 v[232:233], off
	v_lshl_add_u64 v[232:233], s[50:51], 0, v[132:133]
	s_mov_b32 m0, s60
	s_nop 0
	global_load_lds_dwordx4 v[232:233], off
	s_waitcnt vmcnt(8)
	s_waitcnt lgkmcnt(0)
	s_barrier
	s_setprio 1
	s_waitcnt lgkmcnt(0)
	v_mfma_f32_16x16x32_bf16 v[124:127], v[144:147], v[186:189], v[124:127]
	v_mfma_f32_16x16x32_bf16 v[120:123], v[160:163], v[186:189], v[120:123]
	v_mfma_f32_16x16x32_bf16 v[108:111], v[144:147], v[194:197], v[108:111]
	v_mfma_f32_16x16x32_bf16 v[104:107], v[160:163], v[194:197], v[104:107]
	v_mfma_f32_16x16x32_bf16 v[92:95], v[144:147], v[208:211], v[92:95]
	v_mfma_f32_16x16x32_bf16 v[88:91], v[160:163], v[208:211], v[88:91]
	v_mfma_f32_16x16x32_bf16 v[76:79], v[144:147], v[216:219], v[76:79]
	v_mfma_f32_16x16x32_bf16 v[72:75], v[160:163], v[216:219], v[72:75]
	v_mfma_f32_16x16x32_bf16 v[124:127], v[156:159], v[190:193], v[124:127]
	v_mfma_f32_16x16x32_bf16 v[120:123], v[164:167], v[190:193], v[120:123]
	v_mfma_f32_16x16x32_bf16 v[108:111], v[156:159], v[198:201], v[108:111]
	v_mfma_f32_16x16x32_bf16 v[104:107], v[164:167], v[198:201], v[104:107]
	v_mfma_f32_16x16x32_bf16 v[92:95], v[156:159], v[212:215], v[92:95]
	v_mfma_f32_16x16x32_bf16 v[88:91], v[164:167], v[212:215], v[88:91]
	v_mfma_f32_16x16x32_bf16 v[76:79], v[156:159], v[220:223], v[76:79]
	v_mfma_f32_16x16x32_bf16 v[72:75], v[164:167], v[220:223], v[72:75]
	s_setprio 0
	s_setprio 1
	v_mfma_f32_16x16x32_bf16 v[116:119], v[168:171], v[186:189], v[116:119]
	v_mfma_f32_16x16x32_bf16 v[112:115], v[176:179], v[186:189], v[112:115]
	v_mfma_f32_16x16x32_bf16 v[100:103], v[168:171], v[194:197], v[100:103]
	v_mfma_f32_16x16x32_bf16 v[96:99], v[176:179], v[194:197], v[96:99]
	v_mfma_f32_16x16x32_bf16 v[84:87], v[168:171], v[208:211], v[84:87]
	v_mfma_f32_16x16x32_bf16 v[80:83], v[176:179], v[208:211], v[80:83]
	v_mfma_f32_16x16x32_bf16 v[68:71], v[168:171], v[216:219], v[68:71]
	v_mfma_f32_16x16x32_bf16 v[64:67], v[176:179], v[216:219], v[64:67]
	v_mfma_f32_16x16x32_bf16 v[116:119], v[172:175], v[190:193], v[116:119]
	v_mfma_f32_16x16x32_bf16 v[112:115], v[182:185], v[190:193], v[112:115]
	v_mfma_f32_16x16x32_bf16 v[100:103], v[172:175], v[198:201], v[100:103]
	v_mfma_f32_16x16x32_bf16 v[96:99], v[182:185], v[198:201], v[96:99]
	v_mfma_f32_16x16x32_bf16 v[84:87], v[172:175], v[212:215], v[84:87]
	v_mfma_f32_16x16x32_bf16 v[80:83], v[182:185], v[212:215], v[80:83]
	v_mfma_f32_16x16x32_bf16 v[68:71], v[172:175], v[220:223], v[68:71]
	v_mfma_f32_16x16x32_bf16 v[64:67], v[182:185], v[220:223], v[64:67]
	s_setprio 0
	s_barrier
; #define PG8_STAGE(bufoff, gbase, voff) do { _Pragma("unroll") for (int _i = 0; _i < 2; ++_i) \
;         __builtin_amdgcn_global_load_lds((const unsigned*)((const char*)(gbase) + (voff)[_i]), (PG8_LAS unsigned*)(lds + (bufoff) + ldsw + _i * 8192), 16, 0, 0); } while (0)
; #define PG8_LDA(dst, b, h) do { _Pragma("unroll") for (int m = 0; m < 4; ++m) _Pragma("unroll") for (int k = 0; k < 2; ++k) dst[m][k] = *(const PG8_LAS bf16x8*)(lds + PG8_SA(b, h) + aoff + m * 2048 + k * 1024); } while (0)
; #define PG8_MMA(ai, bj, At, Bt) do { __builtin_amdgcn_s_setprio(1); _Pragma("unroll") for (int m = 0; m < 4; ++m) _Pragma("unroll") for (int n = 0; n < 2; ++n) _Pragma("unroll") for (int k = 0; k < 2; ++k) \
;         acc[ai][bj][m][n] = __builtin_amdgcn_mfma_f32_16x16x32_bf16(Bt[n][k], At[m][k], acc[ai][bj][m][n], 0, 0, 0); __builtin_amdgcn_s_setprio(0); } while (0)
; #define PG8_WAIT_V(n) asm volatile("s_waitcnt vmcnt(" #n ")" ::: "memory")
; #define PG8_WAIT_L(n) asm volatile("s_waitcnt lgkmcnt(" #n ")" ::: "memory")
; #define PG8_BAR __builtin_amdgcn_s_barrier()
; #define PG8_SCHED __builtin_amdgcn_sched_barrier(0)
; template <class Epi, class Sched, bool ALIGN_EPI = false, bool SP2 = false>
; __device__ __forceinline__ void gemm_phase(PG8_LAS unsigned char* lds, const Gemm g, const Sched& S, const Epi& E) {
;     ...
;             PG8_LDA(At, 1, 1); PG8_STAGE(PG8_SB(1, 0), b3, voffB); PG8_STAGE(PG8_SB(1, 1), b3 + hstep, voffB); PG8_STAGE(PG8_SA(1, 0), a3, voffA);
;             PG8_WAIT_V(8); PG8_WAIT_L(0); PG8_BAR; PG8_MMA(1, 0, At, B0); PG8_MMA(1, 1, At, B1); PG8_BAR; PG8_SCHED;
;     ...
;         if constexpr (ALIGN_EPI) { if (wr == 0) PG8_BAR; }
	s_add_i32 s50, s78, s33
	v_lshl_add_u64 v[224:225], v[224:225], 0, s[42:43]
	s_mov_b32 m0, s50
	ds_read_b128 v[186:189], v153 offset:49152
	ds_read_b128 v[190:193], v153 offset:50176
	ds_read_b128 v[194:197], v153 offset:51200
	ds_read_b128 v[198:201], v153 offset:52224
	ds_read_b128 v[208:211], v153 offset:53248
	ds_read_b128 v[212:215], v153 offset:54272
	ds_read_b128 v[216:219], v153 offset:55296
	ds_read_b128 v[220:223], v153 offset:56320
	global_load_lds_dwordx4 v[224:225], off
	s_add_i32 m0, s50, 0x2000
	s_add_u32 s50, s54, 0xb0080
	v_lshl_add_u64 v[224:225], v[226:227], 0, s[42:43]
	s_addc_u32 s51, s55, 0
	s_add_i32 s54, s79, s33
	global_load_lds_dwordx4 v[224:225], off
	v_lshl_add_u64 v[224:225], s[50:51], 0, v[130:131]
	s_mov_b32 m0, s54
	s_nop 0
	global_load_lds_dwordx4 v[224:225], off
	v_lshl_add_u64 v[224:225], s[50:51], 0, v[134:135]
	s_add_i32 m0, s54, 0x2000
	s_nop 0
	global_load_lds_dwordx4 v[224:225], off
	s_waitcnt vmcnt(6)
	s_waitcnt lgkmcnt(0)
	s_barrier
	s_setprio 1
	s_waitcnt lgkmcnt(0)
	v_mfma_f32_16x16x32_bf16 v[60:63], v[144:147], v[186:189], v[60:63]
	v_mfma_f32_16x16x32_bf16 v[56:59], v[160:163], v[186:189], v[56:59]
	v_mfma_f32_16x16x32_bf16 v[44:47], v[144:147], v[194:197], v[44:47]
	v_mfma_f32_16x16x32_bf16 v[40:43], v[160:163], v[194:197], v[40:43]
	v_mfma_f32_16x16x32_bf16 v[28:31], v[144:147], v[208:211], v[28:31]
	v_mfma_f32_16x16x32_bf16 v[24:27], v[160:163], v[208:211], v[24:27]
	v_lshl_add_u64 v[224:225], v[228:229], 0, s[42:43]
	s_mov_b32 m0, s62
	s_nop 0
	global_load_lds_dwordx4 v[224:225], off
	v_mfma_f32_16x16x32_bf16 v[12:15], v[144:147], v[216:219], v[12:15]
	v_mfma_f32_16x16x32_bf16 v[8:11], v[160:163], v[216:219], v[8:11]
	v_mfma_f32_16x16x32_bf16 v[60:63], v[156:159], v[190:193], v[60:63]
	v_mfma_f32_16x16x32_bf16 v[56:59], v[164:167], v[190:193], v[56:59]
	v_mfma_f32_16x16x32_bf16 v[44:47], v[156:159], v[198:201], v[44:47]
	v_mfma_f32_16x16x32_bf16 v[40:43], v[164:167], v[198:201], v[40:43]
	v_mfma_f32_16x16x32_bf16 v[28:31], v[156:159], v[212:215], v[28:31]
	v_mfma_f32_16x16x32_bf16 v[24:27], v[164:167], v[212:215], v[24:27]
	v_mfma_f32_16x16x32_bf16 v[12:15], v[156:159], v[220:223], v[12:15]
	v_mfma_f32_16x16x32_bf16 v[8:11], v[164:167], v[220:223], v[8:11]
	s_setprio 0
	s_setprio 1
	v_mfma_f32_16x16x32_bf16 v[52:55], v[168:171], v[186:189], v[52:55]
	v_mfma_f32_16x16x32_bf16 v[48:51], v[176:179], v[186:189], v[48:51]
	v_lshl_add_u64 v[224:225], v[230:231], 0, s[42:43]
	s_mov_b32 m0, s63
	s_nop 0
	global_load_lds_dwordx4 v[224:225], off
	v_mfma_f32_16x16x32_bf16 v[36:39], v[168:171], v[194:197], v[36:39]
	v_mfma_f32_16x16x32_bf16 v[32:35], v[176:179], v[194:197], v[32:35]
	v_mfma_f32_16x16x32_bf16 v[20:23], v[168:171], v[208:211], v[20:23]
	v_mfma_f32_16x16x32_bf16 v[16:19], v[176:179], v[208:211], v[16:19]
	v_mfma_f32_16x16x32_bf16 v[4:7], v[168:171], v[216:219], v[4:7]
	v_mfma_f32_16x16x32_bf16 v[0:3], v[176:179], v[216:219], v[0:3]
	v_mfma_f32_16x16x32_bf16 v[52:55], v[172:175], v[190:193], v[52:55]
	v_mfma_f32_16x16x32_bf16 v[48:51], v[182:185], v[190:193], v[48:51]
	v_mfma_f32_16x16x32_bf16 v[36:39], v[172:175], v[198:201], v[36:39]
	v_mfma_f32_16x16x32_bf16 v[32:35], v[182:185], v[198:201], v[32:35]
	v_mfma_f32_16x16x32_bf16 v[20:23], v[172:175], v[212:215], v[20:23]
	v_mfma_f32_16x16x32_bf16 v[16:19], v[182:185], v[212:215], v[16:19]
	v_mfma_f32_16x16x32_bf16 v[4:7], v[172:175], v[220:223], v[4:7]
	v_mfma_f32_16x16x32_bf16 v[0:3], v[182:185], v[220:223], v[0:3]
	s_setprio 0
	s_barrier
	s_add_i32 s84, s84, 2
	s_add_u32 s82, s82, 0x100
	s_addc_u32 s83, s83, 0
	s_cmp_gt_u32 s84, 41
	s_mov_b64 s[50:51], s[52:53]
	s_cbranch_scc0 .LBB0_1197
	s_and_b64 vcc, exec, s[44:45]
	s_cbranch_vccz .LBB0_1200
	s_barrier

; #define PG8_STAGE(bufoff, gbase, voff) do { _Pragma("unroll") for (int _i = 0; _i < 2; ++_i) \
;         __builtin_amdgcn_global_load_lds((const unsigned*)((const char*)(gbase) + (voff)[_i]), (PG8_LAS unsigned*)(lds + (bufoff) + ldsw + _i * 8192), 16, 0, 0); } while (0)
; #define PG8_LDA(dst, b, h) do { _Pragma("unroll") for (int m = 0; m < 4; ++m) _Pragma("unroll") for (int k = 0; k < 2; ++k) dst[m][k] = *(const PG8_LAS bf16x8*)(lds + PG8_SA(b, h) + aoff + m * 2048 + k * 1024); } while (0)
; #define PG8_LDB(dst, b, h) do { _Pragma("unroll") for (int n = 0; n < 2; ++n) _Pragma("unroll") for (int k = 0; k < 2; ++k) dst[n][k] = *(const PG8_LAS bf16x8*)(lds + PG8_SB(b, h) + boff + n * 2048 + k * 1024); } while (0)
; #define PG8_WAIT_V(n) asm volatile("s_waitcnt vmcnt(" #n ")" ::: "memory")
; #define PG8_WAIT_L(n) asm volatile("s_waitcnt lgkmcnt(" #n ")" ::: "memory")
; #define PG8_BAR __builtin_amdgcn_s_barrier()
; #define PG8_SCHED __builtin_amdgcn_sched_barrier(0)
; template <class Epi, class Sched, bool ALIGN_EPI = false, bool SP2 = false>
; __device__ __forceinline__ void gemm_phase(PG8_LAS unsigned char* lds, const Gemm g, const Sched& S, const Epi& E) {
;     ...
;         const bool has_next = S.next(ui + 1, nxt);
;         const char* nA = has_next ? (const char*)g.A + (size_t)nxt.pm * tstep : cA; const char* nB = has_next ? (const char*)g.Bt + (size_t)nxt.pn * tstep : cB;
;         for (int t = 0; t < nt; t += 2) {
;             const bool last = (t == nt - 2);
;             const char* a1 = cA + (size_t)(t + 1) * kstep;
;             const char* a2 = last ? nA : cA + (size_t)(t + 2) * kstep; const char* b2 = last ? nB : cB + (size_t)(t + 2) * kstep;
;             const char* a3 = a2 + kstep; const char* b3 = b2 + kstep;
;             if (last && has_next) S.a_ready(nxt);
;             if constexpr (SP2) {
;             PG8_LDB(B0, 0, 0); PG8_LDB(B1, 0, 1); PG8_SCHED; PG8_LDA(At, 0, 0); PG8_STAGE(PG8_SA(1, 1), a1 + hstep, voffA);
;             PG8_WAIT_V(8); PG8_WAIT_L(0); PG8_BAR; PG8_MMA(0, 0, At, B0); PG8_MMA(0, 1, At, B1); PG8_BAR; PG8_SCHED;
;             PG8_LDA(At, 0, 1); PG8_STAGE(PG8_SB(0, 0), b2, voffB); PG8_STAGE(PG8_SB(0, 1), b2 + hstep, voffB); PG8_STAGE(PG8_SA(0, 0), a2, voffA);
;             PG8_WAIT_V(8); PG8_WAIT_L(0); PG8_BAR; PG8_MMA(1, 0, At, B0); PG8_MMA(1, 1, At, B1); PG8_BAR; PG8_SCHED;
.LBB0_1286:
	s_ashr_i32 s51, s50, 31
	s_lshl_b64 s[52:53], s[50:51], 19
	s_add_u32 s52, s22, s52
	s_addc_u32 s53, s23, s53
	s_and_b64 s[54:55], s[12:13], exec
	s_cselect_b32 s51, s53, s59
	s_cselect_b32 s61, s52, s58
	s_ashr_i32 s49, s48, 31
	s_lshl_b64 s[54:55], s[48:49], 19
	v_readlane_b32 s64, v250, 9
	v_readlane_b32 s65, v250, 10
	s_add_u32 s54, s64, s54
	s_addc_u32 s55, s65, s55
	s_and_b64 s[64:65], s[12:13], exec
	s_cselect_b32 s49, s55, s63
	s_cselect_b32 s87, s54, s62
	s_add_u32 s58, s58, 0x40080
	s_addc_u32 s59, s59, 0
	s_add_u32 s88, s62, 0x100
	s_addc_u32 s89, s63, 0
	s_mov_b32 s90, -2
	s_waitcnt lgkmcnt(0)
	ds_read_b128 v[128:131], v181
	ds_read_b128 v[160:163], v181 offset:1024
	ds_read_b128 v[164:167], v181 offset:2048
	ds_read_b128 v[168:171], v181 offset:3072
	ds_read_b128 v[172:175], v203
	ds_read_b128 v[176:179], v203 offset:1024
	ds_read_b128 v[182:185], v203 offset:2048
	ds_read_b128 v[186:189], v203 offset:3072
	s_add_u32 s62, s58, 0xfffc0080
	s_addc_u32 s63, s59, -1
	s_cmp_eq_u32 s90, 12
	s_cselect_b32 s65, s51, s63
	s_cselect_b32 s64, s61, s62
	s_cselect_b32 s63, s49, s89
	s_cselect_b32 s62, s87, s88
	v_lshl_add_u64 v[232:233], s[58:59], 0, v[152:153]
	s_add_i32 m0, s15, 0xc000
	ds_read_b128 v[190:193], v208
	ds_read_b128 v[194:197], v208 offset:1024
	ds_read_b128 v[198:201], v208 offset:2048
	ds_read_b128 v[212:215], v208 offset:3072
	ds_read_b128 v[216:219], v208 offset:4096
	ds_read_b128 v[220:223], v208 offset:5120
	ds_read_b128 v[224:227], v208 offset:6144
	ds_read_b128 v[228:231], v208 offset:7168
	global_load_lds_dwordx4 v[232:233], off
	v_lshl_add_u64 v[232:233], s[58:59], 0, v[154:155]
	s_add_i32 m0, s15, 0xe000
	s_nop 0
	global_load_lds_dwordx4 v[232:233], off
	s_waitcnt vmcnt(8)
	s_waitcnt lgkmcnt(0)
	s_barrier
	s_setprio 1
	s_waitcnt lgkmcnt(0)
	v_mfma_f32_16x16x32_bf16 v[124:127], v[128:131], v[190:193], 0
	v_mfma_f32_16x16x32_bf16 v[120:123], v[164:167], v[190:193], 0
	v_mfma_f32_16x16x32_bf16 v[116:119], v[128:131], v[198:201], 0
	v_mfma_f32_16x16x32_bf16 v[112:115], v[164:167], v[198:201], 0
	v_mfma_f32_16x16x32_bf16 v[108:111], v[128:131], v[216:219], 0
	v_mfma_f32_16x16x32_bf16 v[104:107], v[164:167], v[216:219], 0
	v_mfma_f32_16x16x32_bf16 v[100:103], v[128:131], v[224:227], 0
	v_mfma_f32_16x16x32_bf16 v[96:99], v[164:167], v[224:227], 0
	v_mfma_f32_16x16x32_bf16 v[124:127], v[160:163], v[194:197], v[124:127]
	v_mfma_f32_16x16x32_bf16 v[120:123], v[168:171], v[194:197], v[120:123]
	v_mfma_f32_16x16x32_bf16 v[116:119], v[160:163], v[212:215], v[116:119]
	v_mfma_f32_16x16x32_bf16 v[112:115], v[168:171], v[212:215], v[112:115]
	v_mfma_f32_16x16x32_bf16 v[108:111], v[160:163], v[220:223], v[108:111]
	v_mfma_f32_16x16x32_bf16 v[104:107], v[168:171], v[220:223], v[104:107]
	v_mfma_f32_16x16x32_bf16 v[100:103], v[160:163], v[228:231], v[100:103]
	v_mfma_f32_16x16x32_bf16 v[96:99], v[168:171], v[228:231], v[96:99]
	s_setprio 0
	s_setprio 1
	v_mfma_f32_16x16x32_bf16 v[60:63], v[172:175], v[190:193], 0
	v_mfma_f32_16x16x32_bf16 v[56:59], v[182:185], v[190:193], 0
	v_mfma_f32_16x16x32_bf16 v[52:55], v[172:175], v[198:201], 0
	v_mfma_f32_16x16x32_bf16 v[48:51], v[182:185], v[198:201], 0
	v_mfma_f32_16x16x32_bf16 v[44:47], v[172:175], v[216:219], 0
	v_mfma_f32_16x16x32_bf16 v[40:43], v[182:185], v[216:219], 0
	v_mfma_f32_16x16x32_bf16 v[36:39], v[172:175], v[224:227], 0
	v_mfma_f32_16x16x32_bf16 v[32:35], v[182:185], v[224:227], 0
	v_mfma_f32_16x16x32_bf16 v[60:63], v[176:179], v[194:197], v[60:63]
	v_mfma_f32_16x16x32_bf16 v[56:59], v[186:189], v[194:197], v[56:59]
	v_mfma_f32_16x16x32_bf16 v[52:55], v[176:179], v[212:215], v[52:55]
	v_mfma_f32_16x16x32_bf16 v[48:51], v[186:189], v[212:215], v[48:51]
	v_mfma_f32_16x16x32_bf16 v[44:47], v[176:179], v[220:223], v[44:47]
	v_mfma_f32_16x16x32_bf16 v[40:43], v[186:189], v[220:223], v[40:43]
	v_mfma_f32_16x16x32_bf16 v[36:39], v[176:179], v[228:231], v[36:39]
	v_mfma_f32_16x16x32_bf16 v[32:35], v[186:189], v[228:231], v[32:35]
	s_setprio 0
	s_barrier
	s_add_i32 s78, s75, s14
	v_lshl_add_u64 v[232:233], s[62:63], 0, v[134:135]
	s_mov_b32 m0, s78
	ds_read_b128 v[190:193], v208 offset:16384
	ds_read_b128 v[194:197], v208 offset:17408
	ds_read_b128 v[198:201], v208 offset:18432
	ds_read_b128 v[212:215], v208 offset:19456
	ds_read_b128 v[216:219], v208 offset:20480
	ds_read_b128 v[220:223], v208 offset:21504
	ds_read_b128 v[224:227], v208 offset:22528
	ds_read_b128 v[228:231], v208 offset:23552
	global_load_lds_dwordx4 v[232:233], off
	s_add_i32 m0, s78, 0x2000
	s_add_u32 s78, s62, 0x40000
	v_lshl_add_u64 v[234:235], s[62:63], 0, v[138:139]
	s_addc_u32 s79, s63, 0
	s_add_i32 s91, s76, s14
	global_load_lds_dwordx4 v[234:235], off
	v_lshl_add_u64 v[236:237], s[78:79], 0, v[134:135]
	s_mov_b32 m0, s91
	v_lshl_add_u64 v[238:239], s[64:65], 0, v[136:137]
	global_load_lds_dwordx4 v[236:237], off
	v_lshl_add_u64 v[236:237], s[78:79], 0, v[138:139]
	s_add_i32 m0, s91, 0x2000
	s_nop 0
	global_load_lds_dwordx4 v[236:237], off
	s_waitcnt vmcnt(6)
	s_waitcnt lgkmcnt(0)
	s_barrier
; #define PG8_STAGE(bufoff, gbase, voff) do { _Pragma("unroll") for (int _i = 0; _i < 2; ++_i) \
;         __builtin_amdgcn_global_load_lds((const unsigned*)((const char*)(gbase) + (voff)[_i]), (PG8_LAS unsigned*)(lds + (bufoff) + ldsw + _i * 8192), 16, 0, 0); } while (0)
; #define PG8_LDA(dst, b, h) do { _Pragma("unroll") for (int m = 0; m < 4; ++m) _Pragma("unroll") for (int k = 0; k < 2; ++k) dst[m][k] = *(const PG8_LAS bf16x8*)(lds + PG8_SA(b, h) + aoff + m * 2048 + k * 1024); } while (0)
; #define PG8_LDB(dst, b, h) do { _Pragma("unroll") for (int n = 0; n < 2; ++n) _Pragma("unroll") for (int k = 0; k < 2; ++k) dst[n][k] = *(const PG8_LAS bf16x8*)(lds + PG8_SB(b, h) + boff + n * 2048 + k * 1024); } while (0)
; #define PG8_MMA(ai, bj, At, Bt) do { __builtin_amdgcn_s_setprio(1); _Pragma("unroll") for (int m = 0; m < 4; ++m) _Pragma("unroll") for (int n = 0; n < 2; ++n) _Pragma("unroll") for (int k = 0; k < 2; ++k) \
;         acc[ai][bj][m][n] = __builtin_amdgcn_mfma_f32_16x16x32_bf16(Bt[n][k], At[m][k], acc[ai][bj][m][n], 0, 0, 0); __builtin_amdgcn_s_setprio(0); } while (0)
; #define PG8_WAIT_V(n) asm volatile("s_waitcnt vmcnt(" #n ")" ::: "memory")
; #define PG8_WAIT_L(n) asm volatile("s_waitcnt lgkmcnt(" #n ")" ::: "memory")
; #define PG8_BAR __builtin_amdgcn_s_barrier()
; #define PG8_SCHED __builtin_amdgcn_sched_barrier(0)
; template <class Epi, class Sched, bool ALIGN_EPI = false, bool SP2 = false>
; __device__ __forceinline__ void gemm_phase(PG8_LAS unsigned char* lds, const Gemm g, const Sched& S, const Epi& E) {
;     ...
;             PG8_WAIT_V(8); PG8_WAIT_L(0); PG8_BAR; PG8_MMA(1, 0, At, B0); PG8_MMA(1, 1, At, B1); PG8_BAR; PG8_SCHED;
;             PG8_LDB(B0, 1, 0); PG8_LDB(B1, 1, 1); PG8_SCHED; PG8_LDA(At, 1, 0); PG8_STAGE(PG8_SA(0, 1), a2 + hstep, voffA);
;             PG8_WAIT_V(8); PG8_WAIT_L(0); PG8_BAR; PG8_MMA(0, 0, At, B0); PG8_MMA(0, 1, At, B1); PG8_BAR; PG8_SCHED;
	s_setprio 1
	s_waitcnt lgkmcnt(0)
	v_mfma_f32_16x16x32_bf16 v[92:95], v[128:131], v[190:193], 0
	v_mfma_f32_16x16x32_bf16 v[88:91], v[164:167], v[190:193], 0
	v_mfma_f32_16x16x32_bf16 v[84:87], v[128:131], v[198:201], 0
	v_mfma_f32_16x16x32_bf16 v[80:83], v[164:167], v[198:201], 0
	v_mfma_f32_16x16x32_bf16 v[76:79], v[128:131], v[216:219], 0
	v_mfma_f32_16x16x32_bf16 v[72:75], v[164:167], v[216:219], 0
	v_lshl_add_u64 v[236:237], s[64:65], 0, v[132:133]
	s_mov_b32 m0, s15
	s_nop 0
	global_load_lds_dwordx4 v[236:237], off
	v_mfma_f32_16x16x32_bf16 v[68:71], v[128:131], v[224:227], 0
	v_mfma_f32_16x16x32_bf16 v[64:67], v[164:167], v[224:227], 0
	v_mfma_f32_16x16x32_bf16 v[92:95], v[160:163], v[194:197], v[92:95]
	v_mfma_f32_16x16x32_bf16 v[88:91], v[168:171], v[194:197], v[88:91]
	v_mfma_f32_16x16x32_bf16 v[84:87], v[160:163], v[212:215], v[84:87]
	v_mfma_f32_16x16x32_bf16 v[80:83], v[168:171], v[212:215], v[80:83]
	v_mfma_f32_16x16x32_bf16 v[76:79], v[160:163], v[220:223], v[76:79]
	v_mfma_f32_16x16x32_bf16 v[72:75], v[168:171], v[220:223], v[72:75]
	v_mfma_f32_16x16x32_bf16 v[68:71], v[160:163], v[228:231], v[68:71]
	v_mfma_f32_16x16x32_bf16 v[64:67], v[168:171], v[228:231], v[64:67]
	s_setprio 0
	s_setprio 1
	v_mfma_f32_16x16x32_bf16 v[28:31], v[172:175], v[190:193], 0
	v_mfma_f32_16x16x32_bf16 v[24:27], v[182:185], v[190:193], 0
	s_mov_b32 m0, s33
	s_nop 0
	global_load_lds_dwordx4 v[238:239], off
	v_mfma_f32_16x16x32_bf16 v[20:23], v[172:175], v[198:201], 0
	v_mfma_f32_16x16x32_bf16 v[16:19], v[182:185], v[198:201], 0
	v_mfma_f32_16x16x32_bf16 v[12:15], v[172:175], v[216:219], 0
	v_mfma_f32_16x16x32_bf16 v[8:11], v[182:185], v[216:219], 0
	v_mfma_f32_16x16x32_bf16 v[4:7], v[172:175], v[224:227], 0
	v_mfma_f32_16x16x32_bf16 v[0:3], v[182:185], v[224:227], 0
	v_mfma_f32_16x16x32_bf16 v[28:31], v[176:179], v[194:197], v[28:31]
	v_mfma_f32_16x16x32_bf16 v[24:27], v[186:189], v[194:197], v[24:27]
	v_mfma_f32_16x16x32_bf16 v[20:23], v[176:179], v[212:215], v[20:23]
	v_mfma_f32_16x16x32_bf16 v[16:19], v[186:189], v[212:215], v[16:19]
	v_mfma_f32_16x16x32_bf16 v[12:15], v[176:179], v[220:223], v[12:15]
	v_mfma_f32_16x16x32_bf16 v[8:11], v[186:189], v[220:223], v[8:11]
	v_mfma_f32_16x16x32_bf16 v[4:7], v[176:179], v[228:231], v[4:7]
	v_mfma_f32_16x16x32_bf16 v[0:3], v[186:189], v[228:231], v[0:3]
	s_setprio 0
	s_barrier
	s_add_i32 s78, 0, 0x18000
	v_add_u32_e32 v140, s78, v147
	s_add_i32 s79, 0, 0x1c000
	ds_read_b128 v[128:131], v140
	ds_read_b128 v[160:163], v140 offset:1024
	ds_read_b128 v[164:167], v140 offset:2048
	ds_read_b128 v[168:171], v140 offset:3072
	v_add_u32_e32 v140, s79, v147
	ds_read_b128 v[172:175], v140
	ds_read_b128 v[176:179], v140 offset:1024
	ds_read_b128 v[182:185], v140 offset:2048
	ds_read_b128 v[186:189], v140 offset:3072
	s_add_u32 s64, s64, 0x40000
	s_addc_u32 s65, s65, 0
	s_mov_b32 m0, s34
	v_lshl_add_u64 v[240:241], s[64:65], 0, v[132:133]
	ds_read_b128 v[190:193], v208 offset:32768
	ds_read_b128 v[194:197], v208 offset:33792
	ds_read_b128 v[198:201], v208 offset:34816
	ds_read_b128 v[212:215], v208 offset:35840
	ds_read_b128 v[216:219], v208 offset:36864
	ds_read_b128 v[220:223], v208 offset:37888
	ds_read_b128 v[224:227], v208 offset:38912
	ds_read_b128 v[228:231], v208 offset:39936
	global_load_lds_dwordx4 v[240:241], off
	v_lshl_add_u64 v[240:241], s[64:65], 0, v[136:137]
	s_mov_b32 m0, s57
	s_nop 0
	global_load_lds_dwordx4 v[240:241], off
	s_waitcnt vmcnt(8)
	s_waitcnt lgkmcnt(0)
	s_barrier
	s_setprio 1
	s_waitcnt lgkmcnt(0)
	v_mfma_f32_16x16x32_bf16 v[124:127], v[128:131], v[190:193], v[124:127]
	v_mfma_f32_16x16x32_bf16 v[120:123], v[164:167], v[190:193], v[120:123]
	v_mfma_f32_16x16x32_bf16 v[116:119], v[128:131], v[198:201], v[116:119]
	v_mfma_f32_16x16x32_bf16 v[112:115], v[164:167], v[198:201], v[112:115]
	v_mfma_f32_16x16x32_bf16 v[108:111], v[128:131], v[216:219], v[108:111]
	v_mfma_f32_16x16x32_bf16 v[104:107], v[164:167], v[216:219], v[104:107]
	v_mfma_f32_16x16x32_bf16 v[100:103], v[128:131], v[224:227], v[100:103]
	v_mfma_f32_16x16x32_bf16 v[96:99], v[164:167], v[224:227], v[96:99]
	v_mfma_f32_16x16x32_bf16 v[124:127], v[160:163], v[194:197], v[124:127]
	v_mfma_f32_16x16x32_bf16 v[120:123], v[168:171], v[194:197], v[120:123]
	v_mfma_f32_16x16x32_bf16 v[116:119], v[160:163], v[212:215], v[116:119]
	v_mfma_f32_16x16x32_bf16 v[112:115], v[168:171], v[212:215], v[112:115]
	v_mfma_f32_16x16x32_bf16 v[108:111], v[160:163], v[220:223], v[108:111]
	v_mfma_f32_16x16x32_bf16 v[104:107], v[168:171], v[220:223], v[104:107]
	v_mfma_f32_16x16x32_bf16 v[100:103], v[160:163], v[228:231], v[100:103]
	v_mfma_f32_16x16x32_bf16 v[96:99], v[168:171], v[228:231], v[96:99]
	s_setprio 0
	s_setprio 1
	v_mfma_f32_16x16x32_bf16 v[60:63], v[172:175], v[190:193], v[60:63]
	v_mfma_f32_16x16x32_bf16 v[56:59], v[182:185], v[190:193], v[56:59]
	v_mfma_f32_16x16x32_bf16 v[52:55], v[172:175], v[198:201], v[52:55]
	v_mfma_f32_16x16x32_bf16 v[48:51], v[182:185], v[198:201], v[48:51]
	v_mfma_f32_16x16x32_bf16 v[44:47], v[172:175], v[216:219], v[44:47]
	v_mfma_f32_16x16x32_bf16 v[40:43], v[182:185], v[216:219], v[40:43]
	v_mfma_f32_16x16x32_bf16 v[36:39], v[172:175], v[224:227], v[36:39]
	v_mfma_f32_16x16x32_bf16 v[32:35], v[182:185], v[224:227], v[32:35]
	v_mfma_f32_16x16x32_bf16 v[60:63], v[176:179], v[194:197], v[60:63]
	v_mfma_f32_16x16x32_bf16 v[56:59], v[186:189], v[194:197], v[56:59]
	v_mfma_f32_16x16x32_bf16 v[52:55], v[176:179], v[212:215], v[52:55]
	v_mfma_f32_16x16x32_bf16 v[48:51], v[186:189], v[212:215], v[48:51]
	v_mfma_f32_16x16x32_bf16 v[44:47], v[176:179], v[220:223], v[44:47]
	v_mfma_f32_16x16x32_bf16 v[40:43], v[186:189], v[220:223], v[40:43]
	v_mfma_f32_16x16x32_bf16 v[36:39], v[176:179], v[228:231], v[36:39]
	v_mfma_f32_16x16x32_bf16 v[32:35], v[186:189], v[228:231], v[32:35]
	s_setprio 0
	s_barrier
; #define PG8_STAGE(bufoff, gbase, voff) do { _Pragma("unroll") for (int _i = 0; _i < 2; ++_i) \
;         __builtin_amdgcn_global_load_lds((const unsigned*)((const char*)(gbase) + (voff)[_i]), (PG8_LAS unsigned*)(lds + (bufoff) + ldsw + _i * 8192), 16, 0, 0); } while (0)
; #define PG8_LDA(dst, b, h) do { _Pragma("unroll") for (int m = 0; m < 4; ++m) _Pragma("unroll") for (int k = 0; k < 2; ++k) dst[m][k] = *(const PG8_LAS bf16x8*)(lds + PG8_SA(b, h) + aoff + m * 2048 + k * 1024); } while (0)
; #define PG8_LDB(dst, b, h) do { _Pragma("unroll") for (int n = 0; n < 2; ++n) _Pragma("unroll") for (int k = 0; k < 2; ++k) dst[n][k] = *(const PG8_LAS bf16x8*)(lds + PG8_SB(b, h) + boff + n * 2048 + k * 1024); } while (0)
; #define PG8_MMA(ai, bj, At, Bt) do { __builtin_amdgcn_s_setprio(1); _Pragma("unroll") for (int m = 0; m < 4; ++m) _Pragma("unroll") for (int n = 0; n < 2; ++n) _Pragma("unroll") for (int k = 0; k < 2; ++k) \
;         acc[ai][bj][m][n] = __builtin_amdgcn_mfma_f32_16x16x32_bf16(Bt[n][k], At[m][k], acc[ai][bj][m][n], 0, 0, 0); __builtin_amdgcn_s_setprio(0); } while (0)
; #define PG8_WAIT_V(n) asm volatile("s_waitcnt vmcnt(" #n ")" ::: "memory")
; #define PG8_WAIT_L(n) asm volatile("s_waitcnt lgkmcnt(" #n ")" ::: "memory")
; #define PG8_BAR __builtin_amdgcn_s_barrier()
; #define PG8_SCHED __builtin_amdgcn_sched_barrier(0)
; template <class Epi, class Sched, bool ALIGN_EPI = false, bool SP2 = false>
; __device__ __forceinline__ void gemm_phase(PG8_LAS unsigned char* lds, const Gemm g, const Sched& S, const Epi& E) {
;     ...
;             PG8_LDB(B0, 0, 0); PG8_LDB(B1, 0, 1); PG8_SCHED; PG8_LDA(At, 0, 0); PG8_STAGE(PG8_SA(1, 1), a1 + hstep, voffA);
;             PG8_WAIT_V(8); PG8_WAIT_L(0); PG8_BAR; PG8_MMA(0, 0, At, B0); PG8_MMA(0, 1, At, B1); PG8_BAR; PG8_SCHED;
;     ...
;             PG8_LDA(At, 1, 1); PG8_STAGE(PG8_SB(1, 0), b3, voffB); PG8_STAGE(PG8_SB(1, 1), b3 + hstep, voffB); PG8_STAGE(PG8_SA(1, 0), a3, voffA);
;             PG8_WAIT_V(8); PG8_WAIT_L(0); PG8_BAR; PG8_MMA(1, 0, At, B0); PG8_MMA(1, 1, At, B1); PG8_BAR; PG8_SCHED;
	s_add_i32 s64, s78, s14
	v_lshl_add_u64 v[232:233], v[232:233], 0, s[42:43]
	s_mov_b32 m0, s64
	ds_read_b128 v[190:193], v208 offset:49152
	ds_read_b128 v[194:197], v208 offset:50176
	ds_read_b128 v[198:201], v208 offset:51200
	ds_read_b128 v[212:215], v208 offset:52224
	ds_read_b128 v[216:219], v208 offset:53248
	ds_read_b128 v[220:223], v208 offset:54272
	ds_read_b128 v[224:227], v208 offset:55296
	ds_read_b128 v[228:231], v208 offset:56320
	global_load_lds_dwordx4 v[232:233], off
	s_add_i32 m0, s64, 0x2000
	s_add_u32 s62, s62, 0x40080
	v_lshl_add_u64 v[232:233], v[234:235], 0, s[42:43]
	s_addc_u32 s63, s63, 0
	s_add_i32 s64, s79, s14
	global_load_lds_dwordx4 v[232:233], off
	v_lshl_add_u64 v[232:233], s[62:63], 0, v[134:135]
	s_mov_b32 m0, s64
	s_nop 0
	global_load_lds_dwordx4 v[232:233], off
	v_lshl_add_u64 v[232:233], s[62:63], 0, v[138:139]
	s_add_i32 m0, s64, 0x2000
	s_nop 0
	global_load_lds_dwordx4 v[232:233], off
	s_waitcnt vmcnt(6)
	s_waitcnt lgkmcnt(0)
	s_barrier
	s_setprio 1
	s_waitcnt lgkmcnt(0)
	v_mfma_f32_16x16x32_bf16 v[92:95], v[128:131], v[190:193], v[92:95]
	v_mfma_f32_16x16x32_bf16 v[88:91], v[164:167], v[190:193], v[88:91]
	v_mfma_f32_16x16x32_bf16 v[84:87], v[128:131], v[198:201], v[84:87]
	v_mfma_f32_16x16x32_bf16 v[80:83], v[164:167], v[198:201], v[80:83]
	v_mfma_f32_16x16x32_bf16 v[76:79], v[128:131], v[216:219], v[76:79]
	v_mfma_f32_16x16x32_bf16 v[72:75], v[164:167], v[216:219], v[72:75]
	v_lshl_add_u64 v[232:233], v[236:237], 0, s[42:43]
	s_mov_b32 m0, s67
	s_nop 0
	global_load_lds_dwordx4 v[232:233], off
	v_mfma_f32_16x16x32_bf16 v[68:71], v[128:131], v[224:227], v[68:71]
	v_mfma_f32_16x16x32_bf16 v[64:67], v[164:167], v[224:227], v[64:67]
	v_mfma_f32_16x16x32_bf16 v[92:95], v[160:163], v[194:197], v[92:95]
	v_mfma_f32_16x16x32_bf16 v[88:91], v[168:171], v[194:197], v[88:91]
	v_mfma_f32_16x16x32_bf16 v[84:87], v[160:163], v[212:215], v[84:87]
	v_mfma_f32_16x16x32_bf16 v[80:83], v[168:171], v[212:215], v[80:83]
	v_mfma_f32_16x16x32_bf16 v[76:79], v[160:163], v[220:223], v[76:79]
	v_mfma_f32_16x16x32_bf16 v[72:75], v[168:171], v[220:223], v[72:75]
	v_mfma_f32_16x16x32_bf16 v[68:71], v[160:163], v[228:231], v[68:71]
	v_mfma_f32_16x16x32_bf16 v[64:67], v[168:171], v[228:231], v[64:67]
	s_setprio 0
	s_setprio 1
	v_mfma_f32_16x16x32_bf16 v[28:31], v[172:175], v[190:193], v[28:31]
	v_mfma_f32_16x16x32_bf16 v[24:27], v[182:185], v[190:193], v[24:27]
	v_lshl_add_u64 v[232:233], v[238:239], 0, s[42:43]
	s_mov_b32 m0, s74
	s_nop 0
	global_load_lds_dwordx4 v[232:233], off
	v_mfma_f32_16x16x32_bf16 v[20:23], v[172:175], v[198:201], v[20:23]
	v_mfma_f32_16x16x32_bf16 v[16:19], v[182:185], v[198:201], v[16:19]
	v_mfma_f32_16x16x32_bf16 v[12:15], v[172:175], v[216:219], v[12:15]
	v_mfma_f32_16x16x32_bf16 v[8:11], v[182:185], v[216:219], v[8:11]
	v_mfma_f32_16x16x32_bf16 v[4:7], v[172:175], v[224:227], v[4:7]
	v_mfma_f32_16x16x32_bf16 v[0:3], v[182:185], v[224:227], v[0:3]
	v_mfma_f32_16x16x32_bf16 v[28:31], v[176:179], v[194:197], v[28:31]
	v_mfma_f32_16x16x32_bf16 v[24:27], v[186:189], v[194:197], v[24:27]
	v_mfma_f32_16x16x32_bf16 v[20:23], v[176:179], v[212:215], v[20:23]
	v_mfma_f32_16x16x32_bf16 v[16:19], v[186:189], v[212:215], v[16:19]
	v_mfma_f32_16x16x32_bf16 v[12:15], v[176:179], v[220:223], v[12:15]
	v_mfma_f32_16x16x32_bf16 v[8:11], v[186:189], v[220:223], v[8:11]
	v_mfma_f32_16x16x32_bf16 v[4:7], v[176:179], v[228:231], v[4:7]
	v_mfma_f32_16x16x32_bf16 v[0:3], v[186:189], v[228:231], v[0:3]
	s_setprio 0
	s_barrier
	s_add_i32 s90, s90, 2
	s_add_u32 s58, s58, 0x100
	s_addc_u32 s59, s59, 0
	s_add_u32 s88, s88, 0x100
	s_addc_u32 s89, s89, 0
.LBB0_1287:
	ds_read_b128 v[128:131], v181
	ds_read_b128 v[160:163], v181 offset:1024
	ds_read_b128 v[164:167], v181 offset:2048
	ds_read_b128 v[168:171], v181 offset:3072
	ds_read_b128 v[172:175], v203
	ds_read_b128 v[176:179], v203 offset:1024
	ds_read_b128 v[182:185], v203 offset:2048
	ds_read_b128 v[186:189], v203 offset:3072
	s_add_u32 s62, s58, 0xfffc0080
	s_addc_u32 s63, s59, -1
	s_cmp_eq_u32 s90, 12
	s_cselect_b32 s65, s51, s63
	s_cselect_b32 s64, s61, s62
	s_cselect_b32 s63, s49, s89
	s_cselect_b32 s62, s87, s88
	v_lshl_add_u64 v[232:233], s[58:59], 0, v[152:153]
	s_add_i32 m0, s15, 0xc000
	ds_read_b128 v[190:193], v208
	ds_read_b128 v[194:197], v208 offset:1024
	ds_read_b128 v[198:201], v208 offset:2048
	ds_read_b128 v[212:215], v208 offset:3072
	ds_read_b128 v[216:219], v208 offset:4096
	ds_read_b128 v[220:223], v208 offset:5120
	ds_read_b128 v[224:227], v208 offset:6144
	ds_read_b128 v[228:231], v208 offset:7168
	global_load_lds_dwordx4 v[232:233], off
	v_lshl_add_u64 v[232:233], s[58:59], 0, v[154:155]
	s_add_i32 m0, s15, 0xe000
	s_nop 0
	global_load_lds_dwordx4 v[232:233], off
	s_waitcnt vmcnt(8)
	s_waitcnt lgkmcnt(0)
	s_barrier
; #define PG8_STAGE(bufoff, gbase, voff) do { _Pragma("unroll") for (int _i = 0; _i < 2; ++_i) \
;         __builtin_amdgcn_global_load_lds((const unsigned*)((const char*)(gbase) + (voff)[_i]), (PG8_LAS unsigned*)(lds + (bufoff) + ldsw + _i * 8192), 16, 0, 0); } while (0)
; #define PG8_LDA(dst, b, h) do { _Pragma("unroll") for (int m = 0; m < 4; ++m) _Pragma("unroll") for (int k = 0; k < 2; ++k) dst[m][k] = *(const PG8_LAS bf16x8*)(lds + PG8_SA(b, h) + aoff + m * 2048 + k * 1024); } while (0)
; #define PG8_LDB(dst, b, h) do { _Pragma("unroll") for (int n = 0; n < 2; ++n) _Pragma("unroll") for (int k = 0; k < 2; ++k) dst[n][k] = *(const PG8_LAS bf16x8*)(lds + PG8_SB(b, h) + boff + n * 2048 + k * 1024); } while (0)
; #define PG8_MMA(ai, bj, At, Bt) do { __builtin_amdgcn_s_setprio(1); _Pragma("unroll") for (int m = 0; m < 4; ++m) _Pragma("unroll") for (int n = 0; n < 2; ++n) _Pragma("unroll") for (int k = 0; k < 2; ++k) \
;         acc[ai][bj][m][n] = __builtin_amdgcn_mfma_f32_16x16x32_bf16(Bt[n][k], At[m][k], acc[ai][bj][m][n], 0, 0, 0); __builtin_amdgcn_s_setprio(0); } while (0)
; #define PG8_WAIT_V(n) asm volatile("s_waitcnt vmcnt(" #n ")" ::: "memory")
; #define PG8_WAIT_L(n) asm volatile("s_waitcnt lgkmcnt(" #n ")" ::: "memory")
; #define PG8_BAR __builtin_amdgcn_s_barrier()
; #define PG8_SCHED __builtin_amdgcn_sched_barrier(0)
; template <class Epi, class Sched, bool ALIGN_EPI = false, bool SP2 = false>
; __device__ __forceinline__ void gemm_phase(PG8_LAS unsigned char* lds, const Gemm g, const Sched& S, const Epi& E) {
;     ...
;             PG8_LDB(B0, 0, 0); PG8_LDB(B1, 0, 1); PG8_SCHED; PG8_LDA(At, 0, 0); PG8_STAGE(PG8_SA(1, 1), a1 + hstep, voffA);
;             PG8_WAIT_V(8); PG8_WAIT_L(0); PG8_BAR; PG8_MMA(0, 0, At, B0); PG8_MMA(0, 1, At, B1); PG8_BAR; PG8_SCHED;
;             PG8_LDA(At, 0, 1); PG8_STAGE(PG8_SB(0, 0), b2, voffB); PG8_STAGE(PG8_SB(0, 1), b2 + hstep, voffB); PG8_STAGE(PG8_SA(0, 0), a2, voffA);
;             PG8_WAIT_V(8); PG8_WAIT_L(0); PG8_BAR; PG8_MMA(1, 0, At, B0); PG8_MMA(1, 1, At, B1); PG8_BAR; PG8_SCHED;
	s_setprio 1
	s_waitcnt lgkmcnt(0)
	v_mfma_f32_16x16x32_bf16 v[124:127], v[128:131], v[190:193], v[124:127]
	v_mfma_f32_16x16x32_bf16 v[120:123], v[164:167], v[190:193], v[120:123]
	v_mfma_f32_16x16x32_bf16 v[116:119], v[128:131], v[198:201], v[116:119]
	v_mfma_f32_16x16x32_bf16 v[112:115], v[164:167], v[198:201], v[112:115]
	v_mfma_f32_16x16x32_bf16 v[108:111], v[128:131], v[216:219], v[108:111]
	v_mfma_f32_16x16x32_bf16 v[104:107], v[164:167], v[216:219], v[104:107]
	v_mfma_f32_16x16x32_bf16 v[100:103], v[128:131], v[224:227], v[100:103]
	v_mfma_f32_16x16x32_bf16 v[96:99], v[164:167], v[224:227], v[96:99]
	v_mfma_f32_16x16x32_bf16 v[124:127], v[160:163], v[194:197], v[124:127]
	v_mfma_f32_16x16x32_bf16 v[120:123], v[168:171], v[194:197], v[120:123]
	v_mfma_f32_16x16x32_bf16 v[116:119], v[160:163], v[212:215], v[116:119]
	v_mfma_f32_16x16x32_bf16 v[112:115], v[168:171], v[212:215], v[112:115]
	v_mfma_f32_16x16x32_bf16 v[108:111], v[160:163], v[220:223], v[108:111]
	v_mfma_f32_16x16x32_bf16 v[104:107], v[168:171], v[220:223], v[104:107]
	v_mfma_f32_16x16x32_bf16 v[100:103], v[160:163], v[228:231], v[100:103]
	v_mfma_f32_16x16x32_bf16 v[96:99], v[168:171], v[228:231], v[96:99]
	s_setprio 0
	s_setprio 1
	v_mfma_f32_16x16x32_bf16 v[60:63], v[172:175], v[190:193], v[60:63]
	v_mfma_f32_16x16x32_bf16 v[56:59], v[182:185], v[190:193], v[56:59]
	v_mfma_f32_16x16x32_bf16 v[52:55], v[172:175], v[198:201], v[52:55]
	v_mfma_f32_16x16x32_bf16 v[48:51], v[182:185], v[198:201], v[48:51]
	v_mfma_f32_16x16x32_bf16 v[44:47], v[172:175], v[216:219], v[44:47]
	v_mfma_f32_16x16x32_bf16 v[40:43], v[182:185], v[216:219], v[40:43]
	v_mfma_f32_16x16x32_bf16 v[36:39], v[172:175], v[224:227], v[36:39]
	v_mfma_f32_16x16x32_bf16 v[32:35], v[182:185], v[224:227], v[32:35]
	v_mfma_f32_16x16x32_bf16 v[60:63], v[176:179], v[194:197], v[60:63]
	v_mfma_f32_16x16x32_bf16 v[56:59], v[186:189], v[194:197], v[56:59]
	v_mfma_f32_16x16x32_bf16 v[52:55], v[176:179], v[212:215], v[52:55]
	v_mfma_f32_16x16x32_bf16 v[48:51], v[186:189], v[212:215], v[48:51]
	v_mfma_f32_16x16x32_bf16 v[44:47], v[176:179], v[220:223], v[44:47]
	v_mfma_f32_16x16x32_bf16 v[40:43], v[186:189], v[220:223], v[40:43]
	v_mfma_f32_16x16x32_bf16 v[36:39], v[176:179], v[228:231], v[36:39]
	v_mfma_f32_16x16x32_bf16 v[32:35], v[186:189], v[228:231], v[32:35]
	s_setprio 0
	s_barrier
	s_add_i32 s78, s75, s14
	v_lshl_add_u64 v[232:233], s[62:63], 0, v[134:135]
	s_mov_b32 m0, s78
	ds_read_b128 v[190:193], v208 offset:16384
	ds_read_b128 v[194:197], v208 offset:17408
	ds_read_b128 v[198:201], v208 offset:18432
	ds_read_b128 v[212:215], v208 offset:19456
	ds_read_b128 v[216:219], v208 offset:20480
	ds_read_b128 v[220:223], v208 offset:21504
	ds_read_b128 v[224:227], v208 offset:22528
	ds_read_b128 v[228:231], v208 offset:23552
	global_load_lds_dwordx4 v[232:233], off
	s_add_i32 m0, s78, 0x2000
	s_add_u32 s78, s62, 0x40000
	v_lshl_add_u64 v[234:235], s[62:63], 0, v[138:139]
	s_addc_u32 s79, s63, 0
	s_add_i32 s91, s76, s14
	global_load_lds_dwordx4 v[234:235], off
	v_lshl_add_u64 v[236:237], s[78:79], 0, v[134:135]
	s_mov_b32 m0, s91
	v_lshl_add_u64 v[238:239], s[64:65], 0, v[136:137]
	global_load_lds_dwordx4 v[236:237], off
	v_lshl_add_u64 v[236:237], s[78:79], 0, v[138:139]
	s_add_i32 m0, s91, 0x2000
	s_nop 0
	global_load_lds_dwordx4 v[236:237], off
	s_waitcnt vmcnt(6)
	s_waitcnt lgkmcnt(0)
	s_barrier
	s_setprio 1
	s_waitcnt lgkmcnt(0)
	v_mfma_f32_16x16x32_bf16 v[92:95], v[128:131], v[190:193], v[92:95]
	v_mfma_f32_16x16x32_bf16 v[88:91], v[164:167], v[190:193], v[88:91]
	v_mfma_f32_16x16x32_bf16 v[84:87], v[128:131], v[198:201], v[84:87]
	v_mfma_f32_16x16x32_bf16 v[80:83], v[164:167], v[198:201], v[80:83]
	v_mfma_f32_16x16x32_bf16 v[76:79], v[128:131], v[216:219], v[76:79]
	v_mfma_f32_16x16x32_bf16 v[72:75], v[164:167], v[216:219], v[72:75]
	v_lshl_add_u64 v[236:237], s[64:65], 0, v[132:133]
	s_mov_b32 m0, s15
	s_nop 0
	global_load_lds_dwordx4 v[236:237], off
	v_mfma_f32_16x16x32_bf16 v[68:71], v[128:131], v[224:227], v[68:71]
	v_mfma_f32_16x16x32_bf16 v[64:67], v[164:167], v[224:227], v[64:67]
	v_mfma_f32_16x16x32_bf16 v[92:95], v[160:163], v[194:197], v[92:95]
	v_mfma_f32_16x16x32_bf16 v[88:91], v[168:171], v[194:197], v[88:91]
	v_mfma_f32_16x16x32_bf16 v[84:87], v[160:163], v[212:215], v[84:87]
	v_mfma_f32_16x16x32_bf16 v[80:83], v[168:171], v[212:215], v[80:83]
	v_mfma_f32_16x16x32_bf16 v[76:79], v[160:163], v[220:223], v[76:79]
	v_mfma_f32_16x16x32_bf16 v[72:75], v[168:171], v[220:223], v[72:75]
	v_mfma_f32_16x16x32_bf16 v[68:71], v[160:163], v[228:231], v[68:71]
	v_mfma_f32_16x16x32_bf16 v[64:67], v[168:171], v[228:231], v[64:67]
	s_setprio 0
	s_setprio 1
	v_mfma_f32_16x16x32_bf16 v[28:31], v[172:175], v[190:193], v[28:31]
	v_mfma_f32_16x16x32_bf16 v[24:27], v[182:185], v[190:193], v[24:27]
	s_mov_b32 m0, s33
	s_nop 0
	global_load_lds_dwordx4 v[238:239], off
	v_mfma_f32_16x16x32_bf16 v[20:23], v[172:175], v[198:201], v[20:23]
	v_mfma_f32_16x16x32_bf16 v[16:19], v[182:185], v[198:201], v[16:19]
	v_mfma_f32_16x16x32_bf16 v[12:15], v[172:175], v[216:219], v[12:15]
	v_mfma_f32_16x16x32_bf16 v[8:11], v[182:185], v[216:219], v[8:11]
	v_mfma_f32_16x16x32_bf16 v[4:7], v[172:175], v[224:227], v[4:7]
	v_mfma_f32_16x16x32_bf16 v[0:3], v[182:185], v[224:227], v[0:3]
	v_mfma_f32_16x16x32_bf16 v[28:31], v[176:179], v[194:197], v[28:31]
	v_mfma_f32_16x16x32_bf16 v[24:27], v[186:189], v[194:197], v[24:27]
	v_mfma_f32_16x16x32_bf16 v[20:23], v[176:179], v[212:215], v[20:23]
	v_mfma_f32_16x16x32_bf16 v[16:19], v[186:189], v[212:215], v[16:19]
	v_mfma_f32_16x16x32_bf16 v[12:15], v[176:179], v[220:223], v[12:15]
	v_mfma_f32_16x16x32_bf16 v[8:11], v[186:189], v[220:223], v[8:11]
	v_mfma_f32_16x16x32_bf16 v[4:7], v[176:179], v[228:231], v[4:7]
	v_mfma_f32_16x16x32_bf16 v[0:3], v[186:189], v[228:231], v[0:3]
	s_setprio 0
	s_barrier
; #define PG8_STAGE(bufoff, gbase, voff) do { _Pragma("unroll") for (int _i = 0; _i < 2; ++_i) \
;         __builtin_amdgcn_global_load_lds((const unsigned*)((const char*)(gbase) + (voff)[_i]), (PG8_LAS unsigned*)(lds + (bufoff) + ldsw + _i * 8192), 16, 0, 0); } while (0)
; #define PG8_LDA(dst, b, h) do { _Pragma("unroll") for (int m = 0; m < 4; ++m) _Pragma("unroll") for (int k = 0; k < 2; ++k) dst[m][k] = *(const PG8_LAS bf16x8*)(lds + PG8_SA(b, h) + aoff + m * 2048 + k * 1024); } while (0)
; #define PG8_LDB(dst, b, h) do { _Pragma("unroll") for (int n = 0; n < 2; ++n) _Pragma("unroll") for (int k = 0; k < 2; ++k) dst[n][k] = *(const PG8_LAS bf16x8*)(lds + PG8_SB(b, h) + boff + n * 2048 + k * 1024); } while (0)
; #define PG8_MMA(ai, bj, At, Bt) do { __builtin_amdgcn_s_setprio(1); _Pragma("unroll") for (int m = 0; m < 4; ++m) _Pragma("unroll") for (int n = 0; n < 2; ++n) _Pragma("unroll") for (int k = 0; k < 2; ++k) \
;         acc[ai][bj][m][n] = __builtin_amdgcn_mfma_f32_16x16x32_bf16(Bt[n][k], At[m][k], acc[ai][bj][m][n], 0, 0, 0); __builtin_amdgcn_s_setprio(0); } while (0)
; #define PG8_WAIT_V(n) asm volatile("s_waitcnt vmcnt(" #n ")" ::: "memory")
; #define PG8_WAIT_L(n) asm volatile("s_waitcnt lgkmcnt(" #n ")" ::: "memory")
; #define PG8_BAR __builtin_amdgcn_s_barrier()
; #define PG8_SCHED __builtin_amdgcn_sched_barrier(0)
; template <class Epi, class Sched, bool ALIGN_EPI = false, bool SP2 = false>
; __device__ __forceinline__ void gemm_phase(PG8_LAS unsigned char* lds, const Gemm g, const Sched& S, const Epi& E) {
;     ...
;             PG8_LDB(B0, 1, 0); PG8_LDB(B1, 1, 1); PG8_SCHED; PG8_LDA(At, 1, 0); PG8_STAGE(PG8_SA(0, 1), a2 + hstep, voffA);
;             PG8_WAIT_V(8); PG8_WAIT_L(0); PG8_BAR; PG8_MMA(0, 0, At, B0); PG8_MMA(0, 1, At, B1); PG8_BAR; PG8_SCHED;
	s_add_i32 s78, 0, 0x18000
	v_add_u32_e32 v140, s78, v147
	s_add_i32 s79, 0, 0x1c000
	ds_read_b128 v[128:131], v140
	ds_read_b128 v[160:163], v140 offset:1024
	ds_read_b128 v[164:167], v140 offset:2048
	ds_read_b128 v[168:171], v140 offset:3072
	v_add_u32_e32 v140, s79, v147
	ds_read_b128 v[172:175], v140
	ds_read_b128 v[176:179], v140 offset:1024
	ds_read_b128 v[182:185], v140 offset:2048
	ds_read_b128 v[186:189], v140 offset:3072
	s_add_u32 s64, s64, 0x40000
	s_addc_u32 s65, s65, 0
	s_mov_b32 m0, s34
	v_lshl_add_u64 v[240:241], s[64:65], 0, v[132:133]
	ds_read_b128 v[190:193], v208 offset:32768
	ds_read_b128 v[194:197], v208 offset:33792
	ds_read_b128 v[198:201], v208 offset:34816
	ds_read_b128 v[212:215], v208 offset:35840
	ds_read_b128 v[216:219], v208 offset:36864
	ds_read_b128 v[220:223], v208 offset:37888
	ds_read_b128 v[224:227], v208 offset:38912
	ds_read_b128 v[228:231], v208 offset:39936
	global_load_lds_dwordx4 v[240:241], off
	v_lshl_add_u64 v[240:241], s[64:65], 0, v[136:137]
	s_mov_b32 m0, s57
	s_nop 0
	global_load_lds_dwordx4 v[240:241], off
	s_waitcnt vmcnt(8)
	s_waitcnt lgkmcnt(0)
	s_barrier
	s_setprio 1
	s_waitcnt lgkmcnt(0)
	v_mfma_f32_16x16x32_bf16 v[124:127], v[128:131], v[190:193], v[124:127]
	v_mfma_f32_16x16x32_bf16 v[120:123], v[164:167], v[190:193], v[120:123]
	v_mfma_f32_16x16x32_bf16 v[116:119], v[128:131], v[198:201], v[116:119]
	v_mfma_f32_16x16x32_bf16 v[112:115], v[164:167], v[198:201], v[112:115]
	v_mfma_f32_16x16x32_bf16 v[108:111], v[128:131], v[216:219], v[108:111]
	v_mfma_f32_16x16x32_bf16 v[104:107], v[164:167], v[216:219], v[104:107]
	v_mfma_f32_16x16x32_bf16 v[100:103], v[128:131], v[224:227], v[100:103]
	v_mfma_f32_16x16x32_bf16 v[96:99], v[164:167], v[224:227], v[96:99]
	v_mfma_f32_16x16x32_bf16 v[124:127], v[160:163], v[194:197], v[124:127]
	v_mfma_f32_16x16x32_bf16 v[120:123], v[168:171], v[194:197], v[120:123]
	v_mfma_f32_16x16x32_bf16 v[116:119], v[160:163], v[212:215], v[116:119]
	v_mfma_f32_16x16x32_bf16 v[112:115], v[168:171], v[212:215], v[112:115]
	v_mfma_f32_16x16x32_bf16 v[108:111], v[160:163], v[220:223], v[108:111]
	v_mfma_f32_16x16x32_bf16 v[104:107], v[168:171], v[220:223], v[104:107]
	v_mfma_f32_16x16x32_bf16 v[100:103], v[160:163], v[228:231], v[100:103]
	v_mfma_f32_16x16x32_bf16 v[96:99], v[168:171], v[228:231], v[96:99]
	s_setprio 0
	s_setprio 1
	v_mfma_f32_16x16x32_bf16 v[60:63], v[172:175], v[190:193], v[60:63]
	v_mfma_f32_16x16x32_bf16 v[56:59], v[182:185], v[190:193], v[56:59]
	v_mfma_f32_16x16x32_bf16 v[52:55], v[172:175], v[198:201], v[52:55]
	v_mfma_f32_16x16x32_bf16 v[48:51], v[182:185], v[198:201], v[48:51]
	v_mfma_f32_16x16x32_bf16 v[44:47], v[172:175], v[216:219], v[44:47]
	v_mfma_f32_16x16x32_bf16 v[40:43], v[182:185], v[216:219], v[40:43]
	v_mfma_f32_16x16x32_bf16 v[36:39], v[172:175], v[224:227], v[36:39]
	v_mfma_f32_16x16x32_bf16 v[32:35], v[182:185], v[224:227], v[32:35]
	v_mfma_f32_16x16x32_bf16 v[60:63], v[176:179], v[194:197], v[60:63]
	v_mfma_f32_16x16x32_bf16 v[56:59], v[186:189], v[194:197], v[56:59]
	v_mfma_f32_16x16x32_bf16 v[52:55], v[176:179], v[212:215], v[52:55]
	v_mfma_f32_16x16x32_bf16 v[48:51], v[186:189], v[212:215], v[48:51]
	v_mfma_f32_16x16x32_bf16 v[44:47], v[176:179], v[220:223], v[44:47]
	v_mfma_f32_16x16x32_bf16 v[40:43], v[186:189], v[220:223], v[40:43]
	v_mfma_f32_16x16x32_bf16 v[36:39], v[176:179], v[228:231], v[36:39]
	v_mfma_f32_16x16x32_bf16 v[32:35], v[186:189], v[228:231], v[32:35]
	s_setprio 0
	s_barrier
; #define PG8_STAGE(bufoff, gbase, voff) do { _Pragma("unroll") for (int _i = 0; _i < 2; ++_i) \
;         __builtin_amdgcn_global_load_lds((const unsigned*)((const char*)(gbase) + (voff)[_i]), (PG8_LAS unsigned*)(lds + (bufoff) + ldsw + _i * 8192), 16, 0, 0); } while (0)
; #define PG8_LDA(dst, b, h) do { _Pragma("unroll") for (int m = 0; m < 4; ++m) _Pragma("unroll") for (int k = 0; k < 2; ++k) dst[m][k] = *(const PG8_LAS bf16x8*)(lds + PG8_SA(b, h) + aoff + m * 2048 + k * 1024); } while (0)
; #define PG8_MMA(ai, bj, At, Bt) do { __builtin_amdgcn_s_setprio(1); _Pragma("unroll") for (int m = 0; m < 4; ++m) _Pragma("unroll") for (int n = 0; n < 2; ++n) _Pragma("unroll") for (int k = 0; k < 2; ++k) \
;         acc[ai][bj][m][n] = __builtin_amdgcn_mfma_f32_16x16x32_bf16(Bt[n][k], At[m][k], acc[ai][bj][m][n], 0, 0, 0); __builtin_amdgcn_s_setprio(0); } while (0)
; #define PG8_WAIT_V(n) asm volatile("s_waitcnt vmcnt(" #n ")" ::: "memory")
; #define PG8_WAIT_L(n) asm volatile("s_waitcnt lgkmcnt(" #n ")" ::: "memory")
; #define PG8_BAR __builtin_amdgcn_s_barrier()
; #define PG8_SCHED __builtin_amdgcn_sched_barrier(0)
; template <class Epi, class Sched, bool ALIGN_EPI = false, bool SP2 = false>
; __device__ __forceinline__ void gemm_phase(PG8_LAS unsigned char* lds, const Gemm g, const Sched& S, const Epi& E) {
;     ...
;             PG8_LDA(At, 1, 1); PG8_STAGE(PG8_SB(1, 0), b3, voffB); PG8_STAGE(PG8_SB(1, 1), b3 + hstep, voffB); PG8_STAGE(PG8_SA(1, 0), a3, voffA);
;             PG8_WAIT_V(8); PG8_WAIT_L(0); PG8_BAR; PG8_MMA(1, 0, At, B0); PG8_MMA(1, 1, At, B1); PG8_BAR; PG8_SCHED;
	s_add_i32 s64, s78, s14
	v_lshl_add_u64 v[232:233], v[232:233], 0, s[42:43]
	s_mov_b32 m0, s64
	ds_read_b128 v[190:193], v208 offset:49152
	ds_read_b128 v[194:197], v208 offset:50176
	ds_read_b128 v[198:201], v208 offset:51200
	ds_read_b128 v[212:215], v208 offset:52224
	ds_read_b128 v[216:219], v208 offset:53248
	ds_read_b128 v[220:223], v208 offset:54272
	ds_read_b128 v[224:227], v208 offset:55296
	ds_read_b128 v[228:231], v208 offset:56320
	global_load_lds_dwordx4 v[232:233], off
	s_add_i32 m0, s64, 0x2000
	s_add_u32 s62, s62, 0x40080
	v_lshl_add_u64 v[232:233], v[234:235], 0, s[42:43]
	s_addc_u32 s63, s63, 0
	s_add_i32 s64, s79, s14
	global_load_lds_dwordx4 v[232:233], off
	v_lshl_add_u64 v[232:233], s[62:63], 0, v[134:135]
	s_mov_b32 m0, s64
	s_nop 0
	global_load_lds_dwordx4 v[232:233], off
	v_lshl_add_u64 v[232:233], s[62:63], 0, v[138:139]
	s_add_i32 m0, s64, 0x2000
	s_nop 0
	global_load_lds_dwordx4 v[232:233], off
	s_waitcnt vmcnt(6)
	s_waitcnt lgkmcnt(0)
	s_barrier
	s_setprio 1
	s_waitcnt lgkmcnt(0)
	v_mfma_f32_16x16x32_bf16 v[92:95], v[128:131], v[190:193], v[92:95]
	v_mfma_f32_16x16x32_bf16 v[88:91], v[164:167], v[190:193], v[88:91]
	v_mfma_f32_16x16x32_bf16 v[84:87], v[128:131], v[198:201], v[84:87]
	v_mfma_f32_16x16x32_bf16 v[80:83], v[164:167], v[198:201], v[80:83]
	v_mfma_f32_16x16x32_bf16 v[76:79], v[128:131], v[216:219], v[76:79]
	v_mfma_f32_16x16x32_bf16 v[72:75], v[164:167], v[216:219], v[72:75]
	v_lshl_add_u64 v[232:233], v[236:237], 0, s[42:43]
	s_mov_b32 m0, s67
	s_nop 0
	global_load_lds_dwordx4 v[232:233], off
	v_mfma_f32_16x16x32_bf16 v[68:71], v[128:131], v[224:227], v[68:71]
	v_mfma_f32_16x16x32_bf16 v[64:67], v[164:167], v[224:227], v[64:67]
	v_mfma_f32_16x16x32_bf16 v[92:95], v[160:163], v[194:197], v[92:95]
	v_mfma_f32_16x16x32_bf16 v[88:91], v[168:171], v[194:197], v[88:91]
	v_mfma_f32_16x16x32_bf16 v[84:87], v[160:163], v[212:215], v[84:87]
	v_mfma_f32_16x16x32_bf16 v[80:83], v[168:171], v[212:215], v[80:83]
	v_mfma_f32_16x16x32_bf16 v[76:79], v[160:163], v[220:223], v[76:79]
	v_mfma_f32_16x16x32_bf16 v[72:75], v[168:171], v[220:223], v[72:75]
	v_mfma_f32_16x16x32_bf16 v[68:71], v[160:163], v[228:231], v[68:71]
	v_mfma_f32_16x16x32_bf16 v[64:67], v[168:171], v[228:231], v[64:67]
	s_setprio 0
	s_setprio 1
	v_mfma_f32_16x16x32_bf16 v[28:31], v[172:175], v[190:193], v[28:31]
	v_mfma_f32_16x16x32_bf16 v[24:27], v[182:185], v[190:193], v[24:27]
	v_lshl_add_u64 v[232:233], v[238:239], 0, s[42:43]
	s_mov_b32 m0, s74
	s_nop 0
	global_load_lds_dwordx4 v[232:233], off
	v_mfma_f32_16x16x32_bf16 v[20:23], v[172:175], v[198:201], v[20:23]
	v_mfma_f32_16x16x32_bf16 v[16:19], v[182:185], v[198:201], v[16:19]
	v_mfma_f32_16x16x32_bf16 v[12:15], v[172:175], v[216:219], v[12:15]
	v_mfma_f32_16x16x32_bf16 v[8:11], v[182:185], v[216:219], v[8:11]
	v_mfma_f32_16x16x32_bf16 v[4:7], v[172:175], v[224:227], v[4:7]
	v_mfma_f32_16x16x32_bf16 v[0:3], v[182:185], v[224:227], v[0:3]
	v_mfma_f32_16x16x32_bf16 v[28:31], v[176:179], v[194:197], v[28:31]
	v_mfma_f32_16x16x32_bf16 v[24:27], v[186:189], v[194:197], v[24:27]
	v_mfma_f32_16x16x32_bf16 v[20:23], v[176:179], v[212:215], v[20:23]
	v_mfma_f32_16x16x32_bf16 v[16:19], v[186:189], v[212:215], v[16:19]
	v_mfma_f32_16x16x32_bf16 v[12:15], v[176:179], v[220:223], v[12:15]
	v_mfma_f32_16x16x32_bf16 v[8:11], v[186:189], v[220:223], v[8:11]
	v_mfma_f32_16x16x32_bf16 v[4:7], v[176:179], v[228:231], v[4:7]
	v_mfma_f32_16x16x32_bf16 v[0:3], v[186:189], v[228:231], v[0:3]
	s_setprio 0
	s_barrier
	s_add_i32 s90, s90, 2
	s_add_u32 s58, s58, 0x100
	s_addc_u32 s59, s59, 0
	s_add_u32 s88, s88, 0x100
	s_addc_u32 s89, s89, 0
	s_cmp_gt_u32 s90, 13
	s_cbranch_scc0 .LBB0_1287
	s_and_b64 vcc, exec, s[44:45]
	s_cbranch_vccz .LBB0_1290
	s_barrier

; #define LAS __attribute__((address_space(3)))
; #define MFMA32(a, b, c) __builtin_amdgcn_mfma_f32_32x32x16_bf16((a), (b), (c), 0, 0, 0)
; #define DMA_PAIR(u_, pb_) do { DMA16(kgu + (size_t)(2 * (u_)) * 4096 + so, (pb_)); DMA16(kgu + (size_t)(2 * (u_) + 1) * 4096 + so, (pb_) + 8192); DMA16(vgu + (size_t)(2 * (u_)) * 4096 + so, 32768 + (pb_)); DMA16(vgu + (size_t)(2 * (u_) + 1) * 4096 + so, 32768 + (pb_) + 8192); } while (0)
; template <int l> __device__ __forceinline__ void layer_body(const Args& args, LAS unsigned char* lds, const XcdBarrier& bar) {
;     ...
;                     for (int u = 0; u <= umax; ++u) {
;                         if (u < umax) DMA_PAIR(u + 1, ((u + 1) & 1) * 16384);
;                         if (2 * u <= j) {
;                             const int ta = 2 * u; const bool hasb = (ta + 1 <= j);
;                             const LAS bf16* kl = (const LAS bf16*)(lds + (u & 1) * 16384) + (hh * 32 + pr) * 8; const LAS bf16* vl = (const LAS bf16*)(lds + 32768 + (u & 1) * 16384) + (hh * 128 + r) * 8;
;                             f32x16 st0, st1;
;                             { bf16x8 kfa[8], kfb[8];
; #pragma unroll
;                               for (int s = 0; s < 8; ++s) { kfa[s] = *(const LAS bf16x8*)(kl + s * 512); kfb[s] = *(const LAS bf16x8*)(kl + 4096 + s * 512); }
; #pragma unroll
;                               for (int i = 0; i < 16; ++i) { st0[i] = 0.f; st1[i] = 0.f; }
; #pragma unroll
;                               for (int s = 0; s < 8; ++s) { st0 = MFMA32(kfa[s], qf[s], st0); st1 = MFMA32(kfb[s], qf[s], st1); } }
;                             if (hasb) logits(ta + 1, st1);
;                             else {
; #pragma unroll
;                               for (int i = 0; i < 16; ++i) st1[i] = -INFINITY; }
;                             logits(ta, st0);
.LBB0_1510:
	s_cmp_gt_i32 s63, s61
	s_cbranch_scc1 .Lmoba_skipdma
	s_cmp_gt_i32 s75, s65
	s_cbranch_scc1 .Lmoba_qk_nodma
	s_and_b32 s76, s48, 0x4000
	v_add_u32_e32 v1, s76, v145
	ds_read_b128 v[218:221], v1
	ds_read_b128 v[222:225], v1 offset:8192
	ds_read_b128 v[226:229], v1 offset:1024
	ds_read_b128 v[230:233], v1 offset:9216
	ds_read_b128 v[234:237], v1 offset:2048
	ds_read_b128 v[238:241], v1 offset:10240
	ds_read_b128 v[242:245], v1 offset:3072
	ds_read_b128 v[246:249], v1 offset:11264
	s_lshr_b32 s77, s75, 2
	v_add_u32_e32 v202, s76, v179
	s_add_i32 s10, s48, 0x4000
	s_and_b32 s10, s10, 0x4000
	v_lshl_add_u64 v[2:3], v[156:157], 0, s[48:49]
	s_add_i32 s10, s33, s10
	v_lshl_add_u64 v[4:5], v[2:3], 0, s[36:37]
	v_lshl_add_u64 v[6:7], v[2:3], 0, s[38:39]
	v_lshl_add_u64 v[8:9], v[2:3], 0, s[42:43]
	v_lshl_add_u64 v[10:11], v[2:3], 0, s[44:45]
	s_waitcnt lgkmcnt(7)
	v_mfma_f32_32x32x16_bf16 v[80:95], v[218:221], v[112:115], 0
	ds_read_b128 v[218:221], v1 offset:4096
	s_waitcnt lgkmcnt(7)
	v_mfma_f32_32x32x16_bf16 v[96:111], v[222:225], v[112:115], 0
	ds_read_b128 v[222:225], v1 offset:12288
	s_mov_b32 m0, s10
	s_waitcnt lgkmcnt(7)
	v_mfma_f32_32x32x16_bf16 v[80:95], v[226:229], v[116:119], v[80:95]
	ds_read_b128 v[226:229], v1 offset:5120
	global_load_lds_dwordx4 v[4:5], off
	s_waitcnt lgkmcnt(7)
	v_mfma_f32_32x32x16_bf16 v[96:111], v[230:233], v[116:119], v[96:111]
	ds_read_b128 v[230:233], v1 offset:13312
	s_waitcnt lgkmcnt(7)
	v_mfma_f32_32x32x16_bf16 v[80:95], v[234:237], v[120:123], v[80:95]
	ds_read_b128 v[234:237], v1 offset:6144
	s_add_i32 m0, s10, 0x2000
	s_waitcnt lgkmcnt(7)
	v_mfma_f32_32x32x16_bf16 v[96:111], v[238:241], v[120:123], v[96:111]
	ds_read_b128 v[238:241], v1 offset:14336
	global_load_lds_dwordx4 v[6:7], off
	s_waitcnt lgkmcnt(7)
	v_mfma_f32_32x32x16_bf16 v[80:95], v[242:245], v[124:127], v[80:95]
	ds_read_b128 v[242:245], v1 offset:7168
	s_waitcnt lgkmcnt(7)
	v_mfma_f32_32x32x16_bf16 v[96:111], v[246:249], v[124:127], v[96:111]
	ds_read_b128 v[246:249], v1 offset:15360
	s_add_i32 m0, s10, 0x8000
	s_waitcnt lgkmcnt(7)
	v_mfma_f32_32x32x16_bf16 v[80:95], v[218:221], v[128:131], v[80:95]
	global_load_lds_dwordx4 v[8:9], off
	s_waitcnt lgkmcnt(6)
	v_mfma_f32_32x32x16_bf16 v[96:111], v[222:225], v[128:131], v[96:111]
	s_waitcnt lgkmcnt(5)
	v_mfma_f32_32x32x16_bf16 v[80:95], v[226:229], v[132:135], v[80:95]
	s_add_i32 m0, s10, 0xa000
	s_waitcnt lgkmcnt(4)
	v_mfma_f32_32x32x16_bf16 v[96:111], v[230:233], v[132:135], v[96:111]
	global_load_lds_dwordx4 v[10:11], off
	s_waitcnt lgkmcnt(3)
	v_mfma_f32_32x32x16_bf16 v[80:95], v[234:237], v[136:139], v[80:95]
	s_waitcnt lgkmcnt(2)
	v_mfma_f32_32x32x16_bf16 v[96:111], v[238:241], v[136:139], v[96:111]
	s_waitcnt lgkmcnt(1)
	v_mfma_f32_32x32x16_bf16 v[80:95], v[242:245], v[140:143], v[80:95]
	s_waitcnt lgkmcnt(0)
	v_mfma_f32_32x32x16_bf16 v[96:111], v[246:249], v[140:143], v[96:111]
	s_branch .Lmoba_qk_done
.Lmoba_skipdma:
	s_cmp_gt_i32 s75, s65
	s_cbranch_scc1 .LBB0_1509
	s_add_i32 s10, s48, 0x4000
	s_and_b32 s10, s10, 0x4000
	v_lshl_add_u64 v[2:3], v[156:157], 0, s[48:49]
	s_add_i32 s10, s33, s10
	v_lshl_add_u64 v[4:5], v[2:3], 0, s[36:37]
	s_mov_b32 m0, s10
	s_nop 0
	global_load_lds_dwordx4 v[4:5], off
	v_lshl_add_u64 v[4:5], v[2:3], 0, s[38:39]
	s_add_i32 m0, s10, 0x2000
	s_nop 0
	global_load_lds_dwordx4 v[4:5], off
	v_lshl_add_u64 v[4:5], v[2:3], 0, s[42:43]
	s_add_i32 m0, s10, 0x8000
	v_lshl_add_u64 v[2:3], v[2:3], 0, s[44:45]
	global_load_lds_dwordx4 v[4:5], off
	s_add_i32 m0, s10, 0xa000
	s_nop 0
	global_load_lds_dwordx4 v[2:3], off
	s_branch .LBB0_1509
.Lmoba_qk_nodma:
	s_and_b32 s76, s48, 0x4000
	v_add_u32_e32 v1, s76, v145
	ds_read_b128 v[218:221], v1
	ds_read_b128 v[222:225], v1 offset:8192
	ds_read_b128 v[226:229], v1 offset:1024
	ds_read_b128 v[230:233], v1 offset:9216
	ds_read_b128 v[234:237], v1 offset:2048
	ds_read_b128 v[238:241], v1 offset:10240
	ds_read_b128 v[242:245], v1 offset:3072
	ds_read_b128 v[246:249], v1 offset:11264
	s_lshr_b32 s77, s75, 2
	s_cmp_lt_i32 s63, s61
	s_mov_b64 s[10:11], -1
	v_add_u32_e32 v202, s76, v179
	s_waitcnt lgkmcnt(7)
	v_mfma_f32_32x32x16_bf16 v[80:95], v[218:221], v[112:115], 0
	ds_read_b128 v[218:221], v1 offset:4096
	s_waitcnt lgkmcnt(7)
	v_mfma_f32_32x32x16_bf16 v[96:111], v[222:225], v[112:115], 0
	ds_read_b128 v[222:225], v1 offset:12288
	s_waitcnt lgkmcnt(7)
	v_mfma_f32_32x32x16_bf16 v[80:95], v[226:229], v[116:119], v[80:95]
	ds_read_b128 v[226:229], v1 offset:5120
	s_waitcnt lgkmcnt(7)
	v_mfma_f32_32x32x16_bf16 v[96:111], v[230:233], v[116:119], v[96:111]
	ds_read_b128 v[230:233], v1 offset:13312
	s_waitcnt lgkmcnt(7)
	v_mfma_f32_32x32x16_bf16 v[80:95], v[234:237], v[120:123], v[80:95]
	ds_read_b128 v[234:237], v1 offset:6144
	s_waitcnt lgkmcnt(7)
	v_mfma_f32_32x32x16_bf16 v[96:111], v[238:241], v[120:123], v[96:111]
	ds_read_b128 v[238:241], v1 offset:14336
	s_waitcnt lgkmcnt(7)
	v_mfma_f32_32x32x16_bf16 v[80:95], v[242:245], v[124:127], v[80:95]
	ds_read_b128 v[242:245], v1 offset:7168
	s_waitcnt lgkmcnt(7)
	v_mfma_f32_32x32x16_bf16 v[96:111], v[246:249], v[124:127], v[96:111]
	ds_read_b128 v[246:249], v1 offset:15360
	s_waitcnt lgkmcnt(7)
	v_mfma_f32_32x32x16_bf16 v[80:95], v[218:221], v[128:131], v[80:95]
	s_waitcnt lgkmcnt(6)
	v_mfma_f32_32x32x16_bf16 v[96:111], v[222:225], v[128:131], v[96:111]
	s_waitcnt lgkmcnt(5)
	v_mfma_f32_32x32x16_bf16 v[80:95], v[226:229], v[132:135], v[80:95]
	s_waitcnt lgkmcnt(4)
	v_mfma_f32_32x32x16_bf16 v[96:111], v[230:233], v[132:135], v[96:111]
	s_waitcnt lgkmcnt(3)
	v_mfma_f32_32x32x16_bf16 v[80:95], v[234:237], v[136:139], v[80:95]
	s_waitcnt lgkmcnt(2)
	v_mfma_f32_32x32x16_bf16 v[96:111], v[238:241], v[136:139], v[96:111]
	s_waitcnt lgkmcnt(1)
	v_mfma_f32_32x32x16_bf16 v[80:95], v[242:245], v[140:143], v[80:95]
	s_waitcnt lgkmcnt(0)
	v_mfma_f32_32x32x16_bf16 v[96:111], v[246:249], v[140:143], v[96:111]
.Lmoba_qk_done:
	s_mov_b64 s[10:11], -1
	ds_read_b128 v[218:221], v202 offset:32768
	ds_read_b128 v[222:225], v202 offset:33280
	ds_read_b128 v[226:229], v202 offset:36864
	ds_read_b128 v[230:233], v202 offset:37376
	ds_read_b128 v[234:237], v202 offset:33792
	ds_read_b128 v[238:241], v202 offset:34304
	ds_read_b128 v[242:245], v202 offset:37888
	ds_read_b128 v[246:249], v202 offset:38400
	s_xor_b32 s50, s74, 0xffffffe0
	s_add_i32 s50, s50, s66
	s_cmpk_ge_i32 s50, 0x80
	s_cbranch_scc1 .Lmoba_fast
	s_cmp_lt_i32 s63, s61
	s_cbranch_scc1 .LBB0_1515
	s_lshl_b32 s10, 1, s77
	v_and_b32_e32 v1, s10, v189
	s_mov_b64 s[10:11], 0

; #define PG8_STAGE(bufoff, gbase, voff) do { _Pragma("unroll") for (int _i = 0; _i < 2; ++_i) \
;         __builtin_amdgcn_global_load_lds((const unsigned*)((const char*)(gbase) + (voff)[_i]), (PG8_LAS unsigned*)(lds + (bufoff) + ldsw + _i * 8192), 16, 0, 0); } while (0)
; #define PG8_LDA(dst, b, h) do { _Pragma("unroll") for (int m = 0; m < 4; ++m) _Pragma("unroll") for (int k = 0; k < 2; ++k) dst[m][k] = *(const PG8_LAS bf16x8*)(lds + PG8_SA(b, h) + aoff + m * 2048 + k * 1024); } while (0)
; #define PG8_LDB(dst, b, h) do { _Pragma("unroll") for (int n = 0; n < 2; ++n) _Pragma("unroll") for (int k = 0; k < 2; ++k) dst[n][k] = *(const PG8_LAS bf16x8*)(lds + PG8_SB(b, h) + boff + n * 2048 + k * 1024); } while (0)
; #define PG8_MMA(ai, bj, At, Bt) do { __builtin_amdgcn_s_setprio(1); _Pragma("unroll") for (int m = 0; m < 4; ++m) _Pragma("unroll") for (int n = 0; n < 2; ++n) _Pragma("unroll") for (int k = 0; k < 2; ++k) \
;         acc[ai][bj][m][n] = __builtin_amdgcn_mfma_f32_16x16x32_bf16(Bt[n][k], At[m][k], acc[ai][bj][m][n], 0, 0, 0); __builtin_amdgcn_s_setprio(0); } while (0)
; #define PG8_BAR __builtin_amdgcn_s_barrier()
; template <class Epi, class Sched, bool ALIGN_EPI = false, bool SP2 = false>
; __device__ __forceinline__ void gemm_phase(PG8_LAS unsigned char* lds, const Gemm g, const Sched& S, const Epi& E) {
;     ...
;         const bool has_next = S.next(ui + 1, nxt);
;         const char* nA = has_next ? (const char*)g.A + (size_t)nxt.pm * tstep : cA; const char* nB = has_next ? (const char*)g.Bt + (size_t)nxt.pn * tstep : cB;
;         for (int t = 0; t < nt; t += 2) {
;             const bool last = (t == nt - 2);
;             const char* a1 = cA + (size_t)(t + 1) * kstep;
;             const char* a2 = last ? nA : cA + (size_t)(t + 2) * kstep; const char* b2 = last ? nB : cB + (size_t)(t + 2) * kstep;
;             const char* a3 = a2 + kstep; const char* b3 = b2 + kstep;
;             if (last && has_next) S.a_ready(nxt);
;             if constexpr (SP2) {
;             PG8_LDB(B0, 0, 0); PG8_LDB(B1, 0, 1); PG8_SCHED; PG8_LDA(At, 0, 0); PG8_STAGE(PG8_SA(1, 1), a1 + hstep, voffA);
;             PG8_WAIT_V(8); PG8_WAIT_L(0); PG8_BAR; PG8_MMA(0, 0, At, B0); PG8_MMA(0, 1, At, B1); PG8_BAR; PG8_SCHED;
;             PG8_LDA(At, 0, 1); PG8_STAGE(PG8_SB(0, 0), b2, voffB); PG8_STAGE(PG8_SB(0, 1), b2 + hstep, voffB); PG8_STAGE(PG8_SA(0, 0), a2, voffA);
.LBB0_1592:
	s_ashr_i32 s39, s38, 31
	s_lshl_b64 s[42:43], s[38:39], 19
	s_add_u32 s42, s40, s42
	s_addc_u32 s43, s41, s43
	s_and_b64 s[44:45], s[10:11], exec
	s_cselect_b32 s39, s43, s51
	s_cselect_b32 s47, s42, s50
	s_ashr_i32 s37, s36, 31
	s_lshl_b64 s[44:45], s[36:37], 19
	v_readlane_b32 s54, v250, 11
	v_readlane_b32 s55, v250, 12
	s_add_u32 s44, s54, s44
	s_addc_u32 s45, s55, s45
	s_and_b64 s[54:55], s[10:11], exec
	s_cselect_b32 s37, s45, s53
	s_cselect_b32 s64, s44, s52
	s_add_u32 s50, s50, 0x40080
	s_addc_u32 s51, s51, 0
	s_add_u32 s65, s52, 0x100
	s_addc_u32 s66, s53, 0
	s_mov_b32 s67, -2
	s_waitcnt lgkmcnt(0)
	ds_read_b128 v[146:149], v152
	ds_read_b128 v[156:159], v152 offset:1024
	ds_read_b128 v[160:163], v152 offset:2048
	ds_read_b128 v[164:167], v152 offset:3072
	ds_read_b128 v[168:171], v153
	ds_read_b128 v[172:175], v153 offset:1024
	ds_read_b128 v[180:183], v153 offset:2048
	ds_read_b128 v[184:187], v153 offset:3072
	s_add_u32 s52, s50, 0xfffc0080
	s_addc_u32 s53, s51, -1
	s_cmp_eq_u32 s67, 12
	s_cselect_b32 s55, s39, s53
	s_cselect_b32 s54, s47, s52
	s_cselect_b32 s53, s37, s66
	s_cselect_b32 s52, s64, s65
	v_lshl_add_u64 v[200:201], s[50:51], 0, v[136:137]
	s_add_i32 m0, s33, 0xc000
	ds_read_b128 v[188:191], v154
	ds_read_b128 v[192:195], v154 offset:1024
	ds_read_b128 v[196:199], v154 offset:2048
	ds_read_b128 v[206:209], v154 offset:3072
	ds_read_b128 v[210:213], v154 offset:4096
	ds_read_b128 v[214:217], v154 offset:5120
	ds_read_b128 v[218:221], v154 offset:6144
	ds_read_b128 v[222:225], v154 offset:7168
	global_load_lds_dwordx4 v[200:201], off
	v_lshl_add_u64 v[200:201], s[50:51], 0, v[138:139]
	s_add_i32 m0, s33, 0xe000
	s_nop 0
	global_load_lds_dwordx4 v[200:201], off
	s_waitcnt vmcnt(8)
	s_waitcnt lgkmcnt(0)
	s_barrier
	s_setprio 1
	s_waitcnt lgkmcnt(0)
	v_mfma_f32_16x16x32_bf16 v[124:127], v[146:149], v[188:191], 0
	v_mfma_f32_16x16x32_bf16 v[120:123], v[160:163], v[188:191], 0
	v_mfma_f32_16x16x32_bf16 v[108:111], v[146:149], v[196:199], 0
	v_mfma_f32_16x16x32_bf16 v[104:107], v[160:163], v[196:199], 0
	v_mfma_f32_16x16x32_bf16 v[92:95], v[146:149], v[210:213], 0
	v_mfma_f32_16x16x32_bf16 v[88:91], v[160:163], v[210:213], 0
	v_mfma_f32_16x16x32_bf16 v[76:79], v[146:149], v[218:221], 0
	v_mfma_f32_16x16x32_bf16 v[72:75], v[160:163], v[218:221], 0
	v_mfma_f32_16x16x32_bf16 v[124:127], v[156:159], v[192:195], v[124:127]
	v_mfma_f32_16x16x32_bf16 v[120:123], v[164:167], v[192:195], v[120:123]
	v_mfma_f32_16x16x32_bf16 v[108:111], v[156:159], v[206:209], v[108:111]
	v_mfma_f32_16x16x32_bf16 v[104:107], v[164:167], v[206:209], v[104:107]
	v_mfma_f32_16x16x32_bf16 v[92:95], v[156:159], v[214:217], v[92:95]
	v_mfma_f32_16x16x32_bf16 v[88:91], v[164:167], v[214:217], v[88:91]
	v_mfma_f32_16x16x32_bf16 v[76:79], v[156:159], v[222:225], v[76:79]
	v_mfma_f32_16x16x32_bf16 v[72:75], v[164:167], v[222:225], v[72:75]
	s_setprio 0
	s_setprio 1
	v_mfma_f32_16x16x32_bf16 v[116:119], v[168:171], v[188:191], 0
	v_mfma_f32_16x16x32_bf16 v[112:115], v[180:183], v[188:191], 0
	v_mfma_f32_16x16x32_bf16 v[100:103], v[168:171], v[196:199], 0
	v_mfma_f32_16x16x32_bf16 v[96:99], v[180:183], v[196:199], 0
	v_mfma_f32_16x16x32_bf16 v[84:87], v[168:171], v[210:213], 0
	v_mfma_f32_16x16x32_bf16 v[80:83], v[180:183], v[210:213], 0
	v_mfma_f32_16x16x32_bf16 v[68:71], v[168:171], v[218:221], 0
	v_mfma_f32_16x16x32_bf16 v[64:67], v[180:183], v[218:221], 0
	v_mfma_f32_16x16x32_bf16 v[116:119], v[172:175], v[192:195], v[116:119]
	v_mfma_f32_16x16x32_bf16 v[112:115], v[184:187], v[192:195], v[112:115]
	v_mfma_f32_16x16x32_bf16 v[100:103], v[172:175], v[206:209], v[100:103]
	v_mfma_f32_16x16x32_bf16 v[96:99], v[184:187], v[206:209], v[96:99]
	v_mfma_f32_16x16x32_bf16 v[84:87], v[172:175], v[214:217], v[84:87]
	v_mfma_f32_16x16x32_bf16 v[80:83], v[184:187], v[214:217], v[80:83]
	v_mfma_f32_16x16x32_bf16 v[68:71], v[172:175], v[222:225], v[68:71]
	v_mfma_f32_16x16x32_bf16 v[64:67], v[184:187], v[222:225], v[64:67]
	s_setprio 0
	s_barrier
	s_add_i32 s74, s60, s15
	v_lshl_add_u64 v[200:201], s[52:53], 0, v[130:131]
	s_mov_b32 m0, s74
	ds_read_b128 v[188:191], v154 offset:16384
	ds_read_b128 v[192:195], v154 offset:17408
	ds_read_b128 v[196:199], v154 offset:18432
	ds_read_b128 v[206:209], v154 offset:19456
	ds_read_b128 v[210:213], v154 offset:20480
	ds_read_b128 v[214:217], v154 offset:21504
	ds_read_b128 v[218:221], v154 offset:22528
	ds_read_b128 v[222:225], v154 offset:23552
	global_load_lds_dwordx4 v[200:201], off
	s_add_i32 m0, s74, 0x2000
	s_add_u32 s74, s52, 0x40000
	v_lshl_add_u64 v[226:227], s[52:53], 0, v[134:135]
	s_addc_u32 s75, s53, 0
	s_add_i32 s76, s61, s15
	global_load_lds_dwordx4 v[226:227], off
	v_lshl_add_u64 v[228:229], s[74:75], 0, v[130:131]
	s_mov_b32 m0, s76
	v_lshl_add_u64 v[230:231], s[54:55], 0, v[132:133]
	global_load_lds_dwordx4 v[228:229], off
	v_lshl_add_u64 v[228:229], s[74:75], 0, v[134:135]
	s_add_i32 m0, s76, 0x2000
	s_nop 0
	global_load_lds_dwordx4 v[228:229], off
	s_waitcnt vmcnt(6)
	s_waitcnt lgkmcnt(0)
	s_barrier
; #define PG8_STAGE(bufoff, gbase, voff) do { _Pragma("unroll") for (int _i = 0; _i < 2; ++_i) \
;         __builtin_amdgcn_global_load_lds((const unsigned*)((const char*)(gbase) + (voff)[_i]), (PG8_LAS unsigned*)(lds + (bufoff) + ldsw + _i * 8192), 16, 0, 0); } while (0)
; #define PG8_LDA(dst, b, h) do { _Pragma("unroll") for (int m = 0; m < 4; ++m) _Pragma("unroll") for (int k = 0; k < 2; ++k) dst[m][k] = *(const PG8_LAS bf16x8*)(lds + PG8_SA(b, h) + aoff + m * 2048 + k * 1024); } while (0)
; #define PG8_LDB(dst, b, h) do { _Pragma("unroll") for (int n = 0; n < 2; ++n) _Pragma("unroll") for (int k = 0; k < 2; ++k) dst[n][k] = *(const PG8_LAS bf16x8*)(lds + PG8_SB(b, h) + boff + n * 2048 + k * 1024); } while (0)
; #define PG8_MMA(ai, bj, At, Bt) do { __builtin_amdgcn_s_setprio(1); _Pragma("unroll") for (int m = 0; m < 4; ++m) _Pragma("unroll") for (int n = 0; n < 2; ++n) _Pragma("unroll") for (int k = 0; k < 2; ++k) \
;         acc[ai][bj][m][n] = __builtin_amdgcn_mfma_f32_16x16x32_bf16(Bt[n][k], At[m][k], acc[ai][bj][m][n], 0, 0, 0); __builtin_amdgcn_s_setprio(0); } while (0)
; #define PG8_WAIT_V(n) asm volatile("s_waitcnt vmcnt(" #n ")" ::: "memory")
; #define PG8_WAIT_L(n) asm volatile("s_waitcnt lgkmcnt(" #n ")" ::: "memory")
; #define PG8_BAR __builtin_amdgcn_s_barrier()
; #define PG8_SCHED __builtin_amdgcn_sched_barrier(0)
; template <class Epi, class Sched, bool ALIGN_EPI = false, bool SP2 = false>
; __device__ __forceinline__ void gemm_phase(PG8_LAS unsigned char* lds, const Gemm g, const Sched& S, const Epi& E) {
;     ...
;             PG8_WAIT_V(8); PG8_WAIT_L(0); PG8_BAR; PG8_MMA(1, 0, At, B0); PG8_MMA(1, 1, At, B1); PG8_BAR; PG8_SCHED;
;             PG8_LDB(B0, 1, 0); PG8_LDB(B1, 1, 1); PG8_SCHED; PG8_LDA(At, 1, 0); PG8_STAGE(PG8_SA(0, 1), a2 + hstep, voffA);
;             PG8_WAIT_V(8); PG8_WAIT_L(0); PG8_BAR; PG8_MMA(0, 0, At, B0); PG8_MMA(0, 1, At, B1); PG8_BAR; PG8_SCHED;
	s_setprio 1
	s_waitcnt lgkmcnt(0)
	v_mfma_f32_16x16x32_bf16 v[60:63], v[146:149], v[188:191], 0
	v_mfma_f32_16x16x32_bf16 v[56:59], v[160:163], v[188:191], 0
	v_mfma_f32_16x16x32_bf16 v[44:47], v[146:149], v[196:199], 0
	v_mfma_f32_16x16x32_bf16 v[40:43], v[160:163], v[196:199], 0
	v_mfma_f32_16x16x32_bf16 v[28:31], v[146:149], v[210:213], 0
	v_mfma_f32_16x16x32_bf16 v[24:27], v[160:163], v[210:213], 0
	v_lshl_add_u64 v[228:229], s[54:55], 0, v[128:129]
	s_mov_b32 m0, s33
	s_nop 0
	global_load_lds_dwordx4 v[228:229], off
	v_mfma_f32_16x16x32_bf16 v[12:15], v[146:149], v[218:221], 0
	v_mfma_f32_16x16x32_bf16 v[8:11], v[160:163], v[218:221], 0
	v_mfma_f32_16x16x32_bf16 v[60:63], v[156:159], v[192:195], v[60:63]
	v_mfma_f32_16x16x32_bf16 v[56:59], v[164:167], v[192:195], v[56:59]
	v_mfma_f32_16x16x32_bf16 v[44:47], v[156:159], v[206:209], v[44:47]
	v_mfma_f32_16x16x32_bf16 v[40:43], v[164:167], v[206:209], v[40:43]
	v_mfma_f32_16x16x32_bf16 v[28:31], v[156:159], v[214:217], v[28:31]
	v_mfma_f32_16x16x32_bf16 v[24:27], v[164:167], v[214:217], v[24:27]
	v_mfma_f32_16x16x32_bf16 v[12:15], v[156:159], v[222:225], v[12:15]
	v_mfma_f32_16x16x32_bf16 v[8:11], v[164:167], v[222:225], v[8:11]
	s_setprio 0
	s_setprio 1
	v_mfma_f32_16x16x32_bf16 v[52:55], v[168:171], v[188:191], 0
	v_mfma_f32_16x16x32_bf16 v[48:51], v[180:183], v[188:191], 0
	s_mov_b32 m0, s34
	s_nop 0
	global_load_lds_dwordx4 v[230:231], off
	v_mfma_f32_16x16x32_bf16 v[36:39], v[168:171], v[196:199], 0
	v_mfma_f32_16x16x32_bf16 v[32:35], v[180:183], v[196:199], 0
	v_mfma_f32_16x16x32_bf16 v[20:23], v[168:171], v[210:213], 0
	v_mfma_f32_16x16x32_bf16 v[16:19], v[180:183], v[210:213], 0
	v_mfma_f32_16x16x32_bf16 v[4:7], v[168:171], v[218:221], 0
	v_mfma_f32_16x16x32_bf16 v[0:3], v[180:183], v[218:221], 0
	v_mfma_f32_16x16x32_bf16 v[52:55], v[172:175], v[192:195], v[52:55]
	v_mfma_f32_16x16x32_bf16 v[48:51], v[184:187], v[192:195], v[48:51]
	v_mfma_f32_16x16x32_bf16 v[36:39], v[172:175], v[206:209], v[36:39]
	v_mfma_f32_16x16x32_bf16 v[32:35], v[184:187], v[206:209], v[32:35]
	v_mfma_f32_16x16x32_bf16 v[20:23], v[172:175], v[214:217], v[20:23]
	v_mfma_f32_16x16x32_bf16 v[16:19], v[184:187], v[214:217], v[16:19]
	v_mfma_f32_16x16x32_bf16 v[4:7], v[172:175], v[222:225], v[4:7]
	v_mfma_f32_16x16x32_bf16 v[0:3], v[184:187], v[222:225], v[0:3]
	s_setprio 0
	s_barrier
	s_add_i32 s74, 0, 0x18000
	s_add_i32 s75, 0, 0x1c000
	v_add_u32_e32 v164, s74, v150
	v_add_u32_e32 v179, s75, v150
	ds_read_b128 v[146:149], v164
	ds_read_b128 v[156:159], v164 offset:1024
	ds_read_b128 v[160:163], v164 offset:2048
	ds_read_b128 v[164:167], v164 offset:3072
	ds_read_b128 v[168:171], v179
	ds_read_b128 v[172:175], v179 offset:1024
	ds_read_b128 v[180:183], v179 offset:2048
	ds_read_b128 v[184:187], v179 offset:3072
	s_add_u32 s54, s54, 0x40000
	s_addc_u32 s55, s55, 0
	s_mov_b32 m0, s49
	v_lshl_add_u64 v[232:233], s[54:55], 0, v[128:129]
	ds_read_b128 v[188:191], v154 offset:32768
	ds_read_b128 v[192:195], v154 offset:33792
	ds_read_b128 v[196:199], v154 offset:34816
	ds_read_b128 v[206:209], v154 offset:35840
	ds_read_b128 v[210:213], v154 offset:36864
	ds_read_b128 v[214:217], v154 offset:37888
	ds_read_b128 v[218:221], v154 offset:38912
	ds_read_b128 v[222:225], v154 offset:39936
	global_load_lds_dwordx4 v[232:233], off
	v_lshl_add_u64 v[232:233], s[54:55], 0, v[132:133]
	s_mov_b32 m0, s56
	s_nop 0
	global_load_lds_dwordx4 v[232:233], off
	s_waitcnt vmcnt(8)
	s_waitcnt lgkmcnt(0)
	s_barrier
	s_setprio 1
	s_waitcnt lgkmcnt(0)
	v_mfma_f32_16x16x32_bf16 v[124:127], v[146:149], v[188:191], v[124:127]
	v_mfma_f32_16x16x32_bf16 v[120:123], v[160:163], v[188:191], v[120:123]
	v_mfma_f32_16x16x32_bf16 v[108:111], v[146:149], v[196:199], v[108:111]
	v_mfma_f32_16x16x32_bf16 v[104:107], v[160:163], v[196:199], v[104:107]
	v_mfma_f32_16x16x32_bf16 v[92:95], v[146:149], v[210:213], v[92:95]
	v_mfma_f32_16x16x32_bf16 v[88:91], v[160:163], v[210:213], v[88:91]
	v_mfma_f32_16x16x32_bf16 v[76:79], v[146:149], v[218:221], v[76:79]
	v_mfma_f32_16x16x32_bf16 v[72:75], v[160:163], v[218:221], v[72:75]
	v_mfma_f32_16x16x32_bf16 v[124:127], v[156:159], v[192:195], v[124:127]
	v_mfma_f32_16x16x32_bf16 v[120:123], v[164:167], v[192:195], v[120:123]
	v_mfma_f32_16x16x32_bf16 v[108:111], v[156:159], v[206:209], v[108:111]
	v_mfma_f32_16x16x32_bf16 v[104:107], v[164:167], v[206:209], v[104:107]
	v_mfma_f32_16x16x32_bf16 v[92:95], v[156:159], v[214:217], v[92:95]
	v_mfma_f32_16x16x32_bf16 v[88:91], v[164:167], v[214:217], v[88:91]
	v_mfma_f32_16x16x32_bf16 v[76:79], v[156:159], v[222:225], v[76:79]
	v_mfma_f32_16x16x32_bf16 v[72:75], v[164:167], v[222:225], v[72:75]
	s_setprio 0
	s_setprio 1
	v_mfma_f32_16x16x32_bf16 v[116:119], v[168:171], v[188:191], v[116:119]
	v_mfma_f32_16x16x32_bf16 v[112:115], v[180:183], v[188:191], v[112:115]
	v_mfma_f32_16x16x32_bf16 v[100:103], v[168:171], v[196:199], v[100:103]
	v_mfma_f32_16x16x32_bf16 v[96:99], v[180:183], v[196:199], v[96:99]
	v_mfma_f32_16x16x32_bf16 v[84:87], v[168:171], v[210:213], v[84:87]
	v_mfma_f32_16x16x32_bf16 v[80:83], v[180:183], v[210:213], v[80:83]
	v_mfma_f32_16x16x32_bf16 v[68:71], v[168:171], v[218:221], v[68:71]
	v_mfma_f32_16x16x32_bf16 v[64:67], v[180:183], v[218:221], v[64:67]
	v_mfma_f32_16x16x32_bf16 v[116:119], v[172:175], v[192:195], v[116:119]
	v_mfma_f32_16x16x32_bf16 v[112:115], v[184:187], v[192:195], v[112:115]
	v_mfma_f32_16x16x32_bf16 v[100:103], v[172:175], v[206:209], v[100:103]
	v_mfma_f32_16x16x32_bf16 v[96:99], v[184:187], v[206:209], v[96:99]
	v_mfma_f32_16x16x32_bf16 v[84:87], v[172:175], v[214:217], v[84:87]
	v_mfma_f32_16x16x32_bf16 v[80:83], v[184:187], v[214:217], v[80:83]
	v_mfma_f32_16x16x32_bf16 v[68:71], v[172:175], v[222:225], v[68:71]
	v_mfma_f32_16x16x32_bf16 v[64:67], v[184:187], v[222:225], v[64:67]
	s_setprio 0
	s_barrier
; #define PG8_STAGE(bufoff, gbase, voff) do { _Pragma("unroll") for (int _i = 0; _i < 2; ++_i) \
;         __builtin_amdgcn_global_load_lds((const unsigned*)((const char*)(gbase) + (voff)[_i]), (PG8_LAS unsigned*)(lds + (bufoff) + ldsw + _i * 8192), 16, 0, 0); } while (0)
; #define PG8_LDA(dst, b, h) do { _Pragma("unroll") for (int m = 0; m < 4; ++m) _Pragma("unroll") for (int k = 0; k < 2; ++k) dst[m][k] = *(const PG8_LAS bf16x8*)(lds + PG8_SA(b, h) + aoff + m * 2048 + k * 1024); } while (0)
; #define PG8_LDB(dst, b, h) do { _Pragma("unroll") for (int n = 0; n < 2; ++n) _Pragma("unroll") for (int k = 0; k < 2; ++k) dst[n][k] = *(const PG8_LAS bf16x8*)(lds + PG8_SB(b, h) + boff + n * 2048 + k * 1024); } while (0)
; #define PG8_MMA(ai, bj, At, Bt) do { __builtin_amdgcn_s_setprio(1); _Pragma("unroll") for (int m = 0; m < 4; ++m) _Pragma("unroll") for (int n = 0; n < 2; ++n) _Pragma("unroll") for (int k = 0; k < 2; ++k) \
;         acc[ai][bj][m][n] = __builtin_amdgcn_mfma_f32_16x16x32_bf16(Bt[n][k], At[m][k], acc[ai][bj][m][n], 0, 0, 0); __builtin_amdgcn_s_setprio(0); } while (0)
; #define PG8_WAIT_V(n) asm volatile("s_waitcnt vmcnt(" #n ")" ::: "memory")
; #define PG8_WAIT_L(n) asm volatile("s_waitcnt lgkmcnt(" #n ")" ::: "memory")
; #define PG8_BAR __builtin_amdgcn_s_barrier()
; #define PG8_SCHED __builtin_amdgcn_sched_barrier(0)
; template <class Epi, class Sched, bool ALIGN_EPI = false, bool SP2 = false>
; __device__ __forceinline__ void gemm_phase(PG8_LAS unsigned char* lds, const Gemm g, const Sched& S, const Epi& E) {
;     ...
;             PG8_LDB(B0, 0, 0); PG8_LDB(B1, 0, 1); PG8_SCHED; PG8_LDA(At, 0, 0); PG8_STAGE(PG8_SA(1, 1), a1 + hstep, voffA);
;             PG8_WAIT_V(8); PG8_WAIT_L(0); PG8_BAR; PG8_MMA(0, 0, At, B0); PG8_MMA(0, 1, At, B1); PG8_BAR; PG8_SCHED;
;     ...
;             PG8_LDA(At, 1, 1); PG8_STAGE(PG8_SB(1, 0), b3, voffB); PG8_STAGE(PG8_SB(1, 1), b3 + hstep, voffB); PG8_STAGE(PG8_SA(1, 0), a3, voffA);
;             PG8_WAIT_V(8); PG8_WAIT_L(0); PG8_BAR; PG8_MMA(1, 0, At, B0); PG8_MMA(1, 1, At, B1); PG8_BAR; PG8_SCHED;
	s_add_i32 s54, s74, s15
	v_lshl_add_u64 v[200:201], v[200:201], 0, s[26:27]
	s_mov_b32 m0, s54
	ds_read_b128 v[188:191], v154 offset:49152
	ds_read_b128 v[192:195], v154 offset:50176
	ds_read_b128 v[196:199], v154 offset:51200
	ds_read_b128 v[206:209], v154 offset:52224
	ds_read_b128 v[210:213], v154 offset:53248
	ds_read_b128 v[214:217], v154 offset:54272
	ds_read_b128 v[218:221], v154 offset:55296
	ds_read_b128 v[222:225], v154 offset:56320
	global_load_lds_dwordx4 v[200:201], off
	s_add_i32 m0, s54, 0x2000
	s_add_u32 s52, s52, 0x40080
	v_lshl_add_u64 v[200:201], v[226:227], 0, s[26:27]
	s_addc_u32 s53, s53, 0
	s_add_i32 s54, s75, s15
	global_load_lds_dwordx4 v[200:201], off
	v_lshl_add_u64 v[200:201], s[52:53], 0, v[130:131]
	s_mov_b32 m0, s54
	s_nop 0
	global_load_lds_dwordx4 v[200:201], off
	v_lshl_add_u64 v[200:201], s[52:53], 0, v[134:135]
	s_add_i32 m0, s54, 0x2000
	s_nop 0
	global_load_lds_dwordx4 v[200:201], off
	s_waitcnt vmcnt(6)
	s_waitcnt lgkmcnt(0)
	s_barrier
	s_setprio 1
	s_waitcnt lgkmcnt(0)
	v_mfma_f32_16x16x32_bf16 v[60:63], v[146:149], v[188:191], v[60:63]
	v_mfma_f32_16x16x32_bf16 v[56:59], v[160:163], v[188:191], v[56:59]
	v_mfma_f32_16x16x32_bf16 v[44:47], v[146:149], v[196:199], v[44:47]
	v_mfma_f32_16x16x32_bf16 v[40:43], v[160:163], v[196:199], v[40:43]
	v_mfma_f32_16x16x32_bf16 v[28:31], v[146:149], v[210:213], v[28:31]
	v_mfma_f32_16x16x32_bf16 v[24:27], v[160:163], v[210:213], v[24:27]
	v_lshl_add_u64 v[200:201], v[228:229], 0, s[26:27]
	s_mov_b32 m0, s58
	s_nop 0
	global_load_lds_dwordx4 v[200:201], off
	v_mfma_f32_16x16x32_bf16 v[12:15], v[146:149], v[218:221], v[12:15]
	v_mfma_f32_16x16x32_bf16 v[8:11], v[160:163], v[218:221], v[8:11]
	v_mfma_f32_16x16x32_bf16 v[60:63], v[156:159], v[192:195], v[60:63]
	v_mfma_f32_16x16x32_bf16 v[56:59], v[164:167], v[192:195], v[56:59]
	v_mfma_f32_16x16x32_bf16 v[44:47], v[156:159], v[206:209], v[44:47]
	v_mfma_f32_16x16x32_bf16 v[40:43], v[164:167], v[206:209], v[40:43]
	v_mfma_f32_16x16x32_bf16 v[28:31], v[156:159], v[214:217], v[28:31]
	v_mfma_f32_16x16x32_bf16 v[24:27], v[164:167], v[214:217], v[24:27]
	v_mfma_f32_16x16x32_bf16 v[12:15], v[156:159], v[222:225], v[12:15]
	v_mfma_f32_16x16x32_bf16 v[8:11], v[164:167], v[222:225], v[8:11]
	s_setprio 0
	s_setprio 1
	v_mfma_f32_16x16x32_bf16 v[52:55], v[168:171], v[188:191], v[52:55]
	v_mfma_f32_16x16x32_bf16 v[48:51], v[180:183], v[188:191], v[48:51]
	v_lshl_add_u64 v[200:201], v[230:231], 0, s[26:27]
	s_mov_b32 m0, s59
	s_nop 0
	global_load_lds_dwordx4 v[200:201], off
	v_mfma_f32_16x16x32_bf16 v[36:39], v[168:171], v[196:199], v[36:39]
	v_mfma_f32_16x16x32_bf16 v[32:35], v[180:183], v[196:199], v[32:35]
	v_mfma_f32_16x16x32_bf16 v[20:23], v[168:171], v[210:213], v[20:23]
	v_mfma_f32_16x16x32_bf16 v[16:19], v[180:183], v[210:213], v[16:19]
	v_mfma_f32_16x16x32_bf16 v[4:7], v[168:171], v[218:221], v[4:7]
	v_mfma_f32_16x16x32_bf16 v[0:3], v[180:183], v[218:221], v[0:3]
	v_mfma_f32_16x16x32_bf16 v[52:55], v[172:175], v[192:195], v[52:55]
	v_mfma_f32_16x16x32_bf16 v[48:51], v[184:187], v[192:195], v[48:51]
	v_mfma_f32_16x16x32_bf16 v[36:39], v[172:175], v[206:209], v[36:39]
	v_mfma_f32_16x16x32_bf16 v[32:35], v[184:187], v[206:209], v[32:35]
	v_mfma_f32_16x16x32_bf16 v[20:23], v[172:175], v[214:217], v[20:23]
	v_mfma_f32_16x16x32_bf16 v[16:19], v[184:187], v[214:217], v[16:19]
	v_mfma_f32_16x16x32_bf16 v[4:7], v[172:175], v[222:225], v[4:7]
	v_mfma_f32_16x16x32_bf16 v[0:3], v[184:187], v[222:225], v[0:3]
	s_setprio 0
	s_barrier
	s_add_i32 s67, s67, 2
	s_add_u32 s50, s50, 0x100
	s_addc_u32 s51, s51, 0
	s_add_u32 s65, s65, 0x100
	s_addc_u32 s66, s66, 0
.LBB0_1593:
	ds_read_b128 v[146:149], v152
	ds_read_b128 v[156:159], v152 offset:1024
	ds_read_b128 v[160:163], v152 offset:2048
	ds_read_b128 v[164:167], v152 offset:3072
	ds_read_b128 v[168:171], v153
	ds_read_b128 v[172:175], v153 offset:1024
	ds_read_b128 v[180:183], v153 offset:2048
	ds_read_b128 v[184:187], v153 offset:3072
	s_add_u32 s52, s50, 0xfffc0080
	s_addc_u32 s53, s51, -1
	s_cmp_eq_u32 s67, 12
	s_cselect_b32 s55, s39, s53
	s_cselect_b32 s54, s47, s52
	s_cselect_b32 s53, s37, s66
	s_cselect_b32 s52, s64, s65
	v_lshl_add_u64 v[200:201], s[50:51], 0, v[136:137]
	s_add_i32 m0, s33, 0xc000
	ds_read_b128 v[188:191], v154
	ds_read_b128 v[192:195], v154 offset:1024
	ds_read_b128 v[196:199], v154 offset:2048
	ds_read_b128 v[206:209], v154 offset:3072
	ds_read_b128 v[210:213], v154 offset:4096
	ds_read_b128 v[214:217], v154 offset:5120
	ds_read_b128 v[218:221], v154 offset:6144
	ds_read_b128 v[222:225], v154 offset:7168
	global_load_lds_dwordx4 v[200:201], off
	v_lshl_add_u64 v[200:201], s[50:51], 0, v[138:139]
	s_add_i32 m0, s33, 0xe000
	s_nop 0
	global_load_lds_dwordx4 v[200:201], off
	s_waitcnt vmcnt(8)
	s_waitcnt lgkmcnt(0)
	s_barrier
; #define PG8_STAGE(bufoff, gbase, voff) do { _Pragma("unroll") for (int _i = 0; _i < 2; ++_i) \
;         __builtin_amdgcn_global_load_lds((const unsigned*)((const char*)(gbase) + (voff)[_i]), (PG8_LAS unsigned*)(lds + (bufoff) + ldsw + _i * 8192), 16, 0, 0); } while (0)
; #define PG8_LDA(dst, b, h) do { _Pragma("unroll") for (int m = 0; m < 4; ++m) _Pragma("unroll") for (int k = 0; k < 2; ++k) dst[m][k] = *(const PG8_LAS bf16x8*)(lds + PG8_SA(b, h) + aoff + m * 2048 + k * 1024); } while (0)
; #define PG8_LDB(dst, b, h) do { _Pragma("unroll") for (int n = 0; n < 2; ++n) _Pragma("unroll") for (int k = 0; k < 2; ++k) dst[n][k] = *(const PG8_LAS bf16x8*)(lds + PG8_SB(b, h) + boff + n * 2048 + k * 1024); } while (0)
; #define PG8_MMA(ai, bj, At, Bt) do { __builtin_amdgcn_s_setprio(1); _Pragma("unroll") for (int m = 0; m < 4; ++m) _Pragma("unroll") for (int n = 0; n < 2; ++n) _Pragma("unroll") for (int k = 0; k < 2; ++k) \
;         acc[ai][bj][m][n] = __builtin_amdgcn_mfma_f32_16x16x32_bf16(Bt[n][k], At[m][k], acc[ai][bj][m][n], 0, 0, 0); __builtin_amdgcn_s_setprio(0); } while (0)
; #define PG8_WAIT_V(n) asm volatile("s_waitcnt vmcnt(" #n ")" ::: "memory")
; #define PG8_WAIT_L(n) asm volatile("s_waitcnt lgkmcnt(" #n ")" ::: "memory")
; #define PG8_BAR __builtin_amdgcn_s_barrier()
; #define PG8_SCHED __builtin_amdgcn_sched_barrier(0)
; template <class Epi, class Sched, bool ALIGN_EPI = false, bool SP2 = false>
; __device__ __forceinline__ void gemm_phase(PG8_LAS unsigned char* lds, const Gemm g, const Sched& S, const Epi& E) {
;     ...
;             PG8_LDB(B0, 0, 0); PG8_LDB(B1, 0, 1); PG8_SCHED; PG8_LDA(At, 0, 0); PG8_STAGE(PG8_SA(1, 1), a1 + hstep, voffA);
;             PG8_WAIT_V(8); PG8_WAIT_L(0); PG8_BAR; PG8_MMA(0, 0, At, B0); PG8_MMA(0, 1, At, B1); PG8_BAR; PG8_SCHED;
;             PG8_LDA(At, 0, 1); PG8_STAGE(PG8_SB(0, 0), b2, voffB); PG8_STAGE(PG8_SB(0, 1), b2 + hstep, voffB); PG8_STAGE(PG8_SA(0, 0), a2, voffA);
;             PG8_WAIT_V(8); PG8_WAIT_L(0); PG8_BAR; PG8_MMA(1, 0, At, B0); PG8_MMA(1, 1, At, B1); PG8_BAR; PG8_SCHED;
	s_setprio 1
	s_waitcnt lgkmcnt(0)
	v_mfma_f32_16x16x32_bf16 v[124:127], v[146:149], v[188:191], v[124:127]
	v_mfma_f32_16x16x32_bf16 v[120:123], v[160:163], v[188:191], v[120:123]
	v_mfma_f32_16x16x32_bf16 v[108:111], v[146:149], v[196:199], v[108:111]
	v_mfma_f32_16x16x32_bf16 v[104:107], v[160:163], v[196:199], v[104:107]
	v_mfma_f32_16x16x32_bf16 v[92:95], v[146:149], v[210:213], v[92:95]
	v_mfma_f32_16x16x32_bf16 v[88:91], v[160:163], v[210:213], v[88:91]
	v_mfma_f32_16x16x32_bf16 v[76:79], v[146:149], v[218:221], v[76:79]
	v_mfma_f32_16x16x32_bf16 v[72:75], v[160:163], v[218:221], v[72:75]
	v_mfma_f32_16x16x32_bf16 v[124:127], v[156:159], v[192:195], v[124:127]
	v_mfma_f32_16x16x32_bf16 v[120:123], v[164:167], v[192:195], v[120:123]
	v_mfma_f32_16x16x32_bf16 v[108:111], v[156:159], v[206:209], v[108:111]
	v_mfma_f32_16x16x32_bf16 v[104:107], v[164:167], v[206:209], v[104:107]
	v_mfma_f32_16x16x32_bf16 v[92:95], v[156:159], v[214:217], v[92:95]
	v_mfma_f32_16x16x32_bf16 v[88:91], v[164:167], v[214:217], v[88:91]
	v_mfma_f32_16x16x32_bf16 v[76:79], v[156:159], v[222:225], v[76:79]
	v_mfma_f32_16x16x32_bf16 v[72:75], v[164:167], v[222:225], v[72:75]
	s_setprio 0
	s_setprio 1
	v_mfma_f32_16x16x32_bf16 v[116:119], v[168:171], v[188:191], v[116:119]
	v_mfma_f32_16x16x32_bf16 v[112:115], v[180:183], v[188:191], v[112:115]
	v_mfma_f32_16x16x32_bf16 v[100:103], v[168:171], v[196:199], v[100:103]
	v_mfma_f32_16x16x32_bf16 v[96:99], v[180:183], v[196:199], v[96:99]
	v_mfma_f32_16x16x32_bf16 v[84:87], v[168:171], v[210:213], v[84:87]
	v_mfma_f32_16x16x32_bf16 v[80:83], v[180:183], v[210:213], v[80:83]
	v_mfma_f32_16x16x32_bf16 v[68:71], v[168:171], v[218:221], v[68:71]
	v_mfma_f32_16x16x32_bf16 v[64:67], v[180:183], v[218:221], v[64:67]
	v_mfma_f32_16x16x32_bf16 v[116:119], v[172:175], v[192:195], v[116:119]
	v_mfma_f32_16x16x32_bf16 v[112:115], v[184:187], v[192:195], v[112:115]
	v_mfma_f32_16x16x32_bf16 v[100:103], v[172:175], v[206:209], v[100:103]
	v_mfma_f32_16x16x32_bf16 v[96:99], v[184:187], v[206:209], v[96:99]
	v_mfma_f32_16x16x32_bf16 v[84:87], v[172:175], v[214:217], v[84:87]
	v_mfma_f32_16x16x32_bf16 v[80:83], v[184:187], v[214:217], v[80:83]
	v_mfma_f32_16x16x32_bf16 v[68:71], v[172:175], v[222:225], v[68:71]
	v_mfma_f32_16x16x32_bf16 v[64:67], v[184:187], v[222:225], v[64:67]
	s_setprio 0
	s_barrier
	s_add_i32 s74, s60, s15
	v_lshl_add_u64 v[200:201], s[52:53], 0, v[130:131]
	s_mov_b32 m0, s74
	ds_read_b128 v[188:191], v154 offset:16384
	ds_read_b128 v[192:195], v154 offset:17408
	ds_read_b128 v[196:199], v154 offset:18432
	ds_read_b128 v[206:209], v154 offset:19456
	ds_read_b128 v[210:213], v154 offset:20480
	ds_read_b128 v[214:217], v154 offset:21504
	ds_read_b128 v[218:221], v154 offset:22528
	ds_read_b128 v[222:225], v154 offset:23552
	global_load_lds_dwordx4 v[200:201], off
	s_add_i32 m0, s74, 0x2000
	s_add_u32 s74, s52, 0x40000
	v_lshl_add_u64 v[226:227], s[52:53], 0, v[134:135]
	s_addc_u32 s75, s53, 0
	s_add_i32 s76, s61, s15
	global_load_lds_dwordx4 v[226:227], off
	v_lshl_add_u64 v[228:229], s[74:75], 0, v[130:131]
	s_mov_b32 m0, s76
	v_lshl_add_u64 v[230:231], s[54:55], 0, v[132:133]
	global_load_lds_dwordx4 v[228:229], off
	v_lshl_add_u64 v[228:229], s[74:75], 0, v[134:135]
	s_add_i32 m0, s76, 0x2000
	s_nop 0
	global_load_lds_dwordx4 v[228:229], off
	s_waitcnt vmcnt(6)
	s_waitcnt lgkmcnt(0)
	s_barrier
	s_setprio 1
	s_waitcnt lgkmcnt(0)
	v_mfma_f32_16x16x32_bf16 v[60:63], v[146:149], v[188:191], v[60:63]
	v_mfma_f32_16x16x32_bf16 v[56:59], v[160:163], v[188:191], v[56:59]
	v_mfma_f32_16x16x32_bf16 v[44:47], v[146:149], v[196:199], v[44:47]
	v_mfma_f32_16x16x32_bf16 v[40:43], v[160:163], v[196:199], v[40:43]
	v_mfma_f32_16x16x32_bf16 v[28:31], v[146:149], v[210:213], v[28:31]
	v_mfma_f32_16x16x32_bf16 v[24:27], v[160:163], v[210:213], v[24:27]
	v_lshl_add_u64 v[228:229], s[54:55], 0, v[128:129]
	s_mov_b32 m0, s33
	s_nop 0
	global_load_lds_dwordx4 v[228:229], off
	v_mfma_f32_16x16x32_bf16 v[12:15], v[146:149], v[218:221], v[12:15]
	v_mfma_f32_16x16x32_bf16 v[8:11], v[160:163], v[218:221], v[8:11]
	v_mfma_f32_16x16x32_bf16 v[60:63], v[156:159], v[192:195], v[60:63]
	v_mfma_f32_16x16x32_bf16 v[56:59], v[164:167], v[192:195], v[56:59]
	v_mfma_f32_16x16x32_bf16 v[44:47], v[156:159], v[206:209], v[44:47]
	v_mfma_f32_16x16x32_bf16 v[40:43], v[164:167], v[206:209], v[40:43]
	v_mfma_f32_16x16x32_bf16 v[28:31], v[156:159], v[214:217], v[28:31]
	v_mfma_f32_16x16x32_bf16 v[24:27], v[164:167], v[214:217], v[24:27]
	v_mfma_f32_16x16x32_bf16 v[12:15], v[156:159], v[222:225], v[12:15]
	v_mfma_f32_16x16x32_bf16 v[8:11], v[164:167], v[222:225], v[8:11]
	s_setprio 0
	s_setprio 1
	v_mfma_f32_16x16x32_bf16 v[52:55], v[168:171], v[188:191], v[52:55]
	v_mfma_f32_16x16x32_bf16 v[48:51], v[180:183], v[188:191], v[48:51]
	s_mov_b32 m0, s34
	s_nop 0
	global_load_lds_dwordx4 v[230:231], off
	v_mfma_f32_16x16x32_bf16 v[36:39], v[168:171], v[196:199], v[36:39]
	v_mfma_f32_16x16x32_bf16 v[32:35], v[180:183], v[196:199], v[32:35]
	v_mfma_f32_16x16x32_bf16 v[20:23], v[168:171], v[210:213], v[20:23]
	v_mfma_f32_16x16x32_bf16 v[16:19], v[180:183], v[210:213], v[16:19]
	v_mfma_f32_16x16x32_bf16 v[4:7], v[168:171], v[218:221], v[4:7]
	v_mfma_f32_16x16x32_bf16 v[0:3], v[180:183], v[218:221], v[0:3]
	v_mfma_f32_16x16x32_bf16 v[52:55], v[172:175], v[192:195], v[52:55]
	v_mfma_f32_16x16x32_bf16 v[48:51], v[184:187], v[192:195], v[48:51]
	v_mfma_f32_16x16x32_bf16 v[36:39], v[172:175], v[206:209], v[36:39]
	v_mfma_f32_16x16x32_bf16 v[32:35], v[184:187], v[206:209], v[32:35]
	v_mfma_f32_16x16x32_bf16 v[20:23], v[172:175], v[214:217], v[20:23]
	v_mfma_f32_16x16x32_bf16 v[16:19], v[184:187], v[214:217], v[16:19]
	v_mfma_f32_16x16x32_bf16 v[4:7], v[172:175], v[222:225], v[4:7]
	v_mfma_f32_16x16x32_bf16 v[0:3], v[184:187], v[222:225], v[0:3]
	s_setprio 0
	s_barrier
; #define PG8_STAGE(bufoff, gbase, voff) do { _Pragma("unroll") for (int _i = 0; _i < 2; ++_i) \
;         __builtin_amdgcn_global_load_lds((const unsigned*)((const char*)(gbase) + (voff)[_i]), (PG8_LAS unsigned*)(lds + (bufoff) + ldsw + _i * 8192), 16, 0, 0); } while (0)
; #define PG8_LDA(dst, b, h) do { _Pragma("unroll") for (int m = 0; m < 4; ++m) _Pragma("unroll") for (int k = 0; k < 2; ++k) dst[m][k] = *(const PG8_LAS bf16x8*)(lds + PG8_SA(b, h) + aoff + m * 2048 + k * 1024); } while (0)
; #define PG8_LDB(dst, b, h) do { _Pragma("unroll") for (int n = 0; n < 2; ++n) _Pragma("unroll") for (int k = 0; k < 2; ++k) dst[n][k] = *(const PG8_LAS bf16x8*)(lds + PG8_SB(b, h) + boff + n * 2048 + k * 1024); } while (0)
; #define PG8_MMA(ai, bj, At, Bt) do { __builtin_amdgcn_s_setprio(1); _Pragma("unroll") for (int m = 0; m < 4; ++m) _Pragma("unroll") for (int n = 0; n < 2; ++n) _Pragma("unroll") for (int k = 0; k < 2; ++k) \
;         acc[ai][bj][m][n] = __builtin_amdgcn_mfma_f32_16x16x32_bf16(Bt[n][k], At[m][k], acc[ai][bj][m][n], 0, 0, 0); __builtin_amdgcn_s_setprio(0); } while (0)
; #define PG8_WAIT_V(n) asm volatile("s_waitcnt vmcnt(" #n ")" ::: "memory")
; #define PG8_WAIT_L(n) asm volatile("s_waitcnt lgkmcnt(" #n ")" ::: "memory")
; #define PG8_BAR __builtin_amdgcn_s_barrier()
; #define PG8_SCHED __builtin_amdgcn_sched_barrier(0)
; template <class Epi, class Sched, bool ALIGN_EPI = false, bool SP2 = false>
; __device__ __forceinline__ void gemm_phase(PG8_LAS unsigned char* lds, const Gemm g, const Sched& S, const Epi& E) {
;     ...
;             PG8_LDB(B0, 1, 0); PG8_LDB(B1, 1, 1); PG8_SCHED; PG8_LDA(At, 1, 0); PG8_STAGE(PG8_SA(0, 1), a2 + hstep, voffA);
;             PG8_WAIT_V(8); PG8_WAIT_L(0); PG8_BAR; PG8_MMA(0, 0, At, B0); PG8_MMA(0, 1, At, B1); PG8_BAR; PG8_SCHED;
	s_add_i32 s74, 0, 0x18000
	s_add_i32 s75, 0, 0x1c000
	v_add_u32_e32 v164, s74, v150
	v_add_u32_e32 v179, s75, v150
	ds_read_b128 v[146:149], v164
	ds_read_b128 v[156:159], v164 offset:1024
	ds_read_b128 v[160:163], v164 offset:2048
	ds_read_b128 v[164:167], v164 offset:3072
	ds_read_b128 v[168:171], v179
	ds_read_b128 v[172:175], v179 offset:1024
	ds_read_b128 v[180:183], v179 offset:2048
	ds_read_b128 v[184:187], v179 offset:3072
	s_add_u32 s54, s54, 0x40000
	s_addc_u32 s55, s55, 0
	s_mov_b32 m0, s49
	v_lshl_add_u64 v[232:233], s[54:55], 0, v[128:129]
	ds_read_b128 v[188:191], v154 offset:32768
	ds_read_b128 v[192:195], v154 offset:33792
	ds_read_b128 v[196:199], v154 offset:34816
	ds_read_b128 v[206:209], v154 offset:35840
	ds_read_b128 v[210:213], v154 offset:36864
	ds_read_b128 v[214:217], v154 offset:37888
	ds_read_b128 v[218:221], v154 offset:38912
	ds_read_b128 v[222:225], v154 offset:39936
	global_load_lds_dwordx4 v[232:233], off
	v_lshl_add_u64 v[232:233], s[54:55], 0, v[132:133]
	s_mov_b32 m0, s56
	s_nop 0
	global_load_lds_dwordx4 v[232:233], off
	s_waitcnt vmcnt(8)
	s_waitcnt lgkmcnt(0)
	s_barrier
	s_setprio 1
	s_waitcnt lgkmcnt(0)
	v_mfma_f32_16x16x32_bf16 v[124:127], v[146:149], v[188:191], v[124:127]
	v_mfma_f32_16x16x32_bf16 v[120:123], v[160:163], v[188:191], v[120:123]
	v_mfma_f32_16x16x32_bf16 v[108:111], v[146:149], v[196:199], v[108:111]
	v_mfma_f32_16x16x32_bf16 v[104:107], v[160:163], v[196:199], v[104:107]
	v_mfma_f32_16x16x32_bf16 v[92:95], v[146:149], v[210:213], v[92:95]
	v_mfma_f32_16x16x32_bf16 v[88:91], v[160:163], v[210:213], v[88:91]
	v_mfma_f32_16x16x32_bf16 v[76:79], v[146:149], v[218:221], v[76:79]
	v_mfma_f32_16x16x32_bf16 v[72:75], v[160:163], v[218:221], v[72:75]
	v_mfma_f32_16x16x32_bf16 v[124:127], v[156:159], v[192:195], v[124:127]
	v_mfma_f32_16x16x32_bf16 v[120:123], v[164:167], v[192:195], v[120:123]
	v_mfma_f32_16x16x32_bf16 v[108:111], v[156:159], v[206:209], v[108:111]
	v_mfma_f32_16x16x32_bf16 v[104:107], v[164:167], v[206:209], v[104:107]
	v_mfma_f32_16x16x32_bf16 v[92:95], v[156:159], v[214:217], v[92:95]
	v_mfma_f32_16x16x32_bf16 v[88:91], v[164:167], v[214:217], v[88:91]
	v_mfma_f32_16x16x32_bf16 v[76:79], v[156:159], v[222:225], v[76:79]
	v_mfma_f32_16x16x32_bf16 v[72:75], v[164:167], v[222:225], v[72:75]
	s_setprio 0
	s_setprio 1
	v_mfma_f32_16x16x32_bf16 v[116:119], v[168:171], v[188:191], v[116:119]
	v_mfma_f32_16x16x32_bf16 v[112:115], v[180:183], v[188:191], v[112:115]
	v_mfma_f32_16x16x32_bf16 v[100:103], v[168:171], v[196:199], v[100:103]
	v_mfma_f32_16x16x32_bf16 v[96:99], v[180:183], v[196:199], v[96:99]
	v_mfma_f32_16x16x32_bf16 v[84:87], v[168:171], v[210:213], v[84:87]
	v_mfma_f32_16x16x32_bf16 v[80:83], v[180:183], v[210:213], v[80:83]
	v_mfma_f32_16x16x32_bf16 v[68:71], v[168:171], v[218:221], v[68:71]
	v_mfma_f32_16x16x32_bf16 v[64:67], v[180:183], v[218:221], v[64:67]
	v_mfma_f32_16x16x32_bf16 v[116:119], v[172:175], v[192:195], v[116:119]
	v_mfma_f32_16x16x32_bf16 v[112:115], v[184:187], v[192:195], v[112:115]
	v_mfma_f32_16x16x32_bf16 v[100:103], v[172:175], v[206:209], v[100:103]
	v_mfma_f32_16x16x32_bf16 v[96:99], v[184:187], v[206:209], v[96:99]
	v_mfma_f32_16x16x32_bf16 v[84:87], v[172:175], v[214:217], v[84:87]
	v_mfma_f32_16x16x32_bf16 v[80:83], v[184:187], v[214:217], v[80:83]
	v_mfma_f32_16x16x32_bf16 v[68:71], v[172:175], v[222:225], v[68:71]
	v_mfma_f32_16x16x32_bf16 v[64:67], v[184:187], v[222:225], v[64:67]
	s_setprio 0
	s_barrier
; #define PG8_STAGE(bufoff, gbase, voff) do { _Pragma("unroll") for (int _i = 0; _i < 2; ++_i) \
;         __builtin_amdgcn_global_load_lds((const unsigned*)((const char*)(gbase) + (voff)[_i]), (PG8_LAS unsigned*)(lds + (bufoff) + ldsw + _i * 8192), 16, 0, 0); } while (0)
; #define PG8_LDA(dst, b, h) do { _Pragma("unroll") for (int m = 0; m < 4; ++m) _Pragma("unroll") for (int k = 0; k < 2; ++k) dst[m][k] = *(const PG8_LAS bf16x8*)(lds + PG8_SA(b, h) + aoff + m * 2048 + k * 1024); } while (0)
; #define PG8_MMA(ai, bj, At, Bt) do { __builtin_amdgcn_s_setprio(1); _Pragma("unroll") for (int m = 0; m < 4; ++m) _Pragma("unroll") for (int n = 0; n < 2; ++n) _Pragma("unroll") for (int k = 0; k < 2; ++k) \
;         acc[ai][bj][m][n] = __builtin_amdgcn_mfma_f32_16x16x32_bf16(Bt[n][k], At[m][k], acc[ai][bj][m][n], 0, 0, 0); __builtin_amdgcn_s_setprio(0); } while (0)
; #define PG8_WAIT_V(n) asm volatile("s_waitcnt vmcnt(" #n ")" ::: "memory")
; #define PG8_WAIT_L(n) asm volatile("s_waitcnt lgkmcnt(" #n ")" ::: "memory")
; #define PG8_BAR __builtin_amdgcn_s_barrier()
; #define PG8_SCHED __builtin_amdgcn_sched_barrier(0)
; template <class Epi, class Sched, bool ALIGN_EPI = false, bool SP2 = false>
; __device__ __forceinline__ void gemm_phase(PG8_LAS unsigned char* lds, const Gemm g, const Sched& S, const Epi& E) {
;     ...
;             PG8_LDA(At, 1, 1); PG8_STAGE(PG8_SB(1, 0), b3, voffB); PG8_STAGE(PG8_SB(1, 1), b3 + hstep, voffB); PG8_STAGE(PG8_SA(1, 0), a3, voffA);
;             PG8_WAIT_V(8); PG8_WAIT_L(0); PG8_BAR; PG8_MMA(1, 0, At, B0); PG8_MMA(1, 1, At, B1); PG8_BAR; PG8_SCHED;
	s_add_i32 s54, s74, s15
	v_lshl_add_u64 v[200:201], v[200:201], 0, s[26:27]
	s_mov_b32 m0, s54
	ds_read_b128 v[188:191], v154 offset:49152
	ds_read_b128 v[192:195], v154 offset:50176
	ds_read_b128 v[196:199], v154 offset:51200
	ds_read_b128 v[206:209], v154 offset:52224
	ds_read_b128 v[210:213], v154 offset:53248
	ds_read_b128 v[214:217], v154 offset:54272
	ds_read_b128 v[218:221], v154 offset:55296
	ds_read_b128 v[222:225], v154 offset:56320
	global_load_lds_dwordx4 v[200:201], off
	s_add_i32 m0, s54, 0x2000
	s_add_u32 s52, s52, 0x40080
	v_lshl_add_u64 v[200:201], v[226:227], 0, s[26:27]
	s_addc_u32 s53, s53, 0
	s_add_i32 s54, s75, s15
	global_load_lds_dwordx4 v[200:201], off
	v_lshl_add_u64 v[200:201], s[52:53], 0, v[130:131]
	s_mov_b32 m0, s54
	s_nop 0
	global_load_lds_dwordx4 v[200:201], off
	v_lshl_add_u64 v[200:201], s[52:53], 0, v[134:135]
	s_add_i32 m0, s54, 0x2000
	s_nop 0
	global_load_lds_dwordx4 v[200:201], off
	s_waitcnt vmcnt(6)
	s_waitcnt lgkmcnt(0)
	s_barrier
	s_setprio 1
	s_waitcnt lgkmcnt(0)
	v_mfma_f32_16x16x32_bf16 v[60:63], v[146:149], v[188:191], v[60:63]
	v_mfma_f32_16x16x32_bf16 v[56:59], v[160:163], v[188:191], v[56:59]
	v_mfma_f32_16x16x32_bf16 v[44:47], v[146:149], v[196:199], v[44:47]
	v_mfma_f32_16x16x32_bf16 v[40:43], v[160:163], v[196:199], v[40:43]
	v_mfma_f32_16x16x32_bf16 v[28:31], v[146:149], v[210:213], v[28:31]
	v_mfma_f32_16x16x32_bf16 v[24:27], v[160:163], v[210:213], v[24:27]
	v_lshl_add_u64 v[200:201], v[228:229], 0, s[26:27]
	s_mov_b32 m0, s58
	s_nop 0
	global_load_lds_dwordx4 v[200:201], off
	v_mfma_f32_16x16x32_bf16 v[12:15], v[146:149], v[218:221], v[12:15]
	v_mfma_f32_16x16x32_bf16 v[8:11], v[160:163], v[218:221], v[8:11]
	v_mfma_f32_16x16x32_bf16 v[60:63], v[156:159], v[192:195], v[60:63]
	v_mfma_f32_16x16x32_bf16 v[56:59], v[164:167], v[192:195], v[56:59]
	v_mfma_f32_16x16x32_bf16 v[44:47], v[156:159], v[206:209], v[44:47]
	v_mfma_f32_16x16x32_bf16 v[40:43], v[164:167], v[206:209], v[40:43]
	v_mfma_f32_16x16x32_bf16 v[28:31], v[156:159], v[214:217], v[28:31]
	v_mfma_f32_16x16x32_bf16 v[24:27], v[164:167], v[214:217], v[24:27]
	v_mfma_f32_16x16x32_bf16 v[12:15], v[156:159], v[222:225], v[12:15]
	v_mfma_f32_16x16x32_bf16 v[8:11], v[164:167], v[222:225], v[8:11]
	s_setprio 0
	s_setprio 1
	v_mfma_f32_16x16x32_bf16 v[52:55], v[168:171], v[188:191], v[52:55]
	v_mfma_f32_16x16x32_bf16 v[48:51], v[180:183], v[188:191], v[48:51]
	v_lshl_add_u64 v[200:201], v[230:231], 0, s[26:27]
	s_mov_b32 m0, s59
	s_nop 0
	global_load_lds_dwordx4 v[200:201], off
	v_mfma_f32_16x16x32_bf16 v[36:39], v[168:171], v[196:199], v[36:39]
	v_mfma_f32_16x16x32_bf16 v[32:35], v[180:183], v[196:199], v[32:35]
	v_mfma_f32_16x16x32_bf16 v[20:23], v[168:171], v[210:213], v[20:23]
	v_mfma_f32_16x16x32_bf16 v[16:19], v[180:183], v[210:213], v[16:19]
	v_mfma_f32_16x16x32_bf16 v[4:7], v[168:171], v[218:221], v[4:7]
	v_mfma_f32_16x16x32_bf16 v[0:3], v[180:183], v[218:221], v[0:3]
	v_mfma_f32_16x16x32_bf16 v[52:55], v[172:175], v[192:195], v[52:55]
	v_mfma_f32_16x16x32_bf16 v[48:51], v[184:187], v[192:195], v[48:51]
	v_mfma_f32_16x16x32_bf16 v[36:39], v[172:175], v[206:209], v[36:39]
	v_mfma_f32_16x16x32_bf16 v[32:35], v[184:187], v[206:209], v[32:35]
	v_mfma_f32_16x16x32_bf16 v[20:23], v[172:175], v[214:217], v[20:23]
	v_mfma_f32_16x16x32_bf16 v[16:19], v[184:187], v[214:217], v[16:19]
	v_mfma_f32_16x16x32_bf16 v[4:7], v[172:175], v[222:225], v[4:7]
	v_mfma_f32_16x16x32_bf16 v[0:3], v[184:187], v[222:225], v[0:3]
	s_setprio 0
	s_barrier
	s_add_i32 s67, s67, 2
	s_add_u32 s50, s50, 0x100
	s_addc_u32 s51, s51, 0
	s_add_u32 s65, s65, 0x100
	s_addc_u32 s66, s66, 0
	s_cmp_gt_u32 s67, 13
	s_cbranch_scc0 .LBB0_1593
	s_and_b64 vcc, exec, s[28:29]
	s_cbranch_vccz .LBB0_1596
	s_barrier

; #define PG8_STAGE(bufoff, gbase, voff) do { _Pragma("unroll") for (int _i = 0; _i < 2; ++_i) \
;         __builtin_amdgcn_global_load_lds((const unsigned*)((const char*)(gbase) + (voff)[_i]), (PG8_LAS unsigned*)(lds + (bufoff) + ldsw + _i * 8192), 16, 0, 0); } while (0)
; #define PG8_LDA(dst, b, h) do { _Pragma("unroll") for (int m = 0; m < 4; ++m) _Pragma("unroll") for (int k = 0; k < 2; ++k) dst[m][k] = *(const PG8_LAS bf16x8*)(lds + PG8_SA(b, h) + aoff + m * 2048 + k * 1024); } while (0)
; #define PG8_LDB(dst, b, h) do { _Pragma("unroll") for (int n = 0; n < 2; ++n) _Pragma("unroll") for (int k = 0; k < 2; ++k) dst[n][k] = *(const PG8_LAS bf16x8*)(lds + PG8_SB(b, h) + boff + n * 2048 + k * 1024); } while (0)
; #define PG8_MMA(ai, bj, At, Bt) do { __builtin_amdgcn_s_setprio(1); _Pragma("unroll") for (int m = 0; m < 4; ++m) _Pragma("unroll") for (int n = 0; n < 2; ++n) _Pragma("unroll") for (int k = 0; k < 2; ++k) \
;         acc[ai][bj][m][n] = __builtin_amdgcn_mfma_f32_16x16x32_bf16(Bt[n][k], At[m][k], acc[ai][bj][m][n], 0, 0, 0); __builtin_amdgcn_s_setprio(0); } while (0)
; #define PG8_BAR __builtin_amdgcn_s_barrier()
; template <class Epi, class Sched, bool ALIGN_EPI = false, bool SP2 = false>
; __device__ __forceinline__ void gemm_phase(PG8_LAS unsigned char* lds, const Gemm g, const Sched& S, const Epi& E) {
;     ...
;         const bool has_next = S.next(ui + 1, nxt);
;         const char* nA = has_next ? (const char*)g.A + (size_t)nxt.pm * tstep : cA; const char* nB = has_next ? (const char*)g.Bt + (size_t)nxt.pn * tstep : cB;
;         for (int t = 0; t < nt; t += 2) {
;             const bool last = (t == nt - 2);
;             const char* a1 = cA + (size_t)(t + 1) * kstep;
;             const char* a2 = last ? nA : cA + (size_t)(t + 2) * kstep; const char* b2 = last ? nB : cB + (size_t)(t + 2) * kstep;
;             const char* a3 = a2 + kstep; const char* b3 = b2 + kstep;
;             if (last && has_next) S.a_ready(nxt);
;             if constexpr (SP2) {
;             PG8_LDB(B0, 0, 0); PG8_LDB(B1, 0, 1); PG8_SCHED; PG8_LDA(At, 0, 0); PG8_STAGE(PG8_SA(1, 1), a1 + hstep, voffA);
;             PG8_WAIT_V(8); PG8_WAIT_L(0); PG8_BAR; PG8_MMA(0, 0, At, B0); PG8_MMA(0, 1, At, B1); PG8_BAR; PG8_SCHED;
;             PG8_LDA(At, 0, 1); PG8_STAGE(PG8_SB(0, 0), b2, voffB); PG8_STAGE(PG8_SB(0, 1), b2 + hstep, voffB); PG8_STAGE(PG8_SA(0, 0), a2, voffA);
.LBB0_1680:
	s_ashr_i32 s47, s46, 31
	s_lshl_b64 s[48:49], s[46:47], 19
	s_add_u32 s48, s22, s48
	s_addc_u32 s49, s23, s49
	s_and_b64 s[50:51], s[4:5], exec
	s_cselect_b32 s47, s49, s53
	s_cselect_b32 s77, s48, s52
	s_ashr_i32 s45, s44, 31
	s_lshl_b64 s[50:51], s[44:45], 19
	s_add_u32 s50, s15, s50
	s_addc_u32 s51, s33, s51
	s_and_b64 s[56:57], s[4:5], exec
	s_cselect_b32 s45, s51, s55
	s_cselect_b32 s78, s50, s54
	s_add_u32 s52, s52, 0x40080
	s_addc_u32 s53, s53, 0
	s_add_u32 s79, s54, 0x100
	s_addc_u32 s80, s55, 0
	s_mov_b32 s81, -2
	ds_read_b128 v[146:149], v152
	ds_read_b128 v[156:159], v152 offset:1024
	ds_read_b128 v[160:163], v152 offset:2048
	ds_read_b128 v[164:167], v152 offset:3072
	ds_read_b128 v[168:171], v153
	ds_read_b128 v[172:175], v153 offset:1024
	ds_read_b128 v[180:183], v153 offset:2048
	ds_read_b128 v[184:187], v153 offset:3072
	s_add_u32 s54, s52, 0xfffc0080
	s_addc_u32 s55, s53, -1
	s_cmp_eq_u32 s81, 12
	s_cselect_b32 s57, s47, s55
	s_cselect_b32 s56, s77, s54
	s_cselect_b32 s55, s45, s80
	s_cselect_b32 s54, s78, s79
	v_lshl_add_u64 v[200:201], s[52:53], 0, v[136:137]
	s_add_i32 m0, s58, 0xc000
	ds_read_b128 v[188:191], v154
	ds_read_b128 v[192:195], v154 offset:1024
	ds_read_b128 v[196:199], v154 offset:2048
	ds_read_b128 v[206:209], v154 offset:3072
	ds_read_b128 v[210:213], v154 offset:4096
	ds_read_b128 v[214:217], v154 offset:5120
	ds_read_b128 v[218:221], v154 offset:6144
	ds_read_b128 v[222:225], v154 offset:7168
	global_load_lds_dwordx4 v[200:201], off
	v_lshl_add_u64 v[200:201], s[52:53], 0, v[138:139]
	s_add_i32 m0, s58, 0xe000
	s_nop 0
	global_load_lds_dwordx4 v[200:201], off
	s_waitcnt vmcnt(8)
	s_waitcnt lgkmcnt(0)
	s_barrier
	s_setprio 1
	s_waitcnt lgkmcnt(0)
	v_mfma_f32_16x16x32_bf16 v[124:127], v[146:149], v[188:191], 0
	v_mfma_f32_16x16x32_bf16 v[120:123], v[160:163], v[188:191], 0
	v_mfma_f32_16x16x32_bf16 v[108:111], v[146:149], v[196:199], 0
	v_mfma_f32_16x16x32_bf16 v[104:107], v[160:163], v[196:199], 0
	v_mfma_f32_16x16x32_bf16 v[92:95], v[146:149], v[210:213], 0
	v_mfma_f32_16x16x32_bf16 v[88:91], v[160:163], v[210:213], 0
	v_mfma_f32_16x16x32_bf16 v[76:79], v[146:149], v[218:221], 0
	v_mfma_f32_16x16x32_bf16 v[72:75], v[160:163], v[218:221], 0
	v_mfma_f32_16x16x32_bf16 v[124:127], v[156:159], v[192:195], v[124:127]
	v_mfma_f32_16x16x32_bf16 v[120:123], v[164:167], v[192:195], v[120:123]
	v_mfma_f32_16x16x32_bf16 v[108:111], v[156:159], v[206:209], v[108:111]
	v_mfma_f32_16x16x32_bf16 v[104:107], v[164:167], v[206:209], v[104:107]
	v_mfma_f32_16x16x32_bf16 v[92:95], v[156:159], v[214:217], v[92:95]
	v_mfma_f32_16x16x32_bf16 v[88:91], v[164:167], v[214:217], v[88:91]
	v_mfma_f32_16x16x32_bf16 v[76:79], v[156:159], v[222:225], v[76:79]
	v_mfma_f32_16x16x32_bf16 v[72:75], v[164:167], v[222:225], v[72:75]
	s_setprio 0
	s_setprio 1
	v_mfma_f32_16x16x32_bf16 v[116:119], v[168:171], v[188:191], 0
	v_mfma_f32_16x16x32_bf16 v[112:115], v[180:183], v[188:191], 0
	v_mfma_f32_16x16x32_bf16 v[100:103], v[168:171], v[196:199], 0
	v_mfma_f32_16x16x32_bf16 v[96:99], v[180:183], v[196:199], 0
	v_mfma_f32_16x16x32_bf16 v[84:87], v[168:171], v[210:213], 0
	v_mfma_f32_16x16x32_bf16 v[80:83], v[180:183], v[210:213], 0
	v_mfma_f32_16x16x32_bf16 v[68:71], v[168:171], v[218:221], 0
	v_mfma_f32_16x16x32_bf16 v[64:67], v[180:183], v[218:221], 0
	v_mfma_f32_16x16x32_bf16 v[116:119], v[172:175], v[192:195], v[116:119]
	v_mfma_f32_16x16x32_bf16 v[112:115], v[184:187], v[192:195], v[112:115]
	v_mfma_f32_16x16x32_bf16 v[100:103], v[172:175], v[206:209], v[100:103]
	v_mfma_f32_16x16x32_bf16 v[96:99], v[184:187], v[206:209], v[96:99]
	v_mfma_f32_16x16x32_bf16 v[84:87], v[172:175], v[214:217], v[84:87]
	v_mfma_f32_16x16x32_bf16 v[80:83], v[184:187], v[214:217], v[80:83]
	v_mfma_f32_16x16x32_bf16 v[68:71], v[172:175], v[222:225], v[68:71]
	v_mfma_f32_16x16x32_bf16 v[64:67], v[184:187], v[222:225], v[64:67]
	s_setprio 0
	s_barrier
	s_add_i32 s82, s65, s34
	v_lshl_add_u64 v[200:201], s[54:55], 0, v[132:133]
	s_mov_b32 m0, s82
	ds_read_b128 v[188:191], v154 offset:16384
	ds_read_b128 v[192:195], v154 offset:17408
	ds_read_b128 v[196:199], v154 offset:18432
	ds_read_b128 v[206:209], v154 offset:19456
	ds_read_b128 v[210:213], v154 offset:20480
	ds_read_b128 v[214:217], v154 offset:21504
	ds_read_b128 v[218:221], v154 offset:22528
	ds_read_b128 v[222:225], v154 offset:23552
	global_load_lds_dwordx4 v[200:201], off
	s_add_i32 m0, s82, 0x2000
	s_add_u32 s82, s54, 0x40000
	v_lshl_add_u64 v[226:227], s[54:55], 0, v[128:129]
	s_addc_u32 s83, s55, 0
	s_add_i32 s84, s66, s34
	global_load_lds_dwordx4 v[226:227], off
	v_lshl_add_u64 v[228:229], s[82:83], 0, v[132:133]
	s_mov_b32 m0, s84
	v_lshl_add_u64 v[230:231], s[56:57], 0, v[130:131]
	global_load_lds_dwordx4 v[228:229], off
	v_lshl_add_u64 v[228:229], s[82:83], 0, v[128:129]
	s_add_i32 m0, s84, 0x2000
	s_nop 0
	global_load_lds_dwordx4 v[228:229], off
	s_waitcnt vmcnt(6)
	s_waitcnt lgkmcnt(0)
	s_barrier
; #define PG8_STAGE(bufoff, gbase, voff) do { _Pragma("unroll") for (int _i = 0; _i < 2; ++_i) \
;         __builtin_amdgcn_global_load_lds((const unsigned*)((const char*)(gbase) + (voff)[_i]), (PG8_LAS unsigned*)(lds + (bufoff) + ldsw + _i * 8192), 16, 0, 0); } while (0)
; #define PG8_LDA(dst, b, h) do { _Pragma("unroll") for (int m = 0; m < 4; ++m) _Pragma("unroll") for (int k = 0; k < 2; ++k) dst[m][k] = *(const PG8_LAS bf16x8*)(lds + PG8_SA(b, h) + aoff + m * 2048 + k * 1024); } while (0)
; #define PG8_LDB(dst, b, h) do { _Pragma("unroll") for (int n = 0; n < 2; ++n) _Pragma("unroll") for (int k = 0; k < 2; ++k) dst[n][k] = *(const PG8_LAS bf16x8*)(lds + PG8_SB(b, h) + boff + n * 2048 + k * 1024); } while (0)
; #define PG8_MMA(ai, bj, At, Bt) do { __builtin_amdgcn_s_setprio(1); _Pragma("unroll") for (int m = 0; m < 4; ++m) _Pragma("unroll") for (int n = 0; n < 2; ++n) _Pragma("unroll") for (int k = 0; k < 2; ++k) \
;         acc[ai][bj][m][n] = __builtin_amdgcn_mfma_f32_16x16x32_bf16(Bt[n][k], At[m][k], acc[ai][bj][m][n], 0, 0, 0); __builtin_amdgcn_s_setprio(0); } while (0)
; #define PG8_WAIT_V(n) asm volatile("s_waitcnt vmcnt(" #n ")" ::: "memory")
; #define PG8_WAIT_L(n) asm volatile("s_waitcnt lgkmcnt(" #n ")" ::: "memory")
; #define PG8_BAR __builtin_amdgcn_s_barrier()
; #define PG8_SCHED __builtin_amdgcn_sched_barrier(0)
; template <class Epi, class Sched, bool ALIGN_EPI = false, bool SP2 = false>
; __device__ __forceinline__ void gemm_phase(PG8_LAS unsigned char* lds, const Gemm g, const Sched& S, const Epi& E) {
;     ...
;             PG8_WAIT_V(8); PG8_WAIT_L(0); PG8_BAR; PG8_MMA(1, 0, At, B0); PG8_MMA(1, 1, At, B1); PG8_BAR; PG8_SCHED;
;             PG8_LDB(B0, 1, 0); PG8_LDB(B1, 1, 1); PG8_SCHED; PG8_LDA(At, 1, 0); PG8_STAGE(PG8_SA(0, 1), a2 + hstep, voffA);
;             PG8_WAIT_V(8); PG8_WAIT_L(0); PG8_BAR; PG8_MMA(0, 0, At, B0); PG8_MMA(0, 1, At, B1); PG8_BAR; PG8_SCHED;
	s_setprio 1
	s_waitcnt lgkmcnt(0)
	v_mfma_f32_16x16x32_bf16 v[60:63], v[146:149], v[188:191], 0
	v_mfma_f32_16x16x32_bf16 v[56:59], v[160:163], v[188:191], 0
	v_mfma_f32_16x16x32_bf16 v[44:47], v[146:149], v[196:199], 0
	v_mfma_f32_16x16x32_bf16 v[40:43], v[160:163], v[196:199], 0
	v_mfma_f32_16x16x32_bf16 v[28:31], v[146:149], v[210:213], 0
	v_mfma_f32_16x16x32_bf16 v[24:27], v[160:163], v[210:213], 0
	v_lshl_add_u64 v[228:229], s[56:57], 0, v[134:135]
	s_mov_b32 m0, s58
	s_nop 0
	global_load_lds_dwordx4 v[228:229], off
	v_mfma_f32_16x16x32_bf16 v[12:15], v[146:149], v[218:221], 0
	v_mfma_f32_16x16x32_bf16 v[8:11], v[160:163], v[218:221], 0
	v_mfma_f32_16x16x32_bf16 v[60:63], v[156:159], v[192:195], v[60:63]
	v_mfma_f32_16x16x32_bf16 v[56:59], v[164:167], v[192:195], v[56:59]
	v_mfma_f32_16x16x32_bf16 v[44:47], v[156:159], v[206:209], v[44:47]
	v_mfma_f32_16x16x32_bf16 v[40:43], v[164:167], v[206:209], v[40:43]
	v_mfma_f32_16x16x32_bf16 v[28:31], v[156:159], v[214:217], v[28:31]
	v_mfma_f32_16x16x32_bf16 v[24:27], v[164:167], v[214:217], v[24:27]
	v_mfma_f32_16x16x32_bf16 v[12:15], v[156:159], v[222:225], v[12:15]
	v_mfma_f32_16x16x32_bf16 v[8:11], v[164:167], v[222:225], v[8:11]
	s_setprio 0
	s_setprio 1
	v_mfma_f32_16x16x32_bf16 v[52:55], v[168:171], v[188:191], 0
	v_mfma_f32_16x16x32_bf16 v[48:51], v[180:183], v[188:191], 0
	s_mov_b32 m0, s59
	s_nop 0
	global_load_lds_dwordx4 v[230:231], off
	v_mfma_f32_16x16x32_bf16 v[36:39], v[168:171], v[196:199], 0
	v_mfma_f32_16x16x32_bf16 v[32:35], v[180:183], v[196:199], 0
	v_mfma_f32_16x16x32_bf16 v[20:23], v[168:171], v[210:213], 0
	v_mfma_f32_16x16x32_bf16 v[16:19], v[180:183], v[210:213], 0
	v_mfma_f32_16x16x32_bf16 v[4:7], v[168:171], v[218:221], 0
	v_mfma_f32_16x16x32_bf16 v[0:3], v[180:183], v[218:221], 0
	v_mfma_f32_16x16x32_bf16 v[52:55], v[172:175], v[192:195], v[52:55]
	v_mfma_f32_16x16x32_bf16 v[48:51], v[184:187], v[192:195], v[48:51]
	v_mfma_f32_16x16x32_bf16 v[36:39], v[172:175], v[206:209], v[36:39]
	v_mfma_f32_16x16x32_bf16 v[32:35], v[184:187], v[206:209], v[32:35]
	v_mfma_f32_16x16x32_bf16 v[20:23], v[172:175], v[214:217], v[20:23]
	v_mfma_f32_16x16x32_bf16 v[16:19], v[184:187], v[214:217], v[16:19]
	v_mfma_f32_16x16x32_bf16 v[4:7], v[172:175], v[222:225], v[4:7]
	v_mfma_f32_16x16x32_bf16 v[0:3], v[184:187], v[222:225], v[0:3]
	s_setprio 0
	s_barrier
	s_add_i32 s82, 0, 0x18000
	s_add_i32 s83, 0, 0x1c000
	v_add_u32_e32 v164, s82, v150
	v_add_u32_e32 v179, s83, v150
	ds_read_b128 v[146:149], v164
	ds_read_b128 v[156:159], v164 offset:1024
	ds_read_b128 v[160:163], v164 offset:2048
	ds_read_b128 v[164:167], v164 offset:3072
	ds_read_b128 v[168:171], v179
	ds_read_b128 v[172:175], v179 offset:1024
	ds_read_b128 v[180:183], v179 offset:2048
	ds_read_b128 v[184:187], v179 offset:3072
	s_add_u32 s56, s56, 0x40000
	s_addc_u32 s57, s57, 0
	s_mov_b32 m0, s60
	v_lshl_add_u64 v[232:233], s[56:57], 0, v[134:135]
	ds_read_b128 v[188:191], v154 offset:32768
	ds_read_b128 v[192:195], v154 offset:33792
	ds_read_b128 v[196:199], v154 offset:34816
	ds_read_b128 v[206:209], v154 offset:35840
	ds_read_b128 v[210:213], v154 offset:36864
	ds_read_b128 v[214:217], v154 offset:37888
	ds_read_b128 v[218:221], v154 offset:38912
	ds_read_b128 v[222:225], v154 offset:39936
	global_load_lds_dwordx4 v[232:233], off
	v_lshl_add_u64 v[232:233], s[56:57], 0, v[130:131]
	s_mov_b32 m0, s61
	s_nop 0
	global_load_lds_dwordx4 v[232:233], off
	s_waitcnt vmcnt(8)
	s_waitcnt lgkmcnt(0)
	s_barrier
	s_setprio 1
	s_waitcnt lgkmcnt(0)
	v_mfma_f32_16x16x32_bf16 v[124:127], v[146:149], v[188:191], v[124:127]
	v_mfma_f32_16x16x32_bf16 v[120:123], v[160:163], v[188:191], v[120:123]
	v_mfma_f32_16x16x32_bf16 v[108:111], v[146:149], v[196:199], v[108:111]
	v_mfma_f32_16x16x32_bf16 v[104:107], v[160:163], v[196:199], v[104:107]
	v_mfma_f32_16x16x32_bf16 v[92:95], v[146:149], v[210:213], v[92:95]
	v_mfma_f32_16x16x32_bf16 v[88:91], v[160:163], v[210:213], v[88:91]
	v_mfma_f32_16x16x32_bf16 v[76:79], v[146:149], v[218:221], v[76:79]
	v_mfma_f32_16x16x32_bf16 v[72:75], v[160:163], v[218:221], v[72:75]
	v_mfma_f32_16x16x32_bf16 v[124:127], v[156:159], v[192:195], v[124:127]
	v_mfma_f32_16x16x32_bf16 v[120:123], v[164:167], v[192:195], v[120:123]
	v_mfma_f32_16x16x32_bf16 v[108:111], v[156:159], v[206:209], v[108:111]
	v_mfma_f32_16x16x32_bf16 v[104:107], v[164:167], v[206:209], v[104:107]
	v_mfma_f32_16x16x32_bf16 v[92:95], v[156:159], v[214:217], v[92:95]
	v_mfma_f32_16x16x32_bf16 v[88:91], v[164:167], v[214:217], v[88:91]
	v_mfma_f32_16x16x32_bf16 v[76:79], v[156:159], v[222:225], v[76:79]
	v_mfma_f32_16x16x32_bf16 v[72:75], v[164:167], v[222:225], v[72:75]
	s_setprio 0
	s_setprio 1
	v_mfma_f32_16x16x32_bf16 v[116:119], v[168:171], v[188:191], v[116:119]
	v_mfma_f32_16x16x32_bf16 v[112:115], v[180:183], v[188:191], v[112:115]
	v_mfma_f32_16x16x32_bf16 v[100:103], v[168:171], v[196:199], v[100:103]
	v_mfma_f32_16x16x32_bf16 v[96:99], v[180:183], v[196:199], v[96:99]
	v_mfma_f32_16x16x32_bf16 v[84:87], v[168:171], v[210:213], v[84:87]
	v_mfma_f32_16x16x32_bf16 v[80:83], v[180:183], v[210:213], v[80:83]
	v_mfma_f32_16x16x32_bf16 v[68:71], v[168:171], v[218:221], v[68:71]
	v_mfma_f32_16x16x32_bf16 v[64:67], v[180:183], v[218:221], v[64:67]
	v_mfma_f32_16x16x32_bf16 v[116:119], v[172:175], v[192:195], v[116:119]
	v_mfma_f32_16x16x32_bf16 v[112:115], v[184:187], v[192:195], v[112:115]
	v_mfma_f32_16x16x32_bf16 v[100:103], v[172:175], v[206:209], v[100:103]
	v_mfma_f32_16x16x32_bf16 v[96:99], v[184:187], v[206:209], v[96:99]
	v_mfma_f32_16x16x32_bf16 v[84:87], v[172:175], v[214:217], v[84:87]
	v_mfma_f32_16x16x32_bf16 v[80:83], v[184:187], v[214:217], v[80:83]
	v_mfma_f32_16x16x32_bf16 v[68:71], v[172:175], v[222:225], v[68:71]
	v_mfma_f32_16x16x32_bf16 v[64:67], v[184:187], v[222:225], v[64:67]
	s_setprio 0
	s_barrier
; #define PG8_STAGE(bufoff, gbase, voff) do { _Pragma("unroll") for (int _i = 0; _i < 2; ++_i) \
;         __builtin_amdgcn_global_load_lds((const unsigned*)((const char*)(gbase) + (voff)[_i]), (PG8_LAS unsigned*)(lds + (bufoff) + ldsw + _i * 8192), 16, 0, 0); } while (0)
; #define PG8_LDA(dst, b, h) do { _Pragma("unroll") for (int m = 0; m < 4; ++m) _Pragma("unroll") for (int k = 0; k < 2; ++k) dst[m][k] = *(const PG8_LAS bf16x8*)(lds + PG8_SA(b, h) + aoff + m * 2048 + k * 1024); } while (0)
; #define PG8_LDB(dst, b, h) do { _Pragma("unroll") for (int n = 0; n < 2; ++n) _Pragma("unroll") for (int k = 0; k < 2; ++k) dst[n][k] = *(const PG8_LAS bf16x8*)(lds + PG8_SB(b, h) + boff + n * 2048 + k * 1024); } while (0)
; #define PG8_MMA(ai, bj, At, Bt) do { __builtin_amdgcn_s_setprio(1); _Pragma("unroll") for (int m = 0; m < 4; ++m) _Pragma("unroll") for (int n = 0; n < 2; ++n) _Pragma("unroll") for (int k = 0; k < 2; ++k) \
;         acc[ai][bj][m][n] = __builtin_amdgcn_mfma_f32_16x16x32_bf16(Bt[n][k], At[m][k], acc[ai][bj][m][n], 0, 0, 0); __builtin_amdgcn_s_setprio(0); } while (0)
; #define PG8_WAIT_V(n) asm volatile("s_waitcnt vmcnt(" #n ")" ::: "memory")
; #define PG8_WAIT_L(n) asm volatile("s_waitcnt lgkmcnt(" #n ")" ::: "memory")
; #define PG8_BAR __builtin_amdgcn_s_barrier()
; #define PG8_SCHED __builtin_amdgcn_sched_barrier(0)
; template <class Epi, class Sched, bool ALIGN_EPI = false, bool SP2 = false>
; __device__ __forceinline__ void gemm_phase(PG8_LAS unsigned char* lds, const Gemm g, const Sched& S, const Epi& E) {
;     ...
;             PG8_LDB(B0, 0, 0); PG8_LDB(B1, 0, 1); PG8_SCHED; PG8_LDA(At, 0, 0); PG8_STAGE(PG8_SA(1, 1), a1 + hstep, voffA);
;             PG8_WAIT_V(8); PG8_WAIT_L(0); PG8_BAR; PG8_MMA(0, 0, At, B0); PG8_MMA(0, 1, At, B1); PG8_BAR; PG8_SCHED;
;     ...
;             PG8_LDA(At, 1, 1); PG8_STAGE(PG8_SB(1, 0), b3, voffB); PG8_STAGE(PG8_SB(1, 1), b3 + hstep, voffB); PG8_STAGE(PG8_SA(1, 0), a3, voffA);
;             PG8_WAIT_V(8); PG8_WAIT_L(0); PG8_BAR; PG8_MMA(1, 0, At, B0); PG8_MMA(1, 1, At, B1); PG8_BAR; PG8_SCHED;
	s_add_i32 s56, s82, s34
	v_lshl_add_u64 v[200:201], v[200:201], 0, s[26:27]
	s_mov_b32 m0, s56
	ds_read_b128 v[188:191], v154 offset:49152
	ds_read_b128 v[192:195], v154 offset:50176
	ds_read_b128 v[196:199], v154 offset:51200
	ds_read_b128 v[206:209], v154 offset:52224
	ds_read_b128 v[210:213], v154 offset:53248
	ds_read_b128 v[214:217], v154 offset:54272
	ds_read_b128 v[218:221], v154 offset:55296
	ds_read_b128 v[222:225], v154 offset:56320
	global_load_lds_dwordx4 v[200:201], off
	s_add_i32 m0, s56, 0x2000
	s_add_u32 s54, s54, 0x40080
	v_lshl_add_u64 v[200:201], v[226:227], 0, s[26:27]
	s_addc_u32 s55, s55, 0
	s_add_i32 s56, s83, s34
	global_load_lds_dwordx4 v[200:201], off
	v_lshl_add_u64 v[200:201], s[54:55], 0, v[132:133]
	s_mov_b32 m0, s56
	s_nop 0
	global_load_lds_dwordx4 v[200:201], off
	v_lshl_add_u64 v[200:201], s[54:55], 0, v[128:129]
	s_add_i32 m0, s56, 0x2000
	s_nop 0
	global_load_lds_dwordx4 v[200:201], off
	s_waitcnt vmcnt(6)
	s_waitcnt lgkmcnt(0)
	s_barrier
	s_setprio 1
	s_waitcnt lgkmcnt(0)
	v_mfma_f32_16x16x32_bf16 v[60:63], v[146:149], v[188:191], v[60:63]
	v_mfma_f32_16x16x32_bf16 v[56:59], v[160:163], v[188:191], v[56:59]
	v_mfma_f32_16x16x32_bf16 v[44:47], v[146:149], v[196:199], v[44:47]
	v_mfma_f32_16x16x32_bf16 v[40:43], v[160:163], v[196:199], v[40:43]
	v_mfma_f32_16x16x32_bf16 v[28:31], v[146:149], v[210:213], v[28:31]
	v_mfma_f32_16x16x32_bf16 v[24:27], v[160:163], v[210:213], v[24:27]
	v_lshl_add_u64 v[200:201], v[228:229], 0, s[26:27]
	s_mov_b32 m0, s63
	s_nop 0
	global_load_lds_dwordx4 v[200:201], off
	v_mfma_f32_16x16x32_bf16 v[12:15], v[146:149], v[218:221], v[12:15]
	v_mfma_f32_16x16x32_bf16 v[8:11], v[160:163], v[218:221], v[8:11]
	v_mfma_f32_16x16x32_bf16 v[60:63], v[156:159], v[192:195], v[60:63]
	v_mfma_f32_16x16x32_bf16 v[56:59], v[164:167], v[192:195], v[56:59]
	v_mfma_f32_16x16x32_bf16 v[44:47], v[156:159], v[206:209], v[44:47]
	v_mfma_f32_16x16x32_bf16 v[40:43], v[164:167], v[206:209], v[40:43]
	v_mfma_f32_16x16x32_bf16 v[28:31], v[156:159], v[214:217], v[28:31]
	v_mfma_f32_16x16x32_bf16 v[24:27], v[164:167], v[214:217], v[24:27]
	v_mfma_f32_16x16x32_bf16 v[12:15], v[156:159], v[222:225], v[12:15]
	v_mfma_f32_16x16x32_bf16 v[8:11], v[164:167], v[222:225], v[8:11]
	s_setprio 0
	s_setprio 1
	v_mfma_f32_16x16x32_bf16 v[52:55], v[168:171], v[188:191], v[52:55]
	v_mfma_f32_16x16x32_bf16 v[48:51], v[180:183], v[188:191], v[48:51]
	v_lshl_add_u64 v[200:201], v[230:231], 0, s[26:27]
	s_mov_b32 m0, s64
	s_nop 0
	global_load_lds_dwordx4 v[200:201], off
	v_mfma_f32_16x16x32_bf16 v[36:39], v[168:171], v[196:199], v[36:39]
	v_mfma_f32_16x16x32_bf16 v[32:35], v[180:183], v[196:199], v[32:35]
	v_mfma_f32_16x16x32_bf16 v[20:23], v[168:171], v[210:213], v[20:23]
	v_mfma_f32_16x16x32_bf16 v[16:19], v[180:183], v[210:213], v[16:19]
	v_mfma_f32_16x16x32_bf16 v[4:7], v[168:171], v[218:221], v[4:7]
	v_mfma_f32_16x16x32_bf16 v[0:3], v[180:183], v[218:221], v[0:3]
	v_mfma_f32_16x16x32_bf16 v[52:55], v[172:175], v[192:195], v[52:55]
	v_mfma_f32_16x16x32_bf16 v[48:51], v[184:187], v[192:195], v[48:51]
	v_mfma_f32_16x16x32_bf16 v[36:39], v[172:175], v[206:209], v[36:39]
	v_mfma_f32_16x16x32_bf16 v[32:35], v[184:187], v[206:209], v[32:35]
	v_mfma_f32_16x16x32_bf16 v[20:23], v[172:175], v[214:217], v[20:23]
	v_mfma_f32_16x16x32_bf16 v[16:19], v[184:187], v[214:217], v[16:19]
	v_mfma_f32_16x16x32_bf16 v[4:7], v[172:175], v[222:225], v[4:7]
	v_mfma_f32_16x16x32_bf16 v[0:3], v[184:187], v[222:225], v[0:3]
	s_setprio 0
	s_barrier
	s_add_i32 s81, s81, 2
	s_add_u32 s52, s52, 0x100
	s_addc_u32 s53, s53, 0
	s_add_u32 s79, s79, 0x100
	s_addc_u32 s80, s80, 0
.LBB0_1681:
	ds_read_b128 v[146:149], v152
	ds_read_b128 v[156:159], v152 offset:1024
	ds_read_b128 v[160:163], v152 offset:2048
	ds_read_b128 v[164:167], v152 offset:3072
	ds_read_b128 v[168:171], v153
	ds_read_b128 v[172:175], v153 offset:1024
	ds_read_b128 v[180:183], v153 offset:2048
	ds_read_b128 v[184:187], v153 offset:3072
	s_add_u32 s54, s52, 0xfffc0080
	s_addc_u32 s55, s53, -1
	s_cmp_eq_u32 s81, 12
	s_cselect_b32 s57, s47, s55
	s_cselect_b32 s56, s77, s54
	s_cselect_b32 s55, s45, s80
	s_cselect_b32 s54, s78, s79
	v_lshl_add_u64 v[200:201], s[52:53], 0, v[136:137]
	s_add_i32 m0, s58, 0xc000
	ds_read_b128 v[188:191], v154
	ds_read_b128 v[192:195], v154 offset:1024
	ds_read_b128 v[196:199], v154 offset:2048
	ds_read_b128 v[206:209], v154 offset:3072
	ds_read_b128 v[210:213], v154 offset:4096
	ds_read_b128 v[214:217], v154 offset:5120
	ds_read_b128 v[218:221], v154 offset:6144
	ds_read_b128 v[222:225], v154 offset:7168
	global_load_lds_dwordx4 v[200:201], off
	v_lshl_add_u64 v[200:201], s[52:53], 0, v[138:139]
	s_add_i32 m0, s58, 0xe000
	s_nop 0
	global_load_lds_dwordx4 v[200:201], off
	s_waitcnt vmcnt(8)
	s_waitcnt lgkmcnt(0)
	s_barrier
; #define PG8_STAGE(bufoff, gbase, voff) do { _Pragma("unroll") for (int _i = 0; _i < 2; ++_i) \
;         __builtin_amdgcn_global_load_lds((const unsigned*)((const char*)(gbase) + (voff)[_i]), (PG8_LAS unsigned*)(lds + (bufoff) + ldsw + _i * 8192), 16, 0, 0); } while (0)
; #define PG8_LDA(dst, b, h) do { _Pragma("unroll") for (int m = 0; m < 4; ++m) _Pragma("unroll") for (int k = 0; k < 2; ++k) dst[m][k] = *(const PG8_LAS bf16x8*)(lds + PG8_SA(b, h) + aoff + m * 2048 + k * 1024); } while (0)
; #define PG8_LDB(dst, b, h) do { _Pragma("unroll") for (int n = 0; n < 2; ++n) _Pragma("unroll") for (int k = 0; k < 2; ++k) dst[n][k] = *(const PG8_LAS bf16x8*)(lds + PG8_SB(b, h) + boff + n * 2048 + k * 1024); } while (0)
; #define PG8_MMA(ai, bj, At, Bt) do { __builtin_amdgcn_s_setprio(1); _Pragma("unroll") for (int m = 0; m < 4; ++m) _Pragma("unroll") for (int n = 0; n < 2; ++n) _Pragma("unroll") for (int k = 0; k < 2; ++k) \
;         acc[ai][bj][m][n] = __builtin_amdgcn_mfma_f32_16x16x32_bf16(Bt[n][k], At[m][k], acc[ai][bj][m][n], 0, 0, 0); __builtin_amdgcn_s_setprio(0); } while (0)
; #define PG8_WAIT_V(n) asm volatile("s_waitcnt vmcnt(" #n ")" ::: "memory")
; #define PG8_WAIT_L(n) asm volatile("s_waitcnt lgkmcnt(" #n ")" ::: "memory")
; #define PG8_BAR __builtin_amdgcn_s_barrier()
; #define PG8_SCHED __builtin_amdgcn_sched_barrier(0)
; template <class Epi, class Sched, bool ALIGN_EPI = false, bool SP2 = false>
; __device__ __forceinline__ void gemm_phase(PG8_LAS unsigned char* lds, const Gemm g, const Sched& S, const Epi& E) {
;     ...
;             PG8_LDB(B0, 0, 0); PG8_LDB(B1, 0, 1); PG8_SCHED; PG8_LDA(At, 0, 0); PG8_STAGE(PG8_SA(1, 1), a1 + hstep, voffA);
;             PG8_WAIT_V(8); PG8_WAIT_L(0); PG8_BAR; PG8_MMA(0, 0, At, B0); PG8_MMA(0, 1, At, B1); PG8_BAR; PG8_SCHED;
;             PG8_LDA(At, 0, 1); PG8_STAGE(PG8_SB(0, 0), b2, voffB); PG8_STAGE(PG8_SB(0, 1), b2 + hstep, voffB); PG8_STAGE(PG8_SA(0, 0), a2, voffA);
;             PG8_WAIT_V(8); PG8_WAIT_L(0); PG8_BAR; PG8_MMA(1, 0, At, B0); PG8_MMA(1, 1, At, B1); PG8_BAR; PG8_SCHED;
	s_setprio 1
	s_waitcnt lgkmcnt(0)
	v_mfma_f32_16x16x32_bf16 v[124:127], v[146:149], v[188:191], v[124:127]
	v_mfma_f32_16x16x32_bf16 v[120:123], v[160:163], v[188:191], v[120:123]
	v_mfma_f32_16x16x32_bf16 v[108:111], v[146:149], v[196:199], v[108:111]
	v_mfma_f32_16x16x32_bf16 v[104:107], v[160:163], v[196:199], v[104:107]
	v_mfma_f32_16x16x32_bf16 v[92:95], v[146:149], v[210:213], v[92:95]
	v_mfma_f32_16x16x32_bf16 v[88:91], v[160:163], v[210:213], v[88:91]
	v_mfma_f32_16x16x32_bf16 v[76:79], v[146:149], v[218:221], v[76:79]
	v_mfma_f32_16x16x32_bf16 v[72:75], v[160:163], v[218:221], v[72:75]
	v_mfma_f32_16x16x32_bf16 v[124:127], v[156:159], v[192:195], v[124:127]
	v_mfma_f32_16x16x32_bf16 v[120:123], v[164:167], v[192:195], v[120:123]
	v_mfma_f32_16x16x32_bf16 v[108:111], v[156:159], v[206:209], v[108:111]
	v_mfma_f32_16x16x32_bf16 v[104:107], v[164:167], v[206:209], v[104:107]
	v_mfma_f32_16x16x32_bf16 v[92:95], v[156:159], v[214:217], v[92:95]
	v_mfma_f32_16x16x32_bf16 v[88:91], v[164:167], v[214:217], v[88:91]
	v_mfma_f32_16x16x32_bf16 v[76:79], v[156:159], v[222:225], v[76:79]
	v_mfma_f32_16x16x32_bf16 v[72:75], v[164:167], v[222:225], v[72:75]
	s_setprio 0
	s_setprio 1
	v_mfma_f32_16x16x32_bf16 v[116:119], v[168:171], v[188:191], v[116:119]
	v_mfma_f32_16x16x32_bf16 v[112:115], v[180:183], v[188:191], v[112:115]
	v_mfma_f32_16x16x32_bf16 v[100:103], v[168:171], v[196:199], v[100:103]
	v_mfma_f32_16x16x32_bf16 v[96:99], v[180:183], v[196:199], v[96:99]
	v_mfma_f32_16x16x32_bf16 v[84:87], v[168:171], v[210:213], v[84:87]
	v_mfma_f32_16x16x32_bf16 v[80:83], v[180:183], v[210:213], v[80:83]
	v_mfma_f32_16x16x32_bf16 v[68:71], v[168:171], v[218:221], v[68:71]
	v_mfma_f32_16x16x32_bf16 v[64:67], v[180:183], v[218:221], v[64:67]
	v_mfma_f32_16x16x32_bf16 v[116:119], v[172:175], v[192:195], v[116:119]
	v_mfma_f32_16x16x32_bf16 v[112:115], v[184:187], v[192:195], v[112:115]
	v_mfma_f32_16x16x32_bf16 v[100:103], v[172:175], v[206:209], v[100:103]
	v_mfma_f32_16x16x32_bf16 v[96:99], v[184:187], v[206:209], v[96:99]
	v_mfma_f32_16x16x32_bf16 v[84:87], v[172:175], v[214:217], v[84:87]
	v_mfma_f32_16x16x32_bf16 v[80:83], v[184:187], v[214:217], v[80:83]
	v_mfma_f32_16x16x32_bf16 v[68:71], v[172:175], v[222:225], v[68:71]
	v_mfma_f32_16x16x32_bf16 v[64:67], v[184:187], v[222:225], v[64:67]
	s_setprio 0
	s_barrier
	s_add_i32 s82, s65, s34
	v_lshl_add_u64 v[200:201], s[54:55], 0, v[132:133]
	s_mov_b32 m0, s82
	ds_read_b128 v[188:191], v154 offset:16384
	ds_read_b128 v[192:195], v154 offset:17408
	ds_read_b128 v[196:199], v154 offset:18432
	ds_read_b128 v[206:209], v154 offset:19456
	ds_read_b128 v[210:213], v154 offset:20480
	ds_read_b128 v[214:217], v154 offset:21504
	ds_read_b128 v[218:221], v154 offset:22528
	ds_read_b128 v[222:225], v154 offset:23552
	global_load_lds_dwordx4 v[200:201], off
	s_add_i32 m0, s82, 0x2000
	s_add_u32 s82, s54, 0x40000
	v_lshl_add_u64 v[226:227], s[54:55], 0, v[128:129]
	s_addc_u32 s83, s55, 0
	s_add_i32 s84, s66, s34
	global_load_lds_dwordx4 v[226:227], off
	v_lshl_add_u64 v[228:229], s[82:83], 0, v[132:133]
	s_mov_b32 m0, s84
	v_lshl_add_u64 v[230:231], s[56:57], 0, v[130:131]
	global_load_lds_dwordx4 v[228:229], off
	v_lshl_add_u64 v[228:229], s[82:83], 0, v[128:129]
	s_add_i32 m0, s84, 0x2000
	s_nop 0
	global_load_lds_dwordx4 v[228:229], off
	s_waitcnt vmcnt(6)
	s_waitcnt lgkmcnt(0)
	s_barrier
	s_setprio 1
	s_waitcnt lgkmcnt(0)
	v_mfma_f32_16x16x32_bf16 v[60:63], v[146:149], v[188:191], v[60:63]
	v_mfma_f32_16x16x32_bf16 v[56:59], v[160:163], v[188:191], v[56:59]
	v_mfma_f32_16x16x32_bf16 v[44:47], v[146:149], v[196:199], v[44:47]
	v_mfma_f32_16x16x32_bf16 v[40:43], v[160:163], v[196:199], v[40:43]
	v_mfma_f32_16x16x32_bf16 v[28:31], v[146:149], v[210:213], v[28:31]
	v_mfma_f32_16x16x32_bf16 v[24:27], v[160:163], v[210:213], v[24:27]
	v_lshl_add_u64 v[228:229], s[56:57], 0, v[134:135]
	s_mov_b32 m0, s58
	s_nop 0
	global_load_lds_dwordx4 v[228:229], off
	v_mfma_f32_16x16x32_bf16 v[12:15], v[146:149], v[218:221], v[12:15]
	v_mfma_f32_16x16x32_bf16 v[8:11], v[160:163], v[218:221], v[8:11]
	v_mfma_f32_16x16x32_bf16 v[60:63], v[156:159], v[192:195], v[60:63]
	v_mfma_f32_16x16x32_bf16 v[56:59], v[164:167], v[192:195], v[56:59]
	v_mfma_f32_16x16x32_bf16 v[44:47], v[156:159], v[206:209], v[44:47]
	v_mfma_f32_16x16x32_bf16 v[40:43], v[164:167], v[206:209], v[40:43]
	v_mfma_f32_16x16x32_bf16 v[28:31], v[156:159], v[214:217], v[28:31]
	v_mfma_f32_16x16x32_bf16 v[24:27], v[164:167], v[214:217], v[24:27]
	v_mfma_f32_16x16x32_bf16 v[12:15], v[156:159], v[222:225], v[12:15]
	v_mfma_f32_16x16x32_bf16 v[8:11], v[164:167], v[222:225], v[8:11]
	s_setprio 0
	s_setprio 1
	v_mfma_f32_16x16x32_bf16 v[52:55], v[168:171], v[188:191], v[52:55]
	v_mfma_f32_16x16x32_bf16 v[48:51], v[180:183], v[188:191], v[48:51]
	s_mov_b32 m0, s59
	s_nop 0
	global_load_lds_dwordx4 v[230:231], off
	v_mfma_f32_16x16x32_bf16 v[36:39], v[168:171], v[196:199], v[36:39]
	v_mfma_f32_16x16x32_bf16 v[32:35], v[180:183], v[196:199], v[32:35]
	v_mfma_f32_16x16x32_bf16 v[20:23], v[168:171], v[210:213], v[20:23]
	v_mfma_f32_16x16x32_bf16 v[16:19], v[180:183], v[210:213], v[16:19]
	v_mfma_f32_16x16x32_bf16 v[4:7], v[168:171], v[218:221], v[4:7]
	v_mfma_f32_16x16x32_bf16 v[0:3], v[180:183], v[218:221], v[0:3]
	v_mfma_f32_16x16x32_bf16 v[52:55], v[172:175], v[192:195], v[52:55]
	v_mfma_f32_16x16x32_bf16 v[48:51], v[184:187], v[192:195], v[48:51]
	v_mfma_f32_16x16x32_bf16 v[36:39], v[172:175], v[206:209], v[36:39]
	v_mfma_f32_16x16x32_bf16 v[32:35], v[184:187], v[206:209], v[32:35]
	v_mfma_f32_16x16x32_bf16 v[20:23], v[172:175], v[214:217], v[20:23]
	v_mfma_f32_16x16x32_bf16 v[16:19], v[184:187], v[214:217], v[16:19]
	v_mfma_f32_16x16x32_bf16 v[4:7], v[172:175], v[222:225], v[4:7]
	v_mfma_f32_16x16x32_bf16 v[0:3], v[184:187], v[222:225], v[0:3]
	s_setprio 0
	s_barrier
; #define PG8_STAGE(bufoff, gbase, voff) do { _Pragma("unroll") for (int _i = 0; _i < 2; ++_i) \
;         __builtin_amdgcn_global_load_lds((const unsigned*)((const char*)(gbase) + (voff)[_i]), (PG8_LAS unsigned*)(lds + (bufoff) + ldsw + _i * 8192), 16, 0, 0); } while (0)
; #define PG8_LDA(dst, b, h) do { _Pragma("unroll") for (int m = 0; m < 4; ++m) _Pragma("unroll") for (int k = 0; k < 2; ++k) dst[m][k] = *(const PG8_LAS bf16x8*)(lds + PG8_SA(b, h) + aoff + m * 2048 + k * 1024); } while (0)
; #define PG8_LDB(dst, b, h) do { _Pragma("unroll") for (int n = 0; n < 2; ++n) _Pragma("unroll") for (int k = 0; k < 2; ++k) dst[n][k] = *(const PG8_LAS bf16x8*)(lds + PG8_SB(b, h) + boff + n * 2048 + k * 1024); } while (0)
; #define PG8_MMA(ai, bj, At, Bt) do { __builtin_amdgcn_s_setprio(1); _Pragma("unroll") for (int m = 0; m < 4; ++m) _Pragma("unroll") for (int n = 0; n < 2; ++n) _Pragma("unroll") for (int k = 0; k < 2; ++k) \
;         acc[ai][bj][m][n] = __builtin_amdgcn_mfma_f32_16x16x32_bf16(Bt[n][k], At[m][k], acc[ai][bj][m][n], 0, 0, 0); __builtin_amdgcn_s_setprio(0); } while (0)
; #define PG8_WAIT_V(n) asm volatile("s_waitcnt vmcnt(" #n ")" ::: "memory")
; #define PG8_WAIT_L(n) asm volatile("s_waitcnt lgkmcnt(" #n ")" ::: "memory")
; #define PG8_BAR __builtin_amdgcn_s_barrier()
; #define PG8_SCHED __builtin_amdgcn_sched_barrier(0)
; template <class Epi, class Sched, bool ALIGN_EPI = false, bool SP2 = false>
; __device__ __forceinline__ void gemm_phase(PG8_LAS unsigned char* lds, const Gemm g, const Sched& S, const Epi& E) {
;     ...
;             PG8_LDB(B0, 1, 0); PG8_LDB(B1, 1, 1); PG8_SCHED; PG8_LDA(At, 1, 0); PG8_STAGE(PG8_SA(0, 1), a2 + hstep, voffA);
;             PG8_WAIT_V(8); PG8_WAIT_L(0); PG8_BAR; PG8_MMA(0, 0, At, B0); PG8_MMA(0, 1, At, B1); PG8_BAR; PG8_SCHED;
	s_add_i32 s82, 0, 0x18000
	s_add_i32 s83, 0, 0x1c000
	v_add_u32_e32 v164, s82, v150
	v_add_u32_e32 v179, s83, v150
	ds_read_b128 v[146:149], v164
	ds_read_b128 v[156:159], v164 offset:1024
	ds_read_b128 v[160:163], v164 offset:2048
	ds_read_b128 v[164:167], v164 offset:3072
	ds_read_b128 v[168:171], v179
	ds_read_b128 v[172:175], v179 offset:1024
	ds_read_b128 v[180:183], v179 offset:2048
	ds_read_b128 v[184:187], v179 offset:3072
	s_add_u32 s56, s56, 0x40000
	s_addc_u32 s57, s57, 0
	s_mov_b32 m0, s60
	v_lshl_add_u64 v[232:233], s[56:57], 0, v[134:135]
	ds_read_b128 v[188:191], v154 offset:32768
	ds_read_b128 v[192:195], v154 offset:33792
	ds_read_b128 v[196:199], v154 offset:34816
	ds_read_b128 v[206:209], v154 offset:35840
	ds_read_b128 v[210:213], v154 offset:36864
	ds_read_b128 v[214:217], v154 offset:37888
	ds_read_b128 v[218:221], v154 offset:38912
	ds_read_b128 v[222:225], v154 offset:39936
	global_load_lds_dwordx4 v[232:233], off
	v_lshl_add_u64 v[232:233], s[56:57], 0, v[130:131]
	s_mov_b32 m0, s61
	s_nop 0
	global_load_lds_dwordx4 v[232:233], off
	s_waitcnt vmcnt(8)
	s_waitcnt lgkmcnt(0)
	s_barrier
	s_setprio 1
	s_waitcnt lgkmcnt(0)
	v_mfma_f32_16x16x32_bf16 v[124:127], v[146:149], v[188:191], v[124:127]
	v_mfma_f32_16x16x32_bf16 v[120:123], v[160:163], v[188:191], v[120:123]
	v_mfma_f32_16x16x32_bf16 v[108:111], v[146:149], v[196:199], v[108:111]
	v_mfma_f32_16x16x32_bf16 v[104:107], v[160:163], v[196:199], v[104:107]
	v_mfma_f32_16x16x32_bf16 v[92:95], v[146:149], v[210:213], v[92:95]
	v_mfma_f32_16x16x32_bf16 v[88:91], v[160:163], v[210:213], v[88:91]
	v_mfma_f32_16x16x32_bf16 v[76:79], v[146:149], v[218:221], v[76:79]
	v_mfma_f32_16x16x32_bf16 v[72:75], v[160:163], v[218:221], v[72:75]
	v_mfma_f32_16x16x32_bf16 v[124:127], v[156:159], v[192:195], v[124:127]
	v_mfma_f32_16x16x32_bf16 v[120:123], v[164:167], v[192:195], v[120:123]
	v_mfma_f32_16x16x32_bf16 v[108:111], v[156:159], v[206:209], v[108:111]
	v_mfma_f32_16x16x32_bf16 v[104:107], v[164:167], v[206:209], v[104:107]
	v_mfma_f32_16x16x32_bf16 v[92:95], v[156:159], v[214:217], v[92:95]
	v_mfma_f32_16x16x32_bf16 v[88:91], v[164:167], v[214:217], v[88:91]
	v_mfma_f32_16x16x32_bf16 v[76:79], v[156:159], v[222:225], v[76:79]
	v_mfma_f32_16x16x32_bf16 v[72:75], v[164:167], v[222:225], v[72:75]
	s_setprio 0
	s_setprio 1
	v_mfma_f32_16x16x32_bf16 v[116:119], v[168:171], v[188:191], v[116:119]
	v_mfma_f32_16x16x32_bf16 v[112:115], v[180:183], v[188:191], v[112:115]
	v_mfma_f32_16x16x32_bf16 v[100:103], v[168:171], v[196:199], v[100:103]
	v_mfma_f32_16x16x32_bf16 v[96:99], v[180:183], v[196:199], v[96:99]
	v_mfma_f32_16x16x32_bf16 v[84:87], v[168:171], v[210:213], v[84:87]
	v_mfma_f32_16x16x32_bf16 v[80:83], v[180:183], v[210:213], v[80:83]
	v_mfma_f32_16x16x32_bf16 v[68:71], v[168:171], v[218:221], v[68:71]
	v_mfma_f32_16x16x32_bf16 v[64:67], v[180:183], v[218:221], v[64:67]
	v_mfma_f32_16x16x32_bf16 v[116:119], v[172:175], v[192:195], v[116:119]
	v_mfma_f32_16x16x32_bf16 v[112:115], v[184:187], v[192:195], v[112:115]
	v_mfma_f32_16x16x32_bf16 v[100:103], v[172:175], v[206:209], v[100:103]
	v_mfma_f32_16x16x32_bf16 v[96:99], v[184:187], v[206:209], v[96:99]
	v_mfma_f32_16x16x32_bf16 v[84:87], v[172:175], v[214:217], v[84:87]
	v_mfma_f32_16x16x32_bf16 v[80:83], v[184:187], v[214:217], v[80:83]
	v_mfma_f32_16x16x32_bf16 v[68:71], v[172:175], v[222:225], v[68:71]
	v_mfma_f32_16x16x32_bf16 v[64:67], v[184:187], v[222:225], v[64:67]
	s_setprio 0
	s_barrier
; #define PG8_STAGE(bufoff, gbase, voff) do { _Pragma("unroll") for (int _i = 0; _i < 2; ++_i) \
;         __builtin_amdgcn_global_load_lds((const unsigned*)((const char*)(gbase) + (voff)[_i]), (PG8_LAS unsigned*)(lds + (bufoff) + ldsw + _i * 8192), 16, 0, 0); } while (0)
; #define PG8_LDA(dst, b, h) do { _Pragma("unroll") for (int m = 0; m < 4; ++m) _Pragma("unroll") for (int k = 0; k < 2; ++k) dst[m][k] = *(const PG8_LAS bf16x8*)(lds + PG8_SA(b, h) + aoff + m * 2048 + k * 1024); } while (0)
; #define PG8_MMA(ai, bj, At, Bt) do { __builtin_amdgcn_s_setprio(1); _Pragma("unroll") for (int m = 0; m < 4; ++m) _Pragma("unroll") for (int n = 0; n < 2; ++n) _Pragma("unroll") for (int k = 0; k < 2; ++k) \
;         acc[ai][bj][m][n] = __builtin_amdgcn_mfma_f32_16x16x32_bf16(Bt[n][k], At[m][k], acc[ai][bj][m][n], 0, 0, 0); __builtin_amdgcn_s_setprio(0); } while (0)
; #define PG8_WAIT_V(n) asm volatile("s_waitcnt vmcnt(" #n ")" ::: "memory")
; #define PG8_WAIT_L(n) asm volatile("s_waitcnt lgkmcnt(" #n ")" ::: "memory")
; #define PG8_BAR __builtin_amdgcn_s_barrier()
; #define PG8_SCHED __builtin_amdgcn_sched_barrier(0)
; template <class Epi, class Sched, bool ALIGN_EPI = false, bool SP2 = false>
; __device__ __forceinline__ void gemm_phase(PG8_LAS unsigned char* lds, const Gemm g, const Sched& S, const Epi& E) {
;     ...
;             PG8_LDA(At, 1, 1); PG8_STAGE(PG8_SB(1, 0), b3, voffB); PG8_STAGE(PG8_SB(1, 1), b3 + hstep, voffB); PG8_STAGE(PG8_SA(1, 0), a3, voffA);
;             PG8_WAIT_V(8); PG8_WAIT_L(0); PG8_BAR; PG8_MMA(1, 0, At, B0); PG8_MMA(1, 1, At, B1); PG8_BAR; PG8_SCHED;
	s_add_i32 s56, s82, s34
	v_lshl_add_u64 v[200:201], v[200:201], 0, s[26:27]
	s_mov_b32 m0, s56
	ds_read_b128 v[188:191], v154 offset:49152
	ds_read_b128 v[192:195], v154 offset:50176
	ds_read_b128 v[196:199], v154 offset:51200
	ds_read_b128 v[206:209], v154 offset:52224
	ds_read_b128 v[210:213], v154 offset:53248
	ds_read_b128 v[214:217], v154 offset:54272
	ds_read_b128 v[218:221], v154 offset:55296
	ds_read_b128 v[222:225], v154 offset:56320
	global_load_lds_dwordx4 v[200:201], off
	s_add_i32 m0, s56, 0x2000
	s_add_u32 s54, s54, 0x40080
	v_lshl_add_u64 v[200:201], v[226:227], 0, s[26:27]
	s_addc_u32 s55, s55, 0
	s_add_i32 s56, s83, s34
	global_load_lds_dwordx4 v[200:201], off
	v_lshl_add_u64 v[200:201], s[54:55], 0, v[132:133]
	s_mov_b32 m0, s56
	s_nop 0
	global_load_lds_dwordx4 v[200:201], off
	v_lshl_add_u64 v[200:201], s[54:55], 0, v[128:129]
	s_add_i32 m0, s56, 0x2000
	s_nop 0
	global_load_lds_dwordx4 v[200:201], off
	s_waitcnt vmcnt(6)
	s_waitcnt lgkmcnt(0)
	s_barrier
	s_setprio 1
	s_waitcnt lgkmcnt(0)
	v_mfma_f32_16x16x32_bf16 v[60:63], v[146:149], v[188:191], v[60:63]
	v_mfma_f32_16x16x32_bf16 v[56:59], v[160:163], v[188:191], v[56:59]
	v_mfma_f32_16x16x32_bf16 v[44:47], v[146:149], v[196:199], v[44:47]
	v_mfma_f32_16x16x32_bf16 v[40:43], v[160:163], v[196:199], v[40:43]
	v_mfma_f32_16x16x32_bf16 v[28:31], v[146:149], v[210:213], v[28:31]
	v_mfma_f32_16x16x32_bf16 v[24:27], v[160:163], v[210:213], v[24:27]
	v_lshl_add_u64 v[200:201], v[228:229], 0, s[26:27]
	s_mov_b32 m0, s63
	s_nop 0
	global_load_lds_dwordx4 v[200:201], off
	v_mfma_f32_16x16x32_bf16 v[12:15], v[146:149], v[218:221], v[12:15]
	v_mfma_f32_16x16x32_bf16 v[8:11], v[160:163], v[218:221], v[8:11]
	v_mfma_f32_16x16x32_bf16 v[60:63], v[156:159], v[192:195], v[60:63]
	v_mfma_f32_16x16x32_bf16 v[56:59], v[164:167], v[192:195], v[56:59]
	v_mfma_f32_16x16x32_bf16 v[44:47], v[156:159], v[206:209], v[44:47]
	v_mfma_f32_16x16x32_bf16 v[40:43], v[164:167], v[206:209], v[40:43]
	v_mfma_f32_16x16x32_bf16 v[28:31], v[156:159], v[214:217], v[28:31]
	v_mfma_f32_16x16x32_bf16 v[24:27], v[164:167], v[214:217], v[24:27]
	v_mfma_f32_16x16x32_bf16 v[12:15], v[156:159], v[222:225], v[12:15]
	v_mfma_f32_16x16x32_bf16 v[8:11], v[164:167], v[222:225], v[8:11]
	s_setprio 0
	s_setprio 1
	v_mfma_f32_16x16x32_bf16 v[52:55], v[168:171], v[188:191], v[52:55]
	v_mfma_f32_16x16x32_bf16 v[48:51], v[180:183], v[188:191], v[48:51]
	v_lshl_add_u64 v[200:201], v[230:231], 0, s[26:27]
	s_mov_b32 m0, s64
	s_nop 0
	global_load_lds_dwordx4 v[200:201], off
	v_mfma_f32_16x16x32_bf16 v[36:39], v[168:171], v[196:199], v[36:39]
	v_mfma_f32_16x16x32_bf16 v[32:35], v[180:183], v[196:199], v[32:35]
	v_mfma_f32_16x16x32_bf16 v[20:23], v[168:171], v[210:213], v[20:23]
	v_mfma_f32_16x16x32_bf16 v[16:19], v[180:183], v[210:213], v[16:19]
	v_mfma_f32_16x16x32_bf16 v[4:7], v[168:171], v[218:221], v[4:7]
	v_mfma_f32_16x16x32_bf16 v[0:3], v[180:183], v[218:221], v[0:3]
	v_mfma_f32_16x16x32_bf16 v[52:55], v[172:175], v[192:195], v[52:55]
	v_mfma_f32_16x16x32_bf16 v[48:51], v[184:187], v[192:195], v[48:51]
	v_mfma_f32_16x16x32_bf16 v[36:39], v[172:175], v[206:209], v[36:39]
	v_mfma_f32_16x16x32_bf16 v[32:35], v[184:187], v[206:209], v[32:35]
	v_mfma_f32_16x16x32_bf16 v[20:23], v[172:175], v[214:217], v[20:23]
	v_mfma_f32_16x16x32_bf16 v[16:19], v[184:187], v[214:217], v[16:19]
	v_mfma_f32_16x16x32_bf16 v[4:7], v[172:175], v[222:225], v[4:7]
	v_mfma_f32_16x16x32_bf16 v[0:3], v[184:187], v[222:225], v[0:3]
	s_setprio 0
	s_barrier
	s_add_i32 s81, s81, 2
	s_add_u32 s52, s52, 0x100
	s_addc_u32 s53, s53, 0
	s_add_u32 s79, s79, 0x100
	s_addc_u32 s80, s80, 0
	s_cmp_gt_u32 s81, 13
	s_cbranch_scc0 .LBB0_1681
	s_and_b64 vcc, exec, s[28:29]
	s_cbranch_vccz .LBB0_1684
	s_barrier

; #define PG8_STAGE(bufoff, gbase, voff) do { _Pragma("unroll") for (int _i = 0; _i < 2; ++_i) \
;         __builtin_amdgcn_global_load_lds((const unsigned*)((const char*)(gbase) + (voff)[_i]), (PG8_LAS unsigned*)(lds + (bufoff) + ldsw + _i * 8192), 16, 0, 0); } while (0)
; #define PG8_LDA(dst, b, h) do { _Pragma("unroll") for (int m = 0; m < 4; ++m) _Pragma("unroll") for (int k = 0; k < 2; ++k) dst[m][k] = *(const PG8_LAS bf16x8*)(lds + PG8_SA(b, h) + aoff + m * 2048 + k * 1024); } while (0)
; #define PG8_LDB(dst, b, h) do { _Pragma("unroll") for (int n = 0; n < 2; ++n) _Pragma("unroll") for (int k = 0; k < 2; ++k) dst[n][k] = *(const PG8_LAS bf16x8*)(lds + PG8_SB(b, h) + boff + n * 2048 + k * 1024); } while (0)
; #define PG8_MMA(ai, bj, At, Bt) do { __builtin_amdgcn_s_setprio(1); _Pragma("unroll") for (int m = 0; m < 4; ++m) _Pragma("unroll") for (int n = 0; n < 2; ++n) _Pragma("unroll") for (int k = 0; k < 2; ++k) \
;         acc[ai][bj][m][n] = __builtin_amdgcn_mfma_f32_16x16x32_bf16(Bt[n][k], At[m][k], acc[ai][bj][m][n], 0, 0, 0); __builtin_amdgcn_s_setprio(0); } while (0)
; #define PG8_BAR __builtin_amdgcn_s_barrier()
; template <class Epi, class Sched, bool ALIGN_EPI = false, bool SP2 = false>
; __device__ __forceinline__ void gemm_phase(PG8_LAS unsigned char* lds, const Gemm g, const Sched& S, const Epi& E) {
;     ...
;         const bool has_next = S.next(ui + 1, nxt);
;         const char* nA = has_next ? (const char*)g.A + (size_t)nxt.pm * tstep : cA; const char* nB = has_next ? (const char*)g.Bt + (size_t)nxt.pn * tstep : cB;
;         for (int t = 0; t < nt; t += 2) {
;             const bool last = (t == nt - 2);
;             const char* a1 = cA + (size_t)(t + 1) * kstep;
;             const char* a2 = last ? nA : cA + (size_t)(t + 2) * kstep; const char* b2 = last ? nB : cB + (size_t)(t + 2) * kstep;
;             const char* a3 = a2 + kstep; const char* b3 = b2 + kstep;
;             if (last && has_next) S.a_ready(nxt);
;             if constexpr (SP2) {
;             PG8_LDB(B0, 0, 0); PG8_LDB(B1, 0, 1); PG8_SCHED; PG8_LDA(At, 0, 0); PG8_STAGE(PG8_SA(1, 1), a1 + hstep, voffA);
;             PG8_WAIT_V(8); PG8_WAIT_L(0); PG8_BAR; PG8_MMA(0, 0, At, B0); PG8_MMA(0, 1, At, B1); PG8_BAR; PG8_SCHED;
;             PG8_LDA(At, 0, 1); PG8_STAGE(PG8_SB(0, 0), b2, voffB); PG8_STAGE(PG8_SB(0, 1), b2 + hstep, voffB); PG8_STAGE(PG8_SA(0, 0), a2, voffA);
.LBB0_1815:
	s_ashr_i32 s29, s28, 31
	s_lshl_b64 s[36:37], s[28:29], 18
	s_add_u32 s36, s92, s36
	s_addc_u32 s37, s93, s37
	s_and_b64 s[38:39], s[6:7], exec
	s_cselect_b32 s29, s37, s45
	s_cselect_b32 s41, s36, s44
	s_ashr_i32 s27, s26, 31
	s_lshl_b64 s[38:39], s[26:27], 18
	s_add_u32 s38, s3, s38
	s_addc_u32 s39, s14, s39
	s_and_b64 s[48:49], s[6:7], exec
	s_cselect_b32 s27, s39, s47
	s_cselect_b32 s58, s38, s46
	s_add_u32 s44, s44, 0x20080
	s_addc_u32 s45, s45, 0
	s_add_u32 s59, s46, 0x100
	s_addc_u32 s60, s47, 0
	s_mov_b32 s61, -2
	s_waitcnt lgkmcnt(0)
	ds_read_b128 v[144:147], v151
	ds_read_b128 v[156:159], v151 offset:1024
	ds_read_b128 v[160:163], v151 offset:2048
	ds_read_b128 v[164:167], v151 offset:3072
	ds_read_b128 v[168:171], v152
	ds_read_b128 v[172:175], v152 offset:1024
	ds_read_b128 v[176:179], v152 offset:2048
	ds_read_b128 v[180:183], v152 offset:3072
	s_add_u32 s46, s44, 0xfffe0080
	s_addc_u32 s47, s45, -1
	s_cmp_eq_u32 s61, 4
	s_cselect_b32 s49, s29, s47
	s_cselect_b32 s48, s41, s46
	s_cselect_b32 s47, s27, s60
	s_cselect_b32 s46, s58, s59
	v_lshl_add_u64 v[218:219], s[44:45], 0, v[136:137]
	s_add_i32 m0, s33, 0xc000
	ds_read_b128 v[184:187], v153
	ds_read_b128 v[188:191], v153 offset:1024
	ds_read_b128 v[192:195], v153 offset:2048
	ds_read_b128 v[196:199], v153 offset:3072
	ds_read_b128 v[200:203], v153 offset:4096
	ds_read_b128 v[206:209], v153 offset:5120
	ds_read_b128 v[210:213], v153 offset:6144
	ds_read_b128 v[214:217], v153 offset:7168
	global_load_lds_dwordx4 v[218:219], off
	v_lshl_add_u64 v[218:219], s[44:45], 0, v[138:139]
	s_add_i32 m0, s33, 0xe000
	s_nop 0
	global_load_lds_dwordx4 v[218:219], off
	s_waitcnt vmcnt(8)
	s_waitcnt lgkmcnt(0)
	s_barrier
	s_setprio 1
	s_waitcnt lgkmcnt(0)
	v_mfma_f32_16x16x32_bf16 v[124:127], v[144:147], v[184:187], 0
	v_mfma_f32_16x16x32_bf16 v[120:123], v[160:163], v[184:187], 0
	v_mfma_f32_16x16x32_bf16 v[108:111], v[144:147], v[192:195], 0
	v_mfma_f32_16x16x32_bf16 v[104:107], v[160:163], v[192:195], 0
	v_mfma_f32_16x16x32_bf16 v[92:95], v[144:147], v[200:203], 0
	v_mfma_f32_16x16x32_bf16 v[88:91], v[160:163], v[200:203], 0
	v_mfma_f32_16x16x32_bf16 v[76:79], v[144:147], v[210:213], 0
	v_mfma_f32_16x16x32_bf16 v[72:75], v[160:163], v[210:213], 0
	v_mfma_f32_16x16x32_bf16 v[124:127], v[156:159], v[188:191], v[124:127]
	v_mfma_f32_16x16x32_bf16 v[120:123], v[164:167], v[188:191], v[120:123]
	v_mfma_f32_16x16x32_bf16 v[108:111], v[156:159], v[196:199], v[108:111]
	v_mfma_f32_16x16x32_bf16 v[104:107], v[164:167], v[196:199], v[104:107]
	v_mfma_f32_16x16x32_bf16 v[92:95], v[156:159], v[206:209], v[92:95]
	v_mfma_f32_16x16x32_bf16 v[88:91], v[164:167], v[206:209], v[88:91]
	v_mfma_f32_16x16x32_bf16 v[76:79], v[156:159], v[214:217], v[76:79]
	v_mfma_f32_16x16x32_bf16 v[72:75], v[164:167], v[214:217], v[72:75]
	s_setprio 0
	s_setprio 1
	v_mfma_f32_16x16x32_bf16 v[116:119], v[168:171], v[184:187], 0
	v_mfma_f32_16x16x32_bf16 v[112:115], v[176:179], v[184:187], 0
	v_mfma_f32_16x16x32_bf16 v[100:103], v[168:171], v[192:195], 0
	v_mfma_f32_16x16x32_bf16 v[96:99], v[176:179], v[192:195], 0
	v_mfma_f32_16x16x32_bf16 v[84:87], v[168:171], v[200:203], 0
	v_mfma_f32_16x16x32_bf16 v[80:83], v[176:179], v[200:203], 0
	v_mfma_f32_16x16x32_bf16 v[68:71], v[168:171], v[210:213], 0
	v_mfma_f32_16x16x32_bf16 v[64:67], v[176:179], v[210:213], 0
	v_mfma_f32_16x16x32_bf16 v[116:119], v[172:175], v[188:191], v[116:119]
	v_mfma_f32_16x16x32_bf16 v[112:115], v[180:183], v[188:191], v[112:115]
	v_mfma_f32_16x16x32_bf16 v[100:103], v[172:175], v[196:199], v[100:103]
	v_mfma_f32_16x16x32_bf16 v[96:99], v[180:183], v[196:199], v[96:99]
	v_mfma_f32_16x16x32_bf16 v[84:87], v[172:175], v[206:209], v[84:87]
	v_mfma_f32_16x16x32_bf16 v[80:83], v[180:183], v[206:209], v[80:83]
	v_mfma_f32_16x16x32_bf16 v[68:71], v[172:175], v[214:217], v[68:71]
	v_mfma_f32_16x16x32_bf16 v[64:67], v[180:183], v[214:217], v[64:67]
	s_setprio 0
	s_barrier
	s_add_i32 s62, s54, s15
	v_lshl_add_u64 v[218:219], s[46:47], 0, v[130:131]
	s_mov_b32 m0, s62
	ds_read_b128 v[184:187], v153 offset:16384
	ds_read_b128 v[188:191], v153 offset:17408
	ds_read_b128 v[192:195], v153 offset:18432
	ds_read_b128 v[196:199], v153 offset:19456
	ds_read_b128 v[200:203], v153 offset:20480
	ds_read_b128 v[206:209], v153 offset:21504
	ds_read_b128 v[210:213], v153 offset:22528
	ds_read_b128 v[214:217], v153 offset:23552
	global_load_lds_dwordx4 v[218:219], off
	s_add_i32 m0, s62, 0x2000
	s_add_u32 s62, s46, 0x20000
	v_lshl_add_u64 v[220:221], s[46:47], 0, v[134:135]
	s_addc_u32 s63, s47, 0
	s_add_i32 s64, s55, s15
	global_load_lds_dwordx4 v[220:221], off
	v_lshl_add_u64 v[222:223], s[62:63], 0, v[130:131]
	s_mov_b32 m0, s64
	v_lshl_add_u64 v[224:225], s[48:49], 0, v[132:133]
	global_load_lds_dwordx4 v[222:223], off
	v_lshl_add_u64 v[222:223], s[62:63], 0, v[134:135]
	s_add_i32 m0, s64, 0x2000
	s_nop 0
	global_load_lds_dwordx4 v[222:223], off
	s_waitcnt vmcnt(6)
	s_waitcnt lgkmcnt(0)
	s_barrier
; #define PG8_STAGE(bufoff, gbase, voff) do { _Pragma("unroll") for (int _i = 0; _i < 2; ++_i) \
;         __builtin_amdgcn_global_load_lds((const unsigned*)((const char*)(gbase) + (voff)[_i]), (PG8_LAS unsigned*)(lds + (bufoff) + ldsw + _i * 8192), 16, 0, 0); } while (0)
; #define PG8_LDA(dst, b, h) do { _Pragma("unroll") for (int m = 0; m < 4; ++m) _Pragma("unroll") for (int k = 0; k < 2; ++k) dst[m][k] = *(const PG8_LAS bf16x8*)(lds + PG8_SA(b, h) + aoff + m * 2048 + k * 1024); } while (0)
; #define PG8_LDB(dst, b, h) do { _Pragma("unroll") for (int n = 0; n < 2; ++n) _Pragma("unroll") for (int k = 0; k < 2; ++k) dst[n][k] = *(const PG8_LAS bf16x8*)(lds + PG8_SB(b, h) + boff + n * 2048 + k * 1024); } while (0)
; #define PG8_MMA(ai, bj, At, Bt) do { __builtin_amdgcn_s_setprio(1); _Pragma("unroll") for (int m = 0; m < 4; ++m) _Pragma("unroll") for (int n = 0; n < 2; ++n) _Pragma("unroll") for (int k = 0; k < 2; ++k) \
;         acc[ai][bj][m][n] = __builtin_amdgcn_mfma_f32_16x16x32_bf16(Bt[n][k], At[m][k], acc[ai][bj][m][n], 0, 0, 0); __builtin_amdgcn_s_setprio(0); } while (0)
; #define PG8_WAIT_V(n) asm volatile("s_waitcnt vmcnt(" #n ")" ::: "memory")
; #define PG8_WAIT_L(n) asm volatile("s_waitcnt lgkmcnt(" #n ")" ::: "memory")
; #define PG8_BAR __builtin_amdgcn_s_barrier()
; #define PG8_SCHED __builtin_amdgcn_sched_barrier(0)
; template <class Epi, class Sched, bool ALIGN_EPI = false, bool SP2 = false>
; __device__ __forceinline__ void gemm_phase(PG8_LAS unsigned char* lds, const Gemm g, const Sched& S, const Epi& E) {
;     ...
;             PG8_WAIT_V(8); PG8_WAIT_L(0); PG8_BAR; PG8_MMA(1, 0, At, B0); PG8_MMA(1, 1, At, B1); PG8_BAR; PG8_SCHED;
;             PG8_LDB(B0, 1, 0); PG8_LDB(B1, 1, 1); PG8_SCHED; PG8_LDA(At, 1, 0); PG8_STAGE(PG8_SA(0, 1), a2 + hstep, voffA);
;             PG8_WAIT_V(8); PG8_WAIT_L(0); PG8_BAR; PG8_MMA(0, 0, At, B0); PG8_MMA(0, 1, At, B1); PG8_BAR; PG8_SCHED;
	s_setprio 1
	s_waitcnt lgkmcnt(0)
	v_mfma_f32_16x16x32_bf16 v[60:63], v[144:147], v[184:187], 0
	v_mfma_f32_16x16x32_bf16 v[56:59], v[160:163], v[184:187], 0
	v_mfma_f32_16x16x32_bf16 v[44:47], v[144:147], v[192:195], 0
	v_mfma_f32_16x16x32_bf16 v[40:43], v[160:163], v[192:195], 0
	v_mfma_f32_16x16x32_bf16 v[28:31], v[144:147], v[200:203], 0
	v_mfma_f32_16x16x32_bf16 v[24:27], v[160:163], v[200:203], 0
	v_lshl_add_u64 v[222:223], s[48:49], 0, v[128:129]
	s_mov_b32 m0, s33
	s_nop 0
	global_load_lds_dwordx4 v[222:223], off
	v_mfma_f32_16x16x32_bf16 v[12:15], v[144:147], v[210:213], 0
	v_mfma_f32_16x16x32_bf16 v[8:11], v[160:163], v[210:213], 0
	v_mfma_f32_16x16x32_bf16 v[60:63], v[156:159], v[188:191], v[60:63]
	v_mfma_f32_16x16x32_bf16 v[56:59], v[164:167], v[188:191], v[56:59]
	v_mfma_f32_16x16x32_bf16 v[44:47], v[156:159], v[196:199], v[44:47]
	v_mfma_f32_16x16x32_bf16 v[40:43], v[164:167], v[196:199], v[40:43]
	v_mfma_f32_16x16x32_bf16 v[28:31], v[156:159], v[206:209], v[28:31]
	v_mfma_f32_16x16x32_bf16 v[24:27], v[164:167], v[206:209], v[24:27]
	v_mfma_f32_16x16x32_bf16 v[12:15], v[156:159], v[214:217], v[12:15]
	v_mfma_f32_16x16x32_bf16 v[8:11], v[164:167], v[214:217], v[8:11]
	s_setprio 0
	s_setprio 1
	v_mfma_f32_16x16x32_bf16 v[52:55], v[168:171], v[184:187], 0
	v_mfma_f32_16x16x32_bf16 v[48:51], v[176:179], v[184:187], 0
	s_mov_b32 m0, s34
	s_nop 0
	global_load_lds_dwordx4 v[224:225], off
	v_mfma_f32_16x16x32_bf16 v[36:39], v[168:171], v[192:195], 0
	v_mfma_f32_16x16x32_bf16 v[32:35], v[176:179], v[192:195], 0
	v_mfma_f32_16x16x32_bf16 v[20:23], v[168:171], v[200:203], 0
	v_mfma_f32_16x16x32_bf16 v[16:19], v[176:179], v[200:203], 0
	v_mfma_f32_16x16x32_bf16 v[4:7], v[168:171], v[210:213], 0
	v_mfma_f32_16x16x32_bf16 v[0:3], v[176:179], v[210:213], 0
	v_mfma_f32_16x16x32_bf16 v[52:55], v[172:175], v[188:191], v[52:55]
	v_mfma_f32_16x16x32_bf16 v[48:51], v[180:183], v[188:191], v[48:51]
	v_mfma_f32_16x16x32_bf16 v[36:39], v[172:175], v[196:199], v[36:39]
	v_mfma_f32_16x16x32_bf16 v[32:35], v[180:183], v[196:199], v[32:35]
	v_mfma_f32_16x16x32_bf16 v[20:23], v[172:175], v[206:209], v[20:23]
	v_mfma_f32_16x16x32_bf16 v[16:19], v[180:183], v[206:209], v[16:19]
	v_mfma_f32_16x16x32_bf16 v[4:7], v[172:175], v[214:217], v[4:7]
	v_mfma_f32_16x16x32_bf16 v[0:3], v[180:183], v[214:217], v[0:3]
	s_setprio 0
	s_barrier
	s_add_i32 s62, 0, 0x18000
	v_add_u32_e32 v155, s62, v149
	s_add_i32 s63, 0, 0x1c000
	ds_read_b128 v[144:147], v155
	ds_read_b128 v[156:159], v155 offset:1024
	ds_read_b128 v[160:163], v155 offset:2048
	ds_read_b128 v[164:167], v155 offset:3072
	v_add_u32_e32 v155, s63, v149
	ds_read_b128 v[168:171], v155
	ds_read_b128 v[172:175], v155 offset:1024
	ds_read_b128 v[176:179], v155 offset:2048
	ds_read_b128 v[180:183], v155 offset:3072
	s_add_u32 s48, s48, 0x20000
	s_addc_u32 s49, s49, 0
	s_mov_b32 m0, s43
	v_lshl_add_u64 v[226:227], s[48:49], 0, v[128:129]
	ds_read_b128 v[184:187], v153 offset:32768
	ds_read_b128 v[188:191], v153 offset:33792
	ds_read_b128 v[192:195], v153 offset:34816
	ds_read_b128 v[196:199], v153 offset:35840
	ds_read_b128 v[200:203], v153 offset:36864
	ds_read_b128 v[206:209], v153 offset:37888
	ds_read_b128 v[210:213], v153 offset:38912
	ds_read_b128 v[214:217], v153 offset:39936
	global_load_lds_dwordx4 v[226:227], off
	v_lshl_add_u64 v[226:227], s[48:49], 0, v[132:133]
	s_mov_b32 m0, s50
	s_nop 0
	global_load_lds_dwordx4 v[226:227], off
	s_waitcnt vmcnt(8)
	s_waitcnt lgkmcnt(0)
	s_barrier
	s_setprio 1
	s_waitcnt lgkmcnt(0)
	v_mfma_f32_16x16x32_bf16 v[124:127], v[144:147], v[184:187], v[124:127]
	v_mfma_f32_16x16x32_bf16 v[120:123], v[160:163], v[184:187], v[120:123]
	v_mfma_f32_16x16x32_bf16 v[108:111], v[144:147], v[192:195], v[108:111]
	v_mfma_f32_16x16x32_bf16 v[104:107], v[160:163], v[192:195], v[104:107]
	v_mfma_f32_16x16x32_bf16 v[92:95], v[144:147], v[200:203], v[92:95]
	v_mfma_f32_16x16x32_bf16 v[88:91], v[160:163], v[200:203], v[88:91]
	v_mfma_f32_16x16x32_bf16 v[76:79], v[144:147], v[210:213], v[76:79]
	v_mfma_f32_16x16x32_bf16 v[72:75], v[160:163], v[210:213], v[72:75]
	v_mfma_f32_16x16x32_bf16 v[124:127], v[156:159], v[188:191], v[124:127]
	v_mfma_f32_16x16x32_bf16 v[120:123], v[164:167], v[188:191], v[120:123]
	v_mfma_f32_16x16x32_bf16 v[108:111], v[156:159], v[196:199], v[108:111]
	v_mfma_f32_16x16x32_bf16 v[104:107], v[164:167], v[196:199], v[104:107]
	v_mfma_f32_16x16x32_bf16 v[92:95], v[156:159], v[206:209], v[92:95]
	v_mfma_f32_16x16x32_bf16 v[88:91], v[164:167], v[206:209], v[88:91]
	v_mfma_f32_16x16x32_bf16 v[76:79], v[156:159], v[214:217], v[76:79]
	v_mfma_f32_16x16x32_bf16 v[72:75], v[164:167], v[214:217], v[72:75]
	s_setprio 0
	s_setprio 1
	v_mfma_f32_16x16x32_bf16 v[116:119], v[168:171], v[184:187], v[116:119]
	v_mfma_f32_16x16x32_bf16 v[112:115], v[176:179], v[184:187], v[112:115]
	v_mfma_f32_16x16x32_bf16 v[100:103], v[168:171], v[192:195], v[100:103]
	v_mfma_f32_16x16x32_bf16 v[96:99], v[176:179], v[192:195], v[96:99]
	v_mfma_f32_16x16x32_bf16 v[84:87], v[168:171], v[200:203], v[84:87]
	v_mfma_f32_16x16x32_bf16 v[80:83], v[176:179], v[200:203], v[80:83]
	v_mfma_f32_16x16x32_bf16 v[68:71], v[168:171], v[210:213], v[68:71]
	v_mfma_f32_16x16x32_bf16 v[64:67], v[176:179], v[210:213], v[64:67]
	v_mfma_f32_16x16x32_bf16 v[116:119], v[172:175], v[188:191], v[116:119]
	v_mfma_f32_16x16x32_bf16 v[112:115], v[180:183], v[188:191], v[112:115]
	v_mfma_f32_16x16x32_bf16 v[100:103], v[172:175], v[196:199], v[100:103]
	v_mfma_f32_16x16x32_bf16 v[96:99], v[180:183], v[196:199], v[96:99]
	v_mfma_f32_16x16x32_bf16 v[84:87], v[172:175], v[206:209], v[84:87]
	v_mfma_f32_16x16x32_bf16 v[80:83], v[180:183], v[206:209], v[80:83]
	v_mfma_f32_16x16x32_bf16 v[68:71], v[172:175], v[214:217], v[68:71]
	v_mfma_f32_16x16x32_bf16 v[64:67], v[180:183], v[214:217], v[64:67]
	s_setprio 0
	s_barrier
; #define PG8_STAGE(bufoff, gbase, voff) do { _Pragma("unroll") for (int _i = 0; _i < 2; ++_i) \
;         __builtin_amdgcn_global_load_lds((const unsigned*)((const char*)(gbase) + (voff)[_i]), (PG8_LAS unsigned*)(lds + (bufoff) + ldsw + _i * 8192), 16, 0, 0); } while (0)
; #define PG8_LDA(dst, b, h) do { _Pragma("unroll") for (int m = 0; m < 4; ++m) _Pragma("unroll") for (int k = 0; k < 2; ++k) dst[m][k] = *(const PG8_LAS bf16x8*)(lds + PG8_SA(b, h) + aoff + m * 2048 + k * 1024); } while (0)
; #define PG8_LDB(dst, b, h) do { _Pragma("unroll") for (int n = 0; n < 2; ++n) _Pragma("unroll") for (int k = 0; k < 2; ++k) dst[n][k] = *(const PG8_LAS bf16x8*)(lds + PG8_SB(b, h) + boff + n * 2048 + k * 1024); } while (0)
; #define PG8_MMA(ai, bj, At, Bt) do { __builtin_amdgcn_s_setprio(1); _Pragma("unroll") for (int m = 0; m < 4; ++m) _Pragma("unroll") for (int n = 0; n < 2; ++n) _Pragma("unroll") for (int k = 0; k < 2; ++k) \
;         acc[ai][bj][m][n] = __builtin_amdgcn_mfma_f32_16x16x32_bf16(Bt[n][k], At[m][k], acc[ai][bj][m][n], 0, 0, 0); __builtin_amdgcn_s_setprio(0); } while (0)
; #define PG8_WAIT_V(n) asm volatile("s_waitcnt vmcnt(" #n ")" ::: "memory")
; #define PG8_WAIT_L(n) asm volatile("s_waitcnt lgkmcnt(" #n ")" ::: "memory")
; #define PG8_BAR __builtin_amdgcn_s_barrier()
; #define PG8_SCHED __builtin_amdgcn_sched_barrier(0)
; template <class Epi, class Sched, bool ALIGN_EPI = false, bool SP2 = false>
; __device__ __forceinline__ void gemm_phase(PG8_LAS unsigned char* lds, const Gemm g, const Sched& S, const Epi& E) {
;     ...
;             PG8_LDB(B0, 0, 0); PG8_LDB(B1, 0, 1); PG8_SCHED; PG8_LDA(At, 0, 0); PG8_STAGE(PG8_SA(1, 1), a1 + hstep, voffA);
;             PG8_WAIT_V(8); PG8_WAIT_L(0); PG8_BAR; PG8_MMA(0, 0, At, B0); PG8_MMA(0, 1, At, B1); PG8_BAR; PG8_SCHED;
;     ...
;             PG8_LDA(At, 1, 1); PG8_STAGE(PG8_SB(1, 0), b3, voffB); PG8_STAGE(PG8_SB(1, 1), b3 + hstep, voffB); PG8_STAGE(PG8_SA(1, 0), a3, voffA);
;             PG8_WAIT_V(8); PG8_WAIT_L(0); PG8_BAR; PG8_MMA(1, 0, At, B0); PG8_MMA(1, 1, At, B1); PG8_BAR; PG8_SCHED;
	s_add_i32 s48, s62, s15
	v_lshl_add_u64 v[218:219], v[218:219], 0, s[12:13]
	s_mov_b32 m0, s48
	ds_read_b128 v[184:187], v153 offset:49152
	ds_read_b128 v[188:191], v153 offset:50176
	ds_read_b128 v[192:195], v153 offset:51200
	ds_read_b128 v[196:199], v153 offset:52224
	ds_read_b128 v[200:203], v153 offset:53248
	ds_read_b128 v[206:209], v153 offset:54272
	ds_read_b128 v[210:213], v153 offset:55296
	ds_read_b128 v[214:217], v153 offset:56320
	global_load_lds_dwordx4 v[218:219], off
	s_add_i32 m0, s48, 0x2000
	s_add_u32 s46, s46, 0x20080
	v_lshl_add_u64 v[218:219], v[220:221], 0, s[12:13]
	s_addc_u32 s47, s47, 0
	s_add_i32 s48, s63, s15
	global_load_lds_dwordx4 v[218:219], off
	v_lshl_add_u64 v[218:219], s[46:47], 0, v[130:131]
	s_mov_b32 m0, s48
	s_nop 0
	global_load_lds_dwordx4 v[218:219], off
	v_lshl_add_u64 v[218:219], s[46:47], 0, v[134:135]
	s_add_i32 m0, s48, 0x2000
	s_nop 0
	global_load_lds_dwordx4 v[218:219], off
	s_waitcnt vmcnt(6)
	s_waitcnt lgkmcnt(0)
	s_barrier
	s_setprio 1
	s_waitcnt lgkmcnt(0)
	v_mfma_f32_16x16x32_bf16 v[60:63], v[144:147], v[184:187], v[60:63]
	v_mfma_f32_16x16x32_bf16 v[56:59], v[160:163], v[184:187], v[56:59]
	v_mfma_f32_16x16x32_bf16 v[44:47], v[144:147], v[192:195], v[44:47]
	v_mfma_f32_16x16x32_bf16 v[40:43], v[160:163], v[192:195], v[40:43]
	v_mfma_f32_16x16x32_bf16 v[28:31], v[144:147], v[200:203], v[28:31]
	v_mfma_f32_16x16x32_bf16 v[24:27], v[160:163], v[200:203], v[24:27]
	v_lshl_add_u64 v[218:219], v[222:223], 0, s[12:13]
	s_mov_b32 m0, s52
	s_nop 0
	global_load_lds_dwordx4 v[218:219], off
	v_mfma_f32_16x16x32_bf16 v[12:15], v[144:147], v[210:213], v[12:15]
	v_mfma_f32_16x16x32_bf16 v[8:11], v[160:163], v[210:213], v[8:11]
	v_mfma_f32_16x16x32_bf16 v[60:63], v[156:159], v[188:191], v[60:63]
	v_mfma_f32_16x16x32_bf16 v[56:59], v[164:167], v[188:191], v[56:59]
	v_mfma_f32_16x16x32_bf16 v[44:47], v[156:159], v[196:199], v[44:47]
	v_mfma_f32_16x16x32_bf16 v[40:43], v[164:167], v[196:199], v[40:43]
	v_mfma_f32_16x16x32_bf16 v[28:31], v[156:159], v[206:209], v[28:31]
	v_mfma_f32_16x16x32_bf16 v[24:27], v[164:167], v[206:209], v[24:27]
	v_mfma_f32_16x16x32_bf16 v[12:15], v[156:159], v[214:217], v[12:15]
	v_mfma_f32_16x16x32_bf16 v[8:11], v[164:167], v[214:217], v[8:11]
	s_setprio 0
	s_setprio 1
	v_mfma_f32_16x16x32_bf16 v[52:55], v[168:171], v[184:187], v[52:55]
	v_mfma_f32_16x16x32_bf16 v[48:51], v[176:179], v[184:187], v[48:51]
	v_lshl_add_u64 v[218:219], v[224:225], 0, s[12:13]
	s_mov_b32 m0, s53
	s_nop 0
	global_load_lds_dwordx4 v[218:219], off
	v_mfma_f32_16x16x32_bf16 v[36:39], v[168:171], v[192:195], v[36:39]
	v_mfma_f32_16x16x32_bf16 v[32:35], v[176:179], v[192:195], v[32:35]
	v_mfma_f32_16x16x32_bf16 v[20:23], v[168:171], v[200:203], v[20:23]
	v_mfma_f32_16x16x32_bf16 v[16:19], v[176:179], v[200:203], v[16:19]
	v_mfma_f32_16x16x32_bf16 v[4:7], v[168:171], v[210:213], v[4:7]
	v_mfma_f32_16x16x32_bf16 v[0:3], v[176:179], v[210:213], v[0:3]
	v_mfma_f32_16x16x32_bf16 v[52:55], v[172:175], v[188:191], v[52:55]
	v_mfma_f32_16x16x32_bf16 v[48:51], v[180:183], v[188:191], v[48:51]
	v_mfma_f32_16x16x32_bf16 v[36:39], v[172:175], v[196:199], v[36:39]
	v_mfma_f32_16x16x32_bf16 v[32:35], v[180:183], v[196:199], v[32:35]
	v_mfma_f32_16x16x32_bf16 v[20:23], v[172:175], v[206:209], v[20:23]
	v_mfma_f32_16x16x32_bf16 v[16:19], v[180:183], v[206:209], v[16:19]
	v_mfma_f32_16x16x32_bf16 v[4:7], v[172:175], v[214:217], v[4:7]
	v_mfma_f32_16x16x32_bf16 v[0:3], v[180:183], v[214:217], v[0:3]
	s_setprio 0
	s_barrier
	s_add_i32 s61, s61, 2
	s_add_u32 s44, s44, 0x100
	s_addc_u32 s45, s45, 0
	s_add_u32 s59, s59, 0x100
	s_addc_u32 s60, s60, 0
.LBB0_1816:
	ds_read_b128 v[144:147], v151
	ds_read_b128 v[156:159], v151 offset:1024
	ds_read_b128 v[160:163], v151 offset:2048
	ds_read_b128 v[164:167], v151 offset:3072
	ds_read_b128 v[168:171], v152
	ds_read_b128 v[172:175], v152 offset:1024
	ds_read_b128 v[176:179], v152 offset:2048
	ds_read_b128 v[180:183], v152 offset:3072
	s_add_u32 s46, s44, 0xfffe0080
	s_addc_u32 s47, s45, -1
	s_cmp_eq_u32 s61, 4
	s_cselect_b32 s49, s29, s47
	s_cselect_b32 s48, s41, s46
	s_cselect_b32 s47, s27, s60
	s_cselect_b32 s46, s58, s59
	v_lshl_add_u64 v[218:219], s[44:45], 0, v[136:137]
	s_add_i32 m0, s33, 0xc000
	ds_read_b128 v[184:187], v153
	ds_read_b128 v[188:191], v153 offset:1024
	ds_read_b128 v[192:195], v153 offset:2048
	ds_read_b128 v[196:199], v153 offset:3072
	ds_read_b128 v[200:203], v153 offset:4096
	ds_read_b128 v[206:209], v153 offset:5120
	ds_read_b128 v[210:213], v153 offset:6144
	ds_read_b128 v[214:217], v153 offset:7168
	global_load_lds_dwordx4 v[218:219], off
	v_lshl_add_u64 v[218:219], s[44:45], 0, v[138:139]
	s_add_i32 m0, s33, 0xe000
	s_nop 0
	global_load_lds_dwordx4 v[218:219], off
	s_waitcnt vmcnt(8)
	s_waitcnt lgkmcnt(0)
	s_barrier
; #define PG8_STAGE(bufoff, gbase, voff) do { _Pragma("unroll") for (int _i = 0; _i < 2; ++_i) \
;         __builtin_amdgcn_global_load_lds((const unsigned*)((const char*)(gbase) + (voff)[_i]), (PG8_LAS unsigned*)(lds + (bufoff) + ldsw + _i * 8192), 16, 0, 0); } while (0)
; #define PG8_LDA(dst, b, h) do { _Pragma("unroll") for (int m = 0; m < 4; ++m) _Pragma("unroll") for (int k = 0; k < 2; ++k) dst[m][k] = *(const PG8_LAS bf16x8*)(lds + PG8_SA(b, h) + aoff + m * 2048 + k * 1024); } while (0)
; #define PG8_LDB(dst, b, h) do { _Pragma("unroll") for (int n = 0; n < 2; ++n) _Pragma("unroll") for (int k = 0; k < 2; ++k) dst[n][k] = *(const PG8_LAS bf16x8*)(lds + PG8_SB(b, h) + boff + n * 2048 + k * 1024); } while (0)
; #define PG8_MMA(ai, bj, At, Bt) do { __builtin_amdgcn_s_setprio(1); _Pragma("unroll") for (int m = 0; m < 4; ++m) _Pragma("unroll") for (int n = 0; n < 2; ++n) _Pragma("unroll") for (int k = 0; k < 2; ++k) \
;         acc[ai][bj][m][n] = __builtin_amdgcn_mfma_f32_16x16x32_bf16(Bt[n][k], At[m][k], acc[ai][bj][m][n], 0, 0, 0); __builtin_amdgcn_s_setprio(0); } while (0)
; #define PG8_WAIT_V(n) asm volatile("s_waitcnt vmcnt(" #n ")" ::: "memory")
; #define PG8_WAIT_L(n) asm volatile("s_waitcnt lgkmcnt(" #n ")" ::: "memory")
; #define PG8_BAR __builtin_amdgcn_s_barrier()
; #define PG8_SCHED __builtin_amdgcn_sched_barrier(0)
; template <class Epi, class Sched, bool ALIGN_EPI = false, bool SP2 = false>
; __device__ __forceinline__ void gemm_phase(PG8_LAS unsigned char* lds, const Gemm g, const Sched& S, const Epi& E) {
;     ...
;             PG8_LDB(B0, 0, 0); PG8_LDB(B1, 0, 1); PG8_SCHED; PG8_LDA(At, 0, 0); PG8_STAGE(PG8_SA(1, 1), a1 + hstep, voffA);
;             PG8_WAIT_V(8); PG8_WAIT_L(0); PG8_BAR; PG8_MMA(0, 0, At, B0); PG8_MMA(0, 1, At, B1); PG8_BAR; PG8_SCHED;
;             PG8_LDA(At, 0, 1); PG8_STAGE(PG8_SB(0, 0), b2, voffB); PG8_STAGE(PG8_SB(0, 1), b2 + hstep, voffB); PG8_STAGE(PG8_SA(0, 0), a2, voffA);
;             PG8_WAIT_V(8); PG8_WAIT_L(0); PG8_BAR; PG8_MMA(1, 0, At, B0); PG8_MMA(1, 1, At, B1); PG8_BAR; PG8_SCHED;
	s_setprio 1
	s_waitcnt lgkmcnt(0)
	v_mfma_f32_16x16x32_bf16 v[124:127], v[144:147], v[184:187], v[124:127]
	v_mfma_f32_16x16x32_bf16 v[120:123], v[160:163], v[184:187], v[120:123]
	v_mfma_f32_16x16x32_bf16 v[108:111], v[144:147], v[192:195], v[108:111]
	v_mfma_f32_16x16x32_bf16 v[104:107], v[160:163], v[192:195], v[104:107]
	v_mfma_f32_16x16x32_bf16 v[92:95], v[144:147], v[200:203], v[92:95]
	v_mfma_f32_16x16x32_bf16 v[88:91], v[160:163], v[200:203], v[88:91]
	v_mfma_f32_16x16x32_bf16 v[76:79], v[144:147], v[210:213], v[76:79]
	v_mfma_f32_16x16x32_bf16 v[72:75], v[160:163], v[210:213], v[72:75]
	v_mfma_f32_16x16x32_bf16 v[124:127], v[156:159], v[188:191], v[124:127]
	v_mfma_f32_16x16x32_bf16 v[120:123], v[164:167], v[188:191], v[120:123]
	v_mfma_f32_16x16x32_bf16 v[108:111], v[156:159], v[196:199], v[108:111]
	v_mfma_f32_16x16x32_bf16 v[104:107], v[164:167], v[196:199], v[104:107]
	v_mfma_f32_16x16x32_bf16 v[92:95], v[156:159], v[206:209], v[92:95]
	v_mfma_f32_16x16x32_bf16 v[88:91], v[164:167], v[206:209], v[88:91]
	v_mfma_f32_16x16x32_bf16 v[76:79], v[156:159], v[214:217], v[76:79]
	v_mfma_f32_16x16x32_bf16 v[72:75], v[164:167], v[214:217], v[72:75]
	s_setprio 0
	s_setprio 1
	v_mfma_f32_16x16x32_bf16 v[116:119], v[168:171], v[184:187], v[116:119]
	v_mfma_f32_16x16x32_bf16 v[112:115], v[176:179], v[184:187], v[112:115]
	v_mfma_f32_16x16x32_bf16 v[100:103], v[168:171], v[192:195], v[100:103]
	v_mfma_f32_16x16x32_bf16 v[96:99], v[176:179], v[192:195], v[96:99]
	v_mfma_f32_16x16x32_bf16 v[84:87], v[168:171], v[200:203], v[84:87]
	v_mfma_f32_16x16x32_bf16 v[80:83], v[176:179], v[200:203], v[80:83]
	v_mfma_f32_16x16x32_bf16 v[68:71], v[168:171], v[210:213], v[68:71]
	v_mfma_f32_16x16x32_bf16 v[64:67], v[176:179], v[210:213], v[64:67]
	v_mfma_f32_16x16x32_bf16 v[116:119], v[172:175], v[188:191], v[116:119]
	v_mfma_f32_16x16x32_bf16 v[112:115], v[180:183], v[188:191], v[112:115]
	v_mfma_f32_16x16x32_bf16 v[100:103], v[172:175], v[196:199], v[100:103]
	v_mfma_f32_16x16x32_bf16 v[96:99], v[180:183], v[196:199], v[96:99]
	v_mfma_f32_16x16x32_bf16 v[84:87], v[172:175], v[206:209], v[84:87]
	v_mfma_f32_16x16x32_bf16 v[80:83], v[180:183], v[206:209], v[80:83]
	v_mfma_f32_16x16x32_bf16 v[68:71], v[172:175], v[214:217], v[68:71]
	v_mfma_f32_16x16x32_bf16 v[64:67], v[180:183], v[214:217], v[64:67]
	s_setprio 0
	s_barrier
	s_add_i32 s62, s54, s15
	v_lshl_add_u64 v[218:219], s[46:47], 0, v[130:131]
	s_mov_b32 m0, s62
	ds_read_b128 v[184:187], v153 offset:16384
	ds_read_b128 v[188:191], v153 offset:17408
	ds_read_b128 v[192:195], v153 offset:18432
	ds_read_b128 v[196:199], v153 offset:19456
	ds_read_b128 v[200:203], v153 offset:20480
	ds_read_b128 v[206:209], v153 offset:21504
	ds_read_b128 v[210:213], v153 offset:22528
	ds_read_b128 v[214:217], v153 offset:23552
	global_load_lds_dwordx4 v[218:219], off
	s_add_i32 m0, s62, 0x2000
	s_add_u32 s62, s46, 0x20000
	v_lshl_add_u64 v[220:221], s[46:47], 0, v[134:135]
	s_addc_u32 s63, s47, 0
	s_add_i32 s64, s55, s15
	global_load_lds_dwordx4 v[220:221], off
	v_lshl_add_u64 v[222:223], s[62:63], 0, v[130:131]
	s_mov_b32 m0, s64
	v_lshl_add_u64 v[224:225], s[48:49], 0, v[132:133]
	global_load_lds_dwordx4 v[222:223], off
	v_lshl_add_u64 v[222:223], s[62:63], 0, v[134:135]
	s_add_i32 m0, s64, 0x2000
	s_nop 0
	global_load_lds_dwordx4 v[222:223], off
	s_waitcnt vmcnt(6)
	s_waitcnt lgkmcnt(0)
	s_barrier
	s_setprio 1
	s_waitcnt lgkmcnt(0)
	v_mfma_f32_16x16x32_bf16 v[60:63], v[144:147], v[184:187], v[60:63]
	v_mfma_f32_16x16x32_bf16 v[56:59], v[160:163], v[184:187], v[56:59]
	v_mfma_f32_16x16x32_bf16 v[44:47], v[144:147], v[192:195], v[44:47]
	v_mfma_f32_16x16x32_bf16 v[40:43], v[160:163], v[192:195], v[40:43]
	v_mfma_f32_16x16x32_bf16 v[28:31], v[144:147], v[200:203], v[28:31]
	v_mfma_f32_16x16x32_bf16 v[24:27], v[160:163], v[200:203], v[24:27]
	v_lshl_add_u64 v[222:223], s[48:49], 0, v[128:129]
	s_mov_b32 m0, s33
	s_nop 0
	global_load_lds_dwordx4 v[222:223], off
	v_mfma_f32_16x16x32_bf16 v[12:15], v[144:147], v[210:213], v[12:15]
	v_mfma_f32_16x16x32_bf16 v[8:11], v[160:163], v[210:213], v[8:11]
	v_mfma_f32_16x16x32_bf16 v[60:63], v[156:159], v[188:191], v[60:63]
	v_mfma_f32_16x16x32_bf16 v[56:59], v[164:167], v[188:191], v[56:59]
	v_mfma_f32_16x16x32_bf16 v[44:47], v[156:159], v[196:199], v[44:47]
	v_mfma_f32_16x16x32_bf16 v[40:43], v[164:167], v[196:199], v[40:43]
	v_mfma_f32_16x16x32_bf16 v[28:31], v[156:159], v[206:209], v[28:31]
	v_mfma_f32_16x16x32_bf16 v[24:27], v[164:167], v[206:209], v[24:27]
	v_mfma_f32_16x16x32_bf16 v[12:15], v[156:159], v[214:217], v[12:15]
	v_mfma_f32_16x16x32_bf16 v[8:11], v[164:167], v[214:217], v[8:11]
	s_setprio 0
	s_setprio 1
	v_mfma_f32_16x16x32_bf16 v[52:55], v[168:171], v[184:187], v[52:55]
	v_mfma_f32_16x16x32_bf16 v[48:51], v[176:179], v[184:187], v[48:51]
	s_mov_b32 m0, s34
	s_nop 0
	global_load_lds_dwordx4 v[224:225], off
	v_mfma_f32_16x16x32_bf16 v[36:39], v[168:171], v[192:195], v[36:39]
	v_mfma_f32_16x16x32_bf16 v[32:35], v[176:179], v[192:195], v[32:35]
	v_mfma_f32_16x16x32_bf16 v[20:23], v[168:171], v[200:203], v[20:23]
	v_mfma_f32_16x16x32_bf16 v[16:19], v[176:179], v[200:203], v[16:19]
	v_mfma_f32_16x16x32_bf16 v[4:7], v[168:171], v[210:213], v[4:7]
	v_mfma_f32_16x16x32_bf16 v[0:3], v[176:179], v[210:213], v[0:3]
	v_mfma_f32_16x16x32_bf16 v[52:55], v[172:175], v[188:191], v[52:55]
	v_mfma_f32_16x16x32_bf16 v[48:51], v[180:183], v[188:191], v[48:51]
	v_mfma_f32_16x16x32_bf16 v[36:39], v[172:175], v[196:199], v[36:39]
	v_mfma_f32_16x16x32_bf16 v[32:35], v[180:183], v[196:199], v[32:35]
	v_mfma_f32_16x16x32_bf16 v[20:23], v[172:175], v[206:209], v[20:23]
	v_mfma_f32_16x16x32_bf16 v[16:19], v[180:183], v[206:209], v[16:19]
	v_mfma_f32_16x16x32_bf16 v[4:7], v[172:175], v[214:217], v[4:7]
	v_mfma_f32_16x16x32_bf16 v[0:3], v[180:183], v[214:217], v[0:3]
	s_setprio 0
	s_barrier
; #define PG8_STAGE(bufoff, gbase, voff) do { _Pragma("unroll") for (int _i = 0; _i < 2; ++_i) \
;         __builtin_amdgcn_global_load_lds((const unsigned*)((const char*)(gbase) + (voff)[_i]), (PG8_LAS unsigned*)(lds + (bufoff) + ldsw + _i * 8192), 16, 0, 0); } while (0)
; #define PG8_LDA(dst, b, h) do { _Pragma("unroll") for (int m = 0; m < 4; ++m) _Pragma("unroll") for (int k = 0; k < 2; ++k) dst[m][k] = *(const PG8_LAS bf16x8*)(lds + PG8_SA(b, h) + aoff + m * 2048 + k * 1024); } while (0)
; #define PG8_LDB(dst, b, h) do { _Pragma("unroll") for (int n = 0; n < 2; ++n) _Pragma("unroll") for (int k = 0; k < 2; ++k) dst[n][k] = *(const PG8_LAS bf16x8*)(lds + PG8_SB(b, h) + boff + n * 2048 + k * 1024); } while (0)
; #define PG8_MMA(ai, bj, At, Bt) do { __builtin_amdgcn_s_setprio(1); _Pragma("unroll") for (int m = 0; m < 4; ++m) _Pragma("unroll") for (int n = 0; n < 2; ++n) _Pragma("unroll") for (int k = 0; k < 2; ++k) \
;         acc[ai][bj][m][n] = __builtin_amdgcn_mfma_f32_16x16x32_bf16(Bt[n][k], At[m][k], acc[ai][bj][m][n], 0, 0, 0); __builtin_amdgcn_s_setprio(0); } while (0)
; #define PG8_WAIT_V(n) asm volatile("s_waitcnt vmcnt(" #n ")" ::: "memory")
; #define PG8_WAIT_L(n) asm volatile("s_waitcnt lgkmcnt(" #n ")" ::: "memory")
; #define PG8_BAR __builtin_amdgcn_s_barrier()
; #define PG8_SCHED __builtin_amdgcn_sched_barrier(0)
; template <class Epi, class Sched, bool ALIGN_EPI = false, bool SP2 = false>
; __device__ __forceinline__ void gemm_phase(PG8_LAS unsigned char* lds, const Gemm g, const Sched& S, const Epi& E) {
;     ...
;             PG8_LDB(B0, 1, 0); PG8_LDB(B1, 1, 1); PG8_SCHED; PG8_LDA(At, 1, 0); PG8_STAGE(PG8_SA(0, 1), a2 + hstep, voffA);
;             PG8_WAIT_V(8); PG8_WAIT_L(0); PG8_BAR; PG8_MMA(0, 0, At, B0); PG8_MMA(0, 1, At, B1); PG8_BAR; PG8_SCHED;
	s_add_i32 s62, 0, 0x18000
	v_add_u32_e32 v155, s62, v149
	s_add_i32 s63, 0, 0x1c000
	ds_read_b128 v[144:147], v155
	ds_read_b128 v[156:159], v155 offset:1024
	ds_read_b128 v[160:163], v155 offset:2048
	ds_read_b128 v[164:167], v155 offset:3072
	v_add_u32_e32 v155, s63, v149
	ds_read_b128 v[168:171], v155
	ds_read_b128 v[172:175], v155 offset:1024
	ds_read_b128 v[176:179], v155 offset:2048
	ds_read_b128 v[180:183], v155 offset:3072
	s_add_u32 s48, s48, 0x20000
	s_addc_u32 s49, s49, 0
	s_mov_b32 m0, s43
	v_lshl_add_u64 v[226:227], s[48:49], 0, v[128:129]
	ds_read_b128 v[184:187], v153 offset:32768
	ds_read_b128 v[188:191], v153 offset:33792
	ds_read_b128 v[192:195], v153 offset:34816
	ds_read_b128 v[196:199], v153 offset:35840
	ds_read_b128 v[200:203], v153 offset:36864
	ds_read_b128 v[206:209], v153 offset:37888
	ds_read_b128 v[210:213], v153 offset:38912
	ds_read_b128 v[214:217], v153 offset:39936
	global_load_lds_dwordx4 v[226:227], off
	v_lshl_add_u64 v[226:227], s[48:49], 0, v[132:133]
	s_mov_b32 m0, s50
	s_nop 0
	global_load_lds_dwordx4 v[226:227], off
	s_waitcnt vmcnt(8)
	s_waitcnt lgkmcnt(0)
	s_barrier
	s_setprio 1
	s_waitcnt lgkmcnt(0)
	v_mfma_f32_16x16x32_bf16 v[124:127], v[144:147], v[184:187], v[124:127]
	v_mfma_f32_16x16x32_bf16 v[120:123], v[160:163], v[184:187], v[120:123]
	v_mfma_f32_16x16x32_bf16 v[108:111], v[144:147], v[192:195], v[108:111]
	v_mfma_f32_16x16x32_bf16 v[104:107], v[160:163], v[192:195], v[104:107]
	v_mfma_f32_16x16x32_bf16 v[92:95], v[144:147], v[200:203], v[92:95]
	v_mfma_f32_16x16x32_bf16 v[88:91], v[160:163], v[200:203], v[88:91]
	v_mfma_f32_16x16x32_bf16 v[76:79], v[144:147], v[210:213], v[76:79]
	v_mfma_f32_16x16x32_bf16 v[72:75], v[160:163], v[210:213], v[72:75]
	v_mfma_f32_16x16x32_bf16 v[124:127], v[156:159], v[188:191], v[124:127]
	v_mfma_f32_16x16x32_bf16 v[120:123], v[164:167], v[188:191], v[120:123]
	v_mfma_f32_16x16x32_bf16 v[108:111], v[156:159], v[196:199], v[108:111]
	v_mfma_f32_16x16x32_bf16 v[104:107], v[164:167], v[196:199], v[104:107]
	v_mfma_f32_16x16x32_bf16 v[92:95], v[156:159], v[206:209], v[92:95]
	v_mfma_f32_16x16x32_bf16 v[88:91], v[164:167], v[206:209], v[88:91]
	v_mfma_f32_16x16x32_bf16 v[76:79], v[156:159], v[214:217], v[76:79]
	v_mfma_f32_16x16x32_bf16 v[72:75], v[164:167], v[214:217], v[72:75]
	s_setprio 0
	s_setprio 1
	v_mfma_f32_16x16x32_bf16 v[116:119], v[168:171], v[184:187], v[116:119]
	v_mfma_f32_16x16x32_bf16 v[112:115], v[176:179], v[184:187], v[112:115]
	v_mfma_f32_16x16x32_bf16 v[100:103], v[168:171], v[192:195], v[100:103]
	v_mfma_f32_16x16x32_bf16 v[96:99], v[176:179], v[192:195], v[96:99]
	v_mfma_f32_16x16x32_bf16 v[84:87], v[168:171], v[200:203], v[84:87]
	v_mfma_f32_16x16x32_bf16 v[80:83], v[176:179], v[200:203], v[80:83]
	v_mfma_f32_16x16x32_bf16 v[68:71], v[168:171], v[210:213], v[68:71]
	v_mfma_f32_16x16x32_bf16 v[64:67], v[176:179], v[210:213], v[64:67]
	v_mfma_f32_16x16x32_bf16 v[116:119], v[172:175], v[188:191], v[116:119]
	v_mfma_f32_16x16x32_bf16 v[112:115], v[180:183], v[188:191], v[112:115]
	v_mfma_f32_16x16x32_bf16 v[100:103], v[172:175], v[196:199], v[100:103]
	v_mfma_f32_16x16x32_bf16 v[96:99], v[180:183], v[196:199], v[96:99]
	v_mfma_f32_16x16x32_bf16 v[84:87], v[172:175], v[206:209], v[84:87]
	v_mfma_f32_16x16x32_bf16 v[80:83], v[180:183], v[206:209], v[80:83]
	v_mfma_f32_16x16x32_bf16 v[68:71], v[172:175], v[214:217], v[68:71]
	v_mfma_f32_16x16x32_bf16 v[64:67], v[180:183], v[214:217], v[64:67]
	s_setprio 0
	s_barrier
; #define PG8_STAGE(bufoff, gbase, voff) do { _Pragma("unroll") for (int _i = 0; _i < 2; ++_i) \
;         __builtin_amdgcn_global_load_lds((const unsigned*)((const char*)(gbase) + (voff)[_i]), (PG8_LAS unsigned*)(lds + (bufoff) + ldsw + _i * 8192), 16, 0, 0); } while (0)
; #define PG8_LDA(dst, b, h) do { _Pragma("unroll") for (int m = 0; m < 4; ++m) _Pragma("unroll") for (int k = 0; k < 2; ++k) dst[m][k] = *(const PG8_LAS bf16x8*)(lds + PG8_SA(b, h) + aoff + m * 2048 + k * 1024); } while (0)
; #define PG8_MMA(ai, bj, At, Bt) do { __builtin_amdgcn_s_setprio(1); _Pragma("unroll") for (int m = 0; m < 4; ++m) _Pragma("unroll") for (int n = 0; n < 2; ++n) _Pragma("unroll") for (int k = 0; k < 2; ++k) \
;         acc[ai][bj][m][n] = __builtin_amdgcn_mfma_f32_16x16x32_bf16(Bt[n][k], At[m][k], acc[ai][bj][m][n], 0, 0, 0); __builtin_amdgcn_s_setprio(0); } while (0)
; #define PG8_WAIT_V(n) asm volatile("s_waitcnt vmcnt(" #n ")" ::: "memory")
; #define PG8_WAIT_L(n) asm volatile("s_waitcnt lgkmcnt(" #n ")" ::: "memory")
; #define PG8_BAR __builtin_amdgcn_s_barrier()
; #define PG8_SCHED __builtin_amdgcn_sched_barrier(0)
; template <class Epi, class Sched, bool ALIGN_EPI = false, bool SP2 = false>
; __device__ __forceinline__ void gemm_phase(PG8_LAS unsigned char* lds, const Gemm g, const Sched& S, const Epi& E) {
;     ...
;             PG8_LDA(At, 1, 1); PG8_STAGE(PG8_SB(1, 0), b3, voffB); PG8_STAGE(PG8_SB(1, 1), b3 + hstep, voffB); PG8_STAGE(PG8_SA(1, 0), a3, voffA);
;             PG8_WAIT_V(8); PG8_WAIT_L(0); PG8_BAR; PG8_MMA(1, 0, At, B0); PG8_MMA(1, 1, At, B1); PG8_BAR; PG8_SCHED;
	s_add_i32 s48, s62, s15
	v_lshl_add_u64 v[218:219], v[218:219], 0, s[12:13]
	s_mov_b32 m0, s48
	ds_read_b128 v[184:187], v153 offset:49152
	ds_read_b128 v[188:191], v153 offset:50176
	ds_read_b128 v[192:195], v153 offset:51200
	ds_read_b128 v[196:199], v153 offset:52224
	ds_read_b128 v[200:203], v153 offset:53248
	ds_read_b128 v[206:209], v153 offset:54272
	ds_read_b128 v[210:213], v153 offset:55296
	ds_read_b128 v[214:217], v153 offset:56320
	global_load_lds_dwordx4 v[218:219], off
	s_add_i32 m0, s48, 0x2000
	s_add_u32 s46, s46, 0x20080
	v_lshl_add_u64 v[218:219], v[220:221], 0, s[12:13]
	s_addc_u32 s47, s47, 0
	s_add_i32 s48, s63, s15
	global_load_lds_dwordx4 v[218:219], off
	v_lshl_add_u64 v[218:219], s[46:47], 0, v[130:131]
	s_mov_b32 m0, s48
	s_nop 0
	global_load_lds_dwordx4 v[218:219], off
	v_lshl_add_u64 v[218:219], s[46:47], 0, v[134:135]
	s_add_i32 m0, s48, 0x2000
	s_nop 0
	global_load_lds_dwordx4 v[218:219], off
	s_waitcnt vmcnt(6)
	s_waitcnt lgkmcnt(0)
	s_barrier
	s_setprio 1
	s_waitcnt lgkmcnt(0)
	v_mfma_f32_16x16x32_bf16 v[60:63], v[144:147], v[184:187], v[60:63]
	v_mfma_f32_16x16x32_bf16 v[56:59], v[160:163], v[184:187], v[56:59]
	v_mfma_f32_16x16x32_bf16 v[44:47], v[144:147], v[192:195], v[44:47]
	v_mfma_f32_16x16x32_bf16 v[40:43], v[160:163], v[192:195], v[40:43]
	v_mfma_f32_16x16x32_bf16 v[28:31], v[144:147], v[200:203], v[28:31]
	v_mfma_f32_16x16x32_bf16 v[24:27], v[160:163], v[200:203], v[24:27]
	v_lshl_add_u64 v[218:219], v[222:223], 0, s[12:13]
	s_mov_b32 m0, s52
	s_nop 0
	global_load_lds_dwordx4 v[218:219], off
	v_mfma_f32_16x16x32_bf16 v[12:15], v[144:147], v[210:213], v[12:15]
	v_mfma_f32_16x16x32_bf16 v[8:11], v[160:163], v[210:213], v[8:11]
	v_mfma_f32_16x16x32_bf16 v[60:63], v[156:159], v[188:191], v[60:63]
	v_mfma_f32_16x16x32_bf16 v[56:59], v[164:167], v[188:191], v[56:59]
	v_mfma_f32_16x16x32_bf16 v[44:47], v[156:159], v[196:199], v[44:47]
	v_mfma_f32_16x16x32_bf16 v[40:43], v[164:167], v[196:199], v[40:43]
	v_mfma_f32_16x16x32_bf16 v[28:31], v[156:159], v[206:209], v[28:31]
	v_mfma_f32_16x16x32_bf16 v[24:27], v[164:167], v[206:209], v[24:27]
	v_mfma_f32_16x16x32_bf16 v[12:15], v[156:159], v[214:217], v[12:15]
	v_mfma_f32_16x16x32_bf16 v[8:11], v[164:167], v[214:217], v[8:11]
	s_setprio 0
	s_setprio 1
	v_mfma_f32_16x16x32_bf16 v[52:55], v[168:171], v[184:187], v[52:55]
	v_mfma_f32_16x16x32_bf16 v[48:51], v[176:179], v[184:187], v[48:51]
	v_lshl_add_u64 v[218:219], v[224:225], 0, s[12:13]
	s_mov_b32 m0, s53
	s_nop 0
	global_load_lds_dwordx4 v[218:219], off
	v_mfma_f32_16x16x32_bf16 v[36:39], v[168:171], v[192:195], v[36:39]
	v_mfma_f32_16x16x32_bf16 v[32:35], v[176:179], v[192:195], v[32:35]
	v_mfma_f32_16x16x32_bf16 v[20:23], v[168:171], v[200:203], v[20:23]
	v_mfma_f32_16x16x32_bf16 v[16:19], v[176:179], v[200:203], v[16:19]
	v_mfma_f32_16x16x32_bf16 v[4:7], v[168:171], v[210:213], v[4:7]
	v_mfma_f32_16x16x32_bf16 v[0:3], v[176:179], v[210:213], v[0:3]
	v_mfma_f32_16x16x32_bf16 v[52:55], v[172:175], v[188:191], v[52:55]
	v_mfma_f32_16x16x32_bf16 v[48:51], v[180:183], v[188:191], v[48:51]
	v_mfma_f32_16x16x32_bf16 v[36:39], v[172:175], v[196:199], v[36:39]
	v_mfma_f32_16x16x32_bf16 v[32:35], v[180:183], v[196:199], v[32:35]
	v_mfma_f32_16x16x32_bf16 v[20:23], v[172:175], v[206:209], v[20:23]
	v_mfma_f32_16x16x32_bf16 v[16:19], v[180:183], v[206:209], v[16:19]
	v_mfma_f32_16x16x32_bf16 v[4:7], v[172:175], v[214:217], v[4:7]
	v_mfma_f32_16x16x32_bf16 v[0:3], v[180:183], v[214:217], v[0:3]
	s_setprio 0
	s_barrier
	s_add_i32 s61, s61, 2
	s_add_u32 s44, s44, 0x100
	s_addc_u32 s45, s45, 0
	s_add_u32 s59, s59, 0x100
	s_addc_u32 s60, s60, 0
	s_cmp_gt_u32 s61, 5
	s_cbranch_scc0 .LBB0_1816
	s_and_b64 vcc, exec, s[24:25]
	s_cbranch_vccz .LBB0_1819
	s_barrier

; #define PG8_STAGE(bufoff, gbase, voff) do { _Pragma("unroll") for (int _i = 0; _i < 2; ++_i) \
;         __builtin_amdgcn_global_load_lds((const unsigned*)((const char*)(gbase) + (voff)[_i]), (PG8_LAS unsigned*)(lds + (bufoff) + ldsw + _i * 8192), 16, 0, 0); } while (0)
; #define PG8_LDA(dst, b, h) do { _Pragma("unroll") for (int m = 0; m < 4; ++m) _Pragma("unroll") for (int k = 0; k < 2; ++k) dst[m][k] = *(const PG8_LAS bf16x8*)(lds + PG8_SA(b, h) + aoff + m * 2048 + k * 1024); } while (0)
; #define PG8_LDB(dst, b, h) do { _Pragma("unroll") for (int n = 0; n < 2; ++n) _Pragma("unroll") for (int k = 0; k < 2; ++k) dst[n][k] = *(const PG8_LAS bf16x8*)(lds + PG8_SB(b, h) + boff + n * 2048 + k * 1024); } while (0)
; #define PG8_MMA(ai, bj, At, Bt) do { __builtin_amdgcn_s_setprio(1); _Pragma("unroll") for (int m = 0; m < 4; ++m) _Pragma("unroll") for (int n = 0; n < 2; ++n) _Pragma("unroll") for (int k = 0; k < 2; ++k) \
;         acc[ai][bj][m][n] = __builtin_amdgcn_mfma_f32_16x16x32_bf16(Bt[n][k], At[m][k], acc[ai][bj][m][n], 0, 0, 0); __builtin_amdgcn_s_setprio(0); } while (0)
; #define PG8_BAR __builtin_amdgcn_s_barrier()
; template <class Epi, class Sched, bool ALIGN_EPI = false, bool SP2 = false>
; __device__ __forceinline__ void gemm_phase(PG8_LAS unsigned char* lds, const Gemm g, const Sched& S, const Epi& E) {
;     ...
;         const bool has_next = S.next(ui + 1, nxt);
;         const char* nA = has_next ? (const char*)g.A + (size_t)nxt.pm * tstep : cA; const char* nB = has_next ? (const char*)g.Bt + (size_t)nxt.pn * tstep : cB;
;         for (int t = 0; t < nt; t += 2) {
;             const bool last = (t == nt - 2);
;             const char* a1 = cA + (size_t)(t + 1) * kstep;
;             const char* a2 = last ? nA : cA + (size_t)(t + 2) * kstep; const char* b2 = last ? nB : cB + (size_t)(t + 2) * kstep;
;             const char* a3 = a2 + kstep; const char* b3 = b2 + kstep;
;             if (last && has_next) S.a_ready(nxt);
;             if constexpr (SP2) {
;             PG8_LDB(B0, 0, 0); PG8_LDB(B1, 0, 1); PG8_SCHED; PG8_LDA(At, 0, 0); PG8_STAGE(PG8_SA(1, 1), a1 + hstep, voffA);
;             PG8_WAIT_V(8); PG8_WAIT_L(0); PG8_BAR; PG8_MMA(0, 0, At, B0); PG8_MMA(0, 1, At, B1); PG8_BAR; PG8_SCHED;
;             PG8_LDA(At, 0, 1); PG8_STAGE(PG8_SB(0, 0), b2, voffB); PG8_STAGE(PG8_SB(0, 1), b2 + hstep, voffB); PG8_STAGE(PG8_SA(0, 0), a2, voffA);
.LBB0_1899:
	s_ashr_i32 s25, s24, 31
	s_lshl_b64 s[26:27], s[24:25], 19
	s_add_u32 s26, s22, s26
	s_addc_u32 s27, s23, s27
	s_and_b64 s[28:29], s[4:5], exec
	s_cselect_b32 s25, s27, s39
	s_cselect_b32 s53, s26, s38
	s_ashr_i32 s13, s12, 31
	s_lshl_b64 s[28:29], s[12:13], 19
	s_add_u32 s28, s3, s28
	s_addc_u32 s29, s14, s29
	s_and_b64 s[42:43], s[4:5], exec
	s_cselect_b32 s13, s29, s41
	s_cselect_b32 s54, s28, s40
	s_add_u32 s38, s38, 0x40080
	s_addc_u32 s39, s39, 0
	s_add_u32 s55, s40, 0x100
	s_addc_u32 s56, s41, 0
	s_mov_b32 s57, -2
	ds_read_b128 v[144:147], v155
	ds_read_b128 v[148:151], v155 offset:1024
	ds_read_b128 v[160:163], v155 offset:2048
	ds_read_b128 v[164:167], v155 offset:3072
	ds_read_b128 v[168:171], v156
	ds_read_b128 v[172:175], v156 offset:1024
	ds_read_b128 v[176:179], v156 offset:2048
	ds_read_b128 v[180:183], v156 offset:3072
	s_add_u32 s40, s38, 0xfffc0080
	s_addc_u32 s41, s39, -1
	s_cmp_eq_u32 s57, 12
	s_cselect_b32 s43, s25, s41
	s_cselect_b32 s42, s53, s40
	s_cselect_b32 s41, s13, s56
	s_cselect_b32 s40, s54, s55
	v_lshl_add_u64 v[218:219], s[38:39], 0, v[136:137]
	s_add_i32 m0, s34, 0xc000
	ds_read_b128 v[184:187], v157
	ds_read_b128 v[188:191], v157 offset:1024
	ds_read_b128 v[192:195], v157 offset:2048
	ds_read_b128 v[196:199], v157 offset:3072
	ds_read_b128 v[200:203], v157 offset:4096
	ds_read_b128 v[206:209], v157 offset:5120
	ds_read_b128 v[210:213], v157 offset:6144
	ds_read_b128 v[214:217], v157 offset:7168
	global_load_lds_dwordx4 v[218:219], off
	v_lshl_add_u64 v[218:219], s[38:39], 0, v[138:139]
	s_add_i32 m0, s34, 0xe000
	s_nop 0
	global_load_lds_dwordx4 v[218:219], off
	s_waitcnt vmcnt(8)
	s_waitcnt lgkmcnt(0)
	s_barrier
	s_setprio 1
	s_waitcnt lgkmcnt(0)
	v_mfma_f32_16x16x32_bf16 v[124:127], v[144:147], v[184:187], 0
	v_mfma_f32_16x16x32_bf16 v[120:123], v[160:163], v[184:187], 0
	v_mfma_f32_16x16x32_bf16 v[108:111], v[144:147], v[192:195], 0
	v_mfma_f32_16x16x32_bf16 v[104:107], v[160:163], v[192:195], 0
	v_mfma_f32_16x16x32_bf16 v[92:95], v[144:147], v[200:203], 0
	v_mfma_f32_16x16x32_bf16 v[88:91], v[160:163], v[200:203], 0
	v_mfma_f32_16x16x32_bf16 v[76:79], v[144:147], v[210:213], 0
	v_mfma_f32_16x16x32_bf16 v[72:75], v[160:163], v[210:213], 0
	v_mfma_f32_16x16x32_bf16 v[124:127], v[148:151], v[188:191], v[124:127]
	v_mfma_f32_16x16x32_bf16 v[120:123], v[164:167], v[188:191], v[120:123]
	v_mfma_f32_16x16x32_bf16 v[108:111], v[148:151], v[196:199], v[108:111]
	v_mfma_f32_16x16x32_bf16 v[104:107], v[164:167], v[196:199], v[104:107]
	v_mfma_f32_16x16x32_bf16 v[92:95], v[148:151], v[206:209], v[92:95]
	v_mfma_f32_16x16x32_bf16 v[88:91], v[164:167], v[206:209], v[88:91]
	v_mfma_f32_16x16x32_bf16 v[76:79], v[148:151], v[214:217], v[76:79]
	v_mfma_f32_16x16x32_bf16 v[72:75], v[164:167], v[214:217], v[72:75]
	s_setprio 0
	s_setprio 1
	v_mfma_f32_16x16x32_bf16 v[116:119], v[168:171], v[184:187], 0
	v_mfma_f32_16x16x32_bf16 v[112:115], v[176:179], v[184:187], 0
	v_mfma_f32_16x16x32_bf16 v[100:103], v[168:171], v[192:195], 0
	v_mfma_f32_16x16x32_bf16 v[96:99], v[176:179], v[192:195], 0
	v_mfma_f32_16x16x32_bf16 v[84:87], v[168:171], v[200:203], 0
	v_mfma_f32_16x16x32_bf16 v[80:83], v[176:179], v[200:203], 0
	v_mfma_f32_16x16x32_bf16 v[68:71], v[168:171], v[210:213], 0
	v_mfma_f32_16x16x32_bf16 v[64:67], v[176:179], v[210:213], 0
	v_mfma_f32_16x16x32_bf16 v[116:119], v[172:175], v[188:191], v[116:119]
	v_mfma_f32_16x16x32_bf16 v[112:115], v[180:183], v[188:191], v[112:115]
	v_mfma_f32_16x16x32_bf16 v[100:103], v[172:175], v[196:199], v[100:103]
	v_mfma_f32_16x16x32_bf16 v[96:99], v[180:183], v[196:199], v[96:99]
	v_mfma_f32_16x16x32_bf16 v[84:87], v[172:175], v[206:209], v[84:87]
	v_mfma_f32_16x16x32_bf16 v[80:83], v[180:183], v[206:209], v[80:83]
	v_mfma_f32_16x16x32_bf16 v[68:71], v[172:175], v[214:217], v[68:71]
	v_mfma_f32_16x16x32_bf16 v[64:67], v[180:183], v[214:217], v[64:67]
	s_setprio 0
	s_barrier
	s_add_i32 s58, s49, s15
	v_lshl_add_u64 v[218:219], s[40:41], 0, v[132:133]
	s_mov_b32 m0, s58
	ds_read_b128 v[184:187], v157 offset:16384
	ds_read_b128 v[188:191], v157 offset:17408
	ds_read_b128 v[192:195], v157 offset:18432
	ds_read_b128 v[196:199], v157 offset:19456
	ds_read_b128 v[200:203], v157 offset:20480
	ds_read_b128 v[206:209], v157 offset:21504
	ds_read_b128 v[210:213], v157 offset:22528
	ds_read_b128 v[214:217], v157 offset:23552
	global_load_lds_dwordx4 v[218:219], off
	s_add_i32 m0, s58, 0x2000
	s_add_u32 s58, s40, 0x40000
	v_lshl_add_u64 v[220:221], s[40:41], 0, v[128:129]
	s_addc_u32 s59, s41, 0
	s_add_i32 s60, s50, s15
	global_load_lds_dwordx4 v[220:221], off
	v_lshl_add_u64 v[222:223], s[58:59], 0, v[132:133]
	s_mov_b32 m0, s60
	v_lshl_add_u64 v[224:225], s[42:43], 0, v[130:131]
	global_load_lds_dwordx4 v[222:223], off
	v_lshl_add_u64 v[222:223], s[58:59], 0, v[128:129]
	s_add_i32 m0, s60, 0x2000
	s_nop 0
	global_load_lds_dwordx4 v[222:223], off
	s_waitcnt vmcnt(6)
	s_waitcnt lgkmcnt(0)
	s_barrier
; #define PG8_STAGE(bufoff, gbase, voff) do { _Pragma("unroll") for (int _i = 0; _i < 2; ++_i) \
;         __builtin_amdgcn_global_load_lds((const unsigned*)((const char*)(gbase) + (voff)[_i]), (PG8_LAS unsigned*)(lds + (bufoff) + ldsw + _i * 8192), 16, 0, 0); } while (0)
; #define PG8_LDA(dst, b, h) do { _Pragma("unroll") for (int m = 0; m < 4; ++m) _Pragma("unroll") for (int k = 0; k < 2; ++k) dst[m][k] = *(const PG8_LAS bf16x8*)(lds + PG8_SA(b, h) + aoff + m * 2048 + k * 1024); } while (0)
; #define PG8_LDB(dst, b, h) do { _Pragma("unroll") for (int n = 0; n < 2; ++n) _Pragma("unroll") for (int k = 0; k < 2; ++k) dst[n][k] = *(const PG8_LAS bf16x8*)(lds + PG8_SB(b, h) + boff + n * 2048 + k * 1024); } while (0)
; #define PG8_MMA(ai, bj, At, Bt) do { __builtin_amdgcn_s_setprio(1); _Pragma("unroll") for (int m = 0; m < 4; ++m) _Pragma("unroll") for (int n = 0; n < 2; ++n) _Pragma("unroll") for (int k = 0; k < 2; ++k) \
;         acc[ai][bj][m][n] = __builtin_amdgcn_mfma_f32_16x16x32_bf16(Bt[n][k], At[m][k], acc[ai][bj][m][n], 0, 0, 0); __builtin_amdgcn_s_setprio(0); } while (0)
; #define PG8_WAIT_V(n) asm volatile("s_waitcnt vmcnt(" #n ")" ::: "memory")
; #define PG8_WAIT_L(n) asm volatile("s_waitcnt lgkmcnt(" #n ")" ::: "memory")
; #define PG8_BAR __builtin_amdgcn_s_barrier()
; #define PG8_SCHED __builtin_amdgcn_sched_barrier(0)
; template <class Epi, class Sched, bool ALIGN_EPI = false, bool SP2 = false>
; __device__ __forceinline__ void gemm_phase(PG8_LAS unsigned char* lds, const Gemm g, const Sched& S, const Epi& E) {
;     ...
;             PG8_WAIT_V(8); PG8_WAIT_L(0); PG8_BAR; PG8_MMA(1, 0, At, B0); PG8_MMA(1, 1, At, B1); PG8_BAR; PG8_SCHED;
;             PG8_LDB(B0, 1, 0); PG8_LDB(B1, 1, 1); PG8_SCHED; PG8_LDA(At, 1, 0); PG8_STAGE(PG8_SA(0, 1), a2 + hstep, voffA);
;             PG8_WAIT_V(8); PG8_WAIT_L(0); PG8_BAR; PG8_MMA(0, 0, At, B0); PG8_MMA(0, 1, At, B1); PG8_BAR; PG8_SCHED;
	s_setprio 1
	s_waitcnt lgkmcnt(0)
	v_mfma_f32_16x16x32_bf16 v[60:63], v[144:147], v[184:187], 0
	v_mfma_f32_16x16x32_bf16 v[56:59], v[160:163], v[184:187], 0
	v_mfma_f32_16x16x32_bf16 v[44:47], v[144:147], v[192:195], 0
	v_mfma_f32_16x16x32_bf16 v[40:43], v[160:163], v[192:195], 0
	v_mfma_f32_16x16x32_bf16 v[28:31], v[144:147], v[200:203], 0
	v_mfma_f32_16x16x32_bf16 v[24:27], v[160:163], v[200:203], 0
	v_lshl_add_u64 v[222:223], s[42:43], 0, v[134:135]
	s_mov_b32 m0, s34
	s_nop 0
	global_load_lds_dwordx4 v[222:223], off
	v_mfma_f32_16x16x32_bf16 v[12:15], v[144:147], v[210:213], 0
	v_mfma_f32_16x16x32_bf16 v[8:11], v[160:163], v[210:213], 0
	v_mfma_f32_16x16x32_bf16 v[60:63], v[148:151], v[188:191], v[60:63]
	v_mfma_f32_16x16x32_bf16 v[56:59], v[164:167], v[188:191], v[56:59]
	v_mfma_f32_16x16x32_bf16 v[44:47], v[148:151], v[196:199], v[44:47]
	v_mfma_f32_16x16x32_bf16 v[40:43], v[164:167], v[196:199], v[40:43]
	v_mfma_f32_16x16x32_bf16 v[28:31], v[148:151], v[206:209], v[28:31]
	v_mfma_f32_16x16x32_bf16 v[24:27], v[164:167], v[206:209], v[24:27]
	v_mfma_f32_16x16x32_bf16 v[12:15], v[148:151], v[214:217], v[12:15]
	v_mfma_f32_16x16x32_bf16 v[8:11], v[164:167], v[214:217], v[8:11]
	s_setprio 0
	s_setprio 1
	v_mfma_f32_16x16x32_bf16 v[52:55], v[168:171], v[184:187], 0
	v_mfma_f32_16x16x32_bf16 v[48:51], v[176:179], v[184:187], 0
	s_mov_b32 m0, s37
	s_nop 0
	global_load_lds_dwordx4 v[224:225], off
	v_mfma_f32_16x16x32_bf16 v[36:39], v[168:171], v[192:195], 0
	v_mfma_f32_16x16x32_bf16 v[32:35], v[176:179], v[192:195], 0
	v_mfma_f32_16x16x32_bf16 v[20:23], v[168:171], v[200:203], 0
	v_mfma_f32_16x16x32_bf16 v[16:19], v[176:179], v[200:203], 0
	v_mfma_f32_16x16x32_bf16 v[4:7], v[168:171], v[210:213], 0
	v_mfma_f32_16x16x32_bf16 v[0:3], v[176:179], v[210:213], 0
	v_mfma_f32_16x16x32_bf16 v[52:55], v[172:175], v[188:191], v[52:55]
	v_mfma_f32_16x16x32_bf16 v[48:51], v[180:183], v[188:191], v[48:51]
	v_mfma_f32_16x16x32_bf16 v[36:39], v[172:175], v[196:199], v[36:39]
	v_mfma_f32_16x16x32_bf16 v[32:35], v[180:183], v[196:199], v[32:35]
	v_mfma_f32_16x16x32_bf16 v[20:23], v[172:175], v[206:209], v[20:23]
	v_mfma_f32_16x16x32_bf16 v[16:19], v[180:183], v[206:209], v[16:19]
	v_mfma_f32_16x16x32_bf16 v[4:7], v[172:175], v[214:217], v[4:7]
	v_mfma_f32_16x16x32_bf16 v[0:3], v[180:183], v[214:217], v[0:3]
	s_setprio 0
	s_barrier
	s_add_i32 s58, 0, 0x18000
	v_add_u32_e32 v159, s58, v153
	s_add_i32 s59, 0, 0x1c000
	ds_read_b128 v[144:147], v159
	ds_read_b128 v[148:151], v159 offset:1024
	ds_read_b128 v[160:163], v159 offset:2048
	ds_read_b128 v[164:167], v159 offset:3072
	v_add_u32_e32 v159, s59, v153
	ds_read_b128 v[168:171], v159
	ds_read_b128 v[172:175], v159 offset:1024
	ds_read_b128 v[176:179], v159 offset:2048
	ds_read_b128 v[180:183], v159 offset:3072
	s_add_u32 s42, s42, 0x40000
	s_addc_u32 s43, s43, 0
	s_mov_b32 m0, s44
	v_lshl_add_u64 v[226:227], s[42:43], 0, v[134:135]
	ds_read_b128 v[184:187], v157 offset:32768
	ds_read_b128 v[188:191], v157 offset:33792
	ds_read_b128 v[192:195], v157 offset:34816
	ds_read_b128 v[196:199], v157 offset:35840
	ds_read_b128 v[200:203], v157 offset:36864
	ds_read_b128 v[206:209], v157 offset:37888
	ds_read_b128 v[210:213], v157 offset:38912
	ds_read_b128 v[214:217], v157 offset:39936
	global_load_lds_dwordx4 v[226:227], off
	v_lshl_add_u64 v[226:227], s[42:43], 0, v[130:131]
	s_mov_b32 m0, s45
	s_nop 0
	global_load_lds_dwordx4 v[226:227], off
	s_waitcnt vmcnt(8)
	s_waitcnt lgkmcnt(0)
	s_barrier
	s_setprio 1
	s_waitcnt lgkmcnt(0)
	v_mfma_f32_16x16x32_bf16 v[124:127], v[144:147], v[184:187], v[124:127]
	v_mfma_f32_16x16x32_bf16 v[120:123], v[160:163], v[184:187], v[120:123]
	v_mfma_f32_16x16x32_bf16 v[108:111], v[144:147], v[192:195], v[108:111]
	v_mfma_f32_16x16x32_bf16 v[104:107], v[160:163], v[192:195], v[104:107]
	v_mfma_f32_16x16x32_bf16 v[92:95], v[144:147], v[200:203], v[92:95]
	v_mfma_f32_16x16x32_bf16 v[88:91], v[160:163], v[200:203], v[88:91]
	v_mfma_f32_16x16x32_bf16 v[76:79], v[144:147], v[210:213], v[76:79]
	v_mfma_f32_16x16x32_bf16 v[72:75], v[160:163], v[210:213], v[72:75]
	v_mfma_f32_16x16x32_bf16 v[124:127], v[148:151], v[188:191], v[124:127]
	v_mfma_f32_16x16x32_bf16 v[120:123], v[164:167], v[188:191], v[120:123]
	v_mfma_f32_16x16x32_bf16 v[108:111], v[148:151], v[196:199], v[108:111]
	v_mfma_f32_16x16x32_bf16 v[104:107], v[164:167], v[196:199], v[104:107]
	v_mfma_f32_16x16x32_bf16 v[92:95], v[148:151], v[206:209], v[92:95]
	v_mfma_f32_16x16x32_bf16 v[88:91], v[164:167], v[206:209], v[88:91]
	v_mfma_f32_16x16x32_bf16 v[76:79], v[148:151], v[214:217], v[76:79]
	v_mfma_f32_16x16x32_bf16 v[72:75], v[164:167], v[214:217], v[72:75]
	s_setprio 0
	s_setprio 1
	v_mfma_f32_16x16x32_bf16 v[116:119], v[168:171], v[184:187], v[116:119]
	v_mfma_f32_16x16x32_bf16 v[112:115], v[176:179], v[184:187], v[112:115]
	v_mfma_f32_16x16x32_bf16 v[100:103], v[168:171], v[192:195], v[100:103]
	v_mfma_f32_16x16x32_bf16 v[96:99], v[176:179], v[192:195], v[96:99]
	v_mfma_f32_16x16x32_bf16 v[84:87], v[168:171], v[200:203], v[84:87]
	v_mfma_f32_16x16x32_bf16 v[80:83], v[176:179], v[200:203], v[80:83]
	v_mfma_f32_16x16x32_bf16 v[68:71], v[168:171], v[210:213], v[68:71]
	v_mfma_f32_16x16x32_bf16 v[64:67], v[176:179], v[210:213], v[64:67]
	v_mfma_f32_16x16x32_bf16 v[116:119], v[172:175], v[188:191], v[116:119]
	v_mfma_f32_16x16x32_bf16 v[112:115], v[180:183], v[188:191], v[112:115]
	v_mfma_f32_16x16x32_bf16 v[100:103], v[172:175], v[196:199], v[100:103]
	v_mfma_f32_16x16x32_bf16 v[96:99], v[180:183], v[196:199], v[96:99]
	v_mfma_f32_16x16x32_bf16 v[84:87], v[172:175], v[206:209], v[84:87]
	v_mfma_f32_16x16x32_bf16 v[80:83], v[180:183], v[206:209], v[80:83]
	v_mfma_f32_16x16x32_bf16 v[68:71], v[172:175], v[214:217], v[68:71]
	v_mfma_f32_16x16x32_bf16 v[64:67], v[180:183], v[214:217], v[64:67]
	s_setprio 0
	s_barrier
; #define PG8_STAGE(bufoff, gbase, voff) do { _Pragma("unroll") for (int _i = 0; _i < 2; ++_i) \
;         __builtin_amdgcn_global_load_lds((const unsigned*)((const char*)(gbase) + (voff)[_i]), (PG8_LAS unsigned*)(lds + (bufoff) + ldsw + _i * 8192), 16, 0, 0); } while (0)
; #define PG8_LDA(dst, b, h) do { _Pragma("unroll") for (int m = 0; m < 4; ++m) _Pragma("unroll") for (int k = 0; k < 2; ++k) dst[m][k] = *(const PG8_LAS bf16x8*)(lds + PG8_SA(b, h) + aoff + m * 2048 + k * 1024); } while (0)
; #define PG8_LDB(dst, b, h) do { _Pragma("unroll") for (int n = 0; n < 2; ++n) _Pragma("unroll") for (int k = 0; k < 2; ++k) dst[n][k] = *(const PG8_LAS bf16x8*)(lds + PG8_SB(b, h) + boff + n * 2048 + k * 1024); } while (0)
; template <class Epi, class Sched, bool ALIGN_EPI = false, bool SP2 = false>
; __device__ __forceinline__ void gemm_phase(PG8_LAS unsigned char* lds, const Gemm g, const Sched& S, const Epi& E) {
;     ...
;         for (int t = 0; t < nt; t += 2) {
;             const bool last = (t == nt - 2);
;             const char* a1 = cA + (size_t)(t + 1) * kstep;
;             const char* a2 = last ? nA : cA + (size_t)(t + 2) * kstep; const char* b2 = last ? nB : cB + (size_t)(t + 2) * kstep;
;             const char* a3 = a2 + kstep; const char* b3 = b2 + kstep;
;             if (last && has_next) S.a_ready(nxt);
;             if constexpr (SP2) {
;             PG8_LDB(B0, 0, 0); PG8_LDB(B1, 0, 1); PG8_SCHED; PG8_LDA(At, 0, 0); PG8_STAGE(PG8_SA(1, 1), a1 + hstep, voffA);
;             PG8_WAIT_V(8); PG8_WAIT_L(0); PG8_BAR; PG8_MMA(0, 0, At, B0); PG8_MMA(0, 1, At, B1); PG8_BAR; PG8_SCHED;
;             PG8_LDA(At, 0, 1); PG8_STAGE(PG8_SB(0, 0), b2, voffB); PG8_STAGE(PG8_SB(0, 1), b2 + hstep, voffB); PG8_STAGE(PG8_SA(0, 0), a2, voffA);
;             PG8_WAIT_V(8); PG8_WAIT_L(0); PG8_BAR; PG8_MMA(1, 0, At, B0); PG8_MMA(1, 1, At, B1); PG8_BAR; PG8_SCHED;
;             PG8_LDB(B0, 1, 0); PG8_LDB(B1, 1, 1); PG8_SCHED; PG8_LDA(At, 1, 0); PG8_STAGE(PG8_SA(0, 1), a2 + hstep, voffA);
;             PG8_WAIT_V(8); PG8_WAIT_L(0); PG8_BAR; PG8_MMA(0, 0, At, B0); PG8_MMA(0, 1, At, B1); PG8_BAR; PG8_SCHED;
;             PG8_LDA(At, 1, 1); PG8_STAGE(PG8_SB(1, 0), b3, voffB); PG8_STAGE(PG8_SB(1, 1), b3 + hstep, voffB); PG8_STAGE(PG8_SA(1, 0), a3, voffA);
;             PG8_WAIT_V(8); PG8_WAIT_L(0); PG8_BAR; PG8_MMA(1, 0, At, B0); PG8_MMA(1, 1, At, B1); PG8_BAR; PG8_SCHED;
	s_add_i32 s42, s58, s15
	v_lshl_add_u64 v[218:219], v[218:219], 0, s[8:9]
	s_mov_b32 m0, s42
	ds_read_b128 v[184:187], v157 offset:49152
	ds_read_b128 v[188:191], v157 offset:50176
	ds_read_b128 v[192:195], v157 offset:51200
	ds_read_b128 v[196:199], v157 offset:52224
	ds_read_b128 v[200:203], v157 offset:53248
	ds_read_b128 v[206:209], v157 offset:54272
	ds_read_b128 v[210:213], v157 offset:55296
	ds_read_b128 v[214:217], v157 offset:56320
	global_load_lds_dwordx4 v[218:219], off
	s_add_i32 m0, s42, 0x2000
	s_add_u32 s40, s40, 0x40080
	v_lshl_add_u64 v[218:219], v[220:221], 0, s[8:9]
	s_addc_u32 s41, s41, 0
	s_add_i32 s42, s59, s15
	global_load_lds_dwordx4 v[218:219], off
	v_lshl_add_u64 v[218:219], s[40:41], 0, v[132:133]
	s_mov_b32 m0, s42
	s_nop 0
	global_load_lds_dwordx4 v[218:219], off
	v_lshl_add_u64 v[218:219], s[40:41], 0, v[128:129]
	s_add_i32 m0, s42, 0x2000
	s_nop 0
	global_load_lds_dwordx4 v[218:219], off
	s_waitcnt vmcnt(6)
	s_waitcnt lgkmcnt(0)
	s_barrier
	s_setprio 1
	s_waitcnt lgkmcnt(0)
	v_mfma_f32_16x16x32_bf16 v[60:63], v[144:147], v[184:187], v[60:63]
	v_mfma_f32_16x16x32_bf16 v[56:59], v[160:163], v[184:187], v[56:59]
	v_mfma_f32_16x16x32_bf16 v[44:47], v[144:147], v[192:195], v[44:47]
	v_mfma_f32_16x16x32_bf16 v[40:43], v[160:163], v[192:195], v[40:43]
	v_mfma_f32_16x16x32_bf16 v[28:31], v[144:147], v[200:203], v[28:31]
	v_mfma_f32_16x16x32_bf16 v[24:27], v[160:163], v[200:203], v[24:27]
	v_lshl_add_u64 v[218:219], v[222:223], 0, s[8:9]
	s_mov_b32 m0, s47
	s_nop 0
	global_load_lds_dwordx4 v[218:219], off
	v_mfma_f32_16x16x32_bf16 v[12:15], v[144:147], v[210:213], v[12:15]
	v_mfma_f32_16x16x32_bf16 v[8:11], v[160:163], v[210:213], v[8:11]
	v_mfma_f32_16x16x32_bf16 v[60:63], v[148:151], v[188:191], v[60:63]
	v_mfma_f32_16x16x32_bf16 v[56:59], v[164:167], v[188:191], v[56:59]
	v_mfma_f32_16x16x32_bf16 v[44:47], v[148:151], v[196:199], v[44:47]
	v_mfma_f32_16x16x32_bf16 v[40:43], v[164:167], v[196:199], v[40:43]
	v_mfma_f32_16x16x32_bf16 v[28:31], v[148:151], v[206:209], v[28:31]
	v_mfma_f32_16x16x32_bf16 v[24:27], v[164:167], v[206:209], v[24:27]
	v_mfma_f32_16x16x32_bf16 v[12:15], v[148:151], v[214:217], v[12:15]
	v_mfma_f32_16x16x32_bf16 v[8:11], v[164:167], v[214:217], v[8:11]
	s_setprio 0
	s_setprio 1
	v_mfma_f32_16x16x32_bf16 v[52:55], v[168:171], v[184:187], v[52:55]
	v_mfma_f32_16x16x32_bf16 v[48:51], v[176:179], v[184:187], v[48:51]
	v_lshl_add_u64 v[218:219], v[224:225], 0, s[8:9]
	s_mov_b32 m0, s48
	s_nop 0
	global_load_lds_dwordx4 v[218:219], off
	v_mfma_f32_16x16x32_bf16 v[36:39], v[168:171], v[192:195], v[36:39]
	v_mfma_f32_16x16x32_bf16 v[32:35], v[176:179], v[192:195], v[32:35]
	v_mfma_f32_16x16x32_bf16 v[20:23], v[168:171], v[200:203], v[20:23]
	v_mfma_f32_16x16x32_bf16 v[16:19], v[176:179], v[200:203], v[16:19]
	v_mfma_f32_16x16x32_bf16 v[4:7], v[168:171], v[210:213], v[4:7]
	v_mfma_f32_16x16x32_bf16 v[0:3], v[176:179], v[210:213], v[0:3]
	v_mfma_f32_16x16x32_bf16 v[52:55], v[172:175], v[188:191], v[52:55]
	v_mfma_f32_16x16x32_bf16 v[48:51], v[180:183], v[188:191], v[48:51]
	v_mfma_f32_16x16x32_bf16 v[36:39], v[172:175], v[196:199], v[36:39]
	v_mfma_f32_16x16x32_bf16 v[32:35], v[180:183], v[196:199], v[32:35]
	v_mfma_f32_16x16x32_bf16 v[20:23], v[172:175], v[206:209], v[20:23]
	v_mfma_f32_16x16x32_bf16 v[16:19], v[180:183], v[206:209], v[16:19]
	v_mfma_f32_16x16x32_bf16 v[4:7], v[172:175], v[214:217], v[4:7]
	v_mfma_f32_16x16x32_bf16 v[0:3], v[180:183], v[214:217], v[0:3]
	s_setprio 0
	s_barrier
	s_add_i32 s57, s57, 2
	s_add_u32 s38, s38, 0x100
	s_addc_u32 s39, s39, 0
	s_add_u32 s55, s55, 0x100
	s_addc_u32 s56, s56, 0
.LBB0_1900:
	ds_read_b128 v[144:147], v155
	ds_read_b128 v[148:151], v155 offset:1024
	ds_read_b128 v[160:163], v155 offset:2048
	ds_read_b128 v[164:167], v155 offset:3072
	ds_read_b128 v[168:171], v156
	ds_read_b128 v[172:175], v156 offset:1024
	ds_read_b128 v[176:179], v156 offset:2048
	ds_read_b128 v[180:183], v156 offset:3072
	s_add_u32 s40, s38, 0xfffc0080
	s_addc_u32 s41, s39, -1
	s_cmp_eq_u32 s57, 12
	s_cselect_b32 s43, s25, s41
	s_cselect_b32 s42, s53, s40
	s_cselect_b32 s41, s13, s56
	s_cselect_b32 s40, s54, s55
	v_lshl_add_u64 v[218:219], s[38:39], 0, v[136:137]
	s_add_i32 m0, s34, 0xc000
	ds_read_b128 v[184:187], v157
	ds_read_b128 v[188:191], v157 offset:1024
	ds_read_b128 v[192:195], v157 offset:2048
	ds_read_b128 v[196:199], v157 offset:3072
	ds_read_b128 v[200:203], v157 offset:4096
	ds_read_b128 v[206:209], v157 offset:5120
	ds_read_b128 v[210:213], v157 offset:6144
	ds_read_b128 v[214:217], v157 offset:7168
	global_load_lds_dwordx4 v[218:219], off
	v_lshl_add_u64 v[218:219], s[38:39], 0, v[138:139]
	s_add_i32 m0, s34, 0xe000
	s_nop 0
	global_load_lds_dwordx4 v[218:219], off
	s_waitcnt vmcnt(8)
	s_waitcnt lgkmcnt(0)
	s_barrier
; #define PG8_STAGE(bufoff, gbase, voff) do { _Pragma("unroll") for (int _i = 0; _i < 2; ++_i) \
;         __builtin_amdgcn_global_load_lds((const unsigned*)((const char*)(gbase) + (voff)[_i]), (PG8_LAS unsigned*)(lds + (bufoff) + ldsw + _i * 8192), 16, 0, 0); } while (0)
; #define PG8_LDA(dst, b, h) do { _Pragma("unroll") for (int m = 0; m < 4; ++m) _Pragma("unroll") for (int k = 0; k < 2; ++k) dst[m][k] = *(const PG8_LAS bf16x8*)(lds + PG8_SA(b, h) + aoff + m * 2048 + k * 1024); } while (0)
; #define PG8_LDB(dst, b, h) do { _Pragma("unroll") for (int n = 0; n < 2; ++n) _Pragma("unroll") for (int k = 0; k < 2; ++k) dst[n][k] = *(const PG8_LAS bf16x8*)(lds + PG8_SB(b, h) + boff + n * 2048 + k * 1024); } while (0)
; #define PG8_MMA(ai, bj, At, Bt) do { __builtin_amdgcn_s_setprio(1); _Pragma("unroll") for (int m = 0; m < 4; ++m) _Pragma("unroll") for (int n = 0; n < 2; ++n) _Pragma("unroll") for (int k = 0; k < 2; ++k) \
;         acc[ai][bj][m][n] = __builtin_amdgcn_mfma_f32_16x16x32_bf16(Bt[n][k], At[m][k], acc[ai][bj][m][n], 0, 0, 0); __builtin_amdgcn_s_setprio(0); } while (0)
; #define PG8_WAIT_V(n) asm volatile("s_waitcnt vmcnt(" #n ")" ::: "memory")
; #define PG8_WAIT_L(n) asm volatile("s_waitcnt lgkmcnt(" #n ")" ::: "memory")
; #define PG8_BAR __builtin_amdgcn_s_barrier()
; #define PG8_SCHED __builtin_amdgcn_sched_barrier(0)
; template <class Epi, class Sched, bool ALIGN_EPI = false, bool SP2 = false>
; __device__ __forceinline__ void gemm_phase(PG8_LAS unsigned char* lds, const Gemm g, const Sched& S, const Epi& E) {
;     ...
;             PG8_LDB(B0, 0, 0); PG8_LDB(B1, 0, 1); PG8_SCHED; PG8_LDA(At, 0, 0); PG8_STAGE(PG8_SA(1, 1), a1 + hstep, voffA);
;             PG8_WAIT_V(8); PG8_WAIT_L(0); PG8_BAR; PG8_MMA(0, 0, At, B0); PG8_MMA(0, 1, At, B1); PG8_BAR; PG8_SCHED;
;             PG8_LDA(At, 0, 1); PG8_STAGE(PG8_SB(0, 0), b2, voffB); PG8_STAGE(PG8_SB(0, 1), b2 + hstep, voffB); PG8_STAGE(PG8_SA(0, 0), a2, voffA);
;             PG8_WAIT_V(8); PG8_WAIT_L(0); PG8_BAR; PG8_MMA(1, 0, At, B0); PG8_MMA(1, 1, At, B1); PG8_BAR; PG8_SCHED;
	s_setprio 1
	s_waitcnt lgkmcnt(0)
	v_mfma_f32_16x16x32_bf16 v[124:127], v[144:147], v[184:187], v[124:127]
	v_mfma_f32_16x16x32_bf16 v[120:123], v[160:163], v[184:187], v[120:123]
	v_mfma_f32_16x16x32_bf16 v[108:111], v[144:147], v[192:195], v[108:111]
	v_mfma_f32_16x16x32_bf16 v[104:107], v[160:163], v[192:195], v[104:107]
	v_mfma_f32_16x16x32_bf16 v[92:95], v[144:147], v[200:203], v[92:95]
	v_mfma_f32_16x16x32_bf16 v[88:91], v[160:163], v[200:203], v[88:91]
	v_mfma_f32_16x16x32_bf16 v[76:79], v[144:147], v[210:213], v[76:79]
	v_mfma_f32_16x16x32_bf16 v[72:75], v[160:163], v[210:213], v[72:75]
	v_mfma_f32_16x16x32_bf16 v[124:127], v[148:151], v[188:191], v[124:127]
	v_mfma_f32_16x16x32_bf16 v[120:123], v[164:167], v[188:191], v[120:123]
	v_mfma_f32_16x16x32_bf16 v[108:111], v[148:151], v[196:199], v[108:111]
	v_mfma_f32_16x16x32_bf16 v[104:107], v[164:167], v[196:199], v[104:107]
	v_mfma_f32_16x16x32_bf16 v[92:95], v[148:151], v[206:209], v[92:95]
	v_mfma_f32_16x16x32_bf16 v[88:91], v[164:167], v[206:209], v[88:91]
	v_mfma_f32_16x16x32_bf16 v[76:79], v[148:151], v[214:217], v[76:79]
	v_mfma_f32_16x16x32_bf16 v[72:75], v[164:167], v[214:217], v[72:75]
	s_setprio 0
	s_setprio 1
	v_mfma_f32_16x16x32_bf16 v[116:119], v[168:171], v[184:187], v[116:119]
	v_mfma_f32_16x16x32_bf16 v[112:115], v[176:179], v[184:187], v[112:115]
	v_mfma_f32_16x16x32_bf16 v[100:103], v[168:171], v[192:195], v[100:103]
	v_mfma_f32_16x16x32_bf16 v[96:99], v[176:179], v[192:195], v[96:99]
	v_mfma_f32_16x16x32_bf16 v[84:87], v[168:171], v[200:203], v[84:87]
	v_mfma_f32_16x16x32_bf16 v[80:83], v[176:179], v[200:203], v[80:83]
	v_mfma_f32_16x16x32_bf16 v[68:71], v[168:171], v[210:213], v[68:71]
	v_mfma_f32_16x16x32_bf16 v[64:67], v[176:179], v[210:213], v[64:67]
	v_mfma_f32_16x16x32_bf16 v[116:119], v[172:175], v[188:191], v[116:119]
	v_mfma_f32_16x16x32_bf16 v[112:115], v[180:183], v[188:191], v[112:115]
	v_mfma_f32_16x16x32_bf16 v[100:103], v[172:175], v[196:199], v[100:103]
	v_mfma_f32_16x16x32_bf16 v[96:99], v[180:183], v[196:199], v[96:99]
	v_mfma_f32_16x16x32_bf16 v[84:87], v[172:175], v[206:209], v[84:87]
	v_mfma_f32_16x16x32_bf16 v[80:83], v[180:183], v[206:209], v[80:83]
	v_mfma_f32_16x16x32_bf16 v[68:71], v[172:175], v[214:217], v[68:71]
	v_mfma_f32_16x16x32_bf16 v[64:67], v[180:183], v[214:217], v[64:67]
	s_setprio 0
	s_barrier
	s_add_i32 s58, s49, s15
	v_lshl_add_u64 v[218:219], s[40:41], 0, v[132:133]
	s_mov_b32 m0, s58
	ds_read_b128 v[184:187], v157 offset:16384
	ds_read_b128 v[188:191], v157 offset:17408
	ds_read_b128 v[192:195], v157 offset:18432
	ds_read_b128 v[196:199], v157 offset:19456
	ds_read_b128 v[200:203], v157 offset:20480
	ds_read_b128 v[206:209], v157 offset:21504
	ds_read_b128 v[210:213], v157 offset:22528
	ds_read_b128 v[214:217], v157 offset:23552
	global_load_lds_dwordx4 v[218:219], off
	s_add_i32 m0, s58, 0x2000
	s_add_u32 s58, s40, 0x40000
	v_lshl_add_u64 v[220:221], s[40:41], 0, v[128:129]
	s_addc_u32 s59, s41, 0
	s_add_i32 s60, s50, s15
	global_load_lds_dwordx4 v[220:221], off
	v_lshl_add_u64 v[222:223], s[58:59], 0, v[132:133]
	s_mov_b32 m0, s60
	v_lshl_add_u64 v[224:225], s[42:43], 0, v[130:131]
	global_load_lds_dwordx4 v[222:223], off
	v_lshl_add_u64 v[222:223], s[58:59], 0, v[128:129]
	s_add_i32 m0, s60, 0x2000
	s_nop 0
	global_load_lds_dwordx4 v[222:223], off
	s_waitcnt vmcnt(6)
	s_waitcnt lgkmcnt(0)
	s_barrier
	s_setprio 1
	s_waitcnt lgkmcnt(0)
	v_mfma_f32_16x16x32_bf16 v[60:63], v[144:147], v[184:187], v[60:63]
	v_mfma_f32_16x16x32_bf16 v[56:59], v[160:163], v[184:187], v[56:59]
	v_mfma_f32_16x16x32_bf16 v[44:47], v[144:147], v[192:195], v[44:47]
	v_mfma_f32_16x16x32_bf16 v[40:43], v[160:163], v[192:195], v[40:43]
	v_mfma_f32_16x16x32_bf16 v[28:31], v[144:147], v[200:203], v[28:31]
	v_mfma_f32_16x16x32_bf16 v[24:27], v[160:163], v[200:203], v[24:27]
	v_lshl_add_u64 v[222:223], s[42:43], 0, v[134:135]
	s_mov_b32 m0, s34
	s_nop 0
	global_load_lds_dwordx4 v[222:223], off
	v_mfma_f32_16x16x32_bf16 v[12:15], v[144:147], v[210:213], v[12:15]
	v_mfma_f32_16x16x32_bf16 v[8:11], v[160:163], v[210:213], v[8:11]
	v_mfma_f32_16x16x32_bf16 v[60:63], v[148:151], v[188:191], v[60:63]
	v_mfma_f32_16x16x32_bf16 v[56:59], v[164:167], v[188:191], v[56:59]
	v_mfma_f32_16x16x32_bf16 v[44:47], v[148:151], v[196:199], v[44:47]
	v_mfma_f32_16x16x32_bf16 v[40:43], v[164:167], v[196:199], v[40:43]
	v_mfma_f32_16x16x32_bf16 v[28:31], v[148:151], v[206:209], v[28:31]
	v_mfma_f32_16x16x32_bf16 v[24:27], v[164:167], v[206:209], v[24:27]
	v_mfma_f32_16x16x32_bf16 v[12:15], v[148:151], v[214:217], v[12:15]
	v_mfma_f32_16x16x32_bf16 v[8:11], v[164:167], v[214:217], v[8:11]
	s_setprio 0
	s_setprio 1
	v_mfma_f32_16x16x32_bf16 v[52:55], v[168:171], v[184:187], v[52:55]
	v_mfma_f32_16x16x32_bf16 v[48:51], v[176:179], v[184:187], v[48:51]
	s_mov_b32 m0, s37
	s_nop 0
	global_load_lds_dwordx4 v[224:225], off
	v_mfma_f32_16x16x32_bf16 v[36:39], v[168:171], v[192:195], v[36:39]
	v_mfma_f32_16x16x32_bf16 v[32:35], v[176:179], v[192:195], v[32:35]
	v_mfma_f32_16x16x32_bf16 v[20:23], v[168:171], v[200:203], v[20:23]
	v_mfma_f32_16x16x32_bf16 v[16:19], v[176:179], v[200:203], v[16:19]
	v_mfma_f32_16x16x32_bf16 v[4:7], v[168:171], v[210:213], v[4:7]
	v_mfma_f32_16x16x32_bf16 v[0:3], v[176:179], v[210:213], v[0:3]
	v_mfma_f32_16x16x32_bf16 v[52:55], v[172:175], v[188:191], v[52:55]
	v_mfma_f32_16x16x32_bf16 v[48:51], v[180:183], v[188:191], v[48:51]
	v_mfma_f32_16x16x32_bf16 v[36:39], v[172:175], v[196:199], v[36:39]
	v_mfma_f32_16x16x32_bf16 v[32:35], v[180:183], v[196:199], v[32:35]
	v_mfma_f32_16x16x32_bf16 v[20:23], v[172:175], v[206:209], v[20:23]
	v_mfma_f32_16x16x32_bf16 v[16:19], v[180:183], v[206:209], v[16:19]
	v_mfma_f32_16x16x32_bf16 v[4:7], v[172:175], v[214:217], v[4:7]
	v_mfma_f32_16x16x32_bf16 v[0:3], v[180:183], v[214:217], v[0:3]
	s_setprio 0
	s_barrier
; #define PG8_STAGE(bufoff, gbase, voff) do { _Pragma("unroll") for (int _i = 0; _i < 2; ++_i) \
;         __builtin_amdgcn_global_load_lds((const unsigned*)((const char*)(gbase) + (voff)[_i]), (PG8_LAS unsigned*)(lds + (bufoff) + ldsw + _i * 8192), 16, 0, 0); } while (0)
; #define PG8_LDA(dst, b, h) do { _Pragma("unroll") for (int m = 0; m < 4; ++m) _Pragma("unroll") for (int k = 0; k < 2; ++k) dst[m][k] = *(const PG8_LAS bf16x8*)(lds + PG8_SA(b, h) + aoff + m * 2048 + k * 1024); } while (0)
; #define PG8_LDB(dst, b, h) do { _Pragma("unroll") for (int n = 0; n < 2; ++n) _Pragma("unroll") for (int k = 0; k < 2; ++k) dst[n][k] = *(const PG8_LAS bf16x8*)(lds + PG8_SB(b, h) + boff + n * 2048 + k * 1024); } while (0)
; #define PG8_MMA(ai, bj, At, Bt) do { __builtin_amdgcn_s_setprio(1); _Pragma("unroll") for (int m = 0; m < 4; ++m) _Pragma("unroll") for (int n = 0; n < 2; ++n) _Pragma("unroll") for (int k = 0; k < 2; ++k) \
;         acc[ai][bj][m][n] = __builtin_amdgcn_mfma_f32_16x16x32_bf16(Bt[n][k], At[m][k], acc[ai][bj][m][n], 0, 0, 0); __builtin_amdgcn_s_setprio(0); } while (0)
; #define PG8_WAIT_V(n) asm volatile("s_waitcnt vmcnt(" #n ")" ::: "memory")
; #define PG8_WAIT_L(n) asm volatile("s_waitcnt lgkmcnt(" #n ")" ::: "memory")
; #define PG8_BAR __builtin_amdgcn_s_barrier()
; #define PG8_SCHED __builtin_amdgcn_sched_barrier(0)
; template <class Epi, class Sched, bool ALIGN_EPI = false, bool SP2 = false>
; __device__ __forceinline__ void gemm_phase(PG8_LAS unsigned char* lds, const Gemm g, const Sched& S, const Epi& E) {
;     ...
;             PG8_LDB(B0, 1, 0); PG8_LDB(B1, 1, 1); PG8_SCHED; PG8_LDA(At, 1, 0); PG8_STAGE(PG8_SA(0, 1), a2 + hstep, voffA);
;             PG8_WAIT_V(8); PG8_WAIT_L(0); PG8_BAR; PG8_MMA(0, 0, At, B0); PG8_MMA(0, 1, At, B1); PG8_BAR; PG8_SCHED;
	s_add_i32 s58, 0, 0x18000
	v_add_u32_e32 v159, s58, v153
	s_add_i32 s59, 0, 0x1c000
	ds_read_b128 v[144:147], v159
	ds_read_b128 v[148:151], v159 offset:1024
	ds_read_b128 v[160:163], v159 offset:2048
	ds_read_b128 v[164:167], v159 offset:3072
	v_add_u32_e32 v159, s59, v153
	ds_read_b128 v[168:171], v159
	ds_read_b128 v[172:175], v159 offset:1024
	ds_read_b128 v[176:179], v159 offset:2048
	ds_read_b128 v[180:183], v159 offset:3072
	s_add_u32 s42, s42, 0x40000
	s_addc_u32 s43, s43, 0
	s_mov_b32 m0, s44
	v_lshl_add_u64 v[226:227], s[42:43], 0, v[134:135]
	ds_read_b128 v[184:187], v157 offset:32768
	ds_read_b128 v[188:191], v157 offset:33792
	ds_read_b128 v[192:195], v157 offset:34816
	ds_read_b128 v[196:199], v157 offset:35840
	ds_read_b128 v[200:203], v157 offset:36864
	ds_read_b128 v[206:209], v157 offset:37888
	ds_read_b128 v[210:213], v157 offset:38912
	ds_read_b128 v[214:217], v157 offset:39936
	global_load_lds_dwordx4 v[226:227], off
	v_lshl_add_u64 v[226:227], s[42:43], 0, v[130:131]
	s_mov_b32 m0, s45
	s_nop 0
	global_load_lds_dwordx4 v[226:227], off
	s_waitcnt vmcnt(8)
	s_waitcnt lgkmcnt(0)
	s_barrier
	s_setprio 1
	s_waitcnt lgkmcnt(0)
	v_mfma_f32_16x16x32_bf16 v[124:127], v[144:147], v[184:187], v[124:127]
	v_mfma_f32_16x16x32_bf16 v[120:123], v[160:163], v[184:187], v[120:123]
	v_mfma_f32_16x16x32_bf16 v[108:111], v[144:147], v[192:195], v[108:111]
	v_mfma_f32_16x16x32_bf16 v[104:107], v[160:163], v[192:195], v[104:107]
	v_mfma_f32_16x16x32_bf16 v[92:95], v[144:147], v[200:203], v[92:95]
	v_mfma_f32_16x16x32_bf16 v[88:91], v[160:163], v[200:203], v[88:91]
	v_mfma_f32_16x16x32_bf16 v[76:79], v[144:147], v[210:213], v[76:79]
	v_mfma_f32_16x16x32_bf16 v[72:75], v[160:163], v[210:213], v[72:75]
	v_mfma_f32_16x16x32_bf16 v[124:127], v[148:151], v[188:191], v[124:127]
	v_mfma_f32_16x16x32_bf16 v[120:123], v[164:167], v[188:191], v[120:123]
	v_mfma_f32_16x16x32_bf16 v[108:111], v[148:151], v[196:199], v[108:111]
	v_mfma_f32_16x16x32_bf16 v[104:107], v[164:167], v[196:199], v[104:107]
	v_mfma_f32_16x16x32_bf16 v[92:95], v[148:151], v[206:209], v[92:95]
	v_mfma_f32_16x16x32_bf16 v[88:91], v[164:167], v[206:209], v[88:91]
	v_mfma_f32_16x16x32_bf16 v[76:79], v[148:151], v[214:217], v[76:79]
	v_mfma_f32_16x16x32_bf16 v[72:75], v[164:167], v[214:217], v[72:75]
	s_setprio 0
	s_setprio 1
	v_mfma_f32_16x16x32_bf16 v[116:119], v[168:171], v[184:187], v[116:119]
	v_mfma_f32_16x16x32_bf16 v[112:115], v[176:179], v[184:187], v[112:115]
	v_mfma_f32_16x16x32_bf16 v[100:103], v[168:171], v[192:195], v[100:103]
	v_mfma_f32_16x16x32_bf16 v[96:99], v[176:179], v[192:195], v[96:99]
	v_mfma_f32_16x16x32_bf16 v[84:87], v[168:171], v[200:203], v[84:87]
	v_mfma_f32_16x16x32_bf16 v[80:83], v[176:179], v[200:203], v[80:83]
	v_mfma_f32_16x16x32_bf16 v[68:71], v[168:171], v[210:213], v[68:71]
	v_mfma_f32_16x16x32_bf16 v[64:67], v[176:179], v[210:213], v[64:67]
	v_mfma_f32_16x16x32_bf16 v[116:119], v[172:175], v[188:191], v[116:119]
	v_mfma_f32_16x16x32_bf16 v[112:115], v[180:183], v[188:191], v[112:115]
	v_mfma_f32_16x16x32_bf16 v[100:103], v[172:175], v[196:199], v[100:103]
	v_mfma_f32_16x16x32_bf16 v[96:99], v[180:183], v[196:199], v[96:99]
	v_mfma_f32_16x16x32_bf16 v[84:87], v[172:175], v[206:209], v[84:87]
	v_mfma_f32_16x16x32_bf16 v[80:83], v[180:183], v[206:209], v[80:83]
	v_mfma_f32_16x16x32_bf16 v[68:71], v[172:175], v[214:217], v[68:71]
	v_mfma_f32_16x16x32_bf16 v[64:67], v[180:183], v[214:217], v[64:67]
	s_setprio 0
	s_barrier
; #define PG8_STAGE(bufoff, gbase, voff) do { _Pragma("unroll") for (int _i = 0; _i < 2; ++_i) \
;         __builtin_amdgcn_global_load_lds((const unsigned*)((const char*)(gbase) + (voff)[_i]), (PG8_LAS unsigned*)(lds + (bufoff) + ldsw + _i * 8192), 16, 0, 0); } while (0)
; #define PG8_LDA(dst, b, h) do { _Pragma("unroll") for (int m = 0; m < 4; ++m) _Pragma("unroll") for (int k = 0; k < 2; ++k) dst[m][k] = *(const PG8_LAS bf16x8*)(lds + PG8_SA(b, h) + aoff + m * 2048 + k * 1024); } while (0)
; #define PG8_MMA(ai, bj, At, Bt) do { __builtin_amdgcn_s_setprio(1); _Pragma("unroll") for (int m = 0; m < 4; ++m) _Pragma("unroll") for (int n = 0; n < 2; ++n) _Pragma("unroll") for (int k = 0; k < 2; ++k) \
;         acc[ai][bj][m][n] = __builtin_amdgcn_mfma_f32_16x16x32_bf16(Bt[n][k], At[m][k], acc[ai][bj][m][n], 0, 0, 0); __builtin_amdgcn_s_setprio(0); } while (0)
; #define PG8_WAIT_V(n) asm volatile("s_waitcnt vmcnt(" #n ")" ::: "memory")
; #define PG8_WAIT_L(n) asm volatile("s_waitcnt lgkmcnt(" #n ")" ::: "memory")
; #define PG8_BAR __builtin_amdgcn_s_barrier()
; #define PG8_SCHED __builtin_amdgcn_sched_barrier(0)
; __device__ __forceinline__ float row_rs(const float* ssp, int row) { const unsigned long long v = ((const unsigned long long*)ssp)[row];
;     return __builtin_amdgcn_rsqf((float)v * (1.0f / 4294967296.0f) * (1.0f / 1024.0f) + RMS_EPS); }
; template <class Epi, class Sched, bool ALIGN_EPI = false, bool SP2 = false>
; __device__ __forceinline__ void gemm_phase(PG8_LAS unsigned char* lds, const Gemm g, const Sched& S, const Epi& E) {
;     ...
;             PG8_LDA(At, 1, 1); PG8_STAGE(PG8_SB(1, 0), b3, voffB); PG8_STAGE(PG8_SB(1, 1), b3 + hstep, voffB); PG8_STAGE(PG8_SA(1, 0), a3, voffA);
;             PG8_WAIT_V(8); PG8_WAIT_L(0); PG8_BAR; PG8_MMA(1, 0, At, B0); PG8_MMA(1, 1, At, B1); PG8_BAR; PG8_SCHED;
	s_add_i32 s42, s58, s15
	v_lshl_add_u64 v[218:219], v[218:219], 0, s[8:9]
	s_mov_b32 m0, s42
	ds_read_b128 v[184:187], v157 offset:49152
	ds_read_b128 v[188:191], v157 offset:50176
	ds_read_b128 v[192:195], v157 offset:51200
	ds_read_b128 v[196:199], v157 offset:52224
	ds_read_b128 v[200:203], v157 offset:53248
	ds_read_b128 v[206:209], v157 offset:54272
	ds_read_b128 v[210:213], v157 offset:55296
	ds_read_b128 v[214:217], v157 offset:56320
	global_load_lds_dwordx4 v[218:219], off
	s_add_i32 m0, s42, 0x2000
	s_add_u32 s40, s40, 0x40080
	v_lshl_add_u64 v[218:219], v[220:221], 0, s[8:9]
	s_addc_u32 s41, s41, 0
	s_add_i32 s42, s59, s15
	global_load_lds_dwordx4 v[218:219], off
	v_lshl_add_u64 v[218:219], s[40:41], 0, v[132:133]
	s_mov_b32 m0, s42
	s_nop 0
	global_load_lds_dwordx4 v[218:219], off
	v_lshl_add_u64 v[218:219], s[40:41], 0, v[128:129]
	s_add_i32 m0, s42, 0x2000
	s_nop 0
	global_load_lds_dwordx4 v[218:219], off
	s_waitcnt vmcnt(6)
	s_waitcnt lgkmcnt(0)
	s_barrier
	s_setprio 1
	s_waitcnt lgkmcnt(0)
	v_mfma_f32_16x16x32_bf16 v[60:63], v[144:147], v[184:187], v[60:63]
	v_mfma_f32_16x16x32_bf16 v[56:59], v[160:163], v[184:187], v[56:59]
	v_mfma_f32_16x16x32_bf16 v[44:47], v[144:147], v[192:195], v[44:47]
	v_mfma_f32_16x16x32_bf16 v[40:43], v[160:163], v[192:195], v[40:43]
	v_mfma_f32_16x16x32_bf16 v[28:31], v[144:147], v[200:203], v[28:31]
	v_mfma_f32_16x16x32_bf16 v[24:27], v[160:163], v[200:203], v[24:27]
	v_lshl_add_u64 v[218:219], v[222:223], 0, s[8:9]
	s_mov_b32 m0, s47
	s_nop 0
	global_load_lds_dwordx4 v[218:219], off
	v_mfma_f32_16x16x32_bf16 v[12:15], v[144:147], v[210:213], v[12:15]
	v_mfma_f32_16x16x32_bf16 v[8:11], v[160:163], v[210:213], v[8:11]
	v_mfma_f32_16x16x32_bf16 v[60:63], v[148:151], v[188:191], v[60:63]
	v_mfma_f32_16x16x32_bf16 v[56:59], v[164:167], v[188:191], v[56:59]
	v_mfma_f32_16x16x32_bf16 v[44:47], v[148:151], v[196:199], v[44:47]
	v_mfma_f32_16x16x32_bf16 v[40:43], v[164:167], v[196:199], v[40:43]
	v_mfma_f32_16x16x32_bf16 v[28:31], v[148:151], v[206:209], v[28:31]
	v_mfma_f32_16x16x32_bf16 v[24:27], v[164:167], v[206:209], v[24:27]
	v_mfma_f32_16x16x32_bf16 v[12:15], v[148:151], v[214:217], v[12:15]
	v_mfma_f32_16x16x32_bf16 v[8:11], v[164:167], v[214:217], v[8:11]
	s_setprio 0
	s_setprio 1
	v_mfma_f32_16x16x32_bf16 v[52:55], v[168:171], v[184:187], v[52:55]
	v_mfma_f32_16x16x32_bf16 v[48:51], v[176:179], v[184:187], v[48:51]
	v_lshl_add_u64 v[218:219], v[224:225], 0, s[8:9]
	s_mov_b32 m0, s48
	s_nop 0
	global_load_lds_dwordx4 v[218:219], off
	v_mfma_f32_16x16x32_bf16 v[36:39], v[168:171], v[192:195], v[36:39]
	v_mfma_f32_16x16x32_bf16 v[32:35], v[176:179], v[192:195], v[32:35]
	v_mfma_f32_16x16x32_bf16 v[20:23], v[168:171], v[200:203], v[20:23]
	v_mfma_f32_16x16x32_bf16 v[16:19], v[176:179], v[200:203], v[16:19]
	v_mfma_f32_16x16x32_bf16 v[4:7], v[168:171], v[210:213], v[4:7]
	v_mfma_f32_16x16x32_bf16 v[0:3], v[176:179], v[210:213], v[0:3]
	v_mfma_f32_16x16x32_bf16 v[52:55], v[172:175], v[188:191], v[52:55]
	v_mfma_f32_16x16x32_bf16 v[48:51], v[180:183], v[188:191], v[48:51]
	v_mfma_f32_16x16x32_bf16 v[36:39], v[172:175], v[196:199], v[36:39]
	v_mfma_f32_16x16x32_bf16 v[32:35], v[180:183], v[196:199], v[32:35]
	v_mfma_f32_16x16x32_bf16 v[20:23], v[172:175], v[206:209], v[20:23]
	v_mfma_f32_16x16x32_bf16 v[16:19], v[180:183], v[206:209], v[16:19]
	v_mfma_f32_16x16x32_bf16 v[4:7], v[172:175], v[214:217], v[4:7]
	v_mfma_f32_16x16x32_bf16 v[0:3], v[180:183], v[214:217], v[0:3]
	s_setprio 0
	s_barrier
	s_add_i32 s57, s57, 2
	s_add_u32 s38, s38, 0x100
	s_addc_u32 s39, s39, 0
	s_add_u32 s55, s55, 0x100
	s_addc_u32 s56, s56, 0
	s_cmp_gt_u32 s57, 13
	s_cbranch_scc0 .LBB0_1900
	v_lshl_add_u32 v144, s36, 8, v152
	v_ashrrev_i32_e32 v145, 31, v144
	v_lshl_add_u64 v[150:151], v[144:145], 3, s[0:1]
	global_load_dwordx2 v[182:183], v[150:151], off
	global_load_dwordx2 v[184:185], v[150:151], off offset:128
	global_load_dwordx2 v[186:187], v[150:151], off offset:256
	global_load_dwordx2 v[188:189], v[150:151], off offset:384
	global_load_dwordx2 v[190:191], v[150:151], off offset:1024
	global_load_dwordx2 v[192:193], v[150:151], off offset:1152
	global_load_dwordx2 v[194:195], v[150:151], off offset:1280
	global_load_dwordx2 v[196:197], v[150:151], off offset:1408
	s_and_b64 vcc, exec, s[10:11]
	s_cbranch_vccz .LBB0_1903
	s_barrier

; #define PG8_STAGE(bufoff, gbase, voff) do { _Pragma("unroll") for (int _i = 0; _i < 2; ++_i) \
;         __builtin_amdgcn_global_load_lds((const unsigned*)((const char*)(gbase) + (voff)[_i]), (PG8_LAS unsigned*)(lds + (bufoff) + ldsw + _i * 8192), 16, 0, 0); } while (0)
; #define PG8_LDA(dst, b, h) do { _Pragma("unroll") for (int m = 0; m < 4; ++m) _Pragma("unroll") for (int k = 0; k < 2; ++k) dst[m][k] = *(const PG8_LAS bf16x8*)(lds + PG8_SA(b, h) + aoff + m * 2048 + k * 1024); } while (0)
; #define PG8_LDB(dst, b, h) do { _Pragma("unroll") for (int n = 0; n < 2; ++n) _Pragma("unroll") for (int k = 0; k < 2; ++k) dst[n][k] = *(const PG8_LAS bf16x8*)(lds + PG8_SB(b, h) + boff + n * 2048 + k * 1024); } while (0)
; #define PG8_MMA(ai, bj, At, Bt) do { __builtin_amdgcn_s_setprio(1); _Pragma("unroll") for (int m = 0; m < 4; ++m) _Pragma("unroll") for (int n = 0; n < 2; ++n) _Pragma("unroll") for (int k = 0; k < 2; ++k) \
;         acc[ai][bj][m][n] = __builtin_amdgcn_mfma_f32_16x16x32_bf16(Bt[n][k], At[m][k], acc[ai][bj][m][n], 0, 0, 0); __builtin_amdgcn_s_setprio(0); } while (0)
; #define PG8_BAR __builtin_amdgcn_s_barrier()
; template <class Epi, class Sched, bool ALIGN_EPI = false, bool SP2 = false>
; __device__ __forceinline__ void gemm_phase(PG8_LAS unsigned char* lds, const Gemm g, const Sched& S, const Epi& E) {
;     ...
;         const bool has_next = S.next(ui + 1, nxt);
;         const char* nA = has_next ? (const char*)g.A + (size_t)nxt.pm * tstep : cA; const char* nB = has_next ? (const char*)g.Bt + (size_t)nxt.pn * tstep : cB;
;         for (int t = 0; t < nt; t += 2) {
;             const bool last = (t == nt - 2);
;             const char* a1 = cA + (size_t)(t + 1) * kstep;
;             const char* a2 = last ? nA : cA + (size_t)(t + 2) * kstep; const char* b2 = last ? nB : cB + (size_t)(t + 2) * kstep;
;             const char* a3 = a2 + kstep; const char* b3 = b2 + kstep;
;             if (last && has_next) S.a_ready(nxt);
;             if constexpr (SP2) {
;             PG8_LDB(B0, 0, 0); PG8_LDB(B1, 0, 1); PG8_SCHED; PG8_LDA(At, 0, 0); PG8_STAGE(PG8_SA(1, 1), a1 + hstep, voffA);
;             PG8_WAIT_V(8); PG8_WAIT_L(0); PG8_BAR; PG8_MMA(0, 0, At, B0); PG8_MMA(0, 1, At, B1); PG8_BAR; PG8_SCHED;
;             PG8_LDA(At, 0, 1); PG8_STAGE(PG8_SB(0, 0), b2, voffB); PG8_STAGE(PG8_SB(0, 1), b2 + hstep, voffB); PG8_STAGE(PG8_SA(0, 0), a2, voffA);
.LBB0_1977:
	s_add_u32 s53, s28, 0x100
	s_addc_u32 s54, s29, 0
	s_mov_b32 s55, -2
	s_waitcnt lgkmcnt(0)
	ds_read_b128 v[144:147], v151
	ds_read_b128 v[156:159], v151 offset:1024
	ds_read_b128 v[160:163], v151 offset:2048
	ds_read_b128 v[164:167], v151 offset:3072
	ds_read_b128 v[168:171], v152
	ds_read_b128 v[172:175], v152 offset:1024
	ds_read_b128 v[176:179], v152 offset:2048
	ds_read_b128 v[180:183], v152 offset:3072
	s_add_u32 s28, s26, 0x100
	s_addc_u32 s29, s27, 0
	s_cmp_eq_u32 s55, 40
	s_cselect_b32 s39, s1, s29
	s_cselect_b32 s38, s0, s28
	s_cselect_b32 s37, s25, s54
	s_cselect_b32 s36, s24, s53
	v_lshl_add_u64 v[218:219], s[26:27], 0, v[136:137]
	s_add_i32 m0, s33, 0xc000
	ds_read_b128 v[184:187], v153
	ds_read_b128 v[188:191], v153 offset:1024
	ds_read_b128 v[192:195], v153 offset:2048
	ds_read_b128 v[196:199], v153 offset:3072
	ds_read_b128 v[200:203], v153 offset:4096
	ds_read_b128 v[206:209], v153 offset:5120
	ds_read_b128 v[210:213], v153 offset:6144
	ds_read_b128 v[214:217], v153 offset:7168
	global_load_lds_dwordx4 v[218:219], off
	v_lshl_add_u64 v[218:219], s[26:27], 0, v[138:139]
	s_add_i32 m0, s33, 0xe000
	s_nop 0
	global_load_lds_dwordx4 v[218:219], off
	s_waitcnt vmcnt(8)
	s_waitcnt lgkmcnt(0)
	s_barrier
	s_setprio 1
	s_waitcnt lgkmcnt(0)
	v_mfma_f32_16x16x32_bf16 v[124:127], v[144:147], v[184:187], 0
	v_mfma_f32_16x16x32_bf16 v[120:123], v[160:163], v[184:187], 0
	v_mfma_f32_16x16x32_bf16 v[108:111], v[144:147], v[192:195], 0
	v_mfma_f32_16x16x32_bf16 v[104:107], v[160:163], v[192:195], 0
	v_mfma_f32_16x16x32_bf16 v[92:95], v[144:147], v[200:203], 0
	v_mfma_f32_16x16x32_bf16 v[88:91], v[160:163], v[200:203], 0
	v_mfma_f32_16x16x32_bf16 v[76:79], v[144:147], v[210:213], 0
	v_mfma_f32_16x16x32_bf16 v[72:75], v[160:163], v[210:213], 0
	v_mfma_f32_16x16x32_bf16 v[124:127], v[156:159], v[188:191], v[124:127]
	v_mfma_f32_16x16x32_bf16 v[120:123], v[164:167], v[188:191], v[120:123]
	v_mfma_f32_16x16x32_bf16 v[108:111], v[156:159], v[196:199], v[108:111]
	v_mfma_f32_16x16x32_bf16 v[104:107], v[164:167], v[196:199], v[104:107]
	v_mfma_f32_16x16x32_bf16 v[92:95], v[156:159], v[206:209], v[92:95]
	v_mfma_f32_16x16x32_bf16 v[88:91], v[164:167], v[206:209], v[88:91]
	v_mfma_f32_16x16x32_bf16 v[76:79], v[156:159], v[214:217], v[76:79]
	v_mfma_f32_16x16x32_bf16 v[72:75], v[164:167], v[214:217], v[72:75]
	s_setprio 0
	s_setprio 1
	v_mfma_f32_16x16x32_bf16 v[116:119], v[168:171], v[184:187], 0
	v_mfma_f32_16x16x32_bf16 v[112:115], v[176:179], v[184:187], 0
	v_mfma_f32_16x16x32_bf16 v[100:103], v[168:171], v[192:195], 0
	v_mfma_f32_16x16x32_bf16 v[96:99], v[176:179], v[192:195], 0
	v_mfma_f32_16x16x32_bf16 v[84:87], v[168:171], v[200:203], 0
	v_mfma_f32_16x16x32_bf16 v[80:83], v[176:179], v[200:203], 0
	v_mfma_f32_16x16x32_bf16 v[68:71], v[168:171], v[210:213], 0
	v_mfma_f32_16x16x32_bf16 v[64:67], v[176:179], v[210:213], 0
	v_mfma_f32_16x16x32_bf16 v[116:119], v[172:175], v[188:191], v[116:119]
	v_mfma_f32_16x16x32_bf16 v[112:115], v[180:183], v[188:191], v[112:115]
	v_mfma_f32_16x16x32_bf16 v[100:103], v[172:175], v[196:199], v[100:103]
	v_mfma_f32_16x16x32_bf16 v[96:99], v[180:183], v[196:199], v[96:99]
	v_mfma_f32_16x16x32_bf16 v[84:87], v[172:175], v[206:209], v[84:87]
	v_mfma_f32_16x16x32_bf16 v[80:83], v[180:183], v[206:209], v[80:83]
	v_mfma_f32_16x16x32_bf16 v[68:71], v[172:175], v[214:217], v[68:71]
	v_mfma_f32_16x16x32_bf16 v[64:67], v[180:183], v[214:217], v[64:67]
	s_setprio 0
	s_barrier
	s_add_i32 s26, s45, s15
	v_lshl_add_u64 v[218:219], s[36:37], 0, v[130:131]
	s_mov_b32 m0, s26
	ds_read_b128 v[184:187], v153 offset:16384
	ds_read_b128 v[188:191], v153 offset:17408
	ds_read_b128 v[192:195], v153 offset:18432
	ds_read_b128 v[196:199], v153 offset:19456
	ds_read_b128 v[200:203], v153 offset:20480
	ds_read_b128 v[206:209], v153 offset:21504
	ds_read_b128 v[210:213], v153 offset:22528
	ds_read_b128 v[214:217], v153 offset:23552
	global_load_lds_dwordx4 v[218:219], off
	s_add_i32 m0, s26, 0x2000
	s_add_u32 s26, s36, 0xb0000
	v_lshl_add_u64 v[220:221], s[36:37], 0, v[134:135]
	s_addc_u32 s27, s37, 0
	s_add_i32 s56, s46, s15
	global_load_lds_dwordx4 v[220:221], off
	v_lshl_add_u64 v[222:223], s[26:27], 0, v[130:131]
	s_mov_b32 m0, s56
	v_lshl_add_u64 v[224:225], s[38:39], 0, v[132:133]
	global_load_lds_dwordx4 v[222:223], off
	v_lshl_add_u64 v[222:223], s[26:27], 0, v[134:135]
	s_add_i32 m0, s56, 0x2000
	s_nop 0
	global_load_lds_dwordx4 v[222:223], off
	s_waitcnt vmcnt(6)
	s_waitcnt lgkmcnt(0)
	s_barrier
; #define PG8_STAGE(bufoff, gbase, voff) do { _Pragma("unroll") for (int _i = 0; _i < 2; ++_i) \
;         __builtin_amdgcn_global_load_lds((const unsigned*)((const char*)(gbase) + (voff)[_i]), (PG8_LAS unsigned*)(lds + (bufoff) + ldsw + _i * 8192), 16, 0, 0); } while (0)
; #define PG8_LDA(dst, b, h) do { _Pragma("unroll") for (int m = 0; m < 4; ++m) _Pragma("unroll") for (int k = 0; k < 2; ++k) dst[m][k] = *(const PG8_LAS bf16x8*)(lds + PG8_SA(b, h) + aoff + m * 2048 + k * 1024); } while (0)
; #define PG8_LDB(dst, b, h) do { _Pragma("unroll") for (int n = 0; n < 2; ++n) _Pragma("unroll") for (int k = 0; k < 2; ++k) dst[n][k] = *(const PG8_LAS bf16x8*)(lds + PG8_SB(b, h) + boff + n * 2048 + k * 1024); } while (0)
; #define PG8_MMA(ai, bj, At, Bt) do { __builtin_amdgcn_s_setprio(1); _Pragma("unroll") for (int m = 0; m < 4; ++m) _Pragma("unroll") for (int n = 0; n < 2; ++n) _Pragma("unroll") for (int k = 0; k < 2; ++k) \
;         acc[ai][bj][m][n] = __builtin_amdgcn_mfma_f32_16x16x32_bf16(Bt[n][k], At[m][k], acc[ai][bj][m][n], 0, 0, 0); __builtin_amdgcn_s_setprio(0); } while (0)
; #define PG8_WAIT_V(n) asm volatile("s_waitcnt vmcnt(" #n ")" ::: "memory")
; #define PG8_WAIT_L(n) asm volatile("s_waitcnt lgkmcnt(" #n ")" ::: "memory")
; #define PG8_BAR __builtin_amdgcn_s_barrier()
; #define PG8_SCHED __builtin_amdgcn_sched_barrier(0)
; template <class Epi, class Sched, bool ALIGN_EPI = false, bool SP2 = false>
; __device__ __forceinline__ void gemm_phase(PG8_LAS unsigned char* lds, const Gemm g, const Sched& S, const Epi& E) {
;     ...
;             PG8_WAIT_V(8); PG8_WAIT_L(0); PG8_BAR; PG8_MMA(1, 0, At, B0); PG8_MMA(1, 1, At, B1); PG8_BAR; PG8_SCHED;
;             PG8_LDB(B0, 1, 0); PG8_LDB(B1, 1, 1); PG8_SCHED; PG8_LDA(At, 1, 0); PG8_STAGE(PG8_SA(0, 1), a2 + hstep, voffA);
;             PG8_WAIT_V(8); PG8_WAIT_L(0); PG8_BAR; PG8_MMA(0, 0, At, B0); PG8_MMA(0, 1, At, B1); PG8_BAR; PG8_SCHED;
	s_setprio 1
	s_waitcnt lgkmcnt(0)
	v_mfma_f32_16x16x32_bf16 v[60:63], v[144:147], v[184:187], 0
	v_mfma_f32_16x16x32_bf16 v[56:59], v[160:163], v[184:187], 0
	v_mfma_f32_16x16x32_bf16 v[44:47], v[144:147], v[192:195], 0
	v_mfma_f32_16x16x32_bf16 v[40:43], v[160:163], v[192:195], 0
	v_mfma_f32_16x16x32_bf16 v[28:31], v[144:147], v[200:203], 0
	v_mfma_f32_16x16x32_bf16 v[24:27], v[160:163], v[200:203], 0
	v_lshl_add_u64 v[222:223], s[38:39], 0, v[128:129]
	s_mov_b32 m0, s33
	s_nop 0
	global_load_lds_dwordx4 v[222:223], off
	v_mfma_f32_16x16x32_bf16 v[12:15], v[144:147], v[210:213], 0
	v_mfma_f32_16x16x32_bf16 v[8:11], v[160:163], v[210:213], 0
	v_mfma_f32_16x16x32_bf16 v[60:63], v[156:159], v[188:191], v[60:63]
	v_mfma_f32_16x16x32_bf16 v[56:59], v[164:167], v[188:191], v[56:59]
	v_mfma_f32_16x16x32_bf16 v[44:47], v[156:159], v[196:199], v[44:47]
	v_mfma_f32_16x16x32_bf16 v[40:43], v[164:167], v[196:199], v[40:43]
	v_mfma_f32_16x16x32_bf16 v[28:31], v[156:159], v[206:209], v[28:31]
	v_mfma_f32_16x16x32_bf16 v[24:27], v[164:167], v[206:209], v[24:27]
	v_mfma_f32_16x16x32_bf16 v[12:15], v[156:159], v[214:217], v[12:15]
	v_mfma_f32_16x16x32_bf16 v[8:11], v[164:167], v[214:217], v[8:11]
	s_setprio 0
	s_setprio 1
	v_mfma_f32_16x16x32_bf16 v[52:55], v[168:171], v[184:187], 0
	v_mfma_f32_16x16x32_bf16 v[48:51], v[176:179], v[184:187], 0
	s_mov_b32 m0, s34
	s_nop 0
	global_load_lds_dwordx4 v[224:225], off
	v_mfma_f32_16x16x32_bf16 v[36:39], v[168:171], v[192:195], 0
	v_mfma_f32_16x16x32_bf16 v[32:35], v[176:179], v[192:195], 0
	v_mfma_f32_16x16x32_bf16 v[20:23], v[168:171], v[200:203], 0
	v_mfma_f32_16x16x32_bf16 v[16:19], v[176:179], v[200:203], 0
	v_mfma_f32_16x16x32_bf16 v[4:7], v[168:171], v[210:213], 0
	v_mfma_f32_16x16x32_bf16 v[0:3], v[176:179], v[210:213], 0
	v_mfma_f32_16x16x32_bf16 v[52:55], v[172:175], v[188:191], v[52:55]
	v_mfma_f32_16x16x32_bf16 v[48:51], v[180:183], v[188:191], v[48:51]
	v_mfma_f32_16x16x32_bf16 v[36:39], v[172:175], v[196:199], v[36:39]
	v_mfma_f32_16x16x32_bf16 v[32:35], v[180:183], v[196:199], v[32:35]
	v_mfma_f32_16x16x32_bf16 v[20:23], v[172:175], v[206:209], v[20:23]
	v_mfma_f32_16x16x32_bf16 v[16:19], v[180:183], v[206:209], v[16:19]
	v_mfma_f32_16x16x32_bf16 v[4:7], v[172:175], v[214:217], v[4:7]
	v_mfma_f32_16x16x32_bf16 v[0:3], v[180:183], v[214:217], v[0:3]
	s_setprio 0
	s_barrier
	s_add_i32 s56, 0, 0x18000
	v_add_u32_e32 v155, s56, v149
	s_add_i32 s57, 0, 0x1c000
	ds_read_b128 v[144:147], v155
	ds_read_b128 v[156:159], v155 offset:1024
	ds_read_b128 v[160:163], v155 offset:2048
	ds_read_b128 v[164:167], v155 offset:3072
	v_add_u32_e32 v155, s57, v149
	ds_read_b128 v[168:171], v155
	ds_read_b128 v[172:175], v155 offset:1024
	ds_read_b128 v[176:179], v155 offset:2048
	ds_read_b128 v[180:183], v155 offset:3072
	s_add_u32 s26, s38, 0xb0000
	s_addc_u32 s27, s39, 0
	s_mov_b32 m0, s40
	v_lshl_add_u64 v[226:227], s[26:27], 0, v[128:129]
	ds_read_b128 v[184:187], v153 offset:32768
	ds_read_b128 v[188:191], v153 offset:33792
	ds_read_b128 v[192:195], v153 offset:34816
	ds_read_b128 v[196:199], v153 offset:35840
	ds_read_b128 v[200:203], v153 offset:36864
	ds_read_b128 v[206:209], v153 offset:37888
	ds_read_b128 v[210:213], v153 offset:38912
	ds_read_b128 v[214:217], v153 offset:39936
	global_load_lds_dwordx4 v[226:227], off
	v_lshl_add_u64 v[226:227], s[26:27], 0, v[132:133]
	s_mov_b32 m0, s41
	s_nop 0
	global_load_lds_dwordx4 v[226:227], off
	s_waitcnt vmcnt(8)
	s_waitcnt lgkmcnt(0)
	s_barrier
	s_setprio 1
	s_waitcnt lgkmcnt(0)
	v_mfma_f32_16x16x32_bf16 v[124:127], v[144:147], v[184:187], v[124:127]
	v_mfma_f32_16x16x32_bf16 v[120:123], v[160:163], v[184:187], v[120:123]
	v_mfma_f32_16x16x32_bf16 v[108:111], v[144:147], v[192:195], v[108:111]
	v_mfma_f32_16x16x32_bf16 v[104:107], v[160:163], v[192:195], v[104:107]
	v_mfma_f32_16x16x32_bf16 v[92:95], v[144:147], v[200:203], v[92:95]
	v_mfma_f32_16x16x32_bf16 v[88:91], v[160:163], v[200:203], v[88:91]
	v_mfma_f32_16x16x32_bf16 v[76:79], v[144:147], v[210:213], v[76:79]
	v_mfma_f32_16x16x32_bf16 v[72:75], v[160:163], v[210:213], v[72:75]
	v_mfma_f32_16x16x32_bf16 v[124:127], v[156:159], v[188:191], v[124:127]
	v_mfma_f32_16x16x32_bf16 v[120:123], v[164:167], v[188:191], v[120:123]
	v_mfma_f32_16x16x32_bf16 v[108:111], v[156:159], v[196:199], v[108:111]
	v_mfma_f32_16x16x32_bf16 v[104:107], v[164:167], v[196:199], v[104:107]
	v_mfma_f32_16x16x32_bf16 v[92:95], v[156:159], v[206:209], v[92:95]
	v_mfma_f32_16x16x32_bf16 v[88:91], v[164:167], v[206:209], v[88:91]
	v_mfma_f32_16x16x32_bf16 v[76:79], v[156:159], v[214:217], v[76:79]
	v_mfma_f32_16x16x32_bf16 v[72:75], v[164:167], v[214:217], v[72:75]
	s_setprio 0
	s_setprio 1
	v_mfma_f32_16x16x32_bf16 v[116:119], v[168:171], v[184:187], v[116:119]
	v_mfma_f32_16x16x32_bf16 v[112:115], v[176:179], v[184:187], v[112:115]
	v_mfma_f32_16x16x32_bf16 v[100:103], v[168:171], v[192:195], v[100:103]
	v_mfma_f32_16x16x32_bf16 v[96:99], v[176:179], v[192:195], v[96:99]
	v_mfma_f32_16x16x32_bf16 v[84:87], v[168:171], v[200:203], v[84:87]
	v_mfma_f32_16x16x32_bf16 v[80:83], v[176:179], v[200:203], v[80:83]
	v_mfma_f32_16x16x32_bf16 v[68:71], v[168:171], v[210:213], v[68:71]
	v_mfma_f32_16x16x32_bf16 v[64:67], v[176:179], v[210:213], v[64:67]
	v_mfma_f32_16x16x32_bf16 v[116:119], v[172:175], v[188:191], v[116:119]
	v_mfma_f32_16x16x32_bf16 v[112:115], v[180:183], v[188:191], v[112:115]
	v_mfma_f32_16x16x32_bf16 v[100:103], v[172:175], v[196:199], v[100:103]
	v_mfma_f32_16x16x32_bf16 v[96:99], v[180:183], v[196:199], v[96:99]
	v_mfma_f32_16x16x32_bf16 v[84:87], v[172:175], v[206:209], v[84:87]
	v_mfma_f32_16x16x32_bf16 v[80:83], v[180:183], v[206:209], v[80:83]
	v_mfma_f32_16x16x32_bf16 v[68:71], v[172:175], v[214:217], v[68:71]
	v_mfma_f32_16x16x32_bf16 v[64:67], v[180:183], v[214:217], v[64:67]
	s_setprio 0
	s_barrier
; #define PG8_STAGE(bufoff, gbase, voff) do { _Pragma("unroll") for (int _i = 0; _i < 2; ++_i) \
;         __builtin_amdgcn_global_load_lds((const unsigned*)((const char*)(gbase) + (voff)[_i]), (PG8_LAS unsigned*)(lds + (bufoff) + ldsw + _i * 8192), 16, 0, 0); } while (0)
; #define PG8_LDA(dst, b, h) do { _Pragma("unroll") for (int m = 0; m < 4; ++m) _Pragma("unroll") for (int k = 0; k < 2; ++k) dst[m][k] = *(const PG8_LAS bf16x8*)(lds + PG8_SA(b, h) + aoff + m * 2048 + k * 1024); } while (0)
; #define PG8_LDB(dst, b, h) do { _Pragma("unroll") for (int n = 0; n < 2; ++n) _Pragma("unroll") for (int k = 0; k < 2; ++k) dst[n][k] = *(const PG8_LAS bf16x8*)(lds + PG8_SB(b, h) + boff + n * 2048 + k * 1024); } while (0)
; template <class Epi, class Sched, bool ALIGN_EPI = false, bool SP2 = false>
; __device__ __forceinline__ void gemm_phase(PG8_LAS unsigned char* lds, const Gemm g, const Sched& S, const Epi& E) {
;     ...
;         for (int t = 0; t < nt; t += 2) {
;             const bool last = (t == nt - 2);
;             const char* a1 = cA + (size_t)(t + 1) * kstep;
;             const char* a2 = last ? nA : cA + (size_t)(t + 2) * kstep; const char* b2 = last ? nB : cB + (size_t)(t + 2) * kstep;
;             const char* a3 = a2 + kstep; const char* b3 = b2 + kstep;
;             if (last && has_next) S.a_ready(nxt);
;             if constexpr (SP2) {
;             PG8_LDB(B0, 0, 0); PG8_LDB(B1, 0, 1); PG8_SCHED; PG8_LDA(At, 0, 0); PG8_STAGE(PG8_SA(1, 1), a1 + hstep, voffA);
;             PG8_WAIT_V(8); PG8_WAIT_L(0); PG8_BAR; PG8_MMA(0, 0, At, B0); PG8_MMA(0, 1, At, B1); PG8_BAR; PG8_SCHED;
;             PG8_LDA(At, 0, 1); PG8_STAGE(PG8_SB(0, 0), b2, voffB); PG8_STAGE(PG8_SB(0, 1), b2 + hstep, voffB); PG8_STAGE(PG8_SA(0, 0), a2, voffA);
;             PG8_WAIT_V(8); PG8_WAIT_L(0); PG8_BAR; PG8_MMA(1, 0, At, B0); PG8_MMA(1, 1, At, B1); PG8_BAR; PG8_SCHED;
;             PG8_LDB(B0, 1, 0); PG8_LDB(B1, 1, 1); PG8_SCHED; PG8_LDA(At, 1, 0); PG8_STAGE(PG8_SA(0, 1), a2 + hstep, voffA);
;             PG8_WAIT_V(8); PG8_WAIT_L(0); PG8_BAR; PG8_MMA(0, 0, At, B0); PG8_MMA(0, 1, At, B1); PG8_BAR; PG8_SCHED;
;             PG8_LDA(At, 1, 1); PG8_STAGE(PG8_SB(1, 0), b3, voffB); PG8_STAGE(PG8_SB(1, 1), b3 + hstep, voffB); PG8_STAGE(PG8_SA(1, 0), a3, voffA);
;             PG8_WAIT_V(8); PG8_WAIT_L(0); PG8_BAR; PG8_MMA(1, 0, At, B0); PG8_MMA(1, 1, At, B1); PG8_BAR; PG8_SCHED;
	s_add_i32 s26, s56, s15
	v_lshl_add_u64 v[218:219], v[218:219], 0, s[12:13]
	s_mov_b32 m0, s26
	ds_read_b128 v[184:187], v153 offset:49152
	ds_read_b128 v[188:191], v153 offset:50176
	ds_read_b128 v[192:195], v153 offset:51200
	ds_read_b128 v[196:199], v153 offset:52224
	ds_read_b128 v[200:203], v153 offset:53248
	ds_read_b128 v[206:209], v153 offset:54272
	ds_read_b128 v[210:213], v153 offset:55296
	ds_read_b128 v[214:217], v153 offset:56320
	global_load_lds_dwordx4 v[218:219], off
	s_add_i32 m0, s26, 0x2000
	s_add_u32 s26, s36, 0xb0080
	v_lshl_add_u64 v[218:219], v[220:221], 0, s[12:13]
	s_addc_u32 s27, s37, 0
	s_add_i32 s36, s57, s15
	global_load_lds_dwordx4 v[218:219], off
	v_lshl_add_u64 v[218:219], s[26:27], 0, v[130:131]
	s_mov_b32 m0, s36
	s_nop 0
	global_load_lds_dwordx4 v[218:219], off
	v_lshl_add_u64 v[218:219], s[26:27], 0, v[134:135]
	s_add_i32 m0, s36, 0x2000
	s_nop 0
	global_load_lds_dwordx4 v[218:219], off
	s_waitcnt vmcnt(6)
	s_waitcnt lgkmcnt(0)
	s_barrier
	s_setprio 1
	s_waitcnt lgkmcnt(0)
	v_mfma_f32_16x16x32_bf16 v[60:63], v[144:147], v[184:187], v[60:63]
	v_mfma_f32_16x16x32_bf16 v[56:59], v[160:163], v[184:187], v[56:59]
	v_mfma_f32_16x16x32_bf16 v[44:47], v[144:147], v[192:195], v[44:47]
	v_mfma_f32_16x16x32_bf16 v[40:43], v[160:163], v[192:195], v[40:43]
	v_mfma_f32_16x16x32_bf16 v[28:31], v[144:147], v[200:203], v[28:31]
	v_mfma_f32_16x16x32_bf16 v[24:27], v[160:163], v[200:203], v[24:27]
	v_lshl_add_u64 v[218:219], v[222:223], 0, s[12:13]
	s_mov_b32 m0, s43
	s_nop 0
	global_load_lds_dwordx4 v[218:219], off
	v_mfma_f32_16x16x32_bf16 v[12:15], v[144:147], v[210:213], v[12:15]
	v_mfma_f32_16x16x32_bf16 v[8:11], v[160:163], v[210:213], v[8:11]
	v_mfma_f32_16x16x32_bf16 v[60:63], v[156:159], v[188:191], v[60:63]
	v_mfma_f32_16x16x32_bf16 v[56:59], v[164:167], v[188:191], v[56:59]
	v_mfma_f32_16x16x32_bf16 v[44:47], v[156:159], v[196:199], v[44:47]
	v_mfma_f32_16x16x32_bf16 v[40:43], v[164:167], v[196:199], v[40:43]
	v_mfma_f32_16x16x32_bf16 v[28:31], v[156:159], v[206:209], v[28:31]
	v_mfma_f32_16x16x32_bf16 v[24:27], v[164:167], v[206:209], v[24:27]
	v_mfma_f32_16x16x32_bf16 v[12:15], v[156:159], v[214:217], v[12:15]
	v_mfma_f32_16x16x32_bf16 v[8:11], v[164:167], v[214:217], v[8:11]
	s_setprio 0
	s_setprio 1
	v_mfma_f32_16x16x32_bf16 v[52:55], v[168:171], v[184:187], v[52:55]
	v_mfma_f32_16x16x32_bf16 v[48:51], v[176:179], v[184:187], v[48:51]
	v_lshl_add_u64 v[218:219], v[224:225], 0, s[12:13]
	s_mov_b32 m0, s44
	s_nop 0
	global_load_lds_dwordx4 v[218:219], off
	v_mfma_f32_16x16x32_bf16 v[36:39], v[168:171], v[192:195], v[36:39]
	v_mfma_f32_16x16x32_bf16 v[32:35], v[176:179], v[192:195], v[32:35]
	v_mfma_f32_16x16x32_bf16 v[20:23], v[168:171], v[200:203], v[20:23]
	v_mfma_f32_16x16x32_bf16 v[16:19], v[176:179], v[200:203], v[16:19]
	v_mfma_f32_16x16x32_bf16 v[4:7], v[168:171], v[210:213], v[4:7]
	v_mfma_f32_16x16x32_bf16 v[0:3], v[176:179], v[210:213], v[0:3]
	v_mfma_f32_16x16x32_bf16 v[52:55], v[172:175], v[188:191], v[52:55]
	v_mfma_f32_16x16x32_bf16 v[48:51], v[180:183], v[188:191], v[48:51]
	v_mfma_f32_16x16x32_bf16 v[36:39], v[172:175], v[196:199], v[36:39]
	v_mfma_f32_16x16x32_bf16 v[32:35], v[180:183], v[196:199], v[32:35]
	v_mfma_f32_16x16x32_bf16 v[20:23], v[172:175], v[206:209], v[20:23]
	v_mfma_f32_16x16x32_bf16 v[16:19], v[180:183], v[206:209], v[16:19]
	v_mfma_f32_16x16x32_bf16 v[4:7], v[172:175], v[214:217], v[4:7]
	v_mfma_f32_16x16x32_bf16 v[0:3], v[180:183], v[214:217], v[0:3]
	s_setprio 0
	s_barrier
	s_add_i32 s55, s55, 2
	s_add_u32 s53, s53, 0x100
	s_addc_u32 s54, s54, 0
	s_mov_b64 s[26:27], s[28:29]
.LBB0_1978:
	ds_read_b128 v[144:147], v151
	ds_read_b128 v[156:159], v151 offset:1024
	ds_read_b128 v[160:163], v151 offset:2048
	ds_read_b128 v[164:167], v151 offset:3072
	ds_read_b128 v[168:171], v152
	ds_read_b128 v[172:175], v152 offset:1024
	ds_read_b128 v[176:179], v152 offset:2048
	ds_read_b128 v[180:183], v152 offset:3072
	s_add_u32 s28, s26, 0x100
	s_addc_u32 s29, s27, 0
	s_cmp_eq_u32 s55, 40
	s_cselect_b32 s39, s1, s29
	s_cselect_b32 s38, s0, s28
	s_cselect_b32 s37, s25, s54
	s_cselect_b32 s36, s24, s53
	v_lshl_add_u64 v[218:219], s[26:27], 0, v[136:137]
	s_add_i32 m0, s33, 0xc000
	ds_read_b128 v[184:187], v153
	ds_read_b128 v[188:191], v153 offset:1024
	ds_read_b128 v[192:195], v153 offset:2048
	ds_read_b128 v[196:199], v153 offset:3072
	ds_read_b128 v[200:203], v153 offset:4096
	ds_read_b128 v[206:209], v153 offset:5120
	ds_read_b128 v[210:213], v153 offset:6144
	ds_read_b128 v[214:217], v153 offset:7168
	global_load_lds_dwordx4 v[218:219], off
	v_lshl_add_u64 v[218:219], s[26:27], 0, v[138:139]
	s_add_i32 m0, s33, 0xe000
	s_nop 0
	global_load_lds_dwordx4 v[218:219], off
	s_waitcnt vmcnt(8)
	s_waitcnt lgkmcnt(0)
	s_barrier
; #define PG8_STAGE(bufoff, gbase, voff) do { _Pragma("unroll") for (int _i = 0; _i < 2; ++_i) \
;         __builtin_amdgcn_global_load_lds((const unsigned*)((const char*)(gbase) + (voff)[_i]), (PG8_LAS unsigned*)(lds + (bufoff) + ldsw + _i * 8192), 16, 0, 0); } while (0)
; #define PG8_LDA(dst, b, h) do { _Pragma("unroll") for (int m = 0; m < 4; ++m) _Pragma("unroll") for (int k = 0; k < 2; ++k) dst[m][k] = *(const PG8_LAS bf16x8*)(lds + PG8_SA(b, h) + aoff + m * 2048 + k * 1024); } while (0)
; #define PG8_LDB(dst, b, h) do { _Pragma("unroll") for (int n = 0; n < 2; ++n) _Pragma("unroll") for (int k = 0; k < 2; ++k) dst[n][k] = *(const PG8_LAS bf16x8*)(lds + PG8_SB(b, h) + boff + n * 2048 + k * 1024); } while (0)
; #define PG8_MMA(ai, bj, At, Bt) do { __builtin_amdgcn_s_setprio(1); _Pragma("unroll") for (int m = 0; m < 4; ++m) _Pragma("unroll") for (int n = 0; n < 2; ++n) _Pragma("unroll") for (int k = 0; k < 2; ++k) \
;         acc[ai][bj][m][n] = __builtin_amdgcn_mfma_f32_16x16x32_bf16(Bt[n][k], At[m][k], acc[ai][bj][m][n], 0, 0, 0); __builtin_amdgcn_s_setprio(0); } while (0)
; #define PG8_WAIT_V(n) asm volatile("s_waitcnt vmcnt(" #n ")" ::: "memory")
; #define PG8_WAIT_L(n) asm volatile("s_waitcnt lgkmcnt(" #n ")" ::: "memory")
; #define PG8_BAR __builtin_amdgcn_s_barrier()
; #define PG8_SCHED __builtin_amdgcn_sched_barrier(0)
; template <class Epi, class Sched, bool ALIGN_EPI = false, bool SP2 = false>
; __device__ __forceinline__ void gemm_phase(PG8_LAS unsigned char* lds, const Gemm g, const Sched& S, const Epi& E) {
;     ...
;             PG8_LDB(B0, 0, 0); PG8_LDB(B1, 0, 1); PG8_SCHED; PG8_LDA(At, 0, 0); PG8_STAGE(PG8_SA(1, 1), a1 + hstep, voffA);
;             PG8_WAIT_V(8); PG8_WAIT_L(0); PG8_BAR; PG8_MMA(0, 0, At, B0); PG8_MMA(0, 1, At, B1); PG8_BAR; PG8_SCHED;
;             PG8_LDA(At, 0, 1); PG8_STAGE(PG8_SB(0, 0), b2, voffB); PG8_STAGE(PG8_SB(0, 1), b2 + hstep, voffB); PG8_STAGE(PG8_SA(0, 0), a2, voffA);
;             PG8_WAIT_V(8); PG8_WAIT_L(0); PG8_BAR; PG8_MMA(1, 0, At, B0); PG8_MMA(1, 1, At, B1); PG8_BAR; PG8_SCHED;
	s_setprio 1
	s_waitcnt lgkmcnt(0)
	v_mfma_f32_16x16x32_bf16 v[124:127], v[144:147], v[184:187], v[124:127]
	v_mfma_f32_16x16x32_bf16 v[120:123], v[160:163], v[184:187], v[120:123]
	v_mfma_f32_16x16x32_bf16 v[108:111], v[144:147], v[192:195], v[108:111]
	v_mfma_f32_16x16x32_bf16 v[104:107], v[160:163], v[192:195], v[104:107]
	v_mfma_f32_16x16x32_bf16 v[92:95], v[144:147], v[200:203], v[92:95]
	v_mfma_f32_16x16x32_bf16 v[88:91], v[160:163], v[200:203], v[88:91]
	v_mfma_f32_16x16x32_bf16 v[76:79], v[144:147], v[210:213], v[76:79]
	v_mfma_f32_16x16x32_bf16 v[72:75], v[160:163], v[210:213], v[72:75]
	v_mfma_f32_16x16x32_bf16 v[124:127], v[156:159], v[188:191], v[124:127]
	v_mfma_f32_16x16x32_bf16 v[120:123], v[164:167], v[188:191], v[120:123]
	v_mfma_f32_16x16x32_bf16 v[108:111], v[156:159], v[196:199], v[108:111]
	v_mfma_f32_16x16x32_bf16 v[104:107], v[164:167], v[196:199], v[104:107]
	v_mfma_f32_16x16x32_bf16 v[92:95], v[156:159], v[206:209], v[92:95]
	v_mfma_f32_16x16x32_bf16 v[88:91], v[164:167], v[206:209], v[88:91]
	v_mfma_f32_16x16x32_bf16 v[76:79], v[156:159], v[214:217], v[76:79]
	v_mfma_f32_16x16x32_bf16 v[72:75], v[164:167], v[214:217], v[72:75]
	s_setprio 0
	s_setprio 1
	v_mfma_f32_16x16x32_bf16 v[116:119], v[168:171], v[184:187], v[116:119]
	v_mfma_f32_16x16x32_bf16 v[112:115], v[176:179], v[184:187], v[112:115]
	v_mfma_f32_16x16x32_bf16 v[100:103], v[168:171], v[192:195], v[100:103]
	v_mfma_f32_16x16x32_bf16 v[96:99], v[176:179], v[192:195], v[96:99]
	v_mfma_f32_16x16x32_bf16 v[84:87], v[168:171], v[200:203], v[84:87]
	v_mfma_f32_16x16x32_bf16 v[80:83], v[176:179], v[200:203], v[80:83]
	v_mfma_f32_16x16x32_bf16 v[68:71], v[168:171], v[210:213], v[68:71]
	v_mfma_f32_16x16x32_bf16 v[64:67], v[176:179], v[210:213], v[64:67]
	v_mfma_f32_16x16x32_bf16 v[116:119], v[172:175], v[188:191], v[116:119]
	v_mfma_f32_16x16x32_bf16 v[112:115], v[180:183], v[188:191], v[112:115]
	v_mfma_f32_16x16x32_bf16 v[100:103], v[172:175], v[196:199], v[100:103]
	v_mfma_f32_16x16x32_bf16 v[96:99], v[180:183], v[196:199], v[96:99]
	v_mfma_f32_16x16x32_bf16 v[84:87], v[172:175], v[206:209], v[84:87]
	v_mfma_f32_16x16x32_bf16 v[80:83], v[180:183], v[206:209], v[80:83]
	v_mfma_f32_16x16x32_bf16 v[68:71], v[172:175], v[214:217], v[68:71]
	v_mfma_f32_16x16x32_bf16 v[64:67], v[180:183], v[214:217], v[64:67]
	s_setprio 0
	s_barrier
	s_add_i32 s26, s45, s15
	v_lshl_add_u64 v[218:219], s[36:37], 0, v[130:131]
	s_mov_b32 m0, s26
	ds_read_b128 v[184:187], v153 offset:16384
	ds_read_b128 v[188:191], v153 offset:17408
	ds_read_b128 v[192:195], v153 offset:18432
	ds_read_b128 v[196:199], v153 offset:19456
	ds_read_b128 v[200:203], v153 offset:20480
	ds_read_b128 v[206:209], v153 offset:21504
	ds_read_b128 v[210:213], v153 offset:22528
	ds_read_b128 v[214:217], v153 offset:23552
	global_load_lds_dwordx4 v[218:219], off
	s_add_i32 m0, s26, 0x2000
	s_add_u32 s26, s36, 0xb0000
	v_lshl_add_u64 v[220:221], s[36:37], 0, v[134:135]
	s_addc_u32 s27, s37, 0
	s_add_i32 s56, s46, s15
	global_load_lds_dwordx4 v[220:221], off
	v_lshl_add_u64 v[222:223], s[26:27], 0, v[130:131]
	s_mov_b32 m0, s56
	v_lshl_add_u64 v[224:225], s[38:39], 0, v[132:133]
	global_load_lds_dwordx4 v[222:223], off
	v_lshl_add_u64 v[222:223], s[26:27], 0, v[134:135]
	s_add_i32 m0, s56, 0x2000
	s_nop 0
	global_load_lds_dwordx4 v[222:223], off
	s_waitcnt vmcnt(6)
	s_waitcnt lgkmcnt(0)
	s_barrier
	s_setprio 1
	s_waitcnt lgkmcnt(0)
	v_mfma_f32_16x16x32_bf16 v[60:63], v[144:147], v[184:187], v[60:63]
	v_mfma_f32_16x16x32_bf16 v[56:59], v[160:163], v[184:187], v[56:59]
	v_mfma_f32_16x16x32_bf16 v[44:47], v[144:147], v[192:195], v[44:47]
	v_mfma_f32_16x16x32_bf16 v[40:43], v[160:163], v[192:195], v[40:43]
	v_mfma_f32_16x16x32_bf16 v[28:31], v[144:147], v[200:203], v[28:31]
	v_mfma_f32_16x16x32_bf16 v[24:27], v[160:163], v[200:203], v[24:27]
	v_lshl_add_u64 v[222:223], s[38:39], 0, v[128:129]
	s_mov_b32 m0, s33
	s_nop 0
	global_load_lds_dwordx4 v[222:223], off
	v_mfma_f32_16x16x32_bf16 v[12:15], v[144:147], v[210:213], v[12:15]
	v_mfma_f32_16x16x32_bf16 v[8:11], v[160:163], v[210:213], v[8:11]
	v_mfma_f32_16x16x32_bf16 v[60:63], v[156:159], v[188:191], v[60:63]
	v_mfma_f32_16x16x32_bf16 v[56:59], v[164:167], v[188:191], v[56:59]
	v_mfma_f32_16x16x32_bf16 v[44:47], v[156:159], v[196:199], v[44:47]
	v_mfma_f32_16x16x32_bf16 v[40:43], v[164:167], v[196:199], v[40:43]
	v_mfma_f32_16x16x32_bf16 v[28:31], v[156:159], v[206:209], v[28:31]
	v_mfma_f32_16x16x32_bf16 v[24:27], v[164:167], v[206:209], v[24:27]
	v_mfma_f32_16x16x32_bf16 v[12:15], v[156:159], v[214:217], v[12:15]
	v_mfma_f32_16x16x32_bf16 v[8:11], v[164:167], v[214:217], v[8:11]
	s_setprio 0
	s_setprio 1
	v_mfma_f32_16x16x32_bf16 v[52:55], v[168:171], v[184:187], v[52:55]
	v_mfma_f32_16x16x32_bf16 v[48:51], v[176:179], v[184:187], v[48:51]
	s_mov_b32 m0, s34
	s_nop 0
	global_load_lds_dwordx4 v[224:225], off
	v_mfma_f32_16x16x32_bf16 v[36:39], v[168:171], v[192:195], v[36:39]
	v_mfma_f32_16x16x32_bf16 v[32:35], v[176:179], v[192:195], v[32:35]
	v_mfma_f32_16x16x32_bf16 v[20:23], v[168:171], v[200:203], v[20:23]
	v_mfma_f32_16x16x32_bf16 v[16:19], v[176:179], v[200:203], v[16:19]
	v_mfma_f32_16x16x32_bf16 v[4:7], v[168:171], v[210:213], v[4:7]
	v_mfma_f32_16x16x32_bf16 v[0:3], v[176:179], v[210:213], v[0:3]
	v_mfma_f32_16x16x32_bf16 v[52:55], v[172:175], v[188:191], v[52:55]
	v_mfma_f32_16x16x32_bf16 v[48:51], v[180:183], v[188:191], v[48:51]
	v_mfma_f32_16x16x32_bf16 v[36:39], v[172:175], v[196:199], v[36:39]
	v_mfma_f32_16x16x32_bf16 v[32:35], v[180:183], v[196:199], v[32:35]
	v_mfma_f32_16x16x32_bf16 v[20:23], v[172:175], v[206:209], v[20:23]
	v_mfma_f32_16x16x32_bf16 v[16:19], v[180:183], v[206:209], v[16:19]
	v_mfma_f32_16x16x32_bf16 v[4:7], v[172:175], v[214:217], v[4:7]
	v_mfma_f32_16x16x32_bf16 v[0:3], v[180:183], v[214:217], v[0:3]
	s_setprio 0
	s_barrier
; #define PG8_STAGE(bufoff, gbase, voff) do { _Pragma("unroll") for (int _i = 0; _i < 2; ++_i) \
;         __builtin_amdgcn_global_load_lds((const unsigned*)((const char*)(gbase) + (voff)[_i]), (PG8_LAS unsigned*)(lds + (bufoff) + ldsw + _i * 8192), 16, 0, 0); } while (0)
; #define PG8_LDA(dst, b, h) do { _Pragma("unroll") for (int m = 0; m < 4; ++m) _Pragma("unroll") for (int k = 0; k < 2; ++k) dst[m][k] = *(const PG8_LAS bf16x8*)(lds + PG8_SA(b, h) + aoff + m * 2048 + k * 1024); } while (0)
; #define PG8_LDB(dst, b, h) do { _Pragma("unroll") for (int n = 0; n < 2; ++n) _Pragma("unroll") for (int k = 0; k < 2; ++k) dst[n][k] = *(const PG8_LAS bf16x8*)(lds + PG8_SB(b, h) + boff + n * 2048 + k * 1024); } while (0)
; #define PG8_MMA(ai, bj, At, Bt) do { __builtin_amdgcn_s_setprio(1); _Pragma("unroll") for (int m = 0; m < 4; ++m) _Pragma("unroll") for (int n = 0; n < 2; ++n) _Pragma("unroll") for (int k = 0; k < 2; ++k) \
;         acc[ai][bj][m][n] = __builtin_amdgcn_mfma_f32_16x16x32_bf16(Bt[n][k], At[m][k], acc[ai][bj][m][n], 0, 0, 0); __builtin_amdgcn_s_setprio(0); } while (0)
; #define PG8_WAIT_V(n) asm volatile("s_waitcnt vmcnt(" #n ")" ::: "memory")
; #define PG8_WAIT_L(n) asm volatile("s_waitcnt lgkmcnt(" #n ")" ::: "memory")
; #define PG8_BAR __builtin_amdgcn_s_barrier()
; #define PG8_SCHED __builtin_amdgcn_sched_barrier(0)
; template <class Epi, class Sched, bool ALIGN_EPI = false, bool SP2 = false>
; __device__ __forceinline__ void gemm_phase(PG8_LAS unsigned char* lds, const Gemm g, const Sched& S, const Epi& E) {
;     ...
;             PG8_LDB(B0, 1, 0); PG8_LDB(B1, 1, 1); PG8_SCHED; PG8_LDA(At, 1, 0); PG8_STAGE(PG8_SA(0, 1), a2 + hstep, voffA);
;             PG8_WAIT_V(8); PG8_WAIT_L(0); PG8_BAR; PG8_MMA(0, 0, At, B0); PG8_MMA(0, 1, At, B1); PG8_BAR; PG8_SCHED;
	s_add_i32 s56, 0, 0x18000
	v_add_u32_e32 v155, s56, v149
	s_add_i32 s57, 0, 0x1c000
	ds_read_b128 v[144:147], v155
	ds_read_b128 v[156:159], v155 offset:1024
	ds_read_b128 v[160:163], v155 offset:2048
	ds_read_b128 v[164:167], v155 offset:3072
	v_add_u32_e32 v155, s57, v149
	ds_read_b128 v[168:171], v155
	ds_read_b128 v[172:175], v155 offset:1024
	ds_read_b128 v[176:179], v155 offset:2048
	ds_read_b128 v[180:183], v155 offset:3072
	s_add_u32 s26, s38, 0xb0000
	s_addc_u32 s27, s39, 0
	s_mov_b32 m0, s40
	v_lshl_add_u64 v[226:227], s[26:27], 0, v[128:129]
	ds_read_b128 v[184:187], v153 offset:32768
	ds_read_b128 v[188:191], v153 offset:33792
	ds_read_b128 v[192:195], v153 offset:34816
	ds_read_b128 v[196:199], v153 offset:35840
	ds_read_b128 v[200:203], v153 offset:36864
	ds_read_b128 v[206:209], v153 offset:37888
	ds_read_b128 v[210:213], v153 offset:38912
	ds_read_b128 v[214:217], v153 offset:39936
	global_load_lds_dwordx4 v[226:227], off
	v_lshl_add_u64 v[226:227], s[26:27], 0, v[132:133]
	s_mov_b32 m0, s41
	s_nop 0
	global_load_lds_dwordx4 v[226:227], off
	s_waitcnt vmcnt(8)
	s_waitcnt lgkmcnt(0)
	s_barrier
	s_setprio 1
	s_waitcnt lgkmcnt(0)
	v_mfma_f32_16x16x32_bf16 v[124:127], v[144:147], v[184:187], v[124:127]
	v_mfma_f32_16x16x32_bf16 v[120:123], v[160:163], v[184:187], v[120:123]
	v_mfma_f32_16x16x32_bf16 v[108:111], v[144:147], v[192:195], v[108:111]
	v_mfma_f32_16x16x32_bf16 v[104:107], v[160:163], v[192:195], v[104:107]
	v_mfma_f32_16x16x32_bf16 v[92:95], v[144:147], v[200:203], v[92:95]
	v_mfma_f32_16x16x32_bf16 v[88:91], v[160:163], v[200:203], v[88:91]
	v_mfma_f32_16x16x32_bf16 v[76:79], v[144:147], v[210:213], v[76:79]
	v_mfma_f32_16x16x32_bf16 v[72:75], v[160:163], v[210:213], v[72:75]
	v_mfma_f32_16x16x32_bf16 v[124:127], v[156:159], v[188:191], v[124:127]
	v_mfma_f32_16x16x32_bf16 v[120:123], v[164:167], v[188:191], v[120:123]
	v_mfma_f32_16x16x32_bf16 v[108:111], v[156:159], v[196:199], v[108:111]
	v_mfma_f32_16x16x32_bf16 v[104:107], v[164:167], v[196:199], v[104:107]
	v_mfma_f32_16x16x32_bf16 v[92:95], v[156:159], v[206:209], v[92:95]
	v_mfma_f32_16x16x32_bf16 v[88:91], v[164:167], v[206:209], v[88:91]
	v_mfma_f32_16x16x32_bf16 v[76:79], v[156:159], v[214:217], v[76:79]
	v_mfma_f32_16x16x32_bf16 v[72:75], v[164:167], v[214:217], v[72:75]
	s_setprio 0
	s_setprio 1
	v_mfma_f32_16x16x32_bf16 v[116:119], v[168:171], v[184:187], v[116:119]
	v_mfma_f32_16x16x32_bf16 v[112:115], v[176:179], v[184:187], v[112:115]
	v_mfma_f32_16x16x32_bf16 v[100:103], v[168:171], v[192:195], v[100:103]
	v_mfma_f32_16x16x32_bf16 v[96:99], v[176:179], v[192:195], v[96:99]
	v_mfma_f32_16x16x32_bf16 v[84:87], v[168:171], v[200:203], v[84:87]
	v_mfma_f32_16x16x32_bf16 v[80:83], v[176:179], v[200:203], v[80:83]
	v_mfma_f32_16x16x32_bf16 v[68:71], v[168:171], v[210:213], v[68:71]
	v_mfma_f32_16x16x32_bf16 v[64:67], v[176:179], v[210:213], v[64:67]
	v_mfma_f32_16x16x32_bf16 v[116:119], v[172:175], v[188:191], v[116:119]
	v_mfma_f32_16x16x32_bf16 v[112:115], v[180:183], v[188:191], v[112:115]
	v_mfma_f32_16x16x32_bf16 v[100:103], v[172:175], v[196:199], v[100:103]
	v_mfma_f32_16x16x32_bf16 v[96:99], v[180:183], v[196:199], v[96:99]
	v_mfma_f32_16x16x32_bf16 v[84:87], v[172:175], v[206:209], v[84:87]
	v_mfma_f32_16x16x32_bf16 v[80:83], v[180:183], v[206:209], v[80:83]
	v_mfma_f32_16x16x32_bf16 v[68:71], v[172:175], v[214:217], v[68:71]
	v_mfma_f32_16x16x32_bf16 v[64:67], v[180:183], v[214:217], v[64:67]
	s_setprio 0
	s_barrier
; #define PG8_STAGE(bufoff, gbase, voff) do { _Pragma("unroll") for (int _i = 0; _i < 2; ++_i) \
;         __builtin_amdgcn_global_load_lds((const unsigned*)((const char*)(gbase) + (voff)[_i]), (PG8_LAS unsigned*)(lds + (bufoff) + ldsw + _i * 8192), 16, 0, 0); } while (0)
; #define PG8_LDA(dst, b, h) do { _Pragma("unroll") for (int m = 0; m < 4; ++m) _Pragma("unroll") for (int k = 0; k < 2; ++k) dst[m][k] = *(const PG8_LAS bf16x8*)(lds + PG8_SA(b, h) + aoff + m * 2048 + k * 1024); } while (0)
; #define PG8_MMA(ai, bj, At, Bt) do { __builtin_amdgcn_s_setprio(1); _Pragma("unroll") for (int m = 0; m < 4; ++m) _Pragma("unroll") for (int n = 0; n < 2; ++n) _Pragma("unroll") for (int k = 0; k < 2; ++k) \
;         acc[ai][bj][m][n] = __builtin_amdgcn_mfma_f32_16x16x32_bf16(Bt[n][k], At[m][k], acc[ai][bj][m][n], 0, 0, 0); __builtin_amdgcn_s_setprio(0); } while (0)
; #define PG8_WAIT_V(n) asm volatile("s_waitcnt vmcnt(" #n ")" ::: "memory")
; #define PG8_WAIT_L(n) asm volatile("s_waitcnt lgkmcnt(" #n ")" ::: "memory")
; #define PG8_BAR __builtin_amdgcn_s_barrier()
; #define PG8_SCHED __builtin_amdgcn_sched_barrier(0)
; template <class Epi, class Sched, bool ALIGN_EPI = false, bool SP2 = false>
; __device__ __forceinline__ void gemm_phase(PG8_LAS unsigned char* lds, const Gemm g, const Sched& S, const Epi& E) {
;     ...
;             PG8_LDA(At, 1, 1); PG8_STAGE(PG8_SB(1, 0), b3, voffB); PG8_STAGE(PG8_SB(1, 1), b3 + hstep, voffB); PG8_STAGE(PG8_SA(1, 0), a3, voffA);
;             PG8_WAIT_V(8); PG8_WAIT_L(0); PG8_BAR; PG8_MMA(1, 0, At, B0); PG8_MMA(1, 1, At, B1); PG8_BAR; PG8_SCHED;
;     ...
;         if constexpr (ALIGN_EPI) { if (wr == 0) PG8_BAR; }
	s_add_i32 s26, s56, s15
	v_lshl_add_u64 v[218:219], v[218:219], 0, s[12:13]
	s_mov_b32 m0, s26
	ds_read_b128 v[184:187], v153 offset:49152
	ds_read_b128 v[188:191], v153 offset:50176
	ds_read_b128 v[192:195], v153 offset:51200
	ds_read_b128 v[196:199], v153 offset:52224
	ds_read_b128 v[200:203], v153 offset:53248
	ds_read_b128 v[206:209], v153 offset:54272
	ds_read_b128 v[210:213], v153 offset:55296
	ds_read_b128 v[214:217], v153 offset:56320
	global_load_lds_dwordx4 v[218:219], off
	s_add_i32 m0, s26, 0x2000
	s_add_u32 s26, s36, 0xb0080
	v_lshl_add_u64 v[218:219], v[220:221], 0, s[12:13]
	s_addc_u32 s27, s37, 0
	s_add_i32 s36, s57, s15
	global_load_lds_dwordx4 v[218:219], off
	v_lshl_add_u64 v[218:219], s[26:27], 0, v[130:131]
	s_mov_b32 m0, s36
	s_nop 0
	global_load_lds_dwordx4 v[218:219], off
	v_lshl_add_u64 v[218:219], s[26:27], 0, v[134:135]
	s_add_i32 m0, s36, 0x2000
	s_nop 0
	global_load_lds_dwordx4 v[218:219], off
	s_waitcnt vmcnt(6)
	s_waitcnt lgkmcnt(0)
	s_barrier
	s_setprio 1
	s_waitcnt lgkmcnt(0)
	v_mfma_f32_16x16x32_bf16 v[60:63], v[144:147], v[184:187], v[60:63]
	v_mfma_f32_16x16x32_bf16 v[56:59], v[160:163], v[184:187], v[56:59]
	v_mfma_f32_16x16x32_bf16 v[44:47], v[144:147], v[192:195], v[44:47]
	v_mfma_f32_16x16x32_bf16 v[40:43], v[160:163], v[192:195], v[40:43]
	v_mfma_f32_16x16x32_bf16 v[28:31], v[144:147], v[200:203], v[28:31]
	v_mfma_f32_16x16x32_bf16 v[24:27], v[160:163], v[200:203], v[24:27]
	v_lshl_add_u64 v[218:219], v[222:223], 0, s[12:13]
	s_mov_b32 m0, s43
	s_nop 0
	global_load_lds_dwordx4 v[218:219], off
	v_mfma_f32_16x16x32_bf16 v[12:15], v[144:147], v[210:213], v[12:15]
	v_mfma_f32_16x16x32_bf16 v[8:11], v[160:163], v[210:213], v[8:11]
	v_mfma_f32_16x16x32_bf16 v[60:63], v[156:159], v[188:191], v[60:63]
	v_mfma_f32_16x16x32_bf16 v[56:59], v[164:167], v[188:191], v[56:59]
	v_mfma_f32_16x16x32_bf16 v[44:47], v[156:159], v[196:199], v[44:47]
	v_mfma_f32_16x16x32_bf16 v[40:43], v[164:167], v[196:199], v[40:43]
	v_mfma_f32_16x16x32_bf16 v[28:31], v[156:159], v[206:209], v[28:31]
	v_mfma_f32_16x16x32_bf16 v[24:27], v[164:167], v[206:209], v[24:27]
	v_mfma_f32_16x16x32_bf16 v[12:15], v[156:159], v[214:217], v[12:15]
	v_mfma_f32_16x16x32_bf16 v[8:11], v[164:167], v[214:217], v[8:11]
	s_setprio 0
	s_setprio 1
	v_mfma_f32_16x16x32_bf16 v[52:55], v[168:171], v[184:187], v[52:55]
	v_mfma_f32_16x16x32_bf16 v[48:51], v[176:179], v[184:187], v[48:51]
	v_lshl_add_u64 v[218:219], v[224:225], 0, s[12:13]
	s_mov_b32 m0, s44
	s_nop 0
	global_load_lds_dwordx4 v[218:219], off
	v_mfma_f32_16x16x32_bf16 v[36:39], v[168:171], v[192:195], v[36:39]
	v_mfma_f32_16x16x32_bf16 v[32:35], v[176:179], v[192:195], v[32:35]
	v_mfma_f32_16x16x32_bf16 v[20:23], v[168:171], v[200:203], v[20:23]
	v_mfma_f32_16x16x32_bf16 v[16:19], v[176:179], v[200:203], v[16:19]
	v_mfma_f32_16x16x32_bf16 v[4:7], v[168:171], v[210:213], v[4:7]
	v_mfma_f32_16x16x32_bf16 v[0:3], v[176:179], v[210:213], v[0:3]
	v_mfma_f32_16x16x32_bf16 v[52:55], v[172:175], v[188:191], v[52:55]
	v_mfma_f32_16x16x32_bf16 v[48:51], v[180:183], v[188:191], v[48:51]
	v_mfma_f32_16x16x32_bf16 v[36:39], v[172:175], v[196:199], v[36:39]
	v_mfma_f32_16x16x32_bf16 v[32:35], v[180:183], v[196:199], v[32:35]
	v_mfma_f32_16x16x32_bf16 v[20:23], v[172:175], v[206:209], v[20:23]
	v_mfma_f32_16x16x32_bf16 v[16:19], v[180:183], v[206:209], v[16:19]
	v_mfma_f32_16x16x32_bf16 v[4:7], v[172:175], v[214:217], v[4:7]
	v_mfma_f32_16x16x32_bf16 v[0:3], v[180:183], v[214:217], v[0:3]
	s_setprio 0
	s_barrier
	s_add_i32 s55, s55, 2
	s_add_u32 s53, s53, 0x100
	s_addc_u32 s54, s54, 0
	s_cmp_gt_u32 s55, 41
	s_mov_b64 s[26:27], s[28:29]
	s_cbranch_scc0 .LBB0_1978
	s_and_b64 vcc, exec, s[16:17]
	s_cbranch_vccz .LBB0_1981
	s_barrier
